# reduction steps fused into v_add_f32_dpp (no separate dpp move), empty lgkmcnt(0) waits removed
# baseline (speedup 1.0000x reference)
.LBB0_209:
	s_or_b64 exec, exec, s[6:7]
	v_ashrrev_i32_e32 v1, 12, v2
	v_mad_i32_i24 v1, v1, s35, s35
	v_cndmask_b32_e64 v34, v1, 0, s[4:5]
	v_ashrrev_i32_e32 v35, 31, v34
	v_lshl_add_u64 v[42:43], v[34:35], 2, s[14:15]
	v_lshl_add_u64 v[54:55], v[42:43], 0, s[28:29]
	v_lshl_add_u64 v[46:47], v[24:25], 0, v[12:13]
	v_lshl_add_u64 v[24:25], v[54:55], 0, v[12:13]
	s_waitcnt lgkmcnt(0)
	v_readfirstlane_b32 s4, v4
	v_readfirstlane_b32 s5, v5
	global_load_dwordx4 v[34:37], v[46:47], off
	s_nop 3
	global_load_dwordx4 v[38:41], v12, s[4:5]
	global_load_dwordx4 v[42:45], v[24:25], off
	v_lshlrev_b64 v[24:25], 12, v[22:23]
	v_lshlrev_b64 v[22:23], 11, v[22:23]
	v_lshl_add_u64 v[58:59], v[6:7], 0, v[24:25]
	v_lshl_add_u64 v[62:63], v[8:9], 0, v[22:23]
	v_lshl_add_u64 v[50:51], v[54:55], 0, v[16:17]
	s_waitcnt vmcnt(2)
	global_store_dwordx4 v[58:59], v[34:37], off sc1
	s_waitcnt vmcnt(2)
	v_pk_mul_f32 v[22:23], v[36:37], v[40:41]
	v_pk_mul_f32 v[24:25], v[34:35], v[38:39]
	s_waitcnt vmcnt(1)
	v_pk_add_f32 v[38:39], v[42:43], 1.0 op_sel_hi:[1,0]
	v_pk_add_f32 v[40:41], v[44:45], 1.0 op_sel_hi:[1,0]
	v_pk_mul_f32 v[24:25], v[38:39], v[24:25]
	v_pk_mul_f32 v[22:23], v[40:41], v[22:23]
	v_cvt_pk_bf16_f32 v24, v24, v25
	v_cvt_pk_bf16_f32 v25, v22, v23
	global_store_dwordx2 v[62:63], v[24:25], off sc1
	v_lshl_add_u64 v[42:43], v[54:55], 0, v[14:15]
	global_load_dwordx4 v[22:25], v[46:47], off offset:1024
	global_load_dwordx4 v[38:41], v12, s[4:5] offset:1024
	v_mul_f32_e32 v1, v35, v35
	global_load_dwordx4 v[42:45], v[42:43], off
	v_fmac_f32_e32 v1, v34, v34
	v_fmac_f32_e32 v1, v36, v36
	v_fmac_f32_e32 v1, v37, v37
	s_waitcnt vmcnt(2)
	global_store_dwordx4 v[58:59], v[22:25], off offset:1024 sc1
	s_waitcnt vmcnt(2)
	v_pk_mul_f32 v[40:41], v[24:25], v[40:41]
	v_pk_mul_f32 v[38:39], v[22:23], v[38:39]
	s_waitcnt vmcnt(1)
	v_pk_add_f32 v[42:43], v[42:43], 1.0 op_sel_hi:[1,0]
	v_pk_add_f32 v[44:45], v[44:45], 1.0 op_sel_hi:[1,0]
	v_pk_mul_f32 v[38:39], v[42:43], v[38:39]
	v_pk_mul_f32 v[40:41], v[44:45], v[40:41]
	v_cvt_pk_bf16_f32 v38, v38, v39
	v_cvt_pk_bf16_f32 v39, v40, v41
	global_store_dwordx2 v[62:63], v[38:39], off offset:512 sc1
	global_load_dwordx4 v[38:41], v[46:47], off offset:2048
	s_nop 0
	global_load_dwordx4 v[42:45], v12, s[4:5] offset:2048
	v_mul_f32_e32 v2, v23, v23
	global_load_dwordx4 v[50:53], v[50:51], off
	v_fmac_f32_e32 v2, v22, v22
	v_fmac_f32_e32 v2, v24, v24
	v_fmac_f32_e32 v2, v25, v25
	v_add_f32_e32 v1, v1, v2
	s_waitcnt vmcnt(2)
	global_store_dwordx4 v[58:59], v[38:41], off offset:2048 sc1
	s_waitcnt vmcnt(2)
	v_pk_mul_f32 v[44:45], v[40:41], v[44:45]
	v_pk_mul_f32 v[42:43], v[38:39], v[42:43]
	s_waitcnt vmcnt(1)
	v_pk_add_f32 v[50:51], v[50:51], 1.0 op_sel_hi:[1,0]
	v_pk_add_f32 v[52:53], v[52:53], 1.0 op_sel_hi:[1,0]
	v_pk_mul_f32 v[42:43], v[50:51], v[42:43]
	v_pk_mul_f32 v[44:45], v[52:53], v[44:45]
	v_cvt_pk_bf16_f32 v42, v42, v43
	v_cvt_pk_bf16_f32 v43, v44, v45
	global_store_dwordx2 v[62:63], v[42:43], off offset:1024 sc1
	global_load_dwordx4 v[42:45], v[46:47], off offset:3072
	s_nop 0
	global_load_dwordx4 v[50:53], v12, s[4:5] offset:3072
	v_lshl_add_u64 v[46:47], v[54:55], 0, v[18:19]
	global_load_dwordx4 v[54:57], v[46:47], off
	v_mul_f32_e32 v2, v39, v39
	v_fmac_f32_e32 v2, v38, v38
	v_fmac_f32_e32 v2, v40, v40
	v_fmac_f32_e32 v2, v41, v41
	v_add_f32_e32 v1, v1, v2
	s_waitcnt vmcnt(2)
	v_mul_f32_e32 v2, v43, v43
	v_fmac_f32_e32 v2, v42, v42
	v_fmac_f32_e32 v2, v44, v44
	v_fmac_f32_e32 v2, v45, v45
	v_add_f32_e32 v1, v1, v2
	s_waitcnt vmcnt(1)
	v_pk_mul_f32 v[24:25], v[42:43], v[50:51]
	s_waitcnt vmcnt(0)
	v_pk_add_f32 v[34:35], v[54:55], 1.0 op_sel_hi:[1,0]
	v_pk_mul_f32 v[22:23], v[44:45], v[52:53]
	v_pk_mul_f32 v[24:25], v[34:35], v[24:25]
	v_add_f32_dpp v1, v1, v1 quad_perm:[1,0,3,2] row_mask:0xf bank_mask:0xf
	v_pk_add_f32 v[34:35], v[56:57], 1.0 op_sel_hi:[1,0]
	v_cvt_pk_bf16_f32 v24, v24, v25
	v_pk_mul_f32 v[22:23], v[34:35], v[22:23]
	global_store_dwordx4 v[58:59], v[42:45], off offset:3072 sc1
	v_add_f32_dpp v1, v1, v1 quad_perm:[2,3,0,1] row_mask:0xf bank_mask:0xf
	v_cvt_pk_bf16_f32 v25, v22, v23
	global_store_dwordx2 v[62:63], v[24:25], off offset:1536 sc1
	v_add_f32_dpp v1, v1, v1 row_half_mirror row_mask:0xf bank_mask:0xf
	s_nop 0
	v_add_f32_dpp v1, v1, v1 row_mirror row_mask:0xf bank_mask:0xf
	v_mov_b32_e32 v2, v1
	s_nop 1
	v_permlane16_swap_b32_e32 v1, v2
	s_nop 0
	v_add_f32_e32 v1, v1, v2
	ds_bpermute_b32 v2, v31, v1
	s_and_saveexec_b64 s[4:5], vcc
	s_cbranch_execz .LBB0_204
	v_add_u32_e32 v22, v32, v20
	v_ashrrev_i32_e32 v23, 31, v22
	s_waitcnt lgkmcnt(0)
	v_add_f32_e32 v1, v1, v2
	v_lshl_add_u64 v[22:23], v[22:23], 2, s[22:23]
	v_cndmask_b32_e64 v1, 0, v1, s[0:1]
	global_store_dword v[22:23], v1, off sc1
	s_branch .LBB0_204

.LBB0_214:
	v_lshl_add_u64 v[72:73], s[14:15], 0, v[54:55]
	s_waitcnt lgkmcnt(1)
	global_load_dwordx4 v[64:67], v[72:73], off
	s_waitcnt lgkmcnt(0)
	global_load_dwordx4 v[68:71], v[72:73], off offset:16
	s_waitcnt vmcnt(1)
	v_lshlrev_b32_e32 v63, 16, v64
	v_and_b32_e32 v64, 0xffff0000, v64
	v_lshlrev_b32_e32 v72, 16, v65
	v_and_b32_e32 v65, 0xffff0000, v65
	v_mul_f32_e32 v79, v9, v64
	v_mul_f32_e32 v80, v25, v64
	v_mul_f32_e32 v64, v41, v64
	v_lshlrev_b32_e32 v73, 16, v66
	v_and_b32_e32 v66, 0xffff0000, v66
	v_mul_f32_e32 v81, v11, v65
	v_mul_f32_e32 v82, v27, v65
	v_mul_f32_e32 v65, v43, v65
	v_fmac_f32_e32 v79, v8, v63
	v_fmac_f32_e32 v80, v24, v63
	v_fmac_f32_e32 v64, v40, v63
	v_lshlrev_b32_e32 v74, 16, v67
	v_and_b32_e32 v67, 0xffff0000, v67
	v_mul_f32_e32 v83, v1, v66
	v_mul_f32_e32 v84, v17, v66
	v_mul_f32_e32 v66, v33, v66
	v_fmac_f32_e32 v81, v10, v72
	v_fmac_f32_e32 v82, v26, v72
	v_fmac_f32_e32 v65, v42, v72
	v_add_f32_e32 v63, 0, v79
	v_add_f32_e32 v72, 0, v80
	v_add_f32_e32 v64, 0, v64
	s_waitcnt vmcnt(0)
	v_lshlrev_b32_e32 v75, 16, v68
	v_and_b32_e32 v68, 0xffff0000, v68
	v_mul_f32_e32 v85, v3, v67
	v_mul_f32_e32 v86, v19, v67
	v_mul_f32_e32 v67, v35, v67
	v_fmac_f32_e32 v83, v0, v73
	v_fmac_f32_e32 v84, v16, v73
	v_fmac_f32_e32 v66, v32, v73
	v_add_f32_e32 v63, v63, v81
	v_add_f32_e32 v72, v72, v82
	v_add_f32_e32 v64, v64, v65
	v_lshlrev_b32_e32 v76, 16, v69
	v_and_b32_e32 v69, 0xffff0000, v69
	v_mul_f32_e32 v87, v5, v68
	v_mul_f32_e32 v88, v21, v68
	v_mul_f32_e32 v68, v37, v68
	v_fmac_f32_e32 v85, v2, v74
	v_fmac_f32_e32 v86, v18, v74
	v_fmac_f32_e32 v67, v34, v74
	v_add_f32_e32 v63, v63, v83
	v_add_f32_e32 v65, v72, v84
	v_add_f32_e32 v64, v64, v66
	v_lshlrev_b32_e32 v77, 16, v70
	v_and_b32_e32 v70, 0xffff0000, v70
	v_mul_f32_e32 v89, v7, v69
	v_mul_f32_e32 v90, v23, v69
	v_mul_f32_e32 v69, v39, v69
	v_fmac_f32_e32 v87, v4, v75
	v_fmac_f32_e32 v88, v20, v75
	v_fmac_f32_e32 v68, v36, v75
	v_add_f32_e32 v63, v63, v85
	v_add_f32_e32 v65, v65, v86
	v_add_f32_e32 v64, v64, v67
	v_lshlrev_b32_e32 v78, 16, v71
	v_and_b32_e32 v71, 0xffff0000, v71
	v_mul_f32_e32 v91, v13, v70
	v_mul_f32_e32 v92, v29, v70
	v_mul_f32_e32 v70, v45, v70
	v_fmac_f32_e32 v89, v6, v76
	v_fmac_f32_e32 v90, v22, v76
	v_fmac_f32_e32 v69, v38, v76
	v_add_f32_e32 v63, v63, v87
	v_add_f32_e32 v65, v65, v88
	v_add_f32_e32 v64, v64, v68
	v_mul_f32_e32 v93, v15, v71
	v_mul_f32_e32 v94, v31, v71
	v_mul_f32_e32 v71, v47, v71
	v_fmac_f32_e32 v91, v12, v77
	v_fmac_f32_e32 v92, v28, v77
	v_fmac_f32_e32 v70, v44, v77
	v_add_f32_e32 v63, v63, v89
	v_add_f32_e32 v65, v65, v90
	v_add_f32_e32 v64, v64, v69
	v_fmac_f32_e32 v93, v14, v78
	v_fmac_f32_e32 v94, v30, v78
	v_fmac_f32_e32 v71, v46, v78
	v_add_f32_e32 v63, v63, v91
	v_add_f32_e32 v65, v65, v92
	v_add_f32_e32 v64, v64, v70
	v_add_f32_e32 v63, v63, v93
	v_add_f32_e32 v65, v65, v94
	v_add_f32_e32 v64, v64, v71
	v_add_f32_dpp v63, v63, v63 quad_perm:[1,0,3,2] row_mask:0xf bank_mask:0xf
	v_add_f32_dpp v65, v65, v65 quad_perm:[1,0,3,2] row_mask:0xf bank_mask:0xf
	v_add_f32_dpp v64, v64, v64 quad_perm:[1,0,3,2] row_mask:0xf bank_mask:0xf
	v_add_f32_dpp v63, v63, v63 quad_perm:[2,3,0,1] row_mask:0xf bank_mask:0xf
	v_add_f32_dpp v65, v65, v65 quad_perm:[2,3,0,1] row_mask:0xf bank_mask:0xf
	v_add_f32_dpp v64, v64, v64 quad_perm:[2,3,0,1] row_mask:0xf bank_mask:0xf
	v_add_f32_dpp v63, v63, v63 row_half_mirror row_mask:0xf bank_mask:0xf
	v_add_f32_dpp v65, v65, v65 row_half_mirror row_mask:0xf bank_mask:0xf
	v_add_f32_dpp v64, v64, v64 row_half_mirror row_mask:0xf bank_mask:0xf
	v_add_f32_dpp v63, v63, v63 row_mirror row_mask:0xf bank_mask:0xf
	v_add_f32_dpp v65, v65, v65 row_mirror row_mask:0xf bank_mask:0xf
	v_add_f32_dpp v66, v64, v64 row_mirror row_mask:0xf bank_mask:0xf
	v_mov_b32_e32 v64, v63
	s_nop 1
	v_permlane16_swap_b32_e32 v63, v64
	s_nop 0
	v_mov_b32_e32 v67, v65
	s_nop 1
	v_permlane16_swap_b32_e32 v65, v67
	s_nop 0
	v_mov_b32_e32 v68, v66
	s_nop 1
	v_permlane16_swap_b32_e32 v66, v68
	s_nop 0
	v_add_f32_e32 v63, v63, v64
	v_add_f32_e32 v64, v65, v67
	v_add_f32_e32 v66, v66, v68
	ds_bpermute_b32 v65, v61, v63
	ds_bpermute_b32 v67, v61, v64
	ds_bpermute_b32 v68, v61, v66
	s_and_saveexec_b64 s[24:25], s[0:1]
	s_cbranch_execz .LBB0_213
	s_waitcnt lgkmcnt(1)
	v_add_f32_e32 v69, v64, v67
	v_add_f32_e32 v63, v63, v65
	v_lshl_add_u64 v[64:65], s[14:15], 0, v[52:53]
	s_waitcnt lgkmcnt(0)
	v_add_f32_e32 v68, v66, v68
	v_add_co_u32_e32 v66, vcc, 0x5be8000, v64
	s_nop 1
	v_addc_co_u32_e32 v67, vcc, 0, v65, vcc
	global_store_dword v[66:67], v63, off sc1
	v_add_co_u32_e32 v66, vcc, 0x5beb000, v64
	s_nop 1
	v_addc_co_u32_e32 v67, vcc, 0, v65, vcc
	v_add_co_u32_e32 v64, vcc, 0x5bee000, v64
	global_store_dword v[66:67], v69, off sc1
	s_nop 0
	v_addc_co_u32_e32 v65, vcc, 0, v65, vcc
	global_store_dword v[64:65], v68, off sc1
	s_branch .LBB0_213

.LBB0_219:
	s_waitcnt lgkmcnt(0)
	v_lshl_add_u64 v[68:69], s[14:15], 0, v[54:55]
	v_add_co_u32_e32 v64, vcc, 0x5a0000, v68
	s_nop 1
	v_addc_co_u32_e32 v65, vcc, 0, v69, vcc
	global_load_dwordx4 v[64:67], v[64:65], off
	v_lshl_add_u64 v[68:69], v[68:69], 0, s[24:25]
	global_load_dwordx4 v[68:71], v[68:69], off offset:16
	s_waitcnt vmcnt(1)
	v_lshlrev_b32_e32 v63, 16, v64
	v_and_b32_e32 v64, 0xffff0000, v64
	v_lshlrev_b32_e32 v72, 16, v65
	v_and_b32_e32 v65, 0xffff0000, v65
	v_mul_f32_e32 v79, v9, v64
	v_mul_f32_e32 v80, v25, v64
	v_mul_f32_e32 v64, v41, v64
	v_lshlrev_b32_e32 v73, 16, v66
	v_and_b32_e32 v66, 0xffff0000, v66
	v_mul_f32_e32 v81, v11, v65
	v_mul_f32_e32 v82, v27, v65
	v_mul_f32_e32 v65, v43, v65
	v_fmac_f32_e32 v79, v8, v63
	v_fmac_f32_e32 v80, v24, v63
	v_fmac_f32_e32 v64, v40, v63
	v_lshlrev_b32_e32 v74, 16, v67
	v_and_b32_e32 v67, 0xffff0000, v67
	v_mul_f32_e32 v83, v1, v66
	v_mul_f32_e32 v84, v17, v66
	v_mul_f32_e32 v66, v33, v66
	v_fmac_f32_e32 v81, v10, v72
	v_fmac_f32_e32 v82, v26, v72
	v_fmac_f32_e32 v65, v42, v72
	v_add_f32_e32 v63, 0, v79
	v_add_f32_e32 v72, 0, v80
	v_add_f32_e32 v64, 0, v64
	s_waitcnt vmcnt(0)
	v_lshlrev_b32_e32 v75, 16, v68
	v_and_b32_e32 v68, 0xffff0000, v68
	v_mul_f32_e32 v85, v3, v67
	v_mul_f32_e32 v86, v19, v67
	v_mul_f32_e32 v67, v35, v67
	v_fmac_f32_e32 v83, v0, v73
	v_fmac_f32_e32 v84, v16, v73
	v_fmac_f32_e32 v66, v32, v73
	v_add_f32_e32 v63, v63, v81
	v_add_f32_e32 v72, v72, v82
	v_add_f32_e32 v64, v64, v65
	v_lshlrev_b32_e32 v76, 16, v69
	v_and_b32_e32 v69, 0xffff0000, v69
	v_mul_f32_e32 v87, v5, v68
	v_mul_f32_e32 v88, v21, v68
	v_mul_f32_e32 v68, v37, v68
	v_fmac_f32_e32 v85, v2, v74
	v_fmac_f32_e32 v86, v18, v74
	v_fmac_f32_e32 v67, v34, v74
	v_add_f32_e32 v63, v63, v83
	v_add_f32_e32 v65, v72, v84
	v_add_f32_e32 v64, v64, v66
	v_lshlrev_b32_e32 v77, 16, v70
	v_and_b32_e32 v70, 0xffff0000, v70
	v_mul_f32_e32 v89, v7, v69
	v_mul_f32_e32 v90, v23, v69
	v_mul_f32_e32 v69, v39, v69
	v_fmac_f32_e32 v87, v4, v75
	v_fmac_f32_e32 v88, v20, v75
	v_fmac_f32_e32 v68, v36, v75
	v_add_f32_e32 v63, v63, v85
	v_add_f32_e32 v65, v65, v86
	v_add_f32_e32 v64, v64, v67
	v_lshlrev_b32_e32 v78, 16, v71
	v_and_b32_e32 v71, 0xffff0000, v71
	v_mul_f32_e32 v91, v13, v70
	v_mul_f32_e32 v92, v29, v70
	v_mul_f32_e32 v70, v45, v70
	v_fmac_f32_e32 v89, v6, v76
	v_fmac_f32_e32 v90, v22, v76
	v_fmac_f32_e32 v69, v38, v76
	v_add_f32_e32 v63, v63, v87
	v_add_f32_e32 v65, v65, v88
	v_add_f32_e32 v64, v64, v68
	v_mul_f32_e32 v93, v15, v71
	v_mul_f32_e32 v94, v31, v71
	v_fmac_f32_e32 v91, v12, v77
	v_fmac_f32_e32 v92, v28, v77
	v_fmac_f32_e32 v70, v44, v77
	v_add_f32_e32 v63, v63, v89
	v_add_f32_e32 v65, v65, v90
	v_add_f32_e32 v64, v64, v69
	v_mul_f32_e32 v66, v47, v71
	v_fmac_f32_e32 v93, v14, v78
	v_fmac_f32_e32 v94, v30, v78
	v_add_f32_e32 v63, v63, v91
	v_add_f32_e32 v65, v65, v92
	v_add_f32_e32 v64, v64, v70
	v_fmac_f32_e32 v66, v46, v78
	v_add_f32_e32 v63, v63, v93
	v_add_f32_e32 v65, v65, v94
	v_add_f32_e32 v64, v64, v66
	v_add_f32_dpp v63, v63, v63 quad_perm:[1,0,3,2] row_mask:0xf bank_mask:0xf
	v_add_f32_dpp v65, v65, v65 quad_perm:[1,0,3,2] row_mask:0xf bank_mask:0xf
	v_add_f32_dpp v64, v64, v64 quad_perm:[1,0,3,2] row_mask:0xf bank_mask:0xf
	v_add_f32_dpp v63, v63, v63 quad_perm:[2,3,0,1] row_mask:0xf bank_mask:0xf
	v_add_f32_dpp v65, v65, v65 quad_perm:[2,3,0,1] row_mask:0xf bank_mask:0xf
	v_add_f32_dpp v64, v64, v64 quad_perm:[2,3,0,1] row_mask:0xf bank_mask:0xf
	v_add_f32_dpp v63, v63, v63 row_half_mirror row_mask:0xf bank_mask:0xf
	v_add_f32_dpp v65, v65, v65 row_half_mirror row_mask:0xf bank_mask:0xf
	v_add_f32_dpp v64, v64, v64 row_half_mirror row_mask:0xf bank_mask:0xf
	v_add_f32_dpp v63, v63, v63 row_mirror row_mask:0xf bank_mask:0xf
	v_add_f32_dpp v65, v65, v65 row_mirror row_mask:0xf bank_mask:0xf
	v_add_f32_dpp v69, v64, v64 row_mirror row_mask:0xf bank_mask:0xf
	v_mov_b32_e32 v67, v63
	s_nop 1
	v_permlane16_swap_b32_e32 v63, v67
	s_nop 0
	v_mov_b32_e32 v68, v65
	s_nop 1
	v_permlane16_swap_b32_e32 v65, v68
	s_nop 0
	ds_bpermute_b32 v70, v59, v69
	s_waitcnt lgkmcnt(1)
	v_add_f32_e32 v63, v63, v67
	s_waitcnt lgkmcnt(1)
	v_add_f32_e32 v65, v65, v68
	s_waitcnt lgkmcnt(0)
	v_add_f32_e32 v67, v69, v70
	ds_bpermute_b32 v64, v61, v63
	ds_bpermute_b32 v66, v61, v65
	ds_bpermute_b32 v68, v61, v67
	s_and_saveexec_b64 s[26:27], s[0:1]
	s_cbranch_execz .LBB0_218
	s_waitcnt lgkmcnt(1)
	v_add_f32_e32 v69, v65, v66
	v_add_f32_e32 v63, v63, v64
	v_lshl_add_u64 v[64:65], s[14:15], 0, v[52:53]
	v_add_co_u32_e32 v66, vcc, 0x5bf1000, v64
	s_waitcnt lgkmcnt(0)
	v_add_f32_e32 v68, v67, v68
	v_addc_co_u32_e32 v67, vcc, 0, v65, vcc
	global_store_dword v[66:67], v63, off sc1
	v_add_co_u32_e32 v66, vcc, 0x5bf4000, v64
	s_nop 1
	v_addc_co_u32_e32 v67, vcc, 0, v65, vcc
	v_add_co_u32_e32 v64, vcc, 0x5bf7000, v64
	global_store_dword v[66:67], v69, off sc1
	s_nop 0
	v_addc_co_u32_e32 v65, vcc, 0, v65, vcc
	global_store_dword v[64:65], v68, off sc1
	s_branch .LBB0_218

.LBB0_224:
	s_waitcnt lgkmcnt(0)
	v_lshl_add_u64 v[68:69], s[14:15], 0, v[54:55]
	v_add_co_u32_e32 v64, vcc, 0xda0000, v68
	s_nop 1
	v_addc_co_u32_e32 v65, vcc, 0, v69, vcc
	global_load_dwordx4 v[64:67], v[64:65], off
	v_lshl_add_u64 v[68:69], v[68:69], 0, s[24:25]
	global_load_dwordx4 v[68:71], v[68:69], off offset:16
	s_waitcnt vmcnt(1)
	v_lshlrev_b32_e32 v63, 16, v64
	v_and_b32_e32 v64, 0xffff0000, v64
	v_lshlrev_b32_e32 v72, 16, v65
	v_and_b32_e32 v65, 0xffff0000, v65
	v_mul_f32_e32 v79, v9, v64
	v_mul_f32_e32 v80, v25, v64
	v_mul_f32_e32 v64, v41, v64
	v_lshlrev_b32_e32 v73, 16, v66
	v_and_b32_e32 v66, 0xffff0000, v66
	v_mul_f32_e32 v81, v11, v65
	v_mul_f32_e32 v82, v27, v65
	v_mul_f32_e32 v65, v43, v65
	v_fmac_f32_e32 v79, v8, v63
	v_fmac_f32_e32 v80, v24, v63
	v_fmac_f32_e32 v64, v40, v63
	v_lshlrev_b32_e32 v74, 16, v67
	v_and_b32_e32 v67, 0xffff0000, v67
	v_mul_f32_e32 v83, v1, v66
	v_mul_f32_e32 v84, v17, v66
	v_mul_f32_e32 v66, v33, v66
	v_fmac_f32_e32 v81, v10, v72
	v_fmac_f32_e32 v82, v26, v72
	v_fmac_f32_e32 v65, v42, v72
	v_add_f32_e32 v63, 0, v79
	v_add_f32_e32 v72, 0, v80
	v_add_f32_e32 v64, 0, v64
	s_waitcnt vmcnt(0)
	v_lshlrev_b32_e32 v75, 16, v68
	v_and_b32_e32 v68, 0xffff0000, v68
	v_mul_f32_e32 v85, v3, v67
	v_mul_f32_e32 v86, v19, v67
	v_mul_f32_e32 v67, v35, v67
	v_fmac_f32_e32 v83, v0, v73
	v_fmac_f32_e32 v84, v16, v73
	v_fmac_f32_e32 v66, v32, v73
	v_add_f32_e32 v63, v63, v81
	v_add_f32_e32 v72, v72, v82
	v_add_f32_e32 v64, v64, v65
	v_lshlrev_b32_e32 v76, 16, v69
	v_and_b32_e32 v69, 0xffff0000, v69
	v_mul_f32_e32 v87, v5, v68
	v_mul_f32_e32 v88, v21, v68
	v_mul_f32_e32 v68, v37, v68
	v_fmac_f32_e32 v85, v2, v74
	v_fmac_f32_e32 v86, v18, v74
	v_fmac_f32_e32 v67, v34, v74
	v_add_f32_e32 v63, v63, v83
	v_add_f32_e32 v65, v72, v84
	v_add_f32_e32 v64, v64, v66
	v_lshlrev_b32_e32 v77, 16, v70
	v_and_b32_e32 v70, 0xffff0000, v70
	v_mul_f32_e32 v89, v7, v69
	v_mul_f32_e32 v90, v23, v69
	v_mul_f32_e32 v69, v39, v69
	v_fmac_f32_e32 v87, v4, v75
	v_fmac_f32_e32 v88, v20, v75
	v_fmac_f32_e32 v68, v36, v75
	v_add_f32_e32 v63, v63, v85
	v_add_f32_e32 v65, v65, v86
	v_add_f32_e32 v64, v64, v67
	v_lshlrev_b32_e32 v78, 16, v71
	v_and_b32_e32 v71, 0xffff0000, v71
	v_mul_f32_e32 v91, v13, v70
	v_mul_f32_e32 v92, v29, v70
	v_mul_f32_e32 v70, v45, v70
	v_fmac_f32_e32 v89, v6, v76
	v_fmac_f32_e32 v90, v22, v76
	v_fmac_f32_e32 v69, v38, v76
	v_add_f32_e32 v63, v63, v87
	v_add_f32_e32 v65, v65, v88
	v_add_f32_e32 v64, v64, v68
	v_mul_f32_e32 v93, v15, v71
	v_mul_f32_e32 v94, v31, v71
	v_fmac_f32_e32 v91, v12, v77
	v_fmac_f32_e32 v92, v28, v77
	v_fmac_f32_e32 v70, v44, v77
	v_add_f32_e32 v63, v63, v89
	v_add_f32_e32 v65, v65, v90
	v_add_f32_e32 v64, v64, v69
	v_mul_f32_e32 v66, v47, v71
	v_fmac_f32_e32 v93, v14, v78
	v_fmac_f32_e32 v94, v30, v78
	v_add_f32_e32 v63, v63, v91
	v_add_f32_e32 v65, v65, v92
	v_add_f32_e32 v64, v64, v70
	v_fmac_f32_e32 v66, v46, v78
	v_add_f32_e32 v63, v63, v93
	v_add_f32_e32 v65, v65, v94
	v_add_f32_e32 v64, v64, v66
	v_add_f32_dpp v63, v63, v63 quad_perm:[1,0,3,2] row_mask:0xf bank_mask:0xf
	v_add_f32_dpp v65, v65, v65 quad_perm:[1,0,3,2] row_mask:0xf bank_mask:0xf
	v_add_f32_dpp v64, v64, v64 quad_perm:[1,0,3,2] row_mask:0xf bank_mask:0xf
	v_add_f32_dpp v63, v63, v63 quad_perm:[2,3,0,1] row_mask:0xf bank_mask:0xf
	v_add_f32_dpp v65, v65, v65 quad_perm:[2,3,0,1] row_mask:0xf bank_mask:0xf
	v_add_f32_dpp v64, v64, v64 quad_perm:[2,3,0,1] row_mask:0xf bank_mask:0xf
	v_add_f32_dpp v63, v63, v63 row_half_mirror row_mask:0xf bank_mask:0xf
	v_add_f32_dpp v65, v65, v65 row_half_mirror row_mask:0xf bank_mask:0xf
	v_add_f32_dpp v64, v64, v64 row_half_mirror row_mask:0xf bank_mask:0xf
	v_add_f32_dpp v63, v63, v63 row_mirror row_mask:0xf bank_mask:0xf
	v_add_f32_dpp v65, v65, v65 row_mirror row_mask:0xf bank_mask:0xf
	v_add_f32_dpp v69, v64, v64 row_mirror row_mask:0xf bank_mask:0xf
	v_mov_b32_e32 v67, v63
	s_nop 1
	v_permlane16_swap_b32_e32 v63, v67
	s_nop 0
	v_mov_b32_e32 v68, v65
	s_nop 1
	v_permlane16_swap_b32_e32 v65, v68
	s_nop 0
	ds_bpermute_b32 v70, v59, v69
	s_waitcnt lgkmcnt(1)
	v_add_f32_e32 v63, v63, v67
	s_waitcnt lgkmcnt(1)
	v_add_f32_e32 v65, v65, v68
	s_waitcnt lgkmcnt(0)
	v_add_f32_e32 v67, v69, v70
	ds_bpermute_b32 v64, v61, v63
	ds_bpermute_b32 v66, v61, v65
	ds_bpermute_b32 v68, v61, v67
	s_and_saveexec_b64 s[26:27], s[0:1]
	s_cbranch_execz .LBB0_223
	s_waitcnt lgkmcnt(1)
	v_add_f32_e32 v69, v65, v66
	v_add_f32_e32 v63, v63, v64
	v_lshl_add_u64 v[64:65], s[14:15], 0, v[52:53]
	v_add_co_u32_e32 v66, vcc, 0x5bfa000, v64
	s_waitcnt lgkmcnt(0)
	v_add_f32_e32 v68, v67, v68
	v_addc_co_u32_e32 v67, vcc, 0, v65, vcc
	global_store_dword v[66:67], v63, off sc1
	v_add_co_u32_e32 v66, vcc, 0x5bfd000, v64
	s_nop 1
	v_addc_co_u32_e32 v67, vcc, 0, v65, vcc
	v_add_co_u32_e32 v64, vcc, 0x5c00000, v64
	global_store_dword v[66:67], v69, off sc1
	s_nop 0
	v_addc_co_u32_e32 v65, vcc, 0, v65, vcc
	global_store_dword v[64:65], v68, off sc1
	s_branch .LBB0_223

.LBB0_231:
	s_waitcnt lgkmcnt(0)
	v_lshl_add_u64 v[70:71], s[14:15], 0, v[52:53]
	v_add_co_u32_e32 v66, vcc, 0x12a0000, v70
	s_nop 1
	v_addc_co_u32_e32 v67, vcc, 0, v71, vcc
	global_load_dwordx4 v[66:69], v[66:67], off
	v_lshl_add_u64 v[70:71], v[70:71], 0, s[24:25]
	global_load_dwordx4 v[70:73], v[70:71], off offset:16
	s_waitcnt vmcnt(1)
	v_lshlrev_b32_e32 v74, 16, v66
	v_and_b32_e32 v66, 0xffff0000, v66
	v_lshlrev_b32_e32 v75, 16, v67
	v_and_b32_e32 v67, 0xffff0000, v67
	v_mul_f32_e32 v82, v9, v66
	v_mul_f32_e32 v83, v25, v66
	v_mul_f32_e32 v66, v41, v66
	v_lshlrev_b32_e32 v76, 16, v68
	v_and_b32_e32 v68, 0xffff0000, v68
	v_mul_f32_e32 v84, v11, v67
	v_mul_f32_e32 v85, v27, v67
	v_mul_f32_e32 v67, v43, v67
	v_fmac_f32_e32 v82, v8, v74
	v_fmac_f32_e32 v83, v24, v74
	v_fmac_f32_e32 v66, v40, v74
	v_lshlrev_b32_e32 v77, 16, v69
	v_and_b32_e32 v69, 0xffff0000, v69
	v_mul_f32_e32 v86, v1, v68
	v_mul_f32_e32 v87, v17, v68
	v_mul_f32_e32 v68, v33, v68
	v_fmac_f32_e32 v84, v10, v75
	v_fmac_f32_e32 v85, v26, v75
	v_fmac_f32_e32 v67, v42, v75
	v_add_f32_e32 v74, 0, v82
	v_add_f32_e32 v75, 0, v83
	v_add_f32_e32 v66, 0, v66
	s_waitcnt vmcnt(0)
	v_lshlrev_b32_e32 v78, 16, v70
	v_and_b32_e32 v70, 0xffff0000, v70
	v_mul_f32_e32 v88, v3, v69
	v_mul_f32_e32 v89, v19, v69
	v_mul_f32_e32 v69, v35, v69
	v_fmac_f32_e32 v86, v0, v76
	v_fmac_f32_e32 v87, v16, v76
	v_fmac_f32_e32 v68, v32, v76
	v_add_f32_e32 v74, v74, v84
	v_add_f32_e32 v75, v75, v85
	v_add_f32_e32 v66, v66, v67
	v_lshlrev_b32_e32 v79, 16, v71
	v_and_b32_e32 v71, 0xffff0000, v71
	v_mul_f32_e32 v90, v5, v70
	v_mul_f32_e32 v91, v21, v70
	v_mul_f32_e32 v70, v37, v70
	v_fmac_f32_e32 v88, v2, v77
	v_fmac_f32_e32 v89, v18, v77
	v_fmac_f32_e32 v69, v34, v77
	v_add_f32_e32 v67, v74, v86
	v_add_f32_e32 v74, v75, v87
	v_add_f32_e32 v66, v66, v68
	v_lshlrev_b32_e32 v80, 16, v72
	v_and_b32_e32 v72, 0xffff0000, v72
	v_mul_f32_e32 v92, v7, v71
	v_mul_f32_e32 v93, v23, v71
	v_mul_f32_e32 v71, v39, v71
	v_fmac_f32_e32 v90, v4, v78
	v_fmac_f32_e32 v91, v20, v78
	v_fmac_f32_e32 v70, v36, v78
	v_add_f32_e32 v67, v67, v88
	v_add_f32_e32 v68, v74, v89
	v_add_f32_e32 v66, v66, v69
	v_lshlrev_b32_e32 v81, 16, v73
	v_and_b32_e32 v73, 0xffff0000, v73
	v_mul_f32_e32 v94, v13, v72
	v_mul_f32_e32 v95, v29, v72
	v_mul_f32_e32 v72, v45, v72
	v_fmac_f32_e32 v92, v6, v79
	v_fmac_f32_e32 v93, v22, v79
	v_fmac_f32_e32 v71, v38, v79
	v_add_f32_e32 v67, v67, v90
	v_add_f32_e32 v68, v68, v91
	v_add_f32_e32 v66, v66, v70
	v_mul_f32_e32 v96, v15, v73
	v_mul_f32_e32 v97, v31, v73
	v_fmac_f32_e32 v94, v12, v80
	v_fmac_f32_e32 v95, v28, v80
	v_fmac_f32_e32 v72, v44, v80
	v_add_f32_e32 v67, v67, v92
	v_add_f32_e32 v68, v68, v93
	v_add_f32_e32 v66, v66, v71
	v_mul_f32_e32 v69, v47, v73
	v_fmac_f32_e32 v96, v14, v81
	v_fmac_f32_e32 v97, v30, v81
	v_add_f32_e32 v67, v67, v94
	v_add_f32_e32 v68, v68, v95
	v_add_f32_e32 v66, v66, v72
	v_fmac_f32_e32 v69, v46, v81
	v_add_f32_e32 v67, v67, v96
	v_add_f32_e32 v68, v68, v97
	v_add_f32_e32 v66, v66, v69
	v_add_f32_dpp v67, v67, v67 quad_perm:[1,0,3,2] row_mask:0xf bank_mask:0xf
	v_add_f32_dpp v68, v68, v68 quad_perm:[1,0,3,2] row_mask:0xf bank_mask:0xf
	v_add_f32_dpp v66, v66, v66 quad_perm:[1,0,3,2] row_mask:0xf bank_mask:0xf
	v_add_f32_dpp v67, v67, v67 quad_perm:[2,3,0,1] row_mask:0xf bank_mask:0xf
	v_add_f32_dpp v68, v68, v68 quad_perm:[2,3,0,1] row_mask:0xf bank_mask:0xf
	v_add_f32_dpp v66, v66, v66 quad_perm:[2,3,0,1] row_mask:0xf bank_mask:0xf
	v_add_f32_dpp v67, v67, v67 row_half_mirror row_mask:0xf bank_mask:0xf
	v_add_f32_dpp v68, v68, v68 row_half_mirror row_mask:0xf bank_mask:0xf
	v_add_f32_dpp v66, v66, v66 row_half_mirror row_mask:0xf bank_mask:0xf
	v_add_f32_dpp v67, v67, v67 row_mirror row_mask:0xf bank_mask:0xf
	v_add_f32_dpp v68, v68, v68 row_mirror row_mask:0xf bank_mask:0xf
	v_add_f32_dpp v72, v66, v66 row_mirror row_mask:0xf bank_mask:0xf
	v_mov_b32_e32 v70, v67
	s_nop 1
	v_permlane16_swap_b32_e32 v67, v70
	s_nop 0
	v_mov_b32_e32 v71, v68
	s_nop 1
	v_permlane16_swap_b32_e32 v68, v71
	s_nop 0
	ds_bpermute_b32 v73, v64, v72
	s_waitcnt lgkmcnt(1)
	v_add_f32_e32 v66, v67, v70
	s_waitcnt lgkmcnt(1)
	v_add_f32_e32 v68, v68, v71
	s_waitcnt lgkmcnt(0)
	v_add_f32_e32 v70, v72, v73
	ds_bpermute_b32 v67, v65, v66
	ds_bpermute_b32 v69, v65, v68
	ds_bpermute_b32 v71, v65, v70
	s_and_saveexec_b64 s[26:27], s[0:1]
	s_cbranch_execz .LBB0_230
	s_waitcnt lgkmcnt(2)
	v_add_f32_e32 v72, v66, v67
	v_lshl_add_u64 v[66:67], s[14:15], 0, v[54:55]
	s_waitcnt lgkmcnt(0)
	v_add_f32_e32 v70, v70, v71
	v_add_f32_e32 v71, v68, v69
	v_add_co_u32_e32 v68, vcc, 0x5c03000, v66
	s_nop 1
	v_addc_co_u32_e32 v69, vcc, 0, v67, vcc
	global_store_dword v[68:69], v72, off sc1
	v_add_co_u32_e32 v68, vcc, 0x5c06000, v66
	s_nop 1
	v_addc_co_u32_e32 v69, vcc, 0, v67, vcc
	v_add_co_u32_e32 v66, vcc, 0x5c09000, v66
	global_store_dword v[68:69], v71, off sc1
	s_nop 0
	v_addc_co_u32_e32 v67, vcc, 0, v67, vcc
	global_store_dword v[66:67], v70, off sc1
	s_branch .LBB0_230

.LBB0_239:
	s_waitcnt lgkmcnt(2)
	global_load_dwordx4 v[78:81], v[60:61], off offset:-16
	s_waitcnt lgkmcnt(0)
	global_load_dwordx4 v[82:85], v[60:61], off
	s_waitcnt vmcnt(1)
	v_lshlrev_b32_e32 v86, 16, v78
	v_and_b32_e32 v78, 0xffff0000, v78
	v_lshlrev_b32_e32 v87, 16, v79
	v_and_b32_e32 v79, 0xffff0000, v79
	v_mul_f32_e32 v94, v9, v78
	v_mul_f32_e32 v95, v25, v78
	v_mul_f32_e32 v78, v41, v78
	v_lshlrev_b32_e32 v88, 16, v80
	v_and_b32_e32 v80, 0xffff0000, v80
	v_mul_f32_e32 v96, v11, v79
	v_mul_f32_e32 v97, v27, v79
	v_mul_f32_e32 v79, v43, v79
	v_fmac_f32_e32 v94, v8, v86
	v_fmac_f32_e32 v95, v24, v86
	v_fmac_f32_e32 v78, v40, v86
	v_lshlrev_b32_e32 v89, 16, v81
	v_and_b32_e32 v81, 0xffff0000, v81
	v_mul_f32_e32 v98, v1, v80
	v_mul_f32_e32 v99, v17, v80
	v_mul_f32_e32 v80, v33, v80
	v_fmac_f32_e32 v96, v10, v87
	v_fmac_f32_e32 v97, v26, v87
	v_fmac_f32_e32 v79, v42, v87
	v_add_f32_e32 v86, 0, v94
	v_add_f32_e32 v87, 0, v95
	v_add_f32_e32 v78, 0, v78
	s_waitcnt vmcnt(0)
	v_lshlrev_b32_e32 v90, 16, v82
	v_and_b32_e32 v82, 0xffff0000, v82
	v_mul_f32_e32 v100, v3, v81
	v_mul_f32_e32 v101, v19, v81
	v_mul_f32_e32 v81, v35, v81
	v_fmac_f32_e32 v98, v0, v88
	v_fmac_f32_e32 v99, v16, v88
	v_fmac_f32_e32 v80, v32, v88
	v_add_f32_e32 v86, v86, v96
	v_add_f32_e32 v87, v87, v97
	v_add_f32_e32 v78, v78, v79
	v_lshlrev_b32_e32 v91, 16, v83
	v_and_b32_e32 v83, 0xffff0000, v83
	v_mul_f32_e32 v102, v5, v82
	v_mul_f32_e32 v103, v21, v82
	v_mul_f32_e32 v82, v37, v82
	v_fmac_f32_e32 v100, v2, v89
	v_fmac_f32_e32 v101, v18, v89
	v_fmac_f32_e32 v81, v34, v89
	v_add_f32_e32 v79, v86, v98
	v_add_f32_e32 v86, v87, v99
	v_add_f32_e32 v78, v78, v80
	v_lshlrev_b32_e32 v92, 16, v84
	v_and_b32_e32 v84, 0xffff0000, v84
	v_mul_f32_e32 v104, v7, v83
	v_mul_f32_e32 v105, v23, v83
	v_mul_f32_e32 v83, v39, v83
	v_fmac_f32_e32 v102, v4, v90
	v_fmac_f32_e32 v103, v20, v90
	v_fmac_f32_e32 v82, v36, v90
	v_add_f32_e32 v79, v79, v100
	v_add_f32_e32 v80, v86, v101
	v_add_f32_e32 v78, v78, v81
	v_lshlrev_b32_e32 v93, 16, v85
	v_and_b32_e32 v85, 0xffff0000, v85
	v_mul_f32_e32 v106, v13, v84
	v_mul_f32_e32 v107, v29, v84
	v_mul_f32_e32 v84, v45, v84
	v_fmac_f32_e32 v104, v6, v91
	v_fmac_f32_e32 v105, v22, v91
	v_fmac_f32_e32 v83, v38, v91
	v_add_f32_e32 v79, v79, v102
	v_add_f32_e32 v80, v80, v103
	v_add_f32_e32 v78, v78, v82
	v_mul_f32_e32 v108, v15, v85
	v_mul_f32_e32 v109, v31, v85
	v_mul_f32_e32 v85, v47, v85
	v_fmac_f32_e32 v106, v12, v92
	v_fmac_f32_e32 v107, v28, v92
	v_fmac_f32_e32 v84, v44, v92
	v_add_f32_e32 v79, v79, v104
	v_add_f32_e32 v80, v80, v105
	v_add_f32_e32 v78, v78, v83
	v_fmac_f32_e32 v108, v14, v93
	v_fmac_f32_e32 v109, v30, v93
	v_fmac_f32_e32 v85, v46, v93
	v_add_f32_e32 v79, v79, v106
	v_add_f32_e32 v80, v80, v107
	v_add_f32_e32 v78, v78, v84
	v_add_f32_e32 v79, v79, v108
	v_add_f32_e32 v80, v80, v109
	v_add_f32_e32 v78, v78, v85
	v_add_f32_dpp v79, v79, v79 quad_perm:[1,0,3,2] row_mask:0xf bank_mask:0xf
	v_add_f32_dpp v80, v80, v80 quad_perm:[1,0,3,2] row_mask:0xf bank_mask:0xf
	v_add_f32_dpp v78, v78, v78 quad_perm:[1,0,3,2] row_mask:0xf bank_mask:0xf
	v_add_f32_dpp v79, v79, v79 quad_perm:[2,3,0,1] row_mask:0xf bank_mask:0xf
	v_add_f32_dpp v80, v80, v80 quad_perm:[2,3,0,1] row_mask:0xf bank_mask:0xf
	v_add_f32_dpp v78, v78, v78 quad_perm:[2,3,0,1] row_mask:0xf bank_mask:0xf
	v_add_f32_dpp v79, v79, v79 row_half_mirror row_mask:0xf bank_mask:0xf
	v_add_f32_dpp v80, v80, v80 row_half_mirror row_mask:0xf bank_mask:0xf
	v_add_f32_dpp v78, v78, v78 row_half_mirror row_mask:0xf bank_mask:0xf
	v_add_f32_dpp v79, v79, v79 row_mirror row_mask:0xf bank_mask:0xf
	v_add_f32_dpp v80, v80, v80 row_mirror row_mask:0xf bank_mask:0xf
	v_add_f32_dpp v81, v78, v78 row_mirror row_mask:0xf bank_mask:0xf
	v_mov_b32_e32 v78, v79
	s_nop 1
	v_permlane16_swap_b32_e32 v79, v78
	s_nop 0
	v_mov_b32_e32 v82, v80
	s_nop 1
	v_permlane16_swap_b32_e32 v80, v82
	s_nop 0
	v_mov_b32_e32 v83, v81
	s_nop 1
	v_permlane16_swap_b32_e32 v81, v83
	s_nop 0
	v_add_f32_e32 v78, v79, v78
	v_add_f32_e32 v79, v80, v82
	v_add_f32_e32 v81, v81, v83
	ds_bpermute_b32 v80, v76, v78
	ds_bpermute_b32 v82, v76, v79
	ds_bpermute_b32 v83, v76, v81
	s_and_saveexec_b64 s[36:37], s[4:5]
	s_cbranch_execz .LBB0_238
	s_waitcnt lgkmcnt(2)
	v_add_f32_e32 v78, v78, v80
	global_store_dword v[62:63], v78, off sc1
	v_add_co_u32_e32 v78, vcc, 0x5000, v62
	s_waitcnt lgkmcnt(1)
	v_add_f32_e32 v82, v79, v82
	v_addc_co_u32_e32 v79, vcc, 0, v63, vcc
	global_store_dword v[78:79], v82, off offset:2048 sc1
	v_add_co_u32_e32 v78, vcc, 0xb000, v62
	s_waitcnt lgkmcnt(0)
	v_add_f32_e32 v81, v81, v83
	v_addc_co_u32_e32 v79, vcc, 0, v63, vcc
	global_store_dword v[78:79], v81, off sc1
	s_branch .LBB0_238

.LBB0_266:
	v_add_u32_e32 v164, s76, v173
	v_and_b32_e32 v222, 31, v199
	v_bfe_u32 v223, v199, 5, 1
	v_lshlrev_b32_e32 v224, 2, v223
	v_sub_u32_e32 v222, v222, v224
	v_add_u32_e32 v224, s76, v173
	v_add_lshl_u32 v222, v222, v224, 2
	v_lshlrev_b32_e32 v223, 4, v223
	global_load_dword v194, v222, s[18:19]
	v_add_u32_e32 v224, 0x10000, v222
	global_load_dword v195, v224, s[18:19]
	v_add_u32_e32 v224, 0x20000, v222
	global_load_dword v196, v224, s[18:19]
	v_add_u32_e32 v224, 0x30000, v222
	global_load_dword v197, v224, s[18:19]
	v_add_u32_e32 v224, 0x40000, v222
	global_load_dword v202, v224, s[18:19]
	v_add_u32_e32 v224, 0x50000, v222
	global_load_dword v203, v224, s[18:19]
	v_add_u32_e32 v224, 0x60000, v222
	global_load_dword v204, v224, s[18:19]
	v_add_u32_e32 v224, 0x70000, v222
	global_load_dword v205, v224, s[18:19]
	s_waitcnt vmcnt(0)
	v_add_f32_e32 v194, v194, v195
	v_add_f32_e32 v196, v196, v197
	v_add_f32_e32 v202, v202, v203
	v_add_f32_e32 v204, v204, v205
	v_add_f32_e32 v194, v194, v196
	v_add_f32_e32 v202, v202, v204
	v_add_f32_e32 v194, v194, v202
	v_fmamk_f32 v194, v194, 0x3a800000, v209
	v_rsq_f32_e32 v194, v194
	s_nop 1
	ds_bpermute_b32 v225, v223, v194
	ds_bpermute_b32 v230, v223, v194 offset:4
	ds_bpermute_b32 v231, v223, v194 offset:8
	ds_bpermute_b32 v232, v223, v194 offset:12
	ds_bpermute_b32 v233, v223, v194 offset:32
	ds_bpermute_b32 v234, v223, v194 offset:36
	ds_bpermute_b32 v235, v223, v194 offset:40
	ds_bpermute_b32 v236, v223, v194 offset:44
	ds_bpermute_b32 v237, v223, v194 offset:64
	ds_bpermute_b32 v238, v223, v194 offset:68
	ds_bpermute_b32 v239, v223, v194 offset:72
	ds_bpermute_b32 v240, v223, v194 offset:76
	ds_bpermute_b32 v241, v223, v194 offset:96
	ds_bpermute_b32 v242, v223, v194 offset:100
	ds_bpermute_b32 v243, v223, v194 offset:104
	ds_bpermute_b32 v244, v223, v194 offset:108
	s_waitcnt lgkmcnt(0)
	s_lshl_b64 s[80:81], s[80:81], 2
	s_add_u32 s80, s84, s80
	s_addc_u32 s81, s85, s81
	s_cmp_gt_i32 s95, 23
	v_or_b32_e32 v92, 16, v164
	v_ashrrev_i32_e32 v93, 31, v92
	v_lshl_add_u64 v[92:93], v[92:93], 2, s[18:19]
	v_or_b32_e32 v68, 24, v164
	v_add_co_u32_e32 v94, vcc, s91, v92
	v_ashrrev_i32_e32 v69, 31, v68
	s_nop 0
	v_addc_co_u32_e32 v95, vcc, 0, v93, vcc
	v_lshl_add_u64 v[80:81], v[68:69], 2, s[18:19]
	v_add_co_u32_e32 v88, vcc, s90, v80
	s_nop 1
	v_addc_co_u32_e32 v89, vcc, 0, v81, vcc
	v_add_co_u32_e32 v84, vcc, s91, v80
	s_nop 1
	v_addc_co_u32_e32 v85, vcc, 0, v81, vcc
	v_add_co_u32_e32 v80, vcc, s92, v80
	s_nop 1
	v_addc_co_u32_e32 v81, vcc, 0, v81, vcc
	v_or_b32_e32 v76, s78, v156
	v_ashrrev_i32_e32 v77, 31, v76
	v_lshl_add_u64 v[64:65], v[76:77], 2, s[80:81]
	global_load_dword v81, v[64:65], off
	global_load_dword v80, v[64:65], off offset:128
	global_load_dword v82, v[64:65], off offset:256
	global_load_dword v83, v[64:65], off offset:384
	v_mov_b32_e32 v65, v48
	v_mov_b32_e32 v48, v33
	v_mov_b32_e32 v33, v50
	v_mov_b32_e32 v50, v35
	s_mov_b64 s[80:81], -1
	v_mov_b32_e32 v94, v234
	v_mov_b32_e32 v96, v235
	v_mov_b32_e32 v98, v236
	v_mov_b32_e32 v100, v237
	v_mov_b32_e32 v84, v225
	v_mov_b32_e32 v102, v238
	v_mov_b32_e32 v86, v230
	v_mov_b32_e32 v104, v239
	v_mov_b32_e32 v88, v231
	v_mov_b32_e32 v106, v240
	v_mov_b32_e32 v90, v232
	v_mov_b32_e32 v108, v241
	v_mov_b32_e32 v92, v233
	v_mov_b32_e32 v110, v242
	v_mov_b32_e32 v112, v243
	v_mov_b32_e32 v114, v244
	v_mov_b32_e32 v64, v32
	v_mov_b32_e32 v32, v34
	s_waitcnt vmcnt(2)
	v_pk_fma_f32 v[72:73], v[32:33], v[88:89], v[80:81] op_sel_hi:[1,0,1]
	v_mov_b32_e32 v32, v36
	v_mov_b32_e32 v33, v52
	v_pk_fma_f32 v[68:69], v[32:33], v[92:93], v[80:81] op_sel_hi:[1,0,1]
	v_mov_b32_e32 v32, v38
	v_mov_b32_e32 v33, v54
	v_pk_fma_f32 v[78:79], v[64:65], v[84:85], v[80:81] op_sel_hi:[1,0,1]
	v_mov_b32_e32 v52, v37
	v_pk_fma_f32 v[64:65], v[32:33], v[96:97], v[80:81] op_sel_hi:[1,0,1]
	v_mov_b32_e32 v32, v40
	v_mov_b32_e32 v33, v56
	v_pk_fma_f32 v[66:67], v[52:53], v[94:95], v[80:81] op_sel_hi:[1,0,1]
	v_pk_fma_f32 v[52:53], v[32:33], v[100:101], v[80:81] op_sel_hi:[1,0,1]
	v_mov_b32_e32 v32, v42
	v_mov_b32_e32 v33, v58
	v_pk_fma_f32 v[74:75], v[48:49], v[86:87], v[80:81] op_sel_hi:[1,0,1]
	v_pk_fma_f32 v[48:49], v[32:33], v[104:105], v[80:81] op_sel_hi:[1,0,1]
	v_mov_b32_e32 v32, v44
	v_mov_b32_e32 v33, v60
	v_mov_b32_e32 v54, v39
	v_mov_b32_e32 v56, v41
	v_mov_b32_e32 v58, v43
	v_pk_fma_f32 v[38:39], v[32:33], v[108:109], v[80:81] op_sel_hi:[1,0,1]
	v_mov_b32_e32 v60, v45
	v_mov_b32_e32 v32, v46
	v_mov_b32_e32 v33, v62
	v_mov_b32_e32 v62, v47
	v_pk_fma_f32 v[70:71], v[50:51], v[90:91], v[80:81] op_sel_hi:[1,0,1]
	v_pk_fma_f32 v[54:55], v[54:55], v[98:99], v[80:81] op_sel_hi:[1,0,1]
	v_pk_fma_f32 v[50:51], v[56:57], v[102:103], v[80:81] op_sel_hi:[1,0,1]
	v_pk_fma_f32 v[40:41], v[58:59], v[106:107], v[80:81] op_sel_hi:[1,0,1]
	v_pk_fma_f32 v[36:37], v[60:61], v[110:111], v[80:81] op_sel_hi:[1,0,1]
	v_pk_fma_f32 v[34:35], v[32:33], v[112:113], v[80:81] op_sel_hi:[1,0,1]
	v_pk_fma_f32 v[32:33], v[62:63], v[114:115], v[80:81] op_sel_hi:[1,0,1]
	s_waitcnt vmcnt(1)
	v_fma_f32 v57, v16, v84, v82
	v_fma_f32 v47, v17, v86, v82
	v_fma_f32 v46, v18, v88, v82
	v_fma_f32 v45, v19, v90, v82
	v_fma_f32 v44, v20, v92, v82
	v_fma_f32 v43, v21, v94, v82
	v_fma_f32 v42, v22, v96, v82
	v_fma_f32 v23, v23, v98, v82
	v_fma_f32 v22, v24, v100, v82
	v_fma_f32 v21, v25, v102, v82
	v_fma_f32 v20, v26, v104, v82
	v_fma_f32 v19, v27, v106, v82
	v_fma_f32 v18, v28, v108, v82
	v_fma_f32 v17, v29, v110, v82
	v_fma_f32 v16, v30, v112, v82
	v_fmac_f32_e32 v82, v31, v114
	s_waitcnt vmcnt(0)
	v_fma_f32 v56, v0, v84, v83
	v_fma_f32 v31, v1, v86, v83
	v_fma_f32 v30, v2, v88, v83
	v_fma_f32 v29, v3, v90, v83
	v_fma_f32 v28, v4, v92, v83
	v_fma_f32 v27, v5, v94, v83
	v_fma_f32 v26, v6, v96, v83
	v_fma_f32 v25, v7, v98, v83
	v_fma_f32 v24, v8, v100, v83
	v_fma_f32 v9, v9, v102, v83
	v_fma_f32 v8, v10, v104, v83
	v_fma_f32 v7, v11, v106, v83
	v_fma_f32 v6, v12, v108, v83
	v_fma_f32 v5, v13, v110, v83
	v_fma_f32 v4, v14, v112, v83
	v_fmac_f32_e32 v83, v15, v114
	s_cbranch_scc0 .LBB0_496
	v_cndmask_b32_e64 v0, 0, 1, s[4:5]
	s_cmp_gt_u32 s10, 4
	v_cmp_ne_u32_e64 s[4:5], 1, v0
	s_cbranch_scc0 .LBB0_333
	v_mov_b32_e32 v0, s93
	ds_read_b64 v[0:1], v0
	v_and_b32_e32 v11, 64, v214
	v_xor_b32_e32 v10, 1, v214
	v_add_u32_e32 v13, 64, v11
	v_pk_mul_f32 v[2:3], v[78:79], v[78:79]
	s_waitcnt lgkmcnt(0)
	v_readfirstlane_b32 s80, v0
	v_readfirstlane_b32 s81, v1
	s_nop 4
	global_load_dword v1, v210, s[80:81] offset:1280
	global_load_dword v0, v210, s[80:81] offset:1408
	v_cmp_lt_i32_e32 vcc, v10, v13
	v_add_f32_e32 v2, v3, v2
	v_xor_b32_e32 v11, 4, v214
	v_cndmask_b32_e32 v3, v214, v10, vcc
	v_lshlrev_b32_e32 v14, 2, v3
	v_xor_b32_e32 v10, 2, v214
	v_cmp_lt_i32_e32 vcc, v10, v13
	v_xor_b32_e32 v12, 8, v214
	v_xor_b32_e32 v15, 16, v214
	v_cndmask_b32_e32 v10, v214, v10, vcc
	v_lshlrev_b32_e32 v10, 2, v10
	v_add_f32_dpp v2, v2, v2 quad_perm:[1,0,3,2] row_mask:0xf bank_mask:0xf
	v_cmp_lt_i32_e32 vcc, v11, v13
	s_mov_b64 s[80:81], -1
	v_add_f32_dpp v2, v2, v2 quad_perm:[2,3,0,1] row_mask:0xf bank_mask:0xf
	v_cndmask_b32_e32 v11, v214, v11, vcc
	v_lshlrev_b32_e32 v11, 2, v11
	v_cmp_lt_i32_e32 vcc, v12, v13
	v_add_f32_dpp v2, v2, v2 row_half_mirror row_mask:0xf bank_mask:0xf
	v_cndmask_b32_e32 v12, v214, v12, vcc
	v_lshlrev_b32_e32 v12, 2, v12
	v_cmp_lt_i32_e32 vcc, v15, v13
	v_add_f32_dpp v2, v2, v2 row_mirror row_mask:0xf bank_mask:0xf
	v_cndmask_b32_e32 v13, v214, v15, vcc
	v_lshlrev_b32_e32 v13, 2, v13
	v_mov_b32_e32 v3, v2
	s_nop 1
	v_permlane16_swap_b32_e32 v2, v3
	s_nop 0
	s_and_b64 vcc, exec, s[4:5]
	v_add_f32_e32 v2, v2, v3
	v_fmamk_f32 v2, v2, 0x3c800000, v209
	v_rsq_f32_e32 v2, v2
	s_waitcnt vmcnt(0)
	v_pk_mul_f32 v[2:3], v[0:1], v[2:3] op_sel_hi:[1,0]
	s_nop 0
	v_pk_mul_f32 v[2:3], v[78:79], v[2:3]
	s_cbranch_vccnz .LBB0_270
	v_lshl_or_b32 v58, v164, 6, v156
	v_ashrrev_i32_e32 v59, 31, v58
	v_lshl_add_u64 v[58:59], v[58:59], 2, s[24:25]
	s_mov_b64 s[80:81], 0
	global_store_dword v[58:59], v3, off sc1
	global_store_dword v[58:59], v2, off offset:128 sc1

.LBB0_272:
	v_cvt_pk_bf16_f32 v60, v2, s0
	v_add_u32_e32 v2, s11, v173
	v_mul_lo_u32 v61, v2, s94
	v_or_b32_e32 v2, v61, v174
	v_cvt_pk_bf16_f32 v15, v3, s0
	v_ashrrev_i32_e32 v3, 31, v2
	v_lshl_add_u64 v[2:3], v[2:3], 1, s[22:23]
	global_store_short v[2:3], v15, off sc1
	v_or_b32_e32 v2, v61, v175
	v_ashrrev_i32_e32 v3, 31, v2
	v_lshl_add_u64 v[2:3], v[2:3], 1, s[22:23]
	v_or_b32_e32 v58, 0xc0, v61
	global_store_short v[2:3], v60, off sc1
	v_add_u32_e32 v2, v58, v174
	v_ashrrev_i32_e32 v3, 31, v2
	v_lshl_add_u64 v[2:3], v[2:3], 1, s[22:23]
	global_store_short v[2:3], v15, off sc1
	v_add_u32_e32 v2, v58, v175
	v_ashrrev_i32_e32 v3, 31, v2
	v_lshl_add_u64 v[2:3], v[2:3], 1, s[22:23]
	v_or_b32_e32 v58, 0x180, v61
	global_store_short v[2:3], v60, off sc1
	v_add_u32_e32 v2, v58, v174
	v_ashrrev_i32_e32 v3, 31, v2
	v_lshl_add_u64 v[2:3], v[2:3], 1, s[22:23]
	global_store_short v[2:3], v15, off sc1
	v_add_u32_e32 v2, v58, v175
	v_ashrrev_i32_e32 v3, 31, v2
	v_lshl_add_u64 v[2:3], v[2:3], 1, s[22:23]
	v_add_u32_e32 v58, 0x240, v61
	global_store_short v[2:3], v60, off sc1
	v_or_b32_e32 v2, v58, v174
	v_ashrrev_i32_e32 v3, 31, v2
	v_lshl_add_u64 v[2:3], v[2:3], 1, s[22:23]
	global_store_short v[2:3], v15, off sc1
	v_or_b32_e32 v2, v58, v175
	v_ashrrev_i32_e32 v3, 31, v2
	v_lshl_add_u64 v[2:3], v[2:3], 1, s[22:23]
	v_add_u32_e32 v58, 0x300, v61
	global_store_short v[2:3], v60, off sc1
	v_or_b32_e32 v2, v58, v174
	v_ashrrev_i32_e32 v3, 31, v2
	v_lshl_add_u64 v[2:3], v[2:3], 1, s[22:23]
	global_store_short v[2:3], v15, off sc1
	v_or_b32_e32 v2, v58, v175
	v_pk_mul_f32 v[58:59], v[74:75], v[74:75]
	v_ashrrev_i32_e32 v3, 31, v2
	v_add_f32_e32 v58, v59, v58
	v_lshl_add_u64 v[2:3], v[2:3], 1, s[22:23]
	v_add_u32_e32 v62, 0x3c0, v61
	global_store_short v[2:3], v60, off sc1
	v_add_u32_e32 v2, v62, v174
	s_waitcnt lgkmcnt(0)
	v_add_f32_dpp v58, v58, v58 quad_perm:[1,0,3,2] row_mask:0xf bank_mask:0xf
	v_ashrrev_i32_e32 v3, 31, v2
	v_lshl_add_u64 v[2:3], v[2:3], 1, s[22:23]
	global_store_short v[2:3], v15, off sc1
	v_add_u32_e32 v2, v62, v175
	v_add_f32_dpp v58, v58, v58 quad_perm:[2,3,0,1] row_mask:0xf bank_mask:0xf
	v_ashrrev_i32_e32 v3, 31, v2
	v_lshl_add_u64 v[2:3], v[2:3], 1, s[22:23]
	v_add_u32_e32 v62, 0x480, v61
	global_store_short v[2:3], v60, off sc1
	v_add_f32_dpp v58, v58, v58 row_half_mirror row_mask:0xf bank_mask:0xf
	v_add_u32_e32 v2, v62, v174
	v_ashrrev_i32_e32 v3, 31, v2
	v_lshl_add_u64 v[2:3], v[2:3], 1, s[22:23]
	global_store_short v[2:3], v15, off sc1
	v_add_u32_e32 v2, v62, v175
	v_add_f32_dpp v58, v58, v58 row_mirror row_mask:0xf bank_mask:0xf
	v_ashrrev_i32_e32 v3, 31, v2
	v_mov_b32_e32 v59, v58
	s_nop 1
	v_permlane16_swap_b32_e32 v58, v59
	s_nop 0
	v_lshl_add_u64 v[2:3], v[2:3], 1, s[22:23]
	v_add_u32_e32 v61, 0x540, v61
	global_store_short v[2:3], v60, off sc1
	v_or_b32_e32 v2, v61, v174
	v_ashrrev_i32_e32 v3, 31, v2
	v_lshl_add_u64 v[2:3], v[2:3], 1, s[22:23]
	global_store_short v[2:3], v15, off sc1
	v_add_f32_e32 v3, v58, v59
	v_fmamk_f32 v3, v3, 0x3c800000, v209
	v_rsq_f32_e32 v58, v3
	v_or_b32_e32 v2, v61, v175
	v_ashrrev_i32_e32 v3, 31, v2
	v_lshl_add_u64 v[2:3], v[2:3], 1, s[22:23]
	global_store_short v[2:3], v60, off sc1
	v_pk_mul_f32 v[2:3], v[0:1], v[58:59] op_sel_hi:[1,0]
	s_and_b64 vcc, exec, s[4:5]
	v_pk_mul_f32 v[2:3], v[74:75], v[2:3]
	s_mov_b64 s[80:81], -1
	s_cbranch_vccnz .LBB0_274
	v_add_u32_e32 v15, s76, v176
	v_lshl_or_b32 v58, v15, 6, v156
	v_ashrrev_i32_e32 v59, 31, v58
	v_lshl_add_u64 v[58:59], v[58:59], 2, s[24:25]
	s_mov_b64 s[80:81], 0
	global_store_dword v[58:59], v3, off sc1
	global_store_dword v[58:59], v2, off offset:128 sc1

.LBB0_276:
	v_cvt_pk_bf16_f32 v60, v2, s0
	v_add_u32_e32 v2, s11, v176
	v_mul_lo_u32 v61, v2, s94
	v_or_b32_e32 v2, v61, v174
	v_cvt_pk_bf16_f32 v15, v3, s0
	v_ashrrev_i32_e32 v3, 31, v2
	v_lshl_add_u64 v[2:3], v[2:3], 1, s[22:23]
	global_store_short v[2:3], v15, off sc1
	v_or_b32_e32 v2, v61, v175
	v_ashrrev_i32_e32 v3, 31, v2
	v_lshl_add_u64 v[2:3], v[2:3], 1, s[22:23]
	v_or_b32_e32 v58, 0xc0, v61
	global_store_short v[2:3], v60, off sc1
	v_add_u32_e32 v2, v58, v174
	v_ashrrev_i32_e32 v3, 31, v2
	v_lshl_add_u64 v[2:3], v[2:3], 1, s[22:23]
	global_store_short v[2:3], v15, off sc1
	v_add_u32_e32 v2, v58, v175
	v_ashrrev_i32_e32 v3, 31, v2
	v_lshl_add_u64 v[2:3], v[2:3], 1, s[22:23]
	v_or_b32_e32 v58, 0x180, v61
	global_store_short v[2:3], v60, off sc1
	v_add_u32_e32 v2, v58, v174
	v_ashrrev_i32_e32 v3, 31, v2
	v_lshl_add_u64 v[2:3], v[2:3], 1, s[22:23]
	global_store_short v[2:3], v15, off sc1
	v_add_u32_e32 v2, v58, v175
	v_ashrrev_i32_e32 v3, 31, v2
	v_lshl_add_u64 v[2:3], v[2:3], 1, s[22:23]
	v_add_u32_e32 v58, 0x240, v61
	global_store_short v[2:3], v60, off sc1
	v_or_b32_e32 v2, v58, v174
	v_ashrrev_i32_e32 v3, 31, v2
	v_lshl_add_u64 v[2:3], v[2:3], 1, s[22:23]
	global_store_short v[2:3], v15, off sc1
	v_or_b32_e32 v2, v58, v175
	v_ashrrev_i32_e32 v3, 31, v2
	v_lshl_add_u64 v[2:3], v[2:3], 1, s[22:23]
	v_add_u32_e32 v58, 0x300, v61
	global_store_short v[2:3], v60, off sc1
	v_or_b32_e32 v2, v58, v174
	v_ashrrev_i32_e32 v3, 31, v2
	v_lshl_add_u64 v[2:3], v[2:3], 1, s[22:23]
	global_store_short v[2:3], v15, off sc1
	v_or_b32_e32 v2, v58, v175
	v_pk_mul_f32 v[58:59], v[72:73], v[72:73]
	v_ashrrev_i32_e32 v3, 31, v2
	v_add_f32_e32 v58, v59, v58
	v_lshl_add_u64 v[2:3], v[2:3], 1, s[22:23]
	v_add_u32_e32 v62, 0x3c0, v61
	global_store_short v[2:3], v60, off sc1
	v_add_u32_e32 v2, v62, v174
	s_waitcnt lgkmcnt(0)
	v_add_f32_dpp v58, v58, v58 quad_perm:[1,0,3,2] row_mask:0xf bank_mask:0xf
	v_ashrrev_i32_e32 v3, 31, v2
	v_lshl_add_u64 v[2:3], v[2:3], 1, s[22:23]
	global_store_short v[2:3], v15, off sc1
	v_add_u32_e32 v2, v62, v175
	v_add_f32_dpp v58, v58, v58 quad_perm:[2,3,0,1] row_mask:0xf bank_mask:0xf
	v_ashrrev_i32_e32 v3, 31, v2
	v_lshl_add_u64 v[2:3], v[2:3], 1, s[22:23]
	v_add_u32_e32 v62, 0x480, v61
	global_store_short v[2:3], v60, off sc1
	v_add_f32_dpp v58, v58, v58 row_half_mirror row_mask:0xf bank_mask:0xf
	v_add_u32_e32 v2, v62, v174
	v_ashrrev_i32_e32 v3, 31, v2
	v_lshl_add_u64 v[2:3], v[2:3], 1, s[22:23]
	global_store_short v[2:3], v15, off sc1
	v_add_u32_e32 v2, v62, v175
	v_add_f32_dpp v58, v58, v58 row_mirror row_mask:0xf bank_mask:0xf
	v_ashrrev_i32_e32 v3, 31, v2
	v_mov_b32_e32 v59, v58
	s_nop 1
	v_permlane16_swap_b32_e32 v58, v59
	s_nop 0
	v_lshl_add_u64 v[2:3], v[2:3], 1, s[22:23]
	v_add_u32_e32 v61, 0x540, v61
	global_store_short v[2:3], v60, off sc1
	v_or_b32_e32 v2, v61, v174
	v_ashrrev_i32_e32 v3, 31, v2
	v_lshl_add_u64 v[2:3], v[2:3], 1, s[22:23]
	global_store_short v[2:3], v15, off sc1
	v_add_f32_e32 v3, v58, v59
	v_fmamk_f32 v3, v3, 0x3c800000, v209
	v_rsq_f32_e32 v58, v3
	v_or_b32_e32 v2, v61, v175
	v_ashrrev_i32_e32 v3, 31, v2
	v_lshl_add_u64 v[2:3], v[2:3], 1, s[22:23]
	global_store_short v[2:3], v60, off sc1
	v_pk_mul_f32 v[2:3], v[0:1], v[58:59] op_sel_hi:[1,0]
	s_and_b64 vcc, exec, s[4:5]
	v_pk_mul_f32 v[2:3], v[72:73], v[2:3]
	s_mov_b64 s[80:81], -1
	s_cbranch_vccnz .LBB0_278
	v_add_u32_e32 v15, s76, v177
	v_lshl_or_b32 v58, v15, 6, v156
	v_ashrrev_i32_e32 v59, 31, v58
	v_lshl_add_u64 v[58:59], v[58:59], 2, s[24:25]
	s_mov_b64 s[80:81], 0
	global_store_dword v[58:59], v3, off sc1
	global_store_dword v[58:59], v2, off offset:128 sc1

.LBB0_280:
	v_cvt_pk_bf16_f32 v60, v2, s0
	v_add_u32_e32 v2, s11, v177
	v_mul_lo_u32 v61, v2, s94
	v_or_b32_e32 v2, v61, v174
	v_cvt_pk_bf16_f32 v15, v3, s0
	v_ashrrev_i32_e32 v3, 31, v2
	v_lshl_add_u64 v[2:3], v[2:3], 1, s[22:23]
	global_store_short v[2:3], v15, off sc1
	v_or_b32_e32 v2, v61, v175
	v_ashrrev_i32_e32 v3, 31, v2
	v_lshl_add_u64 v[2:3], v[2:3], 1, s[22:23]
	v_or_b32_e32 v58, 0xc0, v61
	global_store_short v[2:3], v60, off sc1
	v_add_u32_e32 v2, v58, v174
	v_ashrrev_i32_e32 v3, 31, v2
	v_lshl_add_u64 v[2:3], v[2:3], 1, s[22:23]
	global_store_short v[2:3], v15, off sc1
	v_add_u32_e32 v2, v58, v175
	v_ashrrev_i32_e32 v3, 31, v2
	v_lshl_add_u64 v[2:3], v[2:3], 1, s[22:23]
	v_or_b32_e32 v58, 0x180, v61
	global_store_short v[2:3], v60, off sc1
	v_add_u32_e32 v2, v58, v174
	v_ashrrev_i32_e32 v3, 31, v2
	v_lshl_add_u64 v[2:3], v[2:3], 1, s[22:23]
	global_store_short v[2:3], v15, off sc1
	v_add_u32_e32 v2, v58, v175
	v_ashrrev_i32_e32 v3, 31, v2
	v_lshl_add_u64 v[2:3], v[2:3], 1, s[22:23]
	v_add_u32_e32 v58, 0x240, v61
	global_store_short v[2:3], v60, off sc1
	v_or_b32_e32 v2, v58, v174
	v_ashrrev_i32_e32 v3, 31, v2
	v_lshl_add_u64 v[2:3], v[2:3], 1, s[22:23]
	global_store_short v[2:3], v15, off sc1
	v_or_b32_e32 v2, v58, v175
	v_ashrrev_i32_e32 v3, 31, v2
	v_lshl_add_u64 v[2:3], v[2:3], 1, s[22:23]
	v_add_u32_e32 v58, 0x300, v61
	global_store_short v[2:3], v60, off sc1
	v_or_b32_e32 v2, v58, v174
	v_ashrrev_i32_e32 v3, 31, v2
	v_lshl_add_u64 v[2:3], v[2:3], 1, s[22:23]
	global_store_short v[2:3], v15, off sc1
	v_or_b32_e32 v2, v58, v175
	v_pk_mul_f32 v[58:59], v[70:71], v[70:71]
	v_ashrrev_i32_e32 v3, 31, v2
	v_add_f32_e32 v58, v59, v58
	v_lshl_add_u64 v[2:3], v[2:3], 1, s[22:23]
	v_add_u32_e32 v62, 0x3c0, v61
	global_store_short v[2:3], v60, off sc1
	v_add_u32_e32 v2, v62, v174
	s_waitcnt lgkmcnt(0)
	v_add_f32_dpp v58, v58, v58 quad_perm:[1,0,3,2] row_mask:0xf bank_mask:0xf
	v_ashrrev_i32_e32 v3, 31, v2
	v_lshl_add_u64 v[2:3], v[2:3], 1, s[22:23]
	global_store_short v[2:3], v15, off sc1
	v_add_u32_e32 v2, v62, v175
	v_add_f32_dpp v58, v58, v58 quad_perm:[2,3,0,1] row_mask:0xf bank_mask:0xf
	v_ashrrev_i32_e32 v3, 31, v2
	v_lshl_add_u64 v[2:3], v[2:3], 1, s[22:23]
	v_add_u32_e32 v62, 0x480, v61
	global_store_short v[2:3], v60, off sc1
	v_add_f32_dpp v58, v58, v58 row_half_mirror row_mask:0xf bank_mask:0xf
	v_add_u32_e32 v2, v62, v174
	v_ashrrev_i32_e32 v3, 31, v2
	v_lshl_add_u64 v[2:3], v[2:3], 1, s[22:23]
	global_store_short v[2:3], v15, off sc1
	v_add_u32_e32 v2, v62, v175
	v_add_f32_dpp v58, v58, v58 row_mirror row_mask:0xf bank_mask:0xf
	v_ashrrev_i32_e32 v3, 31, v2
	v_mov_b32_e32 v59, v58
	s_nop 1
	v_permlane16_swap_b32_e32 v58, v59
	s_nop 0
	v_lshl_add_u64 v[2:3], v[2:3], 1, s[22:23]
	v_add_u32_e32 v61, 0x540, v61
	global_store_short v[2:3], v60, off sc1
	v_or_b32_e32 v2, v61, v174
	v_ashrrev_i32_e32 v3, 31, v2
	v_lshl_add_u64 v[2:3], v[2:3], 1, s[22:23]
	global_store_short v[2:3], v15, off sc1
	v_add_f32_e32 v3, v58, v59
	v_fmamk_f32 v3, v3, 0x3c800000, v209
	v_rsq_f32_e32 v58, v3
	v_or_b32_e32 v2, v61, v175
	v_ashrrev_i32_e32 v3, 31, v2
	v_lshl_add_u64 v[2:3], v[2:3], 1, s[22:23]
	global_store_short v[2:3], v60, off sc1
	v_pk_mul_f32 v[2:3], v[0:1], v[58:59] op_sel_hi:[1,0]
	s_and_b64 vcc, exec, s[4:5]
	v_pk_mul_f32 v[2:3], v[70:71], v[2:3]
	s_mov_b64 s[80:81], -1
	s_cbranch_vccnz .LBB0_282
	v_add_u32_e32 v15, s76, v178
	v_lshl_or_b32 v58, v15, 6, v156
	v_ashrrev_i32_e32 v59, 31, v58
	v_lshl_add_u64 v[58:59], v[58:59], 2, s[24:25]
	s_mov_b64 s[80:81], 0
	global_store_dword v[58:59], v3, off sc1
	global_store_dword v[58:59], v2, off offset:128 sc1

.LBB0_284:
	v_cvt_pk_bf16_f32 v60, v2, s0
	v_add_u32_e32 v2, s11, v178
	v_mul_lo_u32 v61, v2, s94
	v_or_b32_e32 v2, v61, v174
	v_cvt_pk_bf16_f32 v15, v3, s0
	v_ashrrev_i32_e32 v3, 31, v2
	v_lshl_add_u64 v[2:3], v[2:3], 1, s[22:23]
	global_store_short v[2:3], v15, off sc1
	v_or_b32_e32 v2, v61, v175
	v_ashrrev_i32_e32 v3, 31, v2
	v_lshl_add_u64 v[2:3], v[2:3], 1, s[22:23]
	v_or_b32_e32 v58, 0xc0, v61
	global_store_short v[2:3], v60, off sc1
	v_add_u32_e32 v2, v58, v174
	v_ashrrev_i32_e32 v3, 31, v2
	v_lshl_add_u64 v[2:3], v[2:3], 1, s[22:23]
	global_store_short v[2:3], v15, off sc1
	v_add_u32_e32 v2, v58, v175
	v_ashrrev_i32_e32 v3, 31, v2
	v_lshl_add_u64 v[2:3], v[2:3], 1, s[22:23]
	v_or_b32_e32 v58, 0x180, v61
	global_store_short v[2:3], v60, off sc1
	v_add_u32_e32 v2, v58, v174
	v_ashrrev_i32_e32 v3, 31, v2
	v_lshl_add_u64 v[2:3], v[2:3], 1, s[22:23]
	global_store_short v[2:3], v15, off sc1
	v_add_u32_e32 v2, v58, v175
	v_ashrrev_i32_e32 v3, 31, v2
	v_lshl_add_u64 v[2:3], v[2:3], 1, s[22:23]
	v_add_u32_e32 v58, 0x240, v61
	global_store_short v[2:3], v60, off sc1
	v_or_b32_e32 v2, v58, v174
	v_ashrrev_i32_e32 v3, 31, v2
	v_lshl_add_u64 v[2:3], v[2:3], 1, s[22:23]
	global_store_short v[2:3], v15, off sc1
	v_or_b32_e32 v2, v58, v175
	v_ashrrev_i32_e32 v3, 31, v2
	v_lshl_add_u64 v[2:3], v[2:3], 1, s[22:23]
	v_add_u32_e32 v58, 0x300, v61
	global_store_short v[2:3], v60, off sc1
	v_or_b32_e32 v2, v58, v174
	v_ashrrev_i32_e32 v3, 31, v2
	v_lshl_add_u64 v[2:3], v[2:3], 1, s[22:23]
	global_store_short v[2:3], v15, off sc1
	v_or_b32_e32 v2, v58, v175
	v_pk_mul_f32 v[58:59], v[68:69], v[68:69]
	v_ashrrev_i32_e32 v3, 31, v2
	v_add_f32_e32 v58, v59, v58
	v_lshl_add_u64 v[2:3], v[2:3], 1, s[22:23]
	v_add_u32_e32 v62, 0x3c0, v61
	global_store_short v[2:3], v60, off sc1
	v_add_u32_e32 v2, v62, v174
	s_waitcnt lgkmcnt(0)
	v_add_f32_dpp v58, v58, v58 quad_perm:[1,0,3,2] row_mask:0xf bank_mask:0xf
	v_ashrrev_i32_e32 v3, 31, v2
	v_lshl_add_u64 v[2:3], v[2:3], 1, s[22:23]
	global_store_short v[2:3], v15, off sc1
	v_add_u32_e32 v2, v62, v175
	v_add_f32_dpp v58, v58, v58 quad_perm:[2,3,0,1] row_mask:0xf bank_mask:0xf
	v_ashrrev_i32_e32 v3, 31, v2
	v_lshl_add_u64 v[2:3], v[2:3], 1, s[22:23]
	v_add_u32_e32 v62, 0x480, v61
	global_store_short v[2:3], v60, off sc1
	v_add_f32_dpp v58, v58, v58 row_half_mirror row_mask:0xf bank_mask:0xf
	v_add_u32_e32 v2, v62, v174
	v_ashrrev_i32_e32 v3, 31, v2
	v_lshl_add_u64 v[2:3], v[2:3], 1, s[22:23]
	global_store_short v[2:3], v15, off sc1
	v_add_u32_e32 v2, v62, v175
	v_add_f32_dpp v58, v58, v58 row_mirror row_mask:0xf bank_mask:0xf
	v_ashrrev_i32_e32 v3, 31, v2
	v_mov_b32_e32 v59, v58
	s_nop 1
	v_permlane16_swap_b32_e32 v58, v59
	s_nop 0
	v_lshl_add_u64 v[2:3], v[2:3], 1, s[22:23]
	v_add_u32_e32 v61, 0x540, v61
	global_store_short v[2:3], v60, off sc1
	v_or_b32_e32 v2, v61, v174
	v_ashrrev_i32_e32 v3, 31, v2
	v_lshl_add_u64 v[2:3], v[2:3], 1, s[22:23]
	global_store_short v[2:3], v15, off sc1
	v_add_f32_e32 v3, v58, v59
	v_fmamk_f32 v3, v3, 0x3c800000, v209
	v_rsq_f32_e32 v58, v3
	v_or_b32_e32 v2, v61, v175
	v_ashrrev_i32_e32 v3, 31, v2
	v_lshl_add_u64 v[2:3], v[2:3], 1, s[22:23]
	global_store_short v[2:3], v60, off sc1
	v_pk_mul_f32 v[2:3], v[0:1], v[58:59] op_sel_hi:[1,0]
	s_and_b64 vcc, exec, s[4:5]
	v_pk_mul_f32 v[2:3], v[68:69], v[2:3]
	s_mov_b64 s[80:81], -1
	s_cbranch_vccnz .LBB0_286
	v_add_u32_e32 v15, s76, v179
	v_lshl_or_b32 v58, v15, 6, v156
	v_ashrrev_i32_e32 v59, 31, v58
	v_lshl_add_u64 v[58:59], v[58:59], 2, s[24:25]
	s_mov_b64 s[80:81], 0
	global_store_dword v[58:59], v3, off sc1
	global_store_dword v[58:59], v2, off offset:128 sc1

.LBB0_288:
	v_cvt_pk_bf16_f32 v60, v2, s0
	v_add_u32_e32 v2, s11, v179
	v_mul_lo_u32 v61, v2, s94
	v_or_b32_e32 v2, v61, v174
	v_cvt_pk_bf16_f32 v15, v3, s0
	v_ashrrev_i32_e32 v3, 31, v2
	v_lshl_add_u64 v[2:3], v[2:3], 1, s[22:23]
	global_store_short v[2:3], v15, off sc1
	v_or_b32_e32 v2, v61, v175
	v_ashrrev_i32_e32 v3, 31, v2
	v_lshl_add_u64 v[2:3], v[2:3], 1, s[22:23]
	v_or_b32_e32 v58, 0xc0, v61
	global_store_short v[2:3], v60, off sc1
	v_add_u32_e32 v2, v58, v174
	v_ashrrev_i32_e32 v3, 31, v2
	v_lshl_add_u64 v[2:3], v[2:3], 1, s[22:23]
	global_store_short v[2:3], v15, off sc1
	v_add_u32_e32 v2, v58, v175
	v_ashrrev_i32_e32 v3, 31, v2
	v_lshl_add_u64 v[2:3], v[2:3], 1, s[22:23]
	v_or_b32_e32 v58, 0x180, v61
	global_store_short v[2:3], v60, off sc1
	v_add_u32_e32 v2, v58, v174
	v_ashrrev_i32_e32 v3, 31, v2
	v_lshl_add_u64 v[2:3], v[2:3], 1, s[22:23]
	global_store_short v[2:3], v15, off sc1
	v_add_u32_e32 v2, v58, v175
	v_ashrrev_i32_e32 v3, 31, v2
	v_lshl_add_u64 v[2:3], v[2:3], 1, s[22:23]
	v_add_u32_e32 v58, 0x240, v61
	global_store_short v[2:3], v60, off sc1
	v_or_b32_e32 v2, v58, v174
	v_ashrrev_i32_e32 v3, 31, v2
	v_lshl_add_u64 v[2:3], v[2:3], 1, s[22:23]
	global_store_short v[2:3], v15, off sc1
	v_or_b32_e32 v2, v58, v175
	v_ashrrev_i32_e32 v3, 31, v2
	v_lshl_add_u64 v[2:3], v[2:3], 1, s[22:23]
	v_add_u32_e32 v58, 0x300, v61
	global_store_short v[2:3], v60, off sc1
	v_or_b32_e32 v2, v58, v174
	v_ashrrev_i32_e32 v3, 31, v2
	v_lshl_add_u64 v[2:3], v[2:3], 1, s[22:23]
	global_store_short v[2:3], v15, off sc1
	v_or_b32_e32 v2, v58, v175
	v_pk_mul_f32 v[58:59], v[66:67], v[66:67]
	v_ashrrev_i32_e32 v3, 31, v2
	v_add_f32_e32 v58, v59, v58
	v_lshl_add_u64 v[2:3], v[2:3], 1, s[22:23]
	v_add_u32_e32 v62, 0x3c0, v61
	global_store_short v[2:3], v60, off sc1
	v_add_u32_e32 v2, v62, v174
	s_waitcnt lgkmcnt(0)
	v_add_f32_dpp v58, v58, v58 quad_perm:[1,0,3,2] row_mask:0xf bank_mask:0xf
	v_ashrrev_i32_e32 v3, 31, v2
	v_lshl_add_u64 v[2:3], v[2:3], 1, s[22:23]
	global_store_short v[2:3], v15, off sc1
	v_add_u32_e32 v2, v62, v175
	v_add_f32_dpp v58, v58, v58 quad_perm:[2,3,0,1] row_mask:0xf bank_mask:0xf
	v_ashrrev_i32_e32 v3, 31, v2
	v_lshl_add_u64 v[2:3], v[2:3], 1, s[22:23]
	v_add_u32_e32 v62, 0x480, v61
	global_store_short v[2:3], v60, off sc1
	v_add_f32_dpp v58, v58, v58 row_half_mirror row_mask:0xf bank_mask:0xf
	v_add_u32_e32 v2, v62, v174
	v_ashrrev_i32_e32 v3, 31, v2
	v_lshl_add_u64 v[2:3], v[2:3], 1, s[22:23]
	global_store_short v[2:3], v15, off sc1
	v_add_u32_e32 v2, v62, v175
	v_add_f32_dpp v58, v58, v58 row_mirror row_mask:0xf bank_mask:0xf
	v_ashrrev_i32_e32 v3, 31, v2
	v_mov_b32_e32 v59, v58
	s_nop 1
	v_permlane16_swap_b32_e32 v58, v59
	s_nop 0
	v_lshl_add_u64 v[2:3], v[2:3], 1, s[22:23]
	v_add_u32_e32 v61, 0x540, v61
	global_store_short v[2:3], v60, off sc1
	v_or_b32_e32 v2, v61, v174
	v_ashrrev_i32_e32 v3, 31, v2
	v_lshl_add_u64 v[2:3], v[2:3], 1, s[22:23]
	global_store_short v[2:3], v15, off sc1
	v_add_f32_e32 v3, v58, v59
	v_fmamk_f32 v3, v3, 0x3c800000, v209
	v_rsq_f32_e32 v58, v3
	v_or_b32_e32 v2, v61, v175
	v_ashrrev_i32_e32 v3, 31, v2
	v_lshl_add_u64 v[2:3], v[2:3], 1, s[22:23]
	global_store_short v[2:3], v60, off sc1
	v_pk_mul_f32 v[2:3], v[0:1], v[58:59] op_sel_hi:[1,0]
	s_and_b64 vcc, exec, s[4:5]
	v_pk_mul_f32 v[2:3], v[66:67], v[2:3]
	s_mov_b64 s[80:81], -1
	s_cbranch_vccnz .LBB0_290
	v_add_u32_e32 v15, s76, v180
	v_lshl_or_b32 v58, v15, 6, v156
	v_ashrrev_i32_e32 v59, 31, v58
	v_lshl_add_u64 v[58:59], v[58:59], 2, s[24:25]
	s_mov_b64 s[80:81], 0
	global_store_dword v[58:59], v3, off sc1
	global_store_dword v[58:59], v2, off offset:128 sc1

.LBB0_292:
	v_cvt_pk_bf16_f32 v60, v2, s0
	v_add_u32_e32 v2, s11, v180
	v_mul_lo_u32 v61, v2, s94
	v_or_b32_e32 v2, v61, v174
	v_cvt_pk_bf16_f32 v15, v3, s0
	v_ashrrev_i32_e32 v3, 31, v2
	v_lshl_add_u64 v[2:3], v[2:3], 1, s[22:23]
	global_store_short v[2:3], v15, off sc1
	v_or_b32_e32 v2, v61, v175
	v_ashrrev_i32_e32 v3, 31, v2
	v_lshl_add_u64 v[2:3], v[2:3], 1, s[22:23]
	v_or_b32_e32 v58, 0xc0, v61
	global_store_short v[2:3], v60, off sc1
	v_add_u32_e32 v2, v58, v174
	v_ashrrev_i32_e32 v3, 31, v2
	v_lshl_add_u64 v[2:3], v[2:3], 1, s[22:23]
	global_store_short v[2:3], v15, off sc1
	v_add_u32_e32 v2, v58, v175
	v_ashrrev_i32_e32 v3, 31, v2
	v_lshl_add_u64 v[2:3], v[2:3], 1, s[22:23]
	v_or_b32_e32 v58, 0x180, v61
	global_store_short v[2:3], v60, off sc1
	v_add_u32_e32 v2, v58, v174
	v_ashrrev_i32_e32 v3, 31, v2
	v_lshl_add_u64 v[2:3], v[2:3], 1, s[22:23]
	global_store_short v[2:3], v15, off sc1
	v_add_u32_e32 v2, v58, v175
	v_ashrrev_i32_e32 v3, 31, v2
	v_lshl_add_u64 v[2:3], v[2:3], 1, s[22:23]
	v_add_u32_e32 v58, 0x240, v61
	global_store_short v[2:3], v60, off sc1
	v_or_b32_e32 v2, v58, v174
	v_ashrrev_i32_e32 v3, 31, v2
	v_lshl_add_u64 v[2:3], v[2:3], 1, s[22:23]
	global_store_short v[2:3], v15, off sc1
	v_or_b32_e32 v2, v58, v175
	v_ashrrev_i32_e32 v3, 31, v2
	v_lshl_add_u64 v[2:3], v[2:3], 1, s[22:23]
	v_add_u32_e32 v58, 0x300, v61
	global_store_short v[2:3], v60, off sc1
	v_or_b32_e32 v2, v58, v174
	v_ashrrev_i32_e32 v3, 31, v2
	v_lshl_add_u64 v[2:3], v[2:3], 1, s[22:23]
	global_store_short v[2:3], v15, off sc1
	v_or_b32_e32 v2, v58, v175
	v_pk_mul_f32 v[58:59], v[64:65], v[64:65]
	v_ashrrev_i32_e32 v3, 31, v2
	v_add_f32_e32 v58, v59, v58
	v_lshl_add_u64 v[2:3], v[2:3], 1, s[22:23]
	v_add_u32_e32 v62, 0x3c0, v61
	global_store_short v[2:3], v60, off sc1
	v_add_u32_e32 v2, v62, v174
	s_waitcnt lgkmcnt(0)
	v_add_f32_dpp v58, v58, v58 quad_perm:[1,0,3,2] row_mask:0xf bank_mask:0xf
	v_ashrrev_i32_e32 v3, 31, v2
	v_lshl_add_u64 v[2:3], v[2:3], 1, s[22:23]
	global_store_short v[2:3], v15, off sc1
	v_add_u32_e32 v2, v62, v175
	v_add_f32_dpp v58, v58, v58 quad_perm:[2,3,0,1] row_mask:0xf bank_mask:0xf
	v_ashrrev_i32_e32 v3, 31, v2
	v_lshl_add_u64 v[2:3], v[2:3], 1, s[22:23]
	v_add_u32_e32 v62, 0x480, v61
	global_store_short v[2:3], v60, off sc1
	v_add_f32_dpp v58, v58, v58 row_half_mirror row_mask:0xf bank_mask:0xf
	v_add_u32_e32 v2, v62, v174
	v_ashrrev_i32_e32 v3, 31, v2
	v_lshl_add_u64 v[2:3], v[2:3], 1, s[22:23]
	global_store_short v[2:3], v15, off sc1
	v_add_u32_e32 v2, v62, v175
	v_add_f32_dpp v58, v58, v58 row_mirror row_mask:0xf bank_mask:0xf
	v_ashrrev_i32_e32 v3, 31, v2
	v_mov_b32_e32 v59, v58
	s_nop 1
	v_permlane16_swap_b32_e32 v58, v59
	s_nop 0
	v_lshl_add_u64 v[2:3], v[2:3], 1, s[22:23]
	v_add_u32_e32 v61, 0x540, v61
	global_store_short v[2:3], v60, off sc1
	v_or_b32_e32 v2, v61, v174
	v_ashrrev_i32_e32 v3, 31, v2
	v_lshl_add_u64 v[2:3], v[2:3], 1, s[22:23]
	global_store_short v[2:3], v15, off sc1
	v_add_f32_e32 v3, v58, v59
	v_fmamk_f32 v3, v3, 0x3c800000, v209
	v_rsq_f32_e32 v58, v3
	v_or_b32_e32 v2, v61, v175
	v_ashrrev_i32_e32 v3, 31, v2
	v_lshl_add_u64 v[2:3], v[2:3], 1, s[22:23]
	global_store_short v[2:3], v60, off sc1
	v_pk_mul_f32 v[2:3], v[0:1], v[58:59] op_sel_hi:[1,0]
	s_and_b64 vcc, exec, s[4:5]
	v_pk_mul_f32 v[2:3], v[64:65], v[2:3]
	s_mov_b64 s[80:81], -1
	s_cbranch_vccnz .LBB0_294
	v_add_u32_e32 v15, s76, v181
	v_lshl_or_b32 v58, v15, 6, v156
	v_ashrrev_i32_e32 v59, 31, v58
	v_lshl_add_u64 v[58:59], v[58:59], 2, s[24:25]
	s_mov_b64 s[80:81], 0
	global_store_dword v[58:59], v3, off sc1
	global_store_dword v[58:59], v2, off offset:128 sc1

.LBB0_296:
	v_cvt_pk_bf16_f32 v60, v2, s0
	v_add_u32_e32 v2, s11, v181
	v_mul_lo_u32 v61, v2, s94
	v_or_b32_e32 v2, v61, v174
	v_cvt_pk_bf16_f32 v15, v3, s0
	v_ashrrev_i32_e32 v3, 31, v2
	v_lshl_add_u64 v[2:3], v[2:3], 1, s[22:23]
	global_store_short v[2:3], v15, off sc1
	v_or_b32_e32 v2, v61, v175
	v_ashrrev_i32_e32 v3, 31, v2
	v_lshl_add_u64 v[2:3], v[2:3], 1, s[22:23]
	v_or_b32_e32 v58, 0xc0, v61
	global_store_short v[2:3], v60, off sc1
	v_add_u32_e32 v2, v58, v174
	v_ashrrev_i32_e32 v3, 31, v2
	v_lshl_add_u64 v[2:3], v[2:3], 1, s[22:23]
	global_store_short v[2:3], v15, off sc1
	v_add_u32_e32 v2, v58, v175
	v_ashrrev_i32_e32 v3, 31, v2
	v_lshl_add_u64 v[2:3], v[2:3], 1, s[22:23]
	v_or_b32_e32 v58, 0x180, v61
	global_store_short v[2:3], v60, off sc1
	v_add_u32_e32 v2, v58, v174
	v_ashrrev_i32_e32 v3, 31, v2
	v_lshl_add_u64 v[2:3], v[2:3], 1, s[22:23]
	global_store_short v[2:3], v15, off sc1
	v_add_u32_e32 v2, v58, v175
	v_ashrrev_i32_e32 v3, 31, v2
	v_lshl_add_u64 v[2:3], v[2:3], 1, s[22:23]
	v_add_u32_e32 v58, 0x240, v61
	global_store_short v[2:3], v60, off sc1
	v_or_b32_e32 v2, v58, v174
	v_ashrrev_i32_e32 v3, 31, v2
	v_lshl_add_u64 v[2:3], v[2:3], 1, s[22:23]
	global_store_short v[2:3], v15, off sc1
	v_or_b32_e32 v2, v58, v175
	v_ashrrev_i32_e32 v3, 31, v2
	v_lshl_add_u64 v[2:3], v[2:3], 1, s[22:23]
	v_add_u32_e32 v58, 0x300, v61
	global_store_short v[2:3], v60, off sc1
	v_or_b32_e32 v2, v58, v174
	v_ashrrev_i32_e32 v3, 31, v2
	v_lshl_add_u64 v[2:3], v[2:3], 1, s[22:23]
	global_store_short v[2:3], v15, off sc1
	v_or_b32_e32 v2, v58, v175
	v_pk_mul_f32 v[58:59], v[54:55], v[54:55]
	v_ashrrev_i32_e32 v3, 31, v2
	v_add_f32_e32 v58, v59, v58
	v_lshl_add_u64 v[2:3], v[2:3], 1, s[22:23]
	v_add_u32_e32 v62, 0x3c0, v61
	global_store_short v[2:3], v60, off sc1
	v_add_u32_e32 v2, v62, v174
	s_waitcnt lgkmcnt(0)
	v_add_f32_dpp v58, v58, v58 quad_perm:[1,0,3,2] row_mask:0xf bank_mask:0xf
	v_ashrrev_i32_e32 v3, 31, v2
	v_lshl_add_u64 v[2:3], v[2:3], 1, s[22:23]
	global_store_short v[2:3], v15, off sc1
	v_add_u32_e32 v2, v62, v175
	v_add_f32_dpp v58, v58, v58 quad_perm:[2,3,0,1] row_mask:0xf bank_mask:0xf
	v_ashrrev_i32_e32 v3, 31, v2
	v_lshl_add_u64 v[2:3], v[2:3], 1, s[22:23]
	v_add_u32_e32 v62, 0x480, v61
	global_store_short v[2:3], v60, off sc1
	v_add_f32_dpp v58, v58, v58 row_half_mirror row_mask:0xf bank_mask:0xf
	v_add_u32_e32 v2, v62, v174
	v_ashrrev_i32_e32 v3, 31, v2
	v_lshl_add_u64 v[2:3], v[2:3], 1, s[22:23]
	global_store_short v[2:3], v15, off sc1
	v_add_u32_e32 v2, v62, v175
	v_add_f32_dpp v58, v58, v58 row_mirror row_mask:0xf bank_mask:0xf
	v_ashrrev_i32_e32 v3, 31, v2
	v_mov_b32_e32 v59, v58
	s_nop 1
	v_permlane16_swap_b32_e32 v58, v59
	s_nop 0
	v_lshl_add_u64 v[2:3], v[2:3], 1, s[22:23]
	v_add_u32_e32 v61, 0x540, v61
	global_store_short v[2:3], v60, off sc1
	v_or_b32_e32 v2, v61, v174
	v_ashrrev_i32_e32 v3, 31, v2
	v_lshl_add_u64 v[2:3], v[2:3], 1, s[22:23]
	global_store_short v[2:3], v15, off sc1
	v_add_f32_e32 v3, v58, v59
	v_fmamk_f32 v3, v3, 0x3c800000, v209
	v_rsq_f32_e32 v58, v3
	v_or_b32_e32 v2, v61, v175
	v_ashrrev_i32_e32 v3, 31, v2
	v_lshl_add_u64 v[2:3], v[2:3], 1, s[22:23]
	global_store_short v[2:3], v60, off sc1
	v_pk_mul_f32 v[2:3], v[0:1], v[58:59] op_sel_hi:[1,0]
	s_and_b64 vcc, exec, s[4:5]
	v_pk_mul_f32 v[2:3], v[54:55], v[2:3]
	s_mov_b64 s[80:81], -1
	s_cbranch_vccnz .LBB0_298
	v_add_u32_e32 v15, s76, v182
	v_lshl_or_b32 v58, v15, 6, v156
	v_ashrrev_i32_e32 v59, 31, v58
	v_lshl_add_u64 v[58:59], v[58:59], 2, s[24:25]
	s_mov_b64 s[80:81], 0
	global_store_dword v[58:59], v3, off sc1
	global_store_dword v[58:59], v2, off offset:128 sc1

.LBB0_300:
	v_cvt_pk_bf16_f32 v60, v2, s0
	v_add_u32_e32 v2, s11, v182
	v_mul_lo_u32 v61, v2, s94
	v_or_b32_e32 v2, v61, v174
	v_cvt_pk_bf16_f32 v15, v3, s0
	v_ashrrev_i32_e32 v3, 31, v2
	v_lshl_add_u64 v[2:3], v[2:3], 1, s[22:23]
	global_store_short v[2:3], v15, off sc1
	v_or_b32_e32 v2, v61, v175
	v_ashrrev_i32_e32 v3, 31, v2
	v_lshl_add_u64 v[2:3], v[2:3], 1, s[22:23]
	v_or_b32_e32 v58, 0xc0, v61
	global_store_short v[2:3], v60, off sc1
	v_add_u32_e32 v2, v58, v174
	v_ashrrev_i32_e32 v3, 31, v2
	v_lshl_add_u64 v[2:3], v[2:3], 1, s[22:23]
	global_store_short v[2:3], v15, off sc1
	v_add_u32_e32 v2, v58, v175
	v_ashrrev_i32_e32 v3, 31, v2
	v_lshl_add_u64 v[2:3], v[2:3], 1, s[22:23]
	v_or_b32_e32 v58, 0x180, v61
	global_store_short v[2:3], v60, off sc1
	v_add_u32_e32 v2, v58, v174
	v_ashrrev_i32_e32 v3, 31, v2
	v_lshl_add_u64 v[2:3], v[2:3], 1, s[22:23]
	global_store_short v[2:3], v15, off sc1
	v_add_u32_e32 v2, v58, v175
	v_ashrrev_i32_e32 v3, 31, v2
	v_lshl_add_u64 v[2:3], v[2:3], 1, s[22:23]
	v_add_u32_e32 v58, 0x240, v61
	global_store_short v[2:3], v60, off sc1
	v_or_b32_e32 v2, v58, v174
	v_ashrrev_i32_e32 v3, 31, v2
	v_lshl_add_u64 v[2:3], v[2:3], 1, s[22:23]
	global_store_short v[2:3], v15, off sc1
	v_or_b32_e32 v2, v58, v175
	v_ashrrev_i32_e32 v3, 31, v2
	v_lshl_add_u64 v[2:3], v[2:3], 1, s[22:23]
	v_add_u32_e32 v58, 0x300, v61
	global_store_short v[2:3], v60, off sc1
	v_or_b32_e32 v2, v58, v174
	v_ashrrev_i32_e32 v3, 31, v2
	v_lshl_add_u64 v[2:3], v[2:3], 1, s[22:23]
	global_store_short v[2:3], v15, off sc1
	v_or_b32_e32 v2, v58, v175
	v_pk_mul_f32 v[58:59], v[52:53], v[52:53]
	v_ashrrev_i32_e32 v3, 31, v2
	v_add_f32_e32 v58, v59, v58
	v_lshl_add_u64 v[2:3], v[2:3], 1, s[22:23]
	v_add_u32_e32 v62, 0x3c0, v61
	global_store_short v[2:3], v60, off sc1
	v_add_u32_e32 v2, v62, v174
	s_waitcnt lgkmcnt(0)
	v_add_f32_dpp v58, v58, v58 quad_perm:[1,0,3,2] row_mask:0xf bank_mask:0xf
	v_ashrrev_i32_e32 v3, 31, v2
	v_lshl_add_u64 v[2:3], v[2:3], 1, s[22:23]
	global_store_short v[2:3], v15, off sc1
	v_add_u32_e32 v2, v62, v175
	v_add_f32_dpp v58, v58, v58 quad_perm:[2,3,0,1] row_mask:0xf bank_mask:0xf
	v_ashrrev_i32_e32 v3, 31, v2
	v_lshl_add_u64 v[2:3], v[2:3], 1, s[22:23]
	v_add_u32_e32 v62, 0x480, v61
	global_store_short v[2:3], v60, off sc1
	v_add_f32_dpp v58, v58, v58 row_half_mirror row_mask:0xf bank_mask:0xf
	v_add_u32_e32 v2, v62, v174
	v_ashrrev_i32_e32 v3, 31, v2
	v_lshl_add_u64 v[2:3], v[2:3], 1, s[22:23]
	global_store_short v[2:3], v15, off sc1
	v_add_u32_e32 v2, v62, v175
	v_add_f32_dpp v58, v58, v58 row_mirror row_mask:0xf bank_mask:0xf
	v_ashrrev_i32_e32 v3, 31, v2
	v_mov_b32_e32 v59, v58
	s_nop 1
	v_permlane16_swap_b32_e32 v58, v59
	s_nop 0
	v_lshl_add_u64 v[2:3], v[2:3], 1, s[22:23]
	v_add_u32_e32 v61, 0x540, v61
	global_store_short v[2:3], v60, off sc1
	v_or_b32_e32 v2, v61, v174
	v_ashrrev_i32_e32 v3, 31, v2
	v_lshl_add_u64 v[2:3], v[2:3], 1, s[22:23]
	global_store_short v[2:3], v15, off sc1
	v_add_f32_e32 v3, v58, v59
	v_fmamk_f32 v3, v3, 0x3c800000, v209
	v_rsq_f32_e32 v58, v3
	v_or_b32_e32 v2, v61, v175
	v_ashrrev_i32_e32 v3, 31, v2
	v_lshl_add_u64 v[2:3], v[2:3], 1, s[22:23]
	global_store_short v[2:3], v60, off sc1
	v_pk_mul_f32 v[2:3], v[0:1], v[58:59] op_sel_hi:[1,0]
	s_and_b64 vcc, exec, s[4:5]
	v_pk_mul_f32 v[2:3], v[52:53], v[2:3]
	s_mov_b64 s[80:81], -1
	s_cbranch_vccnz .LBB0_302
	v_add_u32_e32 v15, s76, v183
	v_lshl_or_b32 v58, v15, 6, v156
	v_ashrrev_i32_e32 v59, 31, v58
	v_lshl_add_u64 v[58:59], v[58:59], 2, s[24:25]
	s_mov_b64 s[80:81], 0
	global_store_dword v[58:59], v3, off sc1
	global_store_dword v[58:59], v2, off offset:128 sc1

.LBB0_304:
	v_cvt_pk_bf16_f32 v60, v2, s0
	v_add_u32_e32 v2, s11, v183
	v_mul_lo_u32 v61, v2, s94
	v_or_b32_e32 v2, v61, v174
	v_cvt_pk_bf16_f32 v15, v3, s0
	v_ashrrev_i32_e32 v3, 31, v2
	v_lshl_add_u64 v[2:3], v[2:3], 1, s[22:23]
	global_store_short v[2:3], v15, off sc1
	v_or_b32_e32 v2, v61, v175
	v_ashrrev_i32_e32 v3, 31, v2
	v_lshl_add_u64 v[2:3], v[2:3], 1, s[22:23]
	v_or_b32_e32 v58, 0xc0, v61
	global_store_short v[2:3], v60, off sc1
	v_add_u32_e32 v2, v58, v174
	v_ashrrev_i32_e32 v3, 31, v2
	v_lshl_add_u64 v[2:3], v[2:3], 1, s[22:23]
	global_store_short v[2:3], v15, off sc1
	v_add_u32_e32 v2, v58, v175
	v_ashrrev_i32_e32 v3, 31, v2
	v_lshl_add_u64 v[2:3], v[2:3], 1, s[22:23]
	v_or_b32_e32 v58, 0x180, v61
	global_store_short v[2:3], v60, off sc1
	v_add_u32_e32 v2, v58, v174
	v_ashrrev_i32_e32 v3, 31, v2
	v_lshl_add_u64 v[2:3], v[2:3], 1, s[22:23]
	global_store_short v[2:3], v15, off sc1
	v_add_u32_e32 v2, v58, v175
	v_ashrrev_i32_e32 v3, 31, v2
	v_lshl_add_u64 v[2:3], v[2:3], 1, s[22:23]
	v_add_u32_e32 v58, 0x240, v61
	global_store_short v[2:3], v60, off sc1
	v_or_b32_e32 v2, v58, v174
	v_ashrrev_i32_e32 v3, 31, v2
	v_lshl_add_u64 v[2:3], v[2:3], 1, s[22:23]
	global_store_short v[2:3], v15, off sc1
	v_or_b32_e32 v2, v58, v175
	v_ashrrev_i32_e32 v3, 31, v2
	v_lshl_add_u64 v[2:3], v[2:3], 1, s[22:23]
	v_add_u32_e32 v58, 0x300, v61
	global_store_short v[2:3], v60, off sc1
	v_or_b32_e32 v2, v58, v174
	v_ashrrev_i32_e32 v3, 31, v2
	v_lshl_add_u64 v[2:3], v[2:3], 1, s[22:23]
	global_store_short v[2:3], v15, off sc1
	v_or_b32_e32 v2, v58, v175
	v_pk_mul_f32 v[58:59], v[50:51], v[50:51]
	v_ashrrev_i32_e32 v3, 31, v2
	v_add_f32_e32 v58, v59, v58
	v_lshl_add_u64 v[2:3], v[2:3], 1, s[22:23]
	v_add_u32_e32 v62, 0x3c0, v61
	global_store_short v[2:3], v60, off sc1
	v_add_u32_e32 v2, v62, v174
	s_waitcnt lgkmcnt(0)
	v_add_f32_dpp v58, v58, v58 quad_perm:[1,0,3,2] row_mask:0xf bank_mask:0xf
	v_ashrrev_i32_e32 v3, 31, v2
	v_lshl_add_u64 v[2:3], v[2:3], 1, s[22:23]
	global_store_short v[2:3], v15, off sc1
	v_add_u32_e32 v2, v62, v175
	v_add_f32_dpp v58, v58, v58 quad_perm:[2,3,0,1] row_mask:0xf bank_mask:0xf
	v_ashrrev_i32_e32 v3, 31, v2
	v_lshl_add_u64 v[2:3], v[2:3], 1, s[22:23]
	v_add_u32_e32 v62, 0x480, v61
	global_store_short v[2:3], v60, off sc1
	v_add_f32_dpp v58, v58, v58 row_half_mirror row_mask:0xf bank_mask:0xf
	v_add_u32_e32 v2, v62, v174
	v_ashrrev_i32_e32 v3, 31, v2
	v_lshl_add_u64 v[2:3], v[2:3], 1, s[22:23]
	global_store_short v[2:3], v15, off sc1
	v_add_u32_e32 v2, v62, v175
	v_add_f32_dpp v58, v58, v58 row_mirror row_mask:0xf bank_mask:0xf
	v_ashrrev_i32_e32 v3, 31, v2
	v_mov_b32_e32 v59, v58
	s_nop 1
	v_permlane16_swap_b32_e32 v58, v59
	s_nop 0
	v_lshl_add_u64 v[2:3], v[2:3], 1, s[22:23]
	v_add_u32_e32 v61, 0x540, v61
	global_store_short v[2:3], v60, off sc1
	v_or_b32_e32 v2, v61, v174
	v_ashrrev_i32_e32 v3, 31, v2
	v_lshl_add_u64 v[2:3], v[2:3], 1, s[22:23]
	global_store_short v[2:3], v15, off sc1
	v_add_f32_e32 v3, v58, v59
	v_fmamk_f32 v3, v3, 0x3c800000, v209
	v_rsq_f32_e32 v58, v3
	v_or_b32_e32 v2, v61, v175
	v_ashrrev_i32_e32 v3, 31, v2
	v_lshl_add_u64 v[2:3], v[2:3], 1, s[22:23]
	global_store_short v[2:3], v60, off sc1
	v_pk_mul_f32 v[2:3], v[0:1], v[58:59] op_sel_hi:[1,0]
	s_and_b64 vcc, exec, s[4:5]
	v_pk_mul_f32 v[2:3], v[50:51], v[2:3]
	s_mov_b64 s[80:81], -1
	s_cbranch_vccnz .LBB0_306
	v_add_u32_e32 v15, s76, v184
	v_lshl_or_b32 v58, v15, 6, v156
	v_ashrrev_i32_e32 v59, 31, v58
	v_lshl_add_u64 v[58:59], v[58:59], 2, s[24:25]
	s_mov_b64 s[80:81], 0
	global_store_dword v[58:59], v3, off sc1
	global_store_dword v[58:59], v2, off offset:128 sc1

.LBB0_308:
	v_cvt_pk_bf16_f32 v60, v2, s0
	v_add_u32_e32 v2, s11, v184
	v_mul_lo_u32 v61, v2, s94
	v_or_b32_e32 v2, v61, v174
	v_cvt_pk_bf16_f32 v15, v3, s0
	v_ashrrev_i32_e32 v3, 31, v2
	v_lshl_add_u64 v[2:3], v[2:3], 1, s[22:23]
	global_store_short v[2:3], v15, off sc1
	v_or_b32_e32 v2, v61, v175
	v_ashrrev_i32_e32 v3, 31, v2
	v_lshl_add_u64 v[2:3], v[2:3], 1, s[22:23]
	v_or_b32_e32 v58, 0xc0, v61
	global_store_short v[2:3], v60, off sc1
	v_add_u32_e32 v2, v58, v174
	v_ashrrev_i32_e32 v3, 31, v2
	v_lshl_add_u64 v[2:3], v[2:3], 1, s[22:23]
	global_store_short v[2:3], v15, off sc1
	v_add_u32_e32 v2, v58, v175
	v_ashrrev_i32_e32 v3, 31, v2
	v_lshl_add_u64 v[2:3], v[2:3], 1, s[22:23]
	v_or_b32_e32 v58, 0x180, v61
	global_store_short v[2:3], v60, off sc1
	v_add_u32_e32 v2, v58, v174
	v_ashrrev_i32_e32 v3, 31, v2
	v_lshl_add_u64 v[2:3], v[2:3], 1, s[22:23]
	global_store_short v[2:3], v15, off sc1
	v_add_u32_e32 v2, v58, v175
	v_ashrrev_i32_e32 v3, 31, v2
	v_lshl_add_u64 v[2:3], v[2:3], 1, s[22:23]
	v_add_u32_e32 v58, 0x240, v61
	global_store_short v[2:3], v60, off sc1
	v_or_b32_e32 v2, v58, v174
	v_ashrrev_i32_e32 v3, 31, v2
	v_lshl_add_u64 v[2:3], v[2:3], 1, s[22:23]
	global_store_short v[2:3], v15, off sc1
	v_or_b32_e32 v2, v58, v175
	v_ashrrev_i32_e32 v3, 31, v2
	v_lshl_add_u64 v[2:3], v[2:3], 1, s[22:23]
	v_add_u32_e32 v58, 0x300, v61
	global_store_short v[2:3], v60, off sc1
	v_or_b32_e32 v2, v58, v174
	v_ashrrev_i32_e32 v3, 31, v2
	v_lshl_add_u64 v[2:3], v[2:3], 1, s[22:23]
	global_store_short v[2:3], v15, off sc1
	v_or_b32_e32 v2, v58, v175
	v_pk_mul_f32 v[58:59], v[48:49], v[48:49]
	v_ashrrev_i32_e32 v3, 31, v2
	v_add_f32_e32 v58, v59, v58
	v_lshl_add_u64 v[2:3], v[2:3], 1, s[22:23]
	v_add_u32_e32 v62, 0x3c0, v61
	global_store_short v[2:3], v60, off sc1
	v_add_u32_e32 v2, v62, v174
	s_waitcnt lgkmcnt(0)
	v_add_f32_dpp v58, v58, v58 quad_perm:[1,0,3,2] row_mask:0xf bank_mask:0xf
	v_ashrrev_i32_e32 v3, 31, v2
	v_lshl_add_u64 v[2:3], v[2:3], 1, s[22:23]
	global_store_short v[2:3], v15, off sc1
	v_add_u32_e32 v2, v62, v175
	v_add_f32_dpp v58, v58, v58 quad_perm:[2,3,0,1] row_mask:0xf bank_mask:0xf
	v_ashrrev_i32_e32 v3, 31, v2
	v_lshl_add_u64 v[2:3], v[2:3], 1, s[22:23]
	v_add_u32_e32 v62, 0x480, v61
	global_store_short v[2:3], v60, off sc1
	v_add_f32_dpp v58, v58, v58 row_half_mirror row_mask:0xf bank_mask:0xf
	v_add_u32_e32 v2, v62, v174
	v_ashrrev_i32_e32 v3, 31, v2
	v_lshl_add_u64 v[2:3], v[2:3], 1, s[22:23]
	global_store_short v[2:3], v15, off sc1
	v_add_u32_e32 v2, v62, v175
	v_add_f32_dpp v58, v58, v58 row_mirror row_mask:0xf bank_mask:0xf
	v_ashrrev_i32_e32 v3, 31, v2
	v_mov_b32_e32 v59, v58
	s_nop 1
	v_permlane16_swap_b32_e32 v58, v59
	s_nop 0
	v_lshl_add_u64 v[2:3], v[2:3], 1, s[22:23]
	v_add_u32_e32 v61, 0x540, v61
	global_store_short v[2:3], v60, off sc1
	v_or_b32_e32 v2, v61, v174
	v_ashrrev_i32_e32 v3, 31, v2
	v_lshl_add_u64 v[2:3], v[2:3], 1, s[22:23]
	global_store_short v[2:3], v15, off sc1
	v_add_f32_e32 v3, v58, v59
	v_fmamk_f32 v3, v3, 0x3c800000, v209
	v_rsq_f32_e32 v58, v3
	v_or_b32_e32 v2, v61, v175
	v_ashrrev_i32_e32 v3, 31, v2
	v_lshl_add_u64 v[2:3], v[2:3], 1, s[22:23]
	global_store_short v[2:3], v60, off sc1
	v_pk_mul_f32 v[2:3], v[0:1], v[58:59] op_sel_hi:[1,0]
	s_and_b64 vcc, exec, s[4:5]
	v_pk_mul_f32 v[2:3], v[48:49], v[2:3]
	s_mov_b64 s[80:81], -1
	s_cbranch_vccnz .LBB0_310
	v_add_u32_e32 v15, s76, v185
	v_lshl_or_b32 v58, v15, 6, v156
	v_ashrrev_i32_e32 v59, 31, v58
	v_lshl_add_u64 v[58:59], v[58:59], 2, s[24:25]
	s_mov_b64 s[80:81], 0
	global_store_dword v[58:59], v3, off sc1
	global_store_dword v[58:59], v2, off offset:128 sc1

.LBB0_312:
	v_cvt_pk_bf16_f32 v60, v2, s0
	v_add_u32_e32 v2, s11, v185
	v_mul_lo_u32 v61, v2, s94
	v_or_b32_e32 v2, v61, v174
	v_cvt_pk_bf16_f32 v15, v3, s0
	v_ashrrev_i32_e32 v3, 31, v2
	v_lshl_add_u64 v[2:3], v[2:3], 1, s[22:23]
	global_store_short v[2:3], v15, off sc1
	v_or_b32_e32 v2, v61, v175
	v_ashrrev_i32_e32 v3, 31, v2
	v_lshl_add_u64 v[2:3], v[2:3], 1, s[22:23]
	v_or_b32_e32 v58, 0xc0, v61
	global_store_short v[2:3], v60, off sc1
	v_add_u32_e32 v2, v58, v174
	v_ashrrev_i32_e32 v3, 31, v2
	v_lshl_add_u64 v[2:3], v[2:3], 1, s[22:23]
	global_store_short v[2:3], v15, off sc1
	v_add_u32_e32 v2, v58, v175
	v_ashrrev_i32_e32 v3, 31, v2
	v_lshl_add_u64 v[2:3], v[2:3], 1, s[22:23]
	v_or_b32_e32 v58, 0x180, v61
	global_store_short v[2:3], v60, off sc1
	v_add_u32_e32 v2, v58, v174
	v_ashrrev_i32_e32 v3, 31, v2
	v_lshl_add_u64 v[2:3], v[2:3], 1, s[22:23]
	global_store_short v[2:3], v15, off sc1
	v_add_u32_e32 v2, v58, v175
	v_ashrrev_i32_e32 v3, 31, v2
	v_lshl_add_u64 v[2:3], v[2:3], 1, s[22:23]
	v_add_u32_e32 v58, 0x240, v61
	global_store_short v[2:3], v60, off sc1
	v_or_b32_e32 v2, v58, v174
	v_ashrrev_i32_e32 v3, 31, v2
	v_lshl_add_u64 v[2:3], v[2:3], 1, s[22:23]
	global_store_short v[2:3], v15, off sc1
	v_or_b32_e32 v2, v58, v175
	v_ashrrev_i32_e32 v3, 31, v2
	v_lshl_add_u64 v[2:3], v[2:3], 1, s[22:23]
	v_add_u32_e32 v58, 0x300, v61
	global_store_short v[2:3], v60, off sc1
	v_or_b32_e32 v2, v58, v174
	v_ashrrev_i32_e32 v3, 31, v2
	v_lshl_add_u64 v[2:3], v[2:3], 1, s[22:23]
	global_store_short v[2:3], v15, off sc1
	v_or_b32_e32 v2, v58, v175
	v_pk_mul_f32 v[58:59], v[40:41], v[40:41]
	v_ashrrev_i32_e32 v3, 31, v2
	v_add_f32_e32 v58, v59, v58
	v_lshl_add_u64 v[2:3], v[2:3], 1, s[22:23]
	v_add_u32_e32 v62, 0x3c0, v61
	global_store_short v[2:3], v60, off sc1
	v_add_u32_e32 v2, v62, v174
	s_waitcnt lgkmcnt(0)
	v_add_f32_dpp v58, v58, v58 quad_perm:[1,0,3,2] row_mask:0xf bank_mask:0xf
	v_ashrrev_i32_e32 v3, 31, v2
	v_lshl_add_u64 v[2:3], v[2:3], 1, s[22:23]
	global_store_short v[2:3], v15, off sc1
	v_add_u32_e32 v2, v62, v175
	v_add_f32_dpp v58, v58, v58 quad_perm:[2,3,0,1] row_mask:0xf bank_mask:0xf
	v_ashrrev_i32_e32 v3, 31, v2
	v_lshl_add_u64 v[2:3], v[2:3], 1, s[22:23]
	v_add_u32_e32 v62, 0x480, v61
	global_store_short v[2:3], v60, off sc1
	v_add_f32_dpp v58, v58, v58 row_half_mirror row_mask:0xf bank_mask:0xf
	v_add_u32_e32 v2, v62, v174
	v_ashrrev_i32_e32 v3, 31, v2
	v_lshl_add_u64 v[2:3], v[2:3], 1, s[22:23]
	global_store_short v[2:3], v15, off sc1
	v_add_u32_e32 v2, v62, v175
	v_add_f32_dpp v58, v58, v58 row_mirror row_mask:0xf bank_mask:0xf
	v_ashrrev_i32_e32 v3, 31, v2
	v_mov_b32_e32 v59, v58
	s_nop 1
	v_permlane16_swap_b32_e32 v58, v59
	s_nop 0
	v_lshl_add_u64 v[2:3], v[2:3], 1, s[22:23]
	v_add_u32_e32 v61, 0x540, v61
	global_store_short v[2:3], v60, off sc1
	v_or_b32_e32 v2, v61, v174
	v_ashrrev_i32_e32 v3, 31, v2
	v_lshl_add_u64 v[2:3], v[2:3], 1, s[22:23]
	global_store_short v[2:3], v15, off sc1
	v_add_f32_e32 v3, v58, v59
	v_fmamk_f32 v3, v3, 0x3c800000, v209
	v_rsq_f32_e32 v58, v3
	v_or_b32_e32 v2, v61, v175
	v_ashrrev_i32_e32 v3, 31, v2
	v_lshl_add_u64 v[2:3], v[2:3], 1, s[22:23]
	global_store_short v[2:3], v60, off sc1
	v_pk_mul_f32 v[2:3], v[0:1], v[58:59] op_sel_hi:[1,0]
	s_and_b64 vcc, exec, s[4:5]
	v_pk_mul_f32 v[2:3], v[40:41], v[2:3]
	s_mov_b64 s[80:81], -1
	s_cbranch_vccnz .LBB0_314
	v_add_u32_e32 v15, s76, v186
	v_lshl_or_b32 v58, v15, 6, v156
	v_ashrrev_i32_e32 v59, 31, v58
	v_lshl_add_u64 v[58:59], v[58:59], 2, s[24:25]
	s_mov_b64 s[80:81], 0
	global_store_dword v[58:59], v3, off sc1
	global_store_dword v[58:59], v2, off offset:128 sc1

.LBB0_316:
	v_cvt_pk_bf16_f32 v60, v2, s0
	v_add_u32_e32 v2, s11, v186
	v_mul_lo_u32 v61, v2, s94
	v_or_b32_e32 v2, v61, v174
	v_cvt_pk_bf16_f32 v15, v3, s0
	v_ashrrev_i32_e32 v3, 31, v2
	v_lshl_add_u64 v[2:3], v[2:3], 1, s[22:23]
	global_store_short v[2:3], v15, off sc1
	v_or_b32_e32 v2, v61, v175
	v_ashrrev_i32_e32 v3, 31, v2
	v_lshl_add_u64 v[2:3], v[2:3], 1, s[22:23]
	v_or_b32_e32 v58, 0xc0, v61
	global_store_short v[2:3], v60, off sc1
	v_add_u32_e32 v2, v58, v174
	v_ashrrev_i32_e32 v3, 31, v2
	v_lshl_add_u64 v[2:3], v[2:3], 1, s[22:23]
	global_store_short v[2:3], v15, off sc1
	v_add_u32_e32 v2, v58, v175
	v_ashrrev_i32_e32 v3, 31, v2
	v_lshl_add_u64 v[2:3], v[2:3], 1, s[22:23]
	v_or_b32_e32 v58, 0x180, v61
	global_store_short v[2:3], v60, off sc1
	v_add_u32_e32 v2, v58, v174
	v_ashrrev_i32_e32 v3, 31, v2
	v_lshl_add_u64 v[2:3], v[2:3], 1, s[22:23]
	global_store_short v[2:3], v15, off sc1
	v_add_u32_e32 v2, v58, v175
	v_ashrrev_i32_e32 v3, 31, v2
	v_lshl_add_u64 v[2:3], v[2:3], 1, s[22:23]
	v_add_u32_e32 v58, 0x240, v61
	global_store_short v[2:3], v60, off sc1
	v_or_b32_e32 v2, v58, v174
	v_ashrrev_i32_e32 v3, 31, v2
	v_lshl_add_u64 v[2:3], v[2:3], 1, s[22:23]
	global_store_short v[2:3], v15, off sc1
	v_or_b32_e32 v2, v58, v175
	v_ashrrev_i32_e32 v3, 31, v2
	v_lshl_add_u64 v[2:3], v[2:3], 1, s[22:23]
	v_add_u32_e32 v58, 0x300, v61
	global_store_short v[2:3], v60, off sc1
	v_or_b32_e32 v2, v58, v174
	v_ashrrev_i32_e32 v3, 31, v2
	v_lshl_add_u64 v[2:3], v[2:3], 1, s[22:23]
	global_store_short v[2:3], v15, off sc1
	v_or_b32_e32 v2, v58, v175
	v_pk_mul_f32 v[58:59], v[38:39], v[38:39]
	v_ashrrev_i32_e32 v3, 31, v2
	v_add_f32_e32 v58, v59, v58
	v_lshl_add_u64 v[2:3], v[2:3], 1, s[22:23]
	v_add_u32_e32 v62, 0x3c0, v61
	global_store_short v[2:3], v60, off sc1
	v_add_u32_e32 v2, v62, v174
	s_waitcnt lgkmcnt(0)
	v_add_f32_dpp v58, v58, v58 quad_perm:[1,0,3,2] row_mask:0xf bank_mask:0xf
	v_ashrrev_i32_e32 v3, 31, v2
	v_lshl_add_u64 v[2:3], v[2:3], 1, s[22:23]
	global_store_short v[2:3], v15, off sc1
	v_add_u32_e32 v2, v62, v175
	v_add_f32_dpp v58, v58, v58 quad_perm:[2,3,0,1] row_mask:0xf bank_mask:0xf
	v_ashrrev_i32_e32 v3, 31, v2
	v_lshl_add_u64 v[2:3], v[2:3], 1, s[22:23]
	v_add_u32_e32 v62, 0x480, v61
	global_store_short v[2:3], v60, off sc1
	v_add_f32_dpp v58, v58, v58 row_half_mirror row_mask:0xf bank_mask:0xf
	v_add_u32_e32 v2, v62, v174
	v_ashrrev_i32_e32 v3, 31, v2
	v_lshl_add_u64 v[2:3], v[2:3], 1, s[22:23]
	global_store_short v[2:3], v15, off sc1
	v_add_u32_e32 v2, v62, v175
	v_add_f32_dpp v58, v58, v58 row_mirror row_mask:0xf bank_mask:0xf
	v_ashrrev_i32_e32 v3, 31, v2
	v_mov_b32_e32 v59, v58
	s_nop 1
	v_permlane16_swap_b32_e32 v58, v59
	s_nop 0
	v_lshl_add_u64 v[2:3], v[2:3], 1, s[22:23]
	v_add_u32_e32 v61, 0x540, v61
	global_store_short v[2:3], v60, off sc1
	v_or_b32_e32 v2, v61, v174
	v_ashrrev_i32_e32 v3, 31, v2
	v_lshl_add_u64 v[2:3], v[2:3], 1, s[22:23]
	global_store_short v[2:3], v15, off sc1
	v_add_f32_e32 v3, v58, v59
	v_fmamk_f32 v3, v3, 0x3c800000, v209
	v_rsq_f32_e32 v58, v3
	v_or_b32_e32 v2, v61, v175
	v_ashrrev_i32_e32 v3, 31, v2
	v_lshl_add_u64 v[2:3], v[2:3], 1, s[22:23]
	global_store_short v[2:3], v60, off sc1
	v_pk_mul_f32 v[2:3], v[0:1], v[58:59] op_sel_hi:[1,0]
	s_and_b64 vcc, exec, s[4:5]
	v_pk_mul_f32 v[2:3], v[38:39], v[2:3]
	s_mov_b64 s[80:81], -1
	s_cbranch_vccnz .LBB0_318
	v_add_u32_e32 v15, s76, v187
	v_lshl_or_b32 v58, v15, 6, v156
	v_ashrrev_i32_e32 v59, 31, v58
	v_lshl_add_u64 v[58:59], v[58:59], 2, s[24:25]
	s_mov_b64 s[80:81], 0
	global_store_dword v[58:59], v3, off sc1
	global_store_dword v[58:59], v2, off offset:128 sc1

.LBB0_320:
	v_cvt_pk_bf16_f32 v60, v2, s0
	v_add_u32_e32 v2, s11, v187
	v_mul_lo_u32 v61, v2, s94
	v_or_b32_e32 v2, v61, v174
	v_cvt_pk_bf16_f32 v15, v3, s0
	v_ashrrev_i32_e32 v3, 31, v2
	v_lshl_add_u64 v[2:3], v[2:3], 1, s[22:23]
	global_store_short v[2:3], v15, off sc1
	v_or_b32_e32 v2, v61, v175
	v_ashrrev_i32_e32 v3, 31, v2
	v_lshl_add_u64 v[2:3], v[2:3], 1, s[22:23]
	v_or_b32_e32 v58, 0xc0, v61
	global_store_short v[2:3], v60, off sc1
	v_add_u32_e32 v2, v58, v174
	v_ashrrev_i32_e32 v3, 31, v2
	v_lshl_add_u64 v[2:3], v[2:3], 1, s[22:23]
	global_store_short v[2:3], v15, off sc1
	v_add_u32_e32 v2, v58, v175
	v_ashrrev_i32_e32 v3, 31, v2
	v_lshl_add_u64 v[2:3], v[2:3], 1, s[22:23]
	v_or_b32_e32 v58, 0x180, v61
	global_store_short v[2:3], v60, off sc1
	v_add_u32_e32 v2, v58, v174
	v_ashrrev_i32_e32 v3, 31, v2
	v_lshl_add_u64 v[2:3], v[2:3], 1, s[22:23]
	global_store_short v[2:3], v15, off sc1
	v_add_u32_e32 v2, v58, v175
	v_ashrrev_i32_e32 v3, 31, v2
	v_lshl_add_u64 v[2:3], v[2:3], 1, s[22:23]
	v_add_u32_e32 v58, 0x240, v61
	global_store_short v[2:3], v60, off sc1
	v_or_b32_e32 v2, v58, v174
	v_ashrrev_i32_e32 v3, 31, v2
	v_lshl_add_u64 v[2:3], v[2:3], 1, s[22:23]
	global_store_short v[2:3], v15, off sc1
	v_or_b32_e32 v2, v58, v175
	v_ashrrev_i32_e32 v3, 31, v2
	v_lshl_add_u64 v[2:3], v[2:3], 1, s[22:23]
	v_add_u32_e32 v58, 0x300, v61
	global_store_short v[2:3], v60, off sc1
	v_or_b32_e32 v2, v58, v174
	v_ashrrev_i32_e32 v3, 31, v2
	v_lshl_add_u64 v[2:3], v[2:3], 1, s[22:23]
	global_store_short v[2:3], v15, off sc1
	v_or_b32_e32 v2, v58, v175
	v_pk_mul_f32 v[58:59], v[36:37], v[36:37]
	v_ashrrev_i32_e32 v3, 31, v2
	v_add_f32_e32 v58, v59, v58
	v_lshl_add_u64 v[2:3], v[2:3], 1, s[22:23]
	v_add_u32_e32 v62, 0x3c0, v61
	global_store_short v[2:3], v60, off sc1
	v_add_u32_e32 v2, v62, v174
	s_waitcnt lgkmcnt(0)
	v_add_f32_dpp v58, v58, v58 quad_perm:[1,0,3,2] row_mask:0xf bank_mask:0xf
	v_ashrrev_i32_e32 v3, 31, v2
	v_lshl_add_u64 v[2:3], v[2:3], 1, s[22:23]
	global_store_short v[2:3], v15, off sc1
	v_add_u32_e32 v2, v62, v175
	v_add_f32_dpp v58, v58, v58 quad_perm:[2,3,0,1] row_mask:0xf bank_mask:0xf
	v_ashrrev_i32_e32 v3, 31, v2
	v_lshl_add_u64 v[2:3], v[2:3], 1, s[22:23]
	v_add_u32_e32 v62, 0x480, v61
	global_store_short v[2:3], v60, off sc1
	v_add_f32_dpp v58, v58, v58 row_half_mirror row_mask:0xf bank_mask:0xf
	v_add_u32_e32 v2, v62, v174
	v_ashrrev_i32_e32 v3, 31, v2
	v_lshl_add_u64 v[2:3], v[2:3], 1, s[22:23]
	global_store_short v[2:3], v15, off sc1
	v_add_u32_e32 v2, v62, v175
	v_add_f32_dpp v58, v58, v58 row_mirror row_mask:0xf bank_mask:0xf
	v_ashrrev_i32_e32 v3, 31, v2
	v_mov_b32_e32 v59, v58
	s_nop 1
	v_permlane16_swap_b32_e32 v58, v59
	s_nop 0
	v_lshl_add_u64 v[2:3], v[2:3], 1, s[22:23]
	v_add_u32_e32 v61, 0x540, v61
	global_store_short v[2:3], v60, off sc1
	v_or_b32_e32 v2, v61, v174
	v_ashrrev_i32_e32 v3, 31, v2
	v_lshl_add_u64 v[2:3], v[2:3], 1, s[22:23]
	global_store_short v[2:3], v15, off sc1
	v_add_f32_e32 v3, v58, v59
	v_fmamk_f32 v3, v3, 0x3c800000, v209
	v_rsq_f32_e32 v58, v3
	v_or_b32_e32 v2, v61, v175
	v_ashrrev_i32_e32 v3, 31, v2
	v_lshl_add_u64 v[2:3], v[2:3], 1, s[22:23]
	global_store_short v[2:3], v60, off sc1
	v_pk_mul_f32 v[2:3], v[0:1], v[58:59] op_sel_hi:[1,0]
	s_and_b64 vcc, exec, s[4:5]
	v_pk_mul_f32 v[2:3], v[36:37], v[2:3]
	s_mov_b64 s[80:81], -1
	s_cbranch_vccnz .LBB0_322
	v_add_u32_e32 v15, s76, v188
	v_lshl_or_b32 v58, v15, 6, v156
	v_ashrrev_i32_e32 v59, 31, v58
	v_lshl_add_u64 v[58:59], v[58:59], 2, s[24:25]
	s_mov_b64 s[80:81], 0
	global_store_dword v[58:59], v3, off sc1
	global_store_dword v[58:59], v2, off offset:128 sc1

.LBB0_324:
	v_cvt_pk_bf16_f32 v60, v2, s0
	v_add_u32_e32 v2, s11, v188
	v_mul_lo_u32 v61, v2, s94
	v_or_b32_e32 v2, v61, v174
	v_cvt_pk_bf16_f32 v15, v3, s0
	v_ashrrev_i32_e32 v3, 31, v2
	v_lshl_add_u64 v[2:3], v[2:3], 1, s[22:23]
	global_store_short v[2:3], v15, off sc1
	v_or_b32_e32 v2, v61, v175
	v_ashrrev_i32_e32 v3, 31, v2
	v_lshl_add_u64 v[2:3], v[2:3], 1, s[22:23]
	v_or_b32_e32 v58, 0xc0, v61
	global_store_short v[2:3], v60, off sc1
	v_add_u32_e32 v2, v58, v174
	v_ashrrev_i32_e32 v3, 31, v2
	v_lshl_add_u64 v[2:3], v[2:3], 1, s[22:23]
	global_store_short v[2:3], v15, off sc1
	v_add_u32_e32 v2, v58, v175
	v_ashrrev_i32_e32 v3, 31, v2
	v_lshl_add_u64 v[2:3], v[2:3], 1, s[22:23]
	v_or_b32_e32 v58, 0x180, v61
	global_store_short v[2:3], v60, off sc1
	v_add_u32_e32 v2, v58, v174
	v_ashrrev_i32_e32 v3, 31, v2
	v_lshl_add_u64 v[2:3], v[2:3], 1, s[22:23]
	global_store_short v[2:3], v15, off sc1
	v_add_u32_e32 v2, v58, v175
	v_ashrrev_i32_e32 v3, 31, v2
	v_lshl_add_u64 v[2:3], v[2:3], 1, s[22:23]
	v_add_u32_e32 v58, 0x240, v61
	global_store_short v[2:3], v60, off sc1
	v_or_b32_e32 v2, v58, v174
	v_ashrrev_i32_e32 v3, 31, v2
	v_lshl_add_u64 v[2:3], v[2:3], 1, s[22:23]
	global_store_short v[2:3], v15, off sc1
	v_or_b32_e32 v2, v58, v175
	v_ashrrev_i32_e32 v3, 31, v2
	v_lshl_add_u64 v[2:3], v[2:3], 1, s[22:23]
	v_add_u32_e32 v58, 0x300, v61
	global_store_short v[2:3], v60, off sc1
	v_or_b32_e32 v2, v58, v174
	v_ashrrev_i32_e32 v3, 31, v2
	v_lshl_add_u64 v[2:3], v[2:3], 1, s[22:23]
	global_store_short v[2:3], v15, off sc1
	v_or_b32_e32 v2, v58, v175
	v_pk_mul_f32 v[58:59], v[34:35], v[34:35]
	v_ashrrev_i32_e32 v3, 31, v2
	v_add_f32_e32 v58, v59, v58
	v_lshl_add_u64 v[2:3], v[2:3], 1, s[22:23]
	v_add_u32_e32 v62, 0x3c0, v61
	global_store_short v[2:3], v60, off sc1
	v_add_u32_e32 v2, v62, v174
	s_waitcnt lgkmcnt(0)
	v_add_f32_dpp v58, v58, v58 quad_perm:[1,0,3,2] row_mask:0xf bank_mask:0xf
	v_ashrrev_i32_e32 v3, 31, v2
	v_lshl_add_u64 v[2:3], v[2:3], 1, s[22:23]
	global_store_short v[2:3], v15, off sc1
	v_add_u32_e32 v2, v62, v175
	v_add_f32_dpp v58, v58, v58 quad_perm:[2,3,0,1] row_mask:0xf bank_mask:0xf
	v_ashrrev_i32_e32 v3, 31, v2
	v_lshl_add_u64 v[2:3], v[2:3], 1, s[22:23]
	v_add_u32_e32 v62, 0x480, v61
	global_store_short v[2:3], v60, off sc1
	v_add_f32_dpp v58, v58, v58 row_half_mirror row_mask:0xf bank_mask:0xf
	v_add_u32_e32 v2, v62, v174
	v_ashrrev_i32_e32 v3, 31, v2
	v_lshl_add_u64 v[2:3], v[2:3], 1, s[22:23]
	global_store_short v[2:3], v15, off sc1
	v_add_u32_e32 v2, v62, v175
	v_add_f32_dpp v58, v58, v58 row_mirror row_mask:0xf bank_mask:0xf
	v_ashrrev_i32_e32 v3, 31, v2
	v_mov_b32_e32 v59, v58
	s_nop 1
	v_permlane16_swap_b32_e32 v58, v59
	s_nop 0
	v_lshl_add_u64 v[2:3], v[2:3], 1, s[22:23]
	v_add_u32_e32 v61, 0x540, v61
	global_store_short v[2:3], v60, off sc1
	v_or_b32_e32 v2, v61, v174
	v_ashrrev_i32_e32 v3, 31, v2
	v_lshl_add_u64 v[2:3], v[2:3], 1, s[22:23]
	global_store_short v[2:3], v15, off sc1
	v_add_f32_e32 v3, v58, v59
	v_fmamk_f32 v3, v3, 0x3c800000, v209
	v_rsq_f32_e32 v58, v3
	v_or_b32_e32 v2, v61, v175
	v_ashrrev_i32_e32 v3, 31, v2
	v_lshl_add_u64 v[2:3], v[2:3], 1, s[22:23]
	global_store_short v[2:3], v60, off sc1
	v_pk_mul_f32 v[2:3], v[0:1], v[58:59] op_sel_hi:[1,0]
	s_and_b64 vcc, exec, s[4:5]
	v_pk_mul_f32 v[2:3], v[34:35], v[2:3]
	s_mov_b64 s[80:81], -1
	s_cbranch_vccnz .LBB0_326
	v_add_u32_e32 v15, s76, v189
	v_lshl_or_b32 v58, v15, 6, v156
	v_ashrrev_i32_e32 v59, 31, v58
	v_lshl_add_u64 v[58:59], v[58:59], 2, s[24:25]
	s_mov_b64 s[80:81], 0
	global_store_dword v[58:59], v3, off sc1
	global_store_dword v[58:59], v2, off offset:128 sc1

.LBB0_328:
	v_cvt_pk_bf16_f32 v60, v2, s0
	v_add_u32_e32 v2, s11, v189
	v_mul_lo_u32 v61, v2, s94
	v_or_b32_e32 v2, v61, v174
	v_cvt_pk_bf16_f32 v15, v3, s0
	v_ashrrev_i32_e32 v3, 31, v2
	v_lshl_add_u64 v[2:3], v[2:3], 1, s[22:23]
	global_store_short v[2:3], v15, off sc1
	v_or_b32_e32 v2, v61, v175
	v_ashrrev_i32_e32 v3, 31, v2
	v_lshl_add_u64 v[2:3], v[2:3], 1, s[22:23]
	v_or_b32_e32 v58, 0xc0, v61
	global_store_short v[2:3], v60, off sc1
	v_add_u32_e32 v2, v58, v174
	v_ashrrev_i32_e32 v3, 31, v2
	v_lshl_add_u64 v[2:3], v[2:3], 1, s[22:23]
	global_store_short v[2:3], v15, off sc1
	v_add_u32_e32 v2, v58, v175
	v_ashrrev_i32_e32 v3, 31, v2
	v_lshl_add_u64 v[2:3], v[2:3], 1, s[22:23]
	v_or_b32_e32 v58, 0x180, v61
	global_store_short v[2:3], v60, off sc1
	v_add_u32_e32 v2, v58, v174
	v_ashrrev_i32_e32 v3, 31, v2
	v_lshl_add_u64 v[2:3], v[2:3], 1, s[22:23]
	global_store_short v[2:3], v15, off sc1
	v_add_u32_e32 v2, v58, v175
	v_ashrrev_i32_e32 v3, 31, v2
	v_lshl_add_u64 v[2:3], v[2:3], 1, s[22:23]
	v_add_u32_e32 v58, 0x240, v61
	global_store_short v[2:3], v60, off sc1
	v_or_b32_e32 v2, v58, v174
	v_ashrrev_i32_e32 v3, 31, v2
	v_lshl_add_u64 v[2:3], v[2:3], 1, s[22:23]
	global_store_short v[2:3], v15, off sc1
	v_or_b32_e32 v2, v58, v175
	v_ashrrev_i32_e32 v3, 31, v2
	v_lshl_add_u64 v[2:3], v[2:3], 1, s[22:23]
	v_add_u32_e32 v58, 0x300, v61
	global_store_short v[2:3], v60, off sc1
	v_or_b32_e32 v2, v58, v174
	v_ashrrev_i32_e32 v3, 31, v2
	v_lshl_add_u64 v[2:3], v[2:3], 1, s[22:23]
	global_store_short v[2:3], v15, off sc1
	v_or_b32_e32 v2, v58, v175
	v_pk_mul_f32 v[58:59], v[32:33], v[32:33]
	v_ashrrev_i32_e32 v3, 31, v2
	v_add_f32_e32 v58, v59, v58
	v_lshl_add_u64 v[2:3], v[2:3], 1, s[22:23]
	v_add_u32_e32 v62, 0x3c0, v61
	global_store_short v[2:3], v60, off sc1
	v_add_u32_e32 v2, v62, v174
	s_waitcnt lgkmcnt(0)
	v_add_f32_dpp v14, v58, v58 quad_perm:[1,0,3,2] row_mask:0xf bank_mask:0xf
	v_ashrrev_i32_e32 v3, 31, v2
	v_lshl_add_u64 v[2:3], v[2:3], 1, s[22:23]
	global_store_short v[2:3], v15, off sc1
	v_add_u32_e32 v2, v62, v175
	v_add_f32_dpp v10, v14, v14 quad_perm:[2,3,0,1] row_mask:0xf bank_mask:0xf
	v_ashrrev_i32_e32 v3, 31, v2
	v_lshl_add_u64 v[2:3], v[2:3], 1, s[22:23]
	v_add_u32_e32 v58, 0x480, v61
	global_store_short v[2:3], v60, off sc1
	v_add_f32_dpp v10, v10, v10 row_half_mirror row_mask:0xf bank_mask:0xf
	v_add_u32_e32 v2, v58, v174
	v_ashrrev_i32_e32 v3, 31, v2
	v_lshl_add_u64 v[2:3], v[2:3], 1, s[22:23]
	global_store_short v[2:3], v15, off sc1
	v_add_u32_e32 v2, v58, v175
	v_add_f32_dpp v10, v10, v10 row_mirror row_mask:0xf bank_mask:0xf
	v_ashrrev_i32_e32 v3, 31, v2
	v_mov_b32_e32 v11, v10
	s_nop 1
	v_permlane16_swap_b32_e32 v10, v11
	s_nop 0
	v_lshl_add_u64 v[2:3], v[2:3], 1, s[22:23]
	v_add_u32_e32 v12, 0x540, v61
	global_store_short v[2:3], v60, off sc1
	v_or_b32_e32 v2, v12, v174
	v_ashrrev_i32_e32 v3, 31, v2
	v_lshl_add_u64 v[2:3], v[2:3], 1, s[22:23]
	global_store_short v[2:3], v15, off sc1
	v_add_f32_e32 v3, v10, v11
	v_fmamk_f32 v3, v3, 0x3c800000, v209
	v_rsq_f32_e32 v10, v3
	v_or_b32_e32 v2, v12, v175
	v_ashrrev_i32_e32 v3, 31, v2
	v_lshl_add_u64 v[2:3], v[2:3], 1, s[22:23]
	v_pk_mul_f32 v[0:1], v[0:1], v[10:11] op_sel_hi:[1,0]
	s_and_b64 vcc, exec, s[4:5]
	v_pk_mul_f32 v[0:1], v[32:33], v[0:1]
	s_mov_b64 s[80:81], -1
	global_store_short v[2:3], v60, off sc1
	s_cbranch_vccnz .LBB0_330
	v_add_u32_e32 v2, s76, v190
	v_lshl_or_b32 v2, v2, 6, v156
	v_ashrrev_i32_e32 v3, 31, v2
	v_lshl_add_u64 v[2:3], v[2:3], 2, s[24:25]
	s_mov_b64 s[80:81], 0
	global_store_dword v[2:3], v1, off sc1
	global_store_dword v[2:3], v0, off offset:128 sc1

.LBB0_462:
	v_pk_mul_f32 v[0:1], v[78:79], v[78:79]
	v_and_b32_e32 v2, 64, v214
	v_add_f32_e32 v0, v1, v0
	v_xor_b32_e32 v1, 1, v214
	v_add_u32_e32 v12, 64, v2
	v_cmp_lt_i32_e32 vcc, v1, v12
	v_fmac_f32_e32 v0, v57, v57
	v_fmac_f32_e32 v0, v56, v56
	v_cndmask_b32_e32 v1, v214, v1, vcc
	v_lshlrev_b32_e32 v2, 2, v1
	v_xor_b32_e32 v3, 2, v214
	v_cmp_lt_i32_e32 vcc, v3, v12
	v_xor_b32_e32 v10, 4, v214
	v_xor_b32_e32 v11, 8, v214
	v_cndmask_b32_e32 v3, v214, v3, vcc
	v_lshlrev_b32_e32 v3, 2, v3
	s_waitcnt lgkmcnt(0)
	v_add_f32_dpp v0, v0, v0 quad_perm:[1,0,3,2] row_mask:0xf bank_mask:0xf
	v_cmp_lt_i32_e32 vcc, v10, v12
	v_xor_b32_e32 v13, 16, v214
	s_mul_i32 s4, s10, 0x4200
	v_cndmask_b32_e32 v10, v214, v10, vcc
	v_lshlrev_b32_e32 v10, 2, v10
	v_add_f32_dpp v0, v0, v0 quad_perm:[2,3,0,1] row_mask:0xf bank_mask:0xf
	v_cmp_lt_i32_e32 vcc, v11, v12
	s_add_i32 s11, s11, s4
	v_add_f32_dpp v0, v0, v0 row_half_mirror row_mask:0xf bank_mask:0xf
	v_cndmask_b32_e32 v11, v214, v11, vcc
	v_lshlrev_b32_e32 v11, 2, v11
	v_cmp_lt_i32_e32 vcc, v13, v12
	v_add_f32_dpp v1, v0, v0 row_mirror row_mask:0xf bank_mask:0xf
	v_cndmask_b32_e32 v12, v214, v13, vcc
	v_lshlrev_b32_e32 v12, 2, v12
	ds_bpermute_b32 v13, v12, v1
	v_add_u32_e32 v0, s11, v191
	s_and_saveexec_b64 s[4:5], s[0:1]
	s_cbranch_execz .LBB0_464
	s_waitcnt lgkmcnt(0)
	v_add_f32_e32 v13, v1, v13
	v_ashrrev_i32_e32 v1, 31, v0
	v_lshl_add_u64 v[14:15], v[0:1], 2, s[30:31]
	global_store_dword v[14:15], v13, off sc1
.LBB0_464:
	s_or_b64 exec, exec, s[4:5]
	v_pk_mul_f32 v[14:15], v[74:75], v[74:75]
	s_nop 0
	v_add_f32_e32 v1, v15, v14
	v_fmac_f32_e32 v1, v47, v47
	v_fmac_f32_e32 v1, v31, v31
	s_waitcnt lgkmcnt(0)
	v_add_f32_dpp v1, v1, v1 quad_perm:[1,0,3,2] row_mask:0xf bank_mask:0xf
	s_nop 0
	v_add_f32_dpp v1, v1, v1 quad_perm:[2,3,0,1] row_mask:0xf bank_mask:0xf
	s_nop 0
	v_add_f32_dpp v1, v1, v1 row_half_mirror row_mask:0xf bank_mask:0xf
	s_nop 0
	v_add_f32_dpp v1, v1, v1 row_mirror row_mask:0xf bank_mask:0xf
	ds_bpermute_b32 v13, v12, v1
	s_and_saveexec_b64 s[4:5], s[0:1]
	s_cbranch_execz .LBB0_466
	v_add_u32_e32 v14, 1, v0
	v_ashrrev_i32_e32 v15, 31, v14
	s_waitcnt lgkmcnt(0)
	v_add_f32_e32 v1, v1, v13
	v_lshl_add_u64 v[14:15], v[14:15], 2, s[30:31]
	global_store_dword v[14:15], v1, off sc1
.LBB0_466:
	s_or_b64 exec, exec, s[4:5]
	v_pk_mul_f32 v[14:15], v[72:73], v[72:73]
	s_nop 0
	v_add_f32_e32 v1, v15, v14
	v_fmac_f32_e32 v1, v46, v46
	v_fmac_f32_e32 v1, v30, v30
	s_waitcnt lgkmcnt(0)
	v_add_f32_dpp v1, v1, v1 quad_perm:[1,0,3,2] row_mask:0xf bank_mask:0xf
	s_nop 0
	v_add_f32_dpp v1, v1, v1 quad_perm:[2,3,0,1] row_mask:0xf bank_mask:0xf
	s_nop 0
	v_add_f32_dpp v1, v1, v1 row_half_mirror row_mask:0xf bank_mask:0xf
	s_nop 0
	v_add_f32_dpp v1, v1, v1 row_mirror row_mask:0xf bank_mask:0xf
	ds_bpermute_b32 v13, v12, v1
	s_and_saveexec_b64 s[4:5], s[0:1]
	s_cbranch_execz .LBB0_468
	v_add_u32_e32 v14, 2, v0
	v_ashrrev_i32_e32 v15, 31, v14
	s_waitcnt lgkmcnt(0)
	v_add_f32_e32 v1, v1, v13
	v_lshl_add_u64 v[14:15], v[14:15], 2, s[30:31]
	global_store_dword v[14:15], v1, off sc1
.LBB0_468:
	s_or_b64 exec, exec, s[4:5]
	v_pk_mul_f32 v[14:15], v[70:71], v[70:71]
	s_nop 0
	v_add_f32_e32 v1, v15, v14
	v_fmac_f32_e32 v1, v45, v45
	v_fmac_f32_e32 v1, v29, v29
	s_waitcnt lgkmcnt(0)
	v_add_f32_dpp v1, v1, v1 quad_perm:[1,0,3,2] row_mask:0xf bank_mask:0xf
	s_nop 0
	v_add_f32_dpp v1, v1, v1 quad_perm:[2,3,0,1] row_mask:0xf bank_mask:0xf
	s_nop 0
	v_add_f32_dpp v1, v1, v1 row_half_mirror row_mask:0xf bank_mask:0xf
	s_nop 0
	v_add_f32_dpp v1, v1, v1 row_mirror row_mask:0xf bank_mask:0xf
	ds_bpermute_b32 v13, v12, v1
	s_and_saveexec_b64 s[4:5], s[0:1]
	s_cbranch_execz .LBB0_470
	v_add_u32_e32 v14, 3, v0
	v_ashrrev_i32_e32 v15, 31, v14
	s_waitcnt lgkmcnt(0)
	v_add_f32_e32 v1, v1, v13
	v_lshl_add_u64 v[14:15], v[14:15], 2, s[30:31]
	global_store_dword v[14:15], v1, off sc1
.LBB0_470:
	s_or_b64 exec, exec, s[4:5]
	v_pk_mul_f32 v[14:15], v[68:69], v[68:69]
	s_nop 0
	v_add_f32_e32 v1, v15, v14
	v_fmac_f32_e32 v1, v44, v44
	v_fmac_f32_e32 v1, v28, v28
	s_waitcnt lgkmcnt(0)
	v_add_f32_dpp v1, v1, v1 quad_perm:[1,0,3,2] row_mask:0xf bank_mask:0xf
	s_nop 0
	v_add_f32_dpp v1, v1, v1 quad_perm:[2,3,0,1] row_mask:0xf bank_mask:0xf
	s_nop 0
	v_add_f32_dpp v1, v1, v1 row_half_mirror row_mask:0xf bank_mask:0xf
	s_nop 0
	v_add_f32_dpp v1, v1, v1 row_mirror row_mask:0xf bank_mask:0xf
	ds_bpermute_b32 v13, v12, v1
	s_and_saveexec_b64 s[4:5], s[0:1]
	s_cbranch_execz .LBB0_472
	v_add_u32_e32 v14, 8, v0
	v_ashrrev_i32_e32 v15, 31, v14
	s_waitcnt lgkmcnt(0)
	v_add_f32_e32 v1, v1, v13
	v_lshl_add_u64 v[14:15], v[14:15], 2, s[30:31]
	global_store_dword v[14:15], v1, off sc1
.LBB0_472:
	s_or_b64 exec, exec, s[4:5]
	v_pk_mul_f32 v[14:15], v[66:67], v[66:67]
	s_nop 0
	v_add_f32_e32 v1, v15, v14
	v_fmac_f32_e32 v1, v43, v43
	v_fmac_f32_e32 v1, v27, v27
	s_waitcnt lgkmcnt(0)
	v_add_f32_dpp v1, v1, v1 quad_perm:[1,0,3,2] row_mask:0xf bank_mask:0xf
	s_nop 0
	v_add_f32_dpp v1, v1, v1 quad_perm:[2,3,0,1] row_mask:0xf bank_mask:0xf
	s_nop 0
	v_add_f32_dpp v1, v1, v1 row_half_mirror row_mask:0xf bank_mask:0xf
	s_nop 0
	v_add_f32_dpp v1, v1, v1 row_mirror row_mask:0xf bank_mask:0xf
	ds_bpermute_b32 v13, v12, v1
	s_and_saveexec_b64 s[4:5], s[0:1]
	s_cbranch_execz .LBB0_474
	v_add_u32_e32 v14, 9, v0
	v_ashrrev_i32_e32 v15, 31, v14
	s_waitcnt lgkmcnt(0)
	v_add_f32_e32 v1, v1, v13
	v_lshl_add_u64 v[14:15], v[14:15], 2, s[30:31]
	global_store_dword v[14:15], v1, off sc1
.LBB0_474:
	s_or_b64 exec, exec, s[4:5]
	v_pk_mul_f32 v[14:15], v[64:65], v[64:65]
	s_nop 0
	v_add_f32_e32 v1, v15, v14
	v_fmac_f32_e32 v1, v42, v42
	v_fmac_f32_e32 v1, v26, v26
	s_waitcnt lgkmcnt(0)
	v_add_f32_dpp v1, v1, v1 quad_perm:[1,0,3,2] row_mask:0xf bank_mask:0xf
	s_nop 0
	v_add_f32_dpp v1, v1, v1 quad_perm:[2,3,0,1] row_mask:0xf bank_mask:0xf
	s_nop 0
	v_add_f32_dpp v1, v1, v1 row_half_mirror row_mask:0xf bank_mask:0xf
	s_nop 0
	v_add_f32_dpp v1, v1, v1 row_mirror row_mask:0xf bank_mask:0xf
	ds_bpermute_b32 v13, v12, v1
	s_and_saveexec_b64 s[4:5], s[0:1]
	s_cbranch_execz .LBB0_476
	v_add_u32_e32 v14, 10, v0
	v_ashrrev_i32_e32 v15, 31, v14
	s_waitcnt lgkmcnt(0)
	v_add_f32_e32 v1, v1, v13
	v_lshl_add_u64 v[14:15], v[14:15], 2, s[30:31]
	global_store_dword v[14:15], v1, off sc1
.LBB0_476:
	s_or_b64 exec, exec, s[4:5]
	v_pk_mul_f32 v[14:15], v[54:55], v[54:55]
	s_nop 0
	v_add_f32_e32 v1, v15, v14
	v_fmac_f32_e32 v1, v23, v23
	v_fmac_f32_e32 v1, v25, v25
	s_waitcnt lgkmcnt(0)
	v_add_f32_dpp v1, v1, v1 quad_perm:[1,0,3,2] row_mask:0xf bank_mask:0xf
	s_nop 0
	v_add_f32_dpp v1, v1, v1 quad_perm:[2,3,0,1] row_mask:0xf bank_mask:0xf
	s_nop 0
	v_add_f32_dpp v1, v1, v1 row_half_mirror row_mask:0xf bank_mask:0xf
	s_nop 0
	v_add_f32_dpp v1, v1, v1 row_mirror row_mask:0xf bank_mask:0xf
	ds_bpermute_b32 v13, v12, v1
	s_and_saveexec_b64 s[4:5], s[0:1]
	s_cbranch_execz .LBB0_478
	v_add_u32_e32 v14, 11, v0
	v_ashrrev_i32_e32 v15, 31, v14
	s_waitcnt lgkmcnt(0)
	v_add_f32_e32 v1, v1, v13
	v_lshl_add_u64 v[14:15], v[14:15], 2, s[30:31]
	global_store_dword v[14:15], v1, off sc1
.LBB0_478:
	s_or_b64 exec, exec, s[4:5]
	v_pk_mul_f32 v[14:15], v[52:53], v[52:53]
	s_nop 0
	v_add_f32_e32 v1, v15, v14
	v_fmac_f32_e32 v1, v22, v22
	v_fmac_f32_e32 v1, v24, v24
	s_waitcnt lgkmcnt(0)
	v_add_f32_dpp v1, v1, v1 quad_perm:[1,0,3,2] row_mask:0xf bank_mask:0xf
	s_nop 0
	v_add_f32_dpp v1, v1, v1 quad_perm:[2,3,0,1] row_mask:0xf bank_mask:0xf
	s_nop 0
	v_add_f32_dpp v1, v1, v1 row_half_mirror row_mask:0xf bank_mask:0xf
	s_nop 0
	v_add_f32_dpp v1, v1, v1 row_mirror row_mask:0xf bank_mask:0xf
	ds_bpermute_b32 v13, v12, v1
	s_and_saveexec_b64 s[4:5], s[0:1]
	s_cbranch_execz .LBB0_480
	v_add_u32_e32 v14, 16, v0
	v_ashrrev_i32_e32 v15, 31, v14
	s_waitcnt lgkmcnt(0)
	v_add_f32_e32 v1, v1, v13
	v_lshl_add_u64 v[14:15], v[14:15], 2, s[30:31]
	global_store_dword v[14:15], v1, off sc1
.LBB0_480:
	s_or_b64 exec, exec, s[4:5]
	v_pk_mul_f32 v[14:15], v[50:51], v[50:51]
	s_nop 0
	v_add_f32_e32 v1, v15, v14
	v_fmac_f32_e32 v1, v21, v21
	v_fmac_f32_e32 v1, v9, v9
	s_waitcnt lgkmcnt(0)
	v_add_f32_dpp v1, v1, v1 quad_perm:[1,0,3,2] row_mask:0xf bank_mask:0xf
	s_nop 0
	v_add_f32_dpp v1, v1, v1 quad_perm:[2,3,0,1] row_mask:0xf bank_mask:0xf
	s_nop 0
	v_add_f32_dpp v1, v1, v1 row_half_mirror row_mask:0xf bank_mask:0xf
	s_nop 0
	v_add_f32_dpp v1, v1, v1 row_mirror row_mask:0xf bank_mask:0xf
	ds_bpermute_b32 v13, v12, v1
	s_and_saveexec_b64 s[4:5], s[0:1]
	s_cbranch_execz .LBB0_482
	v_add_u32_e32 v14, 17, v0
	v_ashrrev_i32_e32 v15, 31, v14
	s_waitcnt lgkmcnt(0)
	v_add_f32_e32 v1, v1, v13
	v_lshl_add_u64 v[14:15], v[14:15], 2, s[30:31]
	global_store_dword v[14:15], v1, off sc1
.LBB0_482:
	s_or_b64 exec, exec, s[4:5]
	v_pk_mul_f32 v[14:15], v[48:49], v[48:49]
	s_nop 0
	v_add_f32_e32 v1, v15, v14
	v_fmac_f32_e32 v1, v20, v20
	v_fmac_f32_e32 v1, v8, v8
	s_waitcnt lgkmcnt(0)
	v_add_f32_dpp v1, v1, v1 quad_perm:[1,0,3,2] row_mask:0xf bank_mask:0xf
	s_nop 0
	v_add_f32_dpp v1, v1, v1 quad_perm:[2,3,0,1] row_mask:0xf bank_mask:0xf
	s_nop 0
	v_add_f32_dpp v1, v1, v1 row_half_mirror row_mask:0xf bank_mask:0xf
	s_nop 0
	v_add_f32_dpp v1, v1, v1 row_mirror row_mask:0xf bank_mask:0xf
	ds_bpermute_b32 v13, v12, v1
	s_and_saveexec_b64 s[4:5], s[0:1]
	s_cbranch_execz .LBB0_484
	v_add_u32_e32 v14, 18, v0
	v_ashrrev_i32_e32 v15, 31, v14
	s_waitcnt lgkmcnt(0)
	v_add_f32_e32 v1, v1, v13
	v_lshl_add_u64 v[14:15], v[14:15], 2, s[30:31]
	global_store_dword v[14:15], v1, off sc1
.LBB0_484:
	s_or_b64 exec, exec, s[4:5]
	v_pk_mul_f32 v[14:15], v[40:41], v[40:41]
	s_nop 0
	v_add_f32_e32 v1, v15, v14
	v_fmac_f32_e32 v1, v19, v19
	v_fmac_f32_e32 v1, v7, v7
	s_waitcnt lgkmcnt(0)
	v_add_f32_dpp v1, v1, v1 quad_perm:[1,0,3,2] row_mask:0xf bank_mask:0xf
	s_nop 0
	v_add_f32_dpp v1, v1, v1 quad_perm:[2,3,0,1] row_mask:0xf bank_mask:0xf
	s_nop 0
	v_add_f32_dpp v1, v1, v1 row_half_mirror row_mask:0xf bank_mask:0xf
	s_nop 0
	v_add_f32_dpp v1, v1, v1 row_mirror row_mask:0xf bank_mask:0xf
	ds_bpermute_b32 v13, v12, v1
	s_and_saveexec_b64 s[4:5], s[0:1]
	s_cbranch_execz .LBB0_486
	v_add_u32_e32 v14, 19, v0
	v_ashrrev_i32_e32 v15, 31, v14
	s_waitcnt lgkmcnt(0)
	v_add_f32_e32 v1, v1, v13
	v_lshl_add_u64 v[14:15], v[14:15], 2, s[30:31]
	global_store_dword v[14:15], v1, off sc1
.LBB0_486:
	s_or_b64 exec, exec, s[4:5]
	v_pk_mul_f32 v[14:15], v[38:39], v[38:39]
	s_nop 0
	v_add_f32_e32 v1, v15, v14
	v_fmac_f32_e32 v1, v18, v18
	v_fmac_f32_e32 v1, v6, v6
	s_waitcnt lgkmcnt(0)
	v_add_f32_dpp v1, v1, v1 quad_perm:[1,0,3,2] row_mask:0xf bank_mask:0xf
	s_nop 0
	v_add_f32_dpp v1, v1, v1 quad_perm:[2,3,0,1] row_mask:0xf bank_mask:0xf
	s_nop 0
	v_add_f32_dpp v1, v1, v1 row_half_mirror row_mask:0xf bank_mask:0xf
	s_nop 0
	v_add_f32_dpp v1, v1, v1 row_mirror row_mask:0xf bank_mask:0xf
	ds_bpermute_b32 v13, v12, v1
	s_and_saveexec_b64 s[4:5], s[0:1]
	s_cbranch_execz .LBB0_488
	v_add_u32_e32 v14, 24, v0
	v_ashrrev_i32_e32 v15, 31, v14
	s_waitcnt lgkmcnt(0)
	v_add_f32_e32 v1, v1, v13
	v_lshl_add_u64 v[14:15], v[14:15], 2, s[30:31]
	global_store_dword v[14:15], v1, off sc1
.LBB0_488:
	s_or_b64 exec, exec, s[4:5]
	v_pk_mul_f32 v[14:15], v[36:37], v[36:37]
	s_nop 0
	v_add_f32_e32 v1, v15, v14
	v_fmac_f32_e32 v1, v17, v17
	v_fmac_f32_e32 v1, v5, v5
	s_waitcnt lgkmcnt(0)
	v_add_f32_dpp v1, v1, v1 quad_perm:[1,0,3,2] row_mask:0xf bank_mask:0xf
	s_nop 0
	v_add_f32_dpp v1, v1, v1 quad_perm:[2,3,0,1] row_mask:0xf bank_mask:0xf
	s_nop 0
	v_add_f32_dpp v1, v1, v1 row_half_mirror row_mask:0xf bank_mask:0xf
	s_nop 0
	v_add_f32_dpp v1, v1, v1 row_mirror row_mask:0xf bank_mask:0xf
	ds_bpermute_b32 v13, v12, v1
	s_and_saveexec_b64 s[4:5], s[0:1]
	s_cbranch_execz .LBB0_490
	v_add_u32_e32 v14, 25, v0
	v_ashrrev_i32_e32 v15, 31, v14
	s_waitcnt lgkmcnt(0)
	v_add_f32_e32 v1, v1, v13
	v_lshl_add_u64 v[14:15], v[14:15], 2, s[30:31]
	global_store_dword v[14:15], v1, off sc1
.LBB0_490:
	s_or_b64 exec, exec, s[4:5]
	v_pk_mul_f32 v[14:15], v[34:35], v[34:35]
	s_nop 0
	v_add_f32_e32 v1, v15, v14
	v_fmac_f32_e32 v1, v16, v16
	v_fmac_f32_e32 v1, v4, v4
	s_waitcnt lgkmcnt(0)
	v_add_f32_dpp v1, v1, v1 quad_perm:[1,0,3,2] row_mask:0xf bank_mask:0xf
	s_nop 0
	v_add_f32_dpp v1, v1, v1 quad_perm:[2,3,0,1] row_mask:0xf bank_mask:0xf
	s_nop 0
	v_add_f32_dpp v1, v1, v1 row_half_mirror row_mask:0xf bank_mask:0xf
	s_nop 0
	v_add_f32_dpp v1, v1, v1 row_mirror row_mask:0xf bank_mask:0xf
	ds_bpermute_b32 v13, v12, v1
	s_and_saveexec_b64 s[4:5], s[0:1]
	s_cbranch_execz .LBB0_492
	v_add_u32_e32 v14, 26, v0
	v_ashrrev_i32_e32 v15, 31, v14
	s_waitcnt lgkmcnt(0)
	v_add_f32_e32 v1, v1, v13
	v_lshl_add_u64 v[14:15], v[14:15], 2, s[30:31]
	global_store_dword v[14:15], v1, off sc1
.LBB0_492:
	s_or_b64 exec, exec, s[4:5]
	v_pk_mul_f32 v[14:15], v[32:33], v[32:33]
	s_nop 0
	v_add_f32_e32 v1, v15, v14
	v_fmac_f32_e32 v1, v82, v82
	v_fmac_f32_e32 v1, v83, v83
	s_waitcnt lgkmcnt(0)
	s_nop 0
	v_add_f32_dpp v1, v1, v1 quad_perm:[1,0,3,2] row_mask:0xf bank_mask:0xf
	s_nop 0
	v_add_f32_dpp v1, v1, v1 quad_perm:[2,3,0,1] row_mask:0xf bank_mask:0xf
	s_nop 0
	v_add_f32_dpp v1, v1, v1 row_half_mirror row_mask:0xf bank_mask:0xf
	s_nop 0
	v_add_f32_dpp v1, v1, v1 row_mirror row_mask:0xf bank_mask:0xf
	ds_bpermute_b32 v2, v12, v1
	s_and_saveexec_b64 s[4:5], s[0:1]
	s_cbranch_execz .LBB0_494
	v_add_u32_e32 v0, 27, v0
	s_waitcnt lgkmcnt(0)
	v_add_f32_e32 v2, v1, v2
	v_ashrrev_i32_e32 v1, 31, v0
	v_lshl_add_u64 v[0:1], v[0:1], 2, s[30:31]
	global_store_dword v[0:1], v2, off sc1

.LBB0_497:
	v_mov_b32_e32 v0, s97
	ds_read_b64 v[0:1], v0
	s_waitcnt lgkmcnt(1)
	v_pk_mul_f32 v[2:3], v[78:79], v[78:79]
	v_or_b32_e32 v88, 32, v76
	v_or_b32_e32 v85, 64, v76
	v_or_b32_e32 v10, 0x60, v76
	s_waitcnt lgkmcnt(0)
	v_readfirstlane_b32 s4, v0
	v_readfirstlane_b32 s5, v1
	v_add_f32_e32 v2, v3, v2
	v_mov_b32_e32 v0, s4
	v_mov_b32_e32 v1, s5
	v_lshl_add_u64 v[0:1], v[76:77], 2, v[0:1]
	global_load_dword v77, v[0:1], off
	s_movk_i32 s4, 0x180
	v_fmac_f32_e32 v2, v57, v57
	v_fmac_f32_e32 v2, v56, v56
	s_waitcnt vmcnt(0)
	v_mul_f32_e32 v11, v79, v77
	v_cvt_pk_bf16_f32 v14, v11, s0
	v_mul_lo_u32 v11, v164, s4
	v_add_u32_e32 v12, v11, v76
	v_ashrrev_i32_e32 v13, 31, v12
	v_lshl_add_u64 v[12:13], v[12:13], 1, s[34:35]
	global_store_short v[12:13], v14, off sc1
	v_mul_f32_e32 v12, v75, v77
	v_cvt_pk_bf16_f32 v13, v12, s0
	v_add_u32_e32 v12, 0x180, v11
	v_add_u32_e32 v14, v12, v76
	v_ashrrev_i32_e32 v15, 31, v14
	v_lshl_add_u64 v[14:15], v[14:15], 1, s[34:35]
	global_store_short v[14:15], v13, off sc1
	v_mul_f32_e32 v13, v73, v77
	v_cvt_pk_bf16_f32 v58, v13, s0
	v_add_u32_e32 v13, 0x300, v11
	v_add_u32_e32 v14, v13, v76
	v_ashrrev_i32_e32 v15, 31, v14
	v_lshl_add_u64 v[14:15], v[14:15], 1, s[34:35]
	global_store_short v[14:15], v58, off sc1
	v_mul_f32_e32 v14, v71, v77
	v_cvt_pk_bf16_f32 v15, v14, s0
	v_add_u32_e32 v14, 0x480, v11
	v_add_u32_e32 v58, v14, v76
	v_ashrrev_i32_e32 v59, 31, v58
	v_lshl_add_u64 v[58:59], v[58:59], 1, s[34:35]
	global_store_short v[58:59], v15, off sc1
	v_mul_f32_e32 v15, v69, v77
	v_cvt_pk_bf16_f32 v60, v15, s0
	v_add_u32_e32 v15, 0xc00, v11
	v_add_u32_e32 v58, v15, v76
	v_ashrrev_i32_e32 v59, 31, v58
	v_lshl_add_u64 v[58:59], v[58:59], 1, s[34:35]
	global_store_short v[58:59], v60, off sc1
	v_mul_f32_e32 v58, v67, v77
	v_cvt_pk_bf16_f32 v59, v58, s0
	v_add_u32_e32 v58, 0xd80, v11
	v_add_u32_e32 v60, v58, v76
	v_ashrrev_i32_e32 v61, 31, v60
	v_lshl_add_u64 v[60:61], v[60:61], 1, s[34:35]
	global_store_short v[60:61], v59, off sc1
	v_mul_f32_e32 v59, v65, v77
	v_cvt_pk_bf16_f32 v62, v59, s0
	v_add_u32_e32 v59, 0xf00, v11
	v_add_u32_e32 v60, v59, v76
	v_ashrrev_i32_e32 v61, 31, v60
	v_lshl_add_u64 v[60:61], v[60:61], 1, s[34:35]
	global_store_short v[60:61], v62, off sc1
	v_mul_f32_e32 v60, v55, v77
	v_cvt_pk_bf16_f32 v61, v60, s0
	v_add_u32_e32 v60, 0x1080, v11
	v_add_u32_e32 v62, v60, v76
	v_ashrrev_i32_e32 v63, 31, v62
	v_lshl_add_u64 v[62:63], v[62:63], 1, s[34:35]
	global_store_short v[62:63], v61, off sc1
	v_mul_f32_e32 v61, v53, v77
	v_cvt_pk_bf16_f32 v79, v61, s0
	v_add_u32_e32 v61, 0x1800, v11
	v_add_u32_e32 v62, v61, v76
	v_ashrrev_i32_e32 v63, 31, v62
	v_lshl_add_u64 v[62:63], v[62:63], 1, s[34:35]
	global_store_short v[62:63], v79, off sc1
	v_mul_f32_e32 v62, v51, v77
	v_cvt_pk_bf16_f32 v63, v62, s0
	v_add_u32_e32 v62, 0x1980, v11
	v_add_u32_e32 v80, v62, v76
	v_ashrrev_i32_e32 v81, 31, v80
	v_lshl_add_u64 v[80:81], v[80:81], 1, s[34:35]
	global_store_short v[80:81], v63, off sc1
	v_mul_f32_e32 v63, v49, v77
	v_cvt_pk_bf16_f32 v79, v63, s0
	v_add_u32_e32 v63, 0x1b00, v11
	v_add_u32_e32 v80, v63, v76
	v_ashrrev_i32_e32 v81, 31, v80
	v_lshl_add_u64 v[80:81], v[80:81], 1, s[34:35]
	v_add_u32_e32 v84, 0x1c80, v11
	global_store_short v[80:81], v79, off sc1
	v_add_u32_e32 v80, v84, v76
	v_mul_f32_e32 v79, v41, v77
	v_ashrrev_i32_e32 v81, 31, v80
	v_cvt_pk_bf16_f32 v79, v79, s0
	v_lshl_add_u64 v[80:81], v[80:81], 1, s[34:35]
	global_store_short v[80:81], v79, off sc1
	v_add_u32_e32 v81, 0x2400, v11
	v_add_u32_e32 v86, v81, v76
	v_mul_f32_e32 v79, v39, v77
	v_ashrrev_i32_e32 v87, 31, v86
	v_cvt_pk_bf16_f32 v79, v79, s0
	v_lshl_add_u64 v[86:87], v[86:87], 1, s[34:35]
	v_add_u32_e32 v80, 0x2580, v11
	global_store_short v[86:87], v79, off sc1
	v_add_u32_e32 v86, v80, v76
	v_mul_f32_e32 v79, v37, v77
	v_ashrrev_i32_e32 v87, 31, v86
	v_cvt_pk_bf16_f32 v79, v79, s0
	v_lshl_add_u64 v[86:87], v[86:87], 1, s[34:35]
	global_store_short v[86:87], v79, off sc1
	v_mul_f32_e32 v79, v35, v77
	v_cvt_pk_bf16_f32 v89, v79, s0
	v_add_u32_e32 v79, 0x2700, v11
	v_add_u32_e32 v86, v79, v76
	v_ashrrev_i32_e32 v87, 31, v86
	v_lshl_add_u64 v[86:87], v[86:87], 1, s[34:35]
	v_mul_f32_e32 v77, v33, v77
	global_store_short v[86:87], v89, off sc1
	v_cvt_pk_bf16_f32 v89, v77, s0
	v_add_u32_e32 v77, 0x2880, v11
	v_add_u32_e32 v86, v77, v76
	global_load_dword v76, v[0:1], off offset:128
	v_ashrrev_i32_e32 v87, 31, v86
	v_lshl_add_u64 v[86:87], v[86:87], 1, s[34:35]
	global_store_short v[86:87], v89, off sc1
	v_add_u32_e32 v86, v11, v88
	v_ashrrev_i32_e32 v87, 31, v86
	v_lshl_add_u64 v[86:87], v[86:87], 1, s[34:35]
	s_waitcnt vmcnt(1)
	v_mul_f32_e32 v3, v78, v76
	v_cvt_pk_bf16_f32 v3, v3, s0
	global_store_short v[86:87], v3, off sc1
	v_add_u32_e32 v86, v12, v88
	v_mul_f32_e32 v3, v74, v76
	v_ashrrev_i32_e32 v87, 31, v86
	v_cvt_pk_bf16_f32 v3, v3, s0
	v_lshl_add_u64 v[86:87], v[86:87], 1, s[34:35]
	global_store_short v[86:87], v3, off sc1
	v_add_u32_e32 v86, v13, v88
	v_mul_f32_e32 v3, v72, v76
	v_ashrrev_i32_e32 v87, 31, v86
	v_cvt_pk_bf16_f32 v3, v3, s0
	v_lshl_add_u64 v[86:87], v[86:87], 1, s[34:35]
	global_store_short v[86:87], v3, off sc1
	v_add_u32_e32 v86, v14, v88
	v_mul_f32_e32 v3, v70, v76
	v_ashrrev_i32_e32 v87, 31, v86
	v_cvt_pk_bf16_f32 v3, v3, s0
	v_lshl_add_u64 v[86:87], v[86:87], 1, s[34:35]
	global_store_short v[86:87], v3, off sc1
	v_add_u32_e32 v86, v15, v88
	v_mul_f32_e32 v3, v68, v76
	v_ashrrev_i32_e32 v87, 31, v86
	v_cvt_pk_bf16_f32 v3, v3, s0
	v_lshl_add_u64 v[86:87], v[86:87], 1, s[34:35]
	global_store_short v[86:87], v3, off sc1
	v_add_u32_e32 v86, v58, v88
	v_mul_f32_e32 v3, v66, v76
	v_ashrrev_i32_e32 v87, 31, v86
	v_cvt_pk_bf16_f32 v3, v3, s0
	v_lshl_add_u64 v[86:87], v[86:87], 1, s[34:35]
	global_store_short v[86:87], v3, off sc1
	v_add_u32_e32 v86, v59, v88
	v_mul_f32_e32 v3, v64, v76
	v_ashrrev_i32_e32 v87, 31, v86
	v_cvt_pk_bf16_f32 v3, v3, s0
	v_lshl_add_u64 v[86:87], v[86:87], 1, s[34:35]
	global_store_short v[86:87], v3, off sc1
	v_add_u32_e32 v86, v60, v88
	v_mul_f32_e32 v3, v54, v76
	v_ashrrev_i32_e32 v87, 31, v86
	v_cvt_pk_bf16_f32 v3, v3, s0
	v_lshl_add_u64 v[86:87], v[86:87], 1, s[34:35]
	global_store_short v[86:87], v3, off sc1
	v_add_u32_e32 v86, v61, v88
	v_mul_f32_e32 v3, v52, v76
	v_ashrrev_i32_e32 v87, 31, v86
	v_cvt_pk_bf16_f32 v3, v3, s0
	v_lshl_add_u64 v[86:87], v[86:87], 1, s[34:35]
	global_store_short v[86:87], v3, off sc1
	v_add_u32_e32 v86, v62, v88
	v_mul_f32_e32 v3, v50, v76
	v_ashrrev_i32_e32 v87, 31, v86
	v_cvt_pk_bf16_f32 v3, v3, s0
	v_lshl_add_u64 v[86:87], v[86:87], 1, s[34:35]
	global_store_short v[86:87], v3, off sc1
	v_add_u32_e32 v86, v63, v88
	v_mul_f32_e32 v3, v48, v76
	v_ashrrev_i32_e32 v87, 31, v86
	v_cvt_pk_bf16_f32 v3, v3, s0
	v_lshl_add_u64 v[86:87], v[86:87], 1, s[34:35]
	global_store_short v[86:87], v3, off sc1
	v_add_u32_e32 v86, v84, v88
	v_mul_f32_e32 v3, v40, v76
	v_ashrrev_i32_e32 v87, 31, v86
	v_cvt_pk_bf16_f32 v3, v3, s0
	v_lshl_add_u64 v[86:87], v[86:87], 1, s[34:35]
	global_store_short v[86:87], v3, off sc1
	v_add_u32_e32 v86, v81, v88
	v_mul_f32_e32 v3, v38, v76
	v_ashrrev_i32_e32 v87, 31, v86
	v_cvt_pk_bf16_f32 v3, v3, s0
	v_lshl_add_u64 v[86:87], v[86:87], 1, s[34:35]
	global_store_short v[86:87], v3, off sc1
	v_add_u32_e32 v86, v80, v88
	v_mul_f32_e32 v3, v36, v76
	v_ashrrev_i32_e32 v87, 31, v86
	v_cvt_pk_bf16_f32 v3, v3, s0
	v_lshl_add_u64 v[86:87], v[86:87], 1, s[34:35]
	global_store_short v[86:87], v3, off sc1
	v_add_u32_e32 v86, v79, v88
	v_mul_f32_e32 v3, v34, v76
	v_ashrrev_i32_e32 v87, 31, v86
	v_cvt_pk_bf16_f32 v3, v3, s0
	v_lshl_add_u64 v[86:87], v[86:87], 1, s[34:35]
	global_store_short v[86:87], v3, off sc1
	v_add_u32_e32 v86, v77, v88
	v_mul_f32_e32 v3, v32, v76
	v_ashrrev_i32_e32 v87, 31, v86
	v_cvt_pk_bf16_f32 v3, v3, s0
	v_lshl_add_u64 v[86:87], v[86:87], 1, s[34:35]
	global_store_short v[86:87], v3, off sc1
	global_load_dword v3, v[0:1], off offset:256
	v_add_u32_e32 v86, v11, v85
	v_ashrrev_i32_e32 v87, 31, v86
	v_lshl_add_u64 v[86:87], v[86:87], 1, s[34:35]
	s_waitcnt vmcnt(0)
	v_mul_f32_e32 v57, v57, v3
	v_cvt_pk_bf16_f32 v57, v57, s0
	global_store_short v[86:87], v57, off sc1
	v_add_u32_e32 v86, v12, v85
	v_mul_f32_e32 v57, v47, v3
	v_ashrrev_i32_e32 v87, 31, v86
	v_cvt_pk_bf16_f32 v57, v57, s0
	v_lshl_add_u64 v[86:87], v[86:87], 1, s[34:35]
	global_store_short v[86:87], v57, off sc1
	v_add_u32_e32 v86, v13, v85
	v_mul_f32_e32 v57, v46, v3
	v_ashrrev_i32_e32 v87, 31, v86
	v_cvt_pk_bf16_f32 v57, v57, s0
	v_lshl_add_u64 v[86:87], v[86:87], 1, s[34:35]
	global_store_short v[86:87], v57, off sc1
	v_add_u32_e32 v86, v14, v85
	v_mul_f32_e32 v57, v45, v3
	v_ashrrev_i32_e32 v87, 31, v86
	v_cvt_pk_bf16_f32 v57, v57, s0
	v_lshl_add_u64 v[86:87], v[86:87], 1, s[34:35]
	global_store_short v[86:87], v57, off sc1
	v_add_u32_e32 v86, v15, v85
	v_mul_f32_e32 v57, v44, v3
	v_ashrrev_i32_e32 v87, 31, v86
	v_cvt_pk_bf16_f32 v57, v57, s0
	v_lshl_add_u64 v[86:87], v[86:87], 1, s[34:35]
	global_store_short v[86:87], v57, off sc1
	v_add_u32_e32 v86, v58, v85
	v_mul_f32_e32 v57, v43, v3
	v_ashrrev_i32_e32 v87, 31, v86
	v_cvt_pk_bf16_f32 v57, v57, s0
	v_lshl_add_u64 v[86:87], v[86:87], 1, s[34:35]
	global_store_short v[86:87], v57, off sc1
	v_add_u32_e32 v86, v59, v85
	v_mul_f32_e32 v57, v42, v3
	v_ashrrev_i32_e32 v87, 31, v86
	v_cvt_pk_bf16_f32 v57, v57, s0
	v_lshl_add_u64 v[86:87], v[86:87], 1, s[34:35]
	global_store_short v[86:87], v57, off sc1
	v_add_u32_e32 v86, v60, v85
	v_mul_f32_e32 v57, v23, v3
	v_ashrrev_i32_e32 v87, 31, v86
	v_cvt_pk_bf16_f32 v57, v57, s0
	v_lshl_add_u64 v[86:87], v[86:87], 1, s[34:35]
	global_store_short v[86:87], v57, off sc1
	v_add_u32_e32 v86, v61, v85
	v_mul_f32_e32 v57, v22, v3
	v_ashrrev_i32_e32 v87, 31, v86
	v_cvt_pk_bf16_f32 v57, v57, s0
	v_lshl_add_u64 v[86:87], v[86:87], 1, s[34:35]
	global_store_short v[86:87], v57, off sc1
	v_add_u32_e32 v86, v62, v85
	v_mul_f32_e32 v57, v21, v3
	v_ashrrev_i32_e32 v87, 31, v86
	v_cvt_pk_bf16_f32 v57, v57, s0
	v_lshl_add_u64 v[86:87], v[86:87], 1, s[34:35]
	global_store_short v[86:87], v57, off sc1
	v_add_u32_e32 v86, v63, v85
	v_mul_f32_e32 v57, v20, v3
	v_ashrrev_i32_e32 v87, 31, v86
	v_cvt_pk_bf16_f32 v57, v57, s0
	v_lshl_add_u64 v[86:87], v[86:87], 1, s[34:35]
	global_store_short v[86:87], v57, off sc1
	v_add_u32_e32 v86, v84, v85
	v_mul_f32_e32 v57, v19, v3
	v_ashrrev_i32_e32 v87, 31, v86
	v_cvt_pk_bf16_f32 v57, v57, s0
	v_lshl_add_u64 v[86:87], v[86:87], 1, s[34:35]
	global_store_short v[86:87], v57, off sc1
	v_add_u32_e32 v86, v81, v85
	v_mul_f32_e32 v57, v18, v3
	v_ashrrev_i32_e32 v87, 31, v86
	v_cvt_pk_bf16_f32 v57, v57, s0
	v_lshl_add_u64 v[86:87], v[86:87], 1, s[34:35]
	global_store_short v[86:87], v57, off sc1
	v_add_u32_e32 v86, v80, v85
	v_mul_f32_e32 v57, v17, v3
	v_ashrrev_i32_e32 v87, 31, v86
	v_cvt_pk_bf16_f32 v57, v57, s0
	v_lshl_add_u64 v[86:87], v[86:87], 1, s[34:35]
	global_store_short v[86:87], v57, off sc1
	v_add_u32_e32 v86, v79, v85
	v_mul_f32_e32 v57, v16, v3
	v_ashrrev_i32_e32 v87, 31, v86
	v_cvt_pk_bf16_f32 v57, v57, s0
	v_lshl_add_u64 v[86:87], v[86:87], 1, s[34:35]
	global_store_short v[86:87], v57, off sc1
	v_add_u32_e32 v86, v77, v85
	v_mul_f32_e32 v3, v82, v3
	v_ashrrev_i32_e32 v87, 31, v86
	v_cvt_pk_bf16_f32 v3, v3, s0
	v_lshl_add_u64 v[86:87], v[86:87], 1, s[34:35]
	global_store_short v[86:87], v3, off sc1
	global_load_dword v3, v[0:1], off offset:384
	s_waitcnt vmcnt(0)
	v_mul_f32_e32 v0, v56, v3
	v_cvt_pk_bf16_f32 v56, v0, s0
	v_add_u32_e32 v0, v11, v10
	v_ashrrev_i32_e32 v1, 31, v0
	v_lshl_add_u64 v[0:1], v[0:1], 1, s[34:35]
	global_store_short v[0:1], v56, off sc1
	v_mul_f32_e32 v0, v31, v3
	v_cvt_pk_bf16_f32 v11, v0, s0
	v_add_u32_e32 v0, v12, v10
	v_ashrrev_i32_e32 v1, 31, v0
	v_lshl_add_u64 v[0:1], v[0:1], 1, s[34:35]
	global_store_short v[0:1], v11, off sc1
	v_mul_f32_e32 v0, v30, v3
	v_cvt_pk_bf16_f32 v11, v0, s0
	v_add_u32_e32 v0, v13, v10
	v_ashrrev_i32_e32 v1, 31, v0
	v_lshl_add_u64 v[0:1], v[0:1], 1, s[34:35]
	global_store_short v[0:1], v11, off sc1
	v_mul_f32_e32 v0, v29, v3
	v_cvt_pk_bf16_f32 v11, v0, s0
	v_add_u32_e32 v0, v14, v10
	v_ashrrev_i32_e32 v1, 31, v0
	v_lshl_add_u64 v[0:1], v[0:1], 1, s[34:35]
	global_store_short v[0:1], v11, off sc1
	v_mul_f32_e32 v0, v28, v3
	v_cvt_pk_bf16_f32 v11, v0, s0
	v_add_u32_e32 v0, v15, v10
	v_ashrrev_i32_e32 v1, 31, v0
	v_lshl_add_u64 v[0:1], v[0:1], 1, s[34:35]
	global_store_short v[0:1], v11, off sc1
	v_mul_f32_e32 v0, v27, v3
	v_cvt_pk_bf16_f32 v11, v0, s0
	v_add_u32_e32 v0, v58, v10
	v_ashrrev_i32_e32 v1, 31, v0
	v_lshl_add_u64 v[0:1], v[0:1], 1, s[34:35]
	global_store_short v[0:1], v11, off sc1
	v_mul_f32_e32 v0, v26, v3
	v_cvt_pk_bf16_f32 v11, v0, s0
	v_add_u32_e32 v0, v59, v10
	v_ashrrev_i32_e32 v1, 31, v0
	v_lshl_add_u64 v[0:1], v[0:1], 1, s[34:35]
	global_store_short v[0:1], v11, off sc1
	v_mul_f32_e32 v0, v25, v3
	v_cvt_pk_bf16_f32 v11, v0, s0
	v_add_u32_e32 v0, v60, v10
	v_ashrrev_i32_e32 v1, 31, v0
	v_lshl_add_u64 v[0:1], v[0:1], 1, s[34:35]
	global_store_short v[0:1], v11, off sc1
	v_mul_f32_e32 v0, v24, v3
	v_cvt_pk_bf16_f32 v11, v0, s0
	v_add_u32_e32 v0, v61, v10
	v_ashrrev_i32_e32 v1, 31, v0
	v_lshl_add_u64 v[0:1], v[0:1], 1, s[34:35]
	global_store_short v[0:1], v11, off sc1
	v_mul_f32_e32 v0, v9, v3
	v_cvt_pk_bf16_f32 v11, v0, s0
	v_add_u32_e32 v0, v62, v10
	v_ashrrev_i32_e32 v1, 31, v0
	v_lshl_add_u64 v[0:1], v[0:1], 1, s[34:35]
	global_store_short v[0:1], v11, off sc1
	v_mul_f32_e32 v0, v8, v3
	v_cvt_pk_bf16_f32 v11, v0, s0
	v_add_u32_e32 v0, v63, v10
	v_ashrrev_i32_e32 v1, 31, v0
	v_lshl_add_u64 v[0:1], v[0:1], 1, s[34:35]
	global_store_short v[0:1], v11, off sc1
	v_mul_f32_e32 v0, v7, v3
	v_cvt_pk_bf16_f32 v11, v0, s0
	v_add_u32_e32 v0, v84, v10
	v_ashrrev_i32_e32 v1, 31, v0
	v_lshl_add_u64 v[0:1], v[0:1], 1, s[34:35]
	global_store_short v[0:1], v11, off sc1
	v_mul_f32_e32 v0, v6, v3
	v_cvt_pk_bf16_f32 v11, v0, s0
	v_add_u32_e32 v0, v81, v10
	v_ashrrev_i32_e32 v1, 31, v0
	v_lshl_add_u64 v[0:1], v[0:1], 1, s[34:35]
	global_store_short v[0:1], v11, off sc1
	v_mul_f32_e32 v0, v5, v3
	v_cvt_pk_bf16_f32 v11, v0, s0
	v_add_u32_e32 v0, v80, v10
	v_ashrrev_i32_e32 v1, 31, v0
	v_lshl_add_u64 v[0:1], v[0:1], 1, s[34:35]
	global_store_short v[0:1], v11, off sc1
	v_mul_f32_e32 v0, v4, v3
	v_cvt_pk_bf16_f32 v11, v0, s0
	v_add_u32_e32 v0, v79, v10
	v_ashrrev_i32_e32 v1, 31, v0
	v_lshl_add_u64 v[0:1], v[0:1], 1, s[34:35]
	global_store_short v[0:1], v11, off sc1
	v_mul_f32_e32 v0, v83, v3
	v_cvt_pk_bf16_f32 v3, v0, s0
	v_add_u32_e32 v0, v77, v10
	v_ashrrev_i32_e32 v1, 31, v0
	v_lshl_add_u64 v[0:1], v[0:1], 1, s[34:35]
	global_store_short v[0:1], v3, off sc1
	v_and_b32_e32 v1, 64, v214
	v_xor_b32_e32 v0, 1, v214
	v_add_u32_e32 v1, 64, v1
	v_cmp_lt_i32_e32 vcc, v0, v1
	s_nop 1
	v_cndmask_b32_e32 v0, v214, v0, vcc
	v_lshlrev_b32_e32 v3, 2, v0
	v_xor_b32_e32 v0, 2, v214
	v_cmp_lt_i32_e32 vcc, v0, v1
	s_nop 1
	v_cndmask_b32_e32 v0, v214, v0, vcc
	v_lshlrev_b32_e32 v10, 2, v0
	v_xor_b32_e32 v0, 4, v214
	v_cmp_lt_i32_e32 vcc, v0, v1
	s_nop 1
	v_cndmask_b32_e32 v0, v214, v0, vcc
	v_lshlrev_b32_e32 v11, 2, v0
	v_xor_b32_e32 v0, 8, v214
	v_cmp_lt_i32_e32 vcc, v0, v1
	s_nop 1
	v_cndmask_b32_e32 v0, v214, v0, vcc
	v_lshlrev_b32_e32 v12, 2, v0
	v_xor_b32_e32 v0, 16, v214
	v_cmp_lt_i32_e32 vcc, v0, v1
	v_add_f32_dpp v1, v2, v2 quad_perm:[1,0,3,2] row_mask:0xf bank_mask:0xf
	v_cndmask_b32_e32 v0, v214, v0, vcc
	v_lshlrev_b32_e32 v13, 2, v0
	v_lshl_add_u32 v0, s10, 14, v164
	v_add_f32_dpp v1, v1, v1 quad_perm:[2,3,0,1] row_mask:0xf bank_mask:0xf
	s_nop 0
	v_add_f32_dpp v1, v1, v1 row_half_mirror row_mask:0xf bank_mask:0xf
	s_nop 0
	v_add_f32_dpp v2, v1, v1 row_mirror row_mask:0xf bank_mask:0xf
	ds_bpermute_b32 v14, v13, v2
	v_ashrrev_i32_e32 v1, 31, v0
	s_and_saveexec_b64 s[4:5], s[0:1]
	s_cbranch_execz .LBB0_499
	s_waitcnt lgkmcnt(0)
	v_add_f32_e32 v2, v2, v14
	v_lshl_add_u64 v[14:15], v[0:1], 2, s[36:37]
	global_store_dword v[14:15], v2, off sc1
.LBB0_499:
	s_or_b64 exec, exec, s[4:5]
	s_waitcnt lgkmcnt(0)
	v_pk_mul_f32 v[14:15], v[74:75], v[74:75]
	s_nop 0
	v_add_f32_e32 v2, v15, v14
	v_fmac_f32_e32 v2, v47, v47
	v_fmac_f32_e32 v2, v31, v31
	s_nop 0
	v_add_f32_dpp v2, v2, v2 quad_perm:[1,0,3,2] row_mask:0xf bank_mask:0xf
	s_nop 0
	v_add_f32_dpp v2, v2, v2 quad_perm:[2,3,0,1] row_mask:0xf bank_mask:0xf
	s_nop 0
	v_add_f32_dpp v2, v2, v2 row_half_mirror row_mask:0xf bank_mask:0xf
	s_nop 0
	v_add_f32_dpp v2, v2, v2 row_mirror row_mask:0xf bank_mask:0xf
	ds_bpermute_b32 v14, v13, v2
	s_and_saveexec_b64 s[4:5], s[0:1]
	s_cbranch_execz .LBB0_501
	s_waitcnt lgkmcnt(0)
	v_add_f32_e32 v2, v2, v14
	v_lshl_add_u64 v[14:15], v[0:1], 2, s[36:37]
	global_store_dword v[14:15], v2, off offset:4 sc1
.LBB0_501:
	s_or_b64 exec, exec, s[4:5]
	s_waitcnt lgkmcnt(0)
	v_pk_mul_f32 v[14:15], v[72:73], v[72:73]
	s_nop 0
	v_add_f32_e32 v2, v15, v14
	v_fmac_f32_e32 v2, v46, v46
	v_fmac_f32_e32 v2, v30, v30
	s_nop 0
	v_add_f32_dpp v2, v2, v2 quad_perm:[1,0,3,2] row_mask:0xf bank_mask:0xf
	s_nop 0
	v_add_f32_dpp v2, v2, v2 quad_perm:[2,3,0,1] row_mask:0xf bank_mask:0xf
	s_nop 0
	v_add_f32_dpp v2, v2, v2 row_half_mirror row_mask:0xf bank_mask:0xf
	s_nop 0
	v_add_f32_dpp v2, v2, v2 row_mirror row_mask:0xf bank_mask:0xf
	ds_bpermute_b32 v14, v13, v2
	s_and_saveexec_b64 s[4:5], s[0:1]
	s_cbranch_execz .LBB0_503
	s_waitcnt lgkmcnt(0)
	v_add_f32_e32 v2, v2, v14
	v_lshl_add_u64 v[14:15], v[0:1], 2, s[36:37]
	global_store_dword v[14:15], v2, off offset:8 sc1
.LBB0_503:
	s_or_b64 exec, exec, s[4:5]
	s_waitcnt lgkmcnt(0)
	v_pk_mul_f32 v[14:15], v[70:71], v[70:71]
	s_nop 0
	v_add_f32_e32 v2, v15, v14
	v_fmac_f32_e32 v2, v45, v45
	v_fmac_f32_e32 v2, v29, v29
	s_nop 0
	v_add_f32_dpp v2, v2, v2 quad_perm:[1,0,3,2] row_mask:0xf bank_mask:0xf
	s_nop 0
	v_add_f32_dpp v2, v2, v2 quad_perm:[2,3,0,1] row_mask:0xf bank_mask:0xf
	s_nop 0
	v_add_f32_dpp v2, v2, v2 row_half_mirror row_mask:0xf bank_mask:0xf
	s_nop 0
	v_add_f32_dpp v2, v2, v2 row_mirror row_mask:0xf bank_mask:0xf
	ds_bpermute_b32 v14, v13, v2
	s_and_saveexec_b64 s[4:5], s[0:1]
	s_cbranch_execz .LBB0_505
	s_waitcnt lgkmcnt(0)
	v_add_f32_e32 v2, v2, v14
	v_lshl_add_u64 v[14:15], v[0:1], 2, s[36:37]
	global_store_dword v[14:15], v2, off offset:12 sc1
.LBB0_505:
	s_or_b64 exec, exec, s[4:5]
	s_waitcnt lgkmcnt(0)
	v_pk_mul_f32 v[14:15], v[68:69], v[68:69]
	s_nop 0
	v_add_f32_e32 v2, v15, v14
	v_fmac_f32_e32 v2, v44, v44
	v_fmac_f32_e32 v2, v28, v28
	s_nop 0
	v_add_f32_dpp v2, v2, v2 quad_perm:[1,0,3,2] row_mask:0xf bank_mask:0xf
	s_nop 0
	v_add_f32_dpp v2, v2, v2 quad_perm:[2,3,0,1] row_mask:0xf bank_mask:0xf
	s_nop 0
	v_add_f32_dpp v2, v2, v2 row_half_mirror row_mask:0xf bank_mask:0xf
	s_nop 0
	v_add_f32_dpp v2, v2, v2 row_mirror row_mask:0xf bank_mask:0xf
	ds_bpermute_b32 v14, v13, v2
	s_and_saveexec_b64 s[4:5], s[0:1]
	s_cbranch_execz .LBB0_507
	s_waitcnt lgkmcnt(0)
	v_add_f32_e32 v2, v2, v14
	v_lshl_add_u64 v[14:15], v[0:1], 2, s[36:37]
	global_store_dword v[14:15], v2, off offset:32 sc1
.LBB0_507:
	s_or_b64 exec, exec, s[4:5]
	s_waitcnt lgkmcnt(0)
	v_pk_mul_f32 v[14:15], v[66:67], v[66:67]
	s_nop 0
	v_add_f32_e32 v2, v15, v14
	v_fmac_f32_e32 v2, v43, v43
	v_fmac_f32_e32 v2, v27, v27
	s_nop 0
	v_add_f32_dpp v2, v2, v2 quad_perm:[1,0,3,2] row_mask:0xf bank_mask:0xf
	s_nop 0
	v_add_f32_dpp v2, v2, v2 quad_perm:[2,3,0,1] row_mask:0xf bank_mask:0xf
	s_nop 0
	v_add_f32_dpp v2, v2, v2 row_half_mirror row_mask:0xf bank_mask:0xf
	s_nop 0
	v_add_f32_dpp v2, v2, v2 row_mirror row_mask:0xf bank_mask:0xf
	ds_bpermute_b32 v14, v13, v2
	s_and_saveexec_b64 s[4:5], s[0:1]
	s_cbranch_execz .LBB0_509
	s_waitcnt lgkmcnt(0)
	v_add_f32_e32 v2, v2, v14
	v_lshl_add_u64 v[14:15], v[0:1], 2, s[36:37]
	global_store_dword v[14:15], v2, off offset:36 sc1
.LBB0_509:
	s_or_b64 exec, exec, s[4:5]
	s_waitcnt lgkmcnt(0)
	v_pk_mul_f32 v[14:15], v[64:65], v[64:65]
	s_nop 0
	v_add_f32_e32 v2, v15, v14
	v_fmac_f32_e32 v2, v42, v42
	v_fmac_f32_e32 v2, v26, v26
	s_nop 0
	v_add_f32_dpp v2, v2, v2 quad_perm:[1,0,3,2] row_mask:0xf bank_mask:0xf
	s_nop 0
	v_add_f32_dpp v2, v2, v2 quad_perm:[2,3,0,1] row_mask:0xf bank_mask:0xf
	s_nop 0
	v_add_f32_dpp v2, v2, v2 row_half_mirror row_mask:0xf bank_mask:0xf
	s_nop 0
	v_add_f32_dpp v2, v2, v2 row_mirror row_mask:0xf bank_mask:0xf
	ds_bpermute_b32 v14, v13, v2
	s_and_saveexec_b64 s[4:5], s[0:1]
	s_cbranch_execz .LBB0_511
	s_waitcnt lgkmcnt(0)
	v_add_f32_e32 v2, v2, v14
	v_lshl_add_u64 v[14:15], v[0:1], 2, s[36:37]
	global_store_dword v[14:15], v2, off offset:40 sc1
.LBB0_511:
	s_or_b64 exec, exec, s[4:5]
	s_waitcnt lgkmcnt(0)
	v_pk_mul_f32 v[14:15], v[54:55], v[54:55]
	s_nop 0
	v_add_f32_e32 v2, v15, v14
	v_fmac_f32_e32 v2, v23, v23
	v_fmac_f32_e32 v2, v25, v25
	s_nop 0
	v_add_f32_dpp v2, v2, v2 quad_perm:[1,0,3,2] row_mask:0xf bank_mask:0xf
	s_nop 0
	v_add_f32_dpp v2, v2, v2 quad_perm:[2,3,0,1] row_mask:0xf bank_mask:0xf
	s_nop 0
	v_add_f32_dpp v2, v2, v2 row_half_mirror row_mask:0xf bank_mask:0xf
	s_nop 0
	v_add_f32_dpp v2, v2, v2 row_mirror row_mask:0xf bank_mask:0xf
	ds_bpermute_b32 v14, v13, v2
	s_and_saveexec_b64 s[4:5], s[0:1]
	s_cbranch_execz .LBB0_513
	s_waitcnt lgkmcnt(0)
	v_add_f32_e32 v2, v2, v14
	v_lshl_add_u64 v[14:15], v[0:1], 2, s[36:37]
	global_store_dword v[14:15], v2, off offset:44 sc1
.LBB0_513:
	s_or_b64 exec, exec, s[4:5]
	s_waitcnt lgkmcnt(0)
	v_pk_mul_f32 v[14:15], v[52:53], v[52:53]
	s_nop 0
	v_add_f32_e32 v2, v15, v14
	v_fmac_f32_e32 v2, v22, v22
	v_fmac_f32_e32 v2, v24, v24
	s_nop 0
	v_add_f32_dpp v2, v2, v2 quad_perm:[1,0,3,2] row_mask:0xf bank_mask:0xf
	s_nop 0
	v_add_f32_dpp v2, v2, v2 quad_perm:[2,3,0,1] row_mask:0xf bank_mask:0xf
	s_nop 0
	v_add_f32_dpp v2, v2, v2 row_half_mirror row_mask:0xf bank_mask:0xf
	s_nop 0
	v_add_f32_dpp v2, v2, v2 row_mirror row_mask:0xf bank_mask:0xf
	ds_bpermute_b32 v14, v13, v2
	s_and_saveexec_b64 s[4:5], s[0:1]
	s_cbranch_execz .LBB0_515
	s_waitcnt lgkmcnt(0)
	v_add_f32_e32 v2, v2, v14
	v_lshl_add_u64 v[14:15], v[0:1], 2, s[36:37]
	global_store_dword v[14:15], v2, off offset:64 sc1
.LBB0_515:
	s_or_b64 exec, exec, s[4:5]
	s_waitcnt lgkmcnt(0)
	v_pk_mul_f32 v[14:15], v[50:51], v[50:51]
	s_nop 0
	v_add_f32_e32 v2, v15, v14
	v_fmac_f32_e32 v2, v21, v21
	v_fmac_f32_e32 v2, v9, v9
	s_nop 0
	v_add_f32_dpp v2, v2, v2 quad_perm:[1,0,3,2] row_mask:0xf bank_mask:0xf
	s_nop 0
	v_add_f32_dpp v2, v2, v2 quad_perm:[2,3,0,1] row_mask:0xf bank_mask:0xf
	s_nop 0
	v_add_f32_dpp v2, v2, v2 row_half_mirror row_mask:0xf bank_mask:0xf
	s_nop 0
	v_add_f32_dpp v2, v2, v2 row_mirror row_mask:0xf bank_mask:0xf
	ds_bpermute_b32 v9, v13, v2
	s_and_saveexec_b64 s[4:5], s[0:1]
	s_cbranch_execz .LBB0_517
	s_waitcnt lgkmcnt(0)
	v_add_f32_e32 v2, v2, v9
	v_lshl_add_u64 v[14:15], v[0:1], 2, s[36:37]
	global_store_dword v[14:15], v2, off offset:68 sc1
.LBB0_517:
	s_or_b64 exec, exec, s[4:5]
	v_pk_mul_f32 v[14:15], v[48:49], v[48:49]
	s_nop 0
	v_add_f32_e32 v2, v15, v14
	v_fmac_f32_e32 v2, v20, v20
	v_fmac_f32_e32 v2, v8, v8
	s_waitcnt lgkmcnt(0)
	s_nop 0
	v_add_f32_dpp v2, v2, v2 quad_perm:[1,0,3,2] row_mask:0xf bank_mask:0xf
	s_nop 0
	v_add_f32_dpp v2, v2, v2 quad_perm:[2,3,0,1] row_mask:0xf bank_mask:0xf
	s_nop 0
	v_add_f32_dpp v2, v2, v2 row_half_mirror row_mask:0xf bank_mask:0xf
	s_nop 0
	v_add_f32_dpp v2, v2, v2 row_mirror row_mask:0xf bank_mask:0xf
	ds_bpermute_b32 v8, v13, v2
	s_and_saveexec_b64 s[4:5], s[0:1]
	s_cbranch_execz .LBB0_519
	s_waitcnt lgkmcnt(0)
	v_add_f32_e32 v2, v2, v8
	v_lshl_add_u64 v[8:9], v[0:1], 2, s[36:37]
	global_store_dword v[8:9], v2, off offset:72 sc1
.LBB0_519:
	s_or_b64 exec, exec, s[4:5]
	s_waitcnt lgkmcnt(0)
	v_pk_mul_f32 v[8:9], v[40:41], v[40:41]
	s_nop 0
	v_add_f32_e32 v2, v9, v8
	v_fmac_f32_e32 v2, v19, v19
	v_fmac_f32_e32 v2, v7, v7
	s_nop 0
	v_add_f32_dpp v2, v2, v2 quad_perm:[1,0,3,2] row_mask:0xf bank_mask:0xf
	s_nop 0
	v_add_f32_dpp v2, v2, v2 quad_perm:[2,3,0,1] row_mask:0xf bank_mask:0xf
	s_nop 0
	v_add_f32_dpp v2, v2, v2 row_half_mirror row_mask:0xf bank_mask:0xf
	s_nop 0
	v_add_f32_dpp v2, v2, v2 row_mirror row_mask:0xf bank_mask:0xf
	ds_bpermute_b32 v7, v13, v2
	s_and_saveexec_b64 s[4:5], s[0:1]
	s_cbranch_execz .LBB0_521
	s_waitcnt lgkmcnt(0)
	v_add_f32_e32 v2, v2, v7
	v_lshl_add_u64 v[8:9], v[0:1], 2, s[36:37]
	global_store_dword v[8:9], v2, off offset:76 sc1
.LBB0_521:
	s_or_b64 exec, exec, s[4:5]
	v_pk_mul_f32 v[8:9], v[38:39], v[38:39]
	s_nop 0
	v_add_f32_e32 v2, v9, v8
	v_fmac_f32_e32 v2, v18, v18
	v_fmac_f32_e32 v2, v6, v6
	s_waitcnt lgkmcnt(0)
	s_nop 0
	v_add_f32_dpp v2, v2, v2 quad_perm:[1,0,3,2] row_mask:0xf bank_mask:0xf
	s_nop 0
	v_add_f32_dpp v2, v2, v2 quad_perm:[2,3,0,1] row_mask:0xf bank_mask:0xf
	s_nop 0
	v_add_f32_dpp v2, v2, v2 row_half_mirror row_mask:0xf bank_mask:0xf
	s_nop 0
	v_add_f32_dpp v2, v2, v2 row_mirror row_mask:0xf bank_mask:0xf
	ds_bpermute_b32 v6, v13, v2
	s_and_saveexec_b64 s[4:5], s[0:1]
	s_cbranch_execz .LBB0_523
	s_waitcnt lgkmcnt(0)
	v_add_f32_e32 v2, v2, v6
	v_lshl_add_u64 v[6:7], v[0:1], 2, s[36:37]
	global_store_dword v[6:7], v2, off offset:96 sc1
.LBB0_523:
	s_or_b64 exec, exec, s[4:5]
	s_waitcnt lgkmcnt(0)
	v_pk_mul_f32 v[6:7], v[36:37], v[36:37]
	s_nop 0
	v_add_f32_e32 v2, v7, v6
	v_fmac_f32_e32 v2, v17, v17
	v_fmac_f32_e32 v2, v5, v5
	s_nop 0
	v_add_f32_dpp v2, v2, v2 quad_perm:[1,0,3,2] row_mask:0xf bank_mask:0xf
	s_nop 0
	v_add_f32_dpp v2, v2, v2 quad_perm:[2,3,0,1] row_mask:0xf bank_mask:0xf
	s_nop 0
	v_add_f32_dpp v2, v2, v2 row_half_mirror row_mask:0xf bank_mask:0xf
	s_nop 0
	v_add_f32_dpp v2, v2, v2 row_mirror row_mask:0xf bank_mask:0xf
	ds_bpermute_b32 v5, v13, v2
	s_and_saveexec_b64 s[4:5], s[0:1]
	s_cbranch_execz .LBB0_525
	s_waitcnt lgkmcnt(0)
	v_add_f32_e32 v2, v2, v5
	v_lshl_add_u64 v[6:7], v[0:1], 2, s[36:37]
	global_store_dword v[6:7], v2, off offset:100 sc1
.LBB0_525:
	s_or_b64 exec, exec, s[4:5]
	v_pk_mul_f32 v[6:7], v[34:35], v[34:35]
	s_nop 0
	v_add_f32_e32 v2, v7, v6
	v_fmac_f32_e32 v2, v16, v16
	v_fmac_f32_e32 v2, v4, v4
	s_waitcnt lgkmcnt(0)
	s_nop 0
	v_add_f32_dpp v2, v2, v2 quad_perm:[1,0,3,2] row_mask:0xf bank_mask:0xf
	s_nop 0
	v_add_f32_dpp v2, v2, v2 quad_perm:[2,3,0,1] row_mask:0xf bank_mask:0xf
	s_nop 0
	v_add_f32_dpp v2, v2, v2 row_half_mirror row_mask:0xf bank_mask:0xf
	s_nop 0
	v_add_f32_dpp v2, v2, v2 row_mirror row_mask:0xf bank_mask:0xf
	ds_bpermute_b32 v4, v13, v2
	s_and_saveexec_b64 s[4:5], s[0:1]
	s_cbranch_execz .LBB0_527
	s_waitcnt lgkmcnt(0)
	v_add_f32_e32 v2, v2, v4
	v_lshl_add_u64 v[4:5], v[0:1], 2, s[36:37]
	global_store_dword v[4:5], v2, off offset:104 sc1
.LBB0_527:
	s_or_b64 exec, exec, s[4:5]
	s_waitcnt lgkmcnt(0)
	v_pk_mul_f32 v[4:5], v[32:33], v[32:33]
	s_nop 0
	v_add_f32_e32 v2, v5, v4
	v_fmac_f32_e32 v2, v82, v82
	v_fmac_f32_e32 v2, v83, v83
	s_nop 0
	v_add_f32_dpp v2, v2, v2 quad_perm:[1,0,3,2] row_mask:0xf bank_mask:0xf
	s_nop 0
	v_add_f32_dpp v2, v2, v2 quad_perm:[2,3,0,1] row_mask:0xf bank_mask:0xf
	s_nop 0
	v_add_f32_dpp v2, v2, v2 row_half_mirror row_mask:0xf bank_mask:0xf
	s_nop 0
	v_add_f32_dpp v2, v2, v2 row_mirror row_mask:0xf bank_mask:0xf
	ds_bpermute_b32 v3, v13, v2
	s_and_saveexec_b64 s[4:5], s[0:1]
	s_cbranch_execz .LBB0_256
	s_waitcnt lgkmcnt(0)
	v_add_f32_e32 v2, v2, v3
	v_lshl_add_u64 v[0:1], v[0:1], 2, s[36:37]
	global_store_dword v[0:1], v2, off offset:108 sc1
	s_branch .LBB0_256

.LBB0_576:
	s_mul_hi_i32 s0, s71, 0x2aaaaaab
	s_lshr_b32 s1, s0, 31
	s_ashr_i32 s0, s0, 4
	s_add_i32 s0, s0, s1
	s_lshl_b32 s1, s0, 3
	s_mulk_i32 s0, 0xffa0
	s_add_i32 s66, s71, s0
	s_ashr_i32 s0, s66, 31
	s_lshr_b32 s0, s0, 29
	s_add_i32 s0, s66, s0
	s_ashr_i32 s72, s0, 3
	s_and_b32 s0, s0, -8
	s_sub_i32 s74, s66, s0
	s_add_i32 s74, s74, s1
	s_lshl_b32 s73, s74, 7
	v_readfirstlane_b32 s85, v100
	s_lshl_b32 s67, s72, 7
	v_mad_i64_i32 v[72:73], s[0:1], s73, v99, v[66:67]
	s_mov_b32 m0, s85
	v_readfirstlane_b32 s78, v101
	v_mad_i64_i32 v[70:71], s[0:1], s67, v99, v[68:69]
	global_load_lds_dwordx4 v[72:73], off
	s_mov_b32 m0, s78
	v_readfirstlane_b32 s79, v102
	global_load_lds_dwordx4 v[70:71], off
	v_lshl_add_u64 v[0:1], v[72:73], 0, s[18:19]
	s_mov_b32 m0, s79
	v_readfirstlane_b32 s80, v103
	global_load_lds_dwordx4 v[0:1], off
	v_lshl_add_u64 v[0:1], v[70:71], 0, s[18:19]
	s_mov_b32 m0, s80
	v_readfirstlane_b32 s81, v104
	global_load_lds_dwordx4 v[0:1], off
	v_lshl_add_u64 v[0:1], v[72:73], 0, s[20:21]
	s_mov_b32 m0, s81
	v_readfirstlane_b32 s82, v105
	global_load_lds_dwordx4 v[0:1], off
	v_lshl_add_u64 v[0:1], v[70:71], 0, s[20:21]
	s_mov_b32 m0, s82
	v_readfirstlane_b32 s83, v106
	global_load_lds_dwordx4 v[0:1], off
	v_lshl_add_u64 v[0:1], v[72:73], 0, s[22:23]
	s_mov_b32 m0, s83
	v_readfirstlane_b32 s84, v107
	global_load_lds_dwordx4 v[0:1], off
	v_lshl_add_u64 v[0:1], v[70:71], 0, s[22:23]
	s_mov_b32 m0, s84
	v_readfirstlane_b32 s77, v108
	global_load_lds_dwordx4 v[0:1], off
	v_lshl_add_u64 v[0:1], v[72:73], 0, s[24:25]
	s_mov_b32 m0, s77
	v_readfirstlane_b32 s0, v109
	s_waitcnt vmcnt(0)
	s_waitcnt vmcnt(0) lgkmcnt(0)
	s_barrier
	v_lshl_add_u64 v[2:3], v[70:71], 0, s[24:25]
	global_load_lds_dwordx4 v[0:1], off
	s_mov_b32 m0, s0
	v_readfirstlane_b32 s1, v110
	global_load_lds_dwordx4 v[2:3], off
	v_lshl_add_u64 v[0:1], v[72:73], 0, s[26:27]
	s_mov_b32 m0, s1
	v_readfirstlane_b32 s67, v111
	global_load_lds_dwordx4 v[0:1], off
	v_lshl_add_u64 v[0:1], v[70:71], 0, s[26:27]
	s_mov_b32 m0, s67
	v_readfirstlane_b32 s68, v112
	global_load_lds_dwordx4 v[0:1], off
	v_lshl_add_u64 v[0:1], v[72:73], 0, s[28:29]
	s_mov_b32 m0, s68
	v_readfirstlane_b32 s69, v113
	global_load_lds_dwordx4 v[0:1], off
	v_lshl_add_u64 v[0:1], v[70:71], 0, s[28:29]
	s_mov_b32 m0, s69
	v_readfirstlane_b32 s75, v114
	global_load_lds_dwordx4 v[0:1], off
	v_lshl_add_u64 v[0:1], v[72:73], 0, s[30:31]
	s_mov_b32 m0, s75
	v_readfirstlane_b32 s76, v115
	global_load_lds_dwordx4 v[0:1], off
	v_lshl_add_u64 v[0:1], v[70:71], 0, s[30:31]
	s_mov_b32 m0, s76
	v_add_u32_e32 v121, v75, v77
	global_load_lds_dwordx4 v[0:1], off
	ds_read_b128 v[0:3], v116
	ds_read_b128 v[4:7], v117 offset:16384
	ds_read_b128 v[8:11], v117 offset:20480
	ds_read_b128 v[12:15], v117 offset:24576
	ds_read_b128 v[122:125], v117 offset:28672
	ds_read_b128 v[126:129], v118
	ds_read_b128 v[130:133], v121 offset:16384
	ds_read_b128 v[134:137], v121 offset:20480
	ds_read_b128 v[138:141], v121 offset:24576
	ds_read_b128 v[142:145], v121 offset:28672
	s_setprio 1
	s_waitcnt lgkmcnt(0)
	v_mfma_f32_32x32x16_bf16 v[48:63], v[0:3], v[4:7], 0
	v_mfma_f32_32x32x16_bf16 v[32:47], v[0:3], v[8:11], 0
	v_mfma_f32_32x32x16_bf16 v[16:31], v[0:3], v[12:15], 0
	v_mfma_f32_32x32x16_bf16 v[0:15], v[0:3], v[122:125], 0
	s_setprio 0
	v_add_u32_e32 v162, v76, v78
	v_add_u32_e32 v163, v75, v78
	ds_read_b128 v[122:125], v162
	ds_read_b128 v[146:149], v163 offset:16384
	ds_read_b128 v[150:153], v163 offset:20480
	ds_read_b128 v[154:157], v163 offset:24576
	ds_read_b128 v[158:161], v163 offset:28672
	s_setprio 1
	v_mfma_f32_32x32x16_bf16 v[48:63], v[126:129], v[130:133], v[48:63]
	v_mfma_f32_32x32x16_bf16 v[32:47], v[126:129], v[134:137], v[32:47]
	v_mfma_f32_32x32x16_bf16 v[16:31], v[126:129], v[138:141], v[16:31]
	v_mfma_f32_32x32x16_bf16 v[0:15], v[126:129], v[142:145], v[0:15]
	s_setprio 0
	v_add_u32_e32 v164, v76, v79
	v_add_u32_e32 v165, v75, v79
	ds_read_b128 v[126:129], v164
	ds_read_b128 v[130:133], v165 offset:16384
	ds_read_b128 v[134:137], v165 offset:20480
	ds_read_b128 v[138:141], v165 offset:24576
	ds_read_b128 v[142:145], v165 offset:28672
	s_setprio 1
	s_waitcnt lgkmcnt(0)
	v_mfma_f32_32x32x16_bf16 v[48:63], v[122:125], v[146:149], v[48:63]
	v_mfma_f32_32x32x16_bf16 v[32:47], v[122:125], v[150:153], v[32:47]
	v_mfma_f32_32x32x16_bf16 v[16:31], v[122:125], v[154:157], v[16:31]
	v_mfma_f32_32x32x16_bf16 v[0:15], v[122:125], v[158:161], v[0:15]
	s_setprio 0
	s_setprio 1
	v_mfma_f32_32x32x16_bf16 v[48:63], v[126:129], v[130:133], v[48:63]
	v_mfma_f32_32x32x16_bf16 v[32:47], v[126:129], v[134:137], v[32:47]
	v_mfma_f32_32x32x16_bf16 v[16:31], v[126:129], v[138:141], v[16:31]
	v_mfma_f32_32x32x16_bf16 v[0:15], v[126:129], v[142:145], v[0:15]
	s_setprio 0
	s_mov_b32 m0, s85
	v_lshl_add_u64 v[122:123], v[72:73], 0, s[34:35]
	s_waitcnt vmcnt(0)
	s_waitcnt vmcnt(0)
	s_barrier
	v_lshl_add_u64 v[124:125], v[70:71], 0, s[34:35]
	global_load_lds_dwordx4 v[122:123], off
	s_mov_b32 m0, s78
	v_lshl_add_u64 v[122:123], v[72:73], 0, s[36:37]
	global_load_lds_dwordx4 v[124:125], off
	s_mov_b32 m0, s79
	s_nop 0
	global_load_lds_dwordx4 v[122:123], off
	v_lshl_add_u64 v[122:123], v[70:71], 0, s[36:37]
	s_mov_b32 m0, s80
	s_nop 0
	global_load_lds_dwordx4 v[122:123], off
	v_lshl_add_u64 v[122:123], v[72:73], 0, s[38:39]
	s_mov_b32 m0, s81
	s_nop 0
	global_load_lds_dwordx4 v[122:123], off
	v_lshl_add_u64 v[122:123], v[70:71], 0, s[38:39]
	s_mov_b32 m0, s82
	s_nop 0
	global_load_lds_dwordx4 v[122:123], off
	v_lshl_add_u64 v[122:123], v[72:73], 0, s[40:41]
	s_mov_b32 m0, s83
	s_nop 0
	global_load_lds_dwordx4 v[122:123], off
	v_lshl_add_u64 v[122:123], v[70:71], 0, s[40:41]
	s_mov_b32 m0, s84
	s_nop 0
	global_load_lds_dwordx4 v[122:123], off
	ds_read_b128 v[122:125], v116 offset:32768
	ds_read_b128 v[126:129], v117 offset:49152
	ds_read_b128 v[130:133], v117 offset:53248
	ds_read_b128 v[134:137], v117 offset:57344
	ds_read_b128 v[138:141], v117 offset:61440
	ds_read_b128 v[142:145], v118 offset:32768
	ds_read_b128 v[146:149], v121 offset:49152
	ds_read_b128 v[150:153], v121 offset:53248
	ds_read_b128 v[154:157], v121 offset:57344
	ds_read_b128 v[158:161], v121 offset:61440
	s_setprio 1
	s_waitcnt lgkmcnt(0)
	v_mfma_f32_32x32x16_bf16 v[48:63], v[122:125], v[126:129], v[48:63]
	v_mfma_f32_32x32x16_bf16 v[32:47], v[122:125], v[130:133], v[32:47]
	v_mfma_f32_32x32x16_bf16 v[16:31], v[122:125], v[134:137], v[16:31]
	v_mfma_f32_32x32x16_bf16 v[0:15], v[122:125], v[138:141], v[0:15]
	s_setprio 0
	ds_read_b128 v[122:125], v162 offset:32768
	ds_read_b128 v[126:129], v163 offset:49152
	ds_read_b128 v[130:133], v163 offset:53248
	ds_read_b128 v[134:137], v163 offset:57344
	ds_read_b128 v[138:141], v163 offset:61440
	s_setprio 1
	v_mfma_f32_32x32x16_bf16 v[48:63], v[142:145], v[146:149], v[48:63]
	v_mfma_f32_32x32x16_bf16 v[32:47], v[142:145], v[150:153], v[32:47]
	v_mfma_f32_32x32x16_bf16 v[16:31], v[142:145], v[154:157], v[16:31]
	v_mfma_f32_32x32x16_bf16 v[0:15], v[142:145], v[158:161], v[0:15]
	s_setprio 0
	ds_read_b128 v[142:145], v164 offset:32768
	ds_read_b128 v[146:149], v165 offset:49152
	ds_read_b128 v[150:153], v165 offset:53248
	ds_read_b128 v[154:157], v165 offset:57344
	ds_read_b128 v[158:161], v165 offset:61440
	s_setprio 1
	s_waitcnt lgkmcnt(0)
	v_mfma_f32_32x32x16_bf16 v[48:63], v[122:125], v[126:129], v[48:63]
	v_mfma_f32_32x32x16_bf16 v[32:47], v[122:125], v[130:133], v[32:47]
	v_mfma_f32_32x32x16_bf16 v[16:31], v[122:125], v[134:137], v[16:31]
	v_mfma_f32_32x32x16_bf16 v[0:15], v[122:125], v[138:141], v[0:15]
	s_setprio 0
	s_setprio 1
	v_mfma_f32_32x32x16_bf16 v[48:63], v[142:145], v[146:149], v[48:63]
	v_mfma_f32_32x32x16_bf16 v[32:47], v[142:145], v[150:153], v[32:47]
	v_mfma_f32_32x32x16_bf16 v[16:31], v[142:145], v[154:157], v[16:31]
	v_mfma_f32_32x32x16_bf16 v[0:15], v[142:145], v[158:161], v[0:15]
	s_setprio 0
	s_mov_b32 m0, s77
	v_lshl_add_u64 v[122:123], v[72:73], 0, s[42:43]
	s_waitcnt vmcnt(0)
	s_waitcnt vmcnt(0)
	s_barrier
	v_lshl_add_u64 v[124:125], v[70:71], 0, s[42:43]
	global_load_lds_dwordx4 v[122:123], off
	s_mov_b32 m0, s0
	v_lshl_add_u64 v[122:123], v[72:73], 0, s[44:45]
	global_load_lds_dwordx4 v[124:125], off
	s_mov_b32 m0, s1
	s_nop 0
	global_load_lds_dwordx4 v[122:123], off
	v_lshl_add_u64 v[122:123], v[70:71], 0, s[44:45]
	s_mov_b32 m0, s67
	s_nop 0
	global_load_lds_dwordx4 v[122:123], off
	v_lshl_add_u64 v[122:123], v[72:73], 0, s[46:47]
	s_mov_b32 m0, s68
	s_nop 0
	global_load_lds_dwordx4 v[122:123], off
	v_lshl_add_u64 v[122:123], v[70:71], 0, s[46:47]
	s_mov_b32 m0, s69
	s_nop 0
	global_load_lds_dwordx4 v[122:123], off
	v_lshl_add_u64 v[122:123], v[72:73], 0, s[48:49]
	s_mov_b32 m0, s75
	s_nop 0
	global_load_lds_dwordx4 v[122:123], off
	v_lshl_add_u64 v[122:123], v[70:71], 0, s[48:49]
	s_mov_b32 m0, s76
	s_nop 0
	global_load_lds_dwordx4 v[122:123], off
	ds_read_b128 v[122:125], v116
	ds_read_b128 v[126:129], v117 offset:16384
	ds_read_b128 v[130:133], v117 offset:20480
	ds_read_b128 v[134:137], v117 offset:24576
	ds_read_b128 v[138:141], v117 offset:28672
	ds_read_b128 v[142:145], v118
	ds_read_b128 v[146:149], v121 offset:16384
	ds_read_b128 v[150:153], v121 offset:20480
	ds_read_b128 v[154:157], v121 offset:24576
	ds_read_b128 v[158:161], v121 offset:28672
	s_setprio 1
	s_waitcnt lgkmcnt(0)
	v_mfma_f32_32x32x16_bf16 v[48:63], v[122:125], v[126:129], v[48:63]
	v_mfma_f32_32x32x16_bf16 v[32:47], v[122:125], v[130:133], v[32:47]
	v_mfma_f32_32x32x16_bf16 v[16:31], v[122:125], v[134:137], v[16:31]
	v_mfma_f32_32x32x16_bf16 v[0:15], v[122:125], v[138:141], v[0:15]
	s_setprio 0
	ds_read_b128 v[122:125], v162
	ds_read_b128 v[126:129], v163 offset:16384
	ds_read_b128 v[130:133], v163 offset:20480
	ds_read_b128 v[134:137], v163 offset:24576
	ds_read_b128 v[138:141], v163 offset:28672
	s_setprio 1
	v_mfma_f32_32x32x16_bf16 v[48:63], v[142:145], v[146:149], v[48:63]
	v_mfma_f32_32x32x16_bf16 v[32:47], v[142:145], v[150:153], v[32:47]
	v_mfma_f32_32x32x16_bf16 v[16:31], v[142:145], v[154:157], v[16:31]
	v_mfma_f32_32x32x16_bf16 v[0:15], v[142:145], v[158:161], v[0:15]
	s_setprio 0
	ds_read_b128 v[142:145], v164
	ds_read_b128 v[146:149], v165 offset:16384
	ds_read_b128 v[150:153], v165 offset:20480
	ds_read_b128 v[154:157], v165 offset:24576
	ds_read_b128 v[158:161], v165 offset:28672
	s_setprio 1
	s_waitcnt lgkmcnt(0)
	v_mfma_f32_32x32x16_bf16 v[48:63], v[122:125], v[126:129], v[48:63]
	v_mfma_f32_32x32x16_bf16 v[32:47], v[122:125], v[130:133], v[32:47]
	v_mfma_f32_32x32x16_bf16 v[16:31], v[122:125], v[134:137], v[16:31]
	v_mfma_f32_32x32x16_bf16 v[0:15], v[122:125], v[138:141], v[0:15]
	s_setprio 0
	s_setprio 1
	v_mfma_f32_32x32x16_bf16 v[48:63], v[142:145], v[146:149], v[48:63]
	v_mfma_f32_32x32x16_bf16 v[32:47], v[142:145], v[150:153], v[32:47]
	v_mfma_f32_32x32x16_bf16 v[16:31], v[142:145], v[154:157], v[16:31]
	v_mfma_f32_32x32x16_bf16 v[0:15], v[142:145], v[158:161], v[0:15]
	s_setprio 0
	s_mov_b32 m0, s85
	v_lshl_add_u64 v[122:123], v[72:73], 0, s[50:51]
	s_waitcnt vmcnt(0)
	s_waitcnt vmcnt(0)
	s_barrier
	v_lshl_add_u64 v[124:125], v[70:71], 0, s[50:51]
	global_load_lds_dwordx4 v[122:123], off
	s_mov_b32 m0, s78
	v_lshl_add_u64 v[122:123], v[72:73], 0, s[52:53]
	global_load_lds_dwordx4 v[124:125], off
	s_mov_b32 m0, s79
	s_nop 0
	global_load_lds_dwordx4 v[122:123], off
	v_lshl_add_u64 v[122:123], v[70:71], 0, s[52:53]
	s_mov_b32 m0, s80
	s_nop 0
	global_load_lds_dwordx4 v[122:123], off
	v_lshl_add_u64 v[122:123], v[72:73], 0, s[54:55]
	s_mov_b32 m0, s81
	s_nop 0
	global_load_lds_dwordx4 v[122:123], off
	v_lshl_add_u64 v[122:123], v[70:71], 0, s[54:55]
	s_mov_b32 m0, s82
	s_nop 0
	global_load_lds_dwordx4 v[122:123], off
	v_lshl_add_u64 v[122:123], v[72:73], 0, s[56:57]
	s_mov_b32 m0, s83
	s_nop 0
	global_load_lds_dwordx4 v[122:123], off
	v_lshl_add_u64 v[122:123], v[70:71], 0, s[56:57]
	s_mov_b32 m0, s84
	s_nop 0
	global_load_lds_dwordx4 v[122:123], off
	ds_read_b128 v[122:125], v116 offset:32768
	ds_read_b128 v[126:129], v117 offset:49152
	ds_read_b128 v[130:133], v117 offset:53248
	ds_read_b128 v[134:137], v117 offset:57344
	ds_read_b128 v[138:141], v117 offset:61440
	ds_read_b128 v[142:145], v118 offset:32768
	ds_read_b128 v[146:149], v121 offset:49152
	ds_read_b128 v[150:153], v121 offset:53248
	ds_read_b128 v[154:157], v121 offset:57344
	ds_read_b128 v[158:161], v121 offset:61440
	s_setprio 1
	s_waitcnt lgkmcnt(0)
	v_mfma_f32_32x32x16_bf16 v[48:63], v[122:125], v[126:129], v[48:63]
	v_mfma_f32_32x32x16_bf16 v[32:47], v[122:125], v[130:133], v[32:47]
	v_mfma_f32_32x32x16_bf16 v[16:31], v[122:125], v[134:137], v[16:31]
	v_mfma_f32_32x32x16_bf16 v[0:15], v[122:125], v[138:141], v[0:15]
	s_setprio 0
	ds_read_b128 v[122:125], v162 offset:32768
	ds_read_b128 v[126:129], v163 offset:49152
	ds_read_b128 v[130:133], v163 offset:53248
	ds_read_b128 v[134:137], v163 offset:57344
	ds_read_b128 v[138:141], v163 offset:61440
	s_setprio 1
	v_mfma_f32_32x32x16_bf16 v[48:63], v[142:145], v[146:149], v[48:63]
	v_mfma_f32_32x32x16_bf16 v[32:47], v[142:145], v[150:153], v[32:47]
	v_mfma_f32_32x32x16_bf16 v[16:31], v[142:145], v[154:157], v[16:31]
	v_mfma_f32_32x32x16_bf16 v[0:15], v[142:145], v[158:161], v[0:15]
	s_setprio 0
	ds_read_b128 v[142:145], v164 offset:32768
	ds_read_b128 v[146:149], v165 offset:49152
	ds_read_b128 v[150:153], v165 offset:53248
	ds_read_b128 v[154:157], v165 offset:57344
	ds_read_b128 v[158:161], v165 offset:61440
	s_setprio 1
	s_waitcnt lgkmcnt(0)
	v_mfma_f32_32x32x16_bf16 v[48:63], v[122:125], v[126:129], v[48:63]
	v_mfma_f32_32x32x16_bf16 v[32:47], v[122:125], v[130:133], v[32:47]
	v_mfma_f32_32x32x16_bf16 v[16:31], v[122:125], v[134:137], v[16:31]
	v_mfma_f32_32x32x16_bf16 v[0:15], v[122:125], v[138:141], v[0:15]
	s_setprio 0
	s_setprio 1
	v_mfma_f32_32x32x16_bf16 v[48:63], v[142:145], v[146:149], v[48:63]
	v_mfma_f32_32x32x16_bf16 v[32:47], v[142:145], v[150:153], v[32:47]
	v_mfma_f32_32x32x16_bf16 v[16:31], v[142:145], v[154:157], v[16:31]
	v_mfma_f32_32x32x16_bf16 v[0:15], v[142:145], v[158:161], v[0:15]
	s_setprio 0
	s_mov_b32 m0, s77
	v_lshl_add_u64 v[122:123], v[72:73], 0, s[58:59]
	s_waitcnt vmcnt(0)
	s_waitcnt vmcnt(0)
	s_barrier
	v_lshl_add_u64 v[124:125], v[70:71], 0, s[58:59]
	global_load_lds_dwordx4 v[122:123], off
	s_mov_b32 m0, s0
	v_lshl_add_u64 v[122:123], v[72:73], 0, s[60:61]
	global_load_lds_dwordx4 v[124:125], off
	s_mov_b32 m0, s1
	s_nop 0
	global_load_lds_dwordx4 v[122:123], off
	v_lshl_add_u64 v[122:123], v[70:71], 0, s[60:61]
	s_mov_b32 m0, s67
	s_nop 0
	global_load_lds_dwordx4 v[122:123], off
	v_lshl_add_u64 v[122:123], v[72:73], 0, s[62:63]
	s_mov_b32 m0, s68
	v_lshl_add_u64 v[72:73], v[72:73], 0, s[64:65]
	global_load_lds_dwordx4 v[122:123], off
	v_lshl_add_u64 v[122:123], v[70:71], 0, s[62:63]
	s_mov_b32 m0, s69
	v_lshl_add_u64 v[70:71], v[70:71], 0, s[64:65]
	global_load_lds_dwordx4 v[122:123], off
	s_mov_b32 m0, s75
	s_nop 0
	global_load_lds_dwordx4 v[72:73], off
	s_mov_b32 m0, s76
	s_nop 0
	global_load_lds_dwordx4 v[70:71], off
	ds_read_b128 v[70:73], v116
	ds_read_b128 v[122:125], v117 offset:16384
	ds_read_b128 v[126:129], v117 offset:20480
	ds_read_b128 v[130:133], v117 offset:24576
	ds_read_b128 v[134:137], v117 offset:28672
	ds_read_b128 v[138:141], v118
	ds_read_b128 v[142:145], v121 offset:16384
	ds_read_b128 v[146:149], v121 offset:20480
	ds_read_b128 v[150:153], v121 offset:24576
	ds_read_b128 v[154:157], v121 offset:28672
	s_setprio 1
	s_waitcnt lgkmcnt(0)
	v_mfma_f32_32x32x16_bf16 v[48:63], v[70:73], v[122:125], v[48:63]
	v_mfma_f32_32x32x16_bf16 v[32:47], v[70:73], v[126:129], v[32:47]
	v_mfma_f32_32x32x16_bf16 v[16:31], v[70:73], v[130:133], v[16:31]
	v_mfma_f32_32x32x16_bf16 v[0:15], v[70:73], v[134:137], v[0:15]
	s_setprio 0
	ds_read_b128 v[70:73], v162
	ds_read_b128 v[122:125], v163 offset:16384
	ds_read_b128 v[126:129], v163 offset:20480
	ds_read_b128 v[130:133], v163 offset:24576
	ds_read_b128 v[134:137], v163 offset:28672
	s_setprio 1
	v_mfma_f32_32x32x16_bf16 v[48:63], v[138:141], v[142:145], v[48:63]
	v_mfma_f32_32x32x16_bf16 v[32:47], v[138:141], v[146:149], v[32:47]
	v_mfma_f32_32x32x16_bf16 v[16:31], v[138:141], v[150:153], v[16:31]
	v_mfma_f32_32x32x16_bf16 v[0:15], v[138:141], v[154:157], v[0:15]
	s_setprio 0
	ds_read_b128 v[138:141], v164
	ds_read_b128 v[142:145], v165 offset:16384
	ds_read_b128 v[146:149], v165 offset:20480
	ds_read_b128 v[150:153], v165 offset:24576
	ds_read_b128 v[154:157], v165 offset:28672
	s_setprio 1
	s_waitcnt lgkmcnt(0)
	v_mfma_f32_32x32x16_bf16 v[48:63], v[70:73], v[122:125], v[48:63]
	v_mfma_f32_32x32x16_bf16 v[32:47], v[70:73], v[126:129], v[32:47]
	v_mfma_f32_32x32x16_bf16 v[16:31], v[70:73], v[130:133], v[16:31]
	v_mfma_f32_32x32x16_bf16 v[0:15], v[70:73], v[134:137], v[0:15]
	s_setprio 0
	s_setprio 1
	v_mfma_f32_32x32x16_bf16 v[48:63], v[138:141], v[142:145], v[48:63]
	v_mfma_f32_32x32x16_bf16 v[32:47], v[138:141], v[146:149], v[32:47]
	v_mfma_f32_32x32x16_bf16 v[16:31], v[138:141], v[150:153], v[16:31]
	v_mfma_f32_32x32x16_bf16 v[0:15], v[138:141], v[154:157], v[0:15]
	s_setprio 0
	s_waitcnt vmcnt(0)
	s_waitcnt vmcnt(0)
	s_barrier
	ds_read_b128 v[70:73], v121 offset:61440
	ds_read_b128 v[122:125], v121 offset:57344
	ds_read_b128 v[126:129], v121 offset:53248
	ds_read_b128 v[130:133], v121 offset:49152
	ds_read_b128 v[134:137], v118 offset:32768
	ds_read_b128 v[138:141], v117 offset:61440
	ds_read_b128 v[142:145], v117 offset:57344
	ds_read_b128 v[146:149], v117 offset:53248
	ds_read_b128 v[150:153], v117 offset:49152
	ds_read_b128 v[154:157], v116 offset:32768
	s_setprio 1
	s_waitcnt lgkmcnt(0)
	v_mfma_f32_32x32x16_bf16 v[48:63], v[154:157], v[150:153], v[48:63]
	v_mfma_f32_32x32x16_bf16 v[32:47], v[154:157], v[146:149], v[32:47]
	v_mfma_f32_32x32x16_bf16 v[16:31], v[154:157], v[142:145], v[16:31]
	v_mfma_f32_32x32x16_bf16 v[0:15], v[154:157], v[138:141], v[0:15]
	s_setprio 0
	ds_read_b128 v[138:141], v162 offset:32768
	ds_read_b128 v[142:145], v163 offset:49152
	ds_read_b128 v[146:149], v163 offset:53248
	ds_read_b128 v[150:153], v163 offset:57344
	ds_read_b128 v[154:157], v163 offset:61440
	s_setprio 1
	v_mfma_f32_32x32x16_bf16 v[48:63], v[134:137], v[130:133], v[48:63]
	v_mfma_f32_32x32x16_bf16 v[32:47], v[134:137], v[126:129], v[32:47]
	v_mfma_f32_32x32x16_bf16 v[16:31], v[134:137], v[122:125], v[16:31]
	v_mfma_f32_32x32x16_bf16 v[0:15], v[134:137], v[70:73], v[0:15]
	s_setprio 0
	ds_read_b128 v[70:73], v164 offset:32768
	ds_read_b128 v[122:125], v165 offset:49152
	ds_read_b128 v[126:129], v165 offset:53248
	ds_read_b128 v[130:133], v165 offset:57344
	ds_read_b128 v[134:137], v165 offset:61440
	s_setprio 1
	s_waitcnt lgkmcnt(8)
	v_mfma_f32_32x32x16_bf16 v[48:63], v[138:141], v[142:145], v[48:63]
	s_waitcnt lgkmcnt(7)
	v_mfma_f32_32x32x16_bf16 v[32:47], v[138:141], v[146:149], v[32:47]
	s_waitcnt lgkmcnt(6)
	v_mfma_f32_32x32x16_bf16 v[16:31], v[138:141], v[150:153], v[16:31]
	s_waitcnt lgkmcnt(5)
	v_mfma_f32_32x32x16_bf16 v[0:15], v[138:141], v[154:157], v[0:15]
	s_setprio 0
	s_setprio 1
	s_waitcnt lgkmcnt(3)
	v_mfma_f32_32x32x16_bf16 v[48:63], v[70:73], v[122:125], v[48:63]
	s_waitcnt lgkmcnt(2)
	v_mfma_f32_32x32x16_bf16 v[32:47], v[70:73], v[126:129], v[32:47]
	s_waitcnt lgkmcnt(1)
	v_mfma_f32_32x32x16_bf16 v[16:31], v[70:73], v[130:133], v[16:31]
	s_waitcnt lgkmcnt(0)
	v_mfma_f32_32x32x16_bf16 v[0:15], v[70:73], v[134:137], v[0:15]
	s_setprio 0
	v_mov_b32_e32 v70, s10
	ds_read_b64 v[70:71], v70
	s_mov_b64 s[0:1], -1
	s_cmp_gt_i32 s66, 63
	v_lshlrev_b32_e32 v121, 2, v64
	v_mbcnt_hi_u32_b32 v122, -1, v120
	s_waitcnt lgkmcnt(0)
	v_readfirstlane_b32 s66, v70
	v_readfirstlane_b32 s67, v71
	s_cbranch_scc0 .LBB0_642
	s_nop 3
	global_load_dword v71, v121, s[66:67] offset:512
	global_load_dword v70, v121, s[66:67] offset:640
	v_and_b32_e32 v124, 64, v122
	v_xor_b32_e32 v123, 1, v122
	v_add_u32_e32 v128, 64, v124
	v_mov_b32_e32 v72, v48
	v_mov_b32_e32 v73, v32
	v_cmp_lt_i32_e32 vcc, v123, v128
	v_pk_mul_f32 v[72:73], v[72:73], v[72:73]
	v_xor_b32_e32 v125, 2, v122
	v_cndmask_b32_e32 v123, v122, v123, vcc
	v_add_f32_e32 v72, v72, v73
	v_lshlrev_b32_e32 v123, 2, v123
	v_cmp_lt_i32_e32 vcc, v125, v128
	v_xor_b32_e32 v126, 4, v122
	v_xor_b32_e32 v127, 8, v122
	v_cndmask_b32_e32 v124, v122, v125, vcc
	v_lshlrev_b32_e32 v124, 2, v124
	v_add_f32_dpp v72, v72, v72 quad_perm:[1,0,3,2] row_mask:0xf bank_mask:0xf
	v_cmp_lt_i32_e32 vcc, v126, v128
	v_xor_b32_e32 v129, 16, v122
	s_cmp_gt_i32 s74, 63
	v_cndmask_b32_e32 v125, v122, v126, vcc
	v_lshlrev_b32_e32 v125, 2, v125
	v_add_f32_dpp v73, v72, v72 quad_perm:[2,3,0,1] row_mask:0xf bank_mask:0xf
	v_cmp_lt_i32_e32 vcc, v127, v128
	s_cselect_b64 s[68:69], -1, 0
	s_and_b64 s[0:1], s[68:69], exec
	v_cndmask_b32_e32 v127, v122, v127, vcc
	v_lshlrev_b32_e32 v127, 2, v127
	v_add_f32_dpp v130, v73, v73 row_half_mirror row_mask:0xf bank_mask:0xf
	s_nop 1
	v_mov_b32_dpp v131, v130 row_mirror row_mask:0xf bank_mask:0xf
	v_cmp_lt_i32_e32 vcc, v129, v128
	s_cselect_b32 s0, s11, 0x80
	s_and_b32 s76, s0, s73
	v_cndmask_b32_e32 v126, v122, v129, vcc
	v_lshlrev_b32_e32 v126, 2, v126
	v_add_f32_e32 v128, v130, v131
	v_mov_b32_e32 v129, v128
	s_nop 1
	v_permlane16_swap_b32_e32 v128, v129
	s_nop 0
	v_mov_b32_e32 v72, v32
	v_mov_b32_e32 v73, v48
	v_lshlrev_b32_e32 v142, 3, v64
	v_add_u32_e32 v130, s76, v80
	v_add_f32_e32 v128, v128, v129
	v_fmamk_f32 v128, v128, 0x3c800000, v119
	v_rsq_f32_e32 v128, v128
	s_cmp_lt_i32 s74, 64
	s_waitcnt vmcnt(0)
	v_pk_mul_f32 v[128:129], v[70:71], v[128:129] op_sel_hi:[1,0]
	s_nop 0
	v_pk_mul_f32 v[72:73], v[72:73], v[128:129]
	v_lshl_or_b32 v128, v130, 8, v142
	s_cbranch_scc1 .LBB0_579
	global_load_dwordx2 v[130:131], v128, s[8:9]
	s_waitcnt vmcnt(0)
	v_pk_mul_f32 v[134:135], v[72:73], v[130:131] op_sel_hi:[0,1]
	v_pk_mul_f32 v[132:133], v[72:73], v[130:131] op_sel:[1,1] op_sel_hi:[1,0]
	v_pk_fma_f32 v[72:73], v[72:73], v[130:131], v[134:135] op_sel:[1,1,0] op_sel_hi:[1,0,1] neg_lo:[0,0,1] neg_hi:[0,0,1]
	s_nop 0
	v_add_f32_e32 v72, v132, v134
.LBB0_579:
	v_mov_b32_e32 v130, v49
	v_mov_b32_e32 v131, v33
	v_pk_mul_f32 v[130:131], v[130:131], v[130:131]
	s_mul_i32 s74, s72, 0x180
	v_add_f32_e32 v129, v130, v131
	v_add_u32_e32 v131, s73, v80
	v_cndmask_b32_e64 v133, 0, 1, s[68:69]
	s_add_i32 s75, s74, 0xfffff400
	v_cvt_pk_bf16_f32 v135, v73, s0
	s_waitcnt lgkmcnt(0)
	v_add_f32_dpp v129, v129, v129 quad_perm:[1,0,3,2] row_mask:0xf bank_mask:0xf
	v_cvt_pk_bf16_f32 v136, v72, s0
	v_cmp_ne_u32_e64 s[0:1], 1, v133
	v_mov_b32_e32 v72, v33
	v_mov_b32_e32 v73, v49
	v_add_f32_dpp v130, v129, v129 quad_perm:[2,3,0,1] row_mask:0xf bank_mask:0xf
	v_mul_lo_u32 v129, v131, s70
	v_add_u32_e32 v133, s75, v129
	v_add_u32_e32 v137, s76, v83
	s_andn2_b64 vcc, exec, s[68:69]
	v_add_f32_dpp v131, v130, v130 row_half_mirror row_mask:0xf bank_mask:0xf
	v_add_u32_e32 v130, v133, v81
	v_add_f32_dpp v134, v131, v131 row_mirror row_mask:0xf bank_mask:0xf
	v_mov_b32_e32 v138, v134
	s_nop 1
	v_permlane16_swap_b32_e32 v134, v138
	s_nop 0
	v_add_u32_e32 v132, v133, v82
	v_ashrrev_i32_e32 v131, 31, v130
	v_ashrrev_i32_e32 v133, 31, v132
	v_lshl_add_u64 v[130:131], v[130:131], 1, s[6:7]
	v_add_f32_e32 v134, v134, v138
	v_fmamk_f32 v134, v134, 0x3c800000, v119
	v_rsq_f32_e32 v134, v134
	v_lshl_add_u64 v[132:133], v[132:133], 1, s[6:7]
	global_store_short v[130:131], v135, off sc1
	global_store_short v[132:133], v136, off sc1
	v_pk_mul_f32 v[130:131], v[70:71], v[134:135] op_sel_hi:[1,0]
	s_nop 0
	v_pk_mul_f32 v[72:73], v[72:73], v[130:131]
	v_lshl_or_b32 v130, v137, 8, v142
	s_cbranch_vccnz .LBB0_581
	global_load_dwordx2 v[132:133], v130, s[8:9]
	s_waitcnt vmcnt(0)
	v_pk_mul_f32 v[136:137], v[72:73], v[132:133] op_sel_hi:[0,1]
	v_pk_mul_f32 v[134:135], v[72:73], v[132:133] op_sel:[1,1] op_sel_hi:[1,0]
	v_pk_fma_f32 v[72:73], v[72:73], v[132:133], v[136:137] op_sel:[1,1,0] op_sel_hi:[1,0,1] neg_lo:[0,0,1] neg_hi:[0,0,1]
	s_nop 0
	v_add_f32_e32 v72, v134, v136
.LBB0_581:
	v_mov_b32_e32 v132, v50
	v_mov_b32_e32 v133, v34
	v_pk_mul_f32 v[132:133], v[132:133], v[132:133]
	v_cvt_pk_bf16_f32 v138, v73, s0
	v_add_f32_e32 v131, v132, v133
	v_add_u32_e32 v133, s73, v83
	v_mul_lo_u32 v133, v133, s70
	v_add_u32_e32 v135, s75, v133
	v_add_u32_e32 v134, v135, v81
	s_waitcnt lgkmcnt(0)
	v_add_f32_dpp v131, v131, v131 quad_perm:[1,0,3,2] row_mask:0xf bank_mask:0xf
	v_add_u32_e32 v136, v135, v82
	v_ashrrev_i32_e32 v135, 31, v134
	v_ashrrev_i32_e32 v137, 31, v136
	v_lshl_add_u64 v[134:135], v[134:135], 1, s[6:7]
	v_add_f32_dpp v131, v131, v131 quad_perm:[2,3,0,1] row_mask:0xf bank_mask:0xf
	v_cvt_pk_bf16_f32 v139, v72, s0
	v_mov_b32_e32 v72, v34
	v_mov_b32_e32 v73, v50
	v_add_u32_e32 v140, s76, v84
	v_add_f32_dpp v131, v131, v131 row_half_mirror row_mask:0xf bank_mask:0xf
	v_lshl_add_u64 v[136:137], v[136:137], 1, s[6:7]
	global_store_short v[134:135], v138, off sc1
	global_store_short v[136:137], v139, off sc1
	s_and_b64 vcc, exec, s[0:1]
	v_add_f32_dpp v131, v131, v131 row_mirror row_mask:0xf bank_mask:0xf
	v_mov_b32_e32 v132, v131
	s_nop 1
	v_permlane16_swap_b32_e32 v131, v132
	s_nop 0
	v_add_f32_e32 v131, v131, v132
	v_fmamk_f32 v131, v131, 0x3c800000, v119
	v_rsq_f32_e32 v132, v131
	v_lshl_or_b32 v131, v140, 8, v142
	v_pk_mul_f32 v[134:135], v[70:71], v[132:133] op_sel_hi:[1,0]
	s_nop 0
	v_pk_mul_f32 v[72:73], v[72:73], v[134:135]
	s_cbranch_vccnz .LBB0_583
	global_load_dwordx2 v[134:135], v131, s[8:9]
	s_waitcnt vmcnt(0)
	v_pk_mul_f32 v[138:139], v[72:73], v[134:135] op_sel_hi:[0,1]
	v_pk_mul_f32 v[136:137], v[72:73], v[134:135] op_sel:[1,1] op_sel_hi:[1,0]
	v_pk_fma_f32 v[72:73], v[72:73], v[134:135], v[138:139] op_sel:[1,1,0] op_sel_hi:[1,0,1] neg_lo:[0,0,1] neg_hi:[0,0,1]
	s_nop 0
	v_add_f32_e32 v72, v136, v138
.LBB0_583:
	v_mov_b32_e32 v134, v51
	v_mov_b32_e32 v135, v35
	v_pk_mul_f32 v[134:135], v[134:135], v[134:135]
	v_cvt_pk_bf16_f32 v140, v73, s0
	v_add_f32_e32 v132, v134, v135
	v_add_u32_e32 v135, s73, v84
	v_mul_lo_u32 v135, v135, s70
	v_add_u32_e32 v137, s75, v135
	v_add_u32_e32 v136, v137, v81
	s_waitcnt lgkmcnt(0)
	v_add_f32_dpp v132, v132, v132 quad_perm:[1,0,3,2] row_mask:0xf bank_mask:0xf
	v_add_u32_e32 v138, v137, v82
	v_ashrrev_i32_e32 v137, 31, v136
	v_ashrrev_i32_e32 v139, 31, v138
	v_lshl_add_u64 v[136:137], v[136:137], 1, s[6:7]
	v_add_f32_dpp v132, v132, v132 quad_perm:[2,3,0,1] row_mask:0xf bank_mask:0xf
	v_cvt_pk_bf16_f32 v141, v72, s0
	v_mov_b32_e32 v72, v35
	v_mov_b32_e32 v73, v51
	v_add_u32_e32 v143, s76, v85
	v_add_f32_dpp v132, v132, v132 row_half_mirror row_mask:0xf bank_mask:0xf
	v_lshl_add_u64 v[138:139], v[138:139], 1, s[6:7]
	global_store_short v[136:137], v140, off sc1
	global_store_short v[138:139], v141, off sc1
	s_and_b64 vcc, exec, s[0:1]
	v_add_f32_dpp v132, v132, v132 row_mirror row_mask:0xf bank_mask:0xf
	v_mov_b32_e32 v134, v132
	s_nop 1
	v_permlane16_swap_b32_e32 v132, v134
	s_nop 0
	v_add_f32_e32 v132, v132, v134
	v_fmamk_f32 v132, v132, 0x3c800000, v119
	v_rsq_f32_e32 v132, v132
	s_nop 0
	v_pk_mul_f32 v[136:137], v[70:71], v[132:133] op_sel_hi:[1,0]
	s_nop 0
	v_pk_mul_f32 v[72:73], v[72:73], v[136:137]
	v_lshl_or_b32 v132, v143, 8, v142
	s_cbranch_vccnz .LBB0_585
	global_load_dwordx2 v[136:137], v132, s[8:9]
	s_waitcnt vmcnt(0)
	v_pk_mul_f32 v[140:141], v[72:73], v[136:137] op_sel_hi:[0,1]
	v_pk_mul_f32 v[138:139], v[72:73], v[136:137] op_sel:[1,1] op_sel_hi:[1,0]
	v_pk_fma_f32 v[72:73], v[72:73], v[136:137], v[140:141] op_sel:[1,1,0] op_sel_hi:[1,0,1] neg_lo:[0,0,1] neg_hi:[0,0,1]
	s_nop 0
	v_add_f32_e32 v72, v138, v140
.LBB0_585:
	v_mov_b32_e32 v136, v52
	v_mov_b32_e32 v137, v36
	v_pk_mul_f32 v[136:137], v[136:137], v[136:137]
	v_cvt_pk_bf16_f32 v143, v73, s0
	v_add_f32_e32 v134, v136, v137
	v_add_u32_e32 v137, s73, v85
	v_mul_lo_u32 v137, v137, s70
	v_add_u32_e32 v139, s75, v137
	v_add_u32_e32 v138, v139, v81
	s_waitcnt lgkmcnt(0)
	v_add_f32_dpp v134, v134, v134 quad_perm:[1,0,3,2] row_mask:0xf bank_mask:0xf
	v_add_u32_e32 v140, v139, v82
	v_ashrrev_i32_e32 v139, 31, v138
	v_ashrrev_i32_e32 v141, 31, v140
	v_lshl_add_u64 v[138:139], v[138:139], 1, s[6:7]
	v_add_f32_dpp v134, v134, v134 quad_perm:[2,3,0,1] row_mask:0xf bank_mask:0xf
	v_cvt_pk_bf16_f32 v144, v72, s0
	v_mov_b32_e32 v72, v36
	v_mov_b32_e32 v73, v52
	v_add_u32_e32 v145, s76, v86
	v_add_f32_dpp v134, v134, v134 row_half_mirror row_mask:0xf bank_mask:0xf
	v_lshl_add_u64 v[140:141], v[140:141], 1, s[6:7]
	global_store_short v[138:139], v143, off sc1
	global_store_short v[140:141], v144, off sc1
	s_and_b64 vcc, exec, s[0:1]
	v_add_f32_dpp v134, v134, v134 row_mirror row_mask:0xf bank_mask:0xf
	v_mov_b32_e32 v136, v134
	s_nop 1
	v_permlane16_swap_b32_e32 v134, v136
	s_nop 0
	v_add_f32_e32 v134, v134, v136
	v_fmamk_f32 v134, v134, 0x3c800000, v119
	v_rsq_f32_e32 v134, v134
	s_nop 0
	v_pk_mul_f32 v[138:139], v[70:71], v[134:135] op_sel_hi:[1,0]
	s_nop 0
	v_pk_mul_f32 v[72:73], v[72:73], v[138:139]
	v_lshl_or_b32 v134, v145, 8, v142
	s_cbranch_vccnz .LBB0_587
	global_load_dwordx2 v[138:139], v134, s[8:9]
	s_waitcnt vmcnt(0)
	v_pk_mul_f32 v[144:145], v[72:73], v[138:139] op_sel_hi:[0,1]
	v_pk_mul_f32 v[140:141], v[72:73], v[138:139] op_sel:[1,1] op_sel_hi:[1,0]
	v_pk_fma_f32 v[72:73], v[72:73], v[138:139], v[144:145] op_sel:[1,1,0] op_sel_hi:[1,0,1] neg_lo:[0,0,1] neg_hi:[0,0,1]
	s_nop 0
	v_add_f32_e32 v72, v140, v144
.LBB0_587:
	v_mov_b32_e32 v138, v53
	v_mov_b32_e32 v139, v37
	v_pk_mul_f32 v[138:139], v[138:139], v[138:139]
	v_cvt_pk_bf16_f32 v143, v73, s0
	v_add_f32_e32 v136, v138, v139
	v_add_u32_e32 v139, s73, v86
	v_mul_lo_u32 v139, v139, s70
	v_add_u32_e32 v141, s75, v139
	v_add_u32_e32 v140, v141, v81
	s_waitcnt lgkmcnt(0)
	v_add_f32_dpp v136, v136, v136 quad_perm:[1,0,3,2] row_mask:0xf bank_mask:0xf
	v_add_u32_e32 v144, v141, v82
	v_ashrrev_i32_e32 v141, 31, v140
	v_ashrrev_i32_e32 v145, 31, v144
	v_lshl_add_u64 v[140:141], v[140:141], 1, s[6:7]
	v_add_f32_dpp v136, v136, v136 quad_perm:[2,3,0,1] row_mask:0xf bank_mask:0xf
	v_cvt_pk_bf16_f32 v146, v72, s0
	v_mov_b32_e32 v72, v37
	v_mov_b32_e32 v73, v53
	v_add_u32_e32 v147, s76, v87
	v_add_f32_dpp v136, v136, v136 row_half_mirror row_mask:0xf bank_mask:0xf
	v_lshl_add_u64 v[144:145], v[144:145], 1, s[6:7]
	global_store_short v[140:141], v143, off sc1
	global_store_short v[144:145], v146, off sc1
	s_and_b64 vcc, exec, s[0:1]
	v_add_f32_dpp v136, v136, v136 row_mirror row_mask:0xf bank_mask:0xf
	v_mov_b32_e32 v138, v136
	s_nop 1
	v_permlane16_swap_b32_e32 v136, v138
	s_nop 0
	v_add_f32_e32 v136, v136, v138
	v_fmamk_f32 v136, v136, 0x3c800000, v119
	v_rsq_f32_e32 v136, v136
	s_nop 0
	v_pk_mul_f32 v[140:141], v[70:71], v[136:137] op_sel_hi:[1,0]
	s_nop 0
	v_pk_mul_f32 v[72:73], v[72:73], v[140:141]
	v_lshl_or_b32 v136, v147, 8, v142
	s_cbranch_vccnz .LBB0_589
	global_load_dwordx2 v[140:141], v136, s[8:9]
	s_waitcnt vmcnt(0)
	v_pk_mul_f32 v[146:147], v[72:73], v[140:141] op_sel_hi:[0,1]
	v_pk_mul_f32 v[144:145], v[72:73], v[140:141] op_sel:[1,1] op_sel_hi:[1,0]
	v_pk_fma_f32 v[72:73], v[72:73], v[140:141], v[146:147] op_sel:[1,1,0] op_sel_hi:[1,0,1] neg_lo:[0,0,1] neg_hi:[0,0,1]
	s_nop 0
	v_add_f32_e32 v72, v144, v146
.LBB0_589:
	v_mov_b32_e32 v140, v54
	v_mov_b32_e32 v141, v38
	v_pk_mul_f32 v[140:141], v[140:141], v[140:141]
	v_cvt_pk_bf16_f32 v143, v73, s0
	v_add_f32_e32 v138, v140, v141
	v_add_u32_e32 v141, s73, v87
	v_mul_lo_u32 v141, v141, s70
	v_add_u32_e32 v145, s75, v141
	v_add_u32_e32 v144, v145, v81
	s_waitcnt lgkmcnt(0)
	v_add_f32_dpp v138, v138, v138 quad_perm:[1,0,3,2] row_mask:0xf bank_mask:0xf
	v_add_u32_e32 v146, v145, v82
	v_ashrrev_i32_e32 v145, 31, v144
	v_ashrrev_i32_e32 v147, 31, v146
	v_lshl_add_u64 v[144:145], v[144:145], 1, s[6:7]
	v_add_f32_dpp v138, v138, v138 quad_perm:[2,3,0,1] row_mask:0xf bank_mask:0xf
	v_cvt_pk_bf16_f32 v148, v72, s0
	v_mov_b32_e32 v72, v38
	v_mov_b32_e32 v73, v54
	v_add_u32_e32 v149, s76, v88
	v_add_f32_dpp v138, v138, v138 row_half_mirror row_mask:0xf bank_mask:0xf
	v_lshl_add_u64 v[146:147], v[146:147], 1, s[6:7]
	global_store_short v[144:145], v143, off sc1
	global_store_short v[146:147], v148, off sc1
	s_and_b64 vcc, exec, s[0:1]
	v_add_f32_dpp v138, v138, v138 row_mirror row_mask:0xf bank_mask:0xf
	v_mov_b32_e32 v140, v138
	s_nop 1
	v_permlane16_swap_b32_e32 v138, v140
	s_nop 0
	v_add_f32_e32 v138, v138, v140
	v_fmamk_f32 v138, v138, 0x3c800000, v119
	v_rsq_f32_e32 v138, v138
	s_nop 0
	v_pk_mul_f32 v[144:145], v[70:71], v[138:139] op_sel_hi:[1,0]
	s_nop 0
	v_pk_mul_f32 v[72:73], v[72:73], v[144:145]
	v_lshl_or_b32 v138, v149, 8, v142
	s_cbranch_vccnz .LBB0_591
	global_load_dwordx2 v[144:145], v138, s[8:9]
	s_waitcnt vmcnt(0)
	v_pk_mul_f32 v[148:149], v[72:73], v[144:145] op_sel_hi:[0,1]
	v_pk_mul_f32 v[146:147], v[72:73], v[144:145] op_sel:[1,1] op_sel_hi:[1,0]
	v_pk_fma_f32 v[72:73], v[72:73], v[144:145], v[148:149] op_sel:[1,1,0] op_sel_hi:[1,0,1] neg_lo:[0,0,1] neg_hi:[0,0,1]
	s_nop 0
	v_add_f32_e32 v72, v146, v148
.LBB0_591:
	v_mov_b32_e32 v144, v55
	v_mov_b32_e32 v145, v39
	v_pk_mul_f32 v[144:145], v[144:145], v[144:145]
	v_cvt_pk_bf16_f32 v150, v72, s0
	v_add_f32_e32 v140, v144, v145
	v_add_u32_e32 v144, s73, v88
	v_mul_lo_u32 v144, v144, s70
	v_add_u32_e32 v147, s75, v144
	v_add_u32_e32 v146, v147, v81
	s_waitcnt lgkmcnt(0)
	v_add_f32_dpp v140, v140, v140 quad_perm:[1,0,3,2] row_mask:0xf bank_mask:0xf
	v_add_u32_e32 v148, v147, v82
	v_ashrrev_i32_e32 v147, 31, v146
	v_cvt_pk_bf16_f32 v145, v73, s0
	v_ashrrev_i32_e32 v149, 31, v148
	v_add_f32_dpp v140, v140, v140 quad_perm:[2,3,0,1] row_mask:0xf bank_mask:0xf
	v_lshl_add_u64 v[146:147], v[146:147], 1, s[6:7]
	v_mov_b32_e32 v72, v39
	v_mov_b32_e32 v73, v55
	v_add_u32_e32 v151, s76, v89
	v_add_f32_dpp v140, v140, v140 row_half_mirror row_mask:0xf bank_mask:0xf
	v_lshl_add_u64 v[148:149], v[148:149], 1, s[6:7]
	global_store_short v[146:147], v145, off sc1
	global_store_short v[148:149], v150, off sc1
	s_and_b64 vcc, exec, s[0:1]
	v_add_f32_dpp v140, v140, v140 row_mirror row_mask:0xf bank_mask:0xf
	v_mov_b32_e32 v143, v140
	s_nop 1
	v_permlane16_swap_b32_e32 v140, v143
	s_nop 0
	v_add_f32_e32 v140, v140, v143
	v_fmamk_f32 v140, v140, 0x3c800000, v119
	v_rsq_f32_e32 v140, v140
	s_nop 0
	v_pk_mul_f32 v[146:147], v[70:71], v[140:141] op_sel_hi:[1,0]
	s_nop 0
	v_pk_mul_f32 v[72:73], v[72:73], v[146:147]
	v_lshl_or_b32 v140, v151, 8, v142
	s_cbranch_vccnz .LBB0_593
	global_load_dwordx2 v[146:147], v140, s[8:9]
	s_waitcnt vmcnt(0)
	v_pk_mul_f32 v[150:151], v[72:73], v[146:147] op_sel_hi:[0,1]
	v_pk_mul_f32 v[148:149], v[72:73], v[146:147] op_sel:[1,1] op_sel_hi:[1,0]
	v_pk_fma_f32 v[72:73], v[72:73], v[146:147], v[150:151] op_sel:[1,1,0] op_sel_hi:[1,0,1] neg_lo:[0,0,1] neg_hi:[0,0,1]
	s_nop 0
	v_add_f32_e32 v72, v148, v150
.LBB0_593:
	v_mov_b32_e32 v146, v56
	v_mov_b32_e32 v147, v40
	v_pk_mul_f32 v[146:147], v[146:147], v[146:147]
	v_cvt_pk_bf16_f32 v153, v72, s0
	v_add_f32_e32 v143, v146, v147
	v_add_u32_e32 v146, s73, v89
	v_mul_lo_u32 v146, v146, s70
	v_add_u32_e32 v149, s75, v146
	v_add_u32_e32 v148, v149, v81
	s_waitcnt lgkmcnt(0)
	v_add_f32_dpp v143, v143, v143 quad_perm:[1,0,3,2] row_mask:0xf bank_mask:0xf
	v_add_u32_e32 v150, v149, v82
	v_ashrrev_i32_e32 v149, 31, v148
	v_cvt_pk_bf16_f32 v147, v73, s0
	v_ashrrev_i32_e32 v151, 31, v150
	v_add_f32_dpp v143, v143, v143 quad_perm:[2,3,0,1] row_mask:0xf bank_mask:0xf
	v_lshl_add_u64 v[148:149], v[148:149], 1, s[6:7]
	v_mov_b32_e32 v72, v40
	v_mov_b32_e32 v73, v56
	v_add_u32_e32 v154, s76, v90
	v_add_f32_dpp v143, v143, v143 row_half_mirror row_mask:0xf bank_mask:0xf
	v_lshl_add_u64 v[150:151], v[150:151], 1, s[6:7]
	global_store_short v[148:149], v147, off sc1
	global_store_short v[150:151], v153, off sc1
	s_and_b64 vcc, exec, s[0:1]
	v_add_f32_dpp v143, v143, v143 row_mirror row_mask:0xf bank_mask:0xf
	v_mov_b32_e32 v145, v143
	s_nop 1
	v_permlane16_swap_b32_e32 v143, v145
	s_nop 0
	v_add_f32_e32 v143, v143, v145
	v_fmamk_f32 v143, v143, 0x3c800000, v119
	v_rsq_f32_e32 v152, v143
	v_lshl_or_b32 v143, v154, 8, v142
	v_pk_mul_f32 v[148:149], v[70:71], v[152:153] op_sel_hi:[1,0]
	s_nop 0
	v_pk_mul_f32 v[72:73], v[72:73], v[148:149]
	s_cbranch_vccnz .LBB0_595
	global_load_dwordx2 v[148:149], v143, s[8:9]
	s_waitcnt vmcnt(0)
	v_pk_mul_f32 v[152:153], v[72:73], v[148:149] op_sel_hi:[0,1]
	v_pk_mul_f32 v[150:151], v[72:73], v[148:149] op_sel:[1,1] op_sel_hi:[1,0]
	v_pk_fma_f32 v[72:73], v[72:73], v[148:149], v[152:153] op_sel:[1,1,0] op_sel_hi:[1,0,1] neg_lo:[0,0,1] neg_hi:[0,0,1]
	s_nop 0
	v_add_f32_e32 v72, v150, v152
.LBB0_595:
	v_mov_b32_e32 v148, v57
	v_mov_b32_e32 v149, v41
	v_pk_mul_f32 v[148:149], v[148:149], v[148:149]
	v_cvt_pk_bf16_f32 v155, v72, s0
	v_add_f32_e32 v145, v148, v149
	v_add_u32_e32 v148, s73, v90
	v_mul_lo_u32 v148, v148, s70
	v_add_u32_e32 v151, s75, v148
	v_add_u32_e32 v150, v151, v81
	s_waitcnt lgkmcnt(0)
	v_add_f32_dpp v145, v145, v145 quad_perm:[1,0,3,2] row_mask:0xf bank_mask:0xf
	v_add_u32_e32 v152, v151, v82
	v_ashrrev_i32_e32 v151, 31, v150
	v_cvt_pk_bf16_f32 v149, v73, s0
	v_ashrrev_i32_e32 v153, 31, v152
	v_add_f32_dpp v145, v145, v145 quad_perm:[2,3,0,1] row_mask:0xf bank_mask:0xf
	v_lshl_add_u64 v[150:151], v[150:151], 1, s[6:7]
	v_mov_b32_e32 v72, v41
	v_mov_b32_e32 v73, v57
	v_add_u32_e32 v156, s76, v91
	v_add_f32_dpp v145, v145, v145 row_half_mirror row_mask:0xf bank_mask:0xf
	v_lshl_add_u64 v[152:153], v[152:153], 1, s[6:7]
	global_store_short v[150:151], v149, off sc1
	global_store_short v[152:153], v155, off sc1
	s_and_b64 vcc, exec, s[0:1]
	v_add_f32_dpp v145, v145, v145 row_mirror row_mask:0xf bank_mask:0xf
	v_mov_b32_e32 v147, v145
	s_nop 1
	v_permlane16_swap_b32_e32 v145, v147
	s_nop 0
	v_add_f32_e32 v145, v145, v147
	v_fmamk_f32 v145, v145, 0x3c800000, v119
	v_rsq_f32_e32 v154, v145
	v_lshl_or_b32 v145, v156, 8, v142
	v_pk_mul_f32 v[150:151], v[70:71], v[154:155] op_sel_hi:[1,0]
	s_nop 0
	v_pk_mul_f32 v[72:73], v[72:73], v[150:151]
	s_cbranch_vccnz .LBB0_597
	global_load_dwordx2 v[150:151], v145, s[8:9]
	s_waitcnt vmcnt(0)
	v_pk_mul_f32 v[154:155], v[72:73], v[150:151] op_sel_hi:[0,1]
	v_pk_mul_f32 v[152:153], v[72:73], v[150:151] op_sel:[1,1] op_sel_hi:[1,0]
	v_pk_fma_f32 v[72:73], v[72:73], v[150:151], v[154:155] op_sel:[1,1,0] op_sel_hi:[1,0,1] neg_lo:[0,0,1] neg_hi:[0,0,1]
	s_nop 0
	v_add_f32_e32 v72, v152, v154
.LBB0_597:
	v_mov_b32_e32 v150, v58
	v_mov_b32_e32 v151, v42
	v_pk_mul_f32 v[150:151], v[150:151], v[150:151]
	v_cvt_pk_bf16_f32 v157, v72, s0
	v_add_f32_e32 v147, v150, v151
	v_add_u32_e32 v150, s73, v91
	v_mul_lo_u32 v150, v150, s70
	v_add_u32_e32 v153, s75, v150
	v_add_u32_e32 v152, v153, v81
	s_waitcnt lgkmcnt(0)
	v_add_f32_dpp v147, v147, v147 quad_perm:[1,0,3,2] row_mask:0xf bank_mask:0xf
	v_add_u32_e32 v154, v153, v82
	v_ashrrev_i32_e32 v153, 31, v152
	v_cvt_pk_bf16_f32 v151, v73, s0
	v_ashrrev_i32_e32 v155, 31, v154
	v_add_f32_dpp v147, v147, v147 quad_perm:[2,3,0,1] row_mask:0xf bank_mask:0xf
	v_lshl_add_u64 v[152:153], v[152:153], 1, s[6:7]
	v_mov_b32_e32 v72, v42
	v_mov_b32_e32 v73, v58
	v_add_u32_e32 v158, s76, v92
	v_add_f32_dpp v147, v147, v147 row_half_mirror row_mask:0xf bank_mask:0xf
	v_lshl_add_u64 v[154:155], v[154:155], 1, s[6:7]
	global_store_short v[152:153], v151, off sc1
	global_store_short v[154:155], v157, off sc1
	s_and_b64 vcc, exec, s[0:1]
	v_add_f32_dpp v147, v147, v147 row_mirror row_mask:0xf bank_mask:0xf
	v_mov_b32_e32 v149, v147
	s_nop 1
	v_permlane16_swap_b32_e32 v147, v149
	s_nop 0
	v_add_f32_e32 v147, v147, v149
	v_fmamk_f32 v147, v147, 0x3c800000, v119
	v_rsq_f32_e32 v156, v147
	v_lshl_or_b32 v147, v158, 8, v142
	v_pk_mul_f32 v[152:153], v[70:71], v[156:157] op_sel_hi:[1,0]
	s_nop 0
	v_pk_mul_f32 v[72:73], v[72:73], v[152:153]
	s_cbranch_vccnz .LBB0_599
	global_load_dwordx2 v[152:153], v147, s[8:9]
	s_waitcnt vmcnt(0)
	v_pk_mul_f32 v[156:157], v[72:73], v[152:153] op_sel_hi:[0,1]
	v_pk_mul_f32 v[154:155], v[72:73], v[152:153] op_sel:[1,1] op_sel_hi:[1,0]
	v_pk_fma_f32 v[72:73], v[72:73], v[152:153], v[156:157] op_sel:[1,1,0] op_sel_hi:[1,0,1] neg_lo:[0,0,1] neg_hi:[0,0,1]
	s_nop 0
	v_add_f32_e32 v72, v154, v156
.LBB0_599:
	v_mov_b32_e32 v152, v59
	v_mov_b32_e32 v153, v43
	v_pk_mul_f32 v[152:153], v[152:153], v[152:153]
	v_cvt_pk_bf16_f32 v159, v72, s0
	v_add_f32_e32 v149, v152, v153
	v_add_u32_e32 v152, s73, v92
	v_mul_lo_u32 v152, v152, s70
	v_add_u32_e32 v155, s75, v152
	v_add_u32_e32 v154, v155, v81
	s_waitcnt lgkmcnt(0)
	v_add_f32_dpp v149, v149, v149 quad_perm:[1,0,3,2] row_mask:0xf bank_mask:0xf
	v_add_u32_e32 v156, v155, v82
	v_ashrrev_i32_e32 v155, 31, v154
	v_cvt_pk_bf16_f32 v153, v73, s0
	v_ashrrev_i32_e32 v157, 31, v156
	v_add_f32_dpp v149, v149, v149 quad_perm:[2,3,0,1] row_mask:0xf bank_mask:0xf
	v_lshl_add_u64 v[154:155], v[154:155], 1, s[6:7]
	v_mov_b32_e32 v72, v43
	v_mov_b32_e32 v73, v59
	v_add_u32_e32 v160, s76, v93
	v_add_f32_dpp v149, v149, v149 row_half_mirror row_mask:0xf bank_mask:0xf
	v_lshl_add_u64 v[156:157], v[156:157], 1, s[6:7]
	global_store_short v[154:155], v153, off sc1
	global_store_short v[156:157], v159, off sc1
	s_and_b64 vcc, exec, s[0:1]
	v_add_f32_dpp v149, v149, v149 row_mirror row_mask:0xf bank_mask:0xf
	v_mov_b32_e32 v151, v149
	s_nop 1
	v_permlane16_swap_b32_e32 v149, v151
	s_nop 0
	v_add_f32_e32 v149, v149, v151
	v_fmamk_f32 v149, v149, 0x3c800000, v119
	v_rsq_f32_e32 v158, v149
	v_lshl_or_b32 v149, v160, 8, v142
	v_pk_mul_f32 v[154:155], v[70:71], v[158:159] op_sel_hi:[1,0]
	s_nop 0
	v_pk_mul_f32 v[72:73], v[72:73], v[154:155]
	s_cbranch_vccnz .LBB0_601
	global_load_dwordx2 v[154:155], v149, s[8:9]
	s_waitcnt vmcnt(0)
	v_pk_mul_f32 v[158:159], v[72:73], v[154:155] op_sel_hi:[0,1]
	v_pk_mul_f32 v[156:157], v[72:73], v[154:155] op_sel:[1,1] op_sel_hi:[1,0]
	v_pk_fma_f32 v[72:73], v[72:73], v[154:155], v[158:159] op_sel:[1,1,0] op_sel_hi:[1,0,1] neg_lo:[0,0,1] neg_hi:[0,0,1]
	s_nop 0
	v_add_f32_e32 v72, v156, v158
.LBB0_601:
	v_mov_b32_e32 v154, v60
	v_mov_b32_e32 v155, v44
	v_pk_mul_f32 v[154:155], v[154:155], v[154:155]
	v_cvt_pk_bf16_f32 v161, v72, s0
	v_add_f32_e32 v151, v154, v155
	v_add_u32_e32 v154, s73, v93
	v_mul_lo_u32 v154, v154, s70
	v_add_u32_e32 v157, s75, v154
	v_add_u32_e32 v156, v157, v81
	s_waitcnt lgkmcnt(0)
	v_add_f32_dpp v151, v151, v151 quad_perm:[1,0,3,2] row_mask:0xf bank_mask:0xf
	v_add_u32_e32 v158, v157, v82
	v_ashrrev_i32_e32 v157, 31, v156
	v_cvt_pk_bf16_f32 v155, v73, s0
	v_ashrrev_i32_e32 v159, 31, v158
	v_add_f32_dpp v151, v151, v151 quad_perm:[2,3,0,1] row_mask:0xf bank_mask:0xf
	v_lshl_add_u64 v[156:157], v[156:157], 1, s[6:7]
	v_mov_b32_e32 v72, v44
	v_mov_b32_e32 v73, v60
	v_add_u32_e32 v162, s76, v94
	v_add_f32_dpp v151, v151, v151 row_half_mirror row_mask:0xf bank_mask:0xf
	v_lshl_add_u64 v[158:159], v[158:159], 1, s[6:7]
	global_store_short v[156:157], v155, off sc1
	global_store_short v[158:159], v161, off sc1
	s_and_b64 vcc, exec, s[0:1]
	v_add_f32_dpp v151, v151, v151 row_mirror row_mask:0xf bank_mask:0xf
	v_mov_b32_e32 v153, v151
	s_nop 1
	v_permlane16_swap_b32_e32 v151, v153
	s_nop 0
	v_add_f32_e32 v151, v151, v153
	v_fmamk_f32 v151, v151, 0x3c800000, v119
	v_rsq_f32_e32 v160, v151
	v_lshl_or_b32 v151, v162, 8, v142
	v_pk_mul_f32 v[156:157], v[70:71], v[160:161] op_sel_hi:[1,0]
	s_nop 0
	v_pk_mul_f32 v[72:73], v[72:73], v[156:157]
	s_cbranch_vccnz .LBB0_603
	global_load_dwordx2 v[156:157], v151, s[8:9]
	s_waitcnt vmcnt(0)
	v_pk_mul_f32 v[160:161], v[72:73], v[156:157] op_sel_hi:[0,1]
	v_pk_mul_f32 v[158:159], v[72:73], v[156:157] op_sel:[1,1] op_sel_hi:[1,0]
	v_pk_fma_f32 v[72:73], v[72:73], v[156:157], v[160:161] op_sel:[1,1,0] op_sel_hi:[1,0,1] neg_lo:[0,0,1] neg_hi:[0,0,1]
	s_nop 0
	v_add_f32_e32 v72, v158, v160
.LBB0_603:
	v_mov_b32_e32 v156, v61
	v_mov_b32_e32 v157, v45
	v_pk_mul_f32 v[156:157], v[156:157], v[156:157]
	v_cvt_pk_bf16_f32 v163, v72, s0
	v_add_f32_e32 v153, v156, v157
	v_add_u32_e32 v156, s73, v94
	v_mul_lo_u32 v156, v156, s70
	v_add_u32_e32 v159, s75, v156
	v_add_u32_e32 v158, v159, v81
	s_waitcnt lgkmcnt(0)
	v_add_f32_dpp v153, v153, v153 quad_perm:[1,0,3,2] row_mask:0xf bank_mask:0xf
	v_add_u32_e32 v160, v159, v82
	v_ashrrev_i32_e32 v159, 31, v158
	v_cvt_pk_bf16_f32 v157, v73, s0
	v_ashrrev_i32_e32 v161, 31, v160
	v_add_f32_dpp v153, v153, v153 quad_perm:[2,3,0,1] row_mask:0xf bank_mask:0xf
	v_lshl_add_u64 v[158:159], v[158:159], 1, s[6:7]
	v_mov_b32_e32 v72, v45
	v_mov_b32_e32 v73, v61
	v_add_u32_e32 v164, s76, v95
	v_add_f32_dpp v153, v153, v153 row_half_mirror row_mask:0xf bank_mask:0xf
	v_lshl_add_u64 v[160:161], v[160:161], 1, s[6:7]
	global_store_short v[158:159], v157, off sc1
	global_store_short v[160:161], v163, off sc1
	s_and_b64 vcc, exec, s[0:1]
	v_add_f32_dpp v153, v153, v153 row_mirror row_mask:0xf bank_mask:0xf
	v_mov_b32_e32 v155, v153
	s_nop 1
	v_permlane16_swap_b32_e32 v153, v155
	s_nop 0
	v_add_f32_e32 v153, v153, v155
	v_fmamk_f32 v153, v153, 0x3c800000, v119
	v_rsq_f32_e32 v162, v153
	v_lshl_or_b32 v153, v164, 8, v142
	v_pk_mul_f32 v[158:159], v[70:71], v[162:163] op_sel_hi:[1,0]
	s_nop 0
	v_pk_mul_f32 v[72:73], v[72:73], v[158:159]
	s_cbranch_vccnz .LBB0_605
	global_load_dwordx2 v[158:159], v153, s[8:9]
	s_waitcnt vmcnt(0)
	v_pk_mul_f32 v[162:163], v[72:73], v[158:159] op_sel_hi:[0,1]
	v_pk_mul_f32 v[160:161], v[72:73], v[158:159] op_sel:[1,1] op_sel_hi:[1,0]
	v_pk_fma_f32 v[72:73], v[72:73], v[158:159], v[162:163] op_sel:[1,1,0] op_sel_hi:[1,0,1] neg_lo:[0,0,1] neg_hi:[0,0,1]
	s_nop 0
	v_add_f32_e32 v72, v160, v162
.LBB0_605:
	v_mov_b32_e32 v158, v62
	v_mov_b32_e32 v159, v46
	v_pk_mul_f32 v[158:159], v[158:159], v[158:159]
	v_cvt_pk_bf16_f32 v163, v73, s0
	v_add_f32_e32 v155, v158, v159
	v_add_u32_e32 v158, s73, v95
	v_cvt_pk_bf16_f32 v164, v72, s0
	v_mov_b32_e32 v72, v46
	v_mov_b32_e32 v73, v62
	s_waitcnt lgkmcnt(0)
	v_add_f32_dpp v155, v155, v155 quad_perm:[1,0,3,2] row_mask:0xf bank_mask:0xf
	v_add_u32_e32 v165, s76, v96
	s_and_b64 vcc, exec, s[0:1]
	v_add_f32_dpp v155, v155, v155 quad_perm:[2,3,0,1] row_mask:0xf bank_mask:0xf
	s_nop 0
	v_add_f32_dpp v155, v155, v155 row_half_mirror row_mask:0xf bank_mask:0xf
	v_mul_lo_u32 v157, v158, s70
	v_add_u32_e32 v160, s75, v157
	v_add_u32_e32 v158, v160, v81
	v_add_u32_e32 v160, v160, v82
	v_add_f32_dpp v155, v155, v155 row_mirror row_mask:0xf bank_mask:0xf
	v_mov_b32_e32 v162, v155
	s_nop 1
	v_permlane16_swap_b32_e32 v155, v162
	s_nop 0
	v_ashrrev_i32_e32 v159, 31, v158
	v_ashrrev_i32_e32 v161, 31, v160
	v_lshl_add_u64 v[158:159], v[158:159], 1, s[6:7]
	v_lshl_add_u64 v[160:161], v[160:161], 1, s[6:7]
	v_add_f32_e32 v155, v155, v162
	v_fmamk_f32 v155, v155, 0x3c800000, v119
	v_rsq_f32_e32 v162, v155
	global_store_short v[158:159], v163, off sc1
	global_store_short v[160:161], v164, off sc1
	v_lshl_or_b32 v155, v165, 8, v142
	v_pk_mul_f32 v[158:159], v[70:71], v[162:163] op_sel_hi:[1,0]
	s_nop 0
	v_pk_mul_f32 v[72:73], v[72:73], v[158:159]
	s_cbranch_vccnz .LBB0_607
	global_load_dwordx2 v[158:159], v155, s[8:9]
	s_waitcnt vmcnt(0)
	v_pk_mul_f32 v[162:163], v[72:73], v[158:159] op_sel_hi:[0,1]
	v_pk_mul_f32 v[160:161], v[72:73], v[158:159] op_sel:[1,1] op_sel_hi:[1,0]
	v_pk_fma_f32 v[72:73], v[72:73], v[158:159], v[162:163] op_sel:[1,1,0] op_sel_hi:[1,0,1] neg_lo:[0,0,1] neg_hi:[0,0,1]
	s_nop 0
	v_add_f32_e32 v72, v160, v162
.LBB0_607:
	v_mov_b32_e32 v158, v63
	v_mov_b32_e32 v159, v47
	v_pk_mul_f32 v[158:159], v[158:159], v[158:159]
	v_add_u32_e32 v160, s73, v96
	v_add_f32_e32 v158, v158, v159
	v_cvt_pk_bf16_f32 v165, v73, s0
	v_cvt_pk_bf16_f32 v166, v72, s0
	v_mov_b32_e32 v72, v47
	v_mov_b32_e32 v73, v63
	s_waitcnt lgkmcnt(0)
	v_add_f32_dpp v158, v158, v158 quad_perm:[1,0,3,2] row_mask:0xf bank_mask:0xf
	v_add_u32_e32 v167, s76, v97
	s_and_b64 vcc, exec, s[0:1]
	v_lshl_or_b32 v142, v167, 8, v142
	v_add_f32_dpp v158, v158, v158 quad_perm:[2,3,0,1] row_mask:0xf bank_mask:0xf
	s_nop 0
	v_add_f32_dpp v159, v158, v158 row_half_mirror row_mask:0xf bank_mask:0xf
	v_mul_lo_u32 v158, v160, s70
	v_add_u32_e32 v162, s75, v158
	v_add_u32_e32 v160, v162, v81
	v_add_u32_e32 v162, v162, v82
	v_add_f32_dpp v159, v159, v159 row_mirror row_mask:0xf bank_mask:0xf
	v_mov_b32_e32 v164, v159
	s_nop 1
	v_permlane16_swap_b32_e32 v159, v164
	s_nop 0
	v_ashrrev_i32_e32 v161, 31, v160
	v_ashrrev_i32_e32 v163, 31, v162
	v_lshl_add_u64 v[160:161], v[160:161], 1, s[6:7]
	v_lshl_add_u64 v[162:163], v[162:163], 1, s[6:7]
	v_add_f32_e32 v159, v159, v164
	v_fmamk_f32 v159, v159, 0x3c800000, v119
	v_rsq_f32_e32 v164, v159
	global_store_short v[160:161], v165, off sc1
	global_store_short v[162:163], v166, off sc1
	v_pk_mul_f32 v[160:161], v[70:71], v[164:165] op_sel_hi:[1,0]
	s_nop 0
	v_pk_mul_f32 v[72:73], v[72:73], v[160:161]
	s_cbranch_vccnz .LBB0_609
	global_load_dwordx2 v[160:161], v142, s[8:9]
	s_waitcnt vmcnt(0)
	v_pk_mul_f32 v[164:165], v[72:73], v[160:161] op_sel_hi:[0,1]
	v_pk_mul_f32 v[162:163], v[72:73], v[160:161] op_sel:[1,1] op_sel_hi:[1,0]
	v_pk_fma_f32 v[72:73], v[72:73], v[160:161], v[164:165] op_sel:[1,1,0] op_sel_hi:[1,0,1] neg_lo:[0,0,1] neg_hi:[0,0,1]
	s_nop 0
	v_add_f32_e32 v72, v162, v164
.LBB0_609:
	v_mov_b32_e32 v160, v16
	v_mov_b32_e32 v161, v0
	v_pk_mul_f32 v[160:161], v[160:161], v[160:161]
	v_cvt_pk_bf16_f32 v165, v73, s0
	v_add_f32_e32 v159, v160, v161
	v_add_u32_e32 v161, s73, v97
	v_cvt_pk_bf16_f32 v166, v72, s0
	v_mov_b32_e32 v72, v0
	v_mov_b32_e32 v73, v16
	s_waitcnt lgkmcnt(0)
	v_add_f32_dpp v159, v159, v159 quad_perm:[1,0,3,2] row_mask:0xf bank_mask:0xf
	s_and_b64 vcc, exec, s[0:1]
	v_add_f32_dpp v159, v159, v159 quad_perm:[2,3,0,1] row_mask:0xf bank_mask:0xf
	s_nop 0
	v_add_f32_dpp v162, v159, v159 row_half_mirror row_mask:0xf bank_mask:0xf
	v_mul_lo_u32 v159, v161, s70
	v_add_u32_e32 v161, s75, v159
	v_add_u32_e32 v160, v161, v81
	v_add_f32_dpp v164, v162, v162 row_mirror row_mask:0xf bank_mask:0xf
	v_mov_b32_e32 v167, v164
	s_nop 1
	v_permlane16_swap_b32_e32 v164, v167
	s_nop 0
	v_add_u32_e32 v162, v161, v82
	v_ashrrev_i32_e32 v161, 31, v160
	v_ashrrev_i32_e32 v163, 31, v162
	v_lshl_add_u64 v[160:161], v[160:161], 1, s[6:7]
	v_add_f32_e32 v164, v164, v167
	v_fmamk_f32 v164, v164, 0x3c800000, v119
	v_rsq_f32_e32 v164, v164
	v_lshl_add_u64 v[162:163], v[162:163], 1, s[6:7]
	global_store_short v[160:161], v165, off sc1
	global_store_short v[162:163], v166, off sc1
	v_pk_mul_f32 v[160:161], v[70:71], v[164:165] op_sel_hi:[1,0]
	s_nop 0
	v_pk_mul_f32 v[72:73], v[72:73], v[160:161]
	s_cbranch_vccnz .LBB0_611
	global_load_dwordx2 v[160:161], v128, s[8:9]
	s_waitcnt vmcnt(0)
	v_pk_mul_f32 v[164:165], v[72:73], v[160:161] op_sel_hi:[0,1]
	v_pk_mul_f32 v[162:163], v[72:73], v[160:161] op_sel:[1,1] op_sel_hi:[1,0]
	v_pk_fma_f32 v[72:73], v[72:73], v[160:161], v[164:165] op_sel:[1,1,0] op_sel_hi:[1,0,1] neg_lo:[0,0,1] neg_hi:[0,0,1]
	s_nop 0
	v_add_f32_e32 v72, v162, v164
.LBB0_611:
	v_mov_b32_e32 v160, v17
	v_mov_b32_e32 v161, v1
	v_pk_mul_f32 v[160:161], v[160:161], v[160:161]
	s_addk_i32 s74, 0xf4c0
	v_add_f32_e32 v128, v160, v161
	v_add_u32_e32 v129, s74, v129
	v_cvt_pk_bf16_f32 v163, v73, s0
	v_cvt_pk_bf16_f32 v164, v72, s0
	v_mov_b32_e32 v72, v1
	s_waitcnt lgkmcnt(0)
	v_add_f32_dpp v128, v128, v128 quad_perm:[1,0,3,2] row_mask:0xf bank_mask:0xf
	v_mov_b32_e32 v73, v17
	s_and_b64 vcc, exec, s[0:1]
	v_add_f32_dpp v128, v128, v128 quad_perm:[2,3,0,1] row_mask:0xf bank_mask:0xf
	s_nop 0
	v_add_f32_dpp v160, v128, v128 row_half_mirror row_mask:0xf bank_mask:0xf
	v_add_u32_e32 v128, v129, v81
	v_add_f32_dpp v162, v160, v160 row_mirror row_mask:0xf bank_mask:0xf
	v_mov_b32_e32 v165, v162
	s_nop 1
	v_permlane16_swap_b32_e32 v162, v165
	s_nop 0
	v_add_u32_e32 v160, v129, v82
	v_ashrrev_i32_e32 v129, 31, v128
	v_ashrrev_i32_e32 v161, 31, v160
	v_lshl_add_u64 v[128:129], v[128:129], 1, s[6:7]
	v_add_f32_e32 v162, v162, v165
	v_fmamk_f32 v162, v162, 0x3c800000, v119
	v_rsq_f32_e32 v162, v162
	v_lshl_add_u64 v[160:161], v[160:161], 1, s[6:7]
	global_store_short v[128:129], v163, off sc1
	global_store_short v[160:161], v164, off sc1
	v_pk_mul_f32 v[128:129], v[70:71], v[162:163] op_sel_hi:[1,0]
	s_nop 0
	v_pk_mul_f32 v[72:73], v[72:73], v[128:129]
	s_cbranch_vccnz .LBB0_613
	global_load_dwordx2 v[128:129], v130, s[8:9]
	s_waitcnt vmcnt(0)
	v_pk_mul_f32 v[162:163], v[72:73], v[128:129] op_sel_hi:[0,1]
	v_pk_mul_f32 v[160:161], v[72:73], v[128:129] op_sel:[1,1] op_sel_hi:[1,0]
	v_pk_fma_f32 v[72:73], v[72:73], v[128:129], v[162:163] op_sel:[1,1,0] op_sel_hi:[1,0,1] neg_lo:[0,0,1] neg_hi:[0,0,1]
	s_nop 0
	v_add_f32_e32 v72, v160, v162
.LBB0_613:
	v_mov_b32_e32 v128, v18
	v_mov_b32_e32 v129, v2
	v_pk_mul_f32 v[128:129], v[128:129], v[128:129]
	v_add_u32_e32 v130, s74, v133
	v_add_f32_e32 v128, v128, v129
	v_add_u32_e32 v160, v130, v82
	v_cvt_pk_bf16_f32 v162, v73, s0
	v_ashrrev_i32_e32 v161, 31, v160
	v_cvt_pk_bf16_f32 v163, v72, s0
	s_waitcnt lgkmcnt(0)
	v_add_f32_dpp v128, v128, v128 quad_perm:[1,0,3,2] row_mask:0xf bank_mask:0xf
	v_mov_b32_e32 v72, v2
	v_mov_b32_e32 v73, v18
	v_lshl_add_u64 v[160:161], v[160:161], 1, s[6:7]
	s_and_b64 vcc, exec, s[0:1]
	v_add_f32_dpp v128, v128, v128 quad_perm:[2,3,0,1] row_mask:0xf bank_mask:0xf
	s_nop 0
	v_add_f32_dpp v129, v128, v128 row_half_mirror row_mask:0xf bank_mask:0xf
	v_add_u32_e32 v128, v130, v81
	v_add_f32_dpp v133, v129, v129 row_mirror row_mask:0xf bank_mask:0xf
	ds_bpermute_b32 v164, v126, v133
	v_ashrrev_i32_e32 v129, 31, v128
	v_lshl_add_u64 v[128:129], v[128:129], 1, s[6:7]
	global_store_short v[128:129], v162, off sc1
	global_store_short v[160:161], v163, off sc1
	s_waitcnt lgkmcnt(0)
	v_add_f32_e32 v130, v133, v164
	v_fmamk_f32 v130, v130, 0x3c800000, v119
	v_rsq_f32_e32 v130, v130
	s_nop 0
	v_pk_mul_f32 v[128:129], v[70:71], v[130:131] op_sel_hi:[1,0]
	s_nop 0
	v_pk_mul_f32 v[72:73], v[72:73], v[128:129]
	s_cbranch_vccnz .LBB0_615
	global_load_dwordx2 v[128:129], v131, s[8:9]
	s_waitcnt vmcnt(0)
	v_pk_mul_f32 v[160:161], v[72:73], v[128:129] op_sel_hi:[0,1]
	v_pk_mul_f32 v[130:131], v[72:73], v[128:129] op_sel:[1,1] op_sel_hi:[1,0]
	v_pk_fma_f32 v[72:73], v[72:73], v[128:129], v[160:161] op_sel:[1,1,0] op_sel_hi:[1,0,1] neg_lo:[0,0,1] neg_hi:[0,0,1]
	s_nop 0
	v_add_f32_e32 v72, v130, v160
.LBB0_615:
	v_mov_b32_e32 v128, v19
	v_mov_b32_e32 v129, v3
	v_pk_mul_f32 v[128:129], v[128:129], v[128:129]
	v_add_u32_e32 v130, s74, v135
	v_add_f32_e32 v128, v128, v129
	v_cvt_pk_bf16_f32 v133, v73, s0
	v_cvt_pk_bf16_f32 v135, v72, s0
	v_mov_b32_e32 v72, v3
	v_mov_b32_e32 v73, v19
	s_waitcnt lgkmcnt(0)
	v_add_f32_dpp v128, v128, v128 quad_perm:[1,0,3,2] row_mask:0xf bank_mask:0xf
	s_and_b64 vcc, exec, s[0:1]
	v_add_f32_dpp v128, v128, v128 quad_perm:[2,3,0,1] row_mask:0xf bank_mask:0xf
	s_nop 0
	v_add_f32_dpp v129, v128, v128 row_half_mirror row_mask:0xf bank_mask:0xf
	v_add_u32_e32 v128, v130, v81
	v_add_u32_e32 v130, v130, v82
	v_add_f32_dpp v160, v129, v129 row_mirror row_mask:0xf bank_mask:0xf
	v_mov_b32_e32 v161, v160
	s_nop 1
	v_permlane16_swap_b32_e32 v160, v161
	s_nop 0
	v_ashrrev_i32_e32 v129, 31, v128
	v_ashrrev_i32_e32 v131, 31, v130
	v_lshl_add_u64 v[128:129], v[128:129], 1, s[6:7]
	v_lshl_add_u64 v[130:131], v[130:131], 1, s[6:7]
	v_add_f32_e32 v160, v160, v161
	v_fmamk_f32 v160, v160, 0x3c800000, v119
	v_rsq_f32_e32 v160, v160
	global_store_short v[128:129], v133, off sc1
	global_store_short v[130:131], v135, off sc1
	v_pk_mul_f32 v[128:129], v[70:71], v[160:161] op_sel_hi:[1,0]
	s_nop 0
	v_pk_mul_f32 v[72:73], v[72:73], v[128:129]
	s_cbranch_vccnz .LBB0_617
	global_load_dwordx2 v[128:129], v132, s[8:9]
	s_waitcnt vmcnt(0)
	v_pk_mul_f32 v[132:133], v[72:73], v[128:129] op_sel_hi:[0,1]
	v_pk_mul_f32 v[130:131], v[72:73], v[128:129] op_sel:[1,1] op_sel_hi:[1,0]
	v_pk_fma_f32 v[72:73], v[72:73], v[128:129], v[132:133] op_sel:[1,1,0] op_sel_hi:[1,0,1] neg_lo:[0,0,1] neg_hi:[0,0,1]
	s_nop 0
	v_add_f32_e32 v72, v130, v132
.LBB0_617:
	v_mov_b32_e32 v128, v20
	v_mov_b32_e32 v129, v4
	v_pk_mul_f32 v[128:129], v[128:129], v[128:129]
	v_add_u32_e32 v130, s74, v137
	v_add_f32_e32 v128, v128, v129
	v_cvt_pk_bf16_f32 v133, v73, s0
	v_cvt_pk_bf16_f32 v135, v72, s0
	v_mov_b32_e32 v72, v4
	v_mov_b32_e32 v73, v20
	s_waitcnt lgkmcnt(0)
	v_add_f32_dpp v128, v128, v128 quad_perm:[1,0,3,2] row_mask:0xf bank_mask:0xf
	s_and_b64 vcc, exec, s[0:1]
	v_add_f32_dpp v128, v128, v128 quad_perm:[2,3,0,1] row_mask:0xf bank_mask:0xf
	s_nop 0
	v_add_f32_dpp v129, v128, v128 row_half_mirror row_mask:0xf bank_mask:0xf
	v_add_u32_e32 v128, v130, v81
	v_add_u32_e32 v130, v130, v82
	v_add_f32_dpp v132, v129, v129 row_mirror row_mask:0xf bank_mask:0xf
	v_mov_b32_e32 v137, v132
	s_nop 1
	v_permlane16_swap_b32_e32 v132, v137
	s_nop 0
	v_ashrrev_i32_e32 v129, 31, v128
	v_ashrrev_i32_e32 v131, 31, v130
	v_lshl_add_u64 v[128:129], v[128:129], 1, s[6:7]
	v_lshl_add_u64 v[130:131], v[130:131], 1, s[6:7]
	v_add_f32_e32 v132, v132, v137
	v_fmamk_f32 v132, v132, 0x3c800000, v119
	v_rsq_f32_e32 v132, v132
	global_store_short v[128:129], v133, off sc1
	global_store_short v[130:131], v135, off sc1
	v_pk_mul_f32 v[128:129], v[70:71], v[132:133] op_sel_hi:[1,0]
	s_nop 0
	v_pk_mul_f32 v[72:73], v[72:73], v[128:129]
	s_cbranch_vccnz .LBB0_619
	global_load_dwordx2 v[128:129], v134, s[8:9]
	s_waitcnt vmcnt(0)
	v_pk_mul_f32 v[132:133], v[72:73], v[128:129] op_sel_hi:[0,1]
	v_pk_mul_f32 v[130:131], v[72:73], v[128:129] op_sel:[1,1] op_sel_hi:[1,0]
	v_pk_fma_f32 v[72:73], v[72:73], v[128:129], v[132:133] op_sel:[1,1,0] op_sel_hi:[1,0,1] neg_lo:[0,0,1] neg_hi:[0,0,1]
	s_nop 0
	v_add_f32_e32 v72, v130, v132
.LBB0_619:
	v_mov_b32_e32 v128, v21
	v_mov_b32_e32 v129, v5
	v_pk_mul_f32 v[128:129], v[128:129], v[128:129]
	v_add_u32_e32 v130, s74, v139
	v_add_f32_e32 v128, v128, v129
	v_cvt_pk_bf16_f32 v133, v73, s0
	v_cvt_pk_bf16_f32 v134, v72, s0
	v_mov_b32_e32 v72, v5
	v_mov_b32_e32 v73, v21
	s_waitcnt lgkmcnt(0)
	v_add_f32_dpp v128, v128, v128 quad_perm:[1,0,3,2] row_mask:0xf bank_mask:0xf
	s_and_b64 vcc, exec, s[0:1]
	v_add_f32_dpp v128, v128, v128 quad_perm:[2,3,0,1] row_mask:0xf bank_mask:0xf
	s_nop 0
	v_add_f32_dpp v129, v128, v128 row_half_mirror row_mask:0xf bank_mask:0xf
	v_add_u32_e32 v128, v130, v81
	v_add_u32_e32 v130, v130, v82
	v_add_f32_dpp v132, v129, v129 row_mirror row_mask:0xf bank_mask:0xf
	v_mov_b32_e32 v135, v132
	s_nop 1
	v_permlane16_swap_b32_e32 v132, v135
	s_nop 0
	v_ashrrev_i32_e32 v129, 31, v128
	v_ashrrev_i32_e32 v131, 31, v130
	v_lshl_add_u64 v[128:129], v[128:129], 1, s[6:7]
	v_lshl_add_u64 v[130:131], v[130:131], 1, s[6:7]
	v_add_f32_e32 v132, v132, v135
	v_fmamk_f32 v132, v132, 0x3c800000, v119
	v_rsq_f32_e32 v132, v132
	global_store_short v[128:129], v133, off sc1
	global_store_short v[130:131], v134, off sc1
	v_pk_mul_f32 v[128:129], v[70:71], v[132:133] op_sel_hi:[1,0]
	s_nop 0
	v_pk_mul_f32 v[72:73], v[72:73], v[128:129]
	s_cbranch_vccnz .LBB0_621
	global_load_dwordx2 v[128:129], v136, s[8:9]
	s_waitcnt vmcnt(0)
	v_pk_mul_f32 v[132:133], v[72:73], v[128:129] op_sel_hi:[0,1]
	v_pk_mul_f32 v[130:131], v[72:73], v[128:129] op_sel:[1,1] op_sel_hi:[1,0]
	v_pk_fma_f32 v[72:73], v[72:73], v[128:129], v[132:133] op_sel:[1,1,0] op_sel_hi:[1,0,1] neg_lo:[0,0,1] neg_hi:[0,0,1]
	s_nop 0
	v_add_f32_e32 v72, v130, v132
.LBB0_621:
	v_mov_b32_e32 v128, v22
	v_mov_b32_e32 v129, v6
	v_pk_mul_f32 v[128:129], v[128:129], v[128:129]
	v_add_u32_e32 v130, s74, v141
	v_add_f32_e32 v128, v128, v129
	v_cvt_pk_bf16_f32 v133, v73, s0
	v_cvt_pk_bf16_f32 v134, v72, s0
	v_mov_b32_e32 v72, v6
	v_mov_b32_e32 v73, v22
	s_waitcnt lgkmcnt(0)
	v_add_f32_dpp v128, v128, v128 quad_perm:[1,0,3,2] row_mask:0xf bank_mask:0xf
	s_and_b64 vcc, exec, s[0:1]
	v_add_f32_dpp v128, v128, v128 quad_perm:[2,3,0,1] row_mask:0xf bank_mask:0xf
	s_nop 0
	v_add_f32_dpp v129, v128, v128 row_half_mirror row_mask:0xf bank_mask:0xf
	v_add_u32_e32 v128, v130, v81
	v_add_u32_e32 v130, v130, v82
	v_add_f32_dpp v132, v129, v129 row_mirror row_mask:0xf bank_mask:0xf
	v_mov_b32_e32 v135, v132
	s_nop 1
	v_permlane16_swap_b32_e32 v132, v135
	s_nop 0
	v_ashrrev_i32_e32 v129, 31, v128
	v_ashrrev_i32_e32 v131, 31, v130
	v_lshl_add_u64 v[128:129], v[128:129], 1, s[6:7]
	v_lshl_add_u64 v[130:131], v[130:131], 1, s[6:7]
	v_add_f32_e32 v132, v132, v135
	v_fmamk_f32 v132, v132, 0x3c800000, v119
	v_rsq_f32_e32 v132, v132
	global_store_short v[128:129], v133, off sc1
	global_store_short v[130:131], v134, off sc1
	v_pk_mul_f32 v[128:129], v[70:71], v[132:133] op_sel_hi:[1,0]
	s_nop 0
	v_pk_mul_f32 v[72:73], v[72:73], v[128:129]
	s_cbranch_vccnz .LBB0_623
	global_load_dwordx2 v[128:129], v138, s[8:9]
	s_waitcnt vmcnt(0)
	v_pk_mul_f32 v[132:133], v[72:73], v[128:129] op_sel_hi:[0,1]
	v_pk_mul_f32 v[130:131], v[72:73], v[128:129] op_sel:[1,1] op_sel_hi:[1,0]
	v_pk_fma_f32 v[72:73], v[72:73], v[128:129], v[132:133] op_sel:[1,1,0] op_sel_hi:[1,0,1] neg_lo:[0,0,1] neg_hi:[0,0,1]
	s_nop 0
	v_add_f32_e32 v72, v130, v132
.LBB0_623:
	v_mov_b32_e32 v128, v23
	v_mov_b32_e32 v129, v7
	v_pk_mul_f32 v[128:129], v[128:129], v[128:129]
	v_add_u32_e32 v130, s74, v144
	v_add_f32_e32 v128, v128, v129
	v_cvt_pk_bf16_f32 v133, v73, s0
	v_cvt_pk_bf16_f32 v134, v72, s0
	v_mov_b32_e32 v72, v7
	v_mov_b32_e32 v73, v23
	s_waitcnt lgkmcnt(0)
	v_add_f32_dpp v128, v128, v128 quad_perm:[1,0,3,2] row_mask:0xf bank_mask:0xf
	s_and_b64 vcc, exec, s[0:1]
	v_add_f32_dpp v128, v128, v128 quad_perm:[2,3,0,1] row_mask:0xf bank_mask:0xf
	s_nop 0
	v_add_f32_dpp v129, v128, v128 row_half_mirror row_mask:0xf bank_mask:0xf
	v_add_u32_e32 v128, v130, v81
	v_add_u32_e32 v130, v130, v82
	v_add_f32_dpp v132, v129, v129 row_mirror row_mask:0xf bank_mask:0xf
	v_mov_b32_e32 v135, v132
	s_nop 1
	v_permlane16_swap_b32_e32 v132, v135
	s_nop 0
	v_ashrrev_i32_e32 v129, 31, v128
	v_ashrrev_i32_e32 v131, 31, v130
	v_lshl_add_u64 v[128:129], v[128:129], 1, s[6:7]
	v_lshl_add_u64 v[130:131], v[130:131], 1, s[6:7]
	v_add_f32_e32 v132, v132, v135
	v_fmamk_f32 v132, v132, 0x3c800000, v119
	v_rsq_f32_e32 v132, v132
	global_store_short v[128:129], v133, off sc1
	global_store_short v[130:131], v134, off sc1
	v_pk_mul_f32 v[128:129], v[70:71], v[132:133] op_sel_hi:[1,0]
	s_nop 0
	v_pk_mul_f32 v[72:73], v[72:73], v[128:129]
	s_cbranch_vccnz .LBB0_625
	global_load_dwordx2 v[128:129], v140, s[8:9]
	s_waitcnt vmcnt(0)
	v_pk_mul_f32 v[132:133], v[72:73], v[128:129] op_sel_hi:[0,1]
	v_pk_mul_f32 v[130:131], v[72:73], v[128:129] op_sel:[1,1] op_sel_hi:[1,0]
	v_pk_fma_f32 v[72:73], v[72:73], v[128:129], v[132:133] op_sel:[1,1,0] op_sel_hi:[1,0,1] neg_lo:[0,0,1] neg_hi:[0,0,1]
	s_nop 0
	v_add_f32_e32 v72, v130, v132
.LBB0_625:
	v_mov_b32_e32 v128, v24
	v_mov_b32_e32 v129, v8
	v_pk_mul_f32 v[128:129], v[128:129], v[128:129]
	v_add_u32_e32 v130, s74, v146
	v_add_f32_e32 v128, v128, v129
	v_cvt_pk_bf16_f32 v133, v73, s0
	v_cvt_pk_bf16_f32 v134, v72, s0
	v_mov_b32_e32 v72, v8
	v_mov_b32_e32 v73, v24
	s_waitcnt lgkmcnt(0)
	v_add_f32_dpp v128, v128, v128 quad_perm:[1,0,3,2] row_mask:0xf bank_mask:0xf
	s_and_b64 vcc, exec, s[0:1]
	v_add_f32_dpp v128, v128, v128 quad_perm:[2,3,0,1] row_mask:0xf bank_mask:0xf
	s_nop 0
	v_add_f32_dpp v129, v128, v128 row_half_mirror row_mask:0xf bank_mask:0xf
	v_add_u32_e32 v128, v130, v81
	v_add_u32_e32 v130, v130, v82
	v_add_f32_dpp v132, v129, v129 row_mirror row_mask:0xf bank_mask:0xf
	v_mov_b32_e32 v135, v132
	s_nop 1
	v_permlane16_swap_b32_e32 v132, v135
	s_nop 0
	v_ashrrev_i32_e32 v129, 31, v128
	v_ashrrev_i32_e32 v131, 31, v130
	v_lshl_add_u64 v[128:129], v[128:129], 1, s[6:7]
	v_lshl_add_u64 v[130:131], v[130:131], 1, s[6:7]
	v_add_f32_e32 v132, v132, v135
	v_fmamk_f32 v132, v132, 0x3c800000, v119
	v_rsq_f32_e32 v132, v132
	global_store_short v[128:129], v133, off sc1
	global_store_short v[130:131], v134, off sc1
	v_pk_mul_f32 v[128:129], v[70:71], v[132:133] op_sel_hi:[1,0]
	s_nop 0
	v_pk_mul_f32 v[72:73], v[72:73], v[128:129]
	s_cbranch_vccnz .LBB0_627
	global_load_dwordx2 v[128:129], v143, s[8:9]
	s_waitcnt vmcnt(0)
	v_pk_mul_f32 v[132:133], v[72:73], v[128:129] op_sel_hi:[0,1]
	v_pk_mul_f32 v[130:131], v[72:73], v[128:129] op_sel:[1,1] op_sel_hi:[1,0]
	v_pk_fma_f32 v[72:73], v[72:73], v[128:129], v[132:133] op_sel:[1,1,0] op_sel_hi:[1,0,1] neg_lo:[0,0,1] neg_hi:[0,0,1]
	s_nop 0
	v_add_f32_e32 v72, v130, v132
.LBB0_627:
	v_mov_b32_e32 v128, v25
	v_mov_b32_e32 v129, v9
	v_pk_mul_f32 v[128:129], v[128:129], v[128:129]
	v_add_u32_e32 v130, s74, v148
	v_add_f32_e32 v128, v128, v129
	v_cvt_pk_bf16_f32 v133, v73, s0
	v_cvt_pk_bf16_f32 v134, v72, s0
	v_mov_b32_e32 v72, v9
	v_mov_b32_e32 v73, v25
	s_waitcnt lgkmcnt(0)
	v_add_f32_dpp v128, v128, v128 quad_perm:[1,0,3,2] row_mask:0xf bank_mask:0xf
	s_and_b64 vcc, exec, s[0:1]
	v_add_f32_dpp v128, v128, v128 quad_perm:[2,3,0,1] row_mask:0xf bank_mask:0xf
	s_nop 0
	v_add_f32_dpp v129, v128, v128 row_half_mirror row_mask:0xf bank_mask:0xf
	v_add_u32_e32 v128, v130, v81
	v_add_u32_e32 v130, v130, v82
	v_add_f32_dpp v132, v129, v129 row_mirror row_mask:0xf bank_mask:0xf
	v_mov_b32_e32 v135, v132
	s_nop 1
	v_permlane16_swap_b32_e32 v132, v135
	s_nop 0
	v_ashrrev_i32_e32 v129, 31, v128
	v_ashrrev_i32_e32 v131, 31, v130
	v_lshl_add_u64 v[128:129], v[128:129], 1, s[6:7]
	v_lshl_add_u64 v[130:131], v[130:131], 1, s[6:7]
	v_add_f32_e32 v132, v132, v135
	v_fmamk_f32 v132, v132, 0x3c800000, v119
	v_rsq_f32_e32 v132, v132
	global_store_short v[128:129], v133, off sc1
	global_store_short v[130:131], v134, off sc1
	v_pk_mul_f32 v[128:129], v[70:71], v[132:133] op_sel_hi:[1,0]
	s_nop 0
	v_pk_mul_f32 v[72:73], v[72:73], v[128:129]
	s_cbranch_vccnz .LBB0_629
	global_load_dwordx2 v[128:129], v145, s[8:9]
	s_waitcnt vmcnt(0)
	v_pk_mul_f32 v[132:133], v[72:73], v[128:129] op_sel_hi:[0,1]
	v_pk_mul_f32 v[130:131], v[72:73], v[128:129] op_sel:[1,1] op_sel_hi:[1,0]
	v_pk_fma_f32 v[72:73], v[72:73], v[128:129], v[132:133] op_sel:[1,1,0] op_sel_hi:[1,0,1] neg_lo:[0,0,1] neg_hi:[0,0,1]
	s_nop 0
	v_add_f32_e32 v72, v130, v132
.LBB0_629:
	v_mov_b32_e32 v128, v26
	v_mov_b32_e32 v129, v10
	v_pk_mul_f32 v[128:129], v[128:129], v[128:129]
	v_add_u32_e32 v130, s74, v150
	v_add_f32_e32 v128, v128, v129
	v_cvt_pk_bf16_f32 v133, v73, s0
	v_cvt_pk_bf16_f32 v134, v72, s0
	v_mov_b32_e32 v72, v10
	v_mov_b32_e32 v73, v26
	s_waitcnt lgkmcnt(0)
	v_add_f32_dpp v128, v128, v128 quad_perm:[1,0,3,2] row_mask:0xf bank_mask:0xf
	s_and_b64 vcc, exec, s[0:1]
	v_add_f32_dpp v128, v128, v128 quad_perm:[2,3,0,1] row_mask:0xf bank_mask:0xf
	s_nop 0
	v_add_f32_dpp v129, v128, v128 row_half_mirror row_mask:0xf bank_mask:0xf
	v_add_u32_e32 v128, v130, v81
	v_add_u32_e32 v130, v130, v82
	v_add_f32_dpp v132, v129, v129 row_mirror row_mask:0xf bank_mask:0xf
	v_mov_b32_e32 v135, v132
	s_nop 1
	v_permlane16_swap_b32_e32 v132, v135
	s_nop 0
	v_ashrrev_i32_e32 v129, 31, v128
	v_ashrrev_i32_e32 v131, 31, v130
	v_lshl_add_u64 v[128:129], v[128:129], 1, s[6:7]
	v_lshl_add_u64 v[130:131], v[130:131], 1, s[6:7]
	v_add_f32_e32 v132, v132, v135
	v_fmamk_f32 v132, v132, 0x3c800000, v119
	v_rsq_f32_e32 v132, v132
	global_store_short v[128:129], v133, off sc1
	global_store_short v[130:131], v134, off sc1
	v_pk_mul_f32 v[128:129], v[70:71], v[132:133] op_sel_hi:[1,0]
	s_nop 0
	v_pk_mul_f32 v[72:73], v[72:73], v[128:129]
	s_cbranch_vccnz .LBB0_631
	global_load_dwordx2 v[128:129], v147, s[8:9]
	s_waitcnt vmcnt(0)
	v_pk_mul_f32 v[132:133], v[72:73], v[128:129] op_sel_hi:[0,1]
	v_pk_mul_f32 v[130:131], v[72:73], v[128:129] op_sel:[1,1] op_sel_hi:[1,0]
	v_pk_fma_f32 v[72:73], v[72:73], v[128:129], v[132:133] op_sel:[1,1,0] op_sel_hi:[1,0,1] neg_lo:[0,0,1] neg_hi:[0,0,1]
	s_nop 0
	v_add_f32_e32 v72, v130, v132
.LBB0_631:
	v_mov_b32_e32 v128, v27
	v_mov_b32_e32 v129, v11
	v_pk_mul_f32 v[128:129], v[128:129], v[128:129]
	v_add_u32_e32 v130, s74, v152
	v_add_f32_e32 v128, v128, v129
	v_cvt_pk_bf16_f32 v133, v73, s0
	v_cvt_pk_bf16_f32 v134, v72, s0
	v_mov_b32_e32 v72, v11
	v_mov_b32_e32 v73, v27
	s_waitcnt lgkmcnt(0)
	v_add_f32_dpp v128, v128, v128 quad_perm:[1,0,3,2] row_mask:0xf bank_mask:0xf
	s_and_b64 vcc, exec, s[0:1]
	v_add_f32_dpp v128, v128, v128 quad_perm:[2,3,0,1] row_mask:0xf bank_mask:0xf
	s_nop 0
	v_add_f32_dpp v129, v128, v128 row_half_mirror row_mask:0xf bank_mask:0xf
	v_add_u32_e32 v128, v130, v81
	v_add_u32_e32 v130, v130, v82
	v_add_f32_dpp v132, v129, v129 row_mirror row_mask:0xf bank_mask:0xf
	v_mov_b32_e32 v135, v132
	s_nop 1
	v_permlane16_swap_b32_e32 v132, v135
	s_nop 0
	v_ashrrev_i32_e32 v129, 31, v128
	v_ashrrev_i32_e32 v131, 31, v130
	v_lshl_add_u64 v[128:129], v[128:129], 1, s[6:7]
	v_lshl_add_u64 v[130:131], v[130:131], 1, s[6:7]
	v_add_f32_e32 v132, v132, v135
	v_fmamk_f32 v132, v132, 0x3c800000, v119
	v_rsq_f32_e32 v132, v132
	global_store_short v[128:129], v133, off sc1
	global_store_short v[130:131], v134, off sc1
	v_pk_mul_f32 v[128:129], v[70:71], v[132:133] op_sel_hi:[1,0]
	s_nop 0
	v_pk_mul_f32 v[72:73], v[72:73], v[128:129]
	s_cbranch_vccnz .LBB0_633
	global_load_dwordx2 v[128:129], v149, s[8:9]
	s_waitcnt vmcnt(0)
	v_pk_mul_f32 v[132:133], v[72:73], v[128:129] op_sel_hi:[0,1]
	v_pk_mul_f32 v[130:131], v[72:73], v[128:129] op_sel:[1,1] op_sel_hi:[1,0]
	v_pk_fma_f32 v[72:73], v[72:73], v[128:129], v[132:133] op_sel:[1,1,0] op_sel_hi:[1,0,1] neg_lo:[0,0,1] neg_hi:[0,0,1]
	s_nop 0
	v_add_f32_e32 v72, v130, v132
.LBB0_633:
	v_mov_b32_e32 v128, v28
	v_mov_b32_e32 v129, v12
	v_pk_mul_f32 v[128:129], v[128:129], v[128:129]
	v_add_u32_e32 v130, s74, v154
	v_add_f32_e32 v128, v128, v129
	v_cvt_pk_bf16_f32 v133, v73, s0
	v_cvt_pk_bf16_f32 v134, v72, s0
	v_mov_b32_e32 v72, v12
	v_mov_b32_e32 v73, v28
	s_waitcnt lgkmcnt(0)
	v_add_f32_dpp v128, v128, v128 quad_perm:[1,0,3,2] row_mask:0xf bank_mask:0xf
	s_and_b64 vcc, exec, s[0:1]
	v_add_f32_dpp v128, v128, v128 quad_perm:[2,3,0,1] row_mask:0xf bank_mask:0xf
	s_nop 0
	v_add_f32_dpp v129, v128, v128 row_half_mirror row_mask:0xf bank_mask:0xf
	v_add_u32_e32 v128, v130, v81
	v_add_u32_e32 v130, v130, v82
	v_add_f32_dpp v132, v129, v129 row_mirror row_mask:0xf bank_mask:0xf
	v_mov_b32_e32 v135, v132
	s_nop 1
	v_permlane16_swap_b32_e32 v132, v135
	s_nop 0
	v_ashrrev_i32_e32 v129, 31, v128
	v_ashrrev_i32_e32 v131, 31, v130
	v_lshl_add_u64 v[128:129], v[128:129], 1, s[6:7]
	v_lshl_add_u64 v[130:131], v[130:131], 1, s[6:7]
	v_add_f32_e32 v132, v132, v135
	v_fmamk_f32 v132, v132, 0x3c800000, v119
	v_rsq_f32_e32 v132, v132
	global_store_short v[128:129], v133, off sc1
	global_store_short v[130:131], v134, off sc1
	v_pk_mul_f32 v[128:129], v[70:71], v[132:133] op_sel_hi:[1,0]
	s_nop 0
	v_pk_mul_f32 v[72:73], v[72:73], v[128:129]
	s_cbranch_vccnz .LBB0_635
	global_load_dwordx2 v[128:129], v151, s[8:9]
	s_waitcnt vmcnt(0)
	v_pk_mul_f32 v[132:133], v[72:73], v[128:129] op_sel_hi:[0,1]
	v_pk_mul_f32 v[130:131], v[72:73], v[128:129] op_sel:[1,1] op_sel_hi:[1,0]
	v_pk_fma_f32 v[72:73], v[72:73], v[128:129], v[132:133] op_sel:[1,1,0] op_sel_hi:[1,0,1] neg_lo:[0,0,1] neg_hi:[0,0,1]
	s_nop 0
	v_add_f32_e32 v72, v130, v132
.LBB0_635:
	v_mov_b32_e32 v128, v29
	v_mov_b32_e32 v129, v13
	v_pk_mul_f32 v[128:129], v[128:129], v[128:129]
	v_add_u32_e32 v130, s74, v156
	v_add_f32_e32 v128, v128, v129
	v_cvt_pk_bf16_f32 v133, v73, s0
	v_cvt_pk_bf16_f32 v134, v72, s0
	v_mov_b32_e32 v72, v13
	v_mov_b32_e32 v73, v29
	s_waitcnt lgkmcnt(0)
	v_add_f32_dpp v128, v128, v128 quad_perm:[1,0,3,2] row_mask:0xf bank_mask:0xf
	s_and_b64 vcc, exec, s[0:1]
	v_add_f32_dpp v128, v128, v128 quad_perm:[2,3,0,1] row_mask:0xf bank_mask:0xf
	s_nop 0
	v_add_f32_dpp v129, v128, v128 row_half_mirror row_mask:0xf bank_mask:0xf
	v_add_u32_e32 v128, v130, v81
	v_add_u32_e32 v130, v130, v82
	v_add_f32_dpp v132, v129, v129 row_mirror row_mask:0xf bank_mask:0xf
	v_mov_b32_e32 v135, v132
	s_nop 1
	v_permlane16_swap_b32_e32 v132, v135
	s_nop 0
	v_ashrrev_i32_e32 v129, 31, v128
	v_ashrrev_i32_e32 v131, 31, v130
	v_lshl_add_u64 v[128:129], v[128:129], 1, s[6:7]
	v_lshl_add_u64 v[130:131], v[130:131], 1, s[6:7]
	v_add_f32_e32 v132, v132, v135
	v_fmamk_f32 v132, v132, 0x3c800000, v119
	v_rsq_f32_e32 v132, v132
	global_store_short v[128:129], v133, off sc1
	global_store_short v[130:131], v134, off sc1
	v_pk_mul_f32 v[128:129], v[70:71], v[132:133] op_sel_hi:[1,0]
	s_nop 0
	v_pk_mul_f32 v[72:73], v[72:73], v[128:129]
	s_cbranch_vccnz .LBB0_637
	global_load_dwordx2 v[128:129], v153, s[8:9]
	s_waitcnt vmcnt(0)
	v_pk_mul_f32 v[132:133], v[72:73], v[128:129] op_sel_hi:[0,1]
	v_pk_mul_f32 v[130:131], v[72:73], v[128:129] op_sel:[1,1] op_sel_hi:[1,0]
	v_pk_fma_f32 v[72:73], v[72:73], v[128:129], v[132:133] op_sel:[1,1,0] op_sel_hi:[1,0,1] neg_lo:[0,0,1] neg_hi:[0,0,1]
	s_nop 0
	v_add_f32_e32 v72, v130, v132
.LBB0_637:
	v_mov_b32_e32 v128, v30
	v_mov_b32_e32 v129, v14
	v_pk_mul_f32 v[128:129], v[128:129], v[128:129]
	v_add_u32_e32 v130, s74, v157
	v_add_f32_e32 v128, v128, v129
	v_cvt_pk_bf16_f32 v133, v73, s0
	v_cvt_pk_bf16_f32 v134, v72, s0
	v_mov_b32_e32 v72, v14
	v_mov_b32_e32 v73, v30
	s_waitcnt lgkmcnt(0)
	v_add_f32_dpp v128, v128, v128 quad_perm:[1,0,3,2] row_mask:0xf bank_mask:0xf
	s_and_b64 vcc, exec, s[0:1]
	v_add_f32_dpp v128, v128, v128 quad_perm:[2,3,0,1] row_mask:0xf bank_mask:0xf
	s_nop 0
	v_add_f32_dpp v129, v128, v128 row_half_mirror row_mask:0xf bank_mask:0xf
	v_add_u32_e32 v128, v130, v81
	v_add_u32_e32 v130, v130, v82
	v_add_f32_dpp v132, v129, v129 row_mirror row_mask:0xf bank_mask:0xf
	v_mov_b32_e32 v135, v132
	s_nop 1
	v_permlane16_swap_b32_e32 v132, v135
	s_nop 0
	v_ashrrev_i32_e32 v129, 31, v128
	v_ashrrev_i32_e32 v131, 31, v130
	v_lshl_add_u64 v[128:129], v[128:129], 1, s[6:7]
	v_lshl_add_u64 v[130:131], v[130:131], 1, s[6:7]
	v_add_f32_e32 v132, v132, v135
	v_fmamk_f32 v132, v132, 0x3c800000, v119
	v_rsq_f32_e32 v132, v132
	global_store_short v[128:129], v133, off sc1
	global_store_short v[130:131], v134, off sc1
	v_pk_mul_f32 v[128:129], v[70:71], v[132:133] op_sel_hi:[1,0]
	s_nop 0
	v_pk_mul_f32 v[72:73], v[72:73], v[128:129]
	s_cbranch_vccnz .LBB0_639
	global_load_dwordx2 v[128:129], v155, s[8:9]
	s_waitcnt vmcnt(0)
	v_pk_mul_f32 v[132:133], v[72:73], v[128:129] op_sel_hi:[0,1]
	v_pk_mul_f32 v[130:131], v[72:73], v[128:129] op_sel:[1,1] op_sel_hi:[1,0]
	v_pk_fma_f32 v[72:73], v[72:73], v[128:129], v[132:133] op_sel:[1,1,0] op_sel_hi:[1,0,1] neg_lo:[0,0,1] neg_hi:[0,0,1]
	s_nop 0
	v_add_f32_e32 v72, v130, v132
.LBB0_639:
	v_mov_b32_e32 v128, v31
	v_mov_b32_e32 v129, v15
	v_pk_mul_f32 v[128:129], v[128:129], v[128:129]
	v_cvt_pk_bf16_f32 v130, v72, s0
	v_add_f32_e32 v128, v128, v129
	v_cvt_pk_bf16_f32 v129, v73, s0
	v_mov_b32_e32 v72, v15
	v_mov_b32_e32 v73, v31
	s_and_b64 vcc, exec, s[0:1]
	s_waitcnt lgkmcnt(0)
	v_add_f32_dpp v123, v128, v128 quad_perm:[1,0,3,2] row_mask:0xf bank_mask:0xf
	s_nop 0
	v_add_f32_dpp v123, v123, v123 quad_perm:[2,3,0,1] row_mask:0xf bank_mask:0xf
	v_add_u32_e32 v125, s74, v158
	v_add_f32_dpp v123, v123, v123 row_half_mirror row_mask:0xf bank_mask:0xf
	v_add_u32_e32 v124, v125, v81
	v_add_f32_dpp v123, v123, v123 row_mirror row_mask:0xf bank_mask:0xf
	v_mov_b32_e32 v128, v123
	s_nop 1
	v_permlane16_swap_b32_e32 v123, v128
	s_nop 0
	v_add_u32_e32 v126, v125, v82
	v_ashrrev_i32_e32 v125, 31, v124
	v_ashrrev_i32_e32 v127, 31, v126
	v_lshl_add_u64 v[124:125], v[124:125], 1, s[6:7]
	v_add_f32_e32 v123, v123, v128
	v_fmamk_f32 v123, v123, 0x3c800000, v119
	v_rsq_f32_e32 v128, v123
	v_lshl_add_u64 v[126:127], v[126:127], 1, s[6:7]
	global_store_short v[124:125], v129, off sc1
	global_store_short v[126:127], v130, off sc1
	v_pk_mul_f32 v[70:71], v[70:71], v[128:129] op_sel_hi:[1,0]
	s_nop 0
	v_pk_mul_f32 v[70:71], v[72:73], v[70:71]
	s_cbranch_vccnz .LBB0_641
	global_load_dwordx2 v[72:73], v142, s[8:9]
	s_waitcnt vmcnt(0)
	v_pk_mul_f32 v[126:127], v[70:71], v[72:73] op_sel_hi:[0,1]
	v_pk_mul_f32 v[124:125], v[70:71], v[72:73] op_sel:[1,1] op_sel_hi:[1,0]
	v_pk_fma_f32 v[70:71], v[70:71], v[72:73], v[126:127] op_sel:[1,1,0] op_sel_hi:[1,0,1] neg_lo:[0,0,1] neg_hi:[0,0,1]
	s_nop 0
	v_add_f32_e32 v70, v124, v126

.LBB0_642:
	s_and_b64 vcc, exec, s[0:1]
	s_cbranch_vccz .LBB0_575
	v_and_b32_e32 v71, 64, v122
	v_xor_b32_e32 v70, 1, v122
	v_add_u32_e32 v71, 64, v71
	v_mul_f32_e32 v72, v32, v32
	v_cmp_lt_i32_e32 vcc, v70, v71
	v_fmac_f32_e32 v72, v48, v48
	v_fmac_f32_e32 v72, v16, v16
	v_cndmask_b32_e32 v70, v122, v70, vcc
	v_lshlrev_b32_e32 v132, 2, v70
	v_fmac_f32_e32 v72, v0, v0
	v_xor_b32_e32 v70, 2, v122
	v_cmp_lt_i32_e32 vcc, v70, v71
	v_mul_f32_e32 v123, v33, v33
	v_fmac_f32_e32 v123, v49, v49
	v_cndmask_b32_e32 v70, v122, v70, vcc
	v_lshlrev_b32_e32 v133, 2, v70
	s_waitcnt lgkmcnt(0)
	v_add_f32_dpp v72, v72, v72 quad_perm:[1,0,3,2] row_mask:0xf bank_mask:0xf
	v_xor_b32_e32 v70, 4, v122
	v_cmp_lt_i32_e32 vcc, v70, v71
	v_fmac_f32_e32 v123, v17, v17
	v_fmac_f32_e32 v123, v1, v1
	v_cndmask_b32_e32 v70, v122, v70, vcc
	v_lshlrev_b32_e32 v135, 2, v70
	v_xor_b32_e32 v70, 8, v122
	v_cmp_lt_i32_e32 vcc, v70, v71
	v_add_f32_dpp v72, v72, v72 quad_perm:[2,3,0,1] row_mask:0xf bank_mask:0xf
	v_cndmask_b32_e32 v70, v122, v70, vcc
	v_lshlrev_b32_e32 v136, 2, v70
	v_xor_b32_e32 v70, 16, v122
	v_cmp_lt_i32_e32 vcc, v70, v71
	v_mul_f32_e32 v128, v40, v40
	v_fmac_f32_e32 v128, v56, v56
	v_cndmask_b32_e32 v70, v122, v70, vcc
	v_mul_f32_e32 v122, v34, v34
	v_fmac_f32_e32 v122, v50, v50
	v_fmac_f32_e32 v122, v18, v18
	v_lshlrev_b32_e32 v137, 2, v70
	v_add_f32_dpp v70, v72, v72 row_half_mirror row_mask:0xf bank_mask:0xf
	v_add_f32_dpp v72, v123, v123 quad_perm:[1,0,3,2] row_mask:0xf bank_mask:0xf
	v_fmac_f32_e32 v122, v2, v2
	v_fmac_f32_e32 v128, v24, v24
	v_fmac_f32_e32 v128, v8, v8
	v_add_f32_dpp v70, v70, v70 row_mirror row_mask:0xf bank_mask:0xf
	v_add_f32_dpp v72, v72, v72 quad_perm:[2,3,0,1] row_mask:0xf bank_mask:0xf
	v_add_f32_dpp v122, v122, v122 quad_perm:[1,0,3,2] row_mask:0xf bank_mask:0xf
	v_mov_b32_e32 v71, v70
	s_nop 1
	v_permlane16_swap_b32_e32 v70, v71
	s_nop 0
	s_nop 1
	v_mov_b32_dpp v129, v128 quad_perm:[1,0,3,2] row_mask:0xf bank_mask:0xf
	v_mul_f32_e32 v141, v46, v46
	v_add_f32_e32 v70, v70, v71
	v_add_f32_dpp v71, v72, v72 row_half_mirror row_mask:0xf bank_mask:0xf
	v_add_f32_dpp v73, v122, v122 quad_perm:[2,3,0,1] row_mask:0xf bank_mask:0xf
	v_mul_f32_e32 v123, v35, v35
	v_fmac_f32_e32 v123, v51, v51
	v_fmac_f32_e32 v123, v19, v19
	v_fmac_f32_e32 v123, v3, v3
	v_fmamk_f32 v70, v70, 0x3c000000, v119
	v_add_f32_e32 v128, v128, v129
	v_add_f32_dpp v72, v71, v71 row_mirror row_mask:0xf bank_mask:0xf
	v_add_f32_dpp v73, v73, v73 row_half_mirror row_mask:0xf bank_mask:0xf
	v_add_f32_dpp v123, v123, v123 quad_perm:[1,0,3,2] row_mask:0xf bank_mask:0xf
	v_mov_b32_e32 v125, v72
	s_nop 1
	v_permlane16_swap_b32_e32 v72, v125
	s_nop 0
	v_rsq_f32_e32 v71, v70
	s_nop 1
	v_mov_b32_dpp v129, v128 quad_perm:[2,3,0,1] row_mask:0xf bank_mask:0xf
	v_add_f32_e32 v70, v72, v125
	v_add_f32_dpp v72, v73, v73 row_mirror row_mask:0xf bank_mask:0xf
	v_add_f32_dpp v122, v123, v123 quad_perm:[2,3,0,1] row_mask:0xf bank_mask:0xf
	v_mov_b32_e32 v73, v72
	s_nop 1
	v_permlane16_swap_b32_e32 v72, v73
	s_nop 0
	v_mul_f32_e32 v125, v37, v37
	v_fmac_f32_e32 v125, v53, v53
	v_fmac_f32_e32 v125, v21, v21
	v_add_f32_e32 v72, v72, v73
	v_add_f32_dpp v73, v122, v122 row_half_mirror row_mask:0xf bank_mask:0xf
	v_mul_f32_e32 v123, v36, v36
	v_fmac_f32_e32 v123, v52, v52
	v_fmac_f32_e32 v123, v20, v20
	v_fmac_f32_e32 v123, v4, v4
	v_fmac_f32_e32 v125, v5, v5
	v_fmamk_f32 v72, v72, 0x3c000000, v119
	v_mul_f32_e32 v143, v47, v47
	v_add_f32_dpp v122, v73, v73 row_mirror row_mask:0xf bank_mask:0xf
	v_add_f32_dpp v123, v123, v123 quad_perm:[1,0,3,2] row_mask:0xf bank_mask:0xf
	v_add_f32_dpp v125, v125, v125 quad_perm:[1,0,3,2] row_mask:0xf bank_mask:0xf
	v_mov_b32_e32 v127, v122
	s_nop 1
	v_permlane16_swap_b32_e32 v122, v127
	s_nop 0
	v_rsq_f32_e32 v73, v72
	v_fmac_f32_e32 v141, v62, v62
	v_add_f32_e32 v72, v122, v127
	v_add_f32_dpp v122, v123, v123 quad_perm:[2,3,0,1] row_mask:0xf bank_mask:0xf
	v_add_f32_dpp v124, v125, v125 quad_perm:[2,3,0,1] row_mask:0xf bank_mask:0xf
	v_mul_f32_e32 v126, v38, v38
	v_fmac_f32_e32 v126, v54, v54
	v_fmac_f32_e32 v126, v22, v22
	v_add_f32_dpp v122, v122, v122 row_half_mirror row_mask:0xf bank_mask:0xf
	v_add_f32_dpp v124, v124, v124 row_half_mirror row_mask:0xf bank_mask:0xf
	v_fmac_f32_e32 v126, v6, v6
	v_fmac_f32_e32 v143, v63, v63
	v_fmac_f32_e32 v141, v30, v30
	v_add_f32_dpp v122, v122, v122 row_mirror row_mask:0xf bank_mask:0xf
	v_add_f32_dpp v124, v124, v124 row_mirror row_mask:0xf bank_mask:0xf
	v_add_f32_dpp v126, v126, v126 quad_perm:[1,0,3,2] row_mask:0xf bank_mask:0xf
	v_mov_b32_e32 v123, v122
	s_nop 1
	v_permlane16_swap_b32_e32 v122, v123
	s_nop 0
	v_mov_b32_e32 v125, v124
	s_nop 1
	v_permlane16_swap_b32_e32 v124, v125
	s_nop 0
	v_fmac_f32_e32 v141, v14, v14
	s_nop 1
	v_mov_b32_dpp v142, v141 quad_perm:[1,0,3,2] row_mask:0xf bank_mask:0xf
	v_add_f32_e32 v122, v122, v123
	v_add_f32_e32 v123, v124, v125
	v_add_f32_dpp v124, v126, v126 quad_perm:[2,3,0,1] row_mask:0xf bank_mask:0xf
	v_mul_f32_e32 v126, v39, v39
	v_fmac_f32_e32 v126, v55, v55
	v_fmac_f32_e32 v126, v23, v23
	v_fmac_f32_e32 v126, v7, v7
	s_mulk_i32 s72, 0xc0
	v_fmamk_f32 v70, v70, 0x3c000000, v119
	v_rsq_f32_e32 v70, v70
	v_add_f32_dpp v124, v124, v124 row_half_mirror row_mask:0xf bank_mask:0xf
	v_add_f32_dpp v126, v126, v126 quad_perm:[1,0,3,2] row_mask:0xf bank_mask:0xf
	v_mul_f32_e32 v49, v49, v70
	v_fmamk_f32 v72, v72, 0x3c000000, v119
	v_rsq_f32_e32 v72, v72
	v_add_f32_dpp v124, v124, v124 row_mirror row_mask:0xf bank_mask:0xf
	v_add_f32_dpp v126, v126, v126 quad_perm:[2,3,0,1] row_mask:0xf bank_mask:0xf
	v_mov_b32_e32 v125, v124
	s_nop 1
	v_permlane16_swap_b32_e32 v124, v125
	s_nop 0
	v_fmamk_f32 v122, v122, 0x3c000000, v119
	v_rsq_f32_e32 v122, v122
	v_fmamk_f32 v123, v123, 0x3c000000, v119
	v_add_f32_e32 v124, v124, v125
	v_add_f32_dpp v125, v126, v126 row_half_mirror row_mask:0xf bank_mask:0xf
	v_add_f32_e32 v127, v128, v129
	v_mul_f32_e32 v129, v41, v41
	v_fmac_f32_e32 v129, v57, v57
	v_fmac_f32_e32 v129, v25, v25
	v_fmac_f32_e32 v129, v9, v9
	v_rsq_f32_e32 v123, v123
	v_fmamk_f32 v124, v124, 0x3c000000, v119
	v_add_f32_dpp v125, v125, v125 row_mirror row_mask:0xf bank_mask:0xf
	v_add_f32_dpp v129, v129, v129 quad_perm:[1,0,3,2] row_mask:0xf bank_mask:0xf
	v_mov_b32_e32 v126, v125
	s_nop 1
	v_permlane16_swap_b32_e32 v125, v126
	s_nop 0
	v_add_f32_dpp v127, v127, v127 row_half_mirror row_mask:0xf bank_mask:0xf
	v_rsq_f32_e32 v124, v124
	v_add_f32_e32 v125, v125, v126
	v_fmamk_f32 v125, v125, 0x3c000000, v119
	v_add_f32_dpp v126, v129, v129 quad_perm:[2,3,0,1] row_mask:0xf bank_mask:0xf
	v_add_f32_dpp v127, v127, v127 row_mirror row_mask:0xf bank_mask:0xf
	v_mul_f32_e32 v129, v42, v42
	v_fmac_f32_e32 v129, v58, v58
	v_fmac_f32_e32 v129, v26, v26
	v_fmac_f32_e32 v129, v10, v10
	v_add_f32_dpp v128, v126, v126 row_half_mirror row_mask:0xf bank_mask:0xf
	v_rsq_f32_e32 v126, v125
	v_mov_b32_e32 v131, v127
	s_nop 1
	v_permlane16_swap_b32_e32 v127, v131
	s_nop 0
	v_mul_f32_e32 v32, v32, v71
	v_add_f32_dpp v125, v129, v129 quad_perm:[1,0,3,2] row_mask:0xf bank_mask:0xf
	v_add_f32_dpp v128, v128, v128 row_mirror row_mask:0xf bank_mask:0xf
	v_mul_f32_e32 v134, v44, v44
	v_fmac_f32_e32 v134, v60, v60
	v_fmac_f32_e32 v134, v28, v28
	v_fmac_f32_e32 v134, v12, v12
	v_mov_b32_e32 v130, v128
	s_nop 1
	v_permlane16_swap_b32_e32 v128, v130
	s_nop 0
	v_add_f32_dpp v129, v125, v125 quad_perm:[2,3,0,1] row_mask:0xf bank_mask:0xf
	v_add_f32_e32 v127, v127, v131
	v_add_f32_e32 v125, v128, v130
	v_mul_f32_e32 v130, v43, v43
	v_add_f32_dpp v138, v134, v134 quad_perm:[1,0,3,2] row_mask:0xf bank_mask:0xf
	global_load_dword v134, v121, s[66:67]
	v_fmac_f32_e32 v130, v59, v59
	v_fmac_f32_e32 v130, v27, v27
	v_add_f32_dpp v128, v129, v129 row_half_mirror row_mask:0xf bank_mask:0xf
	v_fmac_f32_e32 v130, v11, v11
	s_nop 1
	v_mov_b32_dpp v139, v138 quad_perm:[2,3,0,1] row_mask:0xf bank_mask:0xf
	v_fmamk_f32 v127, v127, 0x3c000000, v119
	v_rsq_f32_e32 v127, v127
	v_add_f32_dpp v128, v128, v128 row_mirror row_mask:0xf bank_mask:0xf
	v_add_f32_dpp v130, v130, v130 quad_perm:[1,0,3,2] row_mask:0xf bank_mask:0xf
	v_mov_b32_e32 v129, v128
	s_nop 1
	v_permlane16_swap_b32_e32 v128, v129
	s_nop 0
	v_fmamk_f32 v125, v125, 0x3c000000, v119
	v_rsq_f32_e32 v125, v125
	v_mul_f32_e32 v16, v16, v71
	v_add_f32_e32 v128, v128, v129
	v_add_f32_dpp v129, v130, v130 quad_perm:[2,3,0,1] row_mask:0xf bank_mask:0xf
	v_add_f32_e32 v131, v138, v139
	v_mul_f32_e32 v139, v45, v45
	v_fmac_f32_e32 v139, v61, v61
	v_fmac_f32_e32 v139, v29, v29
	v_add_f32_dpp v129, v129, v129 row_half_mirror row_mask:0xf bank_mask:0xf
	v_add_f32_dpp v131, v131, v131 row_half_mirror row_mask:0xf bank_mask:0xf
	v_fmac_f32_e32 v139, v13, v13
	v_fmamk_f32 v128, v128, 0x3c000000, v119
	v_add_f32_dpp v129, v129, v129 row_mirror row_mask:0xf bank_mask:0xf
	v_add_f32_dpp v131, v131, v131 row_mirror row_mask:0xf bank_mask:0xf
	v_mov_b32_e32 v130, v129
	s_nop 1
	v_permlane16_swap_b32_e32 v129, v130
	s_nop 0
	v_mov_b32_e32 v138, v131
	s_nop 1
	v_permlane16_swap_b32_e32 v131, v138
	s_nop 0
	v_add_f32_dpp v139, v139, v139 quad_perm:[1,0,3,2] row_mask:0xf bank_mask:0xf
	v_rsq_f32_e32 v128, v128
	v_add_f32_e32 v129, v129, v130
	v_add_f32_e32 v138, v131, v138
	v_mov_b32_e32 v130, v31
	v_mov_b32_e32 v131, v15
	v_pk_mul_f32 v[130:131], v[130:131], v[130:131]
	v_add_f32_dpp v139, v139, v139 quad_perm:[2,3,0,1] row_mask:0xf bank_mask:0xf
	v_add_f32_e32 v130, v143, v130
	v_add_f32_e32 v130, v130, v131
	v_fmamk_f32 v129, v129, 0x3c000000, v119
	v_rsq_f32_e32 v129, v129
	v_mul_f32_e32 v0, v0, v71
	v_add_f32_dpp v132, v139, v139 row_half_mirror row_mask:0xf bank_mask:0xf
	v_add_f32_e32 v139, v141, v142
	v_add_f32_dpp v130, v130, v130 quad_perm:[1,0,3,2] row_mask:0xf bank_mask:0xf
	v_fmamk_f32 v133, v138, 0x3c000000, v119
	v_add_f32_dpp v138, v139, v139 quad_perm:[2,3,0,1] row_mask:0xf bank_mask:0xf
	v_add_f32_dpp v130, v130, v130 quad_perm:[2,3,0,1] row_mask:0xf bank_mask:0xf
	v_add_f32_dpp v140, v132, v132 row_mirror row_mask:0xf bank_mask:0xf
	v_mov_b32_e32 v135, v140
	s_nop 1
	v_permlane16_swap_b32_e32 v140, v135
	s_nop 0
	v_rsq_f32_e32 v132, v133
	v_add_f32_dpp v138, v138, v138 row_half_mirror row_mask:0xf bank_mask:0xf
	v_add_f32_dpp v130, v130, v130 row_half_mirror row_mask:0xf bank_mask:0xf
	v_add_f32_e32 v133, v140, v135
	v_fmamk_f32 v133, v133, 0x3c000000, v119
	v_rsq_f32_e32 v133, v133
	v_add_f32_dpp v135, v138, v138 row_mirror row_mask:0xf bank_mask:0xf
	v_add_f32_dpp v130, v130, v130 row_mirror row_mask:0xf bank_mask:0xf
	v_mov_b32_e32 v136, v135
	s_nop 1
	v_permlane16_swap_b32_e32 v135, v136
	s_nop 0
	v_mov_b32_e32 v137, v130
	s_nop 1
	v_permlane16_swap_b32_e32 v130, v137
	s_nop 0
	s_waitcnt vmcnt(0)
	v_mul_f32_e32 v49, v49, v134
	v_add_f32_e32 v131, v135, v136
	v_add_f32_e32 v130, v130, v137
	v_mul_f32_e32 v137, v48, v71
	global_load_dword v48, v121, s[66:67] offset:128
	global_load_dword v138, v121, s[66:67] offset:256
	s_nop 0
	global_load_dword v121, v121, s[66:67] offset:384
	v_add_u32_e32 v136, s73, v80
	v_or_b32_e32 v135, s72, v64
	v_mul_lo_u32 v140, v136, s70
	v_mul_f32_e32 v137, v137, v134
	v_add_u32_e32 v136, v140, v135
	v_cvt_pk_bf16_f32 v139, v137, s0
	v_ashrrev_i32_e32 v137, 31, v136
	v_lshl_add_u64 v[136:137], v[136:137], 1, s[6:7]
	global_store_short v[136:137], v139, off sc1
	v_or_b32_e32 v139, 0x600, v140
	v_add_u32_e32 v136, v139, v135
	v_ashrrev_i32_e32 v137, 31, v136
	v_cvt_pk_bf16_f32 v49, v49, s0
	v_lshl_add_u64 v[136:137], v[136:137], 1, s[6:7]
	v_add_u32_e32 v141, 0xc00, v140
	global_store_short v[136:137], v49, off sc1
	v_mul_f32_e32 v49, v50, v73
	v_add_u32_e32 v136, v141, v135
	v_mul_f32_e32 v49, v49, v134
	v_ashrrev_i32_e32 v137, 31, v136
	v_cvt_pk_bf16_f32 v49, v49, s0
	v_lshl_add_u64 v[136:137], v[136:137], 1, s[6:7]
	global_store_short v[136:137], v49, off sc1
	v_add_u32_e32 v136, 0x1200, v140
	v_mul_f32_e32 v49, v51, v72
	v_add_u32_e32 v50, v136, v135
	v_mul_f32_e32 v49, v49, v134
	v_ashrrev_i32_e32 v51, 31, v50
	v_cvt_pk_bf16_f32 v49, v49, s0
	v_lshl_add_u64 v[50:51], v[50:51], 1, s[6:7]
	global_store_short v[50:51], v49, off sc1
	v_mul_f32_e32 v49, v52, v122
	v_add_u32_e32 v52, 0x3000, v140
	v_add_u32_e32 v50, v52, v135
	v_mul_f32_e32 v49, v49, v134
	v_ashrrev_i32_e32 v51, 31, v50
	v_cvt_pk_bf16_f32 v49, v49, s0
	v_lshl_add_u64 v[50:51], v[50:51], 1, s[6:7]
	global_store_short v[50:51], v49, off sc1
	v_mul_f32_e32 v49, v53, v123
	v_add_u32_e32 v53, 0x3600, v140
	v_add_u32_e32 v50, v53, v135
	v_mul_f32_e32 v49, v49, v134
	v_ashrrev_i32_e32 v51, 31, v50
	v_cvt_pk_bf16_f32 v49, v49, s0
	v_lshl_add_u64 v[50:51], v[50:51], 1, s[6:7]
	global_store_short v[50:51], v49, off sc1
	v_mul_f32_e32 v49, v54, v124
	v_add_u32_e32 v54, 0x3c00, v140
	v_add_u32_e32 v50, v54, v135
	v_mul_f32_e32 v49, v49, v134
	v_ashrrev_i32_e32 v51, 31, v50
	v_cvt_pk_bf16_f32 v49, v49, s0
	v_lshl_add_u64 v[50:51], v[50:51], 1, s[6:7]
	global_store_short v[50:51], v49, off sc1
	v_mul_f32_e32 v49, v55, v126
	v_add_u32_e32 v55, 0x4200, v140
	v_add_u32_e32 v50, v55, v135
	v_mul_f32_e32 v49, v49, v134
	v_ashrrev_i32_e32 v51, 31, v50
	v_cvt_pk_bf16_f32 v49, v49, s0
	v_lshl_add_u64 v[50:51], v[50:51], 1, s[6:7]
	global_store_short v[50:51], v49, off sc1
	v_mul_f32_e32 v49, v56, v127
	v_add_u32_e32 v56, 0x6000, v140
	v_add_u32_e32 v50, v56, v135
	v_mul_f32_e32 v49, v49, v134
	v_ashrrev_i32_e32 v51, 31, v50
	v_cvt_pk_bf16_f32 v49, v49, s0
	v_lshl_add_u64 v[50:51], v[50:51], 1, s[6:7]
	global_store_short v[50:51], v49, off sc1
	v_mul_f32_e32 v49, v57, v125
	v_add_u32_e32 v57, 0x6600, v140
	v_add_u32_e32 v50, v57, v135
	v_mul_f32_e32 v49, v49, v134
	v_ashrrev_i32_e32 v51, 31, v50
	v_cvt_pk_bf16_f32 v49, v49, s0
	v_lshl_add_u64 v[50:51], v[50:51], 1, s[6:7]
	global_store_short v[50:51], v49, off sc1
	v_mul_f32_e32 v49, v58, v128
	v_add_u32_e32 v58, 0x6c00, v140
	v_add_u32_e32 v50, v58, v135
	v_mul_f32_e32 v49, v49, v134
	v_ashrrev_i32_e32 v51, 31, v50
	v_cvt_pk_bf16_f32 v49, v49, s0
	v_lshl_add_u64 v[50:51], v[50:51], 1, s[6:7]
	global_store_short v[50:51], v49, off sc1
	v_mul_f32_e32 v49, v59, v129
	v_add_u32_e32 v59, 0x7200, v140
	v_add_u32_e32 v50, v59, v135
	v_mul_f32_e32 v49, v49, v134
	v_ashrrev_i32_e32 v51, 31, v50
	v_cvt_pk_bf16_f32 v49, v49, s0
	v_lshl_add_u64 v[50:51], v[50:51], 1, s[6:7]
	global_store_short v[50:51], v49, off sc1
	v_mul_f32_e32 v49, v60, v132
	v_add_u32_e32 v60, 0x9000, v140
	v_add_u32_e32 v50, v60, v135
	v_mul_f32_e32 v49, v49, v134
	v_ashrrev_i32_e32 v51, 31, v50
	v_fmamk_f32 v131, v131, 0x3c000000, v119
	v_cvt_pk_bf16_f32 v49, v49, s0
	v_lshl_add_u64 v[50:51], v[50:51], 1, s[6:7]
	v_rsq_f32_e32 v131, v131
	global_store_short v[50:51], v49, off sc1
	v_mul_f32_e32 v49, v61, v133
	v_add_u32_e32 v61, 0x9600, v140
	v_add_u32_e32 v50, v61, v135
	v_mul_f32_e32 v49, v49, v134
	v_ashrrev_i32_e32 v51, 31, v50
	v_fmamk_f32 v130, v130, 0x3c000000, v119
	v_cvt_pk_bf16_f32 v49, v49, s0
	v_lshl_add_u64 v[50:51], v[50:51], 1, s[6:7]
	v_rsq_f32_e32 v130, v130
	global_store_short v[50:51], v49, off sc1
	v_mul_f32_e32 v49, v62, v131
	v_add_u32_e32 v62, 0x9c00, v140
	v_add_u32_e32 v50, v62, v135
	v_mul_f32_e32 v49, v134, v49
	v_ashrrev_i32_e32 v51, 31, v50
	v_cvt_pk_bf16_f32 v49, v49, s0
	v_lshl_add_u64 v[50:51], v[50:51], 1, s[6:7]
	global_store_short v[50:51], v49, off sc1
	v_mul_f32_e32 v49, v63, v130
	v_add_u32_e32 v63, 0xa200, v140
	v_add_u32_e32 v50, v63, v135
	v_mul_f32_e32 v49, v134, v49
	v_ashrrev_i32_e32 v51, 31, v50
	v_cvt_pk_bf16_f32 v49, v49, s0
	v_lshl_add_u64 v[50:51], v[50:51], 1, s[6:7]
	global_store_short v[50:51], v49, off sc1
	v_or_b32_e32 v49, s72, v65
	v_add_u32_e32 v50, v140, v49
	s_waitcnt vmcnt(18)
	v_mul_f32_e32 v32, v32, v48
	v_ashrrev_i32_e32 v51, 31, v50
	v_cvt_pk_bf16_f32 v32, v32, s0
	v_lshl_add_u64 v[50:51], v[50:51], 1, s[6:7]
	global_store_short v[50:51], v32, off sc1
	v_mul_f32_e32 v32, v33, v70
	v_mul_f32_e32 v32, v32, v48
	v_cvt_pk_bf16_f32 v50, v32, s0
	v_add_u32_e32 v32, v139, v49
	v_ashrrev_i32_e32 v33, 31, v32
	v_lshl_add_u64 v[32:33], v[32:33], 1, s[6:7]
	global_store_short v[32:33], v50, off sc1
	v_mul_f32_e32 v32, v34, v73
	v_mul_f32_e32 v32, v32, v48
	v_cvt_pk_bf16_f32 v34, v32, s0
	v_add_u32_e32 v32, v141, v49
	v_ashrrev_i32_e32 v33, 31, v32
	v_lshl_add_u64 v[32:33], v[32:33], 1, s[6:7]
	global_store_short v[32:33], v34, off sc1
	v_mul_f32_e32 v32, v35, v72
	v_mul_f32_e32 v32, v32, v48
	v_cvt_pk_bf16_f32 v34, v32, s0
	v_add_u32_e32 v32, v136, v49
	v_ashrrev_i32_e32 v33, 31, v32
	v_lshl_add_u64 v[32:33], v[32:33], 1, s[6:7]
	global_store_short v[32:33], v34, off sc1
	v_mul_f32_e32 v32, v36, v122
	v_mul_f32_e32 v32, v32, v48
	v_cvt_pk_bf16_f32 v34, v32, s0
	v_add_u32_e32 v32, v52, v49
	v_ashrrev_i32_e32 v33, 31, v32
	v_lshl_add_u64 v[32:33], v[32:33], 1, s[6:7]
	global_store_short v[32:33], v34, off sc1
	v_mul_f32_e32 v32, v37, v123
	v_mul_f32_e32 v32, v32, v48
	v_cvt_pk_bf16_f32 v34, v32, s0
	v_add_u32_e32 v32, v53, v49
	v_ashrrev_i32_e32 v33, 31, v32
	v_lshl_add_u64 v[32:33], v[32:33], 1, s[6:7]
	global_store_short v[32:33], v34, off sc1
	v_mul_f32_e32 v32, v38, v124
	v_mul_f32_e32 v32, v32, v48
	v_cvt_pk_bf16_f32 v34, v32, s0
	v_add_u32_e32 v32, v54, v49
	v_ashrrev_i32_e32 v33, 31, v32
	v_lshl_add_u64 v[32:33], v[32:33], 1, s[6:7]
	global_store_short v[32:33], v34, off sc1
	v_mul_f32_e32 v32, v39, v126
	v_mul_f32_e32 v32, v32, v48
	v_cvt_pk_bf16_f32 v34, v32, s0
	v_add_u32_e32 v32, v55, v49
	v_ashrrev_i32_e32 v33, 31, v32
	v_lshl_add_u64 v[32:33], v[32:33], 1, s[6:7]
	global_store_short v[32:33], v34, off sc1
	v_mul_f32_e32 v32, v40, v127
	v_mul_f32_e32 v32, v32, v48
	v_cvt_pk_bf16_f32 v34, v32, s0
	v_add_u32_e32 v32, v56, v49
	v_ashrrev_i32_e32 v33, 31, v32
	v_lshl_add_u64 v[32:33], v[32:33], 1, s[6:7]
	global_store_short v[32:33], v34, off sc1
	v_mul_f32_e32 v32, v41, v125
	v_mul_f32_e32 v32, v32, v48
	v_cvt_pk_bf16_f32 v34, v32, s0
	v_add_u32_e32 v32, v57, v49
	v_ashrrev_i32_e32 v33, 31, v32
	v_lshl_add_u64 v[32:33], v[32:33], 1, s[6:7]
	global_store_short v[32:33], v34, off sc1
	v_mul_f32_e32 v32, v42, v128
	v_mul_f32_e32 v32, v32, v48
	v_cvt_pk_bf16_f32 v34, v32, s0
	v_add_u32_e32 v32, v58, v49
	v_ashrrev_i32_e32 v33, 31, v32
	v_lshl_add_u64 v[32:33], v[32:33], 1, s[6:7]
	global_store_short v[32:33], v34, off sc1
	v_mul_f32_e32 v32, v43, v129
	v_mul_f32_e32 v32, v32, v48
	v_cvt_pk_bf16_f32 v34, v32, s0
	v_add_u32_e32 v32, v59, v49
	v_ashrrev_i32_e32 v33, 31, v32
	v_lshl_add_u64 v[32:33], v[32:33], 1, s[6:7]
	global_store_short v[32:33], v34, off sc1
	v_mul_f32_e32 v32, v44, v132
	v_mul_f32_e32 v32, v32, v48
	v_cvt_pk_bf16_f32 v34, v32, s0
	v_add_u32_e32 v32, v60, v49
	v_ashrrev_i32_e32 v33, 31, v32
	v_lshl_add_u64 v[32:33], v[32:33], 1, s[6:7]
	global_store_short v[32:33], v34, off sc1
	v_mul_f32_e32 v32, v45, v133
	v_mul_f32_e32 v32, v32, v48
	v_cvt_pk_bf16_f32 v34, v32, s0
	v_add_u32_e32 v32, v61, v49
	v_ashrrev_i32_e32 v33, 31, v32
	v_lshl_add_u64 v[32:33], v[32:33], 1, s[6:7]
	global_store_short v[32:33], v34, off sc1
	v_mul_f32_e32 v32, v46, v131
	v_mul_f32_e32 v32, v32, v48
	v_cvt_pk_bf16_f32 v34, v32, s0
	v_add_u32_e32 v32, v62, v49
	v_ashrrev_i32_e32 v33, 31, v32
	v_lshl_add_u64 v[32:33], v[32:33], 1, s[6:7]
	global_store_short v[32:33], v34, off sc1
	v_mul_f32_e32 v32, v47, v130
	v_mul_f32_e32 v32, v32, v48
	v_cvt_pk_bf16_f32 v34, v32, s0
	v_add_u32_e32 v32, v63, v49
	v_ashrrev_i32_e32 v33, 31, v32
	v_lshl_add_u64 v[32:33], v[32:33], 1, s[6:7]
	global_store_short v[32:33], v34, off sc1
	v_add_u32_e32 v34, s72, v74
	v_add_u32_e32 v32, v140, v34
	s_waitcnt vmcnt(33)
	v_mul_f32_e32 v16, v16, v138
	v_ashrrev_i32_e32 v33, 31, v32
	v_cvt_pk_bf16_f32 v16, v16, s0
	v_lshl_add_u64 v[32:33], v[32:33], 1, s[6:7]
	global_store_short v[32:33], v16, off sc1
	v_mul_f32_e32 v16, v17, v70
	v_mul_f32_e32 v16, v16, v138
	v_cvt_pk_bf16_f32 v32, v16, s0
	v_add_u32_e32 v16, v139, v34
	v_ashrrev_i32_e32 v17, 31, v16
	v_lshl_add_u64 v[16:17], v[16:17], 1, s[6:7]
	global_store_short v[16:17], v32, off sc1
	v_mul_f32_e32 v16, v18, v73
	v_mul_f32_e32 v16, v16, v138
	v_cvt_pk_bf16_f32 v18, v16, s0
	v_add_u32_e32 v16, v141, v34
	v_ashrrev_i32_e32 v17, 31, v16
	v_lshl_add_u64 v[16:17], v[16:17], 1, s[6:7]
	global_store_short v[16:17], v18, off sc1
	v_mul_f32_e32 v16, v19, v72
	v_mul_f32_e32 v16, v16, v138
	v_cvt_pk_bf16_f32 v18, v16, s0
	v_add_u32_e32 v16, v136, v34
	v_ashrrev_i32_e32 v17, 31, v16
	v_lshl_add_u64 v[16:17], v[16:17], 1, s[6:7]
	global_store_short v[16:17], v18, off sc1
	v_mul_f32_e32 v16, v20, v122
	v_mul_f32_e32 v16, v16, v138
	v_cvt_pk_bf16_f32 v18, v16, s0
	v_add_u32_e32 v16, v52, v34
	v_ashrrev_i32_e32 v17, 31, v16
	v_lshl_add_u64 v[16:17], v[16:17], 1, s[6:7]
	global_store_short v[16:17], v18, off sc1
	v_mul_f32_e32 v16, v21, v123
	v_mul_f32_e32 v16, v16, v138
	v_cvt_pk_bf16_f32 v18, v16, s0
	v_add_u32_e32 v16, v53, v34
	v_ashrrev_i32_e32 v17, 31, v16
	v_lshl_add_u64 v[16:17], v[16:17], 1, s[6:7]
	global_store_short v[16:17], v18, off sc1
	v_mul_f32_e32 v16, v22, v124
	v_mul_f32_e32 v16, v16, v138
	v_cvt_pk_bf16_f32 v18, v16, s0
	v_add_u32_e32 v16, v54, v34
	v_ashrrev_i32_e32 v17, 31, v16
	v_lshl_add_u64 v[16:17], v[16:17], 1, s[6:7]
	global_store_short v[16:17], v18, off sc1
	v_mul_f32_e32 v16, v23, v126
	v_mul_f32_e32 v16, v16, v138
	v_cvt_pk_bf16_f32 v18, v16, s0
	v_add_u32_e32 v16, v55, v34
	v_ashrrev_i32_e32 v17, 31, v16
	v_lshl_add_u64 v[16:17], v[16:17], 1, s[6:7]
	global_store_short v[16:17], v18, off sc1
	v_mul_f32_e32 v16, v24, v127
	v_mul_f32_e32 v16, v16, v138
	v_cvt_pk_bf16_f32 v18, v16, s0
	v_add_u32_e32 v16, v56, v34
	v_ashrrev_i32_e32 v17, 31, v16
	v_lshl_add_u64 v[16:17], v[16:17], 1, s[6:7]
	global_store_short v[16:17], v18, off sc1
	v_mul_f32_e32 v16, v25, v125
	v_mul_f32_e32 v16, v16, v138
	v_cvt_pk_bf16_f32 v18, v16, s0
	v_add_u32_e32 v16, v57, v34
	v_ashrrev_i32_e32 v17, 31, v16
	v_lshl_add_u64 v[16:17], v[16:17], 1, s[6:7]
	global_store_short v[16:17], v18, off sc1
	v_mul_f32_e32 v16, v26, v128
	v_mul_f32_e32 v16, v16, v138
	v_cvt_pk_bf16_f32 v18, v16, s0
	v_add_u32_e32 v16, v58, v34
	v_ashrrev_i32_e32 v17, 31, v16
	v_lshl_add_u64 v[16:17], v[16:17], 1, s[6:7]
	global_store_short v[16:17], v18, off sc1
	v_mul_f32_e32 v16, v27, v129
	v_mul_f32_e32 v16, v16, v138
	v_cvt_pk_bf16_f32 v18, v16, s0
	v_add_u32_e32 v16, v59, v34
	v_ashrrev_i32_e32 v17, 31, v16
	v_lshl_add_u64 v[16:17], v[16:17], 1, s[6:7]
	global_store_short v[16:17], v18, off sc1
	v_mul_f32_e32 v16, v28, v132
	v_mul_f32_e32 v16, v16, v138
	v_cvt_pk_bf16_f32 v18, v16, s0
	v_add_u32_e32 v16, v60, v34
	v_ashrrev_i32_e32 v17, 31, v16
	v_lshl_add_u64 v[16:17], v[16:17], 1, s[6:7]
	global_store_short v[16:17], v18, off sc1
	v_mul_f32_e32 v16, v29, v133
	v_mul_f32_e32 v16, v16, v138
	v_cvt_pk_bf16_f32 v18, v16, s0
	v_add_u32_e32 v16, v61, v34
	v_ashrrev_i32_e32 v17, 31, v16
	v_lshl_add_u64 v[16:17], v[16:17], 1, s[6:7]
	global_store_short v[16:17], v18, off sc1
	v_mul_f32_e32 v16, v30, v131
	v_mul_f32_e32 v16, v16, v138
	v_cvt_pk_bf16_f32 v18, v16, s0
	v_add_u32_e32 v16, v62, v34
	v_ashrrev_i32_e32 v17, 31, v16
	v_lshl_add_u64 v[16:17], v[16:17], 1, s[6:7]
	global_store_short v[16:17], v18, off sc1
	v_mul_f32_e32 v16, v31, v130
	v_mul_f32_e32 v16, v16, v138
	v_cvt_pk_bf16_f32 v18, v16, s0
	v_add_u32_e32 v16, v63, v34
	v_ashrrev_i32_e32 v17, 31, v16
	v_lshl_add_u64 v[16:17], v[16:17], 1, s[6:7]
	global_store_short v[16:17], v18, off sc1
	v_add_u32_e32 v18, s72, v98
	v_add_u32_e32 v16, v140, v18
	s_waitcnt vmcnt(48)
	v_mul_f32_e32 v0, v0, v121
	v_ashrrev_i32_e32 v17, 31, v16
	v_cvt_pk_bf16_f32 v0, v0, s0
	v_lshl_add_u64 v[16:17], v[16:17], 1, s[6:7]
	global_store_short v[16:17], v0, off sc1
	v_mul_f32_e32 v0, v1, v70
	v_mul_f32_e32 v0, v0, v121
	v_cvt_pk_bf16_f32 v16, v0, s0
	v_add_u32_e32 v0, v139, v18
	v_ashrrev_i32_e32 v1, 31, v0
	v_lshl_add_u64 v[0:1], v[0:1], 1, s[6:7]
	global_store_short v[0:1], v16, off sc1
	v_mul_f32_e32 v0, v2, v73
	v_mul_f32_e32 v0, v0, v121
	v_cvt_pk_bf16_f32 v2, v0, s0
	v_add_u32_e32 v0, v141, v18
	v_ashrrev_i32_e32 v1, 31, v0
	v_lshl_add_u64 v[0:1], v[0:1], 1, s[6:7]
	global_store_short v[0:1], v2, off sc1
	v_mul_f32_e32 v0, v3, v72
	v_mul_f32_e32 v0, v0, v121
	v_cvt_pk_bf16_f32 v2, v0, s0
	v_add_u32_e32 v0, v136, v18
	v_ashrrev_i32_e32 v1, 31, v0
	v_lshl_add_u64 v[0:1], v[0:1], 1, s[6:7]
	global_store_short v[0:1], v2, off sc1
	v_mul_f32_e32 v0, v4, v122
	v_mul_f32_e32 v0, v0, v121
	v_cvt_pk_bf16_f32 v2, v0, s0
	v_add_u32_e32 v0, v52, v18
	v_ashrrev_i32_e32 v1, 31, v0
	v_lshl_add_u64 v[0:1], v[0:1], 1, s[6:7]
	global_store_short v[0:1], v2, off sc1
	v_mul_f32_e32 v0, v5, v123
	v_mul_f32_e32 v0, v0, v121
	v_cvt_pk_bf16_f32 v2, v0, s0
	v_add_u32_e32 v0, v53, v18
	v_ashrrev_i32_e32 v1, 31, v0
	v_lshl_add_u64 v[0:1], v[0:1], 1, s[6:7]
	global_store_short v[0:1], v2, off sc1
	v_mul_f32_e32 v0, v6, v124
	v_mul_f32_e32 v0, v0, v121
	v_cvt_pk_bf16_f32 v2, v0, s0
	v_add_u32_e32 v0, v54, v18
	v_ashrrev_i32_e32 v1, 31, v0
	v_lshl_add_u64 v[0:1], v[0:1], 1, s[6:7]
	global_store_short v[0:1], v2, off sc1
	v_mul_f32_e32 v0, v7, v126
	v_mul_f32_e32 v0, v0, v121
	v_cvt_pk_bf16_f32 v2, v0, s0
	v_add_u32_e32 v0, v55, v18
	v_ashrrev_i32_e32 v1, 31, v0
	v_lshl_add_u64 v[0:1], v[0:1], 1, s[6:7]
	global_store_short v[0:1], v2, off sc1
	v_mul_f32_e32 v0, v8, v127
	v_mul_f32_e32 v0, v0, v121
	v_cvt_pk_bf16_f32 v2, v0, s0
	v_add_u32_e32 v0, v56, v18
	v_ashrrev_i32_e32 v1, 31, v0
	v_lshl_add_u64 v[0:1], v[0:1], 1, s[6:7]
	global_store_short v[0:1], v2, off sc1
	v_mul_f32_e32 v0, v9, v125
	v_mul_f32_e32 v0, v0, v121
	v_cvt_pk_bf16_f32 v2, v0, s0
	v_add_u32_e32 v0, v57, v18
	v_ashrrev_i32_e32 v1, 31, v0
	v_lshl_add_u64 v[0:1], v[0:1], 1, s[6:7]
	global_store_short v[0:1], v2, off sc1
	v_mul_f32_e32 v0, v10, v128
	v_mul_f32_e32 v0, v0, v121
	v_cvt_pk_bf16_f32 v2, v0, s0
	v_add_u32_e32 v0, v58, v18
	v_ashrrev_i32_e32 v1, 31, v0
	v_lshl_add_u64 v[0:1], v[0:1], 1, s[6:7]
	global_store_short v[0:1], v2, off sc1
	v_mul_f32_e32 v0, v11, v129
	v_mul_f32_e32 v0, v0, v121
	v_cvt_pk_bf16_f32 v2, v0, s0
	v_add_u32_e32 v0, v59, v18
	v_ashrrev_i32_e32 v1, 31, v0
	v_lshl_add_u64 v[0:1], v[0:1], 1, s[6:7]
	global_store_short v[0:1], v2, off sc1
	v_mul_f32_e32 v0, v12, v132
	v_mul_f32_e32 v0, v0, v121
	v_cvt_pk_bf16_f32 v2, v0, s0
	v_add_u32_e32 v0, v60, v18
	v_ashrrev_i32_e32 v1, 31, v0
	v_lshl_add_u64 v[0:1], v[0:1], 1, s[6:7]
	global_store_short v[0:1], v2, off sc1
	v_mul_f32_e32 v0, v13, v133
	v_mul_f32_e32 v0, v0, v121
	v_cvt_pk_bf16_f32 v2, v0, s0
	v_add_u32_e32 v0, v61, v18
	v_ashrrev_i32_e32 v1, 31, v0
	v_lshl_add_u64 v[0:1], v[0:1], 1, s[6:7]
	global_store_short v[0:1], v2, off sc1
	v_mul_f32_e32 v0, v14, v131
	v_mul_f32_e32 v0, v0, v121
	v_cvt_pk_bf16_f32 v2, v0, s0
	v_add_u32_e32 v0, v62, v18
	v_ashrrev_i32_e32 v1, 31, v0
	v_lshl_add_u64 v[0:1], v[0:1], 1, s[6:7]
	global_store_short v[0:1], v2, off sc1
	v_mul_f32_e32 v0, v15, v130
	v_mul_f32_e32 v70, v0, v121
	v_add_u32_e32 v72, v63, v18
	s_branch .LBB0_575
.LBB0_644:
	s_cmpk_gt_i32 s3, 0x83f
	s_cbranch_scc1 .LBB0_655
	v_lshrrev_b32_e32 v0, 3, v199
	v_lshrrev_b32_e32 v1, 5, v199
	v_bfe_u32 v4, v199, 1, 3
	v_lshlrev_b32_e32 v5, 4, v199
	v_bfe_u32 v2, v199, 5, 1
	v_xor_b32_e32 v6, v5, v199
	v_lshlrev_b32_e32 v7, 9, v0
	s_movk_i32 s0, 0x70
	v_bitop3_b32 v1, v1, v4, 1 bitop3:0x6c
	v_and_or_b32 v66, v6, s0, v7
	v_lshlrev_b32_e32 v7, 4, v1
	v_bitop3_b32 v1, v2, v4, 2 bitop3:0x36
	s_add_u32 s10, s14, 0x13e1f000
	v_lshrrev_b32_e32 v3, 1, v199
	v_lshlrev_b32_e32 v8, 4, v1
	v_bitop3_b32 v1, v2, v4, 4 bitop3:0x36
	s_addc_u32 s11, s15, 0
	v_mov_b32_e32 v67, 0
	v_and_b32_e32 v3, 0x1e0, v3
	v_lshlrev_b32_e32 v9, 4, v1
	v_bitop3_b32 v1, v2, v4, 6 bitop3:0x36
	s_add_u32 s52, s14, 0x2a0000
	v_lshlrev_b32_e32 v2, 4, v1
	v_and_or_b32 v72, v0, 4, v3
	v_lshlrev_b32_e32 v0, 1, v64
	v_mov_b32_e32 v1, v67
	s_addc_u32 s53, s15, 0
	v_or_b32_e32 v6, v3, v64
	v_lshl_add_u64 v[0:1], s[14:15], 0, v[0:1]
	s_mov_b64 s[0:1], 0xdf9f000
	v_lshl_add_u32 v6, v6, 7, 0
	v_or_b32_e32 v78, 0x60, v64
	s_add_u32 s6, s14, 0x1111f000
	v_lshl_add_u64 v[68:69], v[0:1], 0, s[0:1]
	s_waitcnt lgkmcnt(0)
	v_add_u32_e32 v80, 0, v5
	v_mbcnt_lo_u32_b32 v0, -1, 0
	v_lshlrev_b32_e32 v73, 8, v64
	v_lshlrev_b32_e32 v76, 8, v65
	v_lshlrev_b32_e32 v77, 8, v74
	v_lshlrev_b32_e32 v79, 8, v78
	s_addc_u32 s7, s15, 0
	v_add_u32_e32 v81, 0x4000, v80
	s_mov_b64 s[8:9], 0x4000
	s_movk_i32 s54, 0x1000
	v_add_u32_e32 v82, 0x1000, v80
	v_add_u32_e32 v83, 0x5000, v80
	s_mov_b64 s[18:19], 0x8000
	s_movk_i32 s55, 0x2000
	v_add_u32_e32 v84, 0x2000, v80
	s_movk_i32 s56, 0x6000
	v_add_u32_e32 v85, 0x6000, v80
	s_mov_b64 s[20:21], 0xc000
	v_add_u32_e32 v86, 0x3000, v80
	s_movk_i32 s57, 0x7000
	v_add_u32_e32 v87, 0x7000, v80
	s_mov_b64 s[22:23], 0x80
	s_mov_b32 s58, 0x8000
	v_add_u32_e32 v88, 0x8000, v80
	s_mov_b32 s59, 0xc000
	v_add_u32_e32 v89, 0xc000, v80
	s_mov_b64 s[24:25], 0x4080
	v_add_u32_e32 v90, 0x9000, v80
	s_mov_b32 s60, 0xd000
	v_add_u32_e32 v91, 0xd000, v80
	s_mov_b64 s[26:27], 0x8080
	v_add_u32_e32 v92, 0xa000, v80
	s_mov_b32 s61, 0xe000
	v_add_u32_e32 v93, 0xe000, v80
	s_mov_b64 s[28:29], 0xc080
	v_add_u32_e32 v94, 0xb000, v80
	v_add_u32_e32 v95, 0xf000, v80
	v_add_u32_e32 v96, v6, v7
	v_add_u32_e32 v97, v75, v7
	v_add_u32_e32 v98, v6, v8
	v_add_u32_e32 v99, v75, v8
	v_add_u32_e32 v100, v6, v9
	v_add_u32_e32 v101, v75, v9
	v_add_u32_e32 v102, v6, v2
	v_add_u32_e32 v75, v75, v2
	s_mov_b64 s[30:31], 0x100
	s_mov_b64 s[34:35], 0x4100
	s_mov_b64 s[36:37], 0x8100
	s_mov_b64 s[38:39], 0xc100
	s_mov_b64 s[40:41], 0x180
	s_mov_b64 s[42:43], 0x4180
	s_mov_b64 s[44:45], 0x8180
	s_mov_b64 s[46:47], 0xc180
	s_movk_i32 s62, 0x1100
	s_add_i32 s63, 0, 0x120b0
	v_lshlrev_b32_e32 v103, 2, v64
	v_mov_b32_e32 v104, 0x358637bd
	s_movk_i32 s64, 0x600
	s_mov_b32 s65, 0x12000
	s_mov_b32 s66, 0x13000
	s_mov_b32 s67, 0x14000
	v_mbcnt_hi_u32_b32 v105, -1, v0
	s_branch .LBB0_647

.LBB0_653:
	s_and_b64 vcc, exec, s[0:1]
	s_cbranch_vccz .LBB0_646
	v_mov_b32_e32 v70, s63
	ds_read_b64 v[70:71], v70
	v_xor_b32_e32 v110, 2, v105
	v_add_u32_e32 v114, s48, v72
	v_xor_b32_e32 v111, 4, v105
	v_mul_f32_e32 v115, v32, v32
	s_waitcnt lgkmcnt(0)
	v_readfirstlane_b32 s0, v70
	v_readfirstlane_b32 s1, v71
	s_nop 4
	global_load_dword v109, v103, s[0:1] offset:768
	global_load_dword v108, v103, s[0:1] offset:896
	global_load_dword v107, v103, s[0:1] offset:1024
	global_load_dword v106, v103, s[0:1] offset:1152
	v_and_b32_e32 v70, 64, v105
	v_xor_b32_e32 v71, 1, v105
	v_add_u32_e32 v116, 64, v70
	v_cmp_lt_i32_e32 vcc, v71, v116
	v_mul_lo_u32 v70, v114, s64
	v_xor_b32_e32 v112, 8, v105
	v_cndmask_b32_e32 v114, v105, v71, vcc
	v_cmp_lt_i32_e32 vcc, v110, v116
	v_fmac_f32_e32 v115, v48, v48
	v_fmac_f32_e32 v115, v16, v16
	v_cndmask_b32_e32 v110, v105, v110, vcc
	v_cmp_lt_i32_e32 vcc, v111, v116
	v_fmac_f32_e32 v115, v0, v0
	v_xor_b32_e32 v113, 16, v105
	v_cndmask_b32_e32 v111, v105, v111, vcc
	v_cmp_lt_i32_e32 vcc, v112, v116
	v_mul_f32_e32 v118, v33, v33
	v_fmac_f32_e32 v118, v49, v49
	v_cndmask_b32_e32 v120, v105, v112, vcc
	v_lshlrev_b32_e32 v112, 2, v114
	v_cmp_lt_i32_e32 vcc, v113, v116
	v_fmac_f32_e32 v118, v17, v17
	v_fmac_f32_e32 v118, v1, v1
	v_cndmask_b32_e32 v121, v105, v113, vcc
	v_lshlrev_b32_e32 v113, 2, v110
	v_add_f32_dpp v110, v115, v115 quad_perm:[1,0,3,2] row_mask:0xf bank_mask:0xf
	v_lshlrev_b32_e32 v114, 2, v111
	v_lshlrev_b32_e32 v111, 2, v120
	v_mul_f32_e32 v119, v34, v34
	v_add_f32_dpp v115, v110, v110 quad_perm:[2,3,0,1] row_mask:0xf bank_mask:0xf
	s_nop 1
	v_mov_b32_dpp v123, v115 row_half_mirror row_mask:0xf bank_mask:0xf
	v_lshlrev_b32_e32 v110, 2, v121
	v_add_f32_dpp v118, v118, v118 quad_perm:[1,0,3,2] row_mask:0xf bank_mask:0xf
	v_fmac_f32_e32 v119, v50, v50
	v_add_f32_e32 v115, v115, v123
	v_fmac_f32_e32 v119, v18, v18
	v_add_f32_dpp v118, v118, v118 quad_perm:[2,3,0,1] row_mask:0xf bank_mask:0xf
	v_fmac_f32_e32 v119, v2, v2
	v_add_f32_dpp v115, v115, v115 row_mirror row_mask:0xf bank_mask:0xf
	v_mov_b32_e32 v121, v115
	s_nop 1
	v_permlane16_swap_b32_e32 v115, v121
	s_nop 0
	s_nop 1
	v_mov_b32_dpp v122, v119 quad_perm:[1,0,3,2] row_mask:0xf bank_mask:0xf
	v_add_f32_dpp v118, v118, v118 row_half_mirror row_mask:0xf bank_mask:0xf
	s_nop 1
	v_mov_b32_dpp v120, v118 row_mirror row_mask:0xf bank_mask:0xf
	s_mul_i32 s0, s49, 0xc0
	v_add_f32_e32 v115, v115, v121
	v_fmamk_f32 v115, v115, 0x3c000000, v104
	v_rsq_f32_e32 v115, v115
	s_ashr_i32 s1, s0, 31
	v_lshl_add_u64 v[116:117], s[0:1], 1, v[68:69]
	v_ashrrev_i32_e32 v71, 31, v70
	v_mul_f32_e32 v48, v48, v115
	v_mul_f32_e32 v16, v16, v115
	v_mul_f32_e32 v32, v32, v115
	v_lshl_add_u64 v[70:71], v[70:71], 1, v[116:117]
	v_add_f32_e32 v116, v118, v120
	v_add_f32_e32 v118, v119, v122
	v_mov_b32_e32 v117, v116
	s_nop 1
	v_permlane16_swap_b32_e32 v116, v117
	s_nop 0
	v_mul_f32_e32 v0, v0, v115
	v_add_f32_e32 v116, v116, v117
	v_fmamk_f32 v116, v116, 0x3c000000, v104
	v_rsq_f32_e32 v116, v116
	s_waitcnt vmcnt(3)
	v_mul_f32_e32 v48, v109, v48
	s_waitcnt vmcnt(2)
	v_mul_f32_e32 v32, v108, v32
	s_waitcnt vmcnt(1)
	v_mul_f32_e32 v16, v107, v16
	v_cvt_pk_bf16_f32 v48, v48, s0
	v_cvt_pk_bf16_f32 v16, v16, s0
	v_cvt_pk_bf16_f32 v32, v32, s0
	global_store_short v[70:71], v48, off sc1
	global_store_short v[70:71], v32, off offset:64 sc1
	global_store_short v[70:71], v16, off offset:128 sc1
	s_waitcnt vmcnt(3)
	v_mul_f32_e32 v0, v106, v0
	v_cvt_pk_bf16_f32 v0, v0, s0
	global_store_short v[70:71], v0, off offset:192 sc1
	v_mul_f32_e32 v0, v49, v116
	v_add_f32_dpp v16, v118, v118 quad_perm:[2,3,0,1] row_mask:0xf bank_mask:0xf
	v_mul_f32_e32 v0, v109, v0
	v_cvt_pk_bf16_f32 v0, v0, s0
	global_store_short v[70:71], v0, off offset:3072 sc1
	v_mul_f32_e32 v0, v33, v116
	v_add_f32_dpp v16, v16, v16 row_half_mirror row_mask:0xf bank_mask:0xf
	v_mul_f32_e32 v0, v108, v0
	v_cvt_pk_bf16_f32 v0, v0, s0
	global_store_short v[70:71], v0, off offset:3136 sc1
	v_mul_f32_e32 v0, v17, v116
	v_add_f32_dpp v16, v16, v16 row_mirror row_mask:0xf bank_mask:0xf
	v_mov_b32_e32 v17, v16
	s_nop 1
	v_permlane16_swap_b32_e32 v16, v17
	s_nop 0
	v_mul_f32_e32 v0, v107, v0
	v_cvt_pk_bf16_f32 v0, v0, s0
	global_store_short v[70:71], v0, off offset:3200 sc1
	v_mul_f32_e32 v0, v1, v116
	v_add_f32_e32 v1, v16, v17
	v_fmamk_f32 v1, v1, 0x3c000000, v104
	v_rsq_f32_e32 v16, v1
	v_mul_f32_e32 v1, v35, v35
	v_fmac_f32_e32 v1, v51, v51
	v_fmac_f32_e32 v1, v19, v19
	v_fmac_f32_e32 v1, v3, v3
	v_mul_f32_e32 v0, v106, v0
	v_cvt_pk_bf16_f32 v0, v0, s0
	global_store_short v[70:71], v0, off offset:3264 sc1
	v_mul_f32_e32 v0, v50, v16
	v_add_f32_dpp v17, v1, v1 quad_perm:[1,0,3,2] row_mask:0xf bank_mask:0xf
	v_mul_f32_e32 v0, v109, v0
	v_cvt_pk_bf16_f32 v32, v0, s0
	v_add_co_u32_e32 v0, vcc, s54, v70
	v_add_f32_dpp v17, v17, v17 quad_perm:[2,3,0,1] row_mask:0xf bank_mask:0xf
	v_addc_co_u32_e32 v1, vcc, 0, v71, vcc
	global_store_short v[0:1], v32, off offset:2048 sc1
	v_mul_f32_e32 v32, v34, v16
	v_add_f32_dpp v17, v17, v17 row_half_mirror row_mask:0xf bank_mask:0xf
	s_nop 1
	v_mov_b32_dpp v33, v17 row_mirror row_mask:0xf bank_mask:0xf
	v_mul_f32_e32 v32, v108, v32
	v_cvt_pk_bf16_f32 v32, v32, s0
	global_store_short v[0:1], v32, off offset:2112 sc1
	v_mul_f32_e32 v18, v18, v16
	v_add_f32_e32 v17, v17, v33
	v_mov_b32_e32 v32, v17
	s_nop 1
	v_permlane16_swap_b32_e32 v17, v32
	s_nop 0
	v_mul_f32_e32 v2, v2, v16
	v_mul_f32_e32 v18, v107, v18
	v_cvt_pk_bf16_f32 v18, v18, s0
	global_store_short v[0:1], v18, off offset:2176 sc1
	v_add_f32_e32 v16, v17, v32
	v_mul_f32_e32 v17, v36, v36
	v_fmac_f32_e32 v17, v52, v52
	v_fmac_f32_e32 v17, v20, v20
	v_fmac_f32_e32 v17, v4, v4
	v_fmamk_f32 v16, v16, 0x3c000000, v104
	v_rsq_f32_e32 v16, v16
	v_mul_f32_e32 v2, v106, v2
	v_cvt_pk_bf16_f32 v2, v2, s0
	v_add_f32_dpp v17, v17, v17 quad_perm:[1,0,3,2] row_mask:0xf bank_mask:0xf
	global_store_short v[0:1], v2, off offset:2240 sc1
	v_mul_f32_e32 v0, v51, v16
	v_mul_f32_e32 v0, v109, v0
	v_cvt_pk_bf16_f32 v2, v0, s0
	v_add_f32_dpp v17, v17, v17 quad_perm:[2,3,0,1] row_mask:0xf bank_mask:0xf
	v_add_co_u32_e32 v0, vcc, s55, v70
	v_add_f32_dpp v17, v17, v17 row_half_mirror row_mask:0xf bank_mask:0xf
	v_addc_co_u32_e32 v1, vcc, 0, v71, vcc
	global_store_short v[0:1], v2, off offset:1024 sc1
	v_mul_f32_e32 v2, v35, v16
	v_mul_f32_e32 v2, v108, v2
	v_cvt_pk_bf16_f32 v2, v2, s0
	global_store_short v[0:1], v2, off offset:1088 sc1
	v_mul_f32_e32 v2, v19, v16
	v_mul_f32_e32 v2, v107, v2
	v_add_f32_dpp v17, v17, v17 row_mirror row_mask:0xf bank_mask:0xf
	v_cvt_pk_bf16_f32 v2, v2, s0
	v_mov_b32_e32 v18, v17
	s_nop 1
	v_permlane16_swap_b32_e32 v17, v18
	s_nop 0
	global_store_short v[0:1], v2, off offset:1152 sc1
	v_mul_f32_e32 v2, v3, v16
	v_mul_f32_e32 v16, v37, v37
	v_fmac_f32_e32 v16, v53, v53
	v_fmac_f32_e32 v16, v21, v21
	v_fmac_f32_e32 v16, v5, v5
	v_add_f32_e32 v3, v17, v18
	v_fmamk_f32 v3, v3, 0x3c000000, v104
	v_rsq_f32_e32 v3, v3
	v_mul_f32_e32 v2, v106, v2
	v_cvt_pk_bf16_f32 v2, v2, s0
	v_add_f32_dpp v16, v16, v16 quad_perm:[1,0,3,2] row_mask:0xf bank_mask:0xf
	global_store_short v[0:1], v2, off offset:1216 sc1
	v_mul_f32_e32 v0, v52, v3
	v_mul_f32_e32 v0, v109, v0
	v_cvt_pk_bf16_f32 v2, v0, s0
	v_add_f32_dpp v16, v16, v16 quad_perm:[2,3,0,1] row_mask:0xf bank_mask:0xf
	v_add_co_u32_e32 v0, vcc, s56, v70
	v_add_f32_dpp v16, v16, v16 row_half_mirror row_mask:0xf bank_mask:0xf
	v_addc_co_u32_e32 v1, vcc, 0, v71, vcc
	global_store_short v[0:1], v2, off sc1
	v_mul_f32_e32 v2, v36, v3
	v_mul_f32_e32 v2, v108, v2
	v_cvt_pk_bf16_f32 v2, v2, s0
	global_store_short v[0:1], v2, off offset:64 sc1
	v_mul_f32_e32 v2, v20, v3
	v_mul_f32_e32 v2, v107, v2
	v_cvt_pk_bf16_f32 v2, v2, s0
	global_store_short v[0:1], v2, off offset:128 sc1
	v_mul_f32_e32 v2, v4, v3
	v_add_f32_dpp v3, v16, v16 row_mirror row_mask:0xf bank_mask:0xf
	v_mul_f32_e32 v16, v38, v38
	v_fmac_f32_e32 v16, v54, v54
	v_fmac_f32_e32 v16, v22, v22
	v_fmac_f32_e32 v16, v6, v6
	v_mov_b32_e32 v4, v3
	s_nop 1
	v_permlane16_swap_b32_e32 v3, v4
	s_nop 0
	s_nop 1
	v_mov_b32_dpp v17, v16 quad_perm:[1,0,3,2] row_mask:0xf bank_mask:0xf
	v_mul_f32_e32 v2, v106, v2
	v_cvt_pk_bf16_f32 v2, v2, s0
	global_store_short v[0:1], v2, off offset:192 sc1
	v_add_f32_e32 v3, v3, v4
	v_add_f32_e32 v4, v16, v17
	v_fmamk_f32 v3, v3, 0x3c000000, v104
	v_rsq_f32_e32 v3, v3
	v_add_f32_dpp v4, v4, v4 quad_perm:[2,3,0,1] row_mask:0xf bank_mask:0xf
	v_mul_f32_e32 v2, v53, v3
	v_mul_f32_e32 v2, v109, v2
	v_cvt_pk_bf16_f32 v2, v2, s0
	global_store_short v[0:1], v2, off offset:3072 sc1
	v_add_f32_dpp v4, v4, v4 row_half_mirror row_mask:0xf bank_mask:0xf
	v_mul_f32_e32 v2, v37, v3
	v_mul_f32_e32 v2, v108, v2
	v_cvt_pk_bf16_f32 v2, v2, s0
	global_store_short v[0:1], v2, off offset:3136 sc1
	v_add_f32_dpp v4, v4, v4 row_mirror row_mask:0xf bank_mask:0xf
	v_mov_b32_e32 v16, v4
	s_nop 1
	v_permlane16_swap_b32_e32 v4, v16
	s_nop 0
	v_mul_f32_e32 v2, v21, v3
	v_mul_f32_e32 v2, v107, v2
	v_cvt_pk_bf16_f32 v2, v2, s0
	global_store_short v[0:1], v2, off offset:3200 sc1
	v_mul_f32_e32 v2, v5, v3
	v_add_f32_e32 v3, v4, v16
	v_mul_f32_e32 v4, v39, v39
	v_fmac_f32_e32 v4, v55, v55
	v_fmac_f32_e32 v4, v23, v23
	v_fmac_f32_e32 v4, v7, v7
	v_fmamk_f32 v3, v3, 0x3c000000, v104
	v_rsq_f32_e32 v3, v3
	v_mul_f32_e32 v2, v106, v2
	v_cvt_pk_bf16_f32 v2, v2, s0
	v_add_f32_dpp v4, v4, v4 quad_perm:[1,0,3,2] row_mask:0xf bank_mask:0xf
	global_store_short v[0:1], v2, off offset:3264 sc1
	v_mul_f32_e32 v0, v54, v3
	v_mul_f32_e32 v0, v109, v0
	v_cvt_pk_bf16_f32 v2, v0, s0
	v_add_f32_dpp v4, v4, v4 quad_perm:[2,3,0,1] row_mask:0xf bank_mask:0xf
	v_add_co_u32_e32 v0, vcc, s57, v70
	v_add_f32_dpp v4, v4, v4 row_half_mirror row_mask:0xf bank_mask:0xf
	v_addc_co_u32_e32 v1, vcc, 0, v71, vcc
	global_store_short v[0:1], v2, off offset:2048 sc1
	v_mul_f32_e32 v2, v38, v3
	v_add_f32_dpp v4, v4, v4 row_mirror row_mask:0xf bank_mask:0xf
	v_mul_f32_e32 v2, v108, v2
	v_mov_b32_e32 v5, v4
	s_nop 1
	v_permlane16_swap_b32_e32 v4, v5
	s_nop 0
	v_cvt_pk_bf16_f32 v2, v2, s0
	global_store_short v[0:1], v2, off offset:2112 sc1
	v_mul_f32_e32 v2, v22, v3
	v_mul_f32_e32 v2, v107, v2
	v_cvt_pk_bf16_f32 v2, v2, s0
	global_store_short v[0:1], v2, off offset:2176 sc1
	v_mul_f32_e32 v2, v6, v3
	v_add_f32_e32 v3, v4, v5
	v_mul_f32_e32 v4, v40, v40
	v_fmac_f32_e32 v4, v56, v56
	v_fmac_f32_e32 v4, v24, v24
	v_fmac_f32_e32 v4, v8, v8
	v_fmamk_f32 v3, v3, 0x3c000000, v104
	v_rsq_f32_e32 v3, v3
	v_mul_f32_e32 v2, v106, v2
	v_cvt_pk_bf16_f32 v2, v2, s0
	v_add_f32_dpp v4, v4, v4 quad_perm:[1,0,3,2] row_mask:0xf bank_mask:0xf
	global_store_short v[0:1], v2, off offset:2240 sc1
	v_mul_f32_e32 v0, v55, v3
	v_mul_f32_e32 v0, v109, v0
	v_cvt_pk_bf16_f32 v2, v0, s0
	v_add_f32_dpp v4, v4, v4 quad_perm:[2,3,0,1] row_mask:0xf bank_mask:0xf
	v_add_co_u32_e32 v0, vcc, s58, v70
	v_add_f32_dpp v4, v4, v4 row_half_mirror row_mask:0xf bank_mask:0xf
	v_addc_co_u32_e32 v1, vcc, 0, v71, vcc
	global_store_short v[0:1], v2, off offset:1024 sc1
	v_mul_f32_e32 v2, v39, v3
	v_add_f32_dpp v4, v4, v4 row_mirror row_mask:0xf bank_mask:0xf
	v_mul_f32_e32 v2, v108, v2
	v_mov_b32_e32 v5, v4
	s_nop 1
	v_permlane16_swap_b32_e32 v4, v5
	s_nop 0
	v_cvt_pk_bf16_f32 v2, v2, s0
	global_store_short v[0:1], v2, off offset:1088 sc1
	v_mul_f32_e32 v2, v23, v3
	v_mul_f32_e32 v2, v107, v2
	v_cvt_pk_bf16_f32 v2, v2, s0
	global_store_short v[0:1], v2, off offset:1152 sc1
	v_mul_f32_e32 v2, v7, v3
	v_add_f32_e32 v3, v4, v5
	v_mul_f32_e32 v4, v41, v41
	v_fmac_f32_e32 v4, v57, v57
	v_fmac_f32_e32 v4, v25, v25
	v_fmac_f32_e32 v4, v9, v9
	v_fmamk_f32 v3, v3, 0x3c000000, v104
	v_rsq_f32_e32 v3, v3
	v_mul_f32_e32 v2, v106, v2
	v_cvt_pk_bf16_f32 v2, v2, s0
	v_add_f32_dpp v4, v4, v4 quad_perm:[1,0,3,2] row_mask:0xf bank_mask:0xf
	global_store_short v[0:1], v2, off offset:1216 sc1
	v_mul_f32_e32 v0, v56, v3
	v_mul_f32_e32 v0, v109, v0
	v_cvt_pk_bf16_f32 v2, v0, s0
	v_add_f32_dpp v4, v4, v4 quad_perm:[2,3,0,1] row_mask:0xf bank_mask:0xf
	v_add_co_u32_e32 v0, vcc, s59, v70
	v_add_f32_dpp v4, v4, v4 row_half_mirror row_mask:0xf bank_mask:0xf
	v_addc_co_u32_e32 v1, vcc, 0, v71, vcc
	global_store_short v[0:1], v2, off sc1
	v_mul_f32_e32 v2, v40, v3
	v_mul_f32_e32 v2, v108, v2
	v_cvt_pk_bf16_f32 v2, v2, s0
	global_store_short v[0:1], v2, off offset:64 sc1
	v_mul_f32_e32 v2, v24, v3
	v_mul_f32_e32 v2, v107, v2
	v_cvt_pk_bf16_f32 v2, v2, s0
	global_store_short v[0:1], v2, off offset:128 sc1
	v_mul_f32_e32 v2, v8, v3
	v_add_f32_dpp v3, v4, v4 row_mirror row_mask:0xf bank_mask:0xf
	v_mul_f32_e32 v5, v42, v42
	v_fmac_f32_e32 v5, v58, v58
	v_fmac_f32_e32 v5, v26, v26
	v_fmac_f32_e32 v5, v10, v10
	v_mov_b32_e32 v4, v3
	s_nop 1
	v_permlane16_swap_b32_e32 v3, v4
	s_nop 0
	v_mul_f32_e32 v2, v106, v2
	v_cvt_pk_bf16_f32 v2, v2, s0
	global_store_short v[0:1], v2, off offset:192 sc1
	v_add_f32_e32 v3, v3, v4
	v_add_f32_dpp v4, v5, v5 quad_perm:[1,0,3,2] row_mask:0xf bank_mask:0xf
	v_fmamk_f32 v3, v3, 0x3c000000, v104
	v_rsq_f32_e32 v3, v3
	v_add_f32_dpp v4, v4, v4 quad_perm:[2,3,0,1] row_mask:0xf bank_mask:0xf
	v_mul_f32_e32 v2, v57, v3
	v_mul_f32_e32 v2, v109, v2
	v_cvt_pk_bf16_f32 v2, v2, s0
	global_store_short v[0:1], v2, off offset:3072 sc1
	v_add_f32_dpp v4, v4, v4 row_half_mirror row_mask:0xf bank_mask:0xf
	v_mul_f32_e32 v2, v41, v3
	v_mul_f32_e32 v2, v108, v2
	v_cvt_pk_bf16_f32 v2, v2, s0
	global_store_short v[0:1], v2, off offset:3136 sc1
	v_add_f32_dpp v4, v4, v4 row_mirror row_mask:0xf bank_mask:0xf
	v_mov_b32_e32 v5, v4
	s_nop 1
	v_permlane16_swap_b32_e32 v4, v5
	s_nop 0
	v_mul_f32_e32 v2, v25, v3
	v_mul_f32_e32 v2, v107, v2
	v_cvt_pk_bf16_f32 v2, v2, s0
	global_store_short v[0:1], v2, off offset:3200 sc1
	v_mul_f32_e32 v2, v9, v3
	v_add_f32_e32 v3, v4, v5
	v_mul_f32_e32 v4, v43, v43
	v_fmac_f32_e32 v4, v59, v59
	v_fmac_f32_e32 v4, v27, v27
	v_fmac_f32_e32 v4, v11, v11
	v_fmamk_f32 v3, v3, 0x3c000000, v104
	v_rsq_f32_e32 v3, v3
	v_mul_f32_e32 v2, v106, v2
	v_cvt_pk_bf16_f32 v2, v2, s0
	v_add_f32_dpp v4, v4, v4 quad_perm:[1,0,3,2] row_mask:0xf bank_mask:0xf
	global_store_short v[0:1], v2, off offset:3264 sc1
	v_mul_f32_e32 v0, v58, v3
	v_mul_f32_e32 v0, v109, v0
	v_cvt_pk_bf16_f32 v2, v0, s0
	v_add_f32_dpp v4, v4, v4 quad_perm:[2,3,0,1] row_mask:0xf bank_mask:0xf
	v_add_co_u32_e32 v0, vcc, s60, v70
	v_add_f32_dpp v4, v4, v4 row_half_mirror row_mask:0xf bank_mask:0xf
	v_addc_co_u32_e32 v1, vcc, 0, v71, vcc
	global_store_short v[0:1], v2, off offset:2048 sc1
	v_mul_f32_e32 v2, v42, v3
	v_add_f32_dpp v4, v4, v4 row_mirror row_mask:0xf bank_mask:0xf
	v_mul_f32_e32 v2, v108, v2
	v_mov_b32_e32 v5, v4
	s_nop 1
	v_permlane16_swap_b32_e32 v4, v5
	s_nop 0
	v_cvt_pk_bf16_f32 v2, v2, s0
	global_store_short v[0:1], v2, off offset:2112 sc1
	v_mul_f32_e32 v2, v26, v3
	v_mul_f32_e32 v2, v107, v2
	v_cvt_pk_bf16_f32 v2, v2, s0
	global_store_short v[0:1], v2, off offset:2176 sc1
	v_mul_f32_e32 v2, v10, v3
	v_add_f32_e32 v3, v4, v5
	v_mul_f32_e32 v4, v44, v44
	v_fmac_f32_e32 v4, v60, v60
	v_fmac_f32_e32 v4, v28, v28
	v_fmac_f32_e32 v4, v12, v12
	v_fmamk_f32 v3, v3, 0x3c000000, v104
	v_rsq_f32_e32 v3, v3
	v_mul_f32_e32 v2, v106, v2
	v_cvt_pk_bf16_f32 v2, v2, s0
	v_add_f32_dpp v4, v4, v4 quad_perm:[1,0,3,2] row_mask:0xf bank_mask:0xf
	global_store_short v[0:1], v2, off offset:2240 sc1
	v_mul_f32_e32 v0, v59, v3
	v_mul_f32_e32 v0, v109, v0
	v_cvt_pk_bf16_f32 v2, v0, s0
	v_add_f32_dpp v4, v4, v4 quad_perm:[2,3,0,1] row_mask:0xf bank_mask:0xf
	v_add_co_u32_e32 v0, vcc, s61, v70
	v_add_f32_dpp v4, v4, v4 row_half_mirror row_mask:0xf bank_mask:0xf
	v_addc_co_u32_e32 v1, vcc, 0, v71, vcc
	global_store_short v[0:1], v2, off offset:1024 sc1
	v_mul_f32_e32 v2, v43, v3
	v_mul_f32_e32 v2, v108, v2
	v_cvt_pk_bf16_f32 v2, v2, s0
	global_store_short v[0:1], v2, off offset:1088 sc1
	v_mul_f32_e32 v2, v27, v3
	v_mul_f32_e32 v2, v107, v2
	v_cvt_pk_bf16_f32 v2, v2, s0
	global_store_short v[0:1], v2, off offset:1152 sc1
	v_mul_f32_e32 v2, v11, v3
	v_add_f32_dpp v3, v4, v4 row_mirror row_mask:0xf bank_mask:0xf
	v_mul_f32_e32 v5, v45, v45
	v_fmac_f32_e32 v5, v61, v61
	v_fmac_f32_e32 v5, v29, v29
	v_fmac_f32_e32 v5, v13, v13
	v_mov_b32_e32 v4, v3
	s_nop 1
	v_permlane16_swap_b32_e32 v3, v4
	s_nop 0
	v_mul_f32_e32 v2, v106, v2
	v_cvt_pk_bf16_f32 v2, v2, s0
	global_store_short v[0:1], v2, off offset:1216 sc1
	v_add_f32_e32 v3, v3, v4
	v_add_f32_dpp v4, v5, v5 quad_perm:[1,0,3,2] row_mask:0xf bank_mask:0xf
	v_fmamk_f32 v3, v3, 0x3c000000, v104
	v_rsq_f32_e32 v3, v3
	v_add_f32_dpp v4, v4, v4 quad_perm:[2,3,0,1] row_mask:0xf bank_mask:0xf
	v_mul_f32_e32 v0, v60, v3
	v_mul_f32_e32 v0, v109, v0
	v_cvt_pk_bf16_f32 v2, v0, s0
	v_add_co_u32_e32 v0, vcc, s65, v70
	v_add_f32_dpp v4, v4, v4 row_half_mirror row_mask:0xf bank_mask:0xf
	v_addc_co_u32_e32 v1, vcc, 0, v71, vcc
	global_store_short v[0:1], v2, off sc1
	v_mul_f32_e32 v2, v44, v3
	v_add_f32_dpp v4, v4, v4 row_mirror row_mask:0xf bank_mask:0xf
	v_mul_f32_e32 v2, v108, v2
	v_mov_b32_e32 v5, v4
	s_nop 1
	v_permlane16_swap_b32_e32 v4, v5
	s_nop 0
	v_cvt_pk_bf16_f32 v2, v2, s0
	global_store_short v[0:1], v2, off offset:64 sc1
	v_mul_f32_e32 v2, v28, v3
	v_mul_f32_e32 v2, v107, v2
	v_cvt_pk_bf16_f32 v2, v2, s0
	global_store_short v[0:1], v2, off offset:128 sc1
	v_mul_f32_e32 v2, v12, v3
	v_add_f32_e32 v3, v4, v5
	v_mul_f32_e32 v4, v46, v46
	v_fmac_f32_e32 v4, v62, v62
	v_fmac_f32_e32 v4, v30, v30
	v_fmac_f32_e32 v4, v14, v14
	v_fmamk_f32 v3, v3, 0x3c000000, v104
	v_rsq_f32_e32 v3, v3
	v_mul_f32_e32 v2, v106, v2
	v_cvt_pk_bf16_f32 v2, v2, s0
	v_add_f32_dpp v4, v4, v4 quad_perm:[1,0,3,2] row_mask:0xf bank_mask:0xf
	global_store_short v[0:1], v2, off offset:192 sc1
	v_mul_f32_e32 v2, v61, v3
	v_mul_f32_e32 v2, v109, v2
	v_cvt_pk_bf16_f32 v2, v2, s0
	v_add_f32_dpp v4, v4, v4 quad_perm:[2,3,0,1] row_mask:0xf bank_mask:0xf
	global_store_short v[0:1], v2, off offset:3072 sc1
	v_mul_f32_e32 v2, v45, v3
	v_mul_f32_e32 v2, v108, v2
	v_cvt_pk_bf16_f32 v2, v2, s0
	v_add_f32_dpp v4, v4, v4 row_half_mirror row_mask:0xf bank_mask:0xf
	global_store_short v[0:1], v2, off offset:3136 sc1
	v_mul_f32_e32 v2, v29, v3
	v_mul_f32_e32 v2, v107, v2
	v_cvt_pk_bf16_f32 v2, v2, s0
	global_store_short v[0:1], v2, off offset:3200 sc1
	v_mul_f32_e32 v2, v13, v3
	v_add_f32_dpp v3, v4, v4 row_mirror row_mask:0xf bank_mask:0xf
	v_mul_f32_e32 v5, v47, v47
	v_fmac_f32_e32 v5, v63, v63
	v_fmac_f32_e32 v5, v31, v31
	v_fmac_f32_e32 v5, v15, v15
	v_mov_b32_e32 v4, v3
	s_nop 1
	v_permlane16_swap_b32_e32 v3, v4
	s_nop 0
	s_nop 1
	v_mov_b32_dpp v6, v5 quad_perm:[1,0,3,2] row_mask:0xf bank_mask:0xf
	v_mul_f32_e32 v2, v106, v2
	v_cvt_pk_bf16_f32 v2, v2, s0
	global_store_short v[0:1], v2, off offset:3264 sc1
	v_add_f32_e32 v3, v3, v4
	v_add_f32_e32 v4, v5, v6
	v_fmamk_f32 v3, v3, 0x3c000000, v104
	v_rsq_f32_e32 v3, v3
	v_add_f32_dpp v4, v4, v4 quad_perm:[2,3,0,1] row_mask:0xf bank_mask:0xf
	v_mul_f32_e32 v0, v62, v3
	v_mul_f32_e32 v0, v109, v0
	v_cvt_pk_bf16_f32 v2, v0, s0
	v_add_co_u32_e32 v0, vcc, s66, v70
	v_add_f32_dpp v4, v4, v4 row_half_mirror row_mask:0xf bank_mask:0xf
	v_addc_co_u32_e32 v1, vcc, 0, v71, vcc
	global_store_short v[0:1], v2, off offset:2048 sc1
	v_mul_f32_e32 v2, v46, v3
	v_add_f32_dpp v4, v4, v4 row_mirror row_mask:0xf bank_mask:0xf
	v_mul_f32_e32 v2, v108, v2
	ds_bpermute_b32 v5, v110, v4
	v_cvt_pk_bf16_f32 v2, v2, s0
	global_store_short v[0:1], v2, off offset:2112 sc1
	v_mul_f32_e32 v2, v30, v3
	v_mul_f32_e32 v2, v107, v2
	v_cvt_pk_bf16_f32 v2, v2, s0
	global_store_short v[0:1], v2, off offset:2176 sc1
	v_mul_f32_e32 v2, v14, v3
	s_waitcnt lgkmcnt(0)
	v_add_f32_e32 v3, v4, v5
	v_fmamk_f32 v3, v3, 0x3c000000, v104
	v_rsq_f32_e32 v3, v3
	v_mul_f32_e32 v2, v106, v2
	v_cvt_pk_bf16_f32 v2, v2, s0
	global_store_short v[0:1], v2, off offset:2240 sc1
	v_mul_f32_e32 v0, v63, v3
	v_mul_f32_e32 v0, v109, v0
	v_cvt_pk_bf16_f32 v2, v0, s0
	v_add_co_u32_e32 v0, vcc, s67, v70
	s_nop 1
	v_addc_co_u32_e32 v1, vcc, 0, v71, vcc
	global_store_short v[0:1], v2, off offset:1024 sc1
	v_mul_f32_e32 v2, v47, v3
	v_mul_f32_e32 v2, v108, v2
	v_cvt_pk_bf16_f32 v2, v2, s0
	global_store_short v[0:1], v2, off offset:1088 sc1
	v_mul_f32_e32 v2, v31, v3
	v_mul_f32_e32 v2, v107, v2
	v_cvt_pk_bf16_f32 v2, v2, s0
	global_store_short v[0:1], v2, off offset:1152 sc1
	v_mul_f32_e32 v2, v15, v3
	v_mul_f32_e32 v2, v106, v2
	v_cvt_pk_bf16_f32 v2, v2, s0
	global_store_short v[0:1], v2, off offset:1216 sc1
	s_branch .LBB0_646

.LBB0_707:
	s_add_i32 s58, s64, 0xffffe000
	s_lshr_b32 s58, s58, 12
	s_mulk_i32 s58, 0x1800
	s_addk_i32 s58, 0x1800
	s_cmp_gt_i32 s6, 63
	s_cselect_b32 s6, s58, 0
	s_lshl_b64 s[58:59], s[6:7], 2
	v_mov_b32_e32 v70, s68
	s_add_u32 s6, s14, s58
	ds_read_b64 v[70:71], v70
	s_addc_u32 s63, s15, s59
	s_lshl_b32 s58, s69, 14
	s_add_i32 s58, s58, 0x20000
	s_ashr_i32 s59, s58, 31
	s_lshl_b64 s[58:59], s[58:59], 2
	s_add_u32 s58, s10, s58
	s_waitcnt lgkmcnt(0)
	v_readfirstlane_b32 s70, v70
	s_addc_u32 s59, s11, s59
	v_add_u32_e32 v70, s64, v141
	s_add_u32 s60, s6, 0x5ba2000
	v_lshlrev_b32_e32 v190, 10, v70
	s_addc_u32 s61, s63, 0
	v_or_b32_e32 v102, s66, v140
	v_or_b32_e32 v188, 0x400, v190
	v_or_b32_e32 v187, 0x4400, v190
	v_or_b32_e32 v191, 0x4c00, v190
	v_or_b32_e32 v195, 0x6c00, v190
	v_readfirstlane_b32 s71, v71
	s_add_u32 s62, s6, 0x5ba4000
	v_ashrrev_i32_e32 v103, 31, v102
	v_add_u32_e32 v134, v190, v102
	v_add_u32_e32 v136, v188, v102
	v_or_b32_e32 v186, 0x800, v190
	v_or_b32_e32 v185, 0xc00, v190
	v_or_b32_e32 v183, 0x2000, v190
	v_or_b32_e32 v181, 0x2400, v190
	v_or_b32_e32 v71, 0x2800, v190
	v_or_b32_e32 v182, 0x2c00, v190
	v_or_b32_e32 v184, 0x4000, v190
	v_add_u32_e32 v114, v187, v102
	v_or_b32_e32 v189, 0x4800, v190
	v_add_u32_e32 v120, v191, v102
	v_or_b32_e32 v192, 0x6000, v190
	v_or_b32_e32 v193, 0x6400, v190
	v_or_b32_e32 v194, 0x6800, v190
	v_add_u32_e32 v130, v195, v102
	s_addc_u32 s63, s63, 0
	v_lshlrev_b64 v[72:73], 2, v[102:103]
	v_ashrrev_i32_e32 v137, 31, v136
	v_add_u32_e32 v138, v186, v102
	v_add_u32_e32 v132, v185, v102
	v_add_u32_e32 v124, v183, v102
	v_add_u32_e32 v116, v181, v102
	v_add_u32_e32 v108, v71, v102
	v_add_u32_e32 v110, v182, v102
	v_add_u32_e32 v112, v184, v102
	v_ashrrev_i32_e32 v115, 31, v114
	v_add_u32_e32 v118, v189, v102
	v_ashrrev_i32_e32 v121, 31, v120
	v_add_u32_e32 v122, v192, v102
	v_add_u32_e32 v126, v193, v102
	v_add_u32_e32 v128, v194, v102
	v_ashrrev_i32_e32 v131, 31, v130
	v_ashrrev_i32_e32 v135, 31, v134
	v_lshl_add_u64 v[74:75], s[60:61], 0, v[72:73]
	v_lshl_add_u64 v[104:105], s[70:71], 0, v[72:73]
	v_lshl_add_u64 v[72:73], s[62:63], 0, v[72:73]
	v_lshl_add_u64 v[88:89], v[136:137], 2, s[12:13]
	v_ashrrev_i32_e32 v139, 31, v138
	v_ashrrev_i32_e32 v133, 31, v132
	v_ashrrev_i32_e32 v125, 31, v124
	v_ashrrev_i32_e32 v117, 31, v116
	v_ashrrev_i32_e32 v109, 31, v108
	v_ashrrev_i32_e32 v111, 31, v110
	v_ashrrev_i32_e32 v113, 31, v112
	v_lshl_add_u64 v[86:87], v[114:115], 2, s[12:13]
	v_ashrrev_i32_e32 v119, 31, v118
	v_lshl_add_u64 v[92:93], v[120:121], 2, s[12:13]
	v_ashrrev_i32_e32 v123, 31, v122
	v_ashrrev_i32_e32 v127, 31, v126
	v_ashrrev_i32_e32 v129, 31, v128
	v_lshl_add_u64 v[100:101], v[130:131], 2, s[12:13]
	v_lshl_add_u64 v[106:107], v[134:135], 2, s[12:13]
	global_load_dword v196, v[74:75], off
	global_load_dword v198, v[72:73], off
	global_load_dword v197, v[104:105], off
	v_lshl_add_u64 v[84:85], v[138:139], 2, s[12:13]
	v_lshl_add_u64 v[82:83], v[132:133], 2, s[12:13]
	v_lshl_add_u64 v[78:79], v[124:125], 2, s[12:13]
	v_lshl_add_u64 v[72:73], v[116:117], 2, s[12:13]
	v_lshl_add_u64 v[74:75], v[108:109], 2, s[12:13]
	v_lshl_add_u64 v[76:77], v[110:111], 2, s[12:13]
	v_lshl_add_u64 v[80:81], v[112:113], 2, s[12:13]
	global_load_dword v180, v[88:89], off
	global_load_dword v179, v[84:85], off
	global_load_dword v178, v[82:83], off
	global_load_dword v177, v[78:79], off
	global_load_dword v176, v[72:73], off
	global_load_dword v175, v[74:75], off
	global_load_dword v174, v[76:77], off
	global_load_dword v173, v[80:81], off
	v_lshl_add_u64 v[90:91], v[118:119], 2, s[12:13]
	global_load_dword v172, v[86:87], off
	global_load_dword v170, v[90:91], off
	v_lshl_add_u64 v[94:95], v[122:123], 2, s[12:13]
	v_lshl_add_u64 v[96:97], v[126:127], 2, s[12:13]
	v_lshl_add_u64 v[98:99], v[128:129], 2, s[12:13]
	global_load_dword v171, v[92:93], off
	global_load_dword v169, v[94:95], off
	global_load_dword v168, v[96:97], off
	global_load_dword v167, v[98:99], off
	global_load_dword v103, v[100:101], off
	global_load_dword v202, v[106:107], off
	v_lshl_add_u64 v[108:109], v[108:109], 1, s[8:9]
	s_waitcnt vmcnt(0)
	v_add_f32_e32 v198, 1.0, v198
	v_mul_f32_e32 v197, v197, v198
	v_fmac_f32_e32 v180, v49, v196
	v_fmac_f32_e32 v179, v50, v196
	v_fmac_f32_e32 v178, v51, v196
	v_fmac_f32_e32 v177, v52, v196
	v_fmac_f32_e32 v176, v53, v196
	v_fmac_f32_e32 v175, v54, v196
	v_fmac_f32_e32 v174, v55, v196
	v_fmac_f32_e32 v173, v56, v196
	v_fmac_f32_e32 v172, v57, v196
	v_fmac_f32_e32 v170, v58, v196
	v_fmac_f32_e32 v171, v59, v196
	v_fmac_f32_e32 v169, v60, v196
	v_fmac_f32_e32 v168, v61, v196
	v_fmac_f32_e32 v167, v62, v196
	v_fmac_f32_e32 v103, v63, v196
	v_fmac_f32_e32 v202, v48, v196
	v_or_b32_e32 v48, 32, v102
	v_ashrrev_i32_e32 v49, 31, v48
	v_lshlrev_b64 v[50:51], 2, v[48:49]
	global_store_dword v[88:89], v180, off sc1
	global_store_dword v[84:85], v179, off sc1
	global_store_dword v[82:83], v178, off sc1
	global_store_dword v[78:79], v177, off sc1
	global_store_dword v[72:73], v176, off sc1
	global_store_dword v[74:75], v175, off sc1
	global_store_dword v[76:77], v174, off sc1
	global_store_dword v[80:81], v173, off sc1
	global_store_dword v[86:87], v172, off sc1
	global_store_dword v[90:91], v170, off sc1
	global_store_dword v[92:93], v171, off sc1
	global_store_dword v[94:95], v169, off sc1
	global_store_dword v[96:97], v168, off sc1
	global_store_dword v[98:99], v167, off sc1
	global_store_dword v[100:101], v103, off sc1
	global_store_dword v[106:107], v202, off sc1
	v_mul_f32_e32 v54, v197, v202
	v_lshl_add_u64 v[52:53], s[60:61], 0, v[50:51]
	v_lshl_add_u64 v[50:51], s[62:63], 0, v[50:51]
	global_load_dword v198, v[106:107], off offset:128
	global_load_dword v196, v[52:53], off
	global_load_dword v203, v[50:51], off
	global_load_dword v204, v[104:105], off offset:128
	v_cvt_pk_bf16_f32 v49, v54, s0
	v_lshl_add_u64 v[50:51], v[134:135], 1, s[8:9]
	global_store_short v[50:51], v49, off sc1
	v_mul_f32_e32 v49, v197, v180
	v_cvt_pk_bf16_f32 v49, v49, s0
	v_lshl_add_u64 v[50:51], v[136:137], 1, s[8:9]
	global_store_short v[50:51], v49, off sc1
	v_mul_f32_e32 v49, v197, v179
	v_cvt_pk_bf16_f32 v49, v49, s0
	v_lshl_add_u64 v[50:51], v[138:139], 1, s[8:9]
	global_store_short v[50:51], v49, off sc1
	v_mul_f32_e32 v49, v197, v178
	v_cvt_pk_bf16_f32 v49, v49, s0
	v_lshl_add_u64 v[50:51], v[132:133], 1, s[8:9]
	global_store_short v[50:51], v49, off sc1
	v_mul_f32_e32 v49, v197, v177
	v_cvt_pk_bf16_f32 v49, v49, s0
	v_lshl_add_u64 v[50:51], v[124:125], 1, s[8:9]
	global_store_short v[50:51], v49, off sc1
	v_mul_f32_e32 v49, v197, v176
	v_cvt_pk_bf16_f32 v49, v49, s0
	v_lshl_add_u64 v[50:51], v[116:117], 1, s[8:9]
	global_store_short v[50:51], v49, off sc1
	v_mul_f32_e32 v49, v197, v175
	global_load_dword v62, v[84:85], off offset:128
	global_load_dword v60, v[78:79], off offset:128
	global_load_dword v59, v[72:73], off offset:128
	global_load_dword v58, v[74:75], off offset:128
	global_load_dword v56, v[80:81], off offset:128
	global_load_dword v57, v[76:77], off offset:128
	global_load_dword v55, v[86:87], off offset:128
	global_load_dword v61, v[82:83], off offset:128
	global_load_dword v54, v[90:91], off offset:128
	global_load_dword v53, v[92:93], off offset:128
	global_load_dword v52, v[94:95], off offset:128
	global_load_dword v51, v[96:97], off offset:128
	global_load_dword v50, v[98:99], off offset:128
	v_cvt_pk_bf16_f32 v63, v49, s0
	global_load_dword v49, v[100:101], off offset:128
	s_waitcnt vmcnt(22)
	v_fmac_f32_e32 v198, v32, v196
	global_store_short v[108:109], v63, off sc1
	global_load_dword v63, v[88:89], off offset:128
	v_mul_f32_e32 v108, v197, v174
	v_cvt_pk_bf16_f32 v116, v108, s0
	v_lshl_add_u64 v[108:109], v[110:111], 1, s[8:9]
	global_store_short v[108:109], v116, off sc1
	v_mul_f32_e32 v108, v197, v173
	v_cvt_pk_bf16_f32 v110, v108, s0
	v_lshl_add_u64 v[108:109], v[112:113], 1, s[8:9]
	global_store_short v[108:109], v110, off sc1
	v_mul_f32_e32 v108, v197, v172
	v_cvt_pk_bf16_f32 v110, v108, s0
	v_lshl_add_u64 v[108:109], v[114:115], 1, s[8:9]
	global_store_short v[108:109], v110, off sc1
	v_mul_f32_e32 v108, v197, v170
	v_cvt_pk_bf16_f32 v110, v108, s0
	v_lshl_add_u64 v[108:109], v[118:119], 1, s[8:9]
	global_store_short v[108:109], v110, off sc1
	v_mul_f32_e32 v108, v197, v171
	v_cvt_pk_bf16_f32 v110, v108, s0
	v_lshl_add_u64 v[108:109], v[120:121], 1, s[8:9]
	global_store_short v[108:109], v110, off sc1
	v_mul_f32_e32 v108, v197, v169
	v_cvt_pk_bf16_f32 v110, v108, s0
	v_lshl_add_u64 v[108:109], v[122:123], 1, s[8:9]
	global_store_short v[108:109], v110, off sc1
	v_mul_f32_e32 v108, v197, v168
	v_cvt_pk_bf16_f32 v110, v108, s0
	v_lshl_add_u64 v[108:109], v[126:127], 1, s[8:9]
	global_store_short v[108:109], v110, off sc1
	v_mul_f32_e32 v108, v197, v167
	v_cvt_pk_bf16_f32 v110, v108, s0
	v_lshl_add_u64 v[108:109], v[128:129], 1, s[8:9]
	global_store_short v[108:109], v110, off sc1
	v_mul_f32_e32 v108, v197, v103
	v_cvt_pk_bf16_f32 v110, v108, s0
	v_lshl_add_u64 v[108:109], v[130:131], 1, s[8:9]
	global_store_short v[108:109], v110, off sc1
	s_waitcnt vmcnt(32)
	v_add_f32_e32 v108, 1.0, v203
	s_waitcnt vmcnt(31)
	v_mul_f32_e32 v112, v204, v108
	v_add_u32_e32 v108, v190, v48
	s_waitcnt vmcnt(24)
	v_fmac_f32_e32 v62, v34, v196
	s_waitcnt vmcnt(17)
	v_fmac_f32_e32 v61, v35, v196
	v_fmac_f32_e32 v60, v36, v196
	v_fmac_f32_e32 v59, v37, v196
	v_fmac_f32_e32 v58, v38, v196
	v_fmac_f32_e32 v57, v39, v196
	v_fmac_f32_e32 v56, v40, v196
	v_fmac_f32_e32 v55, v41, v196
	s_waitcnt vmcnt(16)
	v_fmac_f32_e32 v54, v42, v196
	s_waitcnt vmcnt(15)
	v_fmac_f32_e32 v53, v43, v196
	s_waitcnt vmcnt(14)
	v_fmac_f32_e32 v52, v44, v196
	s_waitcnt vmcnt(13)
	v_fmac_f32_e32 v51, v45, v196
	s_waitcnt vmcnt(12)
	v_fmac_f32_e32 v50, v46, v196
	s_waitcnt vmcnt(11)
	v_fmac_f32_e32 v49, v47, v196
	v_ashrrev_i32_e32 v109, 31, v108
	global_store_dword v[106:107], v198, off offset:128 sc1
	v_mul_f32_e32 v32, v112, v198
	global_store_dword v[84:85], v62, off offset:128 sc1
	global_store_dword v[82:83], v61, off offset:128 sc1
	global_store_dword v[78:79], v60, off offset:128 sc1
	global_store_dword v[72:73], v59, off offset:128 sc1
	global_store_dword v[74:75], v58, off offset:128 sc1
	global_store_dword v[76:77], v57, off offset:128 sc1
	global_store_dword v[80:81], v56, off offset:128 sc1
	global_store_dword v[86:87], v55, off offset:128 sc1
	global_store_dword v[90:91], v54, off offset:128 sc1
	global_store_dword v[92:93], v53, off offset:128 sc1
	global_store_dword v[94:95], v52, off offset:128 sc1
	global_store_dword v[96:97], v51, off offset:128 sc1
	global_store_dword v[98:99], v50, off offset:128 sc1
	global_store_dword v[100:101], v49, off offset:128 sc1
	v_cvt_pk_bf16_f32 v32, v32, s0
	v_lshl_add_u64 v[108:109], v[108:109], 1, s[8:9]
	v_add_u32_e32 v110, v188, v48
	global_load_dword v45, v[88:89], off offset:256
	v_ashrrev_i32_e32 v111, 31, v110
	global_store_short v[108:109], v32, off sc1
	v_mul_f32_e32 v40, v112, v59
	v_mul_f32_e32 v115, v112, v56
	v_cvt_pk_bf16_f32 v115, v115, s0
	s_waitcnt vmcnt(26)
	v_fmac_f32_e32 v63, v33, v196
	v_mul_f32_e32 v32, v112, v63
	v_cvt_pk_bf16_f32 v34, v32, s0
	v_lshl_add_u64 v[32:33], v[110:111], 1, s[8:9]
	global_store_short v[32:33], v34, off sc1
	v_add_u32_e32 v32, v186, v48
	v_ashrrev_i32_e32 v33, 31, v32
	v_mul_f32_e32 v34, v112, v62
	v_cvt_pk_bf16_f32 v34, v34, s0
	v_lshl_add_u64 v[32:33], v[32:33], 1, s[8:9]
	global_store_short v[32:33], v34, off sc1
	v_add_u32_e32 v32, v185, v48
	v_ashrrev_i32_e32 v33, 31, v32
	v_mul_f32_e32 v34, v112, v61
	v_cvt_pk_bf16_f32 v34, v34, s0
	v_lshl_add_u64 v[32:33], v[32:33], 1, s[8:9]
	global_store_short v[32:33], v34, off sc1
	v_add_u32_e32 v32, v183, v48
	v_ashrrev_i32_e32 v33, 31, v32
	v_mul_f32_e32 v34, v112, v60
	v_cvt_pk_bf16_f32 v34, v34, s0
	v_lshl_add_u64 v[32:33], v[32:33], 1, s[8:9]
	global_store_short v[32:33], v34, off sc1
	v_or_b32_e32 v32, 64, v102
	v_add_u32_e32 v34, v181, v48
	v_ashrrev_i32_e32 v33, 31, v32
	v_ashrrev_i32_e32 v35, 31, v34
	v_lshlrev_b64 v[36:37], 2, v[32:33]
	global_store_dword v[88:89], v63, off offset:128 sc1
	v_lshl_add_u64 v[38:39], s[60:61], 0, v[36:37]
	v_cvt_pk_bf16_f32 v33, v40, s0
	v_lshl_add_u64 v[34:35], v[34:35], 1, s[8:9]
	v_lshl_add_u64 v[36:37], s[62:63], 0, v[36:37]
	global_load_dword v109, v[38:39], off
	global_load_dword v113, v[36:37], off
	global_load_dword v114, v[104:105], off offset:256
	global_load_dword v116, v[106:107], off offset:256
	global_load_dword v47, v[84:85], off offset:256
	global_load_dword v44, v[78:79], off offset:256
	global_load_dword v39, v[86:87], off offset:256
	global_load_dword v46, v[82:83], off offset:256
	global_load_dword v43, v[72:73], off offset:256
	global_load_dword v42, v[74:75], off offset:256
	global_load_dword v40, v[80:81], off offset:256
	global_load_dword v41, v[76:77], off offset:256
	global_load_dword v38, v[90:91], off offset:256
	global_load_dword v37, v[92:93], off offset:256
	global_load_dword v36, v[94:95], off offset:256
	v_add_u32_e32 v110, v184, v48
	global_store_short v[34:35], v33, off sc1
	v_add_u32_e32 v34, v71, v48
	v_ashrrev_i32_e32 v35, 31, v34
	v_mul_f32_e32 v33, v112, v58
	v_cvt_pk_bf16_f32 v33, v33, s0
	v_lshl_add_u64 v[34:35], v[34:35], 1, s[8:9]
	global_store_short v[34:35], v33, off sc1
	v_add_u32_e32 v34, v182, v48
	v_ashrrev_i32_e32 v35, 31, v34
	v_mul_f32_e32 v33, v112, v57
	v_cvt_pk_bf16_f32 v33, v33, s0
	v_lshl_add_u64 v[34:35], v[34:35], 1, s[8:9]
	global_store_short v[34:35], v33, off sc1
	global_load_dword v35, v[96:97], off offset:256
	v_ashrrev_i32_e32 v111, 31, v110
	global_load_dword v34, v[98:99], off offset:256
	global_load_dword v33, v[100:101], off offset:256
	v_lshl_add_u64 v[110:111], v[110:111], 1, s[8:9]
	global_store_short v[110:111], v115, off sc1
	v_add_u32_e32 v110, v187, v48
	v_ashrrev_i32_e32 v111, 31, v110
	v_mul_f32_e32 v115, v112, v55
	v_cvt_pk_bf16_f32 v115, v115, s0
	v_lshl_add_u64 v[110:111], v[110:111], 1, s[8:9]
	global_store_short v[110:111], v115, off sc1
	v_add_u32_e32 v110, v189, v48
	v_ashrrev_i32_e32 v111, 31, v110
	v_mul_f32_e32 v115, v112, v54
	v_cvt_pk_bf16_f32 v115, v115, s0
	v_lshl_add_u64 v[110:111], v[110:111], 1, s[8:9]
	global_store_short v[110:111], v115, off sc1
	v_add_u32_e32 v110, v191, v48
	v_ashrrev_i32_e32 v111, 31, v110
	v_mul_f32_e32 v115, v112, v53
	v_cvt_pk_bf16_f32 v115, v115, s0
	v_lshl_add_u64 v[110:111], v[110:111], 1, s[8:9]
	global_store_short v[110:111], v115, off sc1
	v_add_u32_e32 v110, v192, v48
	v_ashrrev_i32_e32 v111, 31, v110
	v_mul_f32_e32 v115, v112, v52
	v_cvt_pk_bf16_f32 v115, v115, s0
	v_lshl_add_u64 v[110:111], v[110:111], 1, s[8:9]
	global_store_short v[110:111], v115, off sc1
	v_add_u32_e32 v110, v193, v48
	v_ashrrev_i32_e32 v111, 31, v110
	v_mul_f32_e32 v115, v112, v51
	v_cvt_pk_bf16_f32 v115, v115, s0
	v_lshl_add_u64 v[110:111], v[110:111], 1, s[8:9]
	global_store_short v[110:111], v115, off sc1
	v_add_u32_e32 v110, v194, v48
	v_ashrrev_i32_e32 v111, 31, v110
	v_mul_f32_e32 v115, v112, v50
	v_cvt_pk_bf16_f32 v115, v115, s0
	v_lshl_add_u64 v[110:111], v[110:111], 1, s[8:9]
	global_store_short v[110:111], v115, off sc1
	v_add_u32_e32 v110, v195, v48
	v_ashrrev_i32_e32 v111, 31, v110
	v_mul_f32_e32 v48, v112, v49
	v_cvt_pk_bf16_f32 v48, v48, s0
	v_lshl_add_u64 v[110:111], v[110:111], 1, s[8:9]
	global_store_short v[110:111], v48, off sc1
	v_add_u32_e32 v110, v190, v32
	v_ashrrev_i32_e32 v111, 31, v110
	v_mul_f32_e32 v108, v198, v198
	s_waitcnt vmcnt(28)
	v_fmac_f32_e32 v45, v17, v109
	s_waitcnt vmcnt(27)
	v_add_f32_e32 v48, 1.0, v113
	s_waitcnt vmcnt(26)
	v_mul_f32_e32 v48, v114, v48
	s_waitcnt vmcnt(25)
	v_fmac_f32_e32 v116, v16, v109
	v_mul_f32_e32 v16, v48, v116
	s_waitcnt vmcnt(24)
	v_fmac_f32_e32 v47, v18, v109
	v_cvt_pk_bf16_f32 v18, v16, s0
	v_lshl_add_u64 v[16:17], v[110:111], 1, s[8:9]
	global_store_short v[16:17], v18, off sc1
	v_add_u32_e32 v16, v188, v32
	v_ashrrev_i32_e32 v17, 31, v16
	v_mul_f32_e32 v18, v48, v45
	v_cvt_pk_bf16_f32 v18, v18, s0
	v_lshl_add_u64 v[16:17], v[16:17], 1, s[8:9]
	global_store_short v[16:17], v18, off sc1
	v_add_u32_e32 v16, v186, v32
	v_ashrrev_i32_e32 v17, 31, v16
	v_mul_f32_e32 v18, v48, v47
	v_cvt_pk_bf16_f32 v18, v18, s0
	v_lshl_add_u64 v[16:17], v[16:17], 1, s[8:9]
	s_waitcnt vmcnt(23)
	v_fmac_f32_e32 v46, v19, v109
	global_store_short v[16:17], v18, off sc1
	v_add_u32_e32 v16, v185, v32
	v_ashrrev_i32_e32 v17, 31, v16
	v_mul_f32_e32 v18, v48, v46
	v_cvt_pk_bf16_f32 v18, v18, s0
	v_lshl_add_u64 v[16:17], v[16:17], 1, s[8:9]
	global_store_short v[16:17], v18, off sc1
	v_or_b32_e32 v16, 0x60, v102
	v_ashrrev_i32_e32 v17, 31, v16
	v_fmac_f32_e32 v44, v20, v109
	s_waitcnt vmcnt(24)
	v_fmac_f32_e32 v43, v21, v109
	s_waitcnt vmcnt(23)
	v_fmac_f32_e32 v42, v22, v109
	s_waitcnt vmcnt(21)
	v_fmac_f32_e32 v41, v23, v109
	v_fmac_f32_e32 v40, v24, v109
	v_fmac_f32_e32 v39, v25, v109
	s_waitcnt vmcnt(20)
	v_fmac_f32_e32 v38, v26, v109
	s_waitcnt vmcnt(19)
	v_fmac_f32_e32 v37, v27, v109
	s_waitcnt vmcnt(18)
	v_fmac_f32_e32 v36, v28, v109
	s_waitcnt vmcnt(14)
	v_fmac_f32_e32 v35, v29, v109
	s_waitcnt vmcnt(13)
	v_fmac_f32_e32 v34, v30, v109
	s_waitcnt vmcnt(12)
	v_fmac_f32_e32 v33, v31, v109
	v_lshlrev_b64 v[20:21], 2, v[16:17]
	global_store_dword v[88:89], v45, off offset:256 sc1
	global_store_dword v[84:85], v47, off offset:256 sc1
	global_store_dword v[82:83], v46, off offset:256 sc1
	global_store_dword v[78:79], v44, off offset:256 sc1
	global_store_dword v[72:73], v43, off offset:256 sc1
	global_store_dword v[74:75], v42, off offset:256 sc1
	global_store_dword v[76:77], v41, off offset:256 sc1
	global_store_dword v[80:81], v40, off offset:256 sc1
	global_store_dword v[86:87], v39, off offset:256 sc1
	global_store_dword v[90:91], v38, off offset:256 sc1
	global_store_dword v[92:93], v37, off offset:256 sc1
	global_store_dword v[94:95], v36, off offset:256 sc1
	global_store_dword v[96:97], v35, off offset:256 sc1
	global_store_dword v[98:99], v34, off offset:256 sc1
	global_store_dword v[100:101], v33, off offset:256 sc1
	global_store_dword v[106:107], v116, off offset:256 sc1
	v_lshl_add_u64 v[22:23], s[60:61], 0, v[20:21]
	v_lshl_add_u64 v[20:21], s[62:63], 0, v[20:21]
	global_load_dword v29, v[106:107], off offset:384
	global_load_dword v102, v[22:23], off
	global_load_dword v17, v[20:21], off
	s_nop 0
	global_load_dword v20, v[104:105], off offset:384
	v_add_u32_e32 v18, v183, v32
	v_ashrrev_i32_e32 v19, 31, v18
	v_mul_f32_e32 v21, v48, v44
	v_cvt_pk_bf16_f32 v21, v21, s0
	v_lshl_add_u64 v[18:19], v[18:19], 1, s[8:9]
	global_store_short v[18:19], v21, off sc1
	v_add_u32_e32 v18, v181, v32
	v_ashrrev_i32_e32 v19, 31, v18
	v_mul_f32_e32 v21, v48, v43
	v_cvt_pk_bf16_f32 v21, v21, s0
	v_lshl_add_u64 v[18:19], v[18:19], 1, s[8:9]
	global_store_short v[18:19], v21, off sc1
	v_add_u32_e32 v18, v71, v32
	v_ashrrev_i32_e32 v19, 31, v18
	v_mul_f32_e32 v21, v48, v42
	v_cvt_pk_bf16_f32 v21, v21, s0
	v_lshl_add_u64 v[18:19], v[18:19], 1, s[8:9]
	global_store_short v[18:19], v21, off sc1
	v_add_u32_e32 v18, v182, v32
	v_ashrrev_i32_e32 v19, 31, v18
	v_mul_f32_e32 v21, v48, v41
	v_cvt_pk_bf16_f32 v21, v21, s0
	v_lshl_add_u64 v[18:19], v[18:19], 1, s[8:9]
	global_store_short v[18:19], v21, off sc1
	v_add_u32_e32 v18, v184, v32
	v_ashrrev_i32_e32 v19, 31, v18
	v_mul_f32_e32 v21, v48, v40
	v_cvt_pk_bf16_f32 v21, v21, s0
	v_lshl_add_u64 v[18:19], v[18:19], 1, s[8:9]
	global_store_short v[18:19], v21, off sc1
	v_add_u32_e32 v18, v187, v32
	v_ashrrev_i32_e32 v19, 31, v18
	v_mul_f32_e32 v21, v48, v39
	v_cvt_pk_bf16_f32 v21, v21, s0
	v_lshl_add_u64 v[18:19], v[18:19], 1, s[8:9]
	global_store_short v[18:19], v21, off sc1
	v_add_u32_e32 v18, v189, v32
	v_ashrrev_i32_e32 v19, 31, v18
	v_mul_f32_e32 v21, v48, v38
	v_cvt_pk_bf16_f32 v21, v21, s0
	v_lshl_add_u64 v[18:19], v[18:19], 1, s[8:9]
	global_store_short v[18:19], v21, off sc1
	v_add_u32_e32 v18, v191, v32
	v_ashrrev_i32_e32 v19, 31, v18
	v_mul_f32_e32 v21, v48, v37
	v_cvt_pk_bf16_f32 v21, v21, s0
	v_lshl_add_u64 v[18:19], v[18:19], 1, s[8:9]
	global_store_short v[18:19], v21, off sc1
	v_add_u32_e32 v18, v192, v32
	v_ashrrev_i32_e32 v19, 31, v18
	v_mul_f32_e32 v21, v48, v36
	v_cvt_pk_bf16_f32 v21, v21, s0
	v_lshl_add_u64 v[18:19], v[18:19], 1, s[8:9]
	global_load_dword v28, v[88:89], off offset:384
	global_load_dword v27, v[84:85], off offset:384
	global_load_dword v25, v[78:79], off offset:384
	global_load_dword v24, v[72:73], off offset:384
	global_load_dword v23, v[74:75], off offset:384
	v_mul_f32_e32 v30, v48, v33
	global_store_short v[18:19], v21, off sc1
	v_add_u32_e32 v18, v193, v32
	v_ashrrev_i32_e32 v19, 31, v18
	v_mul_f32_e32 v21, v48, v35
	v_cvt_pk_bf16_f32 v21, v21, s0
	v_lshl_add_u64 v[18:19], v[18:19], 1, s[8:9]
	global_store_short v[18:19], v21, off sc1
	v_add_u32_e32 v18, v194, v32
	v_ashrrev_i32_e32 v19, 31, v18
	v_mul_f32_e32 v21, v48, v34
	v_cvt_pk_bf16_f32 v21, v21, s0
	v_lshl_add_u64 v[18:19], v[18:19], 1, s[8:9]
	global_store_short v[18:19], v21, off sc1
	v_add_u32_e32 v18, v195, v32
	global_load_dword v21, v[80:81], off offset:384
	global_load_dword v22, v[76:77], off offset:384
	v_ashrrev_i32_e32 v19, 31, v18
	v_cvt_pk_bf16_f32 v30, v30, s0
	v_lshl_add_u64 v[18:19], v[18:19], 1, s[8:9]
	s_waitcnt vmcnt(19)
	v_add_f32_e32 v17, 1.0, v17
	s_waitcnt vmcnt(18)
	v_mul_f32_e32 v32, v20, v17
	global_load_dword v20, v[86:87], off offset:384
	global_load_dword v26, v[82:83], off offset:384
	v_fmac_f32_e32 v29, v0, v102
	global_store_short v[18:19], v30, off sc1
	v_add_u32_e32 v18, v190, v16
	v_ashrrev_i32_e32 v19, 31, v18
	v_mul_f32_e32 v0, v32, v29
	v_cvt_pk_bf16_f32 v0, v0, s0
	v_lshl_add_u64 v[18:19], v[18:19], 1, s[8:9]
	global_store_short v[18:19], v0, off sc1
	global_load_dword v19, v[90:91], off offset:384
	v_add_u32_e32 v30, v188, v16
	global_load_dword v18, v[92:93], off offset:384
	v_ashrrev_i32_e32 v31, 31, v30
	v_fmac_f32_e32 v108, v202, v202
	v_fmac_f32_e32 v108, v116, v116
	v_fmac_f32_e32 v108, v29, v29
	global_store_dword v[106:107], v29, off offset:384 sc1
	s_waitcnt vmcnt(16)
	v_fmac_f32_e32 v28, v1, v102
	v_mul_f32_e32 v0, v32, v28
	v_cvt_pk_bf16_f32 v17, v0, s0
	v_lshl_add_u64 v[0:1], v[30:31], 1, s[8:9]
	global_store_short v[0:1], v17, off sc1
	v_add_u32_e32 v0, v186, v16
	s_waitcnt vmcnt(16)
	v_fmac_f32_e32 v27, v2, v102
	global_load_dword v17, v[94:95], off offset:384
	v_ashrrev_i32_e32 v1, 31, v0
	v_mul_f32_e32 v2, v32, v27
	v_cvt_pk_bf16_f32 v2, v2, s0
	v_lshl_add_u64 v[0:1], v[0:1], 1, s[8:9]
	global_store_short v[0:1], v2, off sc1
	v_add_u32_e32 v0, v185, v16
	global_load_dword v2, v[96:97], off offset:384
	v_ashrrev_i32_e32 v1, 31, v0
	v_lshl_add_u64 v[0:1], v[0:1], 1, s[8:9]
	v_add_u32_e32 v30, v183, v16
	s_waitcnt vmcnt(18)
	v_fmac_f32_e32 v25, v4, v102
	v_ashrrev_i32_e32 v31, 31, v30
	v_lshl_add_u64 v[30:31], v[30:31], 1, s[8:9]
	s_waitcnt vmcnt(17)
	v_fmac_f32_e32 v24, v5, v102
	s_waitcnt vmcnt(16)
	v_fmac_f32_e32 v23, v6, v102
	s_waitcnt vmcnt(11)
	v_fmac_f32_e32 v22, v7, v102
	v_fmac_f32_e32 v21, v8, v102
	global_store_dword v[88:89], v28, off offset:384 sc1
	global_store_dword v[84:85], v27, off offset:384 sc1
	s_waitcnt vmcnt(12)
	v_fmac_f32_e32 v20, v9, v102
	s_waitcnt vmcnt(11)
	v_fmac_f32_e32 v26, v3, v102
	v_mul_f32_e32 v3, v32, v26
	v_cvt_pk_bf16_f32 v3, v3, s0
	global_store_short v[0:1], v3, off sc1
	global_load_dword v1, v[98:99], off offset:384
	v_mul_f32_e32 v0, v32, v25
	v_cvt_pk_bf16_f32 v0, v0, s0
	global_store_short v[30:31], v0, off sc1
	global_load_dword v0, v[100:101], off offset:384
	v_add_u32_e32 v30, v181, v16
	v_ashrrev_i32_e32 v31, 31, v30
	v_mul_f32_e32 v3, v32, v24
	v_cvt_pk_bf16_f32 v3, v3, s0
	v_lshl_add_u64 v[4:5], v[30:31], 1, s[8:9]
	global_store_short v[4:5], v3, off sc1
	v_add_u32_e32 v4, v71, v16
	v_ashrrev_i32_e32 v5, 31, v4
	v_mul_f32_e32 v3, v32, v23
	v_cvt_pk_bf16_f32 v3, v3, s0
	v_lshl_add_u64 v[4:5], v[4:5], 1, s[8:9]
	global_store_short v[4:5], v3, off sc1
	v_add_u32_e32 v4, v182, v16
	v_ashrrev_i32_e32 v5, 31, v4
	v_mul_f32_e32 v3, v32, v22
	v_cvt_pk_bf16_f32 v3, v3, s0
	v_lshl_add_u64 v[4:5], v[4:5], 1, s[8:9]
	global_store_short v[4:5], v3, off sc1
	v_add_u32_e32 v4, v184, v16
	v_ashrrev_i32_e32 v5, 31, v4
	v_mul_f32_e32 v3, v32, v21
	v_cvt_pk_bf16_f32 v3, v3, s0
	v_lshl_add_u64 v[4:5], v[4:5], 1, s[8:9]
	global_store_short v[4:5], v3, off sc1
	v_add_u32_e32 v4, v187, v16
	v_ashrrev_i32_e32 v5, 31, v4
	v_mul_f32_e32 v3, v32, v20
	v_cvt_pk_bf16_f32 v3, v3, s0
	v_lshl_add_u64 v[4:5], v[4:5], 1, s[8:9]
	global_store_short v[4:5], v3, off sc1
	v_add_u32_e32 v4, v189, v16
	s_waitcnt vmcnt(17)
	v_fmac_f32_e32 v19, v10, v102
	v_ashrrev_i32_e32 v5, 31, v4
	v_mul_f32_e32 v3, v32, v19
	v_cvt_pk_bf16_f32 v3, v3, s0
	v_lshl_add_u64 v[4:5], v[4:5], 1, s[8:9]
	global_store_short v[4:5], v3, off sc1
	v_add_u32_e32 v4, v191, v16
	s_waitcnt vmcnt(17)
	v_fmac_f32_e32 v18, v11, v102
	v_ashrrev_i32_e32 v5, 31, v4
	v_mul_f32_e32 v3, v32, v18
	v_cvt_pk_bf16_f32 v3, v3, s0
	v_lshl_add_u64 v[4:5], v[4:5], 1, s[8:9]
	global_store_short v[4:5], v3, off sc1
	v_add_u32_e32 v4, v192, v16
	v_ashrrev_i32_e32 v5, 31, v4
	v_lshl_add_u64 v[4:5], v[4:5], 1, s[8:9]
	v_add_u32_e32 v10, v195, v16
	v_ashrrev_i32_e32 v11, 31, v10
	v_lshl_add_u64 v[10:11], v[10:11], 1, s[8:9]
	s_waitcnt vmcnt(15)
	v_fmac_f32_e32 v17, v12, v102
	v_mul_f32_e32 v3, v32, v17
	v_cvt_pk_bf16_f32 v3, v3, s0
	global_store_short v[4:5], v3, off sc1
	v_add_u32_e32 v4, v193, v16
	v_ashrrev_i32_e32 v5, 31, v4
	v_lshl_add_u64 v[4:5], v[4:5], 1, s[8:9]
	s_waitcnt vmcnt(14)
	v_fmac_f32_e32 v2, v13, v102
	v_mul_f32_e32 v3, v32, v2
	v_cvt_pk_bf16_f32 v3, v3, s0
	global_store_short v[4:5], v3, off sc1
	v_add_u32_e32 v4, v194, v16
	v_ashrrev_i32_e32 v5, 31, v4
	v_lshl_add_u64 v[4:5], v[4:5], 1, s[8:9]
	v_xor_b32_e32 v13, 16, v166
	v_ashrrev_i32_e32 v71, 31, v70
	global_store_dword v[82:83], v26, off offset:384 sc1
	global_store_dword v[78:79], v25, off offset:384 sc1
	global_store_dword v[72:73], v24, off offset:384 sc1
	global_store_dword v[74:75], v23, off offset:384 sc1
	global_store_dword v[76:77], v22, off offset:384 sc1
	global_store_dword v[80:81], v21, off offset:384 sc1
	global_store_dword v[86:87], v20, off offset:384 sc1
	global_store_dword v[90:91], v19, off offset:384 sc1
	global_store_dword v[92:93], v18, off offset:384 sc1
	s_waitcnt vmcnt(20)
	v_fmac_f32_e32 v1, v14, v102
	v_mul_f32_e32 v3, v32, v1
	v_cvt_pk_bf16_f32 v3, v3, s0
	global_store_short v[4:5], v3, off sc1
	v_and_b32_e32 v4, 64, v166
	v_xor_b32_e32 v3, 1, v166
	v_add_u32_e32 v7, 64, v4
	v_cmp_lt_i32_e32 vcc, v3, v7
	v_xor_b32_e32 v4, 2, v166
	s_waitcnt vmcnt(19)
	v_fmac_f32_e32 v0, v15, v102
	v_cndmask_b32_e32 v3, v166, v3, vcc
	v_lshlrev_b32_e32 v3, 2, v3
	v_cmp_lt_i32_e32 vcc, v4, v7
	v_mul_f32_e32 v12, v32, v0
	v_cvt_pk_bf16_f32 v12, v12, s0
	v_cndmask_b32_e32 v4, v166, v4, vcc
	v_lshlrev_b32_e32 v4, 2, v4
	v_add_f32_dpp v6, v108, v108 quad_perm:[1,0,3,2] row_mask:0xf bank_mask:0xf
	v_xor_b32_e32 v5, 4, v166
	v_cmp_lt_i32_e32 vcc, v5, v7
	global_store_dword v[94:95], v17, off offset:384 sc1
	global_store_dword v[96:97], v2, off offset:384 sc1
	v_cndmask_b32_e32 v5, v166, v5, vcc
	v_lshlrev_b32_e32 v5, 2, v5
	v_add_f32_dpp v8, v6, v6 quad_perm:[2,3,0,1] row_mask:0xf bank_mask:0xf
	v_xor_b32_e32 v6, 8, v166
	v_cmp_lt_i32_e32 vcc, v6, v7
	global_store_dword v[98:99], v1, off offset:384 sc1
	global_store_dword v[100:101], v0, off offset:384 sc1
	v_cndmask_b32_e32 v6, v166, v6, vcc
	v_lshlrev_b32_e32 v6, 2, v6
	v_add_f32_dpp v8, v8, v8 row_half_mirror row_mask:0xf bank_mask:0xf
	v_cmp_lt_i32_e32 vcc, v13, v7
	global_store_short v[10:11], v12, off sc1
	v_add_f32_dpp v8, v8, v8 row_mirror row_mask:0xf bank_mask:0xf
	v_cndmask_b32_e32 v7, v166, v13, vcc
	v_lshlrev_b32_e32 v7, 2, v7
	ds_bpermute_b32 v9, v7, v8
	s_and_saveexec_b64 s[60:61], s[0:1]
	s_cbranch_execz .LBB0_709
	s_waitcnt lgkmcnt(0)
	v_add_f32_e32 v10, v8, v9
	v_lshl_add_u64 v[8:9], v[70:71], 2, s[58:59]
	global_store_dword v[8:9], v10, off sc1
.LBB0_709:
	s_or_b64 exec, exec, s[60:61]
	v_mul_f32_e32 v8, v63, v63
	v_fmac_f32_e32 v8, v180, v180
	v_fmac_f32_e32 v8, v45, v45
	v_fmac_f32_e32 v8, v28, v28
	s_waitcnt lgkmcnt(0)
	v_add_f32_dpp v8, v8, v8 quad_perm:[1,0,3,2] row_mask:0xf bank_mask:0xf
	s_nop 0
	v_add_f32_dpp v8, v8, v8 quad_perm:[2,3,0,1] row_mask:0xf bank_mask:0xf
	s_nop 0
	v_add_f32_dpp v8, v8, v8 row_half_mirror row_mask:0xf bank_mask:0xf
	s_nop 0
	v_add_f32_dpp v8, v8, v8 row_mirror row_mask:0xf bank_mask:0xf
	ds_bpermute_b32 v9, v7, v8
	s_and_saveexec_b64 s[60:61], s[0:1]
	s_cbranch_execz .LBB0_711
	s_waitcnt lgkmcnt(0)
	v_add_f32_e32 v10, v8, v9
	v_lshl_add_u64 v[8:9], v[70:71], 2, s[58:59]
	global_store_dword v[8:9], v10, off offset:4 sc1
.LBB0_711:
	s_or_b64 exec, exec, s[60:61]
	v_mul_f32_e32 v8, v62, v62
	v_fmac_f32_e32 v8, v179, v179
	v_fmac_f32_e32 v8, v47, v47
	v_fmac_f32_e32 v8, v27, v27
	s_waitcnt lgkmcnt(0)
	v_add_f32_dpp v8, v8, v8 quad_perm:[1,0,3,2] row_mask:0xf bank_mask:0xf
	s_nop 0
	v_add_f32_dpp v8, v8, v8 quad_perm:[2,3,0,1] row_mask:0xf bank_mask:0xf
	s_nop 0
	v_add_f32_dpp v8, v8, v8 row_half_mirror row_mask:0xf bank_mask:0xf
	s_nop 0
	v_add_f32_dpp v8, v8, v8 row_mirror row_mask:0xf bank_mask:0xf
	ds_bpermute_b32 v9, v7, v8
	s_and_saveexec_b64 s[60:61], s[0:1]
	s_cbranch_execz .LBB0_713
	s_waitcnt lgkmcnt(0)
	v_add_f32_e32 v10, v8, v9
	v_lshl_add_u64 v[8:9], v[70:71], 2, s[58:59]
	global_store_dword v[8:9], v10, off offset:8 sc1
.LBB0_713:
	s_or_b64 exec, exec, s[60:61]
	v_mul_f32_e32 v8, v61, v61
	v_fmac_f32_e32 v8, v178, v178
	v_fmac_f32_e32 v8, v46, v46
	v_fmac_f32_e32 v8, v26, v26
	s_waitcnt lgkmcnt(0)
	v_add_f32_dpp v8, v8, v8 quad_perm:[1,0,3,2] row_mask:0xf bank_mask:0xf
	s_nop 0
	v_add_f32_dpp v8, v8, v8 quad_perm:[2,3,0,1] row_mask:0xf bank_mask:0xf
	s_nop 0
	v_add_f32_dpp v8, v8, v8 row_half_mirror row_mask:0xf bank_mask:0xf
	s_nop 0
	v_add_f32_dpp v8, v8, v8 row_mirror row_mask:0xf bank_mask:0xf
	ds_bpermute_b32 v9, v7, v8
	s_and_saveexec_b64 s[60:61], s[0:1]
	s_cbranch_execz .LBB0_715
	s_waitcnt lgkmcnt(0)
	v_add_f32_e32 v10, v8, v9
	v_lshl_add_u64 v[8:9], v[70:71], 2, s[58:59]
	global_store_dword v[8:9], v10, off offset:12 sc1
.LBB0_715:
	s_or_b64 exec, exec, s[60:61]
	v_mul_f32_e32 v8, v60, v60
	v_fmac_f32_e32 v8, v177, v177
	v_fmac_f32_e32 v8, v44, v44
	v_fmac_f32_e32 v8, v25, v25
	s_waitcnt lgkmcnt(0)
	v_add_f32_dpp v8, v8, v8 quad_perm:[1,0,3,2] row_mask:0xf bank_mask:0xf
	s_nop 0
	v_add_f32_dpp v8, v8, v8 quad_perm:[2,3,0,1] row_mask:0xf bank_mask:0xf
	s_nop 0
	v_add_f32_dpp v8, v8, v8 row_half_mirror row_mask:0xf bank_mask:0xf
	s_nop 0
	v_add_f32_dpp v8, v8, v8 row_mirror row_mask:0xf bank_mask:0xf
	ds_bpermute_b32 v9, v7, v8
	s_and_saveexec_b64 s[60:61], s[0:1]
	s_cbranch_execz .LBB0_717
	s_waitcnt lgkmcnt(0)
	v_add_f32_e32 v10, v8, v9
	v_lshl_add_u64 v[8:9], v[70:71], 2, s[58:59]
	global_store_dword v[8:9], v10, off offset:32 sc1
.LBB0_717:
	s_or_b64 exec, exec, s[60:61]
	v_mul_f32_e32 v8, v59, v59
	v_fmac_f32_e32 v8, v176, v176
	v_fmac_f32_e32 v8, v43, v43
	v_fmac_f32_e32 v8, v24, v24
	s_waitcnt lgkmcnt(0)
	v_add_f32_dpp v8, v8, v8 quad_perm:[1,0,3,2] row_mask:0xf bank_mask:0xf
	s_nop 0
	v_add_f32_dpp v8, v8, v8 quad_perm:[2,3,0,1] row_mask:0xf bank_mask:0xf
	s_nop 0
	v_add_f32_dpp v8, v8, v8 row_half_mirror row_mask:0xf bank_mask:0xf
	s_nop 0
	v_add_f32_dpp v8, v8, v8 row_mirror row_mask:0xf bank_mask:0xf
	ds_bpermute_b32 v9, v7, v8
	s_and_saveexec_b64 s[60:61], s[0:1]
	s_cbranch_execz .LBB0_719
	s_waitcnt lgkmcnt(0)
	v_add_f32_e32 v10, v8, v9
	v_lshl_add_u64 v[8:9], v[70:71], 2, s[58:59]
	global_store_dword v[8:9], v10, off offset:36 sc1
.LBB0_719:
	s_or_b64 exec, exec, s[60:61]
	v_mul_f32_e32 v8, v58, v58
	v_fmac_f32_e32 v8, v175, v175
	v_fmac_f32_e32 v8, v42, v42
	v_fmac_f32_e32 v8, v23, v23
	s_waitcnt lgkmcnt(0)
	v_add_f32_dpp v8, v8, v8 quad_perm:[1,0,3,2] row_mask:0xf bank_mask:0xf
	s_nop 0
	v_add_f32_dpp v8, v8, v8 quad_perm:[2,3,0,1] row_mask:0xf bank_mask:0xf
	s_nop 0
	v_add_f32_dpp v8, v8, v8 row_half_mirror row_mask:0xf bank_mask:0xf
	s_nop 0
	v_add_f32_dpp v8, v8, v8 row_mirror row_mask:0xf bank_mask:0xf
	ds_bpermute_b32 v9, v7, v8
	s_and_saveexec_b64 s[60:61], s[0:1]
	s_cbranch_execz .LBB0_721
	s_waitcnt lgkmcnt(0)
	v_add_f32_e32 v10, v8, v9
	v_lshl_add_u64 v[8:9], v[70:71], 2, s[58:59]
	global_store_dword v[8:9], v10, off offset:40 sc1
.LBB0_721:
	s_or_b64 exec, exec, s[60:61]
	v_mul_f32_e32 v8, v57, v57
	v_fmac_f32_e32 v8, v174, v174
	v_fmac_f32_e32 v8, v41, v41
	v_fmac_f32_e32 v8, v22, v22
	s_waitcnt lgkmcnt(0)
	v_add_f32_dpp v8, v8, v8 quad_perm:[1,0,3,2] row_mask:0xf bank_mask:0xf
	s_nop 0
	v_add_f32_dpp v8, v8, v8 quad_perm:[2,3,0,1] row_mask:0xf bank_mask:0xf
	s_nop 0
	v_add_f32_dpp v8, v8, v8 row_half_mirror row_mask:0xf bank_mask:0xf
	s_nop 0
	v_add_f32_dpp v8, v8, v8 row_mirror row_mask:0xf bank_mask:0xf
	ds_bpermute_b32 v9, v7, v8
	s_and_saveexec_b64 s[60:61], s[0:1]
	s_cbranch_execz .LBB0_723
	s_waitcnt lgkmcnt(0)
	v_add_f32_e32 v10, v8, v9
	v_lshl_add_u64 v[8:9], v[70:71], 2, s[58:59]
	global_store_dword v[8:9], v10, off offset:44 sc1
.LBB0_723:
	s_or_b64 exec, exec, s[60:61]
	v_mul_f32_e32 v8, v56, v56
	v_fmac_f32_e32 v8, v173, v173
	v_fmac_f32_e32 v8, v40, v40
	v_fmac_f32_e32 v8, v21, v21
	s_waitcnt lgkmcnt(0)
	v_add_f32_dpp v8, v8, v8 quad_perm:[1,0,3,2] row_mask:0xf bank_mask:0xf
	s_nop 0
	v_add_f32_dpp v8, v8, v8 quad_perm:[2,3,0,1] row_mask:0xf bank_mask:0xf
	s_nop 0
	v_add_f32_dpp v8, v8, v8 row_half_mirror row_mask:0xf bank_mask:0xf
	s_nop 0
	v_add_f32_dpp v8, v8, v8 row_mirror row_mask:0xf bank_mask:0xf
	ds_bpermute_b32 v9, v7, v8
	s_and_saveexec_b64 s[60:61], s[0:1]
	s_cbranch_execz .LBB0_725
	s_waitcnt lgkmcnt(0)
	v_add_f32_e32 v10, v8, v9
	v_lshl_add_u64 v[8:9], v[70:71], 2, s[58:59]
	global_store_dword v[8:9], v10, off offset:64 sc1
.LBB0_725:
	s_or_b64 exec, exec, s[60:61]
	v_mul_f32_e32 v8, v55, v55
	v_fmac_f32_e32 v8, v172, v172
	v_fmac_f32_e32 v8, v39, v39
	v_fmac_f32_e32 v8, v20, v20
	s_waitcnt lgkmcnt(0)
	v_add_f32_dpp v8, v8, v8 quad_perm:[1,0,3,2] row_mask:0xf bank_mask:0xf
	s_nop 0
	v_add_f32_dpp v8, v8, v8 quad_perm:[2,3,0,1] row_mask:0xf bank_mask:0xf
	s_nop 0
	v_add_f32_dpp v8, v8, v8 row_half_mirror row_mask:0xf bank_mask:0xf
	s_nop 0
	v_add_f32_dpp v8, v8, v8 row_mirror row_mask:0xf bank_mask:0xf
	ds_bpermute_b32 v9, v7, v8
	s_and_saveexec_b64 s[60:61], s[0:1]
	s_cbranch_execz .LBB0_727
	s_waitcnt lgkmcnt(0)
	v_add_f32_e32 v10, v8, v9
	v_lshl_add_u64 v[8:9], v[70:71], 2, s[58:59]
	global_store_dword v[8:9], v10, off offset:68 sc1
.LBB0_727:
	s_or_b64 exec, exec, s[60:61]
	v_mul_f32_e32 v8, v54, v54
	v_fmac_f32_e32 v8, v170, v170
	v_fmac_f32_e32 v8, v38, v38
	v_fmac_f32_e32 v8, v19, v19
	s_waitcnt lgkmcnt(0)
	v_add_f32_dpp v8, v8, v8 quad_perm:[1,0,3,2] row_mask:0xf bank_mask:0xf
	s_nop 0
	v_add_f32_dpp v8, v8, v8 quad_perm:[2,3,0,1] row_mask:0xf bank_mask:0xf
	s_nop 0
	v_add_f32_dpp v8, v8, v8 row_half_mirror row_mask:0xf bank_mask:0xf
	s_nop 0
	v_add_f32_dpp v8, v8, v8 row_mirror row_mask:0xf bank_mask:0xf
	ds_bpermute_b32 v9, v7, v8
	s_and_saveexec_b64 s[60:61], s[0:1]
	s_cbranch_execz .LBB0_729
	s_waitcnt lgkmcnt(0)
	v_add_f32_e32 v10, v8, v9
	v_lshl_add_u64 v[8:9], v[70:71], 2, s[58:59]
	global_store_dword v[8:9], v10, off offset:72 sc1
.LBB0_729:
	s_or_b64 exec, exec, s[60:61]
	v_mul_f32_e32 v8, v53, v53
	v_fmac_f32_e32 v8, v171, v171
	v_fmac_f32_e32 v8, v37, v37
	v_fmac_f32_e32 v8, v18, v18
	s_waitcnt lgkmcnt(0)
	v_add_f32_dpp v8, v8, v8 quad_perm:[1,0,3,2] row_mask:0xf bank_mask:0xf
	s_nop 0
	v_add_f32_dpp v8, v8, v8 quad_perm:[2,3,0,1] row_mask:0xf bank_mask:0xf
	s_nop 0
	v_add_f32_dpp v8, v8, v8 row_half_mirror row_mask:0xf bank_mask:0xf
	s_nop 0
	v_add_f32_dpp v8, v8, v8 row_mirror row_mask:0xf bank_mask:0xf
	ds_bpermute_b32 v9, v7, v8
	s_and_saveexec_b64 s[60:61], s[0:1]
	s_cbranch_execz .LBB0_731
	s_waitcnt lgkmcnt(0)
	v_add_f32_e32 v10, v8, v9
	v_lshl_add_u64 v[8:9], v[70:71], 2, s[58:59]
	global_store_dword v[8:9], v10, off offset:76 sc1
.LBB0_731:
	s_or_b64 exec, exec, s[60:61]
	v_mul_f32_e32 v8, v52, v52
	v_fmac_f32_e32 v8, v169, v169
	v_fmac_f32_e32 v8, v36, v36
	v_fmac_f32_e32 v8, v17, v17
	s_waitcnt lgkmcnt(0)
	v_add_f32_dpp v8, v8, v8 quad_perm:[1,0,3,2] row_mask:0xf bank_mask:0xf
	s_nop 0
	v_add_f32_dpp v8, v8, v8 quad_perm:[2,3,0,1] row_mask:0xf bank_mask:0xf
	s_nop 0
	v_add_f32_dpp v8, v8, v8 row_half_mirror row_mask:0xf bank_mask:0xf
	s_nop 0
	v_add_f32_dpp v8, v8, v8 row_mirror row_mask:0xf bank_mask:0xf
	ds_bpermute_b32 v9, v7, v8
	s_and_saveexec_b64 s[60:61], s[0:1]
	s_cbranch_execz .LBB0_733
	s_waitcnt lgkmcnt(0)
	v_add_f32_e32 v10, v8, v9
	v_lshl_add_u64 v[8:9], v[70:71], 2, s[58:59]
	global_store_dword v[8:9], v10, off offset:96 sc1
.LBB0_733:
	s_or_b64 exec, exec, s[60:61]
	v_mul_f32_e32 v8, v51, v51
	v_fmac_f32_e32 v8, v168, v168
	v_fmac_f32_e32 v8, v35, v35
	v_fmac_f32_e32 v8, v2, v2
	s_waitcnt lgkmcnt(0)
	s_nop 0
	v_add_f32_dpp v2, v8, v8 quad_perm:[1,0,3,2] row_mask:0xf bank_mask:0xf
	s_nop 0
	v_add_f32_dpp v2, v2, v2 quad_perm:[2,3,0,1] row_mask:0xf bank_mask:0xf
	s_nop 0
	v_add_f32_dpp v2, v2, v2 row_half_mirror row_mask:0xf bank_mask:0xf
	s_nop 0
	v_add_f32_dpp v2, v2, v2 row_mirror row_mask:0xf bank_mask:0xf
	ds_bpermute_b32 v8, v7, v2
	s_and_saveexec_b64 s[60:61], s[0:1]
	s_cbranch_execz .LBB0_735
	s_waitcnt lgkmcnt(0)
	v_add_f32_e32 v2, v2, v8
	v_lshl_add_u64 v[8:9], v[70:71], 2, s[58:59]
	global_store_dword v[8:9], v2, off offset:100 sc1
.LBB0_735:
	s_or_b64 exec, exec, s[60:61]
	v_mul_f32_e32 v2, v50, v50
	v_fmac_f32_e32 v2, v167, v167
	v_fmac_f32_e32 v2, v34, v34
	v_fmac_f32_e32 v2, v1, v1
	s_waitcnt lgkmcnt(0)
	s_nop 0
	v_add_f32_dpp v1, v2, v2 quad_perm:[1,0,3,2] row_mask:0xf bank_mask:0xf
	s_nop 0
	v_add_f32_dpp v1, v1, v1 quad_perm:[2,3,0,1] row_mask:0xf bank_mask:0xf
	s_nop 0
	v_add_f32_dpp v1, v1, v1 row_half_mirror row_mask:0xf bank_mask:0xf
	s_nop 0
	v_add_f32_dpp v1, v1, v1 row_mirror row_mask:0xf bank_mask:0xf
	ds_bpermute_b32 v2, v7, v1
	s_and_saveexec_b64 s[60:61], s[0:1]
	s_cbranch_execz .LBB0_737
	s_waitcnt lgkmcnt(0)
	v_add_f32_e32 v1, v1, v2
	v_lshl_add_u64 v[8:9], v[70:71], 2, s[58:59]
	global_store_dword v[8:9], v1, off offset:104 sc1
.LBB0_737:
	s_or_b64 exec, exec, s[60:61]
	v_mul_f32_e32 v1, v49, v49
	v_fmac_f32_e32 v1, v103, v103
	v_fmac_f32_e32 v1, v33, v33
	v_fmac_f32_e32 v1, v0, v0
	s_waitcnt lgkmcnt(0)
	s_nop 0
	v_add_f32_dpp v0, v1, v1 quad_perm:[1,0,3,2] row_mask:0xf bank_mask:0xf
	s_nop 0
	v_add_f32_dpp v0, v0, v0 quad_perm:[2,3,0,1] row_mask:0xf bank_mask:0xf
	s_nop 0
	v_add_f32_dpp v0, v0, v0 row_half_mirror row_mask:0xf bank_mask:0xf
	s_nop 0
	v_add_f32_dpp v0, v0, v0 row_mirror row_mask:0xf bank_mask:0xf
	ds_bpermute_b32 v1, v7, v0
	s_and_saveexec_b64 s[60:61], s[0:1]
	s_cbranch_execz .LBB0_702
	s_waitcnt lgkmcnt(0)
	v_add_f32_e32 v2, v0, v1
	v_lshl_add_u64 v[0:1], v[70:71], 2, s[58:59]
	global_store_dword v[0:1], v2, off offset:108 sc1
	s_branch .LBB0_702

.LBB0_779:
	s_add_i32 s58, s67, 0xffffe000
	s_lshr_b32 s58, s58, 12
	s_mulk_i32 s58, 0x1800
	s_addk_i32 s58, 0x1800
	s_cmp_gt_i32 s6, 63
	s_cselect_b32 s6, s58, 0
	s_lshl_b64 s[58:59], s[6:7], 2
	s_add_u32 s58, s14, s58
	s_addc_u32 s59, s15, s59
	s_add_u32 s60, s58, 0x5ba5000
	s_addc_u32 s61, s59, 0
	s_addk_i32 s6, 0x4800
	s_lshl_b64 s[58:59], s[6:7], 2
	v_mov_b32_e32 v70, s66
	s_add_u32 s6, s14, s58
	ds_read_b64 v[70:71], v70
	s_addc_u32 s65, s15, s59
	s_lshl_b32 s58, s64, 14
	s_add_i32 s58, s58, 0x40000
	s_ashr_i32 s59, s58, 31
	s_lshl_b64 s[58:59], s[58:59], 2
	s_add_u32 s58, s10, s58
	s_waitcnt lgkmcnt(0)
	v_readfirstlane_b32 s62, v70
	s_addc_u32 s59, s11, s59
	v_or_b32_e32 v102, s68, v138
	v_add_u32_e32 v70, s67, v139
	v_readfirstlane_b32 s63, v71
	s_add_u32 s62, s62, 0x1000
	v_ashrrev_i32_e32 v103, 31, v102
	v_lshlrev_b32_e32 v191, 10, v70
	s_addc_u32 s63, s63, 0
	v_lshlrev_b64 v[72:73], 2, v[102:103]
	v_or_b32_e32 v187, 0x400, v191
	v_or_b32_e32 v186, 0x4400, v191
	v_or_b32_e32 v189, 0x4c00, v191
	v_or_b32_e32 v194, 0x6c00, v191
	s_add_u32 s64, s6, 0x5ba1000
	v_lshl_add_u64 v[74:75], s[60:61], 0, v[72:73]
	v_add_u32_e32 v130, v191, v102
	v_add_u32_e32 v132, v187, v102
	v_or_b32_e32 v185, 0x800, v191
	v_or_b32_e32 v184, 0xc00, v191
	v_or_b32_e32 v182, 0x2000, v191
	v_or_b32_e32 v180, 0x2400, v191
	v_or_b32_e32 v71, 0x2800, v191
	v_or_b32_e32 v181, 0x2c00, v191
	v_or_b32_e32 v183, 0x4000, v191
	v_add_u32_e32 v112, v186, v102
	v_or_b32_e32 v188, 0x4800, v191
	v_add_u32_e32 v116, v189, v102
	v_or_b32_e32 v190, 0x6000, v191
	v_or_b32_e32 v192, 0x6400, v191
	v_or_b32_e32 v193, 0x6800, v191
	v_add_u32_e32 v128, v194, v102
	s_addc_u32 s65, s65, 0
	global_load_dword v195, v[74:75], off
	v_lshl_add_u64 v[74:75], s[62:63], 0, v[72:73]
	v_ashrrev_i32_e32 v133, 31, v132
	v_add_u32_e32 v134, v185, v102
	v_add_u32_e32 v136, v184, v102
	v_add_u32_e32 v126, v182, v102
	v_add_u32_e32 v118, v180, v102
	v_add_u32_e32 v110, v71, v102
	v_add_u32_e32 v106, v181, v102
	v_add_u32_e32 v108, v183, v102
	v_ashrrev_i32_e32 v113, 31, v112
	v_add_u32_e32 v114, v188, v102
	v_ashrrev_i32_e32 v117, 31, v116
	v_add_u32_e32 v120, v190, v102
	v_add_u32_e32 v122, v192, v102
	v_add_u32_e32 v124, v193, v102
	v_ashrrev_i32_e32 v129, 31, v128
	v_ashrrev_i32_e32 v131, 31, v130
	v_lshl_add_u64 v[72:73], s[64:65], 0, v[72:73]
	global_load_dword v196, v[74:75], off
	global_load_dword v197, v[72:73], off
	v_lshl_add_u64 v[88:89], v[132:133], 2, s[12:13]
	v_ashrrev_i32_e32 v135, 31, v134
	v_ashrrev_i32_e32 v137, 31, v136
	v_ashrrev_i32_e32 v127, 31, v126
	v_ashrrev_i32_e32 v119, 31, v118
	v_ashrrev_i32_e32 v111, 31, v110
	v_ashrrev_i32_e32 v107, 31, v106
	v_ashrrev_i32_e32 v109, 31, v108
	v_lshl_add_u64 v[86:87], v[112:113], 2, s[12:13]
	v_ashrrev_i32_e32 v115, 31, v114
	v_lshl_add_u64 v[92:93], v[116:117], 2, s[12:13]
	v_ashrrev_i32_e32 v121, 31, v120
	v_ashrrev_i32_e32 v123, 31, v122
	v_ashrrev_i32_e32 v125, 31, v124
	v_lshl_add_u64 v[100:101], v[128:129], 2, s[12:13]
	v_lshl_add_u64 v[104:105], v[130:131], 2, s[12:13]
	v_lshl_add_u64 v[84:85], v[134:135], 2, s[12:13]
	v_lshl_add_u64 v[82:83], v[136:137], 2, s[12:13]
	v_lshl_add_u64 v[78:79], v[126:127], 2, s[12:13]
	v_lshl_add_u64 v[72:73], v[118:119], 2, s[12:13]
	v_lshl_add_u64 v[74:75], v[110:111], 2, s[12:13]
	v_lshl_add_u64 v[76:77], v[106:107], 2, s[12:13]
	v_lshl_add_u64 v[80:81], v[108:109], 2, s[12:13]
	global_load_dword v179, v[88:89], off
	global_load_dword v178, v[84:85], off
	global_load_dword v177, v[82:83], off
	global_load_dword v176, v[78:79], off
	global_load_dword v175, v[72:73], off
	global_load_dword v174, v[74:75], off
	global_load_dword v173, v[76:77], off
	global_load_dword v172, v[80:81], off
	v_lshl_add_u64 v[90:91], v[114:115], 2, s[12:13]
	global_load_dword v171, v[86:87], off
	global_load_dword v169, v[90:91], off
	v_lshl_add_u64 v[94:95], v[120:121], 2, s[12:13]
	v_lshl_add_u64 v[96:97], v[122:123], 2, s[12:13]
	v_lshl_add_u64 v[98:99], v[124:125], 2, s[12:13]
	global_load_dword v170, v[92:93], off
	global_load_dword v168, v[94:95], off
	global_load_dword v167, v[96:97], off
	global_load_dword v166, v[98:99], off
	global_load_dword v103, v[100:101], off
	global_load_dword v198, v[104:105], off
	v_lshl_add_u64 v[110:111], v[110:111], 1, s[8:9]
	v_lshl_add_u64 v[106:107], v[106:107], 1, s[8:9]
	s_waitcnt vmcnt(0)
	v_add_f32_e32 v197, 1.0, v197
	v_mul_f32_e32 v196, v196, v197
	v_fmac_f32_e32 v179, v49, v195
	v_fmac_f32_e32 v178, v50, v195
	v_fmac_f32_e32 v177, v51, v195
	v_fmac_f32_e32 v176, v52, v195
	v_fmac_f32_e32 v175, v53, v195
	v_fmac_f32_e32 v174, v54, v195
	v_fmac_f32_e32 v173, v55, v195
	v_fmac_f32_e32 v172, v56, v195
	v_fmac_f32_e32 v171, v57, v195
	v_fmac_f32_e32 v169, v58, v195
	v_fmac_f32_e32 v170, v59, v195
	v_fmac_f32_e32 v168, v60, v195
	v_fmac_f32_e32 v167, v61, v195
	v_fmac_f32_e32 v166, v62, v195
	v_fmac_f32_e32 v103, v63, v195
	v_fmac_f32_e32 v198, v48, v195
	v_mul_f32_e32 v48, v196, v198
	v_cvt_pk_bf16_f32 v58, v48, s0
	v_or_b32_e32 v48, 32, v102
	v_ashrrev_i32_e32 v49, 31, v48
	v_lshlrev_b64 v[52:53], 2, v[48:49]
	global_store_dword v[88:89], v179, off sc1
	global_store_dword v[84:85], v178, off sc1
	global_store_dword v[82:83], v177, off sc1
	global_store_dword v[78:79], v176, off sc1
	global_store_dword v[72:73], v175, off sc1
	global_store_dword v[74:75], v174, off sc1
	global_store_dword v[76:77], v173, off sc1
	global_store_dword v[80:81], v172, off sc1
	global_store_dword v[86:87], v171, off sc1
	global_store_dword v[90:91], v169, off sc1
	global_store_dword v[92:93], v170, off sc1
	global_store_dword v[94:95], v168, off sc1
	global_store_dword v[96:97], v167, off sc1
	global_store_dword v[98:99], v166, off sc1
	global_store_dword v[100:101], v103, off sc1
	global_store_dword v[104:105], v198, off sc1
	v_lshl_add_u64 v[50:51], v[130:131], 1, s[8:9]
	v_lshl_add_u64 v[56:57], s[64:65], 0, v[52:53]
	global_load_dword v197, v[104:105], off offset:128
	v_lshl_add_u64 v[54:55], s[62:63], 0, v[52:53]
	global_load_dword v130, v[56:57], off
	global_load_dword v131, v[54:55], off
	v_mul_f32_e32 v49, v196, v179
	global_store_short v[50:51], v58, off sc1
	v_lshl_add_u64 v[50:51], s[60:61], 0, v[52:53]
	global_load_dword v195, v[50:51], off
	v_lshl_add_u64 v[50:51], v[132:133], 1, s[8:9]
	v_cvt_pk_bf16_f32 v49, v49, s0
	global_store_short v[50:51], v49, off sc1
	v_mul_f32_e32 v49, v196, v178
	v_lshl_add_u64 v[50:51], v[134:135], 1, s[8:9]
	v_cvt_pk_bf16_f32 v49, v49, s0
	global_store_short v[50:51], v49, off sc1
	v_mul_f32_e32 v49, v196, v177
	v_lshl_add_u64 v[50:51], v[136:137], 1, s[8:9]
	v_cvt_pk_bf16_f32 v49, v49, s0
	global_store_short v[50:51], v49, off sc1
	v_mul_f32_e32 v49, v196, v176
	v_lshl_add_u64 v[50:51], v[126:127], 1, s[8:9]
	v_cvt_pk_bf16_f32 v49, v49, s0
	global_store_short v[50:51], v49, off sc1
	v_mul_f32_e32 v49, v196, v175
	v_lshl_add_u64 v[50:51], v[118:119], 1, s[8:9]
	v_cvt_pk_bf16_f32 v49, v49, s0
	global_load_dword v62, v[84:85], off offset:128
	global_load_dword v60, v[78:79], off offset:128
	global_load_dword v59, v[72:73], off offset:128
	global_load_dword v58, v[74:75], off offset:128
	global_load_dword v56, v[80:81], off offset:128
	global_load_dword v57, v[76:77], off offset:128
	global_load_dword v55, v[86:87], off offset:128
	global_load_dword v61, v[82:83], off offset:128
	global_load_dword v54, v[90:91], off offset:128
	global_load_dword v53, v[92:93], off offset:128
	global_load_dword v52, v[94:95], off offset:128
	v_mul_f32_e32 v63, v196, v174
	global_store_short v[50:51], v49, off sc1
	global_load_dword v51, v[96:97], off offset:128
	v_cvt_pk_bf16_f32 v63, v63, s0
	global_load_dword v50, v[98:99], off offset:128
	global_load_dword v49, v[100:101], off offset:128
	s_waitcnt vmcnt(19)
	v_fmac_f32_e32 v197, v32, v195
	global_store_short v[110:111], v63, off sc1
	global_load_dword v63, v[88:89], off offset:128
	v_mul_f32_e32 v110, v196, v173
	v_cvt_pk_bf16_f32 v110, v110, s0
	global_store_short v[106:107], v110, off sc1
	v_lshl_add_u64 v[106:107], v[108:109], 1, s[8:9]
	v_mul_f32_e32 v108, v196, v172
	v_cvt_pk_bf16_f32 v108, v108, s0
	global_store_short v[106:107], v108, off sc1
	v_mul_f32_e32 v108, v196, v171
	v_lshl_add_u64 v[106:107], v[112:113], 1, s[8:9]
	v_cvt_pk_bf16_f32 v108, v108, s0
	global_store_short v[106:107], v108, off sc1
	v_mul_f32_e32 v108, v196, v169
	v_lshl_add_u64 v[106:107], v[114:115], 1, s[8:9]
	v_cvt_pk_bf16_f32 v108, v108, s0
	global_store_short v[106:107], v108, off sc1
	v_mul_f32_e32 v108, v196, v170
	v_lshl_add_u64 v[106:107], v[116:117], 1, s[8:9]
	v_cvt_pk_bf16_f32 v108, v108, s0
	global_store_short v[106:107], v108, off sc1
	v_mul_f32_e32 v108, v196, v168
	v_lshl_add_u64 v[106:107], v[120:121], 1, s[8:9]
	v_cvt_pk_bf16_f32 v108, v108, s0
	global_store_short v[106:107], v108, off sc1
	v_mul_f32_e32 v108, v196, v167
	v_lshl_add_u64 v[106:107], v[122:123], 1, s[8:9]
	v_cvt_pk_bf16_f32 v108, v108, s0
	global_store_short v[106:107], v108, off sc1
	v_mul_f32_e32 v108, v196, v166
	v_lshl_add_u64 v[106:107], v[124:125], 1, s[8:9]
	v_cvt_pk_bf16_f32 v108, v108, s0
	global_store_short v[106:107], v108, off sc1
	v_mul_f32_e32 v108, v196, v103
	v_lshl_add_u64 v[106:107], v[128:129], 1, s[8:9]
	v_cvt_pk_bf16_f32 v108, v108, s0
	global_store_short v[106:107], v108, off sc1
	v_add_f32_e32 v106, 1.0, v130
	v_mul_f32_e32 v107, v131, v106
	v_add_u32_e32 v108, v191, v48
	v_ashrrev_i32_e32 v109, 31, v108
	v_mul_f32_e32 v32, v107, v197
	s_waitcnt vmcnt(25)
	v_fmac_f32_e32 v62, v34, v195
	s_waitcnt vmcnt(18)
	v_fmac_f32_e32 v61, v35, v195
	v_fmac_f32_e32 v60, v36, v195
	v_fmac_f32_e32 v59, v37, v195
	v_fmac_f32_e32 v58, v38, v195
	v_fmac_f32_e32 v57, v39, v195
	v_fmac_f32_e32 v56, v40, v195
	v_fmac_f32_e32 v55, v41, v195
	s_waitcnt vmcnt(17)
	v_fmac_f32_e32 v54, v42, v195
	s_waitcnt vmcnt(16)
	v_fmac_f32_e32 v53, v43, v195
	s_waitcnt vmcnt(15)
	v_fmac_f32_e32 v52, v44, v195
	s_waitcnt vmcnt(13)
	v_fmac_f32_e32 v51, v45, v195
	s_waitcnt vmcnt(12)
	v_fmac_f32_e32 v50, v46, v195
	s_waitcnt vmcnt(11)
	v_fmac_f32_e32 v49, v47, v195
	global_store_dword v[104:105], v197, off offset:128 sc1
	v_lshl_add_u64 v[108:109], v[108:109], 1, s[8:9]
	v_cvt_pk_bf16_f32 v32, v32, s0
	global_store_dword v[84:85], v62, off offset:128 sc1
	global_store_dword v[82:83], v61, off offset:128 sc1
	global_store_dword v[78:79], v60, off offset:128 sc1
	global_store_dword v[72:73], v59, off offset:128 sc1
	global_store_dword v[74:75], v58, off offset:128 sc1
	global_store_dword v[76:77], v57, off offset:128 sc1
	global_store_dword v[80:81], v56, off offset:128 sc1
	global_store_dword v[86:87], v55, off offset:128 sc1
	global_store_dword v[90:91], v54, off offset:128 sc1
	global_store_dword v[92:93], v53, off offset:128 sc1
	global_store_dword v[94:95], v52, off offset:128 sc1
	global_store_dword v[96:97], v51, off offset:128 sc1
	global_store_dword v[98:99], v50, off offset:128 sc1
	global_store_dword v[100:101], v49, off offset:128 sc1
	global_store_short v[108:109], v32, off sc1
	v_add_u32_e32 v108, v187, v48
	global_load_dword v45, v[88:89], off offset:256
	v_ashrrev_i32_e32 v109, 31, v108
	v_mul_f32_e32 v113, v107, v56
	v_cvt_pk_bf16_f32 v113, v113, s0
	v_mul_f32_e32 v106, v197, v197
	v_fmac_f32_e32 v106, v198, v198
	s_waitcnt vmcnt(26)
	v_fmac_f32_e32 v63, v33, v195
	v_mul_f32_e32 v34, v107, v63
	v_lshl_add_u64 v[32:33], v[108:109], 1, s[8:9]
	v_cvt_pk_bf16_f32 v34, v34, s0
	global_store_short v[32:33], v34, off sc1
	v_add_u32_e32 v32, v185, v48
	v_ashrrev_i32_e32 v33, 31, v32
	v_mul_f32_e32 v34, v107, v62
	v_lshl_add_u64 v[32:33], v[32:33], 1, s[8:9]
	v_cvt_pk_bf16_f32 v34, v34, s0
	global_store_short v[32:33], v34, off sc1
	v_add_u32_e32 v32, v184, v48
	v_ashrrev_i32_e32 v33, 31, v32
	v_mul_f32_e32 v34, v107, v61
	v_lshl_add_u64 v[32:33], v[32:33], 1, s[8:9]
	v_cvt_pk_bf16_f32 v34, v34, s0
	global_store_short v[32:33], v34, off sc1
	v_add_u32_e32 v32, v182, v48
	v_ashrrev_i32_e32 v33, 31, v32
	v_mul_f32_e32 v34, v107, v60
	v_lshl_add_u64 v[32:33], v[32:33], 1, s[8:9]
	v_cvt_pk_bf16_f32 v34, v34, s0
	global_store_short v[32:33], v34, off sc1
	v_add_u32_e32 v32, v180, v48
	v_ashrrev_i32_e32 v33, 31, v32
	v_lshl_add_u64 v[34:35], v[32:33], 1, s[8:9]
	v_mul_f32_e32 v32, v107, v59
	v_cvt_pk_bf16_f32 v42, v32, s0
	v_or_b32_e32 v32, 64, v102
	v_ashrrev_i32_e32 v33, 31, v32
	v_lshlrev_b64 v[36:37], 2, v[32:33]
	global_store_dword v[88:89], v63, off offset:128 sc1
	v_lshl_add_u64 v[40:41], s[64:65], 0, v[36:37]
	v_lshl_add_u64 v[38:39], s[62:63], 0, v[36:37]
	global_load_dword v110, v[40:41], off
	global_load_dword v111, v[38:39], off
	v_mul_f32_e32 v33, v107, v58
	global_store_short v[34:35], v42, off sc1
	v_lshl_add_u64 v[34:35], s[60:61], 0, v[36:37]
	global_load_dword v112, v[34:35], off
	v_add_u32_e32 v34, v71, v48
	v_ashrrev_i32_e32 v35, 31, v34
	v_lshl_add_u64 v[34:35], v[34:35], 1, s[8:9]
	v_cvt_pk_bf16_f32 v33, v33, s0
	global_store_short v[34:35], v33, off sc1
	v_add_u32_e32 v34, v181, v48
	v_ashrrev_i32_e32 v35, 31, v34
	v_mul_f32_e32 v33, v107, v57
	v_lshl_add_u64 v[34:35], v[34:35], 1, s[8:9]
	v_cvt_pk_bf16_f32 v33, v33, s0
	global_load_dword v38, v[90:91], off offset:256
	global_load_dword v37, v[92:93], off offset:256
	global_load_dword v36, v[94:95], off offset:256
	global_load_dword v114, v[104:105], off offset:256
	global_load_dword v47, v[84:85], off offset:256
	global_load_dword v39, v[86:87], off offset:256
	global_load_dword v46, v[82:83], off offset:256
	global_load_dword v44, v[78:79], off offset:256
	global_load_dword v43, v[72:73], off offset:256
	global_load_dword v42, v[74:75], off offset:256
	global_load_dword v40, v[80:81], off offset:256
	global_load_dword v41, v[76:77], off offset:256
	v_add_u32_e32 v108, v183, v48
	global_store_short v[34:35], v33, off sc1
	global_load_dword v35, v[96:97], off offset:256
	v_ashrrev_i32_e32 v109, 31, v108
	global_load_dword v34, v[98:99], off offset:256
	global_load_dword v33, v[100:101], off offset:256
	v_lshl_add_u64 v[108:109], v[108:109], 1, s[8:9]
	global_store_short v[108:109], v113, off sc1
	v_add_u32_e32 v108, v186, v48
	v_ashrrev_i32_e32 v109, 31, v108
	v_mul_f32_e32 v113, v107, v55
	v_lshl_add_u64 v[108:109], v[108:109], 1, s[8:9]
	v_cvt_pk_bf16_f32 v113, v113, s0
	global_store_short v[108:109], v113, off sc1
	v_add_u32_e32 v108, v188, v48
	v_ashrrev_i32_e32 v109, 31, v108
	v_mul_f32_e32 v113, v107, v54
	v_lshl_add_u64 v[108:109], v[108:109], 1, s[8:9]
	v_cvt_pk_bf16_f32 v113, v113, s0
	global_store_short v[108:109], v113, off sc1
	v_add_u32_e32 v108, v189, v48
	v_ashrrev_i32_e32 v109, 31, v108
	v_mul_f32_e32 v113, v107, v53
	v_lshl_add_u64 v[108:109], v[108:109], 1, s[8:9]
	v_cvt_pk_bf16_f32 v113, v113, s0
	global_store_short v[108:109], v113, off sc1
	v_add_u32_e32 v108, v190, v48
	v_ashrrev_i32_e32 v109, 31, v108
	v_mul_f32_e32 v113, v107, v52
	v_lshl_add_u64 v[108:109], v[108:109], 1, s[8:9]
	v_cvt_pk_bf16_f32 v113, v113, s0
	global_store_short v[108:109], v113, off sc1
	v_add_u32_e32 v108, v192, v48
	v_ashrrev_i32_e32 v109, 31, v108
	v_mul_f32_e32 v113, v107, v51
	v_lshl_add_u64 v[108:109], v[108:109], 1, s[8:9]
	v_cvt_pk_bf16_f32 v113, v113, s0
	global_store_short v[108:109], v113, off sc1
	v_add_u32_e32 v108, v193, v48
	v_ashrrev_i32_e32 v109, 31, v108
	v_mul_f32_e32 v113, v107, v50
	v_lshl_add_u64 v[108:109], v[108:109], 1, s[8:9]
	v_cvt_pk_bf16_f32 v113, v113, s0
	global_store_short v[108:109], v113, off sc1
	v_add_u32_e32 v108, v194, v48
	v_ashrrev_i32_e32 v109, 31, v108
	v_mul_f32_e32 v48, v107, v49
	v_lshl_add_u64 v[108:109], v[108:109], 1, s[8:9]
	v_cvt_pk_bf16_f32 v48, v48, s0
	global_store_short v[108:109], v48, off sc1
	v_add_u32_e32 v108, v191, v32
	v_ashrrev_i32_e32 v109, 31, v108
	s_waitcnt vmcnt(28)
	v_add_f32_e32 v48, 1.0, v110
	s_waitcnt vmcnt(27)
	v_mul_f32_e32 v48, v111, v48
	s_waitcnt vmcnt(25)
	v_fmac_f32_e32 v45, v17, v112
	global_store_dword v[88:89], v45, off offset:256 sc1
	s_waitcnt vmcnt(24)
	v_fmac_f32_e32 v38, v26, v112
	s_waitcnt vmcnt(23)
	v_fmac_f32_e32 v37, v27, v112
	s_waitcnt vmcnt(22)
	v_fmac_f32_e32 v36, v28, v112
	s_waitcnt vmcnt(21)
	v_fmac_f32_e32 v114, v16, v112
	s_waitcnt vmcnt(20)
	v_fmac_f32_e32 v47, v18, v112
	v_mul_f32_e32 v18, v48, v114
	v_lshl_add_u64 v[16:17], v[108:109], 1, s[8:9]
	v_cvt_pk_bf16_f32 v18, v18, s0
	global_store_short v[16:17], v18, off sc1
	v_add_u32_e32 v16, v187, v32
	v_ashrrev_i32_e32 v17, 31, v16
	v_mul_f32_e32 v18, v48, v45
	v_lshl_add_u64 v[16:17], v[16:17], 1, s[8:9]
	v_cvt_pk_bf16_f32 v18, v18, s0
	global_store_short v[16:17], v18, off sc1
	v_add_u32_e32 v16, v185, v32
	v_ashrrev_i32_e32 v17, 31, v16
	v_mul_f32_e32 v18, v48, v47
	v_lshl_add_u64 v[16:17], v[16:17], 1, s[8:9]
	v_cvt_pk_bf16_f32 v18, v18, s0
	s_waitcnt vmcnt(20)
	v_fmac_f32_e32 v46, v19, v112
	global_store_short v[16:17], v18, off sc1
	v_add_u32_e32 v16, v184, v32
	v_ashrrev_i32_e32 v17, 31, v16
	v_mul_f32_e32 v18, v48, v46
	v_lshl_add_u64 v[16:17], v[16:17], 1, s[8:9]
	v_cvt_pk_bf16_f32 v18, v18, s0
	global_store_short v[16:17], v18, off sc1
	v_add_u32_e32 v16, v182, v32
	v_ashrrev_i32_e32 v17, 31, v16
	v_lshl_add_u64 v[18:19], v[16:17], 1, s[8:9]
	v_or_b32_e32 v16, 0x60, v102
	v_ashrrev_i32_e32 v17, 31, v16
	s_waitcnt vmcnt(21)
	v_fmac_f32_e32 v44, v20, v112
	s_waitcnt vmcnt(20)
	v_fmac_f32_e32 v43, v21, v112
	s_waitcnt vmcnt(19)
	v_fmac_f32_e32 v42, v22, v112
	s_waitcnt vmcnt(17)
	v_fmac_f32_e32 v41, v23, v112
	v_fmac_f32_e32 v40, v24, v112
	v_fmac_f32_e32 v39, v25, v112
	s_waitcnt vmcnt(15)
	v_fmac_f32_e32 v35, v29, v112
	s_waitcnt vmcnt(14)
	v_fmac_f32_e32 v34, v30, v112
	s_waitcnt vmcnt(13)
	v_fmac_f32_e32 v33, v31, v112
	v_lshlrev_b64 v[20:21], 2, v[16:17]
	global_store_dword v[84:85], v47, off offset:256 sc1
	global_store_dword v[82:83], v46, off offset:256 sc1
	global_store_dword v[78:79], v44, off offset:256 sc1
	global_store_dword v[72:73], v43, off offset:256 sc1
	global_store_dword v[74:75], v42, off offset:256 sc1
	global_store_dword v[76:77], v41, off offset:256 sc1
	global_store_dword v[80:81], v40, off offset:256 sc1
	global_store_dword v[86:87], v39, off offset:256 sc1
	global_store_dword v[90:91], v38, off offset:256 sc1
	global_store_dword v[92:93], v37, off offset:256 sc1
	global_store_dword v[94:95], v36, off offset:256 sc1
	global_store_dword v[96:97], v35, off offset:256 sc1
	global_store_dword v[98:99], v34, off offset:256 sc1
	global_store_dword v[100:101], v33, off offset:256 sc1
	global_store_dword v[104:105], v114, off offset:256 sc1
	v_mul_f32_e32 v26, v48, v44
	v_lshl_add_u64 v[22:23], s[62:63], 0, v[20:21]
	v_lshl_add_u64 v[24:25], s[64:65], 0, v[20:21]
	global_load_dword v29, v[104:105], off offset:384
	global_load_dword v17, v[24:25], off
	global_load_dword v30, v[22:23], off
	v_cvt_pk_bf16_f32 v22, v26, s0
	global_store_short v[18:19], v22, off sc1
	v_lshl_add_u64 v[18:19], s[60:61], 0, v[20:21]
	global_load_dword v102, v[18:19], off
	v_add_u32_e32 v18, v180, v32
	v_ashrrev_i32_e32 v19, 31, v18
	v_mul_f32_e32 v20, v48, v43
	v_lshl_add_u64 v[18:19], v[18:19], 1, s[8:9]
	v_cvt_pk_bf16_f32 v20, v20, s0
	global_store_short v[18:19], v20, off sc1
	v_add_u32_e32 v18, v71, v32
	v_ashrrev_i32_e32 v19, 31, v18
	v_mul_f32_e32 v20, v48, v42
	v_lshl_add_u64 v[18:19], v[18:19], 1, s[8:9]
	v_cvt_pk_bf16_f32 v20, v20, s0
	global_store_short v[18:19], v20, off sc1
	v_add_u32_e32 v18, v181, v32
	v_ashrrev_i32_e32 v19, 31, v18
	v_mul_f32_e32 v20, v48, v41
	v_lshl_add_u64 v[18:19], v[18:19], 1, s[8:9]
	v_cvt_pk_bf16_f32 v20, v20, s0
	global_store_short v[18:19], v20, off sc1
	v_add_u32_e32 v18, v183, v32
	v_ashrrev_i32_e32 v19, 31, v18
	v_mul_f32_e32 v20, v48, v40
	v_lshl_add_u64 v[18:19], v[18:19], 1, s[8:9]
	v_cvt_pk_bf16_f32 v20, v20, s0
	global_store_short v[18:19], v20, off sc1
	v_add_u32_e32 v18, v186, v32
	v_ashrrev_i32_e32 v19, 31, v18
	v_mul_f32_e32 v20, v48, v39
	v_lshl_add_u64 v[18:19], v[18:19], 1, s[8:9]
	v_cvt_pk_bf16_f32 v20, v20, s0
	global_store_short v[18:19], v20, off sc1
	v_add_u32_e32 v18, v188, v32
	v_ashrrev_i32_e32 v19, 31, v18
	v_mul_f32_e32 v20, v48, v38
	v_lshl_add_u64 v[18:19], v[18:19], 1, s[8:9]
	v_cvt_pk_bf16_f32 v20, v20, s0
	global_store_short v[18:19], v20, off sc1
	v_add_u32_e32 v18, v189, v32
	v_ashrrev_i32_e32 v19, 31, v18
	v_mul_f32_e32 v20, v48, v37
	v_lshl_add_u64 v[18:19], v[18:19], 1, s[8:9]
	v_cvt_pk_bf16_f32 v20, v20, s0
	global_store_short v[18:19], v20, off sc1
	v_add_u32_e32 v18, v190, v32
	v_ashrrev_i32_e32 v19, 31, v18
	v_mul_f32_e32 v20, v48, v36
	v_lshl_add_u64 v[18:19], v[18:19], 1, s[8:9]
	v_cvt_pk_bf16_f32 v20, v20, s0
	global_store_short v[18:19], v20, off sc1
	v_add_u32_e32 v18, v192, v32
	v_ashrrev_i32_e32 v19, 31, v18
	v_mul_f32_e32 v20, v48, v35
	v_lshl_add_u64 v[18:19], v[18:19], 1, s[8:9]
	v_cvt_pk_bf16_f32 v20, v20, s0
	global_load_dword v28, v[88:89], off offset:384
	global_load_dword v27, v[84:85], off offset:384
	global_load_dword v25, v[78:79], off offset:384
	global_load_dword v24, v[72:73], off offset:384
	global_load_dword v23, v[74:75], off offset:384
	global_load_dword v21, v[80:81], off offset:384
	global_load_dword v22, v[76:77], off offset:384
	v_fmac_f32_e32 v106, v114, v114
	global_store_short v[18:19], v20, off sc1
	v_add_u32_e32 v18, v193, v32
	v_ashrrev_i32_e32 v19, 31, v18
	v_mul_f32_e32 v20, v48, v34
	v_lshl_add_u64 v[18:19], v[18:19], 1, s[8:9]
	v_cvt_pk_bf16_f32 v20, v20, s0
	global_store_short v[18:19], v20, off sc1
	v_add_u32_e32 v18, v194, v32
	v_ashrrev_i32_e32 v19, 31, v18
	v_mul_f32_e32 v20, v48, v33
	v_lshl_add_u64 v[18:19], v[18:19], 1, s[8:9]
	v_cvt_pk_bf16_f32 v20, v20, s0
	global_store_short v[18:19], v20, off sc1
	global_load_dword v20, v[86:87], off offset:384
	s_waitcnt vmcnt(22)
	v_add_f32_e32 v17, 1.0, v17
	global_load_dword v26, v[82:83], off offset:384
	s_waitcnt vmcnt(22)
	v_mul_f32_e32 v32, v30, v17
	v_add_u32_e32 v18, v191, v16
	s_waitcnt vmcnt(20)
	v_fmac_f32_e32 v29, v0, v102
	v_ashrrev_i32_e32 v19, 31, v18
	v_mul_f32_e32 v0, v32, v29
	v_lshl_add_u64 v[18:19], v[18:19], 1, s[8:9]
	v_cvt_pk_bf16_f32 v0, v0, s0
	global_store_short v[18:19], v0, off sc1
	global_load_dword v19, v[90:91], off offset:384
	v_add_u32_e32 v30, v187, v16
	global_load_dword v18, v[92:93], off offset:384
	v_ashrrev_i32_e32 v31, 31, v30
	v_fmac_f32_e32 v106, v29, v29
	global_store_dword v[104:105], v29, off offset:384 sc1
	s_waitcnt vmcnt(15)
	v_fmac_f32_e32 v28, v1, v102
	v_mul_f32_e32 v17, v32, v28
	v_lshl_add_u64 v[0:1], v[30:31], 1, s[8:9]
	v_cvt_pk_bf16_f32 v17, v17, s0
	global_store_short v[0:1], v17, off sc1
	v_add_u32_e32 v0, v185, v16
	s_waitcnt vmcnt(15)
	v_fmac_f32_e32 v27, v2, v102
	global_load_dword v17, v[94:95], off offset:384
	v_ashrrev_i32_e32 v1, 31, v0
	v_mul_f32_e32 v2, v32, v27
	v_lshl_add_u64 v[0:1], v[0:1], 1, s[8:9]
	v_cvt_pk_bf16_f32 v2, v2, s0
	global_store_short v[0:1], v2, off sc1
	v_add_u32_e32 v0, v184, v16
	global_load_dword v2, v[96:97], off offset:384
	v_ashrrev_i32_e32 v1, 31, v0
	v_lshl_add_u64 v[0:1], v[0:1], 1, s[8:9]
	v_add_u32_e32 v30, v182, v16
	s_waitcnt vmcnt(17)
	v_fmac_f32_e32 v25, v4, v102
	v_ashrrev_i32_e32 v31, 31, v30
	v_lshl_add_u64 v[30:31], v[30:31], 1, s[8:9]
	s_waitcnt vmcnt(16)
	v_fmac_f32_e32 v24, v5, v102
	s_waitcnt vmcnt(15)
	v_fmac_f32_e32 v23, v6, v102
	s_waitcnt vmcnt(8)
	v_fmac_f32_e32 v26, v3, v102
	v_mul_f32_e32 v3, v32, v26
	v_cvt_pk_bf16_f32 v3, v3, s0
	global_store_short v[0:1], v3, off sc1
	global_load_dword v1, v[98:99], off offset:384
	v_mul_f32_e32 v0, v32, v25
	v_cvt_pk_bf16_f32 v0, v0, s0
	global_store_short v[30:31], v0, off sc1
	global_load_dword v0, v[100:101], off offset:384
	v_add_u32_e32 v30, v180, v16
	v_ashrrev_i32_e32 v31, 31, v30
	v_mul_f32_e32 v3, v32, v24
	v_lshl_add_u64 v[4:5], v[30:31], 1, s[8:9]
	v_cvt_pk_bf16_f32 v3, v3, s0
	global_store_short v[4:5], v3, off sc1
	v_add_u32_e32 v4, v71, v16
	v_ashrrev_i32_e32 v5, 31, v4
	v_mul_f32_e32 v3, v32, v23
	v_lshl_add_u64 v[4:5], v[4:5], 1, s[8:9]
	v_cvt_pk_bf16_f32 v3, v3, s0
	global_store_short v[4:5], v3, off sc1
	v_add_u32_e32 v4, v181, v16
	v_fmac_f32_e32 v22, v7, v102
	v_ashrrev_i32_e32 v5, 31, v4
	v_mul_f32_e32 v3, v32, v22
	v_lshl_add_u64 v[4:5], v[4:5], 1, s[8:9]
	v_cvt_pk_bf16_f32 v3, v3, s0
	global_store_short v[4:5], v3, off sc1
	v_add_u32_e32 v4, v183, v16
	v_fmac_f32_e32 v21, v8, v102
	v_ashrrev_i32_e32 v5, 31, v4
	v_mul_f32_e32 v3, v32, v21
	v_lshl_add_u64 v[4:5], v[4:5], 1, s[8:9]
	v_cvt_pk_bf16_f32 v3, v3, s0
	global_store_short v[4:5], v3, off sc1
	v_add_u32_e32 v4, v186, v16
	v_fmac_f32_e32 v20, v9, v102
	v_ashrrev_i32_e32 v5, 31, v4
	v_mul_f32_e32 v3, v32, v20
	v_lshl_add_u64 v[4:5], v[4:5], 1, s[8:9]
	v_cvt_pk_bf16_f32 v3, v3, s0
	global_store_short v[4:5], v3, off sc1
	v_add_u32_e32 v4, v188, v16
	s_waitcnt vmcnt(15)
	v_fmac_f32_e32 v19, v10, v102
	v_ashrrev_i32_e32 v5, 31, v4
	v_mul_f32_e32 v3, v32, v19
	v_lshl_add_u64 v[4:5], v[4:5], 1, s[8:9]
	v_cvt_pk_bf16_f32 v3, v3, s0
	global_store_short v[4:5], v3, off sc1
	v_add_u32_e32 v4, v189, v16
	s_waitcnt vmcnt(15)
	v_fmac_f32_e32 v18, v11, v102
	v_ashrrev_i32_e32 v5, 31, v4
	v_mul_f32_e32 v3, v32, v18
	v_lshl_add_u64 v[4:5], v[4:5], 1, s[8:9]
	v_cvt_pk_bf16_f32 v3, v3, s0
	global_store_short v[4:5], v3, off sc1
	v_add_u32_e32 v4, v190, v16
	v_ashrrev_i32_e32 v5, 31, v4
	v_lshl_add_u64 v[4:5], v[4:5], 1, s[8:9]
	v_ashrrev_i32_e32 v71, 31, v70
	global_store_dword v[88:89], v28, off offset:384 sc1
	global_store_dword v[84:85], v27, off offset:384 sc1
	global_store_dword v[82:83], v26, off offset:384 sc1
	global_store_dword v[78:79], v25, off offset:384 sc1
	s_waitcnt vmcnt(17)
	v_fmac_f32_e32 v17, v12, v102
	v_mul_f32_e32 v3, v32, v17
	v_cvt_pk_bf16_f32 v3, v3, s0
	global_store_short v[4:5], v3, off sc1
	v_add_u32_e32 v4, v192, v16
	v_ashrrev_i32_e32 v5, 31, v4
	v_lshl_add_u64 v[4:5], v[4:5], 1, s[8:9]
	s_waitcnt vmcnt(16)
	v_fmac_f32_e32 v2, v13, v102
	v_mul_f32_e32 v3, v32, v2
	v_cvt_pk_bf16_f32 v3, v3, s0
	global_store_short v[4:5], v3, off sc1
	v_add_u32_e32 v4, v193, v16
	v_ashrrev_i32_e32 v5, 31, v4
	v_lshl_add_u64 v[4:5], v[4:5], 1, s[8:9]
	v_xor_b32_e32 v12, 16, v165
	global_store_dword v[72:73], v24, off offset:384 sc1
	global_store_dword v[74:75], v23, off offset:384 sc1
	global_store_dword v[76:77], v22, off offset:384 sc1
	global_store_dword v[80:81], v21, off offset:384 sc1
	global_store_dword v[86:87], v20, off offset:384 sc1
	s_waitcnt vmcnt(20)
	v_fmac_f32_e32 v1, v14, v102
	v_mul_f32_e32 v3, v32, v1
	v_cvt_pk_bf16_f32 v3, v3, s0
	global_store_short v[4:5], v3, off sc1
	v_add_u32_e32 v4, v194, v16
	v_ashrrev_i32_e32 v5, 31, v4
	v_lshl_add_u64 v[10:11], v[4:5], 1, s[8:9]
	v_and_b32_e32 v4, 64, v165
	v_xor_b32_e32 v3, 1, v165
	v_add_u32_e32 v7, 64, v4
	v_cmp_lt_i32_e32 vcc, v3, v7
	v_xor_b32_e32 v4, 2, v165
	s_waitcnt vmcnt(19)
	v_fmac_f32_e32 v0, v15, v102
	v_cndmask_b32_e32 v3, v165, v3, vcc
	v_lshlrev_b32_e32 v3, 2, v3
	v_cmp_lt_i32_e32 vcc, v4, v7
	global_store_dword v[90:91], v19, off offset:384 sc1
	global_store_dword v[92:93], v18, off offset:384 sc1
	v_cndmask_b32_e32 v4, v165, v4, vcc
	v_lshlrev_b32_e32 v4, 2, v4
	v_add_f32_dpp v6, v106, v106 quad_perm:[1,0,3,2] row_mask:0xf bank_mask:0xf
	v_xor_b32_e32 v5, 4, v165
	v_cmp_lt_i32_e32 vcc, v5, v7
	global_store_dword v[94:95], v17, off offset:384 sc1
	global_store_dword v[96:97], v2, off offset:384 sc1
	v_cndmask_b32_e32 v5, v165, v5, vcc
	v_lshlrev_b32_e32 v5, 2, v5
	v_add_f32_dpp v8, v6, v6 quad_perm:[2,3,0,1] row_mask:0xf bank_mask:0xf
	v_xor_b32_e32 v6, 8, v165
	v_cmp_lt_i32_e32 vcc, v6, v7
	global_store_dword v[98:99], v1, off offset:384 sc1
	global_store_dword v[100:101], v0, off offset:384 sc1
	v_cndmask_b32_e32 v6, v165, v6, vcc
	v_lshlrev_b32_e32 v6, 2, v6
	v_add_f32_dpp v8, v8, v8 row_half_mirror row_mask:0xf bank_mask:0xf
	v_cmp_lt_i32_e32 vcc, v12, v7
	v_add_f32_dpp v8, v8, v8 row_mirror row_mask:0xf bank_mask:0xf
	v_cndmask_b32_e32 v7, v165, v12, vcc
	v_lshlrev_b32_e32 v7, 2, v7
	ds_bpermute_b32 v9, v7, v8
	v_mul_f32_e32 v12, v32, v0
	v_cvt_pk_bf16_f32 v12, v12, s0
	global_store_short v[10:11], v12, off sc1
	s_and_saveexec_b64 s[60:61], s[0:1]
	s_cbranch_execz .LBB0_781
	s_waitcnt lgkmcnt(0)
	v_add_f32_e32 v10, v8, v9
	v_lshl_add_u64 v[8:9], v[70:71], 2, s[58:59]
	global_store_dword v[8:9], v10, off sc1
.LBB0_781:
	s_or_b64 exec, exec, s[60:61]
	v_mul_f32_e32 v8, v63, v63
	v_fmac_f32_e32 v8, v179, v179
	v_fmac_f32_e32 v8, v45, v45
	v_fmac_f32_e32 v8, v28, v28
	s_waitcnt lgkmcnt(0)
	v_add_f32_dpp v8, v8, v8 quad_perm:[1,0,3,2] row_mask:0xf bank_mask:0xf
	s_nop 0
	v_add_f32_dpp v8, v8, v8 quad_perm:[2,3,0,1] row_mask:0xf bank_mask:0xf
	s_nop 0
	v_add_f32_dpp v8, v8, v8 row_half_mirror row_mask:0xf bank_mask:0xf
	s_nop 0
	v_add_f32_dpp v8, v8, v8 row_mirror row_mask:0xf bank_mask:0xf
	ds_bpermute_b32 v9, v7, v8
	s_and_saveexec_b64 s[60:61], s[0:1]
	s_cbranch_execz .LBB0_783
	s_waitcnt lgkmcnt(0)
	v_add_f32_e32 v10, v8, v9
	v_lshl_add_u64 v[8:9], v[70:71], 2, s[58:59]
	global_store_dword v[8:9], v10, off offset:4 sc1
.LBB0_783:
	s_or_b64 exec, exec, s[60:61]
	v_mul_f32_e32 v8, v62, v62
	v_fmac_f32_e32 v8, v178, v178
	v_fmac_f32_e32 v8, v47, v47
	v_fmac_f32_e32 v8, v27, v27
	s_waitcnt lgkmcnt(0)
	v_add_f32_dpp v8, v8, v8 quad_perm:[1,0,3,2] row_mask:0xf bank_mask:0xf
	s_nop 0
	v_add_f32_dpp v8, v8, v8 quad_perm:[2,3,0,1] row_mask:0xf bank_mask:0xf
	s_nop 0
	v_add_f32_dpp v8, v8, v8 row_half_mirror row_mask:0xf bank_mask:0xf
	s_nop 0
	v_add_f32_dpp v8, v8, v8 row_mirror row_mask:0xf bank_mask:0xf
	ds_bpermute_b32 v9, v7, v8
	s_and_saveexec_b64 s[60:61], s[0:1]
	s_cbranch_execz .LBB0_785
	s_waitcnt lgkmcnt(0)
	v_add_f32_e32 v10, v8, v9
	v_lshl_add_u64 v[8:9], v[70:71], 2, s[58:59]
	global_store_dword v[8:9], v10, off offset:8 sc1
.LBB0_785:
	s_or_b64 exec, exec, s[60:61]
	v_mul_f32_e32 v8, v61, v61
	v_fmac_f32_e32 v8, v177, v177
	v_fmac_f32_e32 v8, v46, v46
	v_fmac_f32_e32 v8, v26, v26
	s_waitcnt lgkmcnt(0)
	v_add_f32_dpp v8, v8, v8 quad_perm:[1,0,3,2] row_mask:0xf bank_mask:0xf
	s_nop 0
	v_add_f32_dpp v8, v8, v8 quad_perm:[2,3,0,1] row_mask:0xf bank_mask:0xf
	s_nop 0
	v_add_f32_dpp v8, v8, v8 row_half_mirror row_mask:0xf bank_mask:0xf
	s_nop 0
	v_add_f32_dpp v8, v8, v8 row_mirror row_mask:0xf bank_mask:0xf
	ds_bpermute_b32 v9, v7, v8
	s_and_saveexec_b64 s[60:61], s[0:1]
	s_cbranch_execz .LBB0_787
	s_waitcnt lgkmcnt(0)
	v_add_f32_e32 v10, v8, v9
	v_lshl_add_u64 v[8:9], v[70:71], 2, s[58:59]
	global_store_dword v[8:9], v10, off offset:12 sc1
.LBB0_787:
	s_or_b64 exec, exec, s[60:61]
	v_mul_f32_e32 v8, v60, v60
	v_fmac_f32_e32 v8, v176, v176
	v_fmac_f32_e32 v8, v44, v44
	v_fmac_f32_e32 v8, v25, v25
	s_waitcnt lgkmcnt(0)
	v_add_f32_dpp v8, v8, v8 quad_perm:[1,0,3,2] row_mask:0xf bank_mask:0xf
	s_nop 0
	v_add_f32_dpp v8, v8, v8 quad_perm:[2,3,0,1] row_mask:0xf bank_mask:0xf
	s_nop 0
	v_add_f32_dpp v8, v8, v8 row_half_mirror row_mask:0xf bank_mask:0xf
	s_nop 0
	v_add_f32_dpp v8, v8, v8 row_mirror row_mask:0xf bank_mask:0xf
	ds_bpermute_b32 v9, v7, v8
	s_and_saveexec_b64 s[60:61], s[0:1]
	s_cbranch_execz .LBB0_789
	s_waitcnt lgkmcnt(0)
	v_add_f32_e32 v10, v8, v9
	v_lshl_add_u64 v[8:9], v[70:71], 2, s[58:59]
	global_store_dword v[8:9], v10, off offset:32 sc1
.LBB0_789:
	s_or_b64 exec, exec, s[60:61]
	v_mul_f32_e32 v8, v59, v59
	v_fmac_f32_e32 v8, v175, v175
	v_fmac_f32_e32 v8, v43, v43
	v_fmac_f32_e32 v8, v24, v24
	s_waitcnt lgkmcnt(0)
	v_add_f32_dpp v8, v8, v8 quad_perm:[1,0,3,2] row_mask:0xf bank_mask:0xf
	s_nop 0
	v_add_f32_dpp v8, v8, v8 quad_perm:[2,3,0,1] row_mask:0xf bank_mask:0xf
	s_nop 0
	v_add_f32_dpp v8, v8, v8 row_half_mirror row_mask:0xf bank_mask:0xf
	s_nop 0
	v_add_f32_dpp v8, v8, v8 row_mirror row_mask:0xf bank_mask:0xf
	ds_bpermute_b32 v9, v7, v8
	s_and_saveexec_b64 s[60:61], s[0:1]
	s_cbranch_execz .LBB0_791
	s_waitcnt lgkmcnt(0)
	v_add_f32_e32 v10, v8, v9
	v_lshl_add_u64 v[8:9], v[70:71], 2, s[58:59]
	global_store_dword v[8:9], v10, off offset:36 sc1
.LBB0_791:
	s_or_b64 exec, exec, s[60:61]
	v_mul_f32_e32 v8, v58, v58
	v_fmac_f32_e32 v8, v174, v174
	v_fmac_f32_e32 v8, v42, v42
	v_fmac_f32_e32 v8, v23, v23
	s_waitcnt lgkmcnt(0)
	v_add_f32_dpp v8, v8, v8 quad_perm:[1,0,3,2] row_mask:0xf bank_mask:0xf
	s_nop 0
	v_add_f32_dpp v8, v8, v8 quad_perm:[2,3,0,1] row_mask:0xf bank_mask:0xf
	s_nop 0
	v_add_f32_dpp v8, v8, v8 row_half_mirror row_mask:0xf bank_mask:0xf
	s_nop 0
	v_add_f32_dpp v8, v8, v8 row_mirror row_mask:0xf bank_mask:0xf
	ds_bpermute_b32 v9, v7, v8
	s_and_saveexec_b64 s[60:61], s[0:1]
	s_cbranch_execz .LBB0_793
	s_waitcnt lgkmcnt(0)
	v_add_f32_e32 v10, v8, v9
	v_lshl_add_u64 v[8:9], v[70:71], 2, s[58:59]
	global_store_dword v[8:9], v10, off offset:40 sc1
.LBB0_793:
	s_or_b64 exec, exec, s[60:61]
	v_mul_f32_e32 v8, v57, v57
	v_fmac_f32_e32 v8, v173, v173
	v_fmac_f32_e32 v8, v41, v41
	v_fmac_f32_e32 v8, v22, v22
	s_waitcnt lgkmcnt(0)
	v_add_f32_dpp v8, v8, v8 quad_perm:[1,0,3,2] row_mask:0xf bank_mask:0xf
	s_nop 0
	v_add_f32_dpp v8, v8, v8 quad_perm:[2,3,0,1] row_mask:0xf bank_mask:0xf
	s_nop 0
	v_add_f32_dpp v8, v8, v8 row_half_mirror row_mask:0xf bank_mask:0xf
	s_nop 0
	v_add_f32_dpp v8, v8, v8 row_mirror row_mask:0xf bank_mask:0xf
	ds_bpermute_b32 v9, v7, v8
	s_and_saveexec_b64 s[60:61], s[0:1]
	s_cbranch_execz .LBB0_795
	s_waitcnt lgkmcnt(0)
	v_add_f32_e32 v10, v8, v9
	v_lshl_add_u64 v[8:9], v[70:71], 2, s[58:59]
	global_store_dword v[8:9], v10, off offset:44 sc1
.LBB0_795:
	s_or_b64 exec, exec, s[60:61]
	v_mul_f32_e32 v8, v56, v56
	v_fmac_f32_e32 v8, v172, v172
	v_fmac_f32_e32 v8, v40, v40
	v_fmac_f32_e32 v8, v21, v21
	s_waitcnt lgkmcnt(0)
	v_add_f32_dpp v8, v8, v8 quad_perm:[1,0,3,2] row_mask:0xf bank_mask:0xf
	s_nop 0
	v_add_f32_dpp v8, v8, v8 quad_perm:[2,3,0,1] row_mask:0xf bank_mask:0xf
	s_nop 0
	v_add_f32_dpp v8, v8, v8 row_half_mirror row_mask:0xf bank_mask:0xf
	s_nop 0
	v_add_f32_dpp v8, v8, v8 row_mirror row_mask:0xf bank_mask:0xf
	ds_bpermute_b32 v9, v7, v8
	s_and_saveexec_b64 s[60:61], s[0:1]
	s_cbranch_execz .LBB0_797
	s_waitcnt lgkmcnt(0)
	v_add_f32_e32 v10, v8, v9
	v_lshl_add_u64 v[8:9], v[70:71], 2, s[58:59]
	global_store_dword v[8:9], v10, off offset:64 sc1
.LBB0_797:
	s_or_b64 exec, exec, s[60:61]
	v_mul_f32_e32 v8, v55, v55
	v_fmac_f32_e32 v8, v171, v171
	v_fmac_f32_e32 v8, v39, v39
	v_fmac_f32_e32 v8, v20, v20
	s_waitcnt lgkmcnt(0)
	v_add_f32_dpp v8, v8, v8 quad_perm:[1,0,3,2] row_mask:0xf bank_mask:0xf
	s_nop 0
	v_add_f32_dpp v8, v8, v8 quad_perm:[2,3,0,1] row_mask:0xf bank_mask:0xf
	s_nop 0
	v_add_f32_dpp v8, v8, v8 row_half_mirror row_mask:0xf bank_mask:0xf
	s_nop 0
	v_add_f32_dpp v8, v8, v8 row_mirror row_mask:0xf bank_mask:0xf
	ds_bpermute_b32 v9, v7, v8
	s_and_saveexec_b64 s[60:61], s[0:1]
	s_cbranch_execz .LBB0_799
	s_waitcnt lgkmcnt(0)
	v_add_f32_e32 v10, v8, v9
	v_lshl_add_u64 v[8:9], v[70:71], 2, s[58:59]
	global_store_dword v[8:9], v10, off offset:68 sc1
.LBB0_799:
	s_or_b64 exec, exec, s[60:61]
	v_mul_f32_e32 v8, v54, v54
	v_fmac_f32_e32 v8, v169, v169
	v_fmac_f32_e32 v8, v38, v38
	v_fmac_f32_e32 v8, v19, v19
	s_waitcnt lgkmcnt(0)
	v_add_f32_dpp v8, v8, v8 quad_perm:[1,0,3,2] row_mask:0xf bank_mask:0xf
	s_nop 0
	v_add_f32_dpp v8, v8, v8 quad_perm:[2,3,0,1] row_mask:0xf bank_mask:0xf
	s_nop 0
	v_add_f32_dpp v8, v8, v8 row_half_mirror row_mask:0xf bank_mask:0xf
	s_nop 0
	v_add_f32_dpp v8, v8, v8 row_mirror row_mask:0xf bank_mask:0xf
	ds_bpermute_b32 v9, v7, v8
	s_and_saveexec_b64 s[60:61], s[0:1]
	s_cbranch_execz .LBB0_801
	s_waitcnt lgkmcnt(0)
	v_add_f32_e32 v10, v8, v9
	v_lshl_add_u64 v[8:9], v[70:71], 2, s[58:59]
	global_store_dword v[8:9], v10, off offset:72 sc1
.LBB0_801:
	s_or_b64 exec, exec, s[60:61]
	v_mul_f32_e32 v8, v53, v53
	v_fmac_f32_e32 v8, v170, v170
	v_fmac_f32_e32 v8, v37, v37
	v_fmac_f32_e32 v8, v18, v18
	s_waitcnt lgkmcnt(0)
	v_add_f32_dpp v8, v8, v8 quad_perm:[1,0,3,2] row_mask:0xf bank_mask:0xf
	s_nop 0
	v_add_f32_dpp v8, v8, v8 quad_perm:[2,3,0,1] row_mask:0xf bank_mask:0xf
	s_nop 0
	v_add_f32_dpp v8, v8, v8 row_half_mirror row_mask:0xf bank_mask:0xf
	s_nop 0
	v_add_f32_dpp v8, v8, v8 row_mirror row_mask:0xf bank_mask:0xf
	ds_bpermute_b32 v9, v7, v8
	s_and_saveexec_b64 s[60:61], s[0:1]
	s_cbranch_execz .LBB0_803
	s_waitcnt lgkmcnt(0)
	v_add_f32_e32 v10, v8, v9
	v_lshl_add_u64 v[8:9], v[70:71], 2, s[58:59]
	global_store_dword v[8:9], v10, off offset:76 sc1
.LBB0_803:
	s_or_b64 exec, exec, s[60:61]
	v_mul_f32_e32 v8, v52, v52
	v_fmac_f32_e32 v8, v168, v168
	v_fmac_f32_e32 v8, v36, v36
	v_fmac_f32_e32 v8, v17, v17
	s_waitcnt lgkmcnt(0)
	v_add_f32_dpp v8, v8, v8 quad_perm:[1,0,3,2] row_mask:0xf bank_mask:0xf
	s_nop 0
	v_add_f32_dpp v8, v8, v8 quad_perm:[2,3,0,1] row_mask:0xf bank_mask:0xf
	s_nop 0
	v_add_f32_dpp v8, v8, v8 row_half_mirror row_mask:0xf bank_mask:0xf
	s_nop 0
	v_add_f32_dpp v8, v8, v8 row_mirror row_mask:0xf bank_mask:0xf
	ds_bpermute_b32 v9, v7, v8
	s_and_saveexec_b64 s[60:61], s[0:1]
	s_cbranch_execz .LBB0_805
	s_waitcnt lgkmcnt(0)
	v_add_f32_e32 v10, v8, v9
	v_lshl_add_u64 v[8:9], v[70:71], 2, s[58:59]
	global_store_dword v[8:9], v10, off offset:96 sc1
.LBB0_805:
	s_or_b64 exec, exec, s[60:61]
	v_mul_f32_e32 v8, v51, v51
	v_fmac_f32_e32 v8, v167, v167
	v_fmac_f32_e32 v8, v35, v35
	v_fmac_f32_e32 v8, v2, v2
	s_waitcnt lgkmcnt(0)
	s_nop 0
	v_add_f32_dpp v2, v8, v8 quad_perm:[1,0,3,2] row_mask:0xf bank_mask:0xf
	s_nop 0
	v_add_f32_dpp v2, v2, v2 quad_perm:[2,3,0,1] row_mask:0xf bank_mask:0xf
	s_nop 0
	v_add_f32_dpp v2, v2, v2 row_half_mirror row_mask:0xf bank_mask:0xf
	s_nop 0
	v_add_f32_dpp v2, v2, v2 row_mirror row_mask:0xf bank_mask:0xf
	ds_bpermute_b32 v8, v7, v2
	s_and_saveexec_b64 s[60:61], s[0:1]
	s_cbranch_execz .LBB0_807
	s_waitcnt lgkmcnt(0)
	v_add_f32_e32 v2, v2, v8
	v_lshl_add_u64 v[8:9], v[70:71], 2, s[58:59]
	global_store_dword v[8:9], v2, off offset:100 sc1
.LBB0_807:
	s_or_b64 exec, exec, s[60:61]
	v_mul_f32_e32 v2, v50, v50
	v_fmac_f32_e32 v2, v166, v166
	v_fmac_f32_e32 v2, v34, v34
	v_fmac_f32_e32 v2, v1, v1
	s_waitcnt lgkmcnt(0)
	s_nop 0
	v_add_f32_dpp v1, v2, v2 quad_perm:[1,0,3,2] row_mask:0xf bank_mask:0xf
	s_nop 0
	v_add_f32_dpp v1, v1, v1 quad_perm:[2,3,0,1] row_mask:0xf bank_mask:0xf
	s_nop 0
	v_add_f32_dpp v1, v1, v1 row_half_mirror row_mask:0xf bank_mask:0xf
	s_nop 0
	v_add_f32_dpp v1, v1, v1 row_mirror row_mask:0xf bank_mask:0xf
	ds_bpermute_b32 v2, v7, v1
	s_and_saveexec_b64 s[60:61], s[0:1]
	s_cbranch_execz .LBB0_809
	s_waitcnt lgkmcnt(0)
	v_add_f32_e32 v1, v1, v2
	v_lshl_add_u64 v[8:9], v[70:71], 2, s[58:59]
	global_store_dword v[8:9], v1, off offset:104 sc1

.LBB0_846:
	s_and_b64 vcc, exec, s[0:1]
	s_cbranch_vccz .LBB0_827
	v_mov_b32_e32 v10, s84
	ds_read_b64 v[10:11], v10
	s_lshl_b32 s0, s8, 6
	s_ashr_i32 s1, s0, 31
	s_lshl_b64 s[0:1], s[0:1], 2
	v_and_b32_e32 v15, 64, v204
	s_waitcnt lgkmcnt(0)
	v_readfirstlane_b32 s70, v10
	v_readfirstlane_b32 s71, v11
	s_add_u32 s0, s70, s0
	s_addc_u32 s1, s71, s1
	global_load_dword v11, v197, s[0:1]
	global_load_dword v10, v197, s[0:1] offset:128
	v_xor_b32_e32 v14, 1, v204
	v_add_u32_e32 v15, 64, v15
	v_pk_mul_f32 v[12:13], v[86:87], v[86:87]
	v_cmp_lt_i32_e32 vcc, v14, v15
	v_add_f32_e32 v12, v13, v12
	s_cmp_eq_u32 s8, 1
	v_cndmask_b32_e32 v13, v204, v14, vcc
	v_lshlrev_b32_e32 v100, 2, v13
	v_xor_b32_e32 v14, 2, v204
	v_cmp_lt_i32_e32 vcc, v14, v15
	s_cselect_b64 s[0:1], -1, 0
	s_xor_b64 s[70:71], s[4:5], -1
	v_cndmask_b32_e32 v14, v204, v14, vcc
	v_lshlrev_b32_e32 v101, 2, v14
	v_add_f32_dpp v12, v12, v12 quad_perm:[1,0,3,2] row_mask:0xf bank_mask:0xf
	v_xor_b32_e32 v14, 4, v204
	v_cmp_lt_i32_e32 vcc, v14, v15
	s_and_b64 s[70:71], s[70:71], s[0:1]
	v_lshl_or_b32 v134, s72, 7, v140
	v_cndmask_b32_e32 v14, v204, v14, vcc
	v_lshlrev_b32_e32 v102, 2, v14
	v_add_f32_dpp v12, v12, v12 quad_perm:[2,3,0,1] row_mask:0xf bank_mask:0xf
	v_xor_b32_e32 v14, 8, v204
	v_cmp_lt_i32_e32 vcc, v14, v15
	v_add_f32_dpp v12, v12, v12 row_half_mirror row_mask:0xf bank_mask:0xf
	v_cndmask_b32_e32 v14, v204, v14, vcc
	v_lshlrev_b32_e32 v103, 2, v14
	v_xor_b32_e32 v14, 16, v204
	v_cmp_lt_i32_e32 vcc, v14, v15
	v_add_f32_dpp v12, v12, v12 row_mirror row_mask:0xf bank_mask:0xf
	v_cndmask_b32_e32 v14, v204, v14, vcc
	v_lshlrev_b32_e32 v104, 2, v14
	v_mov_b32_e32 v13, v12
	s_nop 1
	v_permlane16_swap_b32_e32 v12, v13
	s_nop 0
	s_and_b64 vcc, exec, s[70:71]
	v_add_f32_e32 v12, v12, v13
	v_fmamk_f32 v12, v12, 0x3c800000, v196
	v_rsq_f32_e32 v12, v12
	v_add_u32_e32 v144, s69, v160
	v_lshl_or_b32 v144, v144, 5, v140
	v_lshlrev_b32_e32 v144, 3, v144
	global_load_dwordx2 v[144:145], v144, s[24:25]
	v_add_u32_e32 v146, s69, v168
	v_lshl_or_b32 v146, v146, 5, v140
	v_lshlrev_b32_e32 v146, 3, v146
	global_load_dwordx2 v[146:147], v146, s[24:25]
	v_add_u32_e32 v184, s69, v169
	v_lshl_or_b32 v184, v184, 5, v140
	v_lshlrev_b32_e32 v184, 3, v184
	global_load_dwordx2 v[184:185], v184, s[24:25]
	v_add_u32_e32 v186, s69, v170
	v_lshl_or_b32 v186, v186, 5, v140
	v_lshlrev_b32_e32 v186, 3, v186
	global_load_dwordx2 v[186:187], v186, s[24:25]
	v_add_u32_e32 v226, s69, v171
	v_lshl_or_b32 v226, v226, 5, v140
	v_lshlrev_b32_e32 v226, 3, v226
	global_load_dwordx2 v[226:227], v226, s[24:25]
	v_add_u32_e32 v230, s69, v172
	v_lshl_or_b32 v230, v230, 5, v140
	v_lshlrev_b32_e32 v230, 3, v230
	global_load_dwordx2 v[230:231], v230, s[24:25]
	v_add_u32_e32 v232, s69, v173
	v_lshl_or_b32 v232, v232, 5, v140
	v_lshlrev_b32_e32 v232, 3, v232
	global_load_dwordx2 v[232:233], v232, s[24:25]
	v_add_u32_e32 v234, s69, v174
	v_lshl_or_b32 v234, v234, 5, v140
	v_lshlrev_b32_e32 v234, 3, v234
	global_load_dwordx2 v[234:235], v234, s[24:25]
	v_add_u32_e32 v236, s69, v175
	v_lshl_or_b32 v236, v236, 5, v140
	v_lshlrev_b32_e32 v236, 3, v236
	global_load_dwordx2 v[236:237], v236, s[24:25]
	v_add_u32_e32 v238, s69, v176
	v_lshl_or_b32 v238, v238, 5, v140
	v_lshlrev_b32_e32 v238, 3, v238
	global_load_dwordx2 v[238:239], v238, s[24:25]
	v_add_u32_e32 v240, s69, v177
	v_lshl_or_b32 v240, v240, 5, v140
	v_lshlrev_b32_e32 v240, 3, v240
	global_load_dwordx2 v[240:241], v240, s[24:25]
	v_add_u32_e32 v242, s69, v178
	v_lshl_or_b32 v242, v242, 5, v140
	v_lshlrev_b32_e32 v242, 3, v242
	global_load_dwordx2 v[242:243], v242, s[24:25]
	v_add_u32_e32 v244, s69, v179
	v_lshl_or_b32 v244, v244, 5, v140
	v_lshlrev_b32_e32 v244, 3, v244
	global_load_dwordx2 v[244:245], v244, s[24:25]
	v_add_u32_e32 v246, s69, v180
	v_lshl_or_b32 v246, v246, 5, v140
	v_lshlrev_b32_e32 v246, 3, v246
	global_load_dwordx2 v[246:247], v246, s[24:25]
	v_add_u32_e32 v248, s69, v181
	v_lshl_or_b32 v248, v248, 5, v140
	v_lshlrev_b32_e32 v248, 3, v248
	global_load_dwordx2 v[248:249], v248, s[24:25]
	v_add_u32_e32 v250, s69, v182
	v_lshl_or_b32 v250, v250, 5, v140
	v_lshlrev_b32_e32 v250, 3, v250
	global_load_dwordx2 v[250:251], v250, s[24:25]
	s_waitcnt vmcnt(0)
	v_pk_mul_f32 v[12:13], v[10:11], v[12:13] op_sel_hi:[1,0]
	s_nop 0
	v_pk_mul_f32 v[14:15], v[86:87], v[12:13]
	s_cbranch_vccz .LBB0_849
	v_lshl_or_b32 v12, v148, 10, v134
	v_ashrrev_i32_e32 v13, 31, v12
	v_lshl_add_u64 v[12:13], v[12:13], 2, s[26:27]
	global_store_dword v[12:13], v15, off sc1
	global_store_dword v[12:13], v14, off offset:128 sc1

.LBB0_851:
	v_pk_mul_f32 v[24:25], v[82:83], v[82:83]
	v_cvt_pk_bf16_f32 v28, v14, s0
	v_add_f32_e32 v13, v25, v24
	s_cmp_lt_u32 s86, 8
	s_cselect_b64 s[4:5], -1, 0
	s_and_b64 s[4:5], s[4:5], exec
	s_cselect_b32 s8, s68, s74
	s_waitcnt lgkmcnt(0)
	v_add_f32_dpp v13, v13, v13 quad_perm:[1,0,3,2] row_mask:0xf bank_mask:0xf
	s_cselect_b32 s4, s85, 0xdf9f000
	s_add_u32 s4, s14, s4
	s_addc_u32 s5, s15, 0
	v_cvt_pk_bf16_f32 v25, v15, s0
	v_add_f32_dpp v13, v13, v13 quad_perm:[2,3,0,1] row_mask:0xf bank_mask:0xf
	v_add_u32_e32 v15, s68, v168
	s_and_b64 vcc, exec, s[70:71]
	v_add_f32_dpp v13, v13, v13 row_half_mirror row_mask:0xf bank_mask:0xf
	v_add_lshl_u32 v24, s8, v160, 10
	v_or_b32_e32 v26, v24, v134
	v_ashrrev_i32_e32 v27, 31, v26
	v_lshl_add_u64 v[26:27], v[26:27], 1, s[4:5]
	v_add_f32_dpp v13, v13, v13 row_mirror row_mask:0xf bank_mask:0xf
	v_mov_b32_e32 v14, v13
	s_nop 1
	v_permlane16_swap_b32_e32 v13, v14
	s_nop 0
	global_store_short v[26:27], v25, off sc1
	global_store_short v[26:27], v28, off offset:64 sc1
	v_add_f32_e32 v13, v13, v14
	v_fmamk_f32 v13, v13, 0x3c800000, v196
	v_rsq_f32_e32 v14, v13
	s_nop 0
	v_pk_mul_f32 v[26:27], v[10:11], v[14:15] op_sel_hi:[1,0]
	s_nop 0
	v_pk_mul_f32 v[28:29], v[82:83], v[26:27]
	s_cbranch_vccz .LBB0_853
	v_lshl_or_b32 v26, v15, 10, v134
	v_ashrrev_i32_e32 v27, 31, v26
	v_lshl_add_u64 v[26:27], v[26:27], 2, s[26:27]
	global_store_dword v[26:27], v29, off sc1
	global_store_dword v[26:27], v28, off offset:128 sc1

.LBB0_855:
	v_pk_mul_f32 v[30:31], v[78:79], v[78:79]
	v_cvt_pk_bf16_f32 v58, v28, s0
	v_add_f32_e32 v13, v31, v30
	v_cvt_pk_bf16_f32 v27, v29, s0
	v_add_u32_e32 v29, s68, v169
	s_and_b64 vcc, exec, s[70:71]
	s_waitcnt lgkmcnt(0)
	v_add_f32_dpp v13, v13, v13 quad_perm:[1,0,3,2] row_mask:0xf bank_mask:0xf
	s_nop 0
	v_add_f32_dpp v13, v13, v13 quad_perm:[2,3,0,1] row_mask:0xf bank_mask:0xf
	s_nop 0
	v_add_f32_dpp v13, v13, v13 row_half_mirror row_mask:0xf bank_mask:0xf
	v_add_lshl_u32 v14, s8, v168, 10
	v_or_b32_e32 v30, v14, v134
	v_ashrrev_i32_e32 v31, 31, v30
	v_lshl_add_u64 v[30:31], v[30:31], 1, s[4:5]
	v_add_f32_dpp v13, v13, v13 row_mirror row_mask:0xf bank_mask:0xf
	v_mov_b32_e32 v25, v13
	s_nop 1
	v_permlane16_swap_b32_e32 v13, v25
	s_nop 0
	global_store_short v[30:31], v27, off sc1
	global_store_short v[30:31], v58, off offset:64 sc1
	v_add_f32_e32 v13, v13, v25
	v_fmamk_f32 v13, v13, 0x3c800000, v196
	v_rsq_f32_e32 v28, v13
	s_nop 0
	v_pk_mul_f32 v[30:31], v[10:11], v[28:29] op_sel_hi:[1,0]
	s_nop 0
	v_pk_mul_f32 v[58:59], v[78:79], v[30:31]
	s_cbranch_vccz .LBB0_857
	v_lshl_or_b32 v30, v29, 10, v134
	v_ashrrev_i32_e32 v31, 31, v30
	v_lshl_add_u64 v[30:31], v[30:31], 2, s[26:27]
	global_store_dword v[30:31], v59, off sc1
	global_store_dword v[30:31], v58, off offset:128 sc1

.LBB0_859:
	v_pk_mul_f32 v[60:61], v[74:75], v[74:75]
	v_add_lshl_u32 v28, s8, v169, 10
	v_add_f32_e32 v13, v61, v60
	v_cvt_pk_bf16_f32 v31, v58, s0
	v_or_b32_e32 v60, v28, v134
	v_ashrrev_i32_e32 v61, 31, v60
	v_cvt_pk_bf16_f32 v27, v59, s0
	s_waitcnt lgkmcnt(0)
	v_add_f32_dpp v13, v13, v13 quad_perm:[1,0,3,2] row_mask:0xf bank_mask:0xf
	v_add_u32_e32 v59, s68, v170
	v_lshl_add_u64 v[60:61], v[60:61], 1, s[4:5]
	global_store_short v[60:61], v27, off sc1
	global_store_short v[60:61], v31, off offset:64 sc1
	s_and_b64 vcc, exec, s[70:71]
	v_add_f32_dpp v13, v13, v13 quad_perm:[2,3,0,1] row_mask:0xf bank_mask:0xf
	s_nop 0
	v_add_f32_dpp v13, v13, v13 row_half_mirror row_mask:0xf bank_mask:0xf
	s_nop 0
	v_add_f32_dpp v13, v13, v13 row_mirror row_mask:0xf bank_mask:0xf
	v_mov_b32_e32 v25, v13
	s_nop 1
	v_permlane16_swap_b32_e32 v13, v25
	s_nop 0
	v_add_f32_e32 v13, v13, v25
	v_fmamk_f32 v13, v13, 0x3c800000, v196
	v_rsq_f32_e32 v58, v13
	s_nop 0
	v_pk_mul_f32 v[60:61], v[10:11], v[58:59] op_sel_hi:[1,0]
	s_nop 0
	v_pk_mul_f32 v[62:63], v[74:75], v[60:61]
	s_cbranch_vccz .LBB0_861
	v_lshl_or_b32 v60, v59, 10, v134
	v_ashrrev_i32_e32 v61, 31, v60
	v_lshl_add_u64 v[60:61], v[60:61], 2, s[26:27]
	global_store_dword v[60:61], v63, off sc1
	global_store_dword v[60:61], v62, off offset:128 sc1

.LBB0_863:
	v_pk_mul_f32 v[74:75], v[70:71], v[70:71]
	v_add_lshl_u32 v58, s8, v170, 10
	v_add_f32_e32 v13, v75, v74
	v_cvt_pk_bf16_f32 v31, v62, s0
	v_or_b32_e32 v74, v58, v134
	v_ashrrev_i32_e32 v75, 31, v74
	v_cvt_pk_bf16_f32 v27, v63, s0
	s_waitcnt lgkmcnt(0)
	v_add_f32_dpp v13, v13, v13 quad_perm:[1,0,3,2] row_mask:0xf bank_mask:0xf
	v_add_u32_e32 v63, s68, v171
	v_lshl_add_u64 v[74:75], v[74:75], 1, s[4:5]
	global_store_short v[74:75], v27, off sc1
	global_store_short v[74:75], v31, off offset:64 sc1
	s_and_b64 vcc, exec, s[70:71]
	v_add_f32_dpp v13, v13, v13 quad_perm:[2,3,0,1] row_mask:0xf bank_mask:0xf
	s_nop 0
	v_add_f32_dpp v13, v13, v13 row_half_mirror row_mask:0xf bank_mask:0xf
	s_nop 0
	v_add_f32_dpp v13, v13, v13 row_mirror row_mask:0xf bank_mask:0xf
	v_mov_b32_e32 v25, v13
	s_nop 1
	v_permlane16_swap_b32_e32 v13, v25
	s_nop 0
	v_add_f32_e32 v13, v13, v25
	v_fmamk_f32 v13, v13, 0x3c800000, v196
	v_rsq_f32_e32 v62, v13
	s_nop 0
	v_pk_mul_f32 v[74:75], v[10:11], v[62:63] op_sel_hi:[1,0]
	s_nop 0
	v_pk_mul_f32 v[74:75], v[70:71], v[74:75]
	s_cbranch_vccz .LBB0_865
	v_lshl_or_b32 v70, v63, 10, v134
	v_ashrrev_i32_e32 v71, 31, v70
	v_lshl_add_u64 v[70:71], v[70:71], 2, s[26:27]
	global_store_dword v[70:71], v75, off sc1
	global_store_dword v[70:71], v74, off offset:128 sc1

.LBB0_867:
	v_pk_mul_f32 v[78:79], v[72:73], v[72:73]
	v_add_lshl_u32 v62, s8, v171, 10
	v_add_f32_e32 v13, v79, v78
	v_cvt_pk_bf16_f32 v31, v74, s0
	v_or_b32_e32 v74, v62, v134
	v_cvt_pk_bf16_f32 v27, v75, s0
	v_ashrrev_i32_e32 v75, 31, v74
	s_waitcnt lgkmcnt(0)
	v_add_f32_dpp v13, v13, v13 quad_perm:[1,0,3,2] row_mask:0xf bank_mask:0xf
	v_lshl_add_u64 v[74:75], v[74:75], 1, s[4:5]
	global_store_short v[74:75], v27, off sc1
	global_store_short v[74:75], v31, off offset:64 sc1
	s_and_b64 vcc, exec, s[70:71]
	v_add_u32_e32 v105, s68, v172
	v_add_f32_dpp v13, v13, v13 quad_perm:[2,3,0,1] row_mask:0xf bank_mask:0xf
	s_nop 0
	v_add_f32_dpp v13, v13, v13 row_half_mirror row_mask:0xf bank_mask:0xf
	s_nop 0
	v_add_f32_dpp v13, v13, v13 row_mirror row_mask:0xf bank_mask:0xf
	v_mov_b32_e32 v25, v13
	s_nop 1
	v_permlane16_swap_b32_e32 v13, v25
	s_nop 0
	v_add_f32_e32 v13, v13, v25
	v_fmamk_f32 v13, v13, 0x3c800000, v196
	v_rsq_f32_e32 v78, v13
	s_nop 0
	v_pk_mul_f32 v[74:75], v[10:11], v[78:79] op_sel_hi:[1,0]
	s_nop 0
	v_pk_mul_f32 v[78:79], v[72:73], v[74:75]
	s_cbranch_vccz .LBB0_869
	v_lshl_or_b32 v72, v105, 10, v134
	v_ashrrev_i32_e32 v73, 31, v72
	v_lshl_add_u64 v[72:73], v[72:73], 2, s[26:27]
	global_store_dword v[72:73], v79, off sc1
	global_store_dword v[72:73], v78, off offset:128 sc1

.LBB0_871:
	v_pk_mul_f32 v[72:73], v[76:77], v[76:77]
	v_cvt_pk_bf16_f32 v31, v78, s0
	v_add_f32_e32 v13, v73, v72
	v_add_lshl_u32 v72, s8, v172, 10
	v_or_b32_e32 v78, v72, v134
	v_cvt_pk_bf16_f32 v27, v79, s0
	v_ashrrev_i32_e32 v79, 31, v78
	s_waitcnt lgkmcnt(0)
	v_add_f32_dpp v13, v13, v13 quad_perm:[1,0,3,2] row_mask:0xf bank_mask:0xf
	v_lshl_add_u64 v[78:79], v[78:79], 1, s[4:5]
	global_store_short v[78:79], v27, off sc1
	global_store_short v[78:79], v31, off offset:64 sc1
	s_and_b64 vcc, exec, s[70:71]
	v_add_u32_e32 v106, s68, v173
	v_add_f32_dpp v13, v13, v13 quad_perm:[2,3,0,1] row_mask:0xf bank_mask:0xf
	s_nop 0
	v_add_f32_dpp v13, v13, v13 row_half_mirror row_mask:0xf bank_mask:0xf
	s_nop 0
	v_add_f32_dpp v13, v13, v13 row_mirror row_mask:0xf bank_mask:0xf
	v_mov_b32_e32 v25, v13
	s_nop 1
	v_permlane16_swap_b32_e32 v13, v25
	s_nop 0
	v_add_f32_e32 v13, v13, v25
	v_fmamk_f32 v13, v13, 0x3c800000, v196
	v_rsq_f32_e32 v80, v13
	s_nop 0
	v_pk_mul_f32 v[78:79], v[10:11], v[80:81] op_sel_hi:[1,0]
	s_nop 0
	v_pk_mul_f32 v[80:81], v[76:77], v[78:79]
	s_cbranch_vccz .LBB0_873
	v_lshl_or_b32 v76, v106, 10, v134
	v_ashrrev_i32_e32 v77, 31, v76
	v_lshl_add_u64 v[76:77], v[76:77], 2, s[26:27]
	global_store_dword v[76:77], v81, off sc1
	global_store_dword v[76:77], v80, off offset:128 sc1

.LBB0_875:
	v_pk_mul_f32 v[76:77], v[68:69], v[68:69]
	v_cvt_pk_bf16_f32 v31, v80, s0
	v_add_f32_e32 v13, v77, v76
	v_add_lshl_u32 v76, s8, v173, 10
	v_or_b32_e32 v80, v76, v134
	v_cvt_pk_bf16_f32 v27, v81, s0
	v_ashrrev_i32_e32 v81, 31, v80
	s_waitcnt lgkmcnt(0)
	v_add_f32_dpp v13, v13, v13 quad_perm:[1,0,3,2] row_mask:0xf bank_mask:0xf
	v_lshl_add_u64 v[80:81], v[80:81], 1, s[4:5]
	global_store_short v[80:81], v27, off sc1
	global_store_short v[80:81], v31, off offset:64 sc1
	s_and_b64 vcc, exec, s[70:71]
	v_add_u32_e32 v107, s68, v174
	v_add_f32_dpp v13, v13, v13 quad_perm:[2,3,0,1] row_mask:0xf bank_mask:0xf
	s_nop 0
	v_add_f32_dpp v13, v13, v13 row_half_mirror row_mask:0xf bank_mask:0xf
	s_nop 0
	v_add_f32_dpp v13, v13, v13 row_mirror row_mask:0xf bank_mask:0xf
	v_mov_b32_e32 v25, v13
	s_nop 1
	v_permlane16_swap_b32_e32 v13, v25
	s_nop 0
	v_add_f32_e32 v13, v13, v25
	v_fmamk_f32 v13, v13, 0x3c800000, v196
	v_rsq_f32_e32 v82, v13
	s_nop 0
	v_pk_mul_f32 v[80:81], v[10:11], v[82:83] op_sel_hi:[1,0]
	s_nop 0
	v_pk_mul_f32 v[82:83], v[68:69], v[80:81]
	s_cbranch_vccz .LBB0_877
	v_lshl_or_b32 v68, v107, 10, v134
	v_ashrrev_i32_e32 v69, 31, v68
	v_lshl_add_u64 v[68:69], v[68:69], 2, s[26:27]
	global_store_dword v[68:69], v83, off sc1
	global_store_dword v[68:69], v82, off offset:128 sc1

.LBB0_879:
	v_pk_mul_f32 v[68:69], v[66:67], v[66:67]
	v_cvt_pk_bf16_f32 v31, v82, s0
	v_add_f32_e32 v13, v69, v68
	v_add_lshl_u32 v68, s8, v174, 10
	v_or_b32_e32 v82, v68, v134
	v_cvt_pk_bf16_f32 v27, v83, s0
	v_ashrrev_i32_e32 v83, 31, v82
	s_waitcnt lgkmcnt(0)
	v_add_f32_dpp v13, v13, v13 quad_perm:[1,0,3,2] row_mask:0xf bank_mask:0xf
	v_lshl_add_u64 v[82:83], v[82:83], 1, s[4:5]
	global_store_short v[82:83], v27, off sc1
	global_store_short v[82:83], v31, off offset:64 sc1
	s_and_b64 vcc, exec, s[70:71]
	v_add_u32_e32 v108, s68, v175
	v_add_f32_dpp v13, v13, v13 quad_perm:[2,3,0,1] row_mask:0xf bank_mask:0xf
	s_nop 0
	v_add_f32_dpp v13, v13, v13 row_half_mirror row_mask:0xf bank_mask:0xf
	s_nop 0
	v_add_f32_dpp v13, v13, v13 row_mirror row_mask:0xf bank_mask:0xf
	v_mov_b32_e32 v25, v13
	s_nop 1
	v_permlane16_swap_b32_e32 v13, v25
	s_nop 0
	v_add_f32_e32 v13, v13, v25
	v_fmamk_f32 v13, v13, 0x3c800000, v196
	v_rsq_f32_e32 v84, v13
	s_nop 0
	v_pk_mul_f32 v[82:83], v[10:11], v[84:85] op_sel_hi:[1,0]
	s_nop 0
	v_pk_mul_f32 v[84:85], v[66:67], v[82:83]
	s_cbranch_vccz .LBB0_881
	v_lshl_or_b32 v66, v108, 10, v134
	v_ashrrev_i32_e32 v67, 31, v66
	v_lshl_add_u64 v[66:67], v[66:67], 2, s[26:27]
	global_store_dword v[66:67], v85, off sc1
	global_store_dword v[66:67], v84, off offset:128 sc1

.LBB0_883:
	v_pk_mul_f32 v[66:67], v[64:65], v[64:65]
	v_cvt_pk_bf16_f32 v31, v84, s0
	v_add_f32_e32 v13, v67, v66
	v_add_lshl_u32 v66, s8, v175, 10
	v_or_b32_e32 v84, v66, v134
	v_cvt_pk_bf16_f32 v27, v85, s0
	v_ashrrev_i32_e32 v85, 31, v84
	s_waitcnt lgkmcnt(0)
	v_add_f32_dpp v13, v13, v13 quad_perm:[1,0,3,2] row_mask:0xf bank_mask:0xf
	v_lshl_add_u64 v[84:85], v[84:85], 1, s[4:5]
	global_store_short v[84:85], v27, off sc1
	global_store_short v[84:85], v31, off offset:64 sc1
	s_and_b64 vcc, exec, s[70:71]
	v_add_u32_e32 v109, s68, v176
	v_add_f32_dpp v13, v13, v13 quad_perm:[2,3,0,1] row_mask:0xf bank_mask:0xf
	s_nop 0
	v_add_f32_dpp v13, v13, v13 row_half_mirror row_mask:0xf bank_mask:0xf
	s_nop 0
	v_add_f32_dpp v13, v13, v13 row_mirror row_mask:0xf bank_mask:0xf
	v_mov_b32_e32 v25, v13
	s_nop 1
	v_permlane16_swap_b32_e32 v13, v25
	s_nop 0
	v_add_f32_e32 v13, v13, v25
	v_fmamk_f32 v13, v13, 0x3c800000, v196
	v_rsq_f32_e32 v86, v13
	s_nop 0
	v_pk_mul_f32 v[84:85], v[10:11], v[86:87] op_sel_hi:[1,0]
	s_nop 0
	v_pk_mul_f32 v[86:87], v[64:65], v[84:85]
	s_cbranch_vccz .LBB0_885
	v_lshl_or_b32 v64, v109, 10, v134
	v_ashrrev_i32_e32 v65, 31, v64
	v_lshl_add_u64 v[64:65], v[64:65], 2, s[26:27]
	global_store_dword v[64:65], v87, off sc1
	global_store_dword v[64:65], v86, off offset:128 sc1

.LBB0_887:
	v_pk_mul_f32 v[64:65], v[56:57], v[56:57]
	v_cvt_pk_bf16_f32 v31, v86, s0
	v_add_f32_e32 v13, v65, v64
	v_add_lshl_u32 v64, s8, v176, 10
	v_or_b32_e32 v86, v64, v134
	v_cvt_pk_bf16_f32 v27, v87, s0
	v_ashrrev_i32_e32 v87, 31, v86
	s_waitcnt lgkmcnt(0)
	v_add_f32_dpp v13, v13, v13 quad_perm:[1,0,3,2] row_mask:0xf bank_mask:0xf
	v_lshl_add_u64 v[86:87], v[86:87], 1, s[4:5]
	global_store_short v[86:87], v27, off sc1
	global_store_short v[86:87], v31, off offset:64 sc1
	s_and_b64 vcc, exec, s[70:71]
	v_add_u32_e32 v110, s68, v177
	v_add_f32_dpp v13, v13, v13 quad_perm:[2,3,0,1] row_mask:0xf bank_mask:0xf
	s_nop 0
	v_add_f32_dpp v13, v13, v13 row_half_mirror row_mask:0xf bank_mask:0xf
	s_nop 0
	v_add_f32_dpp v13, v13, v13 row_mirror row_mask:0xf bank_mask:0xf
	v_mov_b32_e32 v25, v13
	s_nop 1
	v_permlane16_swap_b32_e32 v13, v25
	s_nop 0
	v_add_f32_e32 v13, v13, v25
	v_fmamk_f32 v13, v13, 0x3c800000, v196
	v_rsq_f32_e32 v88, v13
	s_nop 0
	v_pk_mul_f32 v[86:87], v[10:11], v[88:89] op_sel_hi:[1,0]
	s_nop 0
	v_pk_mul_f32 v[88:89], v[56:57], v[86:87]
	s_cbranch_vccz .LBB0_889
	v_lshl_or_b32 v56, v110, 10, v134
	v_ashrrev_i32_e32 v57, 31, v56
	v_lshl_add_u64 v[56:57], v[56:57], 2, s[26:27]
	global_store_dword v[56:57], v89, off sc1
	global_store_dword v[56:57], v88, off offset:128 sc1

.LBB0_891:
	v_pk_mul_f32 v[56:57], v[54:55], v[54:55]
	v_cvt_pk_bf16_f32 v31, v88, s0
	v_add_f32_e32 v13, v57, v56
	v_add_lshl_u32 v56, s8, v177, 10
	v_or_b32_e32 v88, v56, v134
	v_cvt_pk_bf16_f32 v27, v89, s0
	v_ashrrev_i32_e32 v89, 31, v88
	s_waitcnt lgkmcnt(0)
	v_add_f32_dpp v13, v13, v13 quad_perm:[1,0,3,2] row_mask:0xf bank_mask:0xf
	v_lshl_add_u64 v[88:89], v[88:89], 1, s[4:5]
	global_store_short v[88:89], v27, off sc1
	global_store_short v[88:89], v31, off offset:64 sc1
	s_and_b64 vcc, exec, s[70:71]
	v_add_u32_e32 v111, s68, v178
	v_add_f32_dpp v13, v13, v13 quad_perm:[2,3,0,1] row_mask:0xf bank_mask:0xf
	s_nop 0
	v_add_f32_dpp v13, v13, v13 row_half_mirror row_mask:0xf bank_mask:0xf
	s_nop 0
	v_add_f32_dpp v13, v13, v13 row_mirror row_mask:0xf bank_mask:0xf
	v_mov_b32_e32 v25, v13
	s_nop 1
	v_permlane16_swap_b32_e32 v13, v25
	s_nop 0
	v_add_f32_e32 v13, v13, v25
	v_fmamk_f32 v13, v13, 0x3c800000, v196
	v_rsq_f32_e32 v90, v13
	s_nop 0
	v_pk_mul_f32 v[88:89], v[10:11], v[90:91] op_sel_hi:[1,0]
	s_nop 0
	v_pk_mul_f32 v[90:91], v[54:55], v[88:89]
	s_cbranch_vccz .LBB0_893
	v_lshl_or_b32 v54, v111, 10, v134
	v_ashrrev_i32_e32 v55, 31, v54
	v_lshl_add_u64 v[54:55], v[54:55], 2, s[26:27]
	global_store_dword v[54:55], v91, off sc1
	global_store_dword v[54:55], v90, off offset:128 sc1

.LBB0_895:
	v_pk_mul_f32 v[54:55], v[52:53], v[52:53]
	v_cvt_pk_bf16_f32 v31, v90, s0
	v_add_f32_e32 v13, v55, v54
	v_add_lshl_u32 v54, s8, v178, 10
	v_or_b32_e32 v90, v54, v134
	v_cvt_pk_bf16_f32 v27, v91, s0
	v_ashrrev_i32_e32 v91, 31, v90
	s_waitcnt lgkmcnt(0)
	v_add_f32_dpp v13, v13, v13 quad_perm:[1,0,3,2] row_mask:0xf bank_mask:0xf
	v_lshl_add_u64 v[90:91], v[90:91], 1, s[4:5]
	global_store_short v[90:91], v27, off sc1
	global_store_short v[90:91], v31, off offset:64 sc1
	s_and_b64 vcc, exec, s[70:71]
	v_add_u32_e32 v112, s68, v179
	v_add_f32_dpp v13, v13, v13 quad_perm:[2,3,0,1] row_mask:0xf bank_mask:0xf
	s_nop 0
	v_add_f32_dpp v13, v13, v13 row_half_mirror row_mask:0xf bank_mask:0xf
	s_nop 0
	v_add_f32_dpp v13, v13, v13 row_mirror row_mask:0xf bank_mask:0xf
	v_mov_b32_e32 v25, v13
	s_nop 1
	v_permlane16_swap_b32_e32 v13, v25
	s_nop 0
	v_add_f32_e32 v13, v13, v25
	v_fmamk_f32 v13, v13, 0x3c800000, v196
	v_rsq_f32_e32 v92, v13
	s_nop 0
	v_pk_mul_f32 v[90:91], v[10:11], v[92:93] op_sel_hi:[1,0]
	s_nop 0
	v_pk_mul_f32 v[92:93], v[52:53], v[90:91]
	s_cbranch_vccz .LBB0_897
	v_lshl_or_b32 v52, v112, 10, v134
	v_ashrrev_i32_e32 v53, 31, v52
	v_lshl_add_u64 v[52:53], v[52:53], 2, s[26:27]
	global_store_dword v[52:53], v93, off sc1
	global_store_dword v[52:53], v92, off offset:128 sc1

.LBB0_899:
	v_pk_mul_f32 v[52:53], v[50:51], v[50:51]
	v_cvt_pk_bf16_f32 v31, v92, s0
	v_add_f32_e32 v13, v53, v52
	v_add_lshl_u32 v52, s8, v179, 10
	v_or_b32_e32 v92, v52, v134
	v_cvt_pk_bf16_f32 v27, v93, s0
	v_ashrrev_i32_e32 v93, 31, v92
	s_waitcnt lgkmcnt(0)
	v_add_f32_dpp v13, v13, v13 quad_perm:[1,0,3,2] row_mask:0xf bank_mask:0xf
	v_lshl_add_u64 v[92:93], v[92:93], 1, s[4:5]
	global_store_short v[92:93], v27, off sc1
	global_store_short v[92:93], v31, off offset:64 sc1
	s_and_b64 vcc, exec, s[70:71]
	v_add_u32_e32 v113, s68, v180
	v_add_f32_dpp v13, v13, v13 quad_perm:[2,3,0,1] row_mask:0xf bank_mask:0xf
	s_nop 0
	v_add_f32_dpp v13, v13, v13 row_half_mirror row_mask:0xf bank_mask:0xf
	s_nop 0
	v_add_f32_dpp v13, v13, v13 row_mirror row_mask:0xf bank_mask:0xf
	v_mov_b32_e32 v25, v13
	s_nop 1
	v_permlane16_swap_b32_e32 v13, v25
	s_nop 0
	v_add_f32_e32 v13, v13, v25
	v_fmamk_f32 v13, v13, 0x3c800000, v196
	v_rsq_f32_e32 v94, v13
	s_nop 0
	v_pk_mul_f32 v[92:93], v[10:11], v[94:95] op_sel_hi:[1,0]
	s_nop 0
	v_pk_mul_f32 v[94:95], v[50:51], v[92:93]
	s_cbranch_vccz .LBB0_901
	v_lshl_or_b32 v50, v113, 10, v134
	v_ashrrev_i32_e32 v51, 31, v50
	v_lshl_add_u64 v[50:51], v[50:51], 2, s[26:27]
	global_store_dword v[50:51], v95, off sc1
	global_store_dword v[50:51], v94, off offset:128 sc1

.LBB0_903:
	v_pk_mul_f32 v[50:51], v[48:49], v[48:49]
	v_cvt_pk_bf16_f32 v31, v94, s0
	v_add_f32_e32 v13, v51, v50
	v_add_lshl_u32 v50, s8, v180, 10
	v_or_b32_e32 v94, v50, v134
	v_cvt_pk_bf16_f32 v27, v95, s0
	v_ashrrev_i32_e32 v95, 31, v94
	s_waitcnt lgkmcnt(0)
	v_add_f32_dpp v13, v13, v13 quad_perm:[1,0,3,2] row_mask:0xf bank_mask:0xf
	v_lshl_add_u64 v[94:95], v[94:95], 1, s[4:5]
	global_store_short v[94:95], v27, off sc1
	global_store_short v[94:95], v31, off offset:64 sc1
	s_and_b64 vcc, exec, s[70:71]
	v_add_u32_e32 v114, s68, v181
	v_add_f32_dpp v13, v13, v13 quad_perm:[2,3,0,1] row_mask:0xf bank_mask:0xf
	s_nop 0
	v_add_f32_dpp v13, v13, v13 row_half_mirror row_mask:0xf bank_mask:0xf
	s_nop 0
	v_add_f32_dpp v13, v13, v13 row_mirror row_mask:0xf bank_mask:0xf
	v_mov_b32_e32 v25, v13
	s_nop 1
	v_permlane16_swap_b32_e32 v13, v25
	s_nop 0
	v_add_f32_e32 v13, v13, v25
	v_fmamk_f32 v13, v13, 0x3c800000, v196
	v_rsq_f32_e32 v96, v13
	s_nop 0
	v_pk_mul_f32 v[94:95], v[10:11], v[96:97] op_sel_hi:[1,0]
	s_nop 0
	v_pk_mul_f32 v[96:97], v[48:49], v[94:95]
	s_cbranch_vccz .LBB0_905
	v_lshl_or_b32 v48, v114, 10, v134
	v_ashrrev_i32_e32 v49, 31, v48
	v_lshl_add_u64 v[48:49], v[48:49], 2, s[26:27]
	global_store_dword v[48:49], v97, off sc1
	global_store_dword v[48:49], v96, off offset:128 sc1

.LBB0_907:
	v_pk_mul_f32 v[48:49], v[46:47], v[46:47]
	v_cvt_pk_bf16_f32 v31, v96, s0
	v_add_f32_e32 v13, v49, v48
	v_add_lshl_u32 v48, s8, v181, 10
	v_or_b32_e32 v98, v48, v134
	v_ashrrev_i32_e32 v99, 31, v98
	v_cvt_pk_bf16_f32 v27, v97, s0
	s_waitcnt lgkmcnt(0)
	v_add_f32_dpp v13, v13, v13 quad_perm:[1,0,3,2] row_mask:0xf bank_mask:0xf
	v_add_u32_e32 v97, s68, v182
	v_lshl_add_u64 v[98:99], v[98:99], 1, s[4:5]
	global_store_short v[98:99], v27, off sc1
	global_store_short v[98:99], v31, off offset:64 sc1
	s_and_b64 vcc, exec, s[70:71]
	v_add_f32_dpp v13, v13, v13 quad_perm:[2,3,0,1] row_mask:0xf bank_mask:0xf
	s_nop 0
	v_add_f32_dpp v13, v13, v13 row_half_mirror row_mask:0xf bank_mask:0xf
	s_nop 0
	v_add_f32_dpp v13, v13, v13 row_mirror row_mask:0xf bank_mask:0xf
	v_mov_b32_e32 v25, v13
	s_nop 1
	v_permlane16_swap_b32_e32 v13, v25
	s_nop 0
	v_add_f32_e32 v13, v13, v25
	v_fmamk_f32 v13, v13, 0x3c800000, v196
	v_rsq_f32_e32 v96, v13
	s_nop 0
	v_pk_mul_f32 v[98:99], v[10:11], v[96:97] op_sel_hi:[1,0]
	s_nop 0
	v_pk_mul_f32 v[98:99], v[46:47], v[98:99]
	s_cbranch_vccz .LBB0_909
	v_lshl_or_b32 v46, v97, 10, v134
	v_ashrrev_i32_e32 v47, 31, v46
	v_lshl_add_u64 v[46:47], v[46:47], 2, s[26:27]
	global_store_dword v[46:47], v99, off sc1
	global_store_dword v[46:47], v98, off offset:128 sc1

.LBB0_911:
	v_pk_mul_f32 v[116:117], v[44:45], v[44:45]
	v_add_lshl_u32 v96, s8, v182, 10
	v_add_f32_e32 v13, v117, v116
	v_cvt_pk_bf16_f32 v31, v98, s0
	v_or_b32_e32 v98, v96, v134
	v_cvt_pk_bf16_f32 v27, v99, s0
	v_ashrrev_i32_e32 v99, 31, v98
	s_waitcnt lgkmcnt(0)
	v_add_f32_dpp v13, v13, v13 quad_perm:[1,0,3,2] row_mask:0xf bank_mask:0xf
	v_lshl_add_u64 v[98:99], v[98:99], 1, s[4:5]
	global_store_short v[98:99], v27, off sc1
	global_store_short v[98:99], v31, off offset:64 sc1
	v_or_b32_e32 v47, 64, v134
	s_and_b64 vcc, exec, s[70:71]
	v_add_f32_dpp v13, v13, v13 quad_perm:[2,3,0,1] row_mask:0xf bank_mask:0xf
	s_nop 0
	v_add_f32_dpp v13, v13, v13 row_half_mirror row_mask:0xf bank_mask:0xf
	s_nop 0
	v_add_f32_dpp v13, v13, v13 row_mirror row_mask:0xf bank_mask:0xf
	v_mov_b32_e32 v25, v13
	s_nop 1
	v_permlane16_swap_b32_e32 v13, v25
	s_nop 0
	v_add_f32_e32 v13, v13, v25
	v_fmamk_f32 v13, v13, 0x3c800000, v196
	v_rsq_f32_e32 v116, v13
	s_nop 0
	v_pk_mul_f32 v[98:99], v[10:11], v[116:117] op_sel_hi:[1,0]
	s_nop 0
	v_pk_mul_f32 v[44:45], v[44:45], v[98:99]
	s_cbranch_vccz .LBB0_913
	v_lshl_or_b32 v98, v148, 10, v47
	v_ashrrev_i32_e32 v99, 31, v98
	v_lshl_add_u64 v[98:99], v[98:99], 2, s[26:27]
	global_store_dword v[98:99], v45, off sc1
	global_store_dword v[98:99], v44, off offset:128 sc1

.LBB0_915:
	v_pk_mul_f32 v[12:13], v[42:43], v[42:43]
	v_cvt_pk_bf16_f32 v27, v45, s0
	v_add_f32_e32 v12, v13, v12
	v_ashrrev_i32_e32 v25, 31, v24
	v_cvt_pk_bf16_f32 v44, v44, s0
	s_and_b64 vcc, exec, s[70:71]
	s_waitcnt lgkmcnt(0)
	v_add_f32_dpp v12, v12, v12 quad_perm:[1,0,3,2] row_mask:0xf bank_mask:0xf
	s_nop 0
	v_add_f32_dpp v12, v12, v12 quad_perm:[2,3,0,1] row_mask:0xf bank_mask:0xf
	s_nop 0
	v_add_f32_dpp v12, v12, v12 row_half_mirror row_mask:0xf bank_mask:0xf
	s_nop 0
	v_add_f32_dpp v31, v12, v12 row_mirror row_mask:0xf bank_mask:0xf
	ds_bpermute_b32 v45, v104, v31
	v_lshl_add_u64 v[12:13], v[24:25], 0, v[134:135]
	v_lshl_add_u64 v[12:13], v[12:13], 1, s[4:5]
	global_store_short v[12:13], v27, off offset:128 sc1
	global_store_short v[12:13], v44, off offset:192 sc1
	s_waitcnt lgkmcnt(0)
	v_add_f32_e32 v24, v31, v45
	v_fmamk_f32 v24, v24, 0x3c800000, v196
	v_rsq_f32_e32 v24, v24
	s_nop 0
	v_pk_mul_f32 v[12:13], v[10:11], v[24:25] op_sel_hi:[1,0]
	s_nop 0
	v_pk_mul_f32 v[12:13], v[42:43], v[12:13]
	s_cbranch_vccz .LBB0_917
	v_lshl_or_b32 v24, v15, 10, v47
	v_ashrrev_i32_e32 v25, 31, v24
	v_lshl_add_u64 v[24:25], v[24:25], 2, s[26:27]
	global_store_dword v[24:25], v13, off sc1
	global_store_dword v[24:25], v12, off offset:128 sc1

.LBB0_919:
	v_pk_mul_f32 v[24:25], v[40:41], v[40:41]
	v_cvt_pk_bf16_f32 v27, v12, s0
	v_add_f32_e32 v15, v25, v24
	v_cvt_pk_bf16_f32 v25, v13, s0
	s_and_b64 vcc, exec, s[70:71]
	s_waitcnt lgkmcnt(0)
	v_add_f32_dpp v15, v15, v15 quad_perm:[1,0,3,2] row_mask:0xf bank_mask:0xf
	s_nop 0
	v_add_f32_dpp v15, v15, v15 quad_perm:[2,3,0,1] row_mask:0xf bank_mask:0xf
	s_nop 0
	v_add_f32_dpp v15, v15, v15 row_half_mirror row_mask:0xf bank_mask:0xf
	s_nop 0
	v_add_f32_dpp v24, v15, v15 row_mirror row_mask:0xf bank_mask:0xf
	ds_bpermute_b32 v26, v104, v24
	v_ashrrev_i32_e32 v15, 31, v14
	v_lshl_add_u64 v[12:13], v[14:15], 0, v[134:135]
	v_lshl_add_u64 v[12:13], v[12:13], 1, s[4:5]
	global_store_short v[12:13], v25, off offset:128 sc1
	global_store_short v[12:13], v27, off offset:192 sc1
	s_waitcnt lgkmcnt(0)
	v_add_f32_e32 v14, v24, v26
	v_fmamk_f32 v14, v14, 0x3c800000, v196
	v_rsq_f32_e32 v14, v14
	s_nop 0
	v_pk_mul_f32 v[12:13], v[10:11], v[14:15] op_sel_hi:[1,0]
	s_nop 0
	v_pk_mul_f32 v[12:13], v[40:41], v[12:13]
	s_cbranch_vccz .LBB0_921
	v_lshl_or_b32 v14, v29, 10, v47
	v_ashrrev_i32_e32 v15, 31, v14
	v_lshl_add_u64 v[14:15], v[14:15], 2, s[26:27]
	global_store_dword v[14:15], v13, off sc1
	global_store_dword v[14:15], v12, off offset:128 sc1

.LBB0_923:
	v_pk_mul_f32 v[14:15], v[38:39], v[38:39]
	v_ashrrev_i32_e32 v29, 31, v28
	v_add_f32_e32 v14, v15, v14
	v_cvt_pk_bf16_f32 v24, v13, s0
	v_cvt_pk_bf16_f32 v25, v12, s0
	v_lshl_add_u64 v[12:13], v[28:29], 0, v[134:135]
	v_lshl_add_u64 v[12:13], v[12:13], 1, s[4:5]
	s_waitcnt lgkmcnt(0)
	v_add_f32_dpp v14, v14, v14 quad_perm:[1,0,3,2] row_mask:0xf bank_mask:0xf
	global_store_short v[12:13], v24, off offset:128 sc1
	global_store_short v[12:13], v25, off offset:192 sc1
	s_and_b64 vcc, exec, s[70:71]
	v_add_f32_dpp v14, v14, v14 quad_perm:[2,3,0,1] row_mask:0xf bank_mask:0xf
	s_nop 0
	v_add_f32_dpp v14, v14, v14 row_half_mirror row_mask:0xf bank_mask:0xf
	s_nop 0
	v_add_f32_dpp v14, v14, v14 row_mirror row_mask:0xf bank_mask:0xf
	v_mov_b32_e32 v15, v14
	s_nop 1
	v_permlane16_swap_b32_e32 v14, v15
	s_nop 0
	v_add_f32_e32 v14, v14, v15
	v_fmamk_f32 v14, v14, 0x3c800000, v196
	v_rsq_f32_e32 v14, v14
	s_nop 0
	v_pk_mul_f32 v[12:13], v[10:11], v[14:15] op_sel_hi:[1,0]
	s_nop 0
	v_pk_mul_f32 v[12:13], v[38:39], v[12:13]
	s_cbranch_vccz .LBB0_925
	v_lshl_or_b32 v14, v59, 10, v47
	v_ashrrev_i32_e32 v15, 31, v14
	v_lshl_add_u64 v[14:15], v[14:15], 2, s[26:27]
	global_store_dword v[14:15], v13, off sc1
	global_store_dword v[14:15], v12, off offset:128 sc1

.LBB0_927:
	v_pk_mul_f32 v[14:15], v[36:37], v[36:37]
	v_ashrrev_i32_e32 v59, 31, v58
	v_add_f32_e32 v14, v15, v14
	v_cvt_pk_bf16_f32 v24, v13, s0
	v_cvt_pk_bf16_f32 v25, v12, s0
	v_lshl_add_u64 v[12:13], v[58:59], 0, v[134:135]
	v_lshl_add_u64 v[12:13], v[12:13], 1, s[4:5]
	s_waitcnt lgkmcnt(0)
	v_add_f32_dpp v14, v14, v14 quad_perm:[1,0,3,2] row_mask:0xf bank_mask:0xf
	global_store_short v[12:13], v24, off offset:128 sc1
	global_store_short v[12:13], v25, off offset:192 sc1
	s_and_b64 vcc, exec, s[70:71]
	v_add_f32_dpp v14, v14, v14 quad_perm:[2,3,0,1] row_mask:0xf bank_mask:0xf
	s_nop 0
	v_add_f32_dpp v14, v14, v14 row_half_mirror row_mask:0xf bank_mask:0xf
	s_nop 0
	v_add_f32_dpp v14, v14, v14 row_mirror row_mask:0xf bank_mask:0xf
	v_mov_b32_e32 v15, v14
	s_nop 1
	v_permlane16_swap_b32_e32 v14, v15
	s_nop 0
	v_add_f32_e32 v14, v14, v15
	v_fmamk_f32 v14, v14, 0x3c800000, v196
	v_rsq_f32_e32 v14, v14
	s_nop 0
	v_pk_mul_f32 v[12:13], v[10:11], v[14:15] op_sel_hi:[1,0]
	s_nop 0
	v_pk_mul_f32 v[12:13], v[36:37], v[12:13]
	s_cbranch_vccz .LBB0_929
	v_lshl_or_b32 v14, v63, 10, v47
	v_ashrrev_i32_e32 v15, 31, v14
	v_lshl_add_u64 v[14:15], v[14:15], 2, s[26:27]
	global_store_dword v[14:15], v13, off sc1
	global_store_dword v[14:15], v12, off offset:128 sc1

.LBB0_931:
	v_pk_mul_f32 v[14:15], v[34:35], v[34:35]
	v_ashrrev_i32_e32 v63, 31, v62
	v_add_f32_e32 v14, v15, v14
	v_cvt_pk_bf16_f32 v24, v13, s0
	v_cvt_pk_bf16_f32 v25, v12, s0
	v_lshl_add_u64 v[12:13], v[62:63], 0, v[134:135]
	v_lshl_add_u64 v[12:13], v[12:13], 1, s[4:5]
	s_waitcnt lgkmcnt(0)
	v_add_f32_dpp v14, v14, v14 quad_perm:[1,0,3,2] row_mask:0xf bank_mask:0xf
	global_store_short v[12:13], v24, off offset:128 sc1
	global_store_short v[12:13], v25, off offset:192 sc1
	s_and_b64 vcc, exec, s[70:71]
	v_add_f32_dpp v14, v14, v14 quad_perm:[2,3,0,1] row_mask:0xf bank_mask:0xf
	s_nop 0
	v_add_f32_dpp v14, v14, v14 row_half_mirror row_mask:0xf bank_mask:0xf
	s_nop 0
	v_add_f32_dpp v14, v14, v14 row_mirror row_mask:0xf bank_mask:0xf
	v_mov_b32_e32 v15, v14
	s_nop 1
	v_permlane16_swap_b32_e32 v14, v15
	s_nop 0
	v_add_f32_e32 v14, v14, v15
	v_fmamk_f32 v14, v14, 0x3c800000, v196
	v_rsq_f32_e32 v14, v14
	s_nop 0
	v_pk_mul_f32 v[12:13], v[10:11], v[14:15] op_sel_hi:[1,0]
	s_nop 0
	v_pk_mul_f32 v[12:13], v[34:35], v[12:13]
	s_cbranch_vccz .LBB0_933
	v_lshl_or_b32 v14, v105, 10, v47
	v_ashrrev_i32_e32 v15, 31, v14
	v_lshl_add_u64 v[14:15], v[14:15], 2, s[26:27]
	global_store_dword v[14:15], v13, off sc1
	global_store_dword v[14:15], v12, off offset:128 sc1

.LBB0_935:
	v_pk_mul_f32 v[14:15], v[32:33], v[32:33]
	v_ashrrev_i32_e32 v73, 31, v72
	v_add_f32_e32 v14, v15, v14
	v_cvt_pk_bf16_f32 v24, v13, s0
	v_cvt_pk_bf16_f32 v25, v12, s0
	v_lshl_add_u64 v[12:13], v[72:73], 0, v[134:135]
	v_lshl_add_u64 v[12:13], v[12:13], 1, s[4:5]
	s_waitcnt lgkmcnt(0)
	v_add_f32_dpp v14, v14, v14 quad_perm:[1,0,3,2] row_mask:0xf bank_mask:0xf
	global_store_short v[12:13], v24, off offset:128 sc1
	global_store_short v[12:13], v25, off offset:192 sc1
	s_and_b64 vcc, exec, s[70:71]
	v_add_f32_dpp v14, v14, v14 quad_perm:[2,3,0,1] row_mask:0xf bank_mask:0xf
	s_nop 0
	v_add_f32_dpp v14, v14, v14 row_half_mirror row_mask:0xf bank_mask:0xf
	s_nop 0
	v_add_f32_dpp v14, v14, v14 row_mirror row_mask:0xf bank_mask:0xf
	v_mov_b32_e32 v15, v14
	s_nop 1
	v_permlane16_swap_b32_e32 v14, v15
	s_nop 0
	v_add_f32_e32 v14, v14, v15
	v_fmamk_f32 v14, v14, 0x3c800000, v196
	v_rsq_f32_e32 v14, v14
	s_nop 0
	v_pk_mul_f32 v[12:13], v[10:11], v[14:15] op_sel_hi:[1,0]
	s_nop 0
	v_pk_mul_f32 v[12:13], v[32:33], v[12:13]
	s_cbranch_vccz .LBB0_937
	v_lshl_or_b32 v14, v106, 10, v47
	v_ashrrev_i32_e32 v15, 31, v14
	v_lshl_add_u64 v[14:15], v[14:15], 2, s[26:27]
	global_store_dword v[14:15], v13, off sc1
	global_store_dword v[14:15], v12, off offset:128 sc1

.LBB0_939:
	v_pk_mul_f32 v[14:15], v[22:23], v[22:23]
	v_ashrrev_i32_e32 v77, 31, v76
	v_add_f32_e32 v14, v15, v14
	v_cvt_pk_bf16_f32 v24, v13, s0
	v_cvt_pk_bf16_f32 v25, v12, s0
	v_lshl_add_u64 v[12:13], v[76:77], 0, v[134:135]
	v_lshl_add_u64 v[12:13], v[12:13], 1, s[4:5]
	s_waitcnt lgkmcnt(0)
	v_add_f32_dpp v14, v14, v14 quad_perm:[1,0,3,2] row_mask:0xf bank_mask:0xf
	global_store_short v[12:13], v24, off offset:128 sc1
	global_store_short v[12:13], v25, off offset:192 sc1
	s_and_b64 vcc, exec, s[70:71]
	v_add_f32_dpp v14, v14, v14 quad_perm:[2,3,0,1] row_mask:0xf bank_mask:0xf
	s_nop 0
	v_add_f32_dpp v14, v14, v14 row_half_mirror row_mask:0xf bank_mask:0xf
	s_nop 0
	v_add_f32_dpp v14, v14, v14 row_mirror row_mask:0xf bank_mask:0xf
	v_mov_b32_e32 v15, v14
	s_nop 1
	v_permlane16_swap_b32_e32 v14, v15
	s_nop 0
	v_add_f32_e32 v14, v14, v15
	v_fmamk_f32 v14, v14, 0x3c800000, v196
	v_rsq_f32_e32 v14, v14
	s_nop 0
	v_pk_mul_f32 v[12:13], v[10:11], v[14:15] op_sel_hi:[1,0]
	s_nop 0
	v_pk_mul_f32 v[12:13], v[22:23], v[12:13]
	s_cbranch_vccz .LBB0_941
	v_lshl_or_b32 v14, v107, 10, v47
	v_ashrrev_i32_e32 v15, 31, v14
	v_lshl_add_u64 v[14:15], v[14:15], 2, s[26:27]
	global_store_dword v[14:15], v13, off sc1
	global_store_dword v[14:15], v12, off offset:128 sc1

.LBB0_943:
	v_pk_mul_f32 v[14:15], v[20:21], v[20:21]
	v_ashrrev_i32_e32 v69, 31, v68
	v_add_f32_e32 v14, v15, v14
	v_cvt_pk_bf16_f32 v22, v13, s0
	v_cvt_pk_bf16_f32 v23, v12, s0
	v_lshl_add_u64 v[12:13], v[68:69], 0, v[134:135]
	v_lshl_add_u64 v[12:13], v[12:13], 1, s[4:5]
	s_waitcnt lgkmcnt(0)
	v_add_f32_dpp v14, v14, v14 quad_perm:[1,0,3,2] row_mask:0xf bank_mask:0xf
	global_store_short v[12:13], v22, off offset:128 sc1
	global_store_short v[12:13], v23, off offset:192 sc1
	s_and_b64 vcc, exec, s[70:71]
	v_add_f32_dpp v14, v14, v14 quad_perm:[2,3,0,1] row_mask:0xf bank_mask:0xf
	s_nop 0
	v_add_f32_dpp v14, v14, v14 row_half_mirror row_mask:0xf bank_mask:0xf
	s_nop 0
	v_add_f32_dpp v14, v14, v14 row_mirror row_mask:0xf bank_mask:0xf
	v_mov_b32_e32 v15, v14
	s_nop 1
	v_permlane16_swap_b32_e32 v14, v15
	s_nop 0
	v_add_f32_e32 v14, v14, v15
	v_fmamk_f32 v14, v14, 0x3c800000, v196
	v_rsq_f32_e32 v14, v14
	s_nop 0
	v_pk_mul_f32 v[12:13], v[10:11], v[14:15] op_sel_hi:[1,0]
	s_nop 0
	v_pk_mul_f32 v[12:13], v[20:21], v[12:13]
	s_cbranch_vccz .LBB0_945
	v_lshl_or_b32 v14, v108, 10, v47
	v_ashrrev_i32_e32 v15, 31, v14
	v_lshl_add_u64 v[14:15], v[14:15], 2, s[26:27]
	global_store_dword v[14:15], v13, off sc1
	global_store_dword v[14:15], v12, off offset:128 sc1

.LBB0_947:
	v_pk_mul_f32 v[14:15], v[18:19], v[18:19]
	v_ashrrev_i32_e32 v67, 31, v66
	v_add_f32_e32 v14, v15, v14
	v_cvt_pk_bf16_f32 v20, v13, s0
	v_cvt_pk_bf16_f32 v21, v12, s0
	v_lshl_add_u64 v[12:13], v[66:67], 0, v[134:135]
	v_lshl_add_u64 v[12:13], v[12:13], 1, s[4:5]
	s_waitcnt lgkmcnt(0)
	v_add_f32_dpp v14, v14, v14 quad_perm:[1,0,3,2] row_mask:0xf bank_mask:0xf
	global_store_short v[12:13], v20, off offset:128 sc1
	global_store_short v[12:13], v21, off offset:192 sc1
	s_and_b64 vcc, exec, s[70:71]
	v_add_f32_dpp v14, v14, v14 quad_perm:[2,3,0,1] row_mask:0xf bank_mask:0xf
	s_nop 0
	v_add_f32_dpp v14, v14, v14 row_half_mirror row_mask:0xf bank_mask:0xf
	s_nop 0
	v_add_f32_dpp v14, v14, v14 row_mirror row_mask:0xf bank_mask:0xf
	v_mov_b32_e32 v15, v14
	s_nop 1
	v_permlane16_swap_b32_e32 v14, v15
	s_nop 0
	v_add_f32_e32 v14, v14, v15
	v_fmamk_f32 v14, v14, 0x3c800000, v196
	v_rsq_f32_e32 v14, v14
	s_nop 0
	v_pk_mul_f32 v[12:13], v[10:11], v[14:15] op_sel_hi:[1,0]
	s_nop 0
	v_pk_mul_f32 v[12:13], v[18:19], v[12:13]
	s_cbranch_vccz .LBB0_949
	v_lshl_or_b32 v14, v109, 10, v47
	v_ashrrev_i32_e32 v15, 31, v14
	v_lshl_add_u64 v[14:15], v[14:15], 2, s[26:27]
	global_store_dword v[14:15], v13, off sc1
	global_store_dword v[14:15], v12, off offset:128 sc1

.LBB0_951:
	v_pk_mul_f32 v[14:15], v[16:17], v[16:17]
	v_ashrrev_i32_e32 v65, 31, v64
	v_add_f32_e32 v14, v15, v14
	v_cvt_pk_bf16_f32 v18, v13, s0
	v_cvt_pk_bf16_f32 v19, v12, s0
	v_lshl_add_u64 v[12:13], v[64:65], 0, v[134:135]
	v_lshl_add_u64 v[12:13], v[12:13], 1, s[4:5]
	s_waitcnt lgkmcnt(0)
	v_add_f32_dpp v14, v14, v14 quad_perm:[1,0,3,2] row_mask:0xf bank_mask:0xf
	global_store_short v[12:13], v18, off offset:128 sc1
	global_store_short v[12:13], v19, off offset:192 sc1
	s_and_b64 vcc, exec, s[70:71]
	v_add_f32_dpp v14, v14, v14 quad_perm:[2,3,0,1] row_mask:0xf bank_mask:0xf
	s_nop 0
	v_add_f32_dpp v14, v14, v14 row_half_mirror row_mask:0xf bank_mask:0xf
	s_nop 0
	v_add_f32_dpp v14, v14, v14 row_mirror row_mask:0xf bank_mask:0xf
	v_mov_b32_e32 v15, v14
	s_nop 1
	v_permlane16_swap_b32_e32 v14, v15
	s_nop 0
	v_add_f32_e32 v14, v14, v15
	v_fmamk_f32 v14, v14, 0x3c800000, v196
	v_rsq_f32_e32 v14, v14
	s_nop 0
	v_pk_mul_f32 v[12:13], v[10:11], v[14:15] op_sel_hi:[1,0]
	s_nop 0
	v_pk_mul_f32 v[12:13], v[16:17], v[12:13]
	s_cbranch_vccz .LBB0_953
	v_lshl_or_b32 v14, v110, 10, v47
	v_ashrrev_i32_e32 v15, 31, v14
	v_lshl_add_u64 v[14:15], v[14:15], 2, s[26:27]
	global_store_dword v[14:15], v13, off sc1
	global_store_dword v[14:15], v12, off offset:128 sc1

.LBB0_955:
	v_pk_mul_f32 v[14:15], v[8:9], v[8:9]
	v_ashrrev_i32_e32 v57, 31, v56
	v_add_f32_e32 v14, v15, v14
	v_cvt_pk_bf16_f32 v16, v13, s0
	v_cvt_pk_bf16_f32 v17, v12, s0
	v_lshl_add_u64 v[12:13], v[56:57], 0, v[134:135]
	v_lshl_add_u64 v[12:13], v[12:13], 1, s[4:5]
	s_waitcnt lgkmcnt(0)
	v_add_f32_dpp v14, v14, v14 quad_perm:[1,0,3,2] row_mask:0xf bank_mask:0xf
	global_store_short v[12:13], v16, off offset:128 sc1
	global_store_short v[12:13], v17, off offset:192 sc1
	s_and_b64 vcc, exec, s[70:71]
	v_add_f32_dpp v14, v14, v14 quad_perm:[2,3,0,1] row_mask:0xf bank_mask:0xf
	s_nop 0
	v_add_f32_dpp v14, v14, v14 row_half_mirror row_mask:0xf bank_mask:0xf
	s_nop 0
	v_add_f32_dpp v14, v14, v14 row_mirror row_mask:0xf bank_mask:0xf
	v_mov_b32_e32 v15, v14
	s_nop 1
	v_permlane16_swap_b32_e32 v14, v15
	s_nop 0
	v_add_f32_e32 v14, v14, v15
	v_fmamk_f32 v14, v14, 0x3c800000, v196
	v_rsq_f32_e32 v14, v14
	s_nop 0
	v_pk_mul_f32 v[12:13], v[10:11], v[14:15] op_sel_hi:[1,0]
	s_nop 0
	v_pk_mul_f32 v[8:9], v[8:9], v[12:13]
	s_cbranch_vccz .LBB0_957
	v_lshl_or_b32 v12, v111, 10, v47
	v_ashrrev_i32_e32 v13, 31, v12
	v_lshl_add_u64 v[12:13], v[12:13], 2, s[26:27]
	global_store_dword v[12:13], v9, off sc1
	global_store_dword v[12:13], v8, off offset:128 sc1

.LBB0_959:
	v_pk_mul_f32 v[12:13], v[6:7], v[6:7]
	v_ashrrev_i32_e32 v55, 31, v54
	v_add_f32_e32 v12, v13, v12
	v_cvt_pk_bf16_f32 v14, v9, s0
	v_cvt_pk_bf16_f32 v15, v8, s0
	v_lshl_add_u64 v[8:9], v[54:55], 0, v[134:135]
	v_lshl_add_u64 v[8:9], v[8:9], 1, s[4:5]
	s_waitcnt lgkmcnt(0)
	v_add_f32_dpp v12, v12, v12 quad_perm:[1,0,3,2] row_mask:0xf bank_mask:0xf
	global_store_short v[8:9], v14, off offset:128 sc1
	global_store_short v[8:9], v15, off offset:192 sc1
	s_and_b64 vcc, exec, s[70:71]
	v_add_f32_dpp v12, v12, v12 quad_perm:[2,3,0,1] row_mask:0xf bank_mask:0xf
	s_nop 0
	v_add_f32_dpp v12, v12, v12 row_half_mirror row_mask:0xf bank_mask:0xf
	s_nop 0
	v_add_f32_dpp v12, v12, v12 row_mirror row_mask:0xf bank_mask:0xf
	v_mov_b32_e32 v13, v12
	s_nop 1
	v_permlane16_swap_b32_e32 v12, v13
	s_nop 0
	v_add_f32_e32 v12, v12, v13
	v_fmamk_f32 v12, v12, 0x3c800000, v196
	v_rsq_f32_e32 v12, v12
	s_nop 0
	v_pk_mul_f32 v[8:9], v[10:11], v[12:13] op_sel_hi:[1,0]
	s_nop 0
	v_pk_mul_f32 v[6:7], v[6:7], v[8:9]
	s_cbranch_vccz .LBB0_961
	v_lshl_or_b32 v8, v112, 10, v47
	v_ashrrev_i32_e32 v9, 31, v8
	v_lshl_add_u64 v[8:9], v[8:9], 2, s[26:27]
	global_store_dword v[8:9], v7, off sc1
	global_store_dword v[8:9], v6, off offset:128 sc1

.LBB0_963:
	v_pk_mul_f32 v[8:9], v[4:5], v[4:5]
	v_ashrrev_i32_e32 v53, 31, v52
	v_add_f32_e32 v8, v9, v8
	v_cvt_pk_bf16_f32 v12, v7, s0
	v_cvt_pk_bf16_f32 v13, v6, s0
	v_lshl_add_u64 v[6:7], v[52:53], 0, v[134:135]
	v_lshl_add_u64 v[6:7], v[6:7], 1, s[4:5]
	s_waitcnt lgkmcnt(0)
	v_add_f32_dpp v8, v8, v8 quad_perm:[1,0,3,2] row_mask:0xf bank_mask:0xf
	global_store_short v[6:7], v12, off offset:128 sc1
	global_store_short v[6:7], v13, off offset:192 sc1
	s_and_b64 vcc, exec, s[70:71]
	v_add_f32_dpp v8, v8, v8 quad_perm:[2,3,0,1] row_mask:0xf bank_mask:0xf
	s_nop 0
	v_add_f32_dpp v8, v8, v8 row_half_mirror row_mask:0xf bank_mask:0xf
	s_nop 0
	v_add_f32_dpp v8, v8, v8 row_mirror row_mask:0xf bank_mask:0xf
	v_mov_b32_e32 v9, v8
	s_nop 1
	v_permlane16_swap_b32_e32 v8, v9
	s_nop 0
	v_add_f32_e32 v8, v8, v9
	v_fmamk_f32 v8, v8, 0x3c800000, v196
	v_rsq_f32_e32 v8, v8
	s_nop 0
	v_pk_mul_f32 v[6:7], v[10:11], v[8:9] op_sel_hi:[1,0]
	s_nop 0
	v_pk_mul_f32 v[4:5], v[4:5], v[6:7]
	s_cbranch_vccz .LBB0_965
	v_lshl_or_b32 v6, v113, 10, v47
	v_ashrrev_i32_e32 v7, 31, v6
	v_lshl_add_u64 v[6:7], v[6:7], 2, s[26:27]
	global_store_dword v[6:7], v5, off sc1
	global_store_dword v[6:7], v4, off offset:128 sc1

.LBB0_967:
	v_pk_mul_f32 v[6:7], v[2:3], v[2:3]
	v_ashrrev_i32_e32 v51, 31, v50
	v_add_f32_e32 v6, v7, v6
	v_cvt_pk_bf16_f32 v8, v5, s0
	v_cvt_pk_bf16_f32 v9, v4, s0
	v_lshl_add_u64 v[4:5], v[50:51], 0, v[134:135]
	v_lshl_add_u64 v[4:5], v[4:5], 1, s[4:5]
	s_waitcnt lgkmcnt(0)
	v_add_f32_dpp v6, v6, v6 quad_perm:[1,0,3,2] row_mask:0xf bank_mask:0xf
	global_store_short v[4:5], v8, off offset:128 sc1
	global_store_short v[4:5], v9, off offset:192 sc1
	s_and_b64 vcc, exec, s[70:71]
	v_add_f32_dpp v6, v6, v6 quad_perm:[2,3,0,1] row_mask:0xf bank_mask:0xf
	s_nop 0
	v_add_f32_dpp v6, v6, v6 row_half_mirror row_mask:0xf bank_mask:0xf
	s_nop 0
	v_add_f32_dpp v6, v6, v6 row_mirror row_mask:0xf bank_mask:0xf
	v_mov_b32_e32 v7, v6
	s_nop 1
	v_permlane16_swap_b32_e32 v6, v7
	s_nop 0
	v_add_f32_e32 v6, v6, v7
	v_fmamk_f32 v6, v6, 0x3c800000, v196
	v_rsq_f32_e32 v6, v6
	s_nop 0
	v_pk_mul_f32 v[4:5], v[10:11], v[6:7] op_sel_hi:[1,0]
	s_nop 0
	v_pk_mul_f32 v[2:3], v[2:3], v[4:5]
	s_cbranch_vccz .LBB0_969
	v_lshl_or_b32 v4, v114, 10, v47
	v_ashrrev_i32_e32 v5, 31, v4
	v_lshl_add_u64 v[4:5], v[4:5], 2, s[26:27]
	global_store_dword v[4:5], v3, off sc1
	global_store_dword v[4:5], v2, off offset:128 sc1

.LBB0_971:
	v_pk_mul_f32 v[4:5], v[0:1], v[0:1]
	v_ashrrev_i32_e32 v49, 31, v48
	v_add_f32_e32 v4, v5, v4
	v_cvt_pk_bf16_f32 v6, v3, s0
	v_cvt_pk_bf16_f32 v7, v2, s0
	v_lshl_add_u64 v[2:3], v[48:49], 0, v[134:135]
	v_lshl_add_u64 v[2:3], v[2:3], 1, s[4:5]
	s_waitcnt lgkmcnt(0)
	v_add_f32_dpp v4, v4, v4 quad_perm:[1,0,3,2] row_mask:0xf bank_mask:0xf
	global_store_short v[2:3], v6, off offset:128 sc1
	global_store_short v[2:3], v7, off offset:192 sc1
	s_and_b64 vcc, exec, s[70:71]
	v_add_f32_dpp v4, v4, v4 quad_perm:[2,3,0,1] row_mask:0xf bank_mask:0xf
	s_nop 0
	v_add_f32_dpp v4, v4, v4 row_half_mirror row_mask:0xf bank_mask:0xf
	s_nop 0
	v_add_f32_dpp v4, v4, v4 row_mirror row_mask:0xf bank_mask:0xf
	v_mov_b32_e32 v5, v4
	s_nop 1
	v_permlane16_swap_b32_e32 v4, v5
	s_nop 0
	v_add_f32_e32 v4, v4, v5
	v_fmamk_f32 v4, v4, 0x3c800000, v196
	v_rsq_f32_e32 v4, v4
	s_nop 0
	v_pk_mul_f32 v[2:3], v[10:11], v[4:5] op_sel_hi:[1,0]
	s_nop 0
	v_pk_mul_f32 v[0:1], v[0:1], v[2:3]
	s_cbranch_vccz .LBB0_973
	v_lshl_or_b32 v2, v97, 10, v47
	v_ashrrev_i32_e32 v3, 31, v2
	v_lshl_add_u64 v[2:3], v[2:3], 2, s[26:27]
	global_store_dword v[2:3], v1, off sc1
	global_store_dword v[2:3], v0, off offset:128 sc1

.LBB0_1050:
	s_add_i32 s58, s66, 0xffffe000
	s_lshr_b32 s58, s58, 12
	s_mulk_i32 s58, 0x1800
	v_mov_b32_e32 v70, s70
	s_addk_i32 s58, 0x6000
	ds_read_b64 v[70:71], v70
	s_cmp_gt_i32 s6, 63
	s_cselect_b32 s6, s58, 0x4800
	s_lshl_b64 s[58:59], s[6:7], 2
	s_add_u32 s6, s14, s58
	s_addc_u32 s65, s15, s59
	s_waitcnt lgkmcnt(0)
	v_readfirstlane_b32 s58, v70
	v_readfirstlane_b32 s59, v71
	s_add_u32 s60, s58, 0x1000
	s_addc_u32 s61, s59, 0
	s_lshl_b32 s58, s64, 14
	s_add_i32 s58, s58, 0x60000
	s_ashr_i32 s59, s58, 31
	s_lshl_b64 s[58:59], s[58:59], 2
	s_add_u32 s58, s10, s58
	s_addc_u32 s59, s11, s59
	s_add_u32 s62, s6, 0x5ba2000
	v_or_b32_e32 v102, s68, v138
	v_add_u32_e32 v70, s66, v139
	s_addc_u32 s63, s65, 0
	v_lshlrev_b32_e32 v188, 10, v70
	v_ashrrev_i32_e32 v103, 31, v102
	s_add_u32 s64, s6, 0x5ba4000
	v_lshlrev_b64 v[72:73], 2, v[102:103]
	v_or_b32_e32 v186, 0x400, v188
	v_or_b32_e32 v185, 0x4400, v188
	v_or_b32_e32 v189, 0x4c00, v188
	v_or_b32_e32 v193, 0x6c00, v188
	s_addc_u32 s65, s65, 0
	v_lshl_add_u64 v[74:75], s[62:63], 0, v[72:73]
	v_add_u32_e32 v132, v188, v102
	v_add_u32_e32 v134, v186, v102
	v_or_b32_e32 v184, 0x800, v188
	v_or_b32_e32 v183, 0xc00, v188
	v_or_b32_e32 v181, 0x2000, v188
	v_or_b32_e32 v179, 0x2400, v188
	v_or_b32_e32 v71, 0x2800, v188
	v_or_b32_e32 v180, 0x2c00, v188
	v_or_b32_e32 v182, 0x4000, v188
	v_add_u32_e32 v112, v185, v102
	v_or_b32_e32 v187, 0x4800, v188
	v_add_u32_e32 v118, v189, v102
	v_or_b32_e32 v190, 0x6000, v188
	v_or_b32_e32 v191, 0x6400, v188
	v_or_b32_e32 v192, 0x6800, v188
	v_add_u32_e32 v128, v193, v102
	global_load_dword v194, v[74:75], off
	v_lshl_add_u64 v[74:75], s[60:61], 0, v[72:73]
	v_lshl_add_u64 v[72:73], s[64:65], 0, v[72:73]
	v_ashrrev_i32_e32 v135, 31, v134
	v_add_u32_e32 v136, v184, v102
	v_add_u32_e32 v130, v183, v102
	v_add_u32_e32 v122, v181, v102
	v_add_u32_e32 v114, v179, v102
	v_add_u32_e32 v106, v71, v102
	v_add_u32_e32 v108, v180, v102
	v_add_u32_e32 v110, v182, v102
	v_ashrrev_i32_e32 v113, 31, v112
	v_add_u32_e32 v116, v187, v102
	v_ashrrev_i32_e32 v119, 31, v118
	v_add_u32_e32 v120, v190, v102
	v_add_u32_e32 v124, v191, v102
	v_add_u32_e32 v126, v192, v102
	v_ashrrev_i32_e32 v129, 31, v128
	v_ashrrev_i32_e32 v133, 31, v132
	global_load_dword v196, v[72:73], off
	v_lshl_add_u64 v[88:89], v[134:135], 2, s[12:13]
	v_ashrrev_i32_e32 v137, 31, v136
	v_ashrrev_i32_e32 v131, 31, v130
	v_ashrrev_i32_e32 v123, 31, v122
	v_ashrrev_i32_e32 v115, 31, v114
	v_ashrrev_i32_e32 v107, 31, v106
	v_ashrrev_i32_e32 v109, 31, v108
	v_ashrrev_i32_e32 v111, 31, v110
	v_lshl_add_u64 v[86:87], v[112:113], 2, s[12:13]
	v_ashrrev_i32_e32 v117, 31, v116
	v_lshl_add_u64 v[92:93], v[118:119], 2, s[12:13]
	v_ashrrev_i32_e32 v121, 31, v120
	v_ashrrev_i32_e32 v125, 31, v124
	v_ashrrev_i32_e32 v127, 31, v126
	v_lshl_add_u64 v[100:101], v[128:129], 2, s[12:13]
	v_lshl_add_u64 v[104:105], v[132:133], 2, s[12:13]
	global_load_dword v195, v[74:75], off
	v_lshl_add_u64 v[84:85], v[136:137], 2, s[12:13]
	v_lshl_add_u64 v[82:83], v[130:131], 2, s[12:13]
	v_lshl_add_u64 v[78:79], v[122:123], 2, s[12:13]
	v_lshl_add_u64 v[72:73], v[114:115], 2, s[12:13]
	v_lshl_add_u64 v[74:75], v[106:107], 2, s[12:13]
	v_lshl_add_u64 v[76:77], v[108:109], 2, s[12:13]
	v_lshl_add_u64 v[80:81], v[110:111], 2, s[12:13]
	global_load_dword v178, v[88:89], off
	global_load_dword v177, v[84:85], off
	global_load_dword v176, v[82:83], off
	global_load_dword v175, v[78:79], off
	global_load_dword v174, v[72:73], off
	global_load_dword v173, v[74:75], off
	global_load_dword v172, v[76:77], off
	global_load_dword v171, v[80:81], off
	v_lshl_add_u64 v[90:91], v[116:117], 2, s[12:13]
	global_load_dword v170, v[86:87], off
	global_load_dword v168, v[90:91], off
	v_lshl_add_u64 v[94:95], v[120:121], 2, s[12:13]
	v_lshl_add_u64 v[96:97], v[124:125], 2, s[12:13]
	v_lshl_add_u64 v[98:99], v[126:127], 2, s[12:13]
	global_load_dword v169, v[92:93], off
	global_load_dword v167, v[94:95], off
	global_load_dword v166, v[96:97], off
	global_load_dword v165, v[98:99], off
	global_load_dword v103, v[100:101], off
	global_load_dword v197, v[104:105], off
	v_lshl_add_u64 v[106:107], v[106:107], 1, s[8:9]
	s_waitcnt vmcnt(0)
	v_add_f32_e32 v196, 1.0, v196
	v_mul_f32_e32 v195, v195, v196
	v_fmac_f32_e32 v178, v49, v194
	v_fmac_f32_e32 v177, v50, v194
	v_fmac_f32_e32 v176, v51, v194
	v_fmac_f32_e32 v175, v52, v194
	v_fmac_f32_e32 v174, v53, v194
	v_fmac_f32_e32 v173, v54, v194
	v_fmac_f32_e32 v172, v55, v194
	v_fmac_f32_e32 v171, v56, v194
	v_fmac_f32_e32 v170, v57, v194
	v_fmac_f32_e32 v168, v58, v194
	v_fmac_f32_e32 v169, v59, v194
	v_fmac_f32_e32 v167, v60, v194
	v_fmac_f32_e32 v166, v61, v194
	v_fmac_f32_e32 v165, v62, v194
	v_fmac_f32_e32 v103, v63, v194
	v_fmac_f32_e32 v197, v48, v194
	v_mul_f32_e32 v48, v195, v197
	v_cvt_pk_bf16_f32 v58, v48, s0
	v_or_b32_e32 v48, 32, v102
	v_ashrrev_i32_e32 v49, 31, v48
	v_lshlrev_b64 v[52:53], 2, v[48:49]
	global_store_dword v[88:89], v178, off sc1
	global_store_dword v[84:85], v177, off sc1
	global_store_dword v[82:83], v176, off sc1
	global_store_dword v[78:79], v175, off sc1
	global_store_dword v[72:73], v174, off sc1
	global_store_dword v[74:75], v173, off sc1
	global_store_dword v[76:77], v172, off sc1
	global_store_dword v[80:81], v171, off sc1
	global_store_dword v[86:87], v170, off sc1
	global_store_dword v[90:91], v168, off sc1
	global_store_dword v[92:93], v169, off sc1
	global_store_dword v[94:95], v167, off sc1
	global_store_dword v[96:97], v166, off sc1
	global_store_dword v[98:99], v165, off sc1
	global_store_dword v[100:101], v103, off sc1
	global_store_dword v[104:105], v197, off sc1
	v_lshl_add_u64 v[50:51], v[132:133], 1, s[8:9]
	v_lshl_add_u64 v[56:57], s[64:65], 0, v[52:53]
	global_load_dword v196, v[104:105], off offset:128
	v_lshl_add_u64 v[54:55], s[60:61], 0, v[52:53]
	global_load_dword v132, v[56:57], off
	global_load_dword v133, v[54:55], off
	v_mul_f32_e32 v49, v195, v178
	global_store_short v[50:51], v58, off sc1
	v_lshl_add_u64 v[50:51], s[62:63], 0, v[52:53]
	global_load_dword v194, v[50:51], off
	v_cvt_pk_bf16_f32 v49, v49, s0
	v_lshl_add_u64 v[50:51], v[134:135], 1, s[8:9]
	global_store_short v[50:51], v49, off sc1
	v_mul_f32_e32 v49, v195, v177
	v_cvt_pk_bf16_f32 v49, v49, s0
	v_lshl_add_u64 v[50:51], v[136:137], 1, s[8:9]
	global_store_short v[50:51], v49, off sc1
	v_mul_f32_e32 v49, v195, v176
	v_cvt_pk_bf16_f32 v49, v49, s0
	v_lshl_add_u64 v[50:51], v[130:131], 1, s[8:9]
	global_store_short v[50:51], v49, off sc1
	v_mul_f32_e32 v49, v195, v175
	v_cvt_pk_bf16_f32 v49, v49, s0
	v_lshl_add_u64 v[50:51], v[122:123], 1, s[8:9]
	global_store_short v[50:51], v49, off sc1
	v_mul_f32_e32 v49, v195, v174
	v_cvt_pk_bf16_f32 v49, v49, s0
	v_lshl_add_u64 v[50:51], v[114:115], 1, s[8:9]
	global_store_short v[50:51], v49, off sc1
	v_mul_f32_e32 v49, v195, v173
	global_load_dword v62, v[84:85], off offset:128
	global_load_dword v60, v[78:79], off offset:128
	global_load_dword v59, v[72:73], off offset:128
	global_load_dword v58, v[74:75], off offset:128
	global_load_dword v56, v[80:81], off offset:128
	global_load_dword v57, v[76:77], off offset:128
	global_load_dword v55, v[86:87], off offset:128
	global_load_dword v61, v[82:83], off offset:128
	global_load_dword v54, v[90:91], off offset:128
	global_load_dword v53, v[92:93], off offset:128
	global_load_dword v52, v[94:95], off offset:128
	global_load_dword v51, v[96:97], off offset:128
	global_load_dword v50, v[98:99], off offset:128
	v_cvt_pk_bf16_f32 v63, v49, s0
	global_load_dword v49, v[100:101], off offset:128
	s_waitcnt vmcnt(19)
	v_fmac_f32_e32 v196, v32, v194
	global_store_short v[106:107], v63, off sc1
	global_load_dword v63, v[88:89], off offset:128
	v_mul_f32_e32 v106, v195, v172
	v_cvt_pk_bf16_f32 v114, v106, s0
	v_lshl_add_u64 v[106:107], v[108:109], 1, s[8:9]
	global_store_short v[106:107], v114, off sc1
	v_mul_f32_e32 v106, v195, v171
	v_cvt_pk_bf16_f32 v108, v106, s0
	v_lshl_add_u64 v[106:107], v[110:111], 1, s[8:9]
	global_store_short v[106:107], v108, off sc1
	v_mul_f32_e32 v106, v195, v170
	v_cvt_pk_bf16_f32 v108, v106, s0
	v_lshl_add_u64 v[106:107], v[112:113], 1, s[8:9]
	global_store_short v[106:107], v108, off sc1
	v_mul_f32_e32 v106, v195, v168
	v_cvt_pk_bf16_f32 v108, v106, s0
	v_lshl_add_u64 v[106:107], v[116:117], 1, s[8:9]
	global_store_short v[106:107], v108, off sc1
	v_mul_f32_e32 v106, v195, v169
	v_cvt_pk_bf16_f32 v108, v106, s0
	v_lshl_add_u64 v[106:107], v[118:119], 1, s[8:9]
	global_store_short v[106:107], v108, off sc1
	v_mul_f32_e32 v106, v195, v167
	v_cvt_pk_bf16_f32 v108, v106, s0
	v_lshl_add_u64 v[106:107], v[120:121], 1, s[8:9]
	global_store_short v[106:107], v108, off sc1
	v_mul_f32_e32 v106, v195, v166
	v_cvt_pk_bf16_f32 v108, v106, s0
	v_lshl_add_u64 v[106:107], v[124:125], 1, s[8:9]
	global_store_short v[106:107], v108, off sc1
	v_mul_f32_e32 v106, v195, v165
	v_cvt_pk_bf16_f32 v108, v106, s0
	v_lshl_add_u64 v[106:107], v[126:127], 1, s[8:9]
	global_store_short v[106:107], v108, off sc1
	v_mul_f32_e32 v106, v195, v103
	v_cvt_pk_bf16_f32 v108, v106, s0
	v_lshl_add_u64 v[106:107], v[128:129], 1, s[8:9]
	global_store_short v[106:107], v108, off sc1
	v_add_f32_e32 v106, 1.0, v132
	v_mul_f32_e32 v110, v133, v106
	v_add_u32_e32 v106, v188, v48
	s_waitcnt vmcnt(24)
	v_fmac_f32_e32 v62, v34, v194
	s_waitcnt vmcnt(17)
	v_fmac_f32_e32 v61, v35, v194
	v_fmac_f32_e32 v60, v36, v194
	v_fmac_f32_e32 v59, v37, v194
	v_fmac_f32_e32 v58, v38, v194
	v_fmac_f32_e32 v57, v39, v194
	v_fmac_f32_e32 v56, v40, v194
	v_fmac_f32_e32 v55, v41, v194
	s_waitcnt vmcnt(16)
	v_fmac_f32_e32 v54, v42, v194
	s_waitcnt vmcnt(15)
	v_fmac_f32_e32 v53, v43, v194
	s_waitcnt vmcnt(14)
	v_fmac_f32_e32 v52, v44, v194
	s_waitcnt vmcnt(13)
	v_fmac_f32_e32 v51, v45, v194
	s_waitcnt vmcnt(12)
	v_fmac_f32_e32 v50, v46, v194
	s_waitcnt vmcnt(11)
	v_fmac_f32_e32 v49, v47, v194
	v_ashrrev_i32_e32 v107, 31, v106
	global_store_dword v[104:105], v196, off offset:128 sc1
	v_mul_f32_e32 v32, v110, v196
	global_store_dword v[84:85], v62, off offset:128 sc1
	global_store_dword v[82:83], v61, off offset:128 sc1
	global_store_dword v[78:79], v60, off offset:128 sc1
	global_store_dword v[72:73], v59, off offset:128 sc1
	global_store_dword v[74:75], v58, off offset:128 sc1
	global_store_dword v[76:77], v57, off offset:128 sc1
	global_store_dword v[80:81], v56, off offset:128 sc1
	global_store_dword v[86:87], v55, off offset:128 sc1
	global_store_dword v[90:91], v54, off offset:128 sc1
	global_store_dword v[92:93], v53, off offset:128 sc1
	global_store_dword v[94:95], v52, off offset:128 sc1
	global_store_dword v[96:97], v51, off offset:128 sc1
	global_store_dword v[98:99], v50, off offset:128 sc1
	global_store_dword v[100:101], v49, off offset:128 sc1
	v_cvt_pk_bf16_f32 v32, v32, s0
	v_lshl_add_u64 v[106:107], v[106:107], 1, s[8:9]
	v_add_u32_e32 v108, v186, v48
	global_load_dword v45, v[88:89], off offset:256
	v_ashrrev_i32_e32 v109, 31, v108
	global_store_short v[106:107], v32, off sc1
	v_mul_f32_e32 v113, v110, v56
	v_cvt_pk_bf16_f32 v113, v113, s0
	v_mul_f32_e32 v106, v196, v196
	s_waitcnt vmcnt(26)
	v_fmac_f32_e32 v63, v33, v194
	v_mul_f32_e32 v32, v110, v63
	v_cvt_pk_bf16_f32 v34, v32, s0
	v_lshl_add_u64 v[32:33], v[108:109], 1, s[8:9]
	global_store_short v[32:33], v34, off sc1
	v_add_u32_e32 v32, v184, v48
	v_ashrrev_i32_e32 v33, 31, v32
	v_mul_f32_e32 v34, v110, v62
	v_cvt_pk_bf16_f32 v34, v34, s0
	v_lshl_add_u64 v[32:33], v[32:33], 1, s[8:9]
	global_store_short v[32:33], v34, off sc1
	v_add_u32_e32 v32, v183, v48
	v_ashrrev_i32_e32 v33, 31, v32
	v_mul_f32_e32 v34, v110, v61
	v_cvt_pk_bf16_f32 v34, v34, s0
	v_lshl_add_u64 v[32:33], v[32:33], 1, s[8:9]
	global_store_short v[32:33], v34, off sc1
	v_add_u32_e32 v32, v181, v48
	v_ashrrev_i32_e32 v33, 31, v32
	v_mul_f32_e32 v34, v110, v60
	v_cvt_pk_bf16_f32 v34, v34, s0
	v_lshl_add_u64 v[32:33], v[32:33], 1, s[8:9]
	global_store_short v[32:33], v34, off sc1
	v_add_u32_e32 v32, v179, v48
	v_ashrrev_i32_e32 v33, 31, v32
	v_mul_f32_e32 v34, v110, v59
	v_cvt_pk_bf16_f32 v42, v34, s0
	v_lshl_add_u64 v[34:35], v[32:33], 1, s[8:9]
	v_or_b32_e32 v32, 64, v102
	v_ashrrev_i32_e32 v33, 31, v32
	v_lshlrev_b64 v[36:37], 2, v[32:33]
	global_store_dword v[88:89], v63, off offset:128 sc1
	v_lshl_add_u64 v[40:41], s[64:65], 0, v[36:37]
	v_lshl_add_u64 v[38:39], s[60:61], 0, v[36:37]
	global_load_dword v107, v[40:41], off
	global_load_dword v111, v[38:39], off
	v_mul_f32_e32 v33, v110, v58
	global_store_short v[34:35], v42, off sc1
	v_lshl_add_u64 v[34:35], s[62:63], 0, v[36:37]
	global_load_dword v112, v[34:35], off
	v_add_u32_e32 v34, v71, v48
	v_ashrrev_i32_e32 v35, 31, v34
	v_cvt_pk_bf16_f32 v33, v33, s0
	v_lshl_add_u64 v[34:35], v[34:35], 1, s[8:9]
	global_store_short v[34:35], v33, off sc1
	v_add_u32_e32 v34, v180, v48
	v_ashrrev_i32_e32 v35, 31, v34
	v_mul_f32_e32 v33, v110, v57
	v_cvt_pk_bf16_f32 v33, v33, s0
	v_lshl_add_u64 v[34:35], v[34:35], 1, s[8:9]
	global_load_dword v38, v[90:91], off offset:256
	global_load_dword v37, v[92:93], off offset:256
	global_load_dword v36, v[94:95], off offset:256
	global_load_dword v114, v[104:105], off offset:256
	global_load_dword v47, v[84:85], off offset:256
	global_load_dword v39, v[86:87], off offset:256
	global_load_dword v46, v[82:83], off offset:256
	global_load_dword v44, v[78:79], off offset:256
	global_load_dword v43, v[72:73], off offset:256
	global_load_dword v42, v[74:75], off offset:256
	global_load_dword v40, v[80:81], off offset:256
	global_load_dword v41, v[76:77], off offset:256
	v_add_u32_e32 v108, v182, v48
	global_store_short v[34:35], v33, off sc1
	global_load_dword v35, v[96:97], off offset:256
	v_ashrrev_i32_e32 v109, 31, v108
	global_load_dword v34, v[98:99], off offset:256
	global_load_dword v33, v[100:101], off offset:256
	v_lshl_add_u64 v[108:109], v[108:109], 1, s[8:9]
	global_store_short v[108:109], v113, off sc1
	v_add_u32_e32 v108, v185, v48
	v_ashrrev_i32_e32 v109, 31, v108
	v_mul_f32_e32 v113, v110, v55
	v_cvt_pk_bf16_f32 v113, v113, s0
	v_lshl_add_u64 v[108:109], v[108:109], 1, s[8:9]
	global_store_short v[108:109], v113, off sc1
	v_add_u32_e32 v108, v187, v48
	v_ashrrev_i32_e32 v109, 31, v108
	v_mul_f32_e32 v113, v110, v54
	v_cvt_pk_bf16_f32 v113, v113, s0
	v_lshl_add_u64 v[108:109], v[108:109], 1, s[8:9]
	global_store_short v[108:109], v113, off sc1
	v_add_u32_e32 v108, v189, v48
	v_ashrrev_i32_e32 v109, 31, v108
	v_mul_f32_e32 v113, v110, v53
	v_cvt_pk_bf16_f32 v113, v113, s0
	v_lshl_add_u64 v[108:109], v[108:109], 1, s[8:9]
	global_store_short v[108:109], v113, off sc1
	v_add_u32_e32 v108, v190, v48
	v_ashrrev_i32_e32 v109, 31, v108
	v_mul_f32_e32 v113, v110, v52
	v_cvt_pk_bf16_f32 v113, v113, s0
	v_lshl_add_u64 v[108:109], v[108:109], 1, s[8:9]
	global_store_short v[108:109], v113, off sc1
	v_add_u32_e32 v108, v191, v48
	v_ashrrev_i32_e32 v109, 31, v108
	v_mul_f32_e32 v113, v110, v51
	v_cvt_pk_bf16_f32 v113, v113, s0
	v_lshl_add_u64 v[108:109], v[108:109], 1, s[8:9]
	global_store_short v[108:109], v113, off sc1
	v_add_u32_e32 v108, v192, v48
	v_ashrrev_i32_e32 v109, 31, v108
	v_mul_f32_e32 v113, v110, v50
	v_cvt_pk_bf16_f32 v113, v113, s0
	v_lshl_add_u64 v[108:109], v[108:109], 1, s[8:9]
	global_store_short v[108:109], v113, off sc1
	v_add_u32_e32 v108, v193, v48
	v_ashrrev_i32_e32 v109, 31, v108
	v_mul_f32_e32 v48, v110, v49
	v_cvt_pk_bf16_f32 v48, v48, s0
	v_lshl_add_u64 v[108:109], v[108:109], 1, s[8:9]
	global_store_short v[108:109], v48, off sc1
	v_add_u32_e32 v108, v188, v32
	v_ashrrev_i32_e32 v109, 31, v108
	s_waitcnt vmcnt(28)
	v_add_f32_e32 v48, 1.0, v107
	s_waitcnt vmcnt(27)
	v_mul_f32_e32 v48, v111, v48
	v_fmac_f32_e32 v106, v197, v197
	s_waitcnt vmcnt(25)
	v_fmac_f32_e32 v45, v17, v112
	global_store_dword v[88:89], v45, off offset:256 sc1
	s_waitcnt vmcnt(24)
	v_fmac_f32_e32 v38, v26, v112
	s_waitcnt vmcnt(23)
	v_fmac_f32_e32 v37, v27, v112
	s_waitcnt vmcnt(22)
	v_fmac_f32_e32 v36, v28, v112
	s_waitcnt vmcnt(21)
	v_fmac_f32_e32 v114, v16, v112
	v_mul_f32_e32 v16, v48, v114
	s_waitcnt vmcnt(20)
	v_fmac_f32_e32 v47, v18, v112
	v_cvt_pk_bf16_f32 v18, v16, s0
	v_lshl_add_u64 v[16:17], v[108:109], 1, s[8:9]
	global_store_short v[16:17], v18, off sc1
	v_add_u32_e32 v16, v186, v32
	v_ashrrev_i32_e32 v17, 31, v16
	v_mul_f32_e32 v18, v48, v45
	v_cvt_pk_bf16_f32 v18, v18, s0
	v_lshl_add_u64 v[16:17], v[16:17], 1, s[8:9]
	global_store_short v[16:17], v18, off sc1
	v_add_u32_e32 v16, v184, v32
	v_ashrrev_i32_e32 v17, 31, v16
	v_mul_f32_e32 v18, v48, v47
	v_cvt_pk_bf16_f32 v18, v18, s0
	v_lshl_add_u64 v[16:17], v[16:17], 1, s[8:9]
	s_waitcnt vmcnt(20)
	v_fmac_f32_e32 v46, v19, v112
	global_store_short v[16:17], v18, off sc1
	v_add_u32_e32 v16, v183, v32
	v_ashrrev_i32_e32 v17, 31, v16
	v_mul_f32_e32 v18, v48, v46
	s_waitcnt vmcnt(20)
	v_fmac_f32_e32 v44, v20, v112
	v_cvt_pk_bf16_f32 v18, v18, s0
	v_lshl_add_u64 v[16:17], v[16:17], 1, s[8:9]
	global_store_short v[16:17], v18, off sc1
	v_mul_f32_e32 v16, v48, v44
	v_cvt_pk_bf16_f32 v26, v16, s0
	v_or_b32_e32 v16, 0x60, v102
	v_add_u32_e32 v18, v181, v32
	v_ashrrev_i32_e32 v17, 31, v16
	s_waitcnt vmcnt(20)
	v_fmac_f32_e32 v43, v21, v112
	s_waitcnt vmcnt(19)
	v_fmac_f32_e32 v42, v22, v112
	s_waitcnt vmcnt(17)
	v_fmac_f32_e32 v41, v23, v112
	v_fmac_f32_e32 v40, v24, v112
	v_fmac_f32_e32 v39, v25, v112
	s_waitcnt vmcnt(15)
	v_fmac_f32_e32 v35, v29, v112
	s_waitcnt vmcnt(14)
	v_fmac_f32_e32 v34, v30, v112
	s_waitcnt vmcnt(13)
	v_fmac_f32_e32 v33, v31, v112
	v_ashrrev_i32_e32 v19, 31, v18
	v_lshlrev_b64 v[20:21], 2, v[16:17]
	global_store_dword v[84:85], v47, off offset:256 sc1
	global_store_dword v[82:83], v46, off offset:256 sc1
	global_store_dword v[78:79], v44, off offset:256 sc1
	global_store_dword v[72:73], v43, off offset:256 sc1
	global_store_dword v[74:75], v42, off offset:256 sc1
	global_store_dword v[76:77], v41, off offset:256 sc1
	global_store_dword v[80:81], v40, off offset:256 sc1
	global_store_dword v[86:87], v39, off offset:256 sc1
	global_store_dword v[90:91], v38, off offset:256 sc1
	global_store_dword v[92:93], v37, off offset:256 sc1
	global_store_dword v[94:95], v36, off offset:256 sc1
	global_store_dword v[96:97], v35, off offset:256 sc1
	global_store_dword v[98:99], v34, off offset:256 sc1
	global_store_dword v[100:101], v33, off offset:256 sc1
	global_store_dword v[104:105], v114, off offset:256 sc1
	v_lshl_add_u64 v[24:25], s[64:65], 0, v[20:21]
	v_lshl_add_u64 v[18:19], v[18:19], 1, s[8:9]
	global_load_dword v29, v[104:105], off offset:384
	v_lshl_add_u64 v[22:23], s[60:61], 0, v[20:21]
	global_load_dword v17, v[24:25], off
	global_load_dword v30, v[22:23], off
	global_load_dword v28, v[88:89], off offset:384
	global_load_dword v27, v[84:85], off offset:384
	v_fmac_f32_e32 v106, v114, v114
	global_store_short v[18:19], v26, off sc1
	v_lshl_add_u64 v[18:19], s[62:63], 0, v[20:21]
	global_load_dword v102, v[18:19], off
	v_add_u32_e32 v18, v179, v32
	v_ashrrev_i32_e32 v19, 31, v18
	v_mul_f32_e32 v20, v48, v43
	v_cvt_pk_bf16_f32 v20, v20, s0
	v_lshl_add_u64 v[18:19], v[18:19], 1, s[8:9]
	global_store_short v[18:19], v20, off sc1
	v_add_u32_e32 v18, v71, v32
	v_ashrrev_i32_e32 v19, 31, v18
	v_mul_f32_e32 v20, v48, v42
	v_cvt_pk_bf16_f32 v20, v20, s0
	v_lshl_add_u64 v[18:19], v[18:19], 1, s[8:9]
	global_store_short v[18:19], v20, off sc1
	v_add_u32_e32 v18, v180, v32
	v_ashrrev_i32_e32 v19, 31, v18
	v_mul_f32_e32 v20, v48, v41
	v_cvt_pk_bf16_f32 v20, v20, s0
	v_lshl_add_u64 v[18:19], v[18:19], 1, s[8:9]
	global_store_short v[18:19], v20, off sc1
	v_add_u32_e32 v18, v182, v32
	v_ashrrev_i32_e32 v19, 31, v18
	v_mul_f32_e32 v20, v48, v40
	v_cvt_pk_bf16_f32 v20, v20, s0
	v_lshl_add_u64 v[18:19], v[18:19], 1, s[8:9]
	global_store_short v[18:19], v20, off sc1
	v_add_u32_e32 v18, v185, v32
	v_ashrrev_i32_e32 v19, 31, v18
	v_mul_f32_e32 v20, v48, v39
	v_cvt_pk_bf16_f32 v20, v20, s0
	v_lshl_add_u64 v[18:19], v[18:19], 1, s[8:9]
	global_store_short v[18:19], v20, off sc1
	v_add_u32_e32 v18, v187, v32
	v_ashrrev_i32_e32 v19, 31, v18
	v_mul_f32_e32 v20, v48, v38
	v_cvt_pk_bf16_f32 v20, v20, s0
	v_lshl_add_u64 v[18:19], v[18:19], 1, s[8:9]
	global_store_short v[18:19], v20, off sc1
	v_add_u32_e32 v18, v189, v32
	v_ashrrev_i32_e32 v19, 31, v18
	v_mul_f32_e32 v20, v48, v37
	v_cvt_pk_bf16_f32 v20, v20, s0
	v_lshl_add_u64 v[18:19], v[18:19], 1, s[8:9]
	global_store_short v[18:19], v20, off sc1
	v_add_u32_e32 v18, v190, v32
	v_ashrrev_i32_e32 v19, 31, v18
	v_mul_f32_e32 v20, v48, v36
	v_cvt_pk_bf16_f32 v20, v20, s0
	v_lshl_add_u64 v[18:19], v[18:19], 1, s[8:9]
	global_store_short v[18:19], v20, off sc1
	v_add_u32_e32 v18, v191, v32
	v_ashrrev_i32_e32 v19, 31, v18
	v_mul_f32_e32 v20, v48, v35
	v_cvt_pk_bf16_f32 v20, v20, s0
	v_lshl_add_u64 v[18:19], v[18:19], 1, s[8:9]
	global_store_short v[18:19], v20, off sc1
	v_add_u32_e32 v18, v192, v32
	v_ashrrev_i32_e32 v19, 31, v18
	v_mul_f32_e32 v20, v48, v34
	v_cvt_pk_bf16_f32 v20, v20, s0
	v_lshl_add_u64 v[18:19], v[18:19], 1, s[8:9]
	global_store_short v[18:19], v20, off sc1
	v_add_u32_e32 v18, v193, v32
	v_ashrrev_i32_e32 v19, 31, v18
	v_mul_f32_e32 v20, v48, v33
	v_cvt_pk_bf16_f32 v20, v20, s0
	v_lshl_add_u64 v[18:19], v[18:19], 1, s[8:9]
	global_store_short v[18:19], v20, off sc1
	global_load_dword v20, v[86:87], off offset:384
	v_add_u32_e32 v18, v188, v16
	global_load_dword v26, v[82:83], off offset:384
	global_load_dword v25, v[78:79], off offset:384
	global_load_dword v24, v[72:73], off offset:384
	global_load_dword v23, v[74:75], off offset:384
	global_load_dword v21, v[80:81], off offset:384
	global_load_dword v22, v[76:77], off offset:384
	s_waitcnt vmcnt(23)
	v_add_f32_e32 v17, 1.0, v17
	s_waitcnt vmcnt(22)
	v_mul_f32_e32 v32, v30, v17
	v_ashrrev_i32_e32 v19, 31, v18
	v_lshl_add_u64 v[18:19], v[18:19], 1, s[8:9]
	v_add_u32_e32 v30, v186, v16
	s_waitcnt vmcnt(18)
	v_fmac_f32_e32 v29, v0, v102
	v_mul_f32_e32 v0, v32, v29
	v_cvt_pk_bf16_f32 v0, v0, s0
	global_store_short v[18:19], v0, off sc1
	global_load_dword v19, v[90:91], off offset:384
	v_ashrrev_i32_e32 v31, 31, v30
	global_load_dword v18, v[92:93], off offset:384
	v_fmac_f32_e32 v28, v1, v102
	v_mul_f32_e32 v0, v32, v28
	v_cvt_pk_bf16_f32 v17, v0, s0
	v_lshl_add_u64 v[0:1], v[30:31], 1, s[8:9]
	global_store_short v[0:1], v17, off sc1
	v_add_u32_e32 v0, v184, v16
	v_fmac_f32_e32 v27, v2, v102
	global_load_dword v17, v[94:95], off offset:384
	v_ashrrev_i32_e32 v1, 31, v0
	v_mul_f32_e32 v2, v32, v27
	v_cvt_pk_bf16_f32 v2, v2, s0
	v_lshl_add_u64 v[0:1], v[0:1], 1, s[8:9]
	global_store_short v[0:1], v2, off sc1
	v_add_u32_e32 v0, v183, v16
	global_load_dword v2, v[96:97], off offset:384
	v_ashrrev_i32_e32 v1, 31, v0
	v_lshl_add_u64 v[0:1], v[0:1], 1, s[8:9]
	v_add_u32_e32 v30, v181, v16
	v_ashrrev_i32_e32 v31, 31, v30
	v_lshl_add_u64 v[30:31], v[30:31], 1, s[8:9]
	v_fmac_f32_e32 v106, v29, v29
	global_store_dword v[104:105], v29, off offset:384 sc1
	global_store_dword v[88:89], v28, off offset:384 sc1
	global_store_dword v[84:85], v27, off offset:384 sc1
	s_waitcnt vmcnt(16)
	v_fmac_f32_e32 v20, v9, v102
	global_store_dword v[86:87], v20, off offset:384 sc1
	s_waitcnt vmcnt(16)
	v_fmac_f32_e32 v26, v3, v102
	v_mul_f32_e32 v3, v32, v26
	v_cvt_pk_bf16_f32 v3, v3, s0
	global_store_short v[0:1], v3, off sc1
	global_load_dword v1, v[98:99], off offset:384
	s_waitcnt vmcnt(17)
	v_fmac_f32_e32 v25, v4, v102
	v_mul_f32_e32 v0, v32, v25
	v_cvt_pk_bf16_f32 v0, v0, s0
	global_store_short v[30:31], v0, off sc1
	global_load_dword v0, v[100:101], off offset:384
	v_add_u32_e32 v30, v179, v16
	s_waitcnt vmcnt(18)
	v_fmac_f32_e32 v24, v5, v102
	v_ashrrev_i32_e32 v31, 31, v30
	v_mul_f32_e32 v3, v32, v24
	v_cvt_pk_bf16_f32 v3, v3, s0
	v_lshl_add_u64 v[4:5], v[30:31], 1, s[8:9]
	global_store_short v[4:5], v3, off sc1
	v_add_u32_e32 v4, v71, v16
	s_waitcnt vmcnt(18)
	v_fmac_f32_e32 v23, v6, v102
	v_ashrrev_i32_e32 v5, 31, v4
	v_mul_f32_e32 v3, v32, v23
	v_cvt_pk_bf16_f32 v3, v3, s0
	v_lshl_add_u64 v[4:5], v[4:5], 1, s[8:9]
	global_store_short v[4:5], v3, off sc1
	v_add_u32_e32 v4, v180, v16
	s_waitcnt vmcnt(17)
	v_fmac_f32_e32 v22, v7, v102
	v_ashrrev_i32_e32 v5, 31, v4
	v_mul_f32_e32 v3, v32, v22
	v_cvt_pk_bf16_f32 v3, v3, s0
	v_lshl_add_u64 v[4:5], v[4:5], 1, s[8:9]
	global_store_short v[4:5], v3, off sc1
	v_add_u32_e32 v4, v182, v16
	v_fmac_f32_e32 v21, v8, v102
	v_ashrrev_i32_e32 v5, 31, v4
	v_mul_f32_e32 v3, v32, v21
	v_cvt_pk_bf16_f32 v3, v3, s0
	v_lshl_add_u64 v[4:5], v[4:5], 1, s[8:9]
	global_store_short v[4:5], v3, off sc1
	v_add_u32_e32 v4, v185, v16
	v_ashrrev_i32_e32 v5, 31, v4
	v_mul_f32_e32 v3, v32, v20
	v_cvt_pk_bf16_f32 v3, v3, s0
	v_lshl_add_u64 v[4:5], v[4:5], 1, s[8:9]
	global_store_short v[4:5], v3, off sc1
	v_add_u32_e32 v4, v187, v16
	s_waitcnt vmcnt(18)
	v_fmac_f32_e32 v19, v10, v102
	v_ashrrev_i32_e32 v5, 31, v4
	v_mul_f32_e32 v3, v32, v19
	v_cvt_pk_bf16_f32 v3, v3, s0
	v_lshl_add_u64 v[4:5], v[4:5], 1, s[8:9]
	global_store_short v[4:5], v3, off sc1
	v_add_u32_e32 v4, v189, v16
	s_waitcnt vmcnt(18)
	v_fmac_f32_e32 v18, v11, v102
	v_ashrrev_i32_e32 v5, 31, v4
	v_mul_f32_e32 v3, v32, v18
	v_cvt_pk_bf16_f32 v3, v3, s0
	v_lshl_add_u64 v[4:5], v[4:5], 1, s[8:9]
	global_store_short v[4:5], v3, off sc1
	v_add_u32_e32 v4, v190, v16
	s_waitcnt vmcnt(17)
	v_fmac_f32_e32 v17, v12, v102
	v_ashrrev_i32_e32 v5, 31, v4
	v_mul_f32_e32 v3, v32, v17
	v_cvt_pk_bf16_f32 v3, v3, s0
	v_lshl_add_u64 v[4:5], v[4:5], 1, s[8:9]
	global_store_short v[4:5], v3, off sc1
	v_add_u32_e32 v4, v191, v16
	s_waitcnt vmcnt(16)
	v_fmac_f32_e32 v2, v13, v102
	v_ashrrev_i32_e32 v5, 31, v4
	v_mul_f32_e32 v3, v32, v2
	v_cvt_pk_bf16_f32 v3, v3, s0
	v_lshl_add_u64 v[4:5], v[4:5], 1, s[8:9]
	global_store_short v[4:5], v3, off sc1
	v_add_u32_e32 v4, v192, v16
	v_ashrrev_i32_e32 v5, 31, v4
	v_lshl_add_u64 v[4:5], v[4:5], 1, s[8:9]
	v_xor_b32_e32 v13, 16, v164
	v_add_u32_e32 v10, v193, v16
	v_ashrrev_i32_e32 v11, 31, v10
	v_lshl_add_u64 v[10:11], v[10:11], 1, s[8:9]
	v_ashrrev_i32_e32 v71, 31, v70
	global_store_dword v[82:83], v26, off offset:384 sc1
	global_store_dword v[78:79], v25, off offset:384 sc1
	global_store_dword v[72:73], v24, off offset:384 sc1
	global_store_dword v[74:75], v23, off offset:384 sc1
	s_waitcnt vmcnt(15)
	v_fmac_f32_e32 v1, v14, v102
	v_mul_f32_e32 v3, v32, v1
	v_cvt_pk_bf16_f32 v3, v3, s0
	global_store_short v[4:5], v3, off sc1
	v_and_b32_e32 v4, 64, v164
	v_xor_b32_e32 v3, 1, v164
	v_add_u32_e32 v7, 64, v4
	v_cmp_lt_i32_e32 vcc, v3, v7
	v_xor_b32_e32 v4, 2, v164
	s_waitcnt vmcnt(14)
	v_fmac_f32_e32 v0, v15, v102
	v_cndmask_b32_e32 v3, v164, v3, vcc
	v_lshlrev_b32_e32 v3, 2, v3
	v_cmp_lt_i32_e32 vcc, v4, v7
	v_mul_f32_e32 v12, v32, v0
	v_cvt_pk_bf16_f32 v12, v12, s0
	v_cndmask_b32_e32 v4, v164, v4, vcc
	v_lshlrev_b32_e32 v4, 2, v4
	v_add_f32_dpp v6, v106, v106 quad_perm:[1,0,3,2] row_mask:0xf bank_mask:0xf
	v_xor_b32_e32 v5, 4, v164
	v_cmp_lt_i32_e32 vcc, v5, v7
	global_store_dword v[76:77], v22, off offset:384 sc1
	global_store_dword v[80:81], v21, off offset:384 sc1
	v_cndmask_b32_e32 v5, v164, v5, vcc
	v_lshlrev_b32_e32 v5, 2, v5
	v_add_f32_dpp v8, v6, v6 quad_perm:[2,3,0,1] row_mask:0xf bank_mask:0xf
	v_xor_b32_e32 v6, 8, v164
	v_cmp_lt_i32_e32 vcc, v6, v7
	global_store_dword v[90:91], v19, off offset:384 sc1
	global_store_dword v[92:93], v18, off offset:384 sc1
	v_cndmask_b32_e32 v6, v164, v6, vcc
	v_lshlrev_b32_e32 v6, 2, v6
	v_add_f32_dpp v8, v8, v8 row_half_mirror row_mask:0xf bank_mask:0xf
	v_cmp_lt_i32_e32 vcc, v13, v7
	global_store_dword v[94:95], v17, off offset:384 sc1
	global_store_dword v[96:97], v2, off offset:384 sc1
	v_cndmask_b32_e32 v7, v164, v13, vcc
	v_lshlrev_b32_e32 v7, 2, v7
	v_add_f32_dpp v8, v8, v8 row_mirror row_mask:0xf bank_mask:0xf
	ds_bpermute_b32 v9, v7, v8
	global_store_dword v[98:99], v1, off offset:384 sc1
	global_store_dword v[100:101], v0, off offset:384 sc1
	global_store_short v[10:11], v12, off sc1
	s_and_saveexec_b64 s[60:61], s[0:1]
	s_cbranch_execz .LBB0_1052
	s_waitcnt lgkmcnt(0)
	v_add_f32_e32 v10, v8, v9
	v_lshl_add_u64 v[8:9], v[70:71], 2, s[58:59]
	global_store_dword v[8:9], v10, off sc1
.LBB0_1052:
	s_or_b64 exec, exec, s[60:61]
	v_mul_f32_e32 v8, v63, v63
	v_fmac_f32_e32 v8, v178, v178
	v_fmac_f32_e32 v8, v45, v45
	v_fmac_f32_e32 v8, v28, v28
	s_waitcnt lgkmcnt(0)
	v_add_f32_dpp v8, v8, v8 quad_perm:[1,0,3,2] row_mask:0xf bank_mask:0xf
	s_nop 0
	v_add_f32_dpp v8, v8, v8 quad_perm:[2,3,0,1] row_mask:0xf bank_mask:0xf
	s_nop 0
	v_add_f32_dpp v8, v8, v8 row_half_mirror row_mask:0xf bank_mask:0xf
	s_nop 0
	v_add_f32_dpp v8, v8, v8 row_mirror row_mask:0xf bank_mask:0xf
	ds_bpermute_b32 v9, v7, v8
	s_and_saveexec_b64 s[60:61], s[0:1]
	s_cbranch_execz .LBB0_1054
	s_waitcnt lgkmcnt(0)
	v_add_f32_e32 v10, v8, v9
	v_lshl_add_u64 v[8:9], v[70:71], 2, s[58:59]
	global_store_dword v[8:9], v10, off offset:4 sc1
.LBB0_1054:
	s_or_b64 exec, exec, s[60:61]
	v_mul_f32_e32 v8, v62, v62
	v_fmac_f32_e32 v8, v177, v177
	v_fmac_f32_e32 v8, v47, v47
	v_fmac_f32_e32 v8, v27, v27
	s_waitcnt lgkmcnt(0)
	v_add_f32_dpp v8, v8, v8 quad_perm:[1,0,3,2] row_mask:0xf bank_mask:0xf
	s_nop 0
	v_add_f32_dpp v8, v8, v8 quad_perm:[2,3,0,1] row_mask:0xf bank_mask:0xf
	s_nop 0
	v_add_f32_dpp v8, v8, v8 row_half_mirror row_mask:0xf bank_mask:0xf
	s_nop 0
	v_add_f32_dpp v8, v8, v8 row_mirror row_mask:0xf bank_mask:0xf
	ds_bpermute_b32 v9, v7, v8
	s_and_saveexec_b64 s[60:61], s[0:1]
	s_cbranch_execz .LBB0_1056
	s_waitcnt lgkmcnt(0)
	v_add_f32_e32 v10, v8, v9
	v_lshl_add_u64 v[8:9], v[70:71], 2, s[58:59]
	global_store_dword v[8:9], v10, off offset:8 sc1
.LBB0_1056:
	s_or_b64 exec, exec, s[60:61]
	v_mul_f32_e32 v8, v61, v61
	v_fmac_f32_e32 v8, v176, v176
	v_fmac_f32_e32 v8, v46, v46
	v_fmac_f32_e32 v8, v26, v26
	s_waitcnt lgkmcnt(0)
	v_add_f32_dpp v8, v8, v8 quad_perm:[1,0,3,2] row_mask:0xf bank_mask:0xf
	s_nop 0
	v_add_f32_dpp v8, v8, v8 quad_perm:[2,3,0,1] row_mask:0xf bank_mask:0xf
	s_nop 0
	v_add_f32_dpp v8, v8, v8 row_half_mirror row_mask:0xf bank_mask:0xf
	s_nop 0
	v_add_f32_dpp v8, v8, v8 row_mirror row_mask:0xf bank_mask:0xf
	ds_bpermute_b32 v9, v7, v8
	s_and_saveexec_b64 s[60:61], s[0:1]
	s_cbranch_execz .LBB0_1058
	s_waitcnt lgkmcnt(0)
	v_add_f32_e32 v10, v8, v9
	v_lshl_add_u64 v[8:9], v[70:71], 2, s[58:59]
	global_store_dword v[8:9], v10, off offset:12 sc1
.LBB0_1058:
	s_or_b64 exec, exec, s[60:61]
	v_mul_f32_e32 v8, v60, v60
	v_fmac_f32_e32 v8, v175, v175
	v_fmac_f32_e32 v8, v44, v44
	v_fmac_f32_e32 v8, v25, v25
	s_waitcnt lgkmcnt(0)
	v_add_f32_dpp v8, v8, v8 quad_perm:[1,0,3,2] row_mask:0xf bank_mask:0xf
	s_nop 0
	v_add_f32_dpp v8, v8, v8 quad_perm:[2,3,0,1] row_mask:0xf bank_mask:0xf
	s_nop 0
	v_add_f32_dpp v8, v8, v8 row_half_mirror row_mask:0xf bank_mask:0xf
	s_nop 0
	v_add_f32_dpp v8, v8, v8 row_mirror row_mask:0xf bank_mask:0xf
	ds_bpermute_b32 v9, v7, v8
	s_and_saveexec_b64 s[60:61], s[0:1]
	s_cbranch_execz .LBB0_1060
	s_waitcnt lgkmcnt(0)
	v_add_f32_e32 v10, v8, v9
	v_lshl_add_u64 v[8:9], v[70:71], 2, s[58:59]
	global_store_dword v[8:9], v10, off offset:32 sc1
.LBB0_1060:
	s_or_b64 exec, exec, s[60:61]
	v_mul_f32_e32 v8, v59, v59
	v_fmac_f32_e32 v8, v174, v174
	v_fmac_f32_e32 v8, v43, v43
	v_fmac_f32_e32 v8, v24, v24
	s_waitcnt lgkmcnt(0)
	v_add_f32_dpp v8, v8, v8 quad_perm:[1,0,3,2] row_mask:0xf bank_mask:0xf
	s_nop 0
	v_add_f32_dpp v8, v8, v8 quad_perm:[2,3,0,1] row_mask:0xf bank_mask:0xf
	s_nop 0
	v_add_f32_dpp v8, v8, v8 row_half_mirror row_mask:0xf bank_mask:0xf
	s_nop 0
	v_add_f32_dpp v8, v8, v8 row_mirror row_mask:0xf bank_mask:0xf
	ds_bpermute_b32 v9, v7, v8
	s_and_saveexec_b64 s[60:61], s[0:1]
	s_cbranch_execz .LBB0_1062
	s_waitcnt lgkmcnt(0)
	v_add_f32_e32 v10, v8, v9
	v_lshl_add_u64 v[8:9], v[70:71], 2, s[58:59]
	global_store_dword v[8:9], v10, off offset:36 sc1
.LBB0_1062:
	s_or_b64 exec, exec, s[60:61]
	v_mul_f32_e32 v8, v58, v58
	v_fmac_f32_e32 v8, v173, v173
	v_fmac_f32_e32 v8, v42, v42
	v_fmac_f32_e32 v8, v23, v23
	s_waitcnt lgkmcnt(0)
	v_add_f32_dpp v8, v8, v8 quad_perm:[1,0,3,2] row_mask:0xf bank_mask:0xf
	s_nop 0
	v_add_f32_dpp v8, v8, v8 quad_perm:[2,3,0,1] row_mask:0xf bank_mask:0xf
	s_nop 0
	v_add_f32_dpp v8, v8, v8 row_half_mirror row_mask:0xf bank_mask:0xf
	s_nop 0
	v_add_f32_dpp v8, v8, v8 row_mirror row_mask:0xf bank_mask:0xf
	ds_bpermute_b32 v9, v7, v8
	s_and_saveexec_b64 s[60:61], s[0:1]
	s_cbranch_execz .LBB0_1064
	s_waitcnt lgkmcnt(0)
	v_add_f32_e32 v10, v8, v9
	v_lshl_add_u64 v[8:9], v[70:71], 2, s[58:59]
	global_store_dword v[8:9], v10, off offset:40 sc1
.LBB0_1064:
	s_or_b64 exec, exec, s[60:61]
	v_mul_f32_e32 v8, v57, v57
	v_fmac_f32_e32 v8, v172, v172
	v_fmac_f32_e32 v8, v41, v41
	v_fmac_f32_e32 v8, v22, v22
	s_waitcnt lgkmcnt(0)
	v_add_f32_dpp v8, v8, v8 quad_perm:[1,0,3,2] row_mask:0xf bank_mask:0xf
	s_nop 0
	v_add_f32_dpp v8, v8, v8 quad_perm:[2,3,0,1] row_mask:0xf bank_mask:0xf
	s_nop 0
	v_add_f32_dpp v8, v8, v8 row_half_mirror row_mask:0xf bank_mask:0xf
	s_nop 0
	v_add_f32_dpp v8, v8, v8 row_mirror row_mask:0xf bank_mask:0xf
	ds_bpermute_b32 v9, v7, v8
	s_and_saveexec_b64 s[60:61], s[0:1]
	s_cbranch_execz .LBB0_1066
	s_waitcnt lgkmcnt(0)
	v_add_f32_e32 v10, v8, v9
	v_lshl_add_u64 v[8:9], v[70:71], 2, s[58:59]
	global_store_dword v[8:9], v10, off offset:44 sc1
.LBB0_1066:
	s_or_b64 exec, exec, s[60:61]
	v_mul_f32_e32 v8, v56, v56
	v_fmac_f32_e32 v8, v171, v171
	v_fmac_f32_e32 v8, v40, v40
	v_fmac_f32_e32 v8, v21, v21
	s_waitcnt lgkmcnt(0)
	v_add_f32_dpp v8, v8, v8 quad_perm:[1,0,3,2] row_mask:0xf bank_mask:0xf
	s_nop 0
	v_add_f32_dpp v8, v8, v8 quad_perm:[2,3,0,1] row_mask:0xf bank_mask:0xf
	s_nop 0
	v_add_f32_dpp v8, v8, v8 row_half_mirror row_mask:0xf bank_mask:0xf
	s_nop 0
	v_add_f32_dpp v8, v8, v8 row_mirror row_mask:0xf bank_mask:0xf
	ds_bpermute_b32 v9, v7, v8
	s_and_saveexec_b64 s[60:61], s[0:1]
	s_cbranch_execz .LBB0_1068
	s_waitcnt lgkmcnt(0)
	v_add_f32_e32 v10, v8, v9
	v_lshl_add_u64 v[8:9], v[70:71], 2, s[58:59]
	global_store_dword v[8:9], v10, off offset:64 sc1
.LBB0_1068:
	s_or_b64 exec, exec, s[60:61]
	v_mul_f32_e32 v8, v55, v55
	v_fmac_f32_e32 v8, v170, v170
	v_fmac_f32_e32 v8, v39, v39
	v_fmac_f32_e32 v8, v20, v20
	s_waitcnt lgkmcnt(0)
	v_add_f32_dpp v8, v8, v8 quad_perm:[1,0,3,2] row_mask:0xf bank_mask:0xf
	s_nop 0
	v_add_f32_dpp v8, v8, v8 quad_perm:[2,3,0,1] row_mask:0xf bank_mask:0xf
	s_nop 0
	v_add_f32_dpp v8, v8, v8 row_half_mirror row_mask:0xf bank_mask:0xf
	s_nop 0
	v_add_f32_dpp v8, v8, v8 row_mirror row_mask:0xf bank_mask:0xf
	ds_bpermute_b32 v9, v7, v8
	s_and_saveexec_b64 s[60:61], s[0:1]
	s_cbranch_execz .LBB0_1070
	s_waitcnt lgkmcnt(0)
	v_add_f32_e32 v10, v8, v9
	v_lshl_add_u64 v[8:9], v[70:71], 2, s[58:59]
	global_store_dword v[8:9], v10, off offset:68 sc1
.LBB0_1070:
	s_or_b64 exec, exec, s[60:61]
	v_mul_f32_e32 v8, v54, v54
	v_fmac_f32_e32 v8, v168, v168
	v_fmac_f32_e32 v8, v38, v38
	v_fmac_f32_e32 v8, v19, v19
	s_waitcnt lgkmcnt(0)
	v_add_f32_dpp v8, v8, v8 quad_perm:[1,0,3,2] row_mask:0xf bank_mask:0xf
	s_nop 0
	v_add_f32_dpp v8, v8, v8 quad_perm:[2,3,0,1] row_mask:0xf bank_mask:0xf
	s_nop 0
	v_add_f32_dpp v8, v8, v8 row_half_mirror row_mask:0xf bank_mask:0xf
	s_nop 0
	v_add_f32_dpp v8, v8, v8 row_mirror row_mask:0xf bank_mask:0xf
	ds_bpermute_b32 v9, v7, v8
	s_and_saveexec_b64 s[60:61], s[0:1]
	s_cbranch_execz .LBB0_1072
	s_waitcnt lgkmcnt(0)
	v_add_f32_e32 v10, v8, v9
	v_lshl_add_u64 v[8:9], v[70:71], 2, s[58:59]
	global_store_dword v[8:9], v10, off offset:72 sc1
.LBB0_1072:
	s_or_b64 exec, exec, s[60:61]
	v_mul_f32_e32 v8, v53, v53
	v_fmac_f32_e32 v8, v169, v169
	v_fmac_f32_e32 v8, v37, v37
	v_fmac_f32_e32 v8, v18, v18
	s_waitcnt lgkmcnt(0)
	v_add_f32_dpp v8, v8, v8 quad_perm:[1,0,3,2] row_mask:0xf bank_mask:0xf
	s_nop 0
	v_add_f32_dpp v8, v8, v8 quad_perm:[2,3,0,1] row_mask:0xf bank_mask:0xf
	s_nop 0
	v_add_f32_dpp v8, v8, v8 row_half_mirror row_mask:0xf bank_mask:0xf
	s_nop 0
	v_add_f32_dpp v8, v8, v8 row_mirror row_mask:0xf bank_mask:0xf
	ds_bpermute_b32 v9, v7, v8
	s_and_saveexec_b64 s[60:61], s[0:1]
	s_cbranch_execz .LBB0_1074
	s_waitcnt lgkmcnt(0)
	v_add_f32_e32 v10, v8, v9
	v_lshl_add_u64 v[8:9], v[70:71], 2, s[58:59]
	global_store_dword v[8:9], v10, off offset:76 sc1
.LBB0_1074:
	s_or_b64 exec, exec, s[60:61]
	v_mul_f32_e32 v8, v52, v52
	v_fmac_f32_e32 v8, v167, v167
	v_fmac_f32_e32 v8, v36, v36
	v_fmac_f32_e32 v8, v17, v17
	s_waitcnt lgkmcnt(0)
	v_add_f32_dpp v8, v8, v8 quad_perm:[1,0,3,2] row_mask:0xf bank_mask:0xf
	s_nop 0
	v_add_f32_dpp v8, v8, v8 quad_perm:[2,3,0,1] row_mask:0xf bank_mask:0xf
	s_nop 0
	v_add_f32_dpp v8, v8, v8 row_half_mirror row_mask:0xf bank_mask:0xf
	s_nop 0
	v_add_f32_dpp v8, v8, v8 row_mirror row_mask:0xf bank_mask:0xf
	ds_bpermute_b32 v9, v7, v8
	s_and_saveexec_b64 s[60:61], s[0:1]
	s_cbranch_execz .LBB0_1076
	s_waitcnt lgkmcnt(0)
	v_add_f32_e32 v10, v8, v9
	v_lshl_add_u64 v[8:9], v[70:71], 2, s[58:59]
	global_store_dword v[8:9], v10, off offset:96 sc1
.LBB0_1076:
	s_or_b64 exec, exec, s[60:61]
	v_mul_f32_e32 v8, v51, v51
	v_fmac_f32_e32 v8, v166, v166
	v_fmac_f32_e32 v8, v35, v35
	v_fmac_f32_e32 v8, v2, v2
	s_waitcnt lgkmcnt(0)
	s_nop 0
	v_add_f32_dpp v2, v8, v8 quad_perm:[1,0,3,2] row_mask:0xf bank_mask:0xf
	s_nop 0
	v_add_f32_dpp v2, v2, v2 quad_perm:[2,3,0,1] row_mask:0xf bank_mask:0xf
	s_nop 0
	v_add_f32_dpp v2, v2, v2 row_half_mirror row_mask:0xf bank_mask:0xf
	s_nop 0
	v_add_f32_dpp v2, v2, v2 row_mirror row_mask:0xf bank_mask:0xf
	ds_bpermute_b32 v8, v7, v2
	s_and_saveexec_b64 s[60:61], s[0:1]
	s_cbranch_execz .LBB0_1078
	s_waitcnt lgkmcnt(0)
	v_add_f32_e32 v2, v2, v8
	v_lshl_add_u64 v[8:9], v[70:71], 2, s[58:59]
	global_store_dword v[8:9], v2, off offset:100 sc1
.LBB0_1078:
	s_or_b64 exec, exec, s[60:61]
	v_mul_f32_e32 v2, v50, v50
	v_fmac_f32_e32 v2, v165, v165
	v_fmac_f32_e32 v2, v34, v34
	v_fmac_f32_e32 v2, v1, v1
	s_waitcnt lgkmcnt(0)
	s_nop 0
	v_add_f32_dpp v1, v2, v2 quad_perm:[1,0,3,2] row_mask:0xf bank_mask:0xf
	s_nop 0
	v_add_f32_dpp v1, v1, v1 quad_perm:[2,3,0,1] row_mask:0xf bank_mask:0xf
	s_nop 0
	v_add_f32_dpp v1, v1, v1 row_half_mirror row_mask:0xf bank_mask:0xf
	s_nop 0
	v_add_f32_dpp v1, v1, v1 row_mirror row_mask:0xf bank_mask:0xf
	ds_bpermute_b32 v2, v7, v1
	s_and_saveexec_b64 s[60:61], s[0:1]
	s_cbranch_execz .LBB0_1080
	s_waitcnt lgkmcnt(0)
	v_add_f32_e32 v1, v1, v2
	v_lshl_add_u64 v[8:9], v[70:71], 2, s[58:59]
	global_store_dword v[8:9], v1, off offset:104 sc1

.LBB0_1122:
	s_add_i32 s58, s67, 0xffffe000
	s_lshr_b32 s58, s58, 12
	s_mulk_i32 s58, 0x1800
	s_addk_i32 s58, 0x1800
	s_cmp_gt_i32 s6, 63
	s_cselect_b32 s62, s58, 0
	s_add_i32 s6, s62, 0x4800
	s_lshl_b64 s[58:59], s[6:7], 2
	s_add_u32 s6, s14, s58
	s_addc_u32 s58, s15, s59
	s_add_u32 s60, s6, 0x5ba5000
	s_addc_u32 s61, s58, 0
	s_add_i32 s6, s62, 0x9000
	s_lshl_b64 s[58:59], s[6:7], 2
	v_mov_b32_e32 v70, s66
	s_add_u32 s6, s14, s58
	ds_read_b64 v[70:71], v70
	s_addc_u32 s69, s15, s59
	s_lshl_b32 s58, s64, 14
	s_add_i32 s58, s58, 0x80000
	s_ashr_i32 s59, s58, 31
	s_lshl_b64 s[58:59], s[58:59], 2
	s_add_u32 s58, s10, s58
	s_waitcnt lgkmcnt(0)
	v_readfirstlane_b32 s63, v70
	s_addc_u32 s59, s11, s59
	v_or_b32_e32 v102, s68, v138
	v_add_u32_e32 v70, s67, v139
	v_readfirstlane_b32 s65, v71
	s_add_u32 s62, s63, 0x2000
	v_ashrrev_i32_e32 v103, 31, v102
	v_lshlrev_b32_e32 v191, 10, v70
	s_addc_u32 s63, s65, 0
	v_lshlrev_b64 v[72:73], 2, v[102:103]
	v_or_b32_e32 v187, 0x400, v191
	v_or_b32_e32 v186, 0x4400, v191
	v_or_b32_e32 v189, 0x4c00, v191
	v_or_b32_e32 v194, 0x6c00, v191
	s_add_u32 s64, s6, 0x5ba1000
	v_lshl_add_u64 v[74:75], s[60:61], 0, v[72:73]
	v_add_u32_e32 v130, v191, v102
	v_add_u32_e32 v132, v187, v102
	v_or_b32_e32 v185, 0x800, v191
	v_or_b32_e32 v184, 0xc00, v191
	v_or_b32_e32 v182, 0x2000, v191
	v_or_b32_e32 v180, 0x2400, v191
	v_or_b32_e32 v71, 0x2800, v191
	v_or_b32_e32 v181, 0x2c00, v191
	v_or_b32_e32 v183, 0x4000, v191
	v_add_u32_e32 v112, v186, v102
	v_or_b32_e32 v188, 0x4800, v191
	v_add_u32_e32 v116, v189, v102
	v_or_b32_e32 v190, 0x6000, v191
	v_or_b32_e32 v192, 0x6400, v191
	v_or_b32_e32 v193, 0x6800, v191
	v_add_u32_e32 v128, v194, v102
	s_addc_u32 s65, s69, 0
	global_load_dword v195, v[74:75], off
	v_lshl_add_u64 v[74:75], s[62:63], 0, v[72:73]
	v_ashrrev_i32_e32 v133, 31, v132
	v_add_u32_e32 v134, v185, v102
	v_add_u32_e32 v136, v184, v102
	v_add_u32_e32 v126, v182, v102
	v_add_u32_e32 v118, v180, v102
	v_add_u32_e32 v110, v71, v102
	v_add_u32_e32 v106, v181, v102
	v_add_u32_e32 v108, v183, v102
	v_ashrrev_i32_e32 v113, 31, v112
	v_add_u32_e32 v114, v188, v102
	v_ashrrev_i32_e32 v117, 31, v116
	v_add_u32_e32 v120, v190, v102
	v_add_u32_e32 v122, v192, v102
	v_add_u32_e32 v124, v193, v102
	v_ashrrev_i32_e32 v129, 31, v128
	v_ashrrev_i32_e32 v131, 31, v130
	v_lshl_add_u64 v[72:73], s[64:65], 0, v[72:73]
	global_load_dword v196, v[74:75], off
	global_load_dword v197, v[72:73], off
	v_lshl_add_u64 v[88:89], v[132:133], 2, s[12:13]
	v_ashrrev_i32_e32 v135, 31, v134
	v_ashrrev_i32_e32 v137, 31, v136
	v_ashrrev_i32_e32 v127, 31, v126
	v_ashrrev_i32_e32 v119, 31, v118
	v_ashrrev_i32_e32 v111, 31, v110
	v_ashrrev_i32_e32 v107, 31, v106
	v_ashrrev_i32_e32 v109, 31, v108
	v_lshl_add_u64 v[86:87], v[112:113], 2, s[12:13]
	v_ashrrev_i32_e32 v115, 31, v114
	v_lshl_add_u64 v[92:93], v[116:117], 2, s[12:13]
	v_ashrrev_i32_e32 v121, 31, v120
	v_ashrrev_i32_e32 v123, 31, v122
	v_ashrrev_i32_e32 v125, 31, v124
	v_lshl_add_u64 v[100:101], v[128:129], 2, s[12:13]
	v_lshl_add_u64 v[104:105], v[130:131], 2, s[12:13]
	v_lshl_add_u64 v[84:85], v[134:135], 2, s[12:13]
	v_lshl_add_u64 v[82:83], v[136:137], 2, s[12:13]
	v_lshl_add_u64 v[78:79], v[126:127], 2, s[12:13]
	v_lshl_add_u64 v[72:73], v[118:119], 2, s[12:13]
	v_lshl_add_u64 v[74:75], v[110:111], 2, s[12:13]
	v_lshl_add_u64 v[76:77], v[106:107], 2, s[12:13]
	v_lshl_add_u64 v[80:81], v[108:109], 2, s[12:13]
	global_load_dword v179, v[88:89], off
	global_load_dword v178, v[84:85], off
	global_load_dword v177, v[82:83], off
	global_load_dword v176, v[78:79], off
	global_load_dword v175, v[72:73], off
	global_load_dword v174, v[74:75], off
	global_load_dword v173, v[76:77], off
	global_load_dword v172, v[80:81], off
	v_lshl_add_u64 v[90:91], v[114:115], 2, s[12:13]
	global_load_dword v171, v[86:87], off
	global_load_dword v169, v[90:91], off
	v_lshl_add_u64 v[94:95], v[120:121], 2, s[12:13]
	v_lshl_add_u64 v[96:97], v[122:123], 2, s[12:13]
	v_lshl_add_u64 v[98:99], v[124:125], 2, s[12:13]
	global_load_dword v170, v[92:93], off
	global_load_dword v168, v[94:95], off
	global_load_dword v167, v[96:97], off
	global_load_dword v166, v[98:99], off
	global_load_dword v103, v[100:101], off
	global_load_dword v198, v[104:105], off
	v_lshl_add_u64 v[110:111], v[110:111], 1, s[8:9]
	v_lshl_add_u64 v[106:107], v[106:107], 1, s[8:9]
	s_waitcnt vmcnt(0)
	v_add_f32_e32 v197, 1.0, v197
	v_mul_f32_e32 v196, v196, v197
	v_fmac_f32_e32 v179, v49, v195
	v_fmac_f32_e32 v178, v50, v195
	v_fmac_f32_e32 v177, v51, v195
	v_fmac_f32_e32 v176, v52, v195
	v_fmac_f32_e32 v175, v53, v195
	v_fmac_f32_e32 v174, v54, v195
	v_fmac_f32_e32 v173, v55, v195
	v_fmac_f32_e32 v172, v56, v195
	v_fmac_f32_e32 v171, v57, v195
	v_fmac_f32_e32 v169, v58, v195
	v_fmac_f32_e32 v170, v59, v195
	v_fmac_f32_e32 v168, v60, v195
	v_fmac_f32_e32 v167, v61, v195
	v_fmac_f32_e32 v166, v62, v195
	v_fmac_f32_e32 v103, v63, v195
	v_fmac_f32_e32 v198, v48, v195
	v_mul_f32_e32 v48, v196, v198
	v_cvt_pk_bf16_f32 v58, v48, s0
	v_or_b32_e32 v48, 32, v102
	v_ashrrev_i32_e32 v49, 31, v48
	v_lshlrev_b64 v[52:53], 2, v[48:49]
	global_store_dword v[88:89], v179, off sc1
	global_store_dword v[84:85], v178, off sc1
	global_store_dword v[82:83], v177, off sc1
	global_store_dword v[78:79], v176, off sc1
	global_store_dword v[72:73], v175, off sc1
	global_store_dword v[74:75], v174, off sc1
	global_store_dword v[76:77], v173, off sc1
	global_store_dword v[80:81], v172, off sc1
	global_store_dword v[86:87], v171, off sc1
	global_store_dword v[90:91], v169, off sc1
	global_store_dword v[92:93], v170, off sc1
	global_store_dword v[94:95], v168, off sc1
	global_store_dword v[96:97], v167, off sc1
	global_store_dword v[98:99], v166, off sc1
	global_store_dword v[100:101], v103, off sc1
	global_store_dword v[104:105], v198, off sc1
	v_lshl_add_u64 v[50:51], v[130:131], 1, s[8:9]
	v_lshl_add_u64 v[56:57], s[64:65], 0, v[52:53]
	global_load_dword v197, v[104:105], off offset:128
	v_lshl_add_u64 v[54:55], s[62:63], 0, v[52:53]
	global_load_dword v130, v[56:57], off
	global_load_dword v131, v[54:55], off
	v_mul_f32_e32 v49, v196, v179
	global_store_short v[50:51], v58, off sc1
	v_lshl_add_u64 v[50:51], s[60:61], 0, v[52:53]
	global_load_dword v195, v[50:51], off
	v_lshl_add_u64 v[50:51], v[132:133], 1, s[8:9]
	v_cvt_pk_bf16_f32 v49, v49, s0
	global_store_short v[50:51], v49, off sc1
	v_mul_f32_e32 v49, v196, v178
	v_lshl_add_u64 v[50:51], v[134:135], 1, s[8:9]
	v_cvt_pk_bf16_f32 v49, v49, s0
	global_store_short v[50:51], v49, off sc1
	v_mul_f32_e32 v49, v196, v177
	v_lshl_add_u64 v[50:51], v[136:137], 1, s[8:9]
	v_cvt_pk_bf16_f32 v49, v49, s0
	global_store_short v[50:51], v49, off sc1
	v_mul_f32_e32 v49, v196, v176
	v_lshl_add_u64 v[50:51], v[126:127], 1, s[8:9]
	v_cvt_pk_bf16_f32 v49, v49, s0
	global_store_short v[50:51], v49, off sc1
	v_mul_f32_e32 v49, v196, v175
	v_lshl_add_u64 v[50:51], v[118:119], 1, s[8:9]
	v_cvt_pk_bf16_f32 v49, v49, s0
	global_load_dword v62, v[84:85], off offset:128
	global_load_dword v60, v[78:79], off offset:128
	global_load_dword v59, v[72:73], off offset:128
	global_load_dword v58, v[74:75], off offset:128
	global_load_dword v56, v[80:81], off offset:128
	global_load_dword v57, v[76:77], off offset:128
	global_load_dword v55, v[86:87], off offset:128
	global_load_dword v61, v[82:83], off offset:128
	global_load_dword v54, v[90:91], off offset:128
	global_load_dword v53, v[92:93], off offset:128
	global_load_dword v52, v[94:95], off offset:128
	v_mul_f32_e32 v63, v196, v174
	global_store_short v[50:51], v49, off sc1
	global_load_dword v51, v[96:97], off offset:128
	v_cvt_pk_bf16_f32 v63, v63, s0
	global_load_dword v50, v[98:99], off offset:128
	global_load_dword v49, v[100:101], off offset:128
	s_waitcnt vmcnt(19)
	v_fmac_f32_e32 v197, v32, v195
	global_store_short v[110:111], v63, off sc1
	global_load_dword v63, v[88:89], off offset:128
	v_mul_f32_e32 v110, v196, v173
	v_cvt_pk_bf16_f32 v110, v110, s0
	global_store_short v[106:107], v110, off sc1
	v_lshl_add_u64 v[106:107], v[108:109], 1, s[8:9]
	v_mul_f32_e32 v108, v196, v172
	v_cvt_pk_bf16_f32 v108, v108, s0
	global_store_short v[106:107], v108, off sc1
	v_mul_f32_e32 v108, v196, v171
	v_lshl_add_u64 v[106:107], v[112:113], 1, s[8:9]
	v_cvt_pk_bf16_f32 v108, v108, s0
	global_store_short v[106:107], v108, off sc1
	v_mul_f32_e32 v108, v196, v169
	v_lshl_add_u64 v[106:107], v[114:115], 1, s[8:9]
	v_cvt_pk_bf16_f32 v108, v108, s0
	global_store_short v[106:107], v108, off sc1
	v_mul_f32_e32 v108, v196, v170
	v_lshl_add_u64 v[106:107], v[116:117], 1, s[8:9]
	v_cvt_pk_bf16_f32 v108, v108, s0
	global_store_short v[106:107], v108, off sc1
	v_mul_f32_e32 v108, v196, v168
	v_lshl_add_u64 v[106:107], v[120:121], 1, s[8:9]
	v_cvt_pk_bf16_f32 v108, v108, s0
	global_store_short v[106:107], v108, off sc1
	v_mul_f32_e32 v108, v196, v167
	v_lshl_add_u64 v[106:107], v[122:123], 1, s[8:9]
	v_cvt_pk_bf16_f32 v108, v108, s0
	global_store_short v[106:107], v108, off sc1
	v_mul_f32_e32 v108, v196, v166
	v_lshl_add_u64 v[106:107], v[124:125], 1, s[8:9]
	v_cvt_pk_bf16_f32 v108, v108, s0
	global_store_short v[106:107], v108, off sc1
	v_mul_f32_e32 v108, v196, v103
	v_lshl_add_u64 v[106:107], v[128:129], 1, s[8:9]
	v_cvt_pk_bf16_f32 v108, v108, s0
	global_store_short v[106:107], v108, off sc1
	v_add_f32_e32 v106, 1.0, v130
	v_mul_f32_e32 v107, v131, v106
	v_add_u32_e32 v108, v191, v48
	v_ashrrev_i32_e32 v109, 31, v108
	v_mul_f32_e32 v32, v107, v197
	s_waitcnt vmcnt(25)
	v_fmac_f32_e32 v62, v34, v195
	s_waitcnt vmcnt(18)
	v_fmac_f32_e32 v61, v35, v195
	v_fmac_f32_e32 v60, v36, v195
	v_fmac_f32_e32 v59, v37, v195
	v_fmac_f32_e32 v58, v38, v195
	v_fmac_f32_e32 v57, v39, v195
	v_fmac_f32_e32 v56, v40, v195
	v_fmac_f32_e32 v55, v41, v195
	s_waitcnt vmcnt(17)
	v_fmac_f32_e32 v54, v42, v195
	s_waitcnt vmcnt(16)
	v_fmac_f32_e32 v53, v43, v195
	s_waitcnt vmcnt(15)
	v_fmac_f32_e32 v52, v44, v195
	s_waitcnt vmcnt(13)
	v_fmac_f32_e32 v51, v45, v195
	s_waitcnt vmcnt(12)
	v_fmac_f32_e32 v50, v46, v195
	s_waitcnt vmcnt(11)
	v_fmac_f32_e32 v49, v47, v195
	global_store_dword v[104:105], v197, off offset:128 sc1
	v_lshl_add_u64 v[108:109], v[108:109], 1, s[8:9]
	v_cvt_pk_bf16_f32 v32, v32, s0
	global_store_dword v[84:85], v62, off offset:128 sc1
	global_store_dword v[82:83], v61, off offset:128 sc1
	global_store_dword v[78:79], v60, off offset:128 sc1
	global_store_dword v[72:73], v59, off offset:128 sc1
	global_store_dword v[74:75], v58, off offset:128 sc1
	global_store_dword v[76:77], v57, off offset:128 sc1
	global_store_dword v[80:81], v56, off offset:128 sc1
	global_store_dword v[86:87], v55, off offset:128 sc1
	global_store_dword v[90:91], v54, off offset:128 sc1
	global_store_dword v[92:93], v53, off offset:128 sc1
	global_store_dword v[94:95], v52, off offset:128 sc1
	global_store_dword v[96:97], v51, off offset:128 sc1
	global_store_dword v[98:99], v50, off offset:128 sc1
	global_store_dword v[100:101], v49, off offset:128 sc1
	global_store_short v[108:109], v32, off sc1
	v_add_u32_e32 v108, v187, v48
	global_load_dword v45, v[88:89], off offset:256
	v_ashrrev_i32_e32 v109, 31, v108
	v_mul_f32_e32 v113, v107, v56
	v_cvt_pk_bf16_f32 v113, v113, s0
	v_mul_f32_e32 v106, v197, v197
	v_fmac_f32_e32 v106, v198, v198
	s_waitcnt vmcnt(26)
	v_fmac_f32_e32 v63, v33, v195
	v_mul_f32_e32 v34, v107, v63
	v_lshl_add_u64 v[32:33], v[108:109], 1, s[8:9]
	v_cvt_pk_bf16_f32 v34, v34, s0
	global_store_short v[32:33], v34, off sc1
	v_add_u32_e32 v32, v185, v48
	v_ashrrev_i32_e32 v33, 31, v32
	v_mul_f32_e32 v34, v107, v62
	v_lshl_add_u64 v[32:33], v[32:33], 1, s[8:9]
	v_cvt_pk_bf16_f32 v34, v34, s0
	global_store_short v[32:33], v34, off sc1
	v_add_u32_e32 v32, v184, v48
	v_ashrrev_i32_e32 v33, 31, v32
	v_mul_f32_e32 v34, v107, v61
	v_lshl_add_u64 v[32:33], v[32:33], 1, s[8:9]
	v_cvt_pk_bf16_f32 v34, v34, s0
	global_store_short v[32:33], v34, off sc1
	v_add_u32_e32 v32, v182, v48
	v_ashrrev_i32_e32 v33, 31, v32
	v_mul_f32_e32 v34, v107, v60
	v_lshl_add_u64 v[32:33], v[32:33], 1, s[8:9]
	v_cvt_pk_bf16_f32 v34, v34, s0
	global_store_short v[32:33], v34, off sc1
	v_add_u32_e32 v32, v180, v48
	v_ashrrev_i32_e32 v33, 31, v32
	v_lshl_add_u64 v[34:35], v[32:33], 1, s[8:9]
	v_mul_f32_e32 v32, v107, v59
	v_cvt_pk_bf16_f32 v42, v32, s0
	v_or_b32_e32 v32, 64, v102
	v_ashrrev_i32_e32 v33, 31, v32
	v_lshlrev_b64 v[36:37], 2, v[32:33]
	global_store_dword v[88:89], v63, off offset:128 sc1
	v_lshl_add_u64 v[40:41], s[64:65], 0, v[36:37]
	v_lshl_add_u64 v[38:39], s[62:63], 0, v[36:37]
	global_load_dword v110, v[40:41], off
	global_load_dword v111, v[38:39], off
	v_mul_f32_e32 v33, v107, v58
	global_store_short v[34:35], v42, off sc1
	v_lshl_add_u64 v[34:35], s[60:61], 0, v[36:37]
	global_load_dword v112, v[34:35], off
	v_add_u32_e32 v34, v71, v48
	v_ashrrev_i32_e32 v35, 31, v34
	v_lshl_add_u64 v[34:35], v[34:35], 1, s[8:9]
	v_cvt_pk_bf16_f32 v33, v33, s0
	global_store_short v[34:35], v33, off sc1
	v_add_u32_e32 v34, v181, v48
	v_ashrrev_i32_e32 v35, 31, v34
	v_mul_f32_e32 v33, v107, v57
	v_lshl_add_u64 v[34:35], v[34:35], 1, s[8:9]
	v_cvt_pk_bf16_f32 v33, v33, s0
	global_load_dword v38, v[90:91], off offset:256
	global_load_dword v37, v[92:93], off offset:256
	global_load_dword v36, v[94:95], off offset:256
	global_load_dword v114, v[104:105], off offset:256
	global_load_dword v47, v[84:85], off offset:256
	global_load_dword v39, v[86:87], off offset:256
	global_load_dword v46, v[82:83], off offset:256
	global_load_dword v44, v[78:79], off offset:256
	global_load_dword v43, v[72:73], off offset:256
	global_load_dword v42, v[74:75], off offset:256
	global_load_dword v40, v[80:81], off offset:256
	global_load_dword v41, v[76:77], off offset:256
	v_add_u32_e32 v108, v183, v48
	global_store_short v[34:35], v33, off sc1
	global_load_dword v35, v[96:97], off offset:256
	v_ashrrev_i32_e32 v109, 31, v108
	global_load_dword v34, v[98:99], off offset:256
	global_load_dword v33, v[100:101], off offset:256
	v_lshl_add_u64 v[108:109], v[108:109], 1, s[8:9]
	global_store_short v[108:109], v113, off sc1
	v_add_u32_e32 v108, v186, v48
	v_ashrrev_i32_e32 v109, 31, v108
	v_mul_f32_e32 v113, v107, v55
	v_lshl_add_u64 v[108:109], v[108:109], 1, s[8:9]
	v_cvt_pk_bf16_f32 v113, v113, s0
	global_store_short v[108:109], v113, off sc1
	v_add_u32_e32 v108, v188, v48
	v_ashrrev_i32_e32 v109, 31, v108
	v_mul_f32_e32 v113, v107, v54
	v_lshl_add_u64 v[108:109], v[108:109], 1, s[8:9]
	v_cvt_pk_bf16_f32 v113, v113, s0
	global_store_short v[108:109], v113, off sc1
	v_add_u32_e32 v108, v189, v48
	v_ashrrev_i32_e32 v109, 31, v108
	v_mul_f32_e32 v113, v107, v53
	v_lshl_add_u64 v[108:109], v[108:109], 1, s[8:9]
	v_cvt_pk_bf16_f32 v113, v113, s0
	global_store_short v[108:109], v113, off sc1
	v_add_u32_e32 v108, v190, v48
	v_ashrrev_i32_e32 v109, 31, v108
	v_mul_f32_e32 v113, v107, v52
	v_lshl_add_u64 v[108:109], v[108:109], 1, s[8:9]
	v_cvt_pk_bf16_f32 v113, v113, s0
	global_store_short v[108:109], v113, off sc1
	v_add_u32_e32 v108, v192, v48
	v_ashrrev_i32_e32 v109, 31, v108
	v_mul_f32_e32 v113, v107, v51
	v_lshl_add_u64 v[108:109], v[108:109], 1, s[8:9]
	v_cvt_pk_bf16_f32 v113, v113, s0
	global_store_short v[108:109], v113, off sc1
	v_add_u32_e32 v108, v193, v48
	v_ashrrev_i32_e32 v109, 31, v108
	v_mul_f32_e32 v113, v107, v50
	v_lshl_add_u64 v[108:109], v[108:109], 1, s[8:9]
	v_cvt_pk_bf16_f32 v113, v113, s0
	global_store_short v[108:109], v113, off sc1
	v_add_u32_e32 v108, v194, v48
	v_ashrrev_i32_e32 v109, 31, v108
	v_mul_f32_e32 v48, v107, v49
	v_lshl_add_u64 v[108:109], v[108:109], 1, s[8:9]
	v_cvt_pk_bf16_f32 v48, v48, s0
	global_store_short v[108:109], v48, off sc1
	v_add_u32_e32 v108, v191, v32
	v_ashrrev_i32_e32 v109, 31, v108
	s_waitcnt vmcnt(28)
	v_add_f32_e32 v48, 1.0, v110
	s_waitcnt vmcnt(27)
	v_mul_f32_e32 v48, v111, v48
	s_waitcnt vmcnt(25)
	v_fmac_f32_e32 v45, v17, v112
	global_store_dword v[88:89], v45, off offset:256 sc1
	s_waitcnt vmcnt(24)
	v_fmac_f32_e32 v38, v26, v112
	s_waitcnt vmcnt(23)
	v_fmac_f32_e32 v37, v27, v112
	s_waitcnt vmcnt(22)
	v_fmac_f32_e32 v36, v28, v112
	s_waitcnt vmcnt(21)
	v_fmac_f32_e32 v114, v16, v112
	s_waitcnt vmcnt(20)
	v_fmac_f32_e32 v47, v18, v112
	v_mul_f32_e32 v18, v48, v114
	v_lshl_add_u64 v[16:17], v[108:109], 1, s[8:9]
	v_cvt_pk_bf16_f32 v18, v18, s0
	global_store_short v[16:17], v18, off sc1
	v_add_u32_e32 v16, v187, v32
	v_ashrrev_i32_e32 v17, 31, v16
	v_mul_f32_e32 v18, v48, v45
	v_lshl_add_u64 v[16:17], v[16:17], 1, s[8:9]
	v_cvt_pk_bf16_f32 v18, v18, s0
	global_store_short v[16:17], v18, off sc1
	v_add_u32_e32 v16, v185, v32
	v_ashrrev_i32_e32 v17, 31, v16
	v_mul_f32_e32 v18, v48, v47
	v_lshl_add_u64 v[16:17], v[16:17], 1, s[8:9]
	v_cvt_pk_bf16_f32 v18, v18, s0
	s_waitcnt vmcnt(20)
	v_fmac_f32_e32 v46, v19, v112
	global_store_short v[16:17], v18, off sc1
	v_add_u32_e32 v16, v184, v32
	v_ashrrev_i32_e32 v17, 31, v16
	v_mul_f32_e32 v18, v48, v46
	v_lshl_add_u64 v[16:17], v[16:17], 1, s[8:9]
	v_cvt_pk_bf16_f32 v18, v18, s0
	global_store_short v[16:17], v18, off sc1
	v_add_u32_e32 v16, v182, v32
	v_ashrrev_i32_e32 v17, 31, v16
	v_lshl_add_u64 v[18:19], v[16:17], 1, s[8:9]
	v_or_b32_e32 v16, 0x60, v102
	v_ashrrev_i32_e32 v17, 31, v16
	s_waitcnt vmcnt(21)
	v_fmac_f32_e32 v44, v20, v112
	s_waitcnt vmcnt(20)
	v_fmac_f32_e32 v43, v21, v112
	s_waitcnt vmcnt(19)
	v_fmac_f32_e32 v42, v22, v112
	s_waitcnt vmcnt(17)
	v_fmac_f32_e32 v41, v23, v112
	v_fmac_f32_e32 v40, v24, v112
	v_fmac_f32_e32 v39, v25, v112
	s_waitcnt vmcnt(15)
	v_fmac_f32_e32 v35, v29, v112
	s_waitcnt vmcnt(14)
	v_fmac_f32_e32 v34, v30, v112
	s_waitcnt vmcnt(13)
	v_fmac_f32_e32 v33, v31, v112
	v_lshlrev_b64 v[20:21], 2, v[16:17]
	global_store_dword v[84:85], v47, off offset:256 sc1
	global_store_dword v[82:83], v46, off offset:256 sc1
	global_store_dword v[78:79], v44, off offset:256 sc1
	global_store_dword v[72:73], v43, off offset:256 sc1
	global_store_dword v[74:75], v42, off offset:256 sc1
	global_store_dword v[76:77], v41, off offset:256 sc1
	global_store_dword v[80:81], v40, off offset:256 sc1
	global_store_dword v[86:87], v39, off offset:256 sc1
	global_store_dword v[90:91], v38, off offset:256 sc1
	global_store_dword v[92:93], v37, off offset:256 sc1
	global_store_dword v[94:95], v36, off offset:256 sc1
	global_store_dword v[96:97], v35, off offset:256 sc1
	global_store_dword v[98:99], v34, off offset:256 sc1
	global_store_dword v[100:101], v33, off offset:256 sc1
	global_store_dword v[104:105], v114, off offset:256 sc1
	v_mul_f32_e32 v26, v48, v44
	v_lshl_add_u64 v[22:23], s[62:63], 0, v[20:21]
	v_lshl_add_u64 v[24:25], s[64:65], 0, v[20:21]
	global_load_dword v29, v[104:105], off offset:384
	global_load_dword v17, v[24:25], off
	global_load_dword v30, v[22:23], off
	v_cvt_pk_bf16_f32 v22, v26, s0
	global_store_short v[18:19], v22, off sc1
	v_lshl_add_u64 v[18:19], s[60:61], 0, v[20:21]
	global_load_dword v102, v[18:19], off
	v_add_u32_e32 v18, v180, v32
	v_ashrrev_i32_e32 v19, 31, v18
	v_mul_f32_e32 v20, v48, v43
	v_lshl_add_u64 v[18:19], v[18:19], 1, s[8:9]
	v_cvt_pk_bf16_f32 v20, v20, s0
	global_store_short v[18:19], v20, off sc1
	v_add_u32_e32 v18, v71, v32
	v_ashrrev_i32_e32 v19, 31, v18
	v_mul_f32_e32 v20, v48, v42
	v_lshl_add_u64 v[18:19], v[18:19], 1, s[8:9]
	v_cvt_pk_bf16_f32 v20, v20, s0
	global_store_short v[18:19], v20, off sc1
	v_add_u32_e32 v18, v181, v32
	v_ashrrev_i32_e32 v19, 31, v18
	v_mul_f32_e32 v20, v48, v41
	v_lshl_add_u64 v[18:19], v[18:19], 1, s[8:9]
	v_cvt_pk_bf16_f32 v20, v20, s0
	global_store_short v[18:19], v20, off sc1
	v_add_u32_e32 v18, v183, v32
	v_ashrrev_i32_e32 v19, 31, v18
	v_mul_f32_e32 v20, v48, v40
	v_lshl_add_u64 v[18:19], v[18:19], 1, s[8:9]
	v_cvt_pk_bf16_f32 v20, v20, s0
	global_store_short v[18:19], v20, off sc1
	v_add_u32_e32 v18, v186, v32
	v_ashrrev_i32_e32 v19, 31, v18
	v_mul_f32_e32 v20, v48, v39
	v_lshl_add_u64 v[18:19], v[18:19], 1, s[8:9]
	v_cvt_pk_bf16_f32 v20, v20, s0
	global_store_short v[18:19], v20, off sc1
	v_add_u32_e32 v18, v188, v32
	v_ashrrev_i32_e32 v19, 31, v18
	v_mul_f32_e32 v20, v48, v38
	v_lshl_add_u64 v[18:19], v[18:19], 1, s[8:9]
	v_cvt_pk_bf16_f32 v20, v20, s0
	global_store_short v[18:19], v20, off sc1
	v_add_u32_e32 v18, v189, v32
	v_ashrrev_i32_e32 v19, 31, v18
	v_mul_f32_e32 v20, v48, v37
	v_lshl_add_u64 v[18:19], v[18:19], 1, s[8:9]
	v_cvt_pk_bf16_f32 v20, v20, s0
	global_store_short v[18:19], v20, off sc1
	v_add_u32_e32 v18, v190, v32
	v_ashrrev_i32_e32 v19, 31, v18
	v_mul_f32_e32 v20, v48, v36
	v_lshl_add_u64 v[18:19], v[18:19], 1, s[8:9]
	v_cvt_pk_bf16_f32 v20, v20, s0
	global_store_short v[18:19], v20, off sc1
	v_add_u32_e32 v18, v192, v32
	v_ashrrev_i32_e32 v19, 31, v18
	v_mul_f32_e32 v20, v48, v35
	v_lshl_add_u64 v[18:19], v[18:19], 1, s[8:9]
	v_cvt_pk_bf16_f32 v20, v20, s0
	global_load_dword v28, v[88:89], off offset:384
	global_load_dword v27, v[84:85], off offset:384
	global_load_dword v25, v[78:79], off offset:384
	global_load_dword v24, v[72:73], off offset:384
	global_load_dword v23, v[74:75], off offset:384
	global_load_dword v21, v[80:81], off offset:384
	global_load_dword v22, v[76:77], off offset:384
	v_fmac_f32_e32 v106, v114, v114
	global_store_short v[18:19], v20, off sc1
	v_add_u32_e32 v18, v193, v32
	v_ashrrev_i32_e32 v19, 31, v18
	v_mul_f32_e32 v20, v48, v34
	v_lshl_add_u64 v[18:19], v[18:19], 1, s[8:9]
	v_cvt_pk_bf16_f32 v20, v20, s0
	global_store_short v[18:19], v20, off sc1
	v_add_u32_e32 v18, v194, v32
	v_ashrrev_i32_e32 v19, 31, v18
	v_mul_f32_e32 v20, v48, v33
	v_lshl_add_u64 v[18:19], v[18:19], 1, s[8:9]
	v_cvt_pk_bf16_f32 v20, v20, s0
	global_store_short v[18:19], v20, off sc1
	global_load_dword v20, v[86:87], off offset:384
	s_waitcnt vmcnt(22)
	v_add_f32_e32 v17, 1.0, v17
	global_load_dword v26, v[82:83], off offset:384
	s_waitcnt vmcnt(22)
	v_mul_f32_e32 v32, v30, v17
	v_add_u32_e32 v18, v191, v16
	s_waitcnt vmcnt(20)
	v_fmac_f32_e32 v29, v0, v102
	v_ashrrev_i32_e32 v19, 31, v18
	v_mul_f32_e32 v0, v32, v29
	v_lshl_add_u64 v[18:19], v[18:19], 1, s[8:9]
	v_cvt_pk_bf16_f32 v0, v0, s0
	global_store_short v[18:19], v0, off sc1
	global_load_dword v19, v[90:91], off offset:384
	v_add_u32_e32 v30, v187, v16
	global_load_dword v18, v[92:93], off offset:384
	v_ashrrev_i32_e32 v31, 31, v30
	v_fmac_f32_e32 v106, v29, v29
	global_store_dword v[104:105], v29, off offset:384 sc1
	s_waitcnt vmcnt(15)
	v_fmac_f32_e32 v28, v1, v102
	v_mul_f32_e32 v17, v32, v28
	v_lshl_add_u64 v[0:1], v[30:31], 1, s[8:9]
	v_cvt_pk_bf16_f32 v17, v17, s0
	global_store_short v[0:1], v17, off sc1
	v_add_u32_e32 v0, v185, v16
	s_waitcnt vmcnt(15)
	v_fmac_f32_e32 v27, v2, v102
	global_load_dword v17, v[94:95], off offset:384
	v_ashrrev_i32_e32 v1, 31, v0
	v_mul_f32_e32 v2, v32, v27
	v_lshl_add_u64 v[0:1], v[0:1], 1, s[8:9]
	v_cvt_pk_bf16_f32 v2, v2, s0
	global_store_short v[0:1], v2, off sc1
	v_add_u32_e32 v0, v184, v16
	global_load_dword v2, v[96:97], off offset:384
	v_ashrrev_i32_e32 v1, 31, v0
	v_lshl_add_u64 v[0:1], v[0:1], 1, s[8:9]
	v_add_u32_e32 v30, v182, v16
	s_waitcnt vmcnt(17)
	v_fmac_f32_e32 v25, v4, v102
	v_ashrrev_i32_e32 v31, 31, v30
	v_lshl_add_u64 v[30:31], v[30:31], 1, s[8:9]
	s_waitcnt vmcnt(16)
	v_fmac_f32_e32 v24, v5, v102
	s_waitcnt vmcnt(15)
	v_fmac_f32_e32 v23, v6, v102
	s_waitcnt vmcnt(8)
	v_fmac_f32_e32 v26, v3, v102
	v_mul_f32_e32 v3, v32, v26
	v_cvt_pk_bf16_f32 v3, v3, s0
	global_store_short v[0:1], v3, off sc1
	global_load_dword v1, v[98:99], off offset:384
	v_mul_f32_e32 v0, v32, v25
	v_cvt_pk_bf16_f32 v0, v0, s0
	global_store_short v[30:31], v0, off sc1
	global_load_dword v0, v[100:101], off offset:384
	v_add_u32_e32 v30, v180, v16
	v_ashrrev_i32_e32 v31, 31, v30
	v_mul_f32_e32 v3, v32, v24
	v_lshl_add_u64 v[4:5], v[30:31], 1, s[8:9]
	v_cvt_pk_bf16_f32 v3, v3, s0
	global_store_short v[4:5], v3, off sc1
	v_add_u32_e32 v4, v71, v16
	v_ashrrev_i32_e32 v5, 31, v4
	v_mul_f32_e32 v3, v32, v23
	v_lshl_add_u64 v[4:5], v[4:5], 1, s[8:9]
	v_cvt_pk_bf16_f32 v3, v3, s0
	global_store_short v[4:5], v3, off sc1
	v_add_u32_e32 v4, v181, v16
	v_fmac_f32_e32 v22, v7, v102
	v_ashrrev_i32_e32 v5, 31, v4
	v_mul_f32_e32 v3, v32, v22
	v_lshl_add_u64 v[4:5], v[4:5], 1, s[8:9]
	v_cvt_pk_bf16_f32 v3, v3, s0
	global_store_short v[4:5], v3, off sc1
	v_add_u32_e32 v4, v183, v16
	v_fmac_f32_e32 v21, v8, v102
	v_ashrrev_i32_e32 v5, 31, v4
	v_mul_f32_e32 v3, v32, v21
	v_lshl_add_u64 v[4:5], v[4:5], 1, s[8:9]
	v_cvt_pk_bf16_f32 v3, v3, s0
	global_store_short v[4:5], v3, off sc1
	v_add_u32_e32 v4, v186, v16
	v_fmac_f32_e32 v20, v9, v102
	v_ashrrev_i32_e32 v5, 31, v4
	v_mul_f32_e32 v3, v32, v20
	v_lshl_add_u64 v[4:5], v[4:5], 1, s[8:9]
	v_cvt_pk_bf16_f32 v3, v3, s0
	global_store_short v[4:5], v3, off sc1
	v_add_u32_e32 v4, v188, v16
	s_waitcnt vmcnt(15)
	v_fmac_f32_e32 v19, v10, v102
	v_ashrrev_i32_e32 v5, 31, v4
	v_mul_f32_e32 v3, v32, v19
	v_lshl_add_u64 v[4:5], v[4:5], 1, s[8:9]
	v_cvt_pk_bf16_f32 v3, v3, s0
	global_store_short v[4:5], v3, off sc1
	v_add_u32_e32 v4, v189, v16
	s_waitcnt vmcnt(15)
	v_fmac_f32_e32 v18, v11, v102
	v_ashrrev_i32_e32 v5, 31, v4
	v_mul_f32_e32 v3, v32, v18
	v_lshl_add_u64 v[4:5], v[4:5], 1, s[8:9]
	v_cvt_pk_bf16_f32 v3, v3, s0
	global_store_short v[4:5], v3, off sc1
	v_add_u32_e32 v4, v190, v16
	v_ashrrev_i32_e32 v5, 31, v4
	v_lshl_add_u64 v[4:5], v[4:5], 1, s[8:9]
	v_ashrrev_i32_e32 v71, 31, v70
	global_store_dword v[88:89], v28, off offset:384 sc1
	global_store_dword v[84:85], v27, off offset:384 sc1
	global_store_dword v[82:83], v26, off offset:384 sc1
	global_store_dword v[78:79], v25, off offset:384 sc1
	s_waitcnt vmcnt(17)
	v_fmac_f32_e32 v17, v12, v102
	v_mul_f32_e32 v3, v32, v17
	v_cvt_pk_bf16_f32 v3, v3, s0
	global_store_short v[4:5], v3, off sc1
	v_add_u32_e32 v4, v192, v16
	v_ashrrev_i32_e32 v5, 31, v4
	v_lshl_add_u64 v[4:5], v[4:5], 1, s[8:9]
	s_waitcnt vmcnt(16)
	v_fmac_f32_e32 v2, v13, v102
	v_mul_f32_e32 v3, v32, v2
	v_cvt_pk_bf16_f32 v3, v3, s0
	global_store_short v[4:5], v3, off sc1
	v_add_u32_e32 v4, v193, v16
	v_ashrrev_i32_e32 v5, 31, v4
	v_lshl_add_u64 v[4:5], v[4:5], 1, s[8:9]
	v_xor_b32_e32 v12, 16, v165
	global_store_dword v[72:73], v24, off offset:384 sc1
	global_store_dword v[74:75], v23, off offset:384 sc1
	global_store_dword v[76:77], v22, off offset:384 sc1
	global_store_dword v[80:81], v21, off offset:384 sc1
	global_store_dword v[86:87], v20, off offset:384 sc1
	s_waitcnt vmcnt(20)
	v_fmac_f32_e32 v1, v14, v102
	v_mul_f32_e32 v3, v32, v1
	v_cvt_pk_bf16_f32 v3, v3, s0
	global_store_short v[4:5], v3, off sc1
	v_add_u32_e32 v4, v194, v16
	v_ashrrev_i32_e32 v5, 31, v4
	v_lshl_add_u64 v[10:11], v[4:5], 1, s[8:9]
	v_and_b32_e32 v4, 64, v165
	v_xor_b32_e32 v3, 1, v165
	v_add_u32_e32 v7, 64, v4
	v_cmp_lt_i32_e32 vcc, v3, v7
	v_xor_b32_e32 v4, 2, v165
	s_waitcnt vmcnt(19)
	v_fmac_f32_e32 v0, v15, v102
	v_cndmask_b32_e32 v3, v165, v3, vcc
	v_lshlrev_b32_e32 v3, 2, v3
	v_cmp_lt_i32_e32 vcc, v4, v7
	global_store_dword v[90:91], v19, off offset:384 sc1
	global_store_dword v[92:93], v18, off offset:384 sc1
	v_cndmask_b32_e32 v4, v165, v4, vcc
	v_lshlrev_b32_e32 v4, 2, v4
	v_add_f32_dpp v6, v106, v106 quad_perm:[1,0,3,2] row_mask:0xf bank_mask:0xf
	v_xor_b32_e32 v5, 4, v165
	v_cmp_lt_i32_e32 vcc, v5, v7
	global_store_dword v[94:95], v17, off offset:384 sc1
	global_store_dword v[96:97], v2, off offset:384 sc1
	v_cndmask_b32_e32 v5, v165, v5, vcc
	v_lshlrev_b32_e32 v5, 2, v5
	v_add_f32_dpp v8, v6, v6 quad_perm:[2,3,0,1] row_mask:0xf bank_mask:0xf
	v_xor_b32_e32 v6, 8, v165
	v_cmp_lt_i32_e32 vcc, v6, v7
	global_store_dword v[98:99], v1, off offset:384 sc1
	global_store_dword v[100:101], v0, off offset:384 sc1
	v_cndmask_b32_e32 v6, v165, v6, vcc
	v_lshlrev_b32_e32 v6, 2, v6
	v_add_f32_dpp v8, v8, v8 row_half_mirror row_mask:0xf bank_mask:0xf
	v_cmp_lt_i32_e32 vcc, v12, v7
	v_add_f32_dpp v8, v8, v8 row_mirror row_mask:0xf bank_mask:0xf
	v_cndmask_b32_e32 v7, v165, v12, vcc
	v_lshlrev_b32_e32 v7, 2, v7
	ds_bpermute_b32 v9, v7, v8
	v_mul_f32_e32 v12, v32, v0
	v_cvt_pk_bf16_f32 v12, v12, s0
	global_store_short v[10:11], v12, off sc1
	s_and_saveexec_b64 s[60:61], s[0:1]
	s_cbranch_execz .LBB0_1124
	s_waitcnt lgkmcnt(0)
	v_add_f32_e32 v10, v8, v9
	v_lshl_add_u64 v[8:9], v[70:71], 2, s[58:59]
	global_store_dword v[8:9], v10, off sc1

.LBB0_1189:
	s_and_b64 vcc, exec, s[4:5]
	s_cbranch_vccz .LBB0_1170
	v_mov_b32_e32 v12, s82
	ds_read_b64 v[12:13], v12
	s_add_i32 s73, s84, -8
	s_cmp_lt_i32 s85, 64
	s_cselect_b64 s[68:69], -1, 0
	s_and_b64 s[4:5], s[68:69], exec
	s_waitcnt lgkmcnt(0)
	v_readfirstlane_b32 s8, v12
	s_cselect_b32 s4, 0, 0x200
	v_readfirstlane_b32 s70, v13
	s_add_u32 s4, s8, s4
	s_addc_u32 s5, s70, 0
	v_lshlrev_b32_e32 v14, 2, v108
	global_load_dword v13, v14, s[4:5]
	global_load_dword v12, v14, s[4:5] offset:128
	global_load_dword v15, v14, s[4:5] offset:256
	s_nop 0
	global_load_dword v14, v14, s[4:5] offset:384
	v_and_b32_e32 v31, 64, v170
	v_xor_b32_e32 v30, 1, v170
	v_pk_mul_f32 v[26:27], v[90:91], v[90:91]
	v_add_u32_e32 v31, 64, v31
	v_pk_mul_f32 v[28:29], v[92:93], v[92:93]
	v_add_f32_e32 v26, v27, v26
	v_cmp_lt_i32_e32 vcc, v30, v31
	v_add_f32_e32 v26, v26, v29
	v_add_f32_e32 v26, v26, v28
	v_cndmask_b32_e32 v27, v170, v30, vcc
	v_lshlrev_b32_e32 v42, 2, v27
	v_xor_b32_e32 v28, 2, v170
	v_cmp_lt_i32_e32 vcc, v28, v31
	s_or_b64 s[70:71], s[68:69], s[0:1]
	s_lshl_b32 s8, s73, 7
	v_cndmask_b32_e32 v28, v170, v28, vcc
	v_lshlrev_b32_e32 v44, 2, v28
	v_add_f32_dpp v26, v26, v26 quad_perm:[1,0,3,2] row_mask:0xf bank_mask:0xf
	v_xor_b32_e32 v28, 4, v170
	v_cmp_lt_i32_e32 vcc, v28, v31
	v_add_f32_dpp v26, v26, v26 quad_perm:[2,3,0,1] row_mask:0xf bank_mask:0xf
	v_cndmask_b32_e32 v28, v170, v28, vcc
	v_lshlrev_b32_e32 v45, 2, v28
	v_xor_b32_e32 v28, 8, v170
	v_cmp_lt_i32_e32 vcc, v28, v31
	v_add_f32_dpp v26, v26, v26 row_half_mirror row_mask:0xf bank_mask:0xf
	v_cndmask_b32_e32 v28, v170, v28, vcc
	v_lshlrev_b32_e32 v46, 2, v28
	v_xor_b32_e32 v28, 16, v170
	v_cmp_lt_i32_e32 vcc, v28, v31
	v_add_f32_dpp v26, v26, v26 row_mirror row_mask:0xf bank_mask:0xf
	v_cndmask_b32_e32 v28, v170, v28, vcc
	v_lshlrev_b32_e32 v43, 2, v28
	v_mov_b32_e32 v27, v26
	s_nop 1
	v_permlane16_swap_b32_e32 v26, v27
	s_nop 0
	s_and_b64 vcc, exec, s[70:71]
	v_add_f32_e32 v26, v26, v27
	v_fmamk_f32 v26, v26, 0x3c000000, v166
	v_rsq_f32_e32 v28, v26
	v_lshl_add_u64 v[26:27], s[8:9], 2, v[116:117]
	s_waitcnt vmcnt(2)
	v_pk_mul_f32 v[30:31], v[12:13], v[28:29] op_sel_hi:[1,0]
	s_nop 0
	v_pk_mul_f32 v[40:41], v[90:91], v[30:31]
	s_waitcnt vmcnt(0)
	v_pk_mul_f32 v[28:29], v[14:15], v[28:29] op_sel_hi:[1,0]
	s_nop 0
	v_pk_mul_f32 v[30:31], v[92:93], v[28:29]
	s_cbranch_vccnz .LBB0_1192
	v_lshlrev_b32_e32 v28, 8, v118
	v_ashrrev_i32_e32 v29, 31, v28
	v_lshl_add_u64 v[28:29], v[28:29], 2, v[26:27]
	global_store_dword v[28:29], v41, off sc1
	global_store_dword v[28:29], v40, off offset:128 sc1
	global_store_dword v[28:29], v31, off offset:256 sc1
	global_store_dword v[28:29], v30, off offset:384 sc1

.LBB0_1194:
	v_pk_mul_f32 v[28:29], v[88:89], v[88:89]
	v_pk_mul_f32 v[54:55], v[86:87], v[86:87]
	v_add_f32_e32 v28, v29, v28
	v_add_f32_e32 v28, v28, v55
	v_add_f32_e32 v28, v28, v54
	s_xor_b64 s[70:71], s[70:71], -1
	s_and_b64 s[0:1], s[68:69], exec
	s_cselect_b32 s0, s83, 0xdf9f000
	s_cselect_b32 s8, s66, s72
	s_waitcnt lgkmcnt(0)
	v_add_f32_dpp v28, v28, v28 quad_perm:[1,0,3,2] row_mask:0xf bank_mask:0xf
	s_cselect_b32 s72, s84, s73
	s_add_u32 s73, s14, s0
	s_addc_u32 s84, s15, 0
	s_and_b64 s[0:1], s[68:69], exec
	v_add_f32_dpp v47, v28, v28 quad_perm:[2,3,0,1] row_mask:0xf bank_mask:0xf
	s_cselect_b32 s68, 10, 8
	s_lshl_b32 s0, s72, 7
	s_ashr_i32 s1, s0, 31
	s_lshl_b64 s[0:1], s[0:1], 1
	v_add_f32_dpp v47, v47, v47 row_half_mirror row_mask:0xf bank_mask:0xf
	s_add_u32 s0, s73, s0
	v_add_u32_e32 v55, s8, v133
	s_addc_u32 s1, s84, s1
	v_lshlrev_b32_e32 v106, 1, v108
	v_add_f32_dpp v47, v47, v47 row_mirror row_mask:0xf bank_mask:0xf
	v_mov_b32_e32 v56, v47
	s_nop 1
	v_permlane16_swap_b32_e32 v47, v56
	s_nop 0
	v_lshlrev_b32_e32 v54, s68, v55
	v_lshl_add_u64 v[28:29], s[0:1], 0, v[106:107]
	v_ashrrev_i32_e32 v55, 31, v54
	v_lshl_add_u64 v[54:55], v[54:55], 1, v[28:29]
	v_cvt_pk_bf16_f32 v40, v40, s0
	global_store_short v[54:55], v40, off offset:64 sc1
	v_add_f32_e32 v40, v47, v56
	v_fmamk_f32 v40, v40, 0x3c000000, v166
	v_rsq_f32_e32 v40, v40
	v_cvt_pk_bf16_f32 v41, v41, s0
	v_cvt_pk_bf16_f32 v31, v31, s0
	v_cvt_pk_bf16_f32 v30, v30, s0
	global_store_short v[54:55], v41, off sc1
	global_store_short v[54:55], v31, off offset:128 sc1
	global_store_short v[54:55], v30, off offset:192 sc1
	v_pk_mul_f32 v[30:31], v[12:13], v[40:41] op_sel_hi:[1,0]
	v_pk_mul_f32 v[40:41], v[14:15], v[40:41] op_sel_hi:[1,0]
	v_cndmask_b32_e64 v47, 0, 1, s[70:71]
	v_pk_mul_f32 v[30:31], v[88:89], v[30:31]
	v_cmp_ne_u32_e64 s[0:1], 1, v47
	s_andn2_b64 vcc, exec, s[70:71]
	v_pk_mul_f32 v[40:41], v[86:87], v[40:41]
	s_cbranch_vccnz .LBB0_1196
	v_add_lshl_u32 v54, s66, v141, 8
	v_ashrrev_i32_e32 v55, 31, v54
	v_lshl_add_u64 v[54:55], v[54:55], 2, v[26:27]
	global_store_dword v[54:55], v31, off sc1
	global_store_dword v[54:55], v30, off offset:128 sc1
	global_store_dword v[54:55], v41, off offset:256 sc1
	global_store_dword v[54:55], v40, off offset:384 sc1

.LBB0_1198:
	v_pk_mul_f32 v[54:55], v[80:81], v[80:81]
	v_pk_mul_f32 v[56:57], v[82:83], v[82:83]
	v_add_f32_e32 v47, v55, v54
	v_add_f32_e32 v47, v47, v57
	v_add_f32_e32 v47, v47, v56
	v_cvt_pk_bf16_f32 v56, v31, s0
	v_cvt_pk_bf16_f32 v57, v40, s0
	v_add_u32_e32 v55, s8, v141
	v_cvt_pk_bf16_f32 v41, v41, s0
	s_waitcnt lgkmcnt(0)
	v_add_f32_dpp v47, v47, v47 quad_perm:[1,0,3,2] row_mask:0xf bank_mask:0xf
	s_and_b64 vcc, exec, s[0:1]
	v_add_f32_dpp v47, v47, v47 quad_perm:[2,3,0,1] row_mask:0xf bank_mask:0xf
	s_nop 0
	v_add_f32_dpp v31, v47, v47 row_half_mirror row_mask:0xf bank_mask:0xf
	v_cvt_pk_bf16_f32 v54, v30, s0
	v_lshlrev_b32_e32 v30, s68, v55
	v_add_f32_dpp v40, v31, v31 row_mirror row_mask:0xf bank_mask:0xf
	v_mov_b32_e32 v47, v40
	s_nop 1
	v_permlane16_swap_b32_e32 v40, v47
	s_nop 0
	v_ashrrev_i32_e32 v31, 31, v30
	v_lshl_add_u64 v[30:31], v[30:31], 1, v[28:29]
	global_store_short v[30:31], v56, off sc1
	global_store_short v[30:31], v54, off offset:64 sc1
	global_store_short v[30:31], v41, off offset:128 sc1
	global_store_short v[30:31], v57, off offset:192 sc1
	v_add_f32_e32 v40, v40, v47
	v_fmamk_f32 v40, v40, 0x3c000000, v166
	v_rsq_f32_e32 v40, v40
	s_nop 0
	v_pk_mul_f32 v[30:31], v[12:13], v[40:41] op_sel_hi:[1,0]
	v_pk_mul_f32 v[54:55], v[14:15], v[40:41] op_sel_hi:[1,0]
	v_pk_mul_f32 v[40:41], v[80:81], v[30:31]
	v_pk_mul_f32 v[30:31], v[82:83], v[54:55]
	s_cbranch_vccnz .LBB0_1200
	v_add_lshl_u32 v54, s66, v142, 8
	v_ashrrev_i32_e32 v55, 31, v54
	v_lshl_add_u64 v[54:55], v[54:55], 2, v[26:27]
	global_store_dword v[54:55], v41, off sc1
	global_store_dword v[54:55], v40, off offset:128 sc1
	global_store_dword v[54:55], v31, off offset:256 sc1
	global_store_dword v[54:55], v30, off offset:384 sc1

.LBB0_1202:
	v_pk_mul_f32 v[54:55], v[76:77], v[76:77]
	v_pk_mul_f32 v[56:57], v[78:79], v[78:79]
	v_add_f32_e32 v47, v55, v54
	v_add_f32_e32 v47, v47, v57
	v_add_f32_e32 v47, v47, v56
	v_cvt_pk_bf16_f32 v56, v40, s0
	v_add_u32_e32 v55, s8, v142
	v_cvt_pk_bf16_f32 v58, v30, s0
	v_lshlrev_b32_e32 v30, s68, v55
	s_waitcnt lgkmcnt(0)
	v_add_f32_dpp v47, v47, v47 quad_perm:[1,0,3,2] row_mask:0xf bank_mask:0xf
	v_cvt_pk_bf16_f32 v57, v31, s0
	v_ashrrev_i32_e32 v31, 31, v30
	v_cvt_pk_bf16_f32 v41, v41, s0
	v_lshl_add_u64 v[30:31], v[30:31], 1, v[28:29]
	v_add_f32_dpp v47, v47, v47 quad_perm:[2,3,0,1] row_mask:0xf bank_mask:0xf
	global_store_short v[30:31], v41, off sc1
	global_store_short v[30:31], v56, off offset:64 sc1
	global_store_short v[30:31], v57, off offset:128 sc1
	global_store_short v[30:31], v58, off offset:192 sc1
	s_and_b64 vcc, exec, s[0:1]
	v_add_f32_dpp v47, v47, v47 row_half_mirror row_mask:0xf bank_mask:0xf
	s_nop 0
	v_add_f32_dpp v40, v47, v47 row_mirror row_mask:0xf bank_mask:0xf
	v_mov_b32_e32 v47, v40
	s_nop 1
	v_permlane16_swap_b32_e32 v40, v47
	s_nop 0
	v_add_f32_e32 v40, v40, v47
	v_fmamk_f32 v40, v40, 0x3c000000, v166
	v_rsq_f32_e32 v40, v40
	s_nop 0
	v_pk_mul_f32 v[30:31], v[12:13], v[40:41] op_sel_hi:[1,0]
	v_pk_mul_f32 v[54:55], v[14:15], v[40:41] op_sel_hi:[1,0]
	v_pk_mul_f32 v[40:41], v[76:77], v[30:31]
	v_pk_mul_f32 v[30:31], v[78:79], v[54:55]
	s_cbranch_vccnz .LBB0_1204
	v_add_lshl_u32 v54, s66, v143, 8
	v_ashrrev_i32_e32 v55, 31, v54
	v_lshl_add_u64 v[54:55], v[54:55], 2, v[26:27]
	global_store_dword v[54:55], v41, off sc1
	global_store_dword v[54:55], v40, off offset:128 sc1
	global_store_dword v[54:55], v31, off offset:256 sc1
	global_store_dword v[54:55], v30, off offset:384 sc1

.LBB0_1206:
	v_pk_mul_f32 v[54:55], v[72:73], v[72:73]
	v_pk_mul_f32 v[56:57], v[74:75], v[74:75]
	v_add_f32_e32 v47, v55, v54
	v_add_f32_e32 v47, v47, v57
	v_add_f32_e32 v47, v47, v56
	v_cvt_pk_bf16_f32 v56, v40, s0
	v_add_u32_e32 v55, s8, v143
	v_cvt_pk_bf16_f32 v58, v30, s0
	v_lshlrev_b32_e32 v30, s68, v55
	s_waitcnt lgkmcnt(0)
	v_add_f32_dpp v47, v47, v47 quad_perm:[1,0,3,2] row_mask:0xf bank_mask:0xf
	v_cvt_pk_bf16_f32 v57, v31, s0
	v_ashrrev_i32_e32 v31, 31, v30
	v_cvt_pk_bf16_f32 v41, v41, s0
	v_lshl_add_u64 v[30:31], v[30:31], 1, v[28:29]
	v_add_f32_dpp v47, v47, v47 quad_perm:[2,3,0,1] row_mask:0xf bank_mask:0xf
	global_store_short v[30:31], v41, off sc1
	global_store_short v[30:31], v56, off offset:64 sc1
	global_store_short v[30:31], v57, off offset:128 sc1
	global_store_short v[30:31], v58, off offset:192 sc1
	s_and_b64 vcc, exec, s[0:1]
	v_add_f32_dpp v47, v47, v47 row_half_mirror row_mask:0xf bank_mask:0xf
	s_nop 0
	v_add_f32_dpp v40, v47, v47 row_mirror row_mask:0xf bank_mask:0xf
	v_mov_b32_e32 v47, v40
	s_nop 1
	v_permlane16_swap_b32_e32 v40, v47
	s_nop 0
	v_add_f32_e32 v40, v40, v47
	v_fmamk_f32 v40, v40, 0x3c000000, v166
	v_rsq_f32_e32 v40, v40
	s_nop 0
	v_pk_mul_f32 v[30:31], v[12:13], v[40:41] op_sel_hi:[1,0]
	v_pk_mul_f32 v[54:55], v[14:15], v[40:41] op_sel_hi:[1,0]
	v_pk_mul_f32 v[40:41], v[72:73], v[30:31]
	v_pk_mul_f32 v[30:31], v[74:75], v[54:55]
	s_cbranch_vccnz .LBB0_1208
	v_add_lshl_u32 v54, s66, v144, 8
	v_ashrrev_i32_e32 v55, 31, v54
	v_lshl_add_u64 v[54:55], v[54:55], 2, v[26:27]
	global_store_dword v[54:55], v41, off sc1
	global_store_dword v[54:55], v40, off offset:128 sc1
	global_store_dword v[54:55], v31, off offset:256 sc1
	global_store_dword v[54:55], v30, off offset:384 sc1

.LBB0_1210:
	v_pk_mul_f32 v[54:55], v[68:69], v[68:69]
	v_pk_mul_f32 v[56:57], v[70:71], v[70:71]
	v_add_f32_e32 v47, v55, v54
	v_add_f32_e32 v47, v47, v57
	v_add_f32_e32 v47, v47, v56
	v_cvt_pk_bf16_f32 v56, v40, s0
	v_add_u32_e32 v55, s8, v144
	v_cvt_pk_bf16_f32 v58, v30, s0
	v_lshlrev_b32_e32 v30, s68, v55
	s_waitcnt lgkmcnt(0)
	v_add_f32_dpp v47, v47, v47 quad_perm:[1,0,3,2] row_mask:0xf bank_mask:0xf
	v_cvt_pk_bf16_f32 v57, v31, s0
	v_ashrrev_i32_e32 v31, 31, v30
	v_cvt_pk_bf16_f32 v41, v41, s0
	v_lshl_add_u64 v[30:31], v[30:31], 1, v[28:29]
	v_add_f32_dpp v47, v47, v47 quad_perm:[2,3,0,1] row_mask:0xf bank_mask:0xf
	global_store_short v[30:31], v41, off sc1
	global_store_short v[30:31], v56, off offset:64 sc1
	global_store_short v[30:31], v57, off offset:128 sc1
	global_store_short v[30:31], v58, off offset:192 sc1
	s_and_b64 vcc, exec, s[0:1]
	v_add_f32_dpp v47, v47, v47 row_half_mirror row_mask:0xf bank_mask:0xf
	s_nop 0
	v_add_f32_dpp v40, v47, v47 row_mirror row_mask:0xf bank_mask:0xf
	v_mov_b32_e32 v47, v40
	s_nop 1
	v_permlane16_swap_b32_e32 v40, v47
	s_nop 0
	v_add_f32_e32 v40, v40, v47
	v_fmamk_f32 v40, v40, 0x3c000000, v166
	v_rsq_f32_e32 v40, v40
	s_nop 0
	v_pk_mul_f32 v[30:31], v[12:13], v[40:41] op_sel_hi:[1,0]
	v_pk_mul_f32 v[54:55], v[14:15], v[40:41] op_sel_hi:[1,0]
	v_pk_mul_f32 v[40:41], v[68:69], v[30:31]
	v_pk_mul_f32 v[30:31], v[70:71], v[54:55]
	s_cbranch_vccnz .LBB0_1212
	v_add_lshl_u32 v54, s66, v145, 8
	v_ashrrev_i32_e32 v55, 31, v54
	v_lshl_add_u64 v[54:55], v[54:55], 2, v[26:27]
	global_store_dword v[54:55], v41, off sc1
	global_store_dword v[54:55], v40, off offset:128 sc1
	global_store_dword v[54:55], v31, off offset:256 sc1
	global_store_dword v[54:55], v30, off offset:384 sc1

.LBB0_1214:
	v_pk_mul_f32 v[54:55], v[64:65], v[64:65]
	v_pk_mul_f32 v[56:57], v[66:67], v[66:67]
	v_add_f32_e32 v47, v55, v54
	v_add_f32_e32 v47, v47, v57
	v_add_f32_e32 v47, v47, v56
	v_cvt_pk_bf16_f32 v56, v40, s0
	v_add_u32_e32 v55, s8, v145
	v_cvt_pk_bf16_f32 v58, v30, s0
	v_lshlrev_b32_e32 v30, s68, v55
	s_waitcnt lgkmcnt(0)
	v_add_f32_dpp v47, v47, v47 quad_perm:[1,0,3,2] row_mask:0xf bank_mask:0xf
	v_cvt_pk_bf16_f32 v57, v31, s0
	v_ashrrev_i32_e32 v31, 31, v30
	v_cvt_pk_bf16_f32 v41, v41, s0
	v_lshl_add_u64 v[30:31], v[30:31], 1, v[28:29]
	v_add_f32_dpp v47, v47, v47 quad_perm:[2,3,0,1] row_mask:0xf bank_mask:0xf
	global_store_short v[30:31], v41, off sc1
	global_store_short v[30:31], v56, off offset:64 sc1
	global_store_short v[30:31], v57, off offset:128 sc1
	global_store_short v[30:31], v58, off offset:192 sc1
	s_and_b64 vcc, exec, s[0:1]
	v_add_f32_dpp v47, v47, v47 row_half_mirror row_mask:0xf bank_mask:0xf
	s_nop 0
	v_add_f32_dpp v40, v47, v47 row_mirror row_mask:0xf bank_mask:0xf
	v_mov_b32_e32 v47, v40
	s_nop 1
	v_permlane16_swap_b32_e32 v40, v47
	s_nop 0
	v_add_f32_e32 v40, v40, v47
	v_fmamk_f32 v40, v40, 0x3c000000, v166
	v_rsq_f32_e32 v40, v40
	s_nop 0
	v_pk_mul_f32 v[30:31], v[12:13], v[40:41] op_sel_hi:[1,0]
	v_pk_mul_f32 v[54:55], v[14:15], v[40:41] op_sel_hi:[1,0]
	v_pk_mul_f32 v[40:41], v[64:65], v[30:31]
	v_pk_mul_f32 v[30:31], v[66:67], v[54:55]
	s_cbranch_vccnz .LBB0_1216
	v_add_lshl_u32 v54, s66, v146, 8
	v_ashrrev_i32_e32 v55, 31, v54
	v_lshl_add_u64 v[54:55], v[54:55], 2, v[26:27]
	global_store_dword v[54:55], v41, off sc1
	global_store_dword v[54:55], v40, off offset:128 sc1
	global_store_dword v[54:55], v31, off offset:256 sc1
	global_store_dword v[54:55], v30, off offset:384 sc1

.LBB0_1218:
	v_pk_mul_f32 v[54:55], v[50:51], v[50:51]
	v_pk_mul_f32 v[56:57], v[52:53], v[52:53]
	v_add_f32_e32 v47, v55, v54
	v_add_f32_e32 v47, v47, v57
	v_add_f32_e32 v47, v47, v56
	v_cvt_pk_bf16_f32 v56, v40, s0
	v_add_u32_e32 v55, s8, v146
	v_cvt_pk_bf16_f32 v58, v30, s0
	v_lshlrev_b32_e32 v30, s68, v55
	s_waitcnt lgkmcnt(0)
	v_add_f32_dpp v47, v47, v47 quad_perm:[1,0,3,2] row_mask:0xf bank_mask:0xf
	v_cvt_pk_bf16_f32 v57, v31, s0
	v_ashrrev_i32_e32 v31, 31, v30
	v_cvt_pk_bf16_f32 v41, v41, s0
	v_lshl_add_u64 v[30:31], v[30:31], 1, v[28:29]
	v_add_f32_dpp v47, v47, v47 quad_perm:[2,3,0,1] row_mask:0xf bank_mask:0xf
	global_store_short v[30:31], v41, off sc1
	global_store_short v[30:31], v56, off offset:64 sc1
	global_store_short v[30:31], v57, off offset:128 sc1
	global_store_short v[30:31], v58, off offset:192 sc1
	s_and_b64 vcc, exec, s[0:1]
	v_add_f32_dpp v47, v47, v47 row_half_mirror row_mask:0xf bank_mask:0xf
	s_nop 0
	v_add_f32_dpp v40, v47, v47 row_mirror row_mask:0xf bank_mask:0xf
	v_mov_b32_e32 v47, v40
	s_nop 1
	v_permlane16_swap_b32_e32 v40, v47
	s_nop 0
	v_add_f32_e32 v40, v40, v47
	v_fmamk_f32 v40, v40, 0x3c000000, v166
	v_rsq_f32_e32 v40, v40
	s_nop 0
	v_pk_mul_f32 v[30:31], v[12:13], v[40:41] op_sel_hi:[1,0]
	v_pk_mul_f32 v[54:55], v[14:15], v[40:41] op_sel_hi:[1,0]
	v_pk_mul_f32 v[40:41], v[50:51], v[30:31]
	v_pk_mul_f32 v[30:31], v[52:53], v[54:55]
	s_cbranch_vccnz .LBB0_1220
	v_add_lshl_u32 v50, s66, v147, 8
	v_ashrrev_i32_e32 v51, 31, v50
	v_lshl_add_u64 v[50:51], v[50:51], 2, v[26:27]
	global_store_dword v[50:51], v41, off sc1
	global_store_dword v[50:51], v40, off offset:128 sc1
	global_store_dword v[50:51], v31, off offset:256 sc1
	global_store_dword v[50:51], v30, off offset:384 sc1

.LBB0_1222:
	v_pk_mul_f32 v[50:51], v[38:39], v[38:39]
	v_pk_mul_f32 v[52:53], v[48:49], v[48:49]
	v_add_f32_e32 v47, v51, v50
	v_add_f32_e32 v47, v47, v53
	v_add_f32_e32 v47, v47, v52
	v_cvt_pk_bf16_f32 v52, v40, s0
	v_add_u32_e32 v51, s8, v147
	v_cvt_pk_bf16_f32 v54, v30, s0
	v_lshlrev_b32_e32 v30, s68, v51
	s_waitcnt lgkmcnt(0)
	v_add_f32_dpp v47, v47, v47 quad_perm:[1,0,3,2] row_mask:0xf bank_mask:0xf
	v_cvt_pk_bf16_f32 v53, v31, s0
	v_ashrrev_i32_e32 v31, 31, v30
	v_cvt_pk_bf16_f32 v41, v41, s0
	v_lshl_add_u64 v[30:31], v[30:31], 1, v[28:29]
	v_add_f32_dpp v47, v47, v47 quad_perm:[2,3,0,1] row_mask:0xf bank_mask:0xf
	global_store_short v[30:31], v41, off sc1
	global_store_short v[30:31], v52, off offset:64 sc1
	global_store_short v[30:31], v53, off offset:128 sc1
	global_store_short v[30:31], v54, off offset:192 sc1
	s_and_b64 vcc, exec, s[0:1]
	v_add_f32_dpp v47, v47, v47 row_half_mirror row_mask:0xf bank_mask:0xf
	s_nop 1
	v_mov_b32_dpp v50, v47 row_mirror row_mask:0xf bank_mask:0xf
	v_add_f32_e32 v40, v47, v50
	v_mov_b32_e32 v47, v40
	s_nop 1
	v_permlane16_swap_b32_e32 v40, v47
	s_nop 0
	v_add_f32_e32 v40, v40, v47
	v_fmamk_f32 v40, v40, 0x3c000000, v166
	v_rsq_f32_e32 v40, v40
	s_nop 0
	v_pk_mul_f32 v[30:31], v[12:13], v[40:41] op_sel_hi:[1,0]
	v_pk_mul_f32 v[40:41], v[14:15], v[40:41] op_sel_hi:[1,0]
	v_pk_mul_f32 v[38:39], v[38:39], v[30:31]
	v_pk_mul_f32 v[30:31], v[48:49], v[40:41]
	s_cbranch_vccnz .LBB0_1224
	v_add_lshl_u32 v40, s66, v148, 8
	v_ashrrev_i32_e32 v41, 31, v40
	v_lshl_add_u64 v[40:41], v[40:41], 2, v[26:27]
	global_store_dword v[40:41], v39, off sc1
	global_store_dword v[40:41], v38, off offset:128 sc1
	global_store_dword v[40:41], v31, off offset:256 sc1
	global_store_dword v[40:41], v30, off offset:384 sc1

.LBB0_1226:
	v_pk_mul_f32 v[40:41], v[34:35], v[34:35]
	v_pk_mul_f32 v[48:49], v[36:37], v[36:37]
	v_add_f32_e32 v40, v41, v40
	v_add_f32_e32 v40, v40, v49
	v_add_f32_e32 v40, v40, v48
	v_cvt_pk_bf16_f32 v48, v38, s0
	v_add_u32_e32 v47, s8, v148
	v_cvt_pk_bf16_f32 v50, v30, s0
	v_lshlrev_b32_e32 v30, s68, v47
	s_waitcnt lgkmcnt(0)
	v_add_f32_dpp v40, v40, v40 quad_perm:[1,0,3,2] row_mask:0xf bank_mask:0xf
	v_cvt_pk_bf16_f32 v49, v31, s0
	v_ashrrev_i32_e32 v31, 31, v30
	v_cvt_pk_bf16_f32 v39, v39, s0
	v_lshl_add_u64 v[30:31], v[30:31], 1, v[28:29]
	v_add_f32_dpp v40, v40, v40 quad_perm:[2,3,0,1] row_mask:0xf bank_mask:0xf
	global_store_short v[30:31], v39, off sc1
	global_store_short v[30:31], v48, off offset:64 sc1
	global_store_short v[30:31], v49, off offset:128 sc1
	global_store_short v[30:31], v50, off offset:192 sc1
	s_and_b64 vcc, exec, s[0:1]
	v_add_f32_dpp v40, v40, v40 row_half_mirror row_mask:0xf bank_mask:0xf
	s_nop 1
	v_mov_b32_dpp v41, v40 row_mirror row_mask:0xf bank_mask:0xf
	v_add_f32_e32 v38, v40, v41
	v_mov_b32_e32 v40, v38
	s_nop 1
	v_permlane16_swap_b32_e32 v38, v40
	s_nop 0
	v_add_f32_e32 v38, v38, v40
	v_fmamk_f32 v38, v38, 0x3c000000, v166
	v_rsq_f32_e32 v38, v38
	s_nop 0
	v_pk_mul_f32 v[30:31], v[12:13], v[38:39] op_sel_hi:[1,0]
	v_pk_mul_f32 v[38:39], v[14:15], v[38:39] op_sel_hi:[1,0]
	v_pk_mul_f32 v[34:35], v[34:35], v[30:31]
	v_pk_mul_f32 v[30:31], v[36:37], v[38:39]
	s_cbranch_vccnz .LBB0_1228
	v_add_lshl_u32 v36, s66, v149, 8
	v_ashrrev_i32_e32 v37, 31, v36
	v_lshl_add_u64 v[36:37], v[36:37], 2, v[26:27]
	global_store_dword v[36:37], v35, off sc1
	global_store_dword v[36:37], v34, off offset:128 sc1
	global_store_dword v[36:37], v31, off offset:256 sc1
	global_store_dword v[36:37], v30, off offset:384 sc1

.LBB0_1230:
	v_pk_mul_f32 v[36:37], v[24:25], v[24:25]
	v_pk_mul_f32 v[38:39], v[32:33], v[32:33]
	v_add_f32_e32 v36, v37, v36
	v_add_f32_e32 v36, v36, v39
	v_add_f32_e32 v36, v36, v38
	v_cvt_pk_bf16_f32 v39, v34, s0
	v_add_u32_e32 v38, s8, v149
	v_cvt_pk_bf16_f32 v41, v30, s0
	v_lshlrev_b32_e32 v30, s68, v38
	s_waitcnt lgkmcnt(0)
	v_add_f32_dpp v36, v36, v36 quad_perm:[1,0,3,2] row_mask:0xf bank_mask:0xf
	v_cvt_pk_bf16_f32 v40, v31, s0
	v_ashrrev_i32_e32 v31, 31, v30
	v_cvt_pk_bf16_f32 v35, v35, s0
	v_lshl_add_u64 v[30:31], v[30:31], 1, v[28:29]
	v_add_f32_dpp v36, v36, v36 quad_perm:[2,3,0,1] row_mask:0xf bank_mask:0xf
	global_store_short v[30:31], v35, off sc1
	global_store_short v[30:31], v39, off offset:64 sc1
	global_store_short v[30:31], v40, off offset:128 sc1
	global_store_short v[30:31], v41, off offset:192 sc1
	s_and_b64 vcc, exec, s[0:1]
	v_add_f32_dpp v36, v36, v36 row_half_mirror row_mask:0xf bank_mask:0xf
	s_nop 1
	v_mov_b32_dpp v37, v36 row_mirror row_mask:0xf bank_mask:0xf
	v_add_f32_e32 v34, v36, v37
	v_mov_b32_e32 v36, v34
	s_nop 1
	v_permlane16_swap_b32_e32 v34, v36
	s_nop 0
	v_add_f32_e32 v34, v34, v36
	v_fmamk_f32 v34, v34, 0x3c000000, v166
	v_rsq_f32_e32 v34, v34
	s_nop 0
	v_pk_mul_f32 v[30:31], v[12:13], v[34:35] op_sel_hi:[1,0]
	v_pk_mul_f32 v[34:35], v[14:15], v[34:35] op_sel_hi:[1,0]
	v_pk_mul_f32 v[30:31], v[24:25], v[30:31]
	v_pk_mul_f32 v[24:25], v[32:33], v[34:35]
	s_cbranch_vccnz .LBB0_1232
	v_add_lshl_u32 v32, s66, v150, 8
	v_ashrrev_i32_e32 v33, 31, v32
	v_lshl_add_u64 v[32:33], v[32:33], 2, v[26:27]
	global_store_dword v[32:33], v31, off sc1
	global_store_dword v[32:33], v30, off offset:128 sc1
	global_store_dword v[32:33], v25, off offset:256 sc1
	global_store_dword v[32:33], v24, off offset:384 sc1

.LBB0_1234:
	v_pk_mul_f32 v[32:33], v[20:21], v[20:21]
	v_pk_mul_f32 v[34:35], v[22:23], v[22:23]
	v_add_f32_e32 v32, v33, v32
	v_add_f32_e32 v32, v32, v35
	v_add_f32_e32 v32, v32, v34
	v_cvt_pk_bf16_f32 v35, v30, s0
	v_add_u32_e32 v34, s8, v150
	v_cvt_pk_bf16_f32 v37, v24, s0
	v_lshlrev_b32_e32 v24, s68, v34
	s_waitcnt lgkmcnt(0)
	v_add_f32_dpp v32, v32, v32 quad_perm:[1,0,3,2] row_mask:0xf bank_mask:0xf
	v_cvt_pk_bf16_f32 v36, v25, s0
	v_ashrrev_i32_e32 v25, 31, v24
	v_cvt_pk_bf16_f32 v31, v31, s0
	v_lshl_add_u64 v[24:25], v[24:25], 1, v[28:29]
	v_add_f32_dpp v32, v32, v32 quad_perm:[2,3,0,1] row_mask:0xf bank_mask:0xf
	global_store_short v[24:25], v31, off sc1
	global_store_short v[24:25], v35, off offset:64 sc1
	global_store_short v[24:25], v36, off offset:128 sc1
	global_store_short v[24:25], v37, off offset:192 sc1
	s_and_b64 vcc, exec, s[0:1]
	v_add_f32_dpp v32, v32, v32 row_half_mirror row_mask:0xf bank_mask:0xf
	s_nop 1
	v_mov_b32_dpp v33, v32 row_mirror row_mask:0xf bank_mask:0xf
	v_add_f32_e32 v30, v32, v33
	v_mov_b32_e32 v32, v30
	s_nop 1
	v_permlane16_swap_b32_e32 v30, v32
	s_nop 0
	v_add_f32_e32 v30, v30, v32
	v_fmamk_f32 v30, v30, 0x3c000000, v166
	v_rsq_f32_e32 v30, v30
	s_nop 0
	v_pk_mul_f32 v[24:25], v[12:13], v[30:31] op_sel_hi:[1,0]
	v_pk_mul_f32 v[30:31], v[14:15], v[30:31] op_sel_hi:[1,0]
	v_pk_mul_f32 v[24:25], v[20:21], v[24:25]
	v_pk_mul_f32 v[20:21], v[22:23], v[30:31]
	s_cbranch_vccnz .LBB0_1236
	v_add_lshl_u32 v22, s66, v151, 8
	v_ashrrev_i32_e32 v23, 31, v22
	v_lshl_add_u64 v[22:23], v[22:23], 2, v[26:27]
	global_store_dword v[22:23], v25, off sc1
	global_store_dword v[22:23], v24, off offset:128 sc1
	global_store_dword v[22:23], v21, off offset:256 sc1
	global_store_dword v[22:23], v20, off offset:384 sc1

.LBB0_1238:
	v_pk_mul_f32 v[22:23], v[16:17], v[16:17]
	v_pk_mul_f32 v[30:31], v[18:19], v[18:19]
	v_add_f32_e32 v22, v23, v22
	v_add_f32_e32 v22, v22, v31
	v_add_f32_e32 v22, v22, v30
	v_add_u32_e32 v30, s8, v151
	v_cvt_pk_bf16_f32 v32, v20, s0
	v_lshlrev_b32_e32 v20, s68, v30
	v_cvt_pk_bf16_f32 v31, v21, s0
	s_waitcnt lgkmcnt(0)
	v_add_f32_dpp v22, v22, v22 quad_perm:[1,0,3,2] row_mask:0xf bank_mask:0xf
	v_ashrrev_i32_e32 v21, 31, v20
	v_cvt_pk_bf16_f32 v25, v25, s0
	v_cvt_pk_bf16_f32 v24, v24, s0
	v_lshl_add_u64 v[20:21], v[20:21], 1, v[28:29]
	v_add_f32_dpp v22, v22, v22 quad_perm:[2,3,0,1] row_mask:0xf bank_mask:0xf
	global_store_short v[20:21], v25, off sc1
	global_store_short v[20:21], v24, off offset:64 sc1
	global_store_short v[20:21], v31, off offset:128 sc1
	global_store_short v[20:21], v32, off offset:192 sc1
	s_and_b64 vcc, exec, s[0:1]
	v_add_f32_dpp v22, v22, v22 row_half_mirror row_mask:0xf bank_mask:0xf
	s_nop 0
	v_add_f32_dpp v22, v22, v22 row_mirror row_mask:0xf bank_mask:0xf
	v_mov_b32_e32 v23, v22
	s_nop 1
	v_permlane16_swap_b32_e32 v22, v23
	s_nop 0
	v_add_f32_e32 v22, v22, v23
	v_fmamk_f32 v22, v22, 0x3c000000, v166
	v_rsq_f32_e32 v22, v22
	s_nop 0
	v_pk_mul_f32 v[20:21], v[12:13], v[22:23] op_sel_hi:[1,0]
	v_pk_mul_f32 v[22:23], v[14:15], v[22:23] op_sel_hi:[1,0]
	v_pk_mul_f32 v[20:21], v[16:17], v[20:21]
	v_pk_mul_f32 v[16:17], v[18:19], v[22:23]
	s_cbranch_vccnz .LBB0_1240
	v_add_lshl_u32 v18, s66, v152, 8
	v_ashrrev_i32_e32 v19, 31, v18
	v_lshl_add_u64 v[18:19], v[18:19], 2, v[26:27]
	global_store_dword v[18:19], v21, off sc1
	global_store_dword v[18:19], v20, off offset:128 sc1
	global_store_dword v[18:19], v17, off offset:256 sc1
	global_store_dword v[18:19], v16, off offset:384 sc1

.LBB0_1242:
	v_pk_mul_f32 v[18:19], v[8:9], v[8:9]
	v_pk_mul_f32 v[22:23], v[10:11], v[10:11]
	v_add_f32_e32 v18, v19, v18
	v_add_f32_e32 v18, v18, v23
	v_add_f32_e32 v18, v18, v22
	v_add_u32_e32 v22, s8, v152
	v_cvt_pk_bf16_f32 v24, v16, s0
	v_lshlrev_b32_e32 v16, s68, v22
	v_cvt_pk_bf16_f32 v23, v17, s0
	s_waitcnt lgkmcnt(0)
	v_add_f32_dpp v18, v18, v18 quad_perm:[1,0,3,2] row_mask:0xf bank_mask:0xf
	v_ashrrev_i32_e32 v17, 31, v16
	v_cvt_pk_bf16_f32 v21, v21, s0
	v_cvt_pk_bf16_f32 v20, v20, s0
	v_lshl_add_u64 v[16:17], v[16:17], 1, v[28:29]
	v_add_f32_dpp v18, v18, v18 quad_perm:[2,3,0,1] row_mask:0xf bank_mask:0xf
	global_store_short v[16:17], v21, off sc1
	global_store_short v[16:17], v20, off offset:64 sc1
	global_store_short v[16:17], v23, off offset:128 sc1
	global_store_short v[16:17], v24, off offset:192 sc1
	s_and_b64 vcc, exec, s[0:1]
	v_add_f32_dpp v18, v18, v18 row_half_mirror row_mask:0xf bank_mask:0xf
	s_nop 0
	v_add_f32_dpp v18, v18, v18 row_mirror row_mask:0xf bank_mask:0xf
	v_mov_b32_e32 v19, v18
	s_nop 1
	v_permlane16_swap_b32_e32 v18, v19
	s_nop 0
	v_add_f32_e32 v18, v18, v19
	v_fmamk_f32 v18, v18, 0x3c000000, v166
	v_rsq_f32_e32 v18, v18
	s_nop 0
	v_pk_mul_f32 v[16:17], v[12:13], v[18:19] op_sel_hi:[1,0]
	v_pk_mul_f32 v[18:19], v[14:15], v[18:19] op_sel_hi:[1,0]
	v_pk_mul_f32 v[16:17], v[8:9], v[16:17]
	v_pk_mul_f32 v[8:9], v[10:11], v[18:19]
	s_cbranch_vccnz .LBB0_1244
	v_add_lshl_u32 v10, s66, v153, 8
	v_ashrrev_i32_e32 v11, 31, v10
	v_lshl_add_u64 v[10:11], v[10:11], 2, v[26:27]
	global_store_dword v[10:11], v17, off sc1
	global_store_dword v[10:11], v16, off offset:128 sc1
	global_store_dword v[10:11], v9, off offset:256 sc1
	global_store_dword v[10:11], v8, off offset:384 sc1

.LBB0_1246:
	v_pk_mul_f32 v[10:11], v[4:5], v[4:5]
	v_pk_mul_f32 v[18:19], v[6:7], v[6:7]
	v_add_f32_e32 v10, v11, v10
	v_add_f32_e32 v10, v10, v19
	v_add_f32_e32 v10, v10, v18
	v_add_u32_e32 v18, s8, v153
	v_cvt_pk_bf16_f32 v20, v8, s0
	v_lshlrev_b32_e32 v8, s68, v18
	v_cvt_pk_bf16_f32 v19, v9, s0
	s_waitcnt lgkmcnt(0)
	v_add_f32_dpp v10, v10, v10 quad_perm:[1,0,3,2] row_mask:0xf bank_mask:0xf
	v_ashrrev_i32_e32 v9, 31, v8
	v_cvt_pk_bf16_f32 v17, v17, s0
	v_cvt_pk_bf16_f32 v16, v16, s0
	v_lshl_add_u64 v[8:9], v[8:9], 1, v[28:29]
	v_add_f32_dpp v10, v10, v10 quad_perm:[2,3,0,1] row_mask:0xf bank_mask:0xf
	global_store_short v[8:9], v17, off sc1
	global_store_short v[8:9], v16, off offset:64 sc1
	global_store_short v[8:9], v19, off offset:128 sc1
	global_store_short v[8:9], v20, off offset:192 sc1
	s_and_b64 vcc, exec, s[0:1]
	v_add_f32_dpp v10, v10, v10 row_half_mirror row_mask:0xf bank_mask:0xf
	s_nop 0
	v_add_f32_dpp v10, v10, v10 row_mirror row_mask:0xf bank_mask:0xf
	v_mov_b32_e32 v11, v10
	s_nop 1
	v_permlane16_swap_b32_e32 v10, v11
	s_nop 0
	v_add_f32_e32 v10, v10, v11
	v_fmamk_f32 v10, v10, 0x3c000000, v166
	v_rsq_f32_e32 v10, v10
	s_nop 0
	v_pk_mul_f32 v[8:9], v[12:13], v[10:11] op_sel_hi:[1,0]
	v_pk_mul_f32 v[10:11], v[14:15], v[10:11] op_sel_hi:[1,0]
	v_pk_mul_f32 v[8:9], v[4:5], v[8:9]
	v_pk_mul_f32 v[4:5], v[6:7], v[10:11]
	s_cbranch_vccnz .LBB0_1248
	v_add_lshl_u32 v6, s66, v154, 8
	v_ashrrev_i32_e32 v7, 31, v6
	v_lshl_add_u64 v[6:7], v[6:7], 2, v[26:27]
	global_store_dword v[6:7], v9, off sc1
	global_store_dword v[6:7], v8, off offset:128 sc1
	global_store_dword v[6:7], v5, off offset:256 sc1
	global_store_dword v[6:7], v4, off offset:384 sc1

.LBB0_1250:
	v_pk_mul_f32 v[6:7], v[0:1], v[0:1]
	v_pk_mul_f32 v[10:11], v[2:3], v[2:3]
	v_add_f32_e32 v6, v7, v6
	v_add_f32_e32 v6, v11, v6
	v_add_f32_e32 v6, v10, v6
	v_add_u32_e32 v10, s8, v154
	v_cvt_pk_bf16_f32 v16, v4, s0
	v_lshlrev_b32_e32 v4, s68, v10
	v_cvt_pk_bf16_f32 v11, v5, s0
	s_waitcnt lgkmcnt(0)
	v_add_f32_dpp v6, v6, v6 quad_perm:[1,0,3,2] row_mask:0xf bank_mask:0xf
	v_ashrrev_i32_e32 v5, 31, v4
	v_cvt_pk_bf16_f32 v9, v9, s0
	v_cvt_pk_bf16_f32 v8, v8, s0
	v_lshl_add_u64 v[4:5], v[4:5], 1, v[28:29]
	v_add_f32_dpp v6, v6, v6 quad_perm:[2,3,0,1] row_mask:0xf bank_mask:0xf
	global_store_short v[4:5], v9, off sc1
	global_store_short v[4:5], v8, off offset:64 sc1
	global_store_short v[4:5], v11, off offset:128 sc1
	global_store_short v[4:5], v16, off offset:192 sc1
	s_and_b64 vcc, exec, s[0:1]
	v_add_f32_dpp v6, v6, v6 row_half_mirror row_mask:0xf bank_mask:0xf
	s_nop 0
	v_add_f32_dpp v6, v6, v6 row_mirror row_mask:0xf bank_mask:0xf
	v_mov_b32_e32 v7, v6
	s_nop 1
	v_permlane16_swap_b32_e32 v6, v7
	s_nop 0
	v_add_f32_e32 v6, v6, v7
	v_fmamk_f32 v6, v6, 0x3c000000, v166
	v_rsq_f32_e32 v6, v6
	s_nop 0
	v_pk_mul_f32 v[4:5], v[12:13], v[6:7] op_sel_hi:[1,0]
	v_pk_mul_f32 v[6:7], v[14:15], v[6:7] op_sel_hi:[1,0]
	v_pk_mul_f32 v[4:5], v[0:1], v[4:5]
	v_pk_mul_f32 v[0:1], v[2:3], v[6:7]
	s_cbranch_vccnz .LBB0_1252
	v_add_lshl_u32 v2, s66, v155, 8
	v_ashrrev_i32_e32 v3, 31, v2
	v_lshl_add_u64 v[2:3], v[2:3], 2, v[26:27]
	global_store_dword v[2:3], v5, off sc1
	global_store_dword v[2:3], v4, off offset:128 sc1
	global_store_dword v[2:3], v1, off offset:256 sc1
	global_store_dword v[2:3], v0, off offset:384 sc1

.LBB0_1326:
	s_add_i32 s58, s66, 0xffffe000
	s_lshr_b32 s58, s58, 12
	s_mulk_i32 s58, 0x1800
	v_mov_b32_e32 v70, s70
	s_add_i32 s58, s58, 0xa800
	ds_read_b64 v[70:71], v70
	s_cmp_gt_i32 s6, 63
	s_cselect_b32 s6, s58, 0x9000
	s_lshl_b64 s[58:59], s[6:7], 2
	s_add_u32 s6, s14, s58
	s_addc_u32 s65, s15, s59
	s_waitcnt lgkmcnt(0)
	v_readfirstlane_b32 s58, v70
	v_readfirstlane_b32 s59, v71
	s_add_u32 s60, s58, 0x2000
	s_addc_u32 s61, s59, 0
	s_lshl_b32 s58, s64, 14
	s_add_i32 s58, s58, 0xa0000
	s_ashr_i32 s59, s58, 31
	s_lshl_b64 s[58:59], s[58:59], 2
	s_add_u32 s58, s10, s58
	s_addc_u32 s59, s11, s59
	s_add_u32 s62, s6, 0x5ba2000
	v_or_b32_e32 v102, s68, v138
	v_add_u32_e32 v70, s66, v139
	s_addc_u32 s63, s65, 0
	v_lshlrev_b32_e32 v188, 10, v70
	v_ashrrev_i32_e32 v103, 31, v102
	s_add_u32 s64, s6, 0x5ba4000
	v_lshlrev_b64 v[72:73], 2, v[102:103]
	v_or_b32_e32 v186, 0x400, v188
	v_or_b32_e32 v185, 0x4400, v188
	v_or_b32_e32 v189, 0x4c00, v188
	v_or_b32_e32 v193, 0x6c00, v188
	s_addc_u32 s65, s65, 0
	v_lshl_add_u64 v[74:75], s[62:63], 0, v[72:73]
	v_add_u32_e32 v132, v188, v102
	v_add_u32_e32 v134, v186, v102
	v_or_b32_e32 v184, 0x800, v188
	v_or_b32_e32 v183, 0xc00, v188
	v_or_b32_e32 v181, 0x2000, v188
	v_or_b32_e32 v179, 0x2400, v188
	v_or_b32_e32 v71, 0x2800, v188
	v_or_b32_e32 v180, 0x2c00, v188
	v_or_b32_e32 v182, 0x4000, v188
	v_add_u32_e32 v112, v185, v102
	v_or_b32_e32 v187, 0x4800, v188
	v_add_u32_e32 v118, v189, v102
	v_or_b32_e32 v190, 0x6000, v188
	v_or_b32_e32 v191, 0x6400, v188
	v_or_b32_e32 v192, 0x6800, v188
	v_add_u32_e32 v128, v193, v102
	global_load_dword v194, v[74:75], off
	v_lshl_add_u64 v[74:75], s[60:61], 0, v[72:73]
	v_lshl_add_u64 v[72:73], s[64:65], 0, v[72:73]
	v_ashrrev_i32_e32 v135, 31, v134
	v_add_u32_e32 v136, v184, v102
	v_add_u32_e32 v130, v183, v102
	v_add_u32_e32 v122, v181, v102
	v_add_u32_e32 v114, v179, v102
	v_add_u32_e32 v106, v71, v102
	v_add_u32_e32 v108, v180, v102
	v_add_u32_e32 v110, v182, v102
	v_ashrrev_i32_e32 v113, 31, v112
	v_add_u32_e32 v116, v187, v102
	v_ashrrev_i32_e32 v119, 31, v118
	v_add_u32_e32 v120, v190, v102
	v_add_u32_e32 v124, v191, v102
	v_add_u32_e32 v126, v192, v102
	v_ashrrev_i32_e32 v129, 31, v128
	v_ashrrev_i32_e32 v133, 31, v132
	global_load_dword v196, v[72:73], off
	v_lshl_add_u64 v[88:89], v[134:135], 2, s[12:13]
	v_ashrrev_i32_e32 v137, 31, v136
	v_ashrrev_i32_e32 v131, 31, v130
	v_ashrrev_i32_e32 v123, 31, v122
	v_ashrrev_i32_e32 v115, 31, v114
	v_ashrrev_i32_e32 v107, 31, v106
	v_ashrrev_i32_e32 v109, 31, v108
	v_ashrrev_i32_e32 v111, 31, v110
	v_lshl_add_u64 v[86:87], v[112:113], 2, s[12:13]
	v_ashrrev_i32_e32 v117, 31, v116
	v_lshl_add_u64 v[92:93], v[118:119], 2, s[12:13]
	v_ashrrev_i32_e32 v121, 31, v120
	v_ashrrev_i32_e32 v125, 31, v124
	v_ashrrev_i32_e32 v127, 31, v126
	v_lshl_add_u64 v[100:101], v[128:129], 2, s[12:13]
	v_lshl_add_u64 v[104:105], v[132:133], 2, s[12:13]
	global_load_dword v195, v[74:75], off
	v_lshl_add_u64 v[84:85], v[136:137], 2, s[12:13]
	v_lshl_add_u64 v[82:83], v[130:131], 2, s[12:13]
	v_lshl_add_u64 v[78:79], v[122:123], 2, s[12:13]
	v_lshl_add_u64 v[72:73], v[114:115], 2, s[12:13]
	v_lshl_add_u64 v[74:75], v[106:107], 2, s[12:13]
	v_lshl_add_u64 v[76:77], v[108:109], 2, s[12:13]
	v_lshl_add_u64 v[80:81], v[110:111], 2, s[12:13]
	global_load_dword v178, v[88:89], off
	global_load_dword v177, v[84:85], off
	global_load_dword v176, v[82:83], off
	global_load_dword v175, v[78:79], off
	global_load_dword v174, v[72:73], off
	global_load_dword v173, v[74:75], off
	global_load_dword v172, v[76:77], off
	global_load_dword v171, v[80:81], off
	v_lshl_add_u64 v[90:91], v[116:117], 2, s[12:13]
	global_load_dword v170, v[86:87], off
	global_load_dword v168, v[90:91], off
	v_lshl_add_u64 v[94:95], v[120:121], 2, s[12:13]
	v_lshl_add_u64 v[96:97], v[124:125], 2, s[12:13]
	v_lshl_add_u64 v[98:99], v[126:127], 2, s[12:13]
	global_load_dword v169, v[92:93], off
	global_load_dword v167, v[94:95], off
	global_load_dword v166, v[96:97], off
	global_load_dword v165, v[98:99], off
	global_load_dword v103, v[100:101], off
	global_load_dword v197, v[104:105], off
	v_lshl_add_u64 v[106:107], v[106:107], 1, s[8:9]
	s_waitcnt vmcnt(0)
	v_add_f32_e32 v196, 1.0, v196
	v_mul_f32_e32 v195, v195, v196
	v_fmac_f32_e32 v178, v49, v194
	v_fmac_f32_e32 v177, v50, v194
	v_fmac_f32_e32 v176, v51, v194
	v_fmac_f32_e32 v175, v52, v194
	v_fmac_f32_e32 v174, v53, v194
	v_fmac_f32_e32 v173, v54, v194
	v_fmac_f32_e32 v172, v55, v194
	v_fmac_f32_e32 v171, v56, v194
	v_fmac_f32_e32 v170, v57, v194
	v_fmac_f32_e32 v168, v58, v194
	v_fmac_f32_e32 v169, v59, v194
	v_fmac_f32_e32 v167, v60, v194
	v_fmac_f32_e32 v166, v61, v194
	v_fmac_f32_e32 v165, v62, v194
	v_fmac_f32_e32 v103, v63, v194
	v_fmac_f32_e32 v197, v48, v194
	v_mul_f32_e32 v48, v195, v197
	v_cvt_pk_bf16_f32 v58, v48, s0
	v_or_b32_e32 v48, 32, v102
	v_ashrrev_i32_e32 v49, 31, v48
	v_lshlrev_b64 v[52:53], 2, v[48:49]
	global_store_dword v[88:89], v178, off sc1
	global_store_dword v[84:85], v177, off sc1
	global_store_dword v[82:83], v176, off sc1
	global_store_dword v[78:79], v175, off sc1
	global_store_dword v[72:73], v174, off sc1
	global_store_dword v[74:75], v173, off sc1
	global_store_dword v[76:77], v172, off sc1
	global_store_dword v[80:81], v171, off sc1
	global_store_dword v[86:87], v170, off sc1
	global_store_dword v[90:91], v168, off sc1
	global_store_dword v[92:93], v169, off sc1
	global_store_dword v[94:95], v167, off sc1
	global_store_dword v[96:97], v166, off sc1
	global_store_dword v[98:99], v165, off sc1
	global_store_dword v[100:101], v103, off sc1
	global_store_dword v[104:105], v197, off sc1
	v_lshl_add_u64 v[50:51], v[132:133], 1, s[8:9]
	v_lshl_add_u64 v[56:57], s[64:65], 0, v[52:53]
	global_load_dword v196, v[104:105], off offset:128
	v_lshl_add_u64 v[54:55], s[60:61], 0, v[52:53]
	global_load_dword v132, v[56:57], off
	global_load_dword v133, v[54:55], off
	v_mul_f32_e32 v49, v195, v178
	global_store_short v[50:51], v58, off sc1
	v_lshl_add_u64 v[50:51], s[62:63], 0, v[52:53]
	global_load_dword v194, v[50:51], off
	v_cvt_pk_bf16_f32 v49, v49, s0
	v_lshl_add_u64 v[50:51], v[134:135], 1, s[8:9]
	global_store_short v[50:51], v49, off sc1
	v_mul_f32_e32 v49, v195, v177
	v_cvt_pk_bf16_f32 v49, v49, s0
	v_lshl_add_u64 v[50:51], v[136:137], 1, s[8:9]
	global_store_short v[50:51], v49, off sc1
	v_mul_f32_e32 v49, v195, v176
	v_cvt_pk_bf16_f32 v49, v49, s0
	v_lshl_add_u64 v[50:51], v[130:131], 1, s[8:9]
	global_store_short v[50:51], v49, off sc1
	v_mul_f32_e32 v49, v195, v175
	v_cvt_pk_bf16_f32 v49, v49, s0
	v_lshl_add_u64 v[50:51], v[122:123], 1, s[8:9]
	global_store_short v[50:51], v49, off sc1
	v_mul_f32_e32 v49, v195, v174
	v_cvt_pk_bf16_f32 v49, v49, s0
	v_lshl_add_u64 v[50:51], v[114:115], 1, s[8:9]
	global_store_short v[50:51], v49, off sc1
	v_mul_f32_e32 v49, v195, v173
	global_load_dword v62, v[84:85], off offset:128
	global_load_dword v60, v[78:79], off offset:128
	global_load_dword v59, v[72:73], off offset:128
	global_load_dword v58, v[74:75], off offset:128
	global_load_dword v56, v[80:81], off offset:128
	global_load_dword v57, v[76:77], off offset:128
	global_load_dword v55, v[86:87], off offset:128
	global_load_dword v61, v[82:83], off offset:128
	global_load_dword v54, v[90:91], off offset:128
	global_load_dword v53, v[92:93], off offset:128
	global_load_dword v52, v[94:95], off offset:128
	global_load_dword v51, v[96:97], off offset:128
	global_load_dword v50, v[98:99], off offset:128
	v_cvt_pk_bf16_f32 v63, v49, s0
	global_load_dword v49, v[100:101], off offset:128
	s_waitcnt vmcnt(19)
	v_fmac_f32_e32 v196, v32, v194
	global_store_short v[106:107], v63, off sc1
	global_load_dword v63, v[88:89], off offset:128
	v_mul_f32_e32 v106, v195, v172
	v_cvt_pk_bf16_f32 v114, v106, s0
	v_lshl_add_u64 v[106:107], v[108:109], 1, s[8:9]
	global_store_short v[106:107], v114, off sc1
	v_mul_f32_e32 v106, v195, v171
	v_cvt_pk_bf16_f32 v108, v106, s0
	v_lshl_add_u64 v[106:107], v[110:111], 1, s[8:9]
	global_store_short v[106:107], v108, off sc1
	v_mul_f32_e32 v106, v195, v170
	v_cvt_pk_bf16_f32 v108, v106, s0
	v_lshl_add_u64 v[106:107], v[112:113], 1, s[8:9]
	global_store_short v[106:107], v108, off sc1
	v_mul_f32_e32 v106, v195, v168
	v_cvt_pk_bf16_f32 v108, v106, s0
	v_lshl_add_u64 v[106:107], v[116:117], 1, s[8:9]
	global_store_short v[106:107], v108, off sc1
	v_mul_f32_e32 v106, v195, v169
	v_cvt_pk_bf16_f32 v108, v106, s0
	v_lshl_add_u64 v[106:107], v[118:119], 1, s[8:9]
	global_store_short v[106:107], v108, off sc1
	v_mul_f32_e32 v106, v195, v167
	v_cvt_pk_bf16_f32 v108, v106, s0
	v_lshl_add_u64 v[106:107], v[120:121], 1, s[8:9]
	global_store_short v[106:107], v108, off sc1
	v_mul_f32_e32 v106, v195, v166
	v_cvt_pk_bf16_f32 v108, v106, s0
	v_lshl_add_u64 v[106:107], v[124:125], 1, s[8:9]
	global_store_short v[106:107], v108, off sc1
	v_mul_f32_e32 v106, v195, v165
	v_cvt_pk_bf16_f32 v108, v106, s0
	v_lshl_add_u64 v[106:107], v[126:127], 1, s[8:9]
	global_store_short v[106:107], v108, off sc1
	v_mul_f32_e32 v106, v195, v103
	v_cvt_pk_bf16_f32 v108, v106, s0
	v_lshl_add_u64 v[106:107], v[128:129], 1, s[8:9]
	global_store_short v[106:107], v108, off sc1
	v_add_f32_e32 v106, 1.0, v132
	v_mul_f32_e32 v110, v133, v106
	v_add_u32_e32 v106, v188, v48
	s_waitcnt vmcnt(24)
	v_fmac_f32_e32 v62, v34, v194
	s_waitcnt vmcnt(17)
	v_fmac_f32_e32 v61, v35, v194
	v_fmac_f32_e32 v60, v36, v194
	v_fmac_f32_e32 v59, v37, v194
	v_fmac_f32_e32 v58, v38, v194
	v_fmac_f32_e32 v57, v39, v194
	v_fmac_f32_e32 v56, v40, v194
	v_fmac_f32_e32 v55, v41, v194
	s_waitcnt vmcnt(16)
	v_fmac_f32_e32 v54, v42, v194
	s_waitcnt vmcnt(15)
	v_fmac_f32_e32 v53, v43, v194
	s_waitcnt vmcnt(14)
	v_fmac_f32_e32 v52, v44, v194
	s_waitcnt vmcnt(13)
	v_fmac_f32_e32 v51, v45, v194
	s_waitcnt vmcnt(12)
	v_fmac_f32_e32 v50, v46, v194
	s_waitcnt vmcnt(11)
	v_fmac_f32_e32 v49, v47, v194
	v_ashrrev_i32_e32 v107, 31, v106
	global_store_dword v[104:105], v196, off offset:128 sc1
	v_mul_f32_e32 v32, v110, v196
	global_store_dword v[84:85], v62, off offset:128 sc1
	global_store_dword v[82:83], v61, off offset:128 sc1
	global_store_dword v[78:79], v60, off offset:128 sc1
	global_store_dword v[72:73], v59, off offset:128 sc1
	global_store_dword v[74:75], v58, off offset:128 sc1
	global_store_dword v[76:77], v57, off offset:128 sc1
	global_store_dword v[80:81], v56, off offset:128 sc1
	global_store_dword v[86:87], v55, off offset:128 sc1
	global_store_dword v[90:91], v54, off offset:128 sc1
	global_store_dword v[92:93], v53, off offset:128 sc1
	global_store_dword v[94:95], v52, off offset:128 sc1
	global_store_dword v[96:97], v51, off offset:128 sc1
	global_store_dword v[98:99], v50, off offset:128 sc1
	global_store_dword v[100:101], v49, off offset:128 sc1
	v_cvt_pk_bf16_f32 v32, v32, s0
	v_lshl_add_u64 v[106:107], v[106:107], 1, s[8:9]
	v_add_u32_e32 v108, v186, v48
	global_load_dword v45, v[88:89], off offset:256
	v_ashrrev_i32_e32 v109, 31, v108
	global_store_short v[106:107], v32, off sc1
	v_mul_f32_e32 v113, v110, v56
	v_cvt_pk_bf16_f32 v113, v113, s0
	v_mul_f32_e32 v106, v196, v196
	s_waitcnt vmcnt(26)
	v_fmac_f32_e32 v63, v33, v194
	v_mul_f32_e32 v32, v110, v63
	v_cvt_pk_bf16_f32 v34, v32, s0
	v_lshl_add_u64 v[32:33], v[108:109], 1, s[8:9]
	global_store_short v[32:33], v34, off sc1
	v_add_u32_e32 v32, v184, v48
	v_ashrrev_i32_e32 v33, 31, v32
	v_mul_f32_e32 v34, v110, v62
	v_cvt_pk_bf16_f32 v34, v34, s0
	v_lshl_add_u64 v[32:33], v[32:33], 1, s[8:9]
	global_store_short v[32:33], v34, off sc1
	v_add_u32_e32 v32, v183, v48
	v_ashrrev_i32_e32 v33, 31, v32
	v_mul_f32_e32 v34, v110, v61
	v_cvt_pk_bf16_f32 v34, v34, s0
	v_lshl_add_u64 v[32:33], v[32:33], 1, s[8:9]
	global_store_short v[32:33], v34, off sc1
	v_add_u32_e32 v32, v181, v48
	v_ashrrev_i32_e32 v33, 31, v32
	v_mul_f32_e32 v34, v110, v60
	v_cvt_pk_bf16_f32 v34, v34, s0
	v_lshl_add_u64 v[32:33], v[32:33], 1, s[8:9]
	global_store_short v[32:33], v34, off sc1
	v_add_u32_e32 v32, v179, v48
	v_ashrrev_i32_e32 v33, 31, v32
	v_mul_f32_e32 v34, v110, v59
	v_cvt_pk_bf16_f32 v42, v34, s0
	v_lshl_add_u64 v[34:35], v[32:33], 1, s[8:9]
	v_or_b32_e32 v32, 64, v102
	v_ashrrev_i32_e32 v33, 31, v32
	v_lshlrev_b64 v[36:37], 2, v[32:33]
	global_store_dword v[88:89], v63, off offset:128 sc1
	v_lshl_add_u64 v[40:41], s[64:65], 0, v[36:37]
	v_lshl_add_u64 v[38:39], s[60:61], 0, v[36:37]
	global_load_dword v107, v[40:41], off
	global_load_dword v111, v[38:39], off
	v_mul_f32_e32 v33, v110, v58
	global_store_short v[34:35], v42, off sc1
	v_lshl_add_u64 v[34:35], s[62:63], 0, v[36:37]
	global_load_dword v112, v[34:35], off
	v_add_u32_e32 v34, v71, v48
	v_ashrrev_i32_e32 v35, 31, v34
	v_cvt_pk_bf16_f32 v33, v33, s0
	v_lshl_add_u64 v[34:35], v[34:35], 1, s[8:9]
	global_store_short v[34:35], v33, off sc1
	v_add_u32_e32 v34, v180, v48
	v_ashrrev_i32_e32 v35, 31, v34
	v_mul_f32_e32 v33, v110, v57
	v_cvt_pk_bf16_f32 v33, v33, s0
	v_lshl_add_u64 v[34:35], v[34:35], 1, s[8:9]
	global_load_dword v38, v[90:91], off offset:256
	global_load_dword v37, v[92:93], off offset:256
	global_load_dword v36, v[94:95], off offset:256
	global_load_dword v114, v[104:105], off offset:256
	global_load_dword v47, v[84:85], off offset:256
	global_load_dword v39, v[86:87], off offset:256
	global_load_dword v46, v[82:83], off offset:256
	global_load_dword v44, v[78:79], off offset:256
	global_load_dword v43, v[72:73], off offset:256
	global_load_dword v42, v[74:75], off offset:256
	global_load_dword v40, v[80:81], off offset:256
	global_load_dword v41, v[76:77], off offset:256
	v_add_u32_e32 v108, v182, v48
	global_store_short v[34:35], v33, off sc1
	global_load_dword v35, v[96:97], off offset:256
	v_ashrrev_i32_e32 v109, 31, v108
	global_load_dword v34, v[98:99], off offset:256
	global_load_dword v33, v[100:101], off offset:256
	v_lshl_add_u64 v[108:109], v[108:109], 1, s[8:9]
	global_store_short v[108:109], v113, off sc1
	v_add_u32_e32 v108, v185, v48
	v_ashrrev_i32_e32 v109, 31, v108
	v_mul_f32_e32 v113, v110, v55
	v_cvt_pk_bf16_f32 v113, v113, s0
	v_lshl_add_u64 v[108:109], v[108:109], 1, s[8:9]
	global_store_short v[108:109], v113, off sc1
	v_add_u32_e32 v108, v187, v48
	v_ashrrev_i32_e32 v109, 31, v108
	v_mul_f32_e32 v113, v110, v54
	v_cvt_pk_bf16_f32 v113, v113, s0
	v_lshl_add_u64 v[108:109], v[108:109], 1, s[8:9]
	global_store_short v[108:109], v113, off sc1
	v_add_u32_e32 v108, v189, v48
	v_ashrrev_i32_e32 v109, 31, v108
	v_mul_f32_e32 v113, v110, v53
	v_cvt_pk_bf16_f32 v113, v113, s0
	v_lshl_add_u64 v[108:109], v[108:109], 1, s[8:9]
	global_store_short v[108:109], v113, off sc1
	v_add_u32_e32 v108, v190, v48
	v_ashrrev_i32_e32 v109, 31, v108
	v_mul_f32_e32 v113, v110, v52
	v_cvt_pk_bf16_f32 v113, v113, s0
	v_lshl_add_u64 v[108:109], v[108:109], 1, s[8:9]
	global_store_short v[108:109], v113, off sc1
	v_add_u32_e32 v108, v191, v48
	v_ashrrev_i32_e32 v109, 31, v108
	v_mul_f32_e32 v113, v110, v51
	v_cvt_pk_bf16_f32 v113, v113, s0
	v_lshl_add_u64 v[108:109], v[108:109], 1, s[8:9]
	global_store_short v[108:109], v113, off sc1
	v_add_u32_e32 v108, v192, v48
	v_ashrrev_i32_e32 v109, 31, v108
	v_mul_f32_e32 v113, v110, v50
	v_cvt_pk_bf16_f32 v113, v113, s0
	v_lshl_add_u64 v[108:109], v[108:109], 1, s[8:9]
	global_store_short v[108:109], v113, off sc1
	v_add_u32_e32 v108, v193, v48
	v_ashrrev_i32_e32 v109, 31, v108
	v_mul_f32_e32 v48, v110, v49
	v_cvt_pk_bf16_f32 v48, v48, s0
	v_lshl_add_u64 v[108:109], v[108:109], 1, s[8:9]
	global_store_short v[108:109], v48, off sc1
	v_add_u32_e32 v108, v188, v32
	v_ashrrev_i32_e32 v109, 31, v108
	s_waitcnt vmcnt(28)
	v_add_f32_e32 v48, 1.0, v107
	s_waitcnt vmcnt(27)
	v_mul_f32_e32 v48, v111, v48
	v_fmac_f32_e32 v106, v197, v197
	s_waitcnt vmcnt(25)
	v_fmac_f32_e32 v45, v17, v112
	global_store_dword v[88:89], v45, off offset:256 sc1
	s_waitcnt vmcnt(24)
	v_fmac_f32_e32 v38, v26, v112
	s_waitcnt vmcnt(23)
	v_fmac_f32_e32 v37, v27, v112
	s_waitcnt vmcnt(22)
	v_fmac_f32_e32 v36, v28, v112
	s_waitcnt vmcnt(21)
	v_fmac_f32_e32 v114, v16, v112
	v_mul_f32_e32 v16, v48, v114
	s_waitcnt vmcnt(20)
	v_fmac_f32_e32 v47, v18, v112
	v_cvt_pk_bf16_f32 v18, v16, s0
	v_lshl_add_u64 v[16:17], v[108:109], 1, s[8:9]
	global_store_short v[16:17], v18, off sc1
	v_add_u32_e32 v16, v186, v32
	v_ashrrev_i32_e32 v17, 31, v16
	v_mul_f32_e32 v18, v48, v45
	v_cvt_pk_bf16_f32 v18, v18, s0
	v_lshl_add_u64 v[16:17], v[16:17], 1, s[8:9]
	global_store_short v[16:17], v18, off sc1
	v_add_u32_e32 v16, v184, v32
	v_ashrrev_i32_e32 v17, 31, v16
	v_mul_f32_e32 v18, v48, v47
	v_cvt_pk_bf16_f32 v18, v18, s0
	v_lshl_add_u64 v[16:17], v[16:17], 1, s[8:9]
	s_waitcnt vmcnt(20)
	v_fmac_f32_e32 v46, v19, v112
	global_store_short v[16:17], v18, off sc1
	v_add_u32_e32 v16, v183, v32
	v_ashrrev_i32_e32 v17, 31, v16
	v_mul_f32_e32 v18, v48, v46
	s_waitcnt vmcnt(20)
	v_fmac_f32_e32 v44, v20, v112
	v_cvt_pk_bf16_f32 v18, v18, s0
	v_lshl_add_u64 v[16:17], v[16:17], 1, s[8:9]
	global_store_short v[16:17], v18, off sc1
	v_mul_f32_e32 v16, v48, v44
	v_cvt_pk_bf16_f32 v26, v16, s0
	v_or_b32_e32 v16, 0x60, v102
	v_add_u32_e32 v18, v181, v32
	v_ashrrev_i32_e32 v17, 31, v16
	s_waitcnt vmcnt(20)
	v_fmac_f32_e32 v43, v21, v112
	s_waitcnt vmcnt(19)
	v_fmac_f32_e32 v42, v22, v112
	s_waitcnt vmcnt(17)
	v_fmac_f32_e32 v41, v23, v112
	v_fmac_f32_e32 v40, v24, v112
	v_fmac_f32_e32 v39, v25, v112
	s_waitcnt vmcnt(15)
	v_fmac_f32_e32 v35, v29, v112
	s_waitcnt vmcnt(14)
	v_fmac_f32_e32 v34, v30, v112
	s_waitcnt vmcnt(13)
	v_fmac_f32_e32 v33, v31, v112
	v_ashrrev_i32_e32 v19, 31, v18
	v_lshlrev_b64 v[20:21], 2, v[16:17]
	global_store_dword v[84:85], v47, off offset:256 sc1
	global_store_dword v[82:83], v46, off offset:256 sc1
	global_store_dword v[78:79], v44, off offset:256 sc1
	global_store_dword v[72:73], v43, off offset:256 sc1
	global_store_dword v[74:75], v42, off offset:256 sc1
	global_store_dword v[76:77], v41, off offset:256 sc1
	global_store_dword v[80:81], v40, off offset:256 sc1
	global_store_dword v[86:87], v39, off offset:256 sc1
	global_store_dword v[90:91], v38, off offset:256 sc1
	global_store_dword v[92:93], v37, off offset:256 sc1
	global_store_dword v[94:95], v36, off offset:256 sc1
	global_store_dword v[96:97], v35, off offset:256 sc1
	global_store_dword v[98:99], v34, off offset:256 sc1
	global_store_dword v[100:101], v33, off offset:256 sc1
	global_store_dword v[104:105], v114, off offset:256 sc1
	v_lshl_add_u64 v[24:25], s[64:65], 0, v[20:21]
	v_lshl_add_u64 v[18:19], v[18:19], 1, s[8:9]
	global_load_dword v29, v[104:105], off offset:384
	v_lshl_add_u64 v[22:23], s[60:61], 0, v[20:21]
	global_load_dword v17, v[24:25], off
	global_load_dword v30, v[22:23], off
	global_load_dword v28, v[88:89], off offset:384
	global_load_dword v27, v[84:85], off offset:384
	v_fmac_f32_e32 v106, v114, v114
	global_store_short v[18:19], v26, off sc1
	v_lshl_add_u64 v[18:19], s[62:63], 0, v[20:21]
	global_load_dword v102, v[18:19], off
	v_add_u32_e32 v18, v179, v32
	v_ashrrev_i32_e32 v19, 31, v18
	v_mul_f32_e32 v20, v48, v43
	v_cvt_pk_bf16_f32 v20, v20, s0
	v_lshl_add_u64 v[18:19], v[18:19], 1, s[8:9]
	global_store_short v[18:19], v20, off sc1
	v_add_u32_e32 v18, v71, v32
	v_ashrrev_i32_e32 v19, 31, v18
	v_mul_f32_e32 v20, v48, v42
	v_cvt_pk_bf16_f32 v20, v20, s0
	v_lshl_add_u64 v[18:19], v[18:19], 1, s[8:9]
	global_store_short v[18:19], v20, off sc1
	v_add_u32_e32 v18, v180, v32
	v_ashrrev_i32_e32 v19, 31, v18
	v_mul_f32_e32 v20, v48, v41
	v_cvt_pk_bf16_f32 v20, v20, s0
	v_lshl_add_u64 v[18:19], v[18:19], 1, s[8:9]
	global_store_short v[18:19], v20, off sc1
	v_add_u32_e32 v18, v182, v32
	v_ashrrev_i32_e32 v19, 31, v18
	v_mul_f32_e32 v20, v48, v40
	v_cvt_pk_bf16_f32 v20, v20, s0
	v_lshl_add_u64 v[18:19], v[18:19], 1, s[8:9]
	global_store_short v[18:19], v20, off sc1
	v_add_u32_e32 v18, v185, v32
	v_ashrrev_i32_e32 v19, 31, v18
	v_mul_f32_e32 v20, v48, v39
	v_cvt_pk_bf16_f32 v20, v20, s0
	v_lshl_add_u64 v[18:19], v[18:19], 1, s[8:9]
	global_store_short v[18:19], v20, off sc1
	v_add_u32_e32 v18, v187, v32
	v_ashrrev_i32_e32 v19, 31, v18
	v_mul_f32_e32 v20, v48, v38
	v_cvt_pk_bf16_f32 v20, v20, s0
	v_lshl_add_u64 v[18:19], v[18:19], 1, s[8:9]
	global_store_short v[18:19], v20, off sc1
	v_add_u32_e32 v18, v189, v32
	v_ashrrev_i32_e32 v19, 31, v18
	v_mul_f32_e32 v20, v48, v37
	v_cvt_pk_bf16_f32 v20, v20, s0
	v_lshl_add_u64 v[18:19], v[18:19], 1, s[8:9]
	global_store_short v[18:19], v20, off sc1
	v_add_u32_e32 v18, v190, v32
	v_ashrrev_i32_e32 v19, 31, v18
	v_mul_f32_e32 v20, v48, v36
	v_cvt_pk_bf16_f32 v20, v20, s0
	v_lshl_add_u64 v[18:19], v[18:19], 1, s[8:9]
	global_store_short v[18:19], v20, off sc1
	v_add_u32_e32 v18, v191, v32
	v_ashrrev_i32_e32 v19, 31, v18
	v_mul_f32_e32 v20, v48, v35
	v_cvt_pk_bf16_f32 v20, v20, s0
	v_lshl_add_u64 v[18:19], v[18:19], 1, s[8:9]
	global_store_short v[18:19], v20, off sc1
	v_add_u32_e32 v18, v192, v32
	v_ashrrev_i32_e32 v19, 31, v18
	v_mul_f32_e32 v20, v48, v34
	v_cvt_pk_bf16_f32 v20, v20, s0
	v_lshl_add_u64 v[18:19], v[18:19], 1, s[8:9]
	global_store_short v[18:19], v20, off sc1
	v_add_u32_e32 v18, v193, v32
	v_ashrrev_i32_e32 v19, 31, v18
	v_mul_f32_e32 v20, v48, v33
	v_cvt_pk_bf16_f32 v20, v20, s0
	v_lshl_add_u64 v[18:19], v[18:19], 1, s[8:9]
	global_store_short v[18:19], v20, off sc1
	global_load_dword v20, v[86:87], off offset:384
	v_add_u32_e32 v18, v188, v16
	global_load_dword v26, v[82:83], off offset:384
	global_load_dword v25, v[78:79], off offset:384
	global_load_dword v24, v[72:73], off offset:384
	global_load_dword v23, v[74:75], off offset:384
	global_load_dword v21, v[80:81], off offset:384
	global_load_dword v22, v[76:77], off offset:384
	s_waitcnt vmcnt(23)
	v_add_f32_e32 v17, 1.0, v17
	s_waitcnt vmcnt(22)
	v_mul_f32_e32 v32, v30, v17
	v_ashrrev_i32_e32 v19, 31, v18
	v_lshl_add_u64 v[18:19], v[18:19], 1, s[8:9]
	v_add_u32_e32 v30, v186, v16
	s_waitcnt vmcnt(18)
	v_fmac_f32_e32 v29, v0, v102
	v_mul_f32_e32 v0, v32, v29
	v_cvt_pk_bf16_f32 v0, v0, s0
	global_store_short v[18:19], v0, off sc1
	global_load_dword v19, v[90:91], off offset:384
	v_ashrrev_i32_e32 v31, 31, v30
	global_load_dword v18, v[92:93], off offset:384
	v_fmac_f32_e32 v28, v1, v102
	v_mul_f32_e32 v0, v32, v28
	v_cvt_pk_bf16_f32 v17, v0, s0
	v_lshl_add_u64 v[0:1], v[30:31], 1, s[8:9]
	global_store_short v[0:1], v17, off sc1
	v_add_u32_e32 v0, v184, v16
	v_fmac_f32_e32 v27, v2, v102
	global_load_dword v17, v[94:95], off offset:384
	v_ashrrev_i32_e32 v1, 31, v0
	v_mul_f32_e32 v2, v32, v27
	v_cvt_pk_bf16_f32 v2, v2, s0
	v_lshl_add_u64 v[0:1], v[0:1], 1, s[8:9]
	global_store_short v[0:1], v2, off sc1
	v_add_u32_e32 v0, v183, v16
	global_load_dword v2, v[96:97], off offset:384
	v_ashrrev_i32_e32 v1, 31, v0
	v_lshl_add_u64 v[0:1], v[0:1], 1, s[8:9]
	v_add_u32_e32 v30, v181, v16
	v_ashrrev_i32_e32 v31, 31, v30
	v_lshl_add_u64 v[30:31], v[30:31], 1, s[8:9]
	v_fmac_f32_e32 v106, v29, v29
	global_store_dword v[104:105], v29, off offset:384 sc1
	global_store_dword v[88:89], v28, off offset:384 sc1
	global_store_dword v[84:85], v27, off offset:384 sc1
	s_waitcnt vmcnt(16)
	v_fmac_f32_e32 v20, v9, v102
	global_store_dword v[86:87], v20, off offset:384 sc1
	s_waitcnt vmcnt(16)
	v_fmac_f32_e32 v26, v3, v102
	v_mul_f32_e32 v3, v32, v26
	v_cvt_pk_bf16_f32 v3, v3, s0
	global_store_short v[0:1], v3, off sc1
	global_load_dword v1, v[98:99], off offset:384
	s_waitcnt vmcnt(17)
	v_fmac_f32_e32 v25, v4, v102
	v_mul_f32_e32 v0, v32, v25
	v_cvt_pk_bf16_f32 v0, v0, s0
	global_store_short v[30:31], v0, off sc1
	global_load_dword v0, v[100:101], off offset:384
	v_add_u32_e32 v30, v179, v16
	s_waitcnt vmcnt(18)
	v_fmac_f32_e32 v24, v5, v102
	v_ashrrev_i32_e32 v31, 31, v30
	v_mul_f32_e32 v3, v32, v24
	v_cvt_pk_bf16_f32 v3, v3, s0
	v_lshl_add_u64 v[4:5], v[30:31], 1, s[8:9]
	global_store_short v[4:5], v3, off sc1
	v_add_u32_e32 v4, v71, v16
	s_waitcnt vmcnt(18)
	v_fmac_f32_e32 v23, v6, v102
	v_ashrrev_i32_e32 v5, 31, v4
	v_mul_f32_e32 v3, v32, v23
	v_cvt_pk_bf16_f32 v3, v3, s0
	v_lshl_add_u64 v[4:5], v[4:5], 1, s[8:9]
	global_store_short v[4:5], v3, off sc1
	v_add_u32_e32 v4, v180, v16
	s_waitcnt vmcnt(17)
	v_fmac_f32_e32 v22, v7, v102
	v_ashrrev_i32_e32 v5, 31, v4
	v_mul_f32_e32 v3, v32, v22
	v_cvt_pk_bf16_f32 v3, v3, s0
	v_lshl_add_u64 v[4:5], v[4:5], 1, s[8:9]
	global_store_short v[4:5], v3, off sc1
	v_add_u32_e32 v4, v182, v16
	v_fmac_f32_e32 v21, v8, v102
	v_ashrrev_i32_e32 v5, 31, v4
	v_mul_f32_e32 v3, v32, v21
	v_cvt_pk_bf16_f32 v3, v3, s0
	v_lshl_add_u64 v[4:5], v[4:5], 1, s[8:9]
	global_store_short v[4:5], v3, off sc1
	v_add_u32_e32 v4, v185, v16
	v_ashrrev_i32_e32 v5, 31, v4
	v_mul_f32_e32 v3, v32, v20
	v_cvt_pk_bf16_f32 v3, v3, s0
	v_lshl_add_u64 v[4:5], v[4:5], 1, s[8:9]
	global_store_short v[4:5], v3, off sc1
	v_add_u32_e32 v4, v187, v16
	s_waitcnt vmcnt(18)
	v_fmac_f32_e32 v19, v10, v102
	v_ashrrev_i32_e32 v5, 31, v4
	v_mul_f32_e32 v3, v32, v19
	v_cvt_pk_bf16_f32 v3, v3, s0
	v_lshl_add_u64 v[4:5], v[4:5], 1, s[8:9]
	global_store_short v[4:5], v3, off sc1
	v_add_u32_e32 v4, v189, v16
	s_waitcnt vmcnt(18)
	v_fmac_f32_e32 v18, v11, v102
	v_ashrrev_i32_e32 v5, 31, v4
	v_mul_f32_e32 v3, v32, v18
	v_cvt_pk_bf16_f32 v3, v3, s0
	v_lshl_add_u64 v[4:5], v[4:5], 1, s[8:9]
	global_store_short v[4:5], v3, off sc1
	v_add_u32_e32 v4, v190, v16
	s_waitcnt vmcnt(17)
	v_fmac_f32_e32 v17, v12, v102
	v_ashrrev_i32_e32 v5, 31, v4
	v_mul_f32_e32 v3, v32, v17
	v_cvt_pk_bf16_f32 v3, v3, s0
	v_lshl_add_u64 v[4:5], v[4:5], 1, s[8:9]
	global_store_short v[4:5], v3, off sc1
	v_add_u32_e32 v4, v191, v16
	s_waitcnt vmcnt(16)
	v_fmac_f32_e32 v2, v13, v102
	v_ashrrev_i32_e32 v5, 31, v4
	v_mul_f32_e32 v3, v32, v2
	v_cvt_pk_bf16_f32 v3, v3, s0
	v_lshl_add_u64 v[4:5], v[4:5], 1, s[8:9]
	global_store_short v[4:5], v3, off sc1
	v_add_u32_e32 v4, v192, v16
	v_ashrrev_i32_e32 v5, 31, v4
	v_lshl_add_u64 v[4:5], v[4:5], 1, s[8:9]
	v_xor_b32_e32 v13, 16, v164
	v_add_u32_e32 v10, v193, v16
	v_ashrrev_i32_e32 v11, 31, v10
	v_lshl_add_u64 v[10:11], v[10:11], 1, s[8:9]
	v_ashrrev_i32_e32 v71, 31, v70
	global_store_dword v[82:83], v26, off offset:384 sc1
	global_store_dword v[78:79], v25, off offset:384 sc1
	global_store_dword v[72:73], v24, off offset:384 sc1
	global_store_dword v[74:75], v23, off offset:384 sc1
	s_waitcnt vmcnt(15)
	v_fmac_f32_e32 v1, v14, v102
	v_mul_f32_e32 v3, v32, v1
	v_cvt_pk_bf16_f32 v3, v3, s0
	global_store_short v[4:5], v3, off sc1
	v_and_b32_e32 v4, 64, v164
	v_xor_b32_e32 v3, 1, v164
	v_add_u32_e32 v7, 64, v4
	v_cmp_lt_i32_e32 vcc, v3, v7
	v_xor_b32_e32 v4, 2, v164
	s_waitcnt vmcnt(14)
	v_fmac_f32_e32 v0, v15, v102
	v_cndmask_b32_e32 v3, v164, v3, vcc
	v_lshlrev_b32_e32 v3, 2, v3
	v_cmp_lt_i32_e32 vcc, v4, v7
	v_mul_f32_e32 v12, v32, v0
	v_cvt_pk_bf16_f32 v12, v12, s0
	v_cndmask_b32_e32 v4, v164, v4, vcc
	v_lshlrev_b32_e32 v4, 2, v4
	v_add_f32_dpp v6, v106, v106 quad_perm:[1,0,3,2] row_mask:0xf bank_mask:0xf
	v_xor_b32_e32 v5, 4, v164
	v_cmp_lt_i32_e32 vcc, v5, v7
	global_store_dword v[76:77], v22, off offset:384 sc1
	global_store_dword v[80:81], v21, off offset:384 sc1
	v_cndmask_b32_e32 v5, v164, v5, vcc
	v_lshlrev_b32_e32 v5, 2, v5
	v_add_f32_dpp v8, v6, v6 quad_perm:[2,3,0,1] row_mask:0xf bank_mask:0xf
	v_xor_b32_e32 v6, 8, v164
	v_cmp_lt_i32_e32 vcc, v6, v7
	global_store_dword v[90:91], v19, off offset:384 sc1
	global_store_dword v[92:93], v18, off offset:384 sc1
	v_cndmask_b32_e32 v6, v164, v6, vcc
	v_lshlrev_b32_e32 v6, 2, v6
	v_add_f32_dpp v8, v8, v8 row_half_mirror row_mask:0xf bank_mask:0xf
	v_cmp_lt_i32_e32 vcc, v13, v7
	global_store_dword v[94:95], v17, off offset:384 sc1
	global_store_dword v[96:97], v2, off offset:384 sc1
	v_cndmask_b32_e32 v7, v164, v13, vcc
	v_lshlrev_b32_e32 v7, 2, v7
	v_add_f32_dpp v8, v8, v8 row_mirror row_mask:0xf bank_mask:0xf
	ds_bpermute_b32 v9, v7, v8
	global_store_dword v[98:99], v1, off offset:384 sc1
	global_store_dword v[100:101], v0, off offset:384 sc1
	global_store_short v[10:11], v12, off sc1
	s_and_saveexec_b64 s[60:61], s[0:1]
	s_cbranch_execz .LBB0_1328
	s_waitcnt lgkmcnt(0)
	v_add_f32_e32 v10, v8, v9
	v_lshl_add_u64 v[8:9], v[70:71], 2, s[58:59]
	global_store_dword v[8:9], v10, off sc1

.LBB0_1398:
	s_add_i32 s58, s67, 0xffffe000
	s_lshr_b32 s58, s58, 12
	s_mulk_i32 s58, 0x1800
	s_addk_i32 s58, 0x1800
	s_cmp_gt_i32 s6, 63
	s_cselect_b32 s62, s58, 0
	s_add_i32 s6, s62, 0x9000
	s_lshl_b64 s[58:59], s[6:7], 2
	s_add_u32 s6, s14, s58
	s_addc_u32 s58, s15, s59
	s_add_u32 s60, s6, 0x5ba5000
	s_addc_u32 s61, s58, 0
	s_add_i32 s6, s62, 0xd800
	s_lshl_b64 s[58:59], s[6:7], 2
	v_mov_b32_e32 v70, s66
	s_add_u32 s6, s14, s58
	ds_read_b64 v[70:71], v70
	s_addc_u32 s69, s15, s59
	s_lshl_b32 s58, s64, 14
	s_add_i32 s58, s58, 0xc0000
	s_ashr_i32 s59, s58, 31
	s_lshl_b64 s[58:59], s[58:59], 2
	s_add_u32 s58, s10, s58
	s_waitcnt lgkmcnt(0)
	v_readfirstlane_b32 s63, v70
	s_addc_u32 s59, s11, s59
	v_or_b32_e32 v102, s68, v138
	v_add_u32_e32 v70, s67, v139
	v_readfirstlane_b32 s65, v71
	s_add_u32 s62, s63, 0x3000
	v_ashrrev_i32_e32 v103, 31, v102
	v_lshlrev_b32_e32 v191, 10, v70
	s_addc_u32 s63, s65, 0
	v_lshlrev_b64 v[72:73], 2, v[102:103]
	v_or_b32_e32 v187, 0x400, v191
	v_or_b32_e32 v186, 0x4400, v191
	v_or_b32_e32 v189, 0x4c00, v191
	v_or_b32_e32 v194, 0x6c00, v191
	s_add_u32 s64, s6, 0x5ba1000
	v_lshl_add_u64 v[74:75], s[60:61], 0, v[72:73]
	v_add_u32_e32 v130, v191, v102
	v_add_u32_e32 v132, v187, v102
	v_or_b32_e32 v185, 0x800, v191
	v_or_b32_e32 v184, 0xc00, v191
	v_or_b32_e32 v182, 0x2000, v191
	v_or_b32_e32 v180, 0x2400, v191
	v_or_b32_e32 v71, 0x2800, v191
	v_or_b32_e32 v181, 0x2c00, v191
	v_or_b32_e32 v183, 0x4000, v191
	v_add_u32_e32 v112, v186, v102
	v_or_b32_e32 v188, 0x4800, v191
	v_add_u32_e32 v116, v189, v102
	v_or_b32_e32 v190, 0x6000, v191
	v_or_b32_e32 v192, 0x6400, v191
	v_or_b32_e32 v193, 0x6800, v191
	v_add_u32_e32 v128, v194, v102
	s_addc_u32 s65, s69, 0
	global_load_dword v195, v[74:75], off
	v_lshl_add_u64 v[74:75], s[62:63], 0, v[72:73]
	v_ashrrev_i32_e32 v133, 31, v132
	v_add_u32_e32 v134, v185, v102
	v_add_u32_e32 v136, v184, v102
	v_add_u32_e32 v126, v182, v102
	v_add_u32_e32 v118, v180, v102
	v_add_u32_e32 v110, v71, v102
	v_add_u32_e32 v106, v181, v102
	v_add_u32_e32 v108, v183, v102
	v_ashrrev_i32_e32 v113, 31, v112
	v_add_u32_e32 v114, v188, v102
	v_ashrrev_i32_e32 v117, 31, v116
	v_add_u32_e32 v120, v190, v102
	v_add_u32_e32 v122, v192, v102
	v_add_u32_e32 v124, v193, v102
	v_ashrrev_i32_e32 v129, 31, v128
	v_ashrrev_i32_e32 v131, 31, v130
	v_lshl_add_u64 v[72:73], s[64:65], 0, v[72:73]
	global_load_dword v196, v[74:75], off
	global_load_dword v197, v[72:73], off
	v_lshl_add_u64 v[88:89], v[132:133], 2, s[12:13]
	v_ashrrev_i32_e32 v135, 31, v134
	v_ashrrev_i32_e32 v137, 31, v136
	v_ashrrev_i32_e32 v127, 31, v126
	v_ashrrev_i32_e32 v119, 31, v118
	v_ashrrev_i32_e32 v111, 31, v110
	v_ashrrev_i32_e32 v107, 31, v106
	v_ashrrev_i32_e32 v109, 31, v108
	v_lshl_add_u64 v[86:87], v[112:113], 2, s[12:13]
	v_ashrrev_i32_e32 v115, 31, v114
	v_lshl_add_u64 v[92:93], v[116:117], 2, s[12:13]
	v_ashrrev_i32_e32 v121, 31, v120
	v_ashrrev_i32_e32 v123, 31, v122
	v_ashrrev_i32_e32 v125, 31, v124
	v_lshl_add_u64 v[100:101], v[128:129], 2, s[12:13]
	v_lshl_add_u64 v[104:105], v[130:131], 2, s[12:13]
	v_lshl_add_u64 v[84:85], v[134:135], 2, s[12:13]
	v_lshl_add_u64 v[82:83], v[136:137], 2, s[12:13]
	v_lshl_add_u64 v[78:79], v[126:127], 2, s[12:13]
	v_lshl_add_u64 v[72:73], v[118:119], 2, s[12:13]
	v_lshl_add_u64 v[74:75], v[110:111], 2, s[12:13]
	v_lshl_add_u64 v[76:77], v[106:107], 2, s[12:13]
	v_lshl_add_u64 v[80:81], v[108:109], 2, s[12:13]
	global_load_dword v179, v[88:89], off
	global_load_dword v178, v[84:85], off
	global_load_dword v177, v[82:83], off
	global_load_dword v176, v[78:79], off
	global_load_dword v175, v[72:73], off
	global_load_dword v174, v[74:75], off
	global_load_dword v173, v[76:77], off
	global_load_dword v172, v[80:81], off
	v_lshl_add_u64 v[90:91], v[114:115], 2, s[12:13]
	global_load_dword v171, v[86:87], off
	global_load_dword v169, v[90:91], off
	v_lshl_add_u64 v[94:95], v[120:121], 2, s[12:13]
	v_lshl_add_u64 v[96:97], v[122:123], 2, s[12:13]
	v_lshl_add_u64 v[98:99], v[124:125], 2, s[12:13]
	global_load_dword v170, v[92:93], off
	global_load_dword v168, v[94:95], off
	global_load_dword v167, v[96:97], off
	global_load_dword v166, v[98:99], off
	global_load_dword v103, v[100:101], off
	global_load_dword v198, v[104:105], off
	v_lshl_add_u64 v[110:111], v[110:111], 1, s[8:9]
	v_lshl_add_u64 v[106:107], v[106:107], 1, s[8:9]
	s_waitcnt vmcnt(0)
	v_add_f32_e32 v197, 1.0, v197
	v_mul_f32_e32 v196, v196, v197
	v_fmac_f32_e32 v179, v49, v195
	v_fmac_f32_e32 v178, v50, v195
	v_fmac_f32_e32 v177, v51, v195
	v_fmac_f32_e32 v176, v52, v195
	v_fmac_f32_e32 v175, v53, v195
	v_fmac_f32_e32 v174, v54, v195
	v_fmac_f32_e32 v173, v55, v195
	v_fmac_f32_e32 v172, v56, v195
	v_fmac_f32_e32 v171, v57, v195
	v_fmac_f32_e32 v169, v58, v195
	v_fmac_f32_e32 v170, v59, v195
	v_fmac_f32_e32 v168, v60, v195
	v_fmac_f32_e32 v167, v61, v195
	v_fmac_f32_e32 v166, v62, v195
	v_fmac_f32_e32 v103, v63, v195
	v_fmac_f32_e32 v198, v48, v195
	v_mul_f32_e32 v48, v196, v198
	v_cvt_pk_bf16_f32 v58, v48, s0
	v_or_b32_e32 v48, 32, v102
	v_ashrrev_i32_e32 v49, 31, v48
	v_lshlrev_b64 v[52:53], 2, v[48:49]
	global_store_dword v[88:89], v179, off sc1
	global_store_dword v[84:85], v178, off sc1
	global_store_dword v[82:83], v177, off sc1
	global_store_dword v[78:79], v176, off sc1
	global_store_dword v[72:73], v175, off sc1
	global_store_dword v[74:75], v174, off sc1
	global_store_dword v[76:77], v173, off sc1
	global_store_dword v[80:81], v172, off sc1
	global_store_dword v[86:87], v171, off sc1
	global_store_dword v[90:91], v169, off sc1
	global_store_dword v[92:93], v170, off sc1
	global_store_dword v[94:95], v168, off sc1
	global_store_dword v[96:97], v167, off sc1
	global_store_dword v[98:99], v166, off sc1
	global_store_dword v[100:101], v103, off sc1
	global_store_dword v[104:105], v198, off sc1
	v_lshl_add_u64 v[50:51], v[130:131], 1, s[8:9]
	v_lshl_add_u64 v[56:57], s[64:65], 0, v[52:53]
	global_load_dword v197, v[104:105], off offset:128
	v_lshl_add_u64 v[54:55], s[62:63], 0, v[52:53]
	global_load_dword v130, v[56:57], off
	global_load_dword v131, v[54:55], off
	v_mul_f32_e32 v49, v196, v179
	global_store_short v[50:51], v58, off sc1
	v_lshl_add_u64 v[50:51], s[60:61], 0, v[52:53]
	global_load_dword v195, v[50:51], off
	v_lshl_add_u64 v[50:51], v[132:133], 1, s[8:9]
	v_cvt_pk_bf16_f32 v49, v49, s0
	global_store_short v[50:51], v49, off sc1
	v_mul_f32_e32 v49, v196, v178
	v_lshl_add_u64 v[50:51], v[134:135], 1, s[8:9]
	v_cvt_pk_bf16_f32 v49, v49, s0
	global_store_short v[50:51], v49, off sc1
	v_mul_f32_e32 v49, v196, v177
	v_lshl_add_u64 v[50:51], v[136:137], 1, s[8:9]
	v_cvt_pk_bf16_f32 v49, v49, s0
	global_store_short v[50:51], v49, off sc1
	v_mul_f32_e32 v49, v196, v176
	v_lshl_add_u64 v[50:51], v[126:127], 1, s[8:9]
	v_cvt_pk_bf16_f32 v49, v49, s0
	global_store_short v[50:51], v49, off sc1
	v_mul_f32_e32 v49, v196, v175
	v_lshl_add_u64 v[50:51], v[118:119], 1, s[8:9]
	v_cvt_pk_bf16_f32 v49, v49, s0
	global_load_dword v62, v[84:85], off offset:128
	global_load_dword v60, v[78:79], off offset:128
	global_load_dword v59, v[72:73], off offset:128
	global_load_dword v58, v[74:75], off offset:128
	global_load_dword v56, v[80:81], off offset:128
	global_load_dword v57, v[76:77], off offset:128
	global_load_dword v55, v[86:87], off offset:128
	global_load_dword v61, v[82:83], off offset:128
	global_load_dword v54, v[90:91], off offset:128
	global_load_dword v53, v[92:93], off offset:128
	global_load_dword v52, v[94:95], off offset:128
	v_mul_f32_e32 v63, v196, v174
	global_store_short v[50:51], v49, off sc1
	global_load_dword v51, v[96:97], off offset:128
	v_cvt_pk_bf16_f32 v63, v63, s0
	global_load_dword v50, v[98:99], off offset:128
	global_load_dword v49, v[100:101], off offset:128
	s_waitcnt vmcnt(19)
	v_fmac_f32_e32 v197, v32, v195
	global_store_short v[110:111], v63, off sc1
	global_load_dword v63, v[88:89], off offset:128
	v_mul_f32_e32 v110, v196, v173
	v_cvt_pk_bf16_f32 v110, v110, s0
	global_store_short v[106:107], v110, off sc1
	v_lshl_add_u64 v[106:107], v[108:109], 1, s[8:9]
	v_mul_f32_e32 v108, v196, v172
	v_cvt_pk_bf16_f32 v108, v108, s0
	global_store_short v[106:107], v108, off sc1
	v_mul_f32_e32 v108, v196, v171
	v_lshl_add_u64 v[106:107], v[112:113], 1, s[8:9]
	v_cvt_pk_bf16_f32 v108, v108, s0
	global_store_short v[106:107], v108, off sc1
	v_mul_f32_e32 v108, v196, v169
	v_lshl_add_u64 v[106:107], v[114:115], 1, s[8:9]
	v_cvt_pk_bf16_f32 v108, v108, s0
	global_store_short v[106:107], v108, off sc1
	v_mul_f32_e32 v108, v196, v170
	v_lshl_add_u64 v[106:107], v[116:117], 1, s[8:9]
	v_cvt_pk_bf16_f32 v108, v108, s0
	global_store_short v[106:107], v108, off sc1
	v_mul_f32_e32 v108, v196, v168
	v_lshl_add_u64 v[106:107], v[120:121], 1, s[8:9]
	v_cvt_pk_bf16_f32 v108, v108, s0
	global_store_short v[106:107], v108, off sc1
	v_mul_f32_e32 v108, v196, v167
	v_lshl_add_u64 v[106:107], v[122:123], 1, s[8:9]
	v_cvt_pk_bf16_f32 v108, v108, s0
	global_store_short v[106:107], v108, off sc1
	v_mul_f32_e32 v108, v196, v166
	v_lshl_add_u64 v[106:107], v[124:125], 1, s[8:9]
	v_cvt_pk_bf16_f32 v108, v108, s0
	global_store_short v[106:107], v108, off sc1
	v_mul_f32_e32 v108, v196, v103
	v_lshl_add_u64 v[106:107], v[128:129], 1, s[8:9]
	v_cvt_pk_bf16_f32 v108, v108, s0
	global_store_short v[106:107], v108, off sc1
	v_add_f32_e32 v106, 1.0, v130
	v_mul_f32_e32 v107, v131, v106
	v_add_u32_e32 v108, v191, v48
	v_ashrrev_i32_e32 v109, 31, v108
	v_mul_f32_e32 v32, v107, v197
	s_waitcnt vmcnt(25)
	v_fmac_f32_e32 v62, v34, v195
	s_waitcnt vmcnt(18)
	v_fmac_f32_e32 v61, v35, v195
	v_fmac_f32_e32 v60, v36, v195
	v_fmac_f32_e32 v59, v37, v195
	v_fmac_f32_e32 v58, v38, v195
	v_fmac_f32_e32 v57, v39, v195
	v_fmac_f32_e32 v56, v40, v195
	v_fmac_f32_e32 v55, v41, v195
	s_waitcnt vmcnt(17)
	v_fmac_f32_e32 v54, v42, v195
	s_waitcnt vmcnt(16)
	v_fmac_f32_e32 v53, v43, v195
	s_waitcnt vmcnt(15)
	v_fmac_f32_e32 v52, v44, v195
	s_waitcnt vmcnt(13)
	v_fmac_f32_e32 v51, v45, v195
	s_waitcnt vmcnt(12)
	v_fmac_f32_e32 v50, v46, v195
	s_waitcnt vmcnt(11)
	v_fmac_f32_e32 v49, v47, v195
	global_store_dword v[104:105], v197, off offset:128 sc1
	v_lshl_add_u64 v[108:109], v[108:109], 1, s[8:9]
	v_cvt_pk_bf16_f32 v32, v32, s0
	global_store_dword v[84:85], v62, off offset:128 sc1
	global_store_dword v[82:83], v61, off offset:128 sc1
	global_store_dword v[78:79], v60, off offset:128 sc1
	global_store_dword v[72:73], v59, off offset:128 sc1
	global_store_dword v[74:75], v58, off offset:128 sc1
	global_store_dword v[76:77], v57, off offset:128 sc1
	global_store_dword v[80:81], v56, off offset:128 sc1
	global_store_dword v[86:87], v55, off offset:128 sc1
	global_store_dword v[90:91], v54, off offset:128 sc1
	global_store_dword v[92:93], v53, off offset:128 sc1
	global_store_dword v[94:95], v52, off offset:128 sc1
	global_store_dword v[96:97], v51, off offset:128 sc1
	global_store_dword v[98:99], v50, off offset:128 sc1
	global_store_dword v[100:101], v49, off offset:128 sc1
	global_store_short v[108:109], v32, off sc1
	v_add_u32_e32 v108, v187, v48
	global_load_dword v45, v[88:89], off offset:256
	v_ashrrev_i32_e32 v109, 31, v108
	v_mul_f32_e32 v113, v107, v56
	v_cvt_pk_bf16_f32 v113, v113, s0
	v_mul_f32_e32 v106, v197, v197
	v_fmac_f32_e32 v106, v198, v198
	s_waitcnt vmcnt(26)
	v_fmac_f32_e32 v63, v33, v195
	v_mul_f32_e32 v34, v107, v63
	v_lshl_add_u64 v[32:33], v[108:109], 1, s[8:9]
	v_cvt_pk_bf16_f32 v34, v34, s0
	global_store_short v[32:33], v34, off sc1
	v_add_u32_e32 v32, v185, v48
	v_ashrrev_i32_e32 v33, 31, v32
	v_mul_f32_e32 v34, v107, v62
	v_lshl_add_u64 v[32:33], v[32:33], 1, s[8:9]
	v_cvt_pk_bf16_f32 v34, v34, s0
	global_store_short v[32:33], v34, off sc1
	v_add_u32_e32 v32, v184, v48
	v_ashrrev_i32_e32 v33, 31, v32
	v_mul_f32_e32 v34, v107, v61
	v_lshl_add_u64 v[32:33], v[32:33], 1, s[8:9]
	v_cvt_pk_bf16_f32 v34, v34, s0
	global_store_short v[32:33], v34, off sc1
	v_add_u32_e32 v32, v182, v48
	v_ashrrev_i32_e32 v33, 31, v32
	v_mul_f32_e32 v34, v107, v60
	v_lshl_add_u64 v[32:33], v[32:33], 1, s[8:9]
	v_cvt_pk_bf16_f32 v34, v34, s0
	global_store_short v[32:33], v34, off sc1
	v_add_u32_e32 v32, v180, v48
	v_ashrrev_i32_e32 v33, 31, v32
	v_lshl_add_u64 v[34:35], v[32:33], 1, s[8:9]
	v_mul_f32_e32 v32, v107, v59
	v_cvt_pk_bf16_f32 v42, v32, s0
	v_or_b32_e32 v32, 64, v102
	v_ashrrev_i32_e32 v33, 31, v32
	v_lshlrev_b64 v[36:37], 2, v[32:33]
	global_store_dword v[88:89], v63, off offset:128 sc1
	v_lshl_add_u64 v[40:41], s[64:65], 0, v[36:37]
	v_lshl_add_u64 v[38:39], s[62:63], 0, v[36:37]
	global_load_dword v110, v[40:41], off
	global_load_dword v111, v[38:39], off
	v_mul_f32_e32 v33, v107, v58
	global_store_short v[34:35], v42, off sc1
	v_lshl_add_u64 v[34:35], s[60:61], 0, v[36:37]
	global_load_dword v112, v[34:35], off
	v_add_u32_e32 v34, v71, v48
	v_ashrrev_i32_e32 v35, 31, v34
	v_lshl_add_u64 v[34:35], v[34:35], 1, s[8:9]
	v_cvt_pk_bf16_f32 v33, v33, s0
	global_store_short v[34:35], v33, off sc1
	v_add_u32_e32 v34, v181, v48
	v_ashrrev_i32_e32 v35, 31, v34
	v_mul_f32_e32 v33, v107, v57
	v_lshl_add_u64 v[34:35], v[34:35], 1, s[8:9]
	v_cvt_pk_bf16_f32 v33, v33, s0
	global_load_dword v38, v[90:91], off offset:256
	global_load_dword v37, v[92:93], off offset:256
	global_load_dword v36, v[94:95], off offset:256
	global_load_dword v114, v[104:105], off offset:256
	global_load_dword v47, v[84:85], off offset:256
	global_load_dword v39, v[86:87], off offset:256
	global_load_dword v46, v[82:83], off offset:256
	global_load_dword v44, v[78:79], off offset:256
	global_load_dword v43, v[72:73], off offset:256
	global_load_dword v42, v[74:75], off offset:256
	global_load_dword v40, v[80:81], off offset:256
	global_load_dword v41, v[76:77], off offset:256
	v_add_u32_e32 v108, v183, v48
	global_store_short v[34:35], v33, off sc1
	global_load_dword v35, v[96:97], off offset:256
	v_ashrrev_i32_e32 v109, 31, v108
	global_load_dword v34, v[98:99], off offset:256
	global_load_dword v33, v[100:101], off offset:256
	v_lshl_add_u64 v[108:109], v[108:109], 1, s[8:9]
	global_store_short v[108:109], v113, off sc1
	v_add_u32_e32 v108, v186, v48
	v_ashrrev_i32_e32 v109, 31, v108
	v_mul_f32_e32 v113, v107, v55
	v_lshl_add_u64 v[108:109], v[108:109], 1, s[8:9]
	v_cvt_pk_bf16_f32 v113, v113, s0
	global_store_short v[108:109], v113, off sc1
	v_add_u32_e32 v108, v188, v48
	v_ashrrev_i32_e32 v109, 31, v108
	v_mul_f32_e32 v113, v107, v54
	v_lshl_add_u64 v[108:109], v[108:109], 1, s[8:9]
	v_cvt_pk_bf16_f32 v113, v113, s0
	global_store_short v[108:109], v113, off sc1
	v_add_u32_e32 v108, v189, v48
	v_ashrrev_i32_e32 v109, 31, v108
	v_mul_f32_e32 v113, v107, v53
	v_lshl_add_u64 v[108:109], v[108:109], 1, s[8:9]
	v_cvt_pk_bf16_f32 v113, v113, s0
	global_store_short v[108:109], v113, off sc1
	v_add_u32_e32 v108, v190, v48
	v_ashrrev_i32_e32 v109, 31, v108
	v_mul_f32_e32 v113, v107, v52
	v_lshl_add_u64 v[108:109], v[108:109], 1, s[8:9]
	v_cvt_pk_bf16_f32 v113, v113, s0
	global_store_short v[108:109], v113, off sc1
	v_add_u32_e32 v108, v192, v48
	v_ashrrev_i32_e32 v109, 31, v108
	v_mul_f32_e32 v113, v107, v51
	v_lshl_add_u64 v[108:109], v[108:109], 1, s[8:9]
	v_cvt_pk_bf16_f32 v113, v113, s0
	global_store_short v[108:109], v113, off sc1
	v_add_u32_e32 v108, v193, v48
	v_ashrrev_i32_e32 v109, 31, v108
	v_mul_f32_e32 v113, v107, v50
	v_lshl_add_u64 v[108:109], v[108:109], 1, s[8:9]
	v_cvt_pk_bf16_f32 v113, v113, s0
	global_store_short v[108:109], v113, off sc1
	v_add_u32_e32 v108, v194, v48
	v_ashrrev_i32_e32 v109, 31, v108
	v_mul_f32_e32 v48, v107, v49
	v_lshl_add_u64 v[108:109], v[108:109], 1, s[8:9]
	v_cvt_pk_bf16_f32 v48, v48, s0
	global_store_short v[108:109], v48, off sc1
	v_add_u32_e32 v108, v191, v32
	v_ashrrev_i32_e32 v109, 31, v108
	s_waitcnt vmcnt(28)
	v_add_f32_e32 v48, 1.0, v110
	s_waitcnt vmcnt(27)
	v_mul_f32_e32 v48, v111, v48
	s_waitcnt vmcnt(25)
	v_fmac_f32_e32 v45, v17, v112
	global_store_dword v[88:89], v45, off offset:256 sc1
	s_waitcnt vmcnt(24)
	v_fmac_f32_e32 v38, v26, v112
	s_waitcnt vmcnt(23)
	v_fmac_f32_e32 v37, v27, v112
	s_waitcnt vmcnt(22)
	v_fmac_f32_e32 v36, v28, v112
	s_waitcnt vmcnt(21)
	v_fmac_f32_e32 v114, v16, v112
	s_waitcnt vmcnt(20)
	v_fmac_f32_e32 v47, v18, v112
	v_mul_f32_e32 v18, v48, v114
	v_lshl_add_u64 v[16:17], v[108:109], 1, s[8:9]
	v_cvt_pk_bf16_f32 v18, v18, s0
	global_store_short v[16:17], v18, off sc1
	v_add_u32_e32 v16, v187, v32
	v_ashrrev_i32_e32 v17, 31, v16
	v_mul_f32_e32 v18, v48, v45
	v_lshl_add_u64 v[16:17], v[16:17], 1, s[8:9]
	v_cvt_pk_bf16_f32 v18, v18, s0
	global_store_short v[16:17], v18, off sc1
	v_add_u32_e32 v16, v185, v32
	v_ashrrev_i32_e32 v17, 31, v16
	v_mul_f32_e32 v18, v48, v47
	v_lshl_add_u64 v[16:17], v[16:17], 1, s[8:9]
	v_cvt_pk_bf16_f32 v18, v18, s0
	s_waitcnt vmcnt(20)
	v_fmac_f32_e32 v46, v19, v112
	global_store_short v[16:17], v18, off sc1
	v_add_u32_e32 v16, v184, v32
	v_ashrrev_i32_e32 v17, 31, v16
	v_mul_f32_e32 v18, v48, v46
	v_lshl_add_u64 v[16:17], v[16:17], 1, s[8:9]
	v_cvt_pk_bf16_f32 v18, v18, s0
	global_store_short v[16:17], v18, off sc1
	v_add_u32_e32 v16, v182, v32
	v_ashrrev_i32_e32 v17, 31, v16
	v_lshl_add_u64 v[18:19], v[16:17], 1, s[8:9]
	v_or_b32_e32 v16, 0x60, v102
	v_ashrrev_i32_e32 v17, 31, v16
	s_waitcnt vmcnt(21)
	v_fmac_f32_e32 v44, v20, v112
	s_waitcnt vmcnt(20)
	v_fmac_f32_e32 v43, v21, v112
	s_waitcnt vmcnt(19)
	v_fmac_f32_e32 v42, v22, v112
	s_waitcnt vmcnt(17)
	v_fmac_f32_e32 v41, v23, v112
	v_fmac_f32_e32 v40, v24, v112
	v_fmac_f32_e32 v39, v25, v112
	s_waitcnt vmcnt(15)
	v_fmac_f32_e32 v35, v29, v112
	s_waitcnt vmcnt(14)
	v_fmac_f32_e32 v34, v30, v112
	s_waitcnt vmcnt(13)
	v_fmac_f32_e32 v33, v31, v112
	v_lshlrev_b64 v[20:21], 2, v[16:17]
	global_store_dword v[84:85], v47, off offset:256 sc1
	global_store_dword v[82:83], v46, off offset:256 sc1
	global_store_dword v[78:79], v44, off offset:256 sc1
	global_store_dword v[72:73], v43, off offset:256 sc1
	global_store_dword v[74:75], v42, off offset:256 sc1
	global_store_dword v[76:77], v41, off offset:256 sc1
	global_store_dword v[80:81], v40, off offset:256 sc1
	global_store_dword v[86:87], v39, off offset:256 sc1
	global_store_dword v[90:91], v38, off offset:256 sc1
	global_store_dword v[92:93], v37, off offset:256 sc1
	global_store_dword v[94:95], v36, off offset:256 sc1
	global_store_dword v[96:97], v35, off offset:256 sc1
	global_store_dword v[98:99], v34, off offset:256 sc1
	global_store_dword v[100:101], v33, off offset:256 sc1
	global_store_dword v[104:105], v114, off offset:256 sc1
	v_mul_f32_e32 v26, v48, v44
	v_lshl_add_u64 v[22:23], s[62:63], 0, v[20:21]
	v_lshl_add_u64 v[24:25], s[64:65], 0, v[20:21]
	global_load_dword v29, v[104:105], off offset:384
	global_load_dword v17, v[24:25], off
	global_load_dword v30, v[22:23], off
	v_cvt_pk_bf16_f32 v22, v26, s0
	global_store_short v[18:19], v22, off sc1
	v_lshl_add_u64 v[18:19], s[60:61], 0, v[20:21]
	global_load_dword v102, v[18:19], off
	v_add_u32_e32 v18, v180, v32
	v_ashrrev_i32_e32 v19, 31, v18
	v_mul_f32_e32 v20, v48, v43
	v_lshl_add_u64 v[18:19], v[18:19], 1, s[8:9]
	v_cvt_pk_bf16_f32 v20, v20, s0
	global_store_short v[18:19], v20, off sc1
	v_add_u32_e32 v18, v71, v32
	v_ashrrev_i32_e32 v19, 31, v18
	v_mul_f32_e32 v20, v48, v42
	v_lshl_add_u64 v[18:19], v[18:19], 1, s[8:9]
	v_cvt_pk_bf16_f32 v20, v20, s0
	global_store_short v[18:19], v20, off sc1
	v_add_u32_e32 v18, v181, v32
	v_ashrrev_i32_e32 v19, 31, v18
	v_mul_f32_e32 v20, v48, v41
	v_lshl_add_u64 v[18:19], v[18:19], 1, s[8:9]
	v_cvt_pk_bf16_f32 v20, v20, s0
	global_store_short v[18:19], v20, off sc1
	v_add_u32_e32 v18, v183, v32
	v_ashrrev_i32_e32 v19, 31, v18
	v_mul_f32_e32 v20, v48, v40
	v_lshl_add_u64 v[18:19], v[18:19], 1, s[8:9]
	v_cvt_pk_bf16_f32 v20, v20, s0
	global_store_short v[18:19], v20, off sc1
	v_add_u32_e32 v18, v186, v32
	v_ashrrev_i32_e32 v19, 31, v18
	v_mul_f32_e32 v20, v48, v39
	v_lshl_add_u64 v[18:19], v[18:19], 1, s[8:9]
	v_cvt_pk_bf16_f32 v20, v20, s0
	global_store_short v[18:19], v20, off sc1
	v_add_u32_e32 v18, v188, v32
	v_ashrrev_i32_e32 v19, 31, v18
	v_mul_f32_e32 v20, v48, v38
	v_lshl_add_u64 v[18:19], v[18:19], 1, s[8:9]
	v_cvt_pk_bf16_f32 v20, v20, s0
	global_store_short v[18:19], v20, off sc1
	v_add_u32_e32 v18, v189, v32
	v_ashrrev_i32_e32 v19, 31, v18
	v_mul_f32_e32 v20, v48, v37
	v_lshl_add_u64 v[18:19], v[18:19], 1, s[8:9]
	v_cvt_pk_bf16_f32 v20, v20, s0
	global_store_short v[18:19], v20, off sc1
	v_add_u32_e32 v18, v190, v32
	v_ashrrev_i32_e32 v19, 31, v18
	v_mul_f32_e32 v20, v48, v36
	v_lshl_add_u64 v[18:19], v[18:19], 1, s[8:9]
	v_cvt_pk_bf16_f32 v20, v20, s0
	global_store_short v[18:19], v20, off sc1
	v_add_u32_e32 v18, v192, v32
	v_ashrrev_i32_e32 v19, 31, v18
	v_mul_f32_e32 v20, v48, v35
	v_lshl_add_u64 v[18:19], v[18:19], 1, s[8:9]
	v_cvt_pk_bf16_f32 v20, v20, s0
	global_load_dword v28, v[88:89], off offset:384
	global_load_dword v27, v[84:85], off offset:384
	global_load_dword v25, v[78:79], off offset:384
	global_load_dword v24, v[72:73], off offset:384
	global_load_dword v23, v[74:75], off offset:384
	global_load_dword v21, v[80:81], off offset:384
	global_load_dword v22, v[76:77], off offset:384
	v_fmac_f32_e32 v106, v114, v114
	global_store_short v[18:19], v20, off sc1
	v_add_u32_e32 v18, v193, v32
	v_ashrrev_i32_e32 v19, 31, v18
	v_mul_f32_e32 v20, v48, v34
	v_lshl_add_u64 v[18:19], v[18:19], 1, s[8:9]
	v_cvt_pk_bf16_f32 v20, v20, s0
	global_store_short v[18:19], v20, off sc1
	v_add_u32_e32 v18, v194, v32
	v_ashrrev_i32_e32 v19, 31, v18
	v_mul_f32_e32 v20, v48, v33
	v_lshl_add_u64 v[18:19], v[18:19], 1, s[8:9]
	v_cvt_pk_bf16_f32 v20, v20, s0
	global_store_short v[18:19], v20, off sc1
	global_load_dword v20, v[86:87], off offset:384
	s_waitcnt vmcnt(22)
	v_add_f32_e32 v17, 1.0, v17
	global_load_dword v26, v[82:83], off offset:384
	s_waitcnt vmcnt(22)
	v_mul_f32_e32 v32, v30, v17
	v_add_u32_e32 v18, v191, v16
	s_waitcnt vmcnt(20)
	v_fmac_f32_e32 v29, v0, v102
	v_ashrrev_i32_e32 v19, 31, v18
	v_mul_f32_e32 v0, v32, v29
	v_lshl_add_u64 v[18:19], v[18:19], 1, s[8:9]
	v_cvt_pk_bf16_f32 v0, v0, s0
	global_store_short v[18:19], v0, off sc1
	global_load_dword v19, v[90:91], off offset:384
	v_add_u32_e32 v30, v187, v16
	global_load_dword v18, v[92:93], off offset:384
	v_ashrrev_i32_e32 v31, 31, v30
	v_fmac_f32_e32 v106, v29, v29
	global_store_dword v[104:105], v29, off offset:384 sc1
	s_waitcnt vmcnt(15)
	v_fmac_f32_e32 v28, v1, v102
	v_mul_f32_e32 v17, v32, v28
	v_lshl_add_u64 v[0:1], v[30:31], 1, s[8:9]
	v_cvt_pk_bf16_f32 v17, v17, s0
	global_store_short v[0:1], v17, off sc1
	v_add_u32_e32 v0, v185, v16
	s_waitcnt vmcnt(15)
	v_fmac_f32_e32 v27, v2, v102
	global_load_dword v17, v[94:95], off offset:384
	v_ashrrev_i32_e32 v1, 31, v0
	v_mul_f32_e32 v2, v32, v27
	v_lshl_add_u64 v[0:1], v[0:1], 1, s[8:9]
	v_cvt_pk_bf16_f32 v2, v2, s0
	global_store_short v[0:1], v2, off sc1
	v_add_u32_e32 v0, v184, v16
	global_load_dword v2, v[96:97], off offset:384
	v_ashrrev_i32_e32 v1, 31, v0
	v_lshl_add_u64 v[0:1], v[0:1], 1, s[8:9]
	v_add_u32_e32 v30, v182, v16
	s_waitcnt vmcnt(17)
	v_fmac_f32_e32 v25, v4, v102
	v_ashrrev_i32_e32 v31, 31, v30
	v_lshl_add_u64 v[30:31], v[30:31], 1, s[8:9]
	s_waitcnt vmcnt(16)
	v_fmac_f32_e32 v24, v5, v102
	s_waitcnt vmcnt(15)
	v_fmac_f32_e32 v23, v6, v102
	s_waitcnt vmcnt(8)
	v_fmac_f32_e32 v26, v3, v102
	v_mul_f32_e32 v3, v32, v26
	v_cvt_pk_bf16_f32 v3, v3, s0
	global_store_short v[0:1], v3, off sc1
	global_load_dword v1, v[98:99], off offset:384
	v_mul_f32_e32 v0, v32, v25
	v_cvt_pk_bf16_f32 v0, v0, s0
	global_store_short v[30:31], v0, off sc1
	global_load_dword v0, v[100:101], off offset:384
	v_add_u32_e32 v30, v180, v16
	v_ashrrev_i32_e32 v31, 31, v30
	v_mul_f32_e32 v3, v32, v24
	v_lshl_add_u64 v[4:5], v[30:31], 1, s[8:9]
	v_cvt_pk_bf16_f32 v3, v3, s0
	global_store_short v[4:5], v3, off sc1
	v_add_u32_e32 v4, v71, v16
	v_ashrrev_i32_e32 v5, 31, v4
	v_mul_f32_e32 v3, v32, v23
	v_lshl_add_u64 v[4:5], v[4:5], 1, s[8:9]
	v_cvt_pk_bf16_f32 v3, v3, s0
	global_store_short v[4:5], v3, off sc1
	v_add_u32_e32 v4, v181, v16
	v_fmac_f32_e32 v22, v7, v102
	v_ashrrev_i32_e32 v5, 31, v4
	v_mul_f32_e32 v3, v32, v22
	v_lshl_add_u64 v[4:5], v[4:5], 1, s[8:9]
	v_cvt_pk_bf16_f32 v3, v3, s0
	global_store_short v[4:5], v3, off sc1
	v_add_u32_e32 v4, v183, v16
	v_fmac_f32_e32 v21, v8, v102
	v_ashrrev_i32_e32 v5, 31, v4
	v_mul_f32_e32 v3, v32, v21
	v_lshl_add_u64 v[4:5], v[4:5], 1, s[8:9]
	v_cvt_pk_bf16_f32 v3, v3, s0
	global_store_short v[4:5], v3, off sc1
	v_add_u32_e32 v4, v186, v16
	v_fmac_f32_e32 v20, v9, v102
	v_ashrrev_i32_e32 v5, 31, v4
	v_mul_f32_e32 v3, v32, v20
	v_lshl_add_u64 v[4:5], v[4:5], 1, s[8:9]
	v_cvt_pk_bf16_f32 v3, v3, s0
	global_store_short v[4:5], v3, off sc1
	v_add_u32_e32 v4, v188, v16
	s_waitcnt vmcnt(15)
	v_fmac_f32_e32 v19, v10, v102
	v_ashrrev_i32_e32 v5, 31, v4
	v_mul_f32_e32 v3, v32, v19
	v_lshl_add_u64 v[4:5], v[4:5], 1, s[8:9]
	v_cvt_pk_bf16_f32 v3, v3, s0
	global_store_short v[4:5], v3, off sc1
	v_add_u32_e32 v4, v189, v16
	s_waitcnt vmcnt(15)
	v_fmac_f32_e32 v18, v11, v102
	v_ashrrev_i32_e32 v5, 31, v4
	v_mul_f32_e32 v3, v32, v18
	v_lshl_add_u64 v[4:5], v[4:5], 1, s[8:9]
	v_cvt_pk_bf16_f32 v3, v3, s0
	global_store_short v[4:5], v3, off sc1
	v_add_u32_e32 v4, v190, v16
	v_ashrrev_i32_e32 v5, 31, v4
	v_lshl_add_u64 v[4:5], v[4:5], 1, s[8:9]
	v_ashrrev_i32_e32 v71, 31, v70
	global_store_dword v[88:89], v28, off offset:384 sc1
	global_store_dword v[84:85], v27, off offset:384 sc1
	global_store_dword v[82:83], v26, off offset:384 sc1
	global_store_dword v[78:79], v25, off offset:384 sc1
	s_waitcnt vmcnt(17)
	v_fmac_f32_e32 v17, v12, v102
	v_mul_f32_e32 v3, v32, v17
	v_cvt_pk_bf16_f32 v3, v3, s0
	global_store_short v[4:5], v3, off sc1
	v_add_u32_e32 v4, v192, v16
	v_ashrrev_i32_e32 v5, 31, v4
	v_lshl_add_u64 v[4:5], v[4:5], 1, s[8:9]
	s_waitcnt vmcnt(16)
	v_fmac_f32_e32 v2, v13, v102
	v_mul_f32_e32 v3, v32, v2
	v_cvt_pk_bf16_f32 v3, v3, s0
	global_store_short v[4:5], v3, off sc1
	v_add_u32_e32 v4, v193, v16
	v_ashrrev_i32_e32 v5, 31, v4
	v_lshl_add_u64 v[4:5], v[4:5], 1, s[8:9]
	v_xor_b32_e32 v12, 16, v165
	global_store_dword v[72:73], v24, off offset:384 sc1
	global_store_dword v[74:75], v23, off offset:384 sc1
	global_store_dword v[76:77], v22, off offset:384 sc1
	global_store_dword v[80:81], v21, off offset:384 sc1
	global_store_dword v[86:87], v20, off offset:384 sc1
	s_waitcnt vmcnt(20)
	v_fmac_f32_e32 v1, v14, v102
	v_mul_f32_e32 v3, v32, v1
	v_cvt_pk_bf16_f32 v3, v3, s0
	global_store_short v[4:5], v3, off sc1
	v_add_u32_e32 v4, v194, v16
	v_ashrrev_i32_e32 v5, 31, v4
	v_lshl_add_u64 v[10:11], v[4:5], 1, s[8:9]
	v_and_b32_e32 v4, 64, v165
	v_xor_b32_e32 v3, 1, v165
	v_add_u32_e32 v7, 64, v4
	v_cmp_lt_i32_e32 vcc, v3, v7
	v_xor_b32_e32 v4, 2, v165
	s_waitcnt vmcnt(19)
	v_fmac_f32_e32 v0, v15, v102
	v_cndmask_b32_e32 v3, v165, v3, vcc
	v_lshlrev_b32_e32 v3, 2, v3
	v_cmp_lt_i32_e32 vcc, v4, v7
	global_store_dword v[90:91], v19, off offset:384 sc1
	global_store_dword v[92:93], v18, off offset:384 sc1
	v_cndmask_b32_e32 v4, v165, v4, vcc
	v_lshlrev_b32_e32 v4, 2, v4
	v_add_f32_dpp v6, v106, v106 quad_perm:[1,0,3,2] row_mask:0xf bank_mask:0xf
	v_xor_b32_e32 v5, 4, v165
	v_cmp_lt_i32_e32 vcc, v5, v7
	global_store_dword v[94:95], v17, off offset:384 sc1
	global_store_dword v[96:97], v2, off offset:384 sc1
	v_cndmask_b32_e32 v5, v165, v5, vcc
	v_lshlrev_b32_e32 v5, 2, v5
	v_add_f32_dpp v8, v6, v6 quad_perm:[2,3,0,1] row_mask:0xf bank_mask:0xf
	v_xor_b32_e32 v6, 8, v165
	v_cmp_lt_i32_e32 vcc, v6, v7
	global_store_dword v[98:99], v1, off offset:384 sc1
	global_store_dword v[100:101], v0, off offset:384 sc1
	v_cndmask_b32_e32 v6, v165, v6, vcc
	v_lshlrev_b32_e32 v6, 2, v6
	v_add_f32_dpp v8, v8, v8 row_half_mirror row_mask:0xf bank_mask:0xf
	v_cmp_lt_i32_e32 vcc, v12, v7
	v_add_f32_dpp v8, v8, v8 row_mirror row_mask:0xf bank_mask:0xf
	v_cndmask_b32_e32 v7, v165, v12, vcc
	v_lshlrev_b32_e32 v7, 2, v7
	ds_bpermute_b32 v9, v7, v8
	v_mul_f32_e32 v12, v32, v0
	v_cvt_pk_bf16_f32 v12, v12, s0
	global_store_short v[10:11], v12, off sc1
	s_and_saveexec_b64 s[60:61], s[0:1]
	s_cbranch_execz .LBB0_1400
	s_waitcnt lgkmcnt(0)
	v_add_f32_e32 v10, v8, v9
	v_lshl_add_u64 v[8:9], v[70:71], 2, s[58:59]
	global_store_dword v[8:9], v10, off sc1

.LBB0_1569:
	s_add_i32 s58, s66, 0xffffe000
	s_lshr_b32 s58, s58, 12
	s_mulk_i32 s58, 0x1800
	v_mov_b32_e32 v70, s70
	s_add_i32 s58, s58, 0xf000
	ds_read_b64 v[70:71], v70
	s_cmp_gt_i32 s6, 63
	s_cselect_b32 s6, s58, 0xd800
	s_lshl_b64 s[58:59], s[6:7], 2
	s_add_u32 s6, s14, s58
	s_addc_u32 s65, s15, s59
	s_waitcnt lgkmcnt(0)
	v_readfirstlane_b32 s58, v70
	v_readfirstlane_b32 s59, v71
	s_add_u32 s60, s58, 0x3000
	s_addc_u32 s61, s59, 0
	s_lshl_b32 s58, s64, 14
	s_add_i32 s58, s58, 0xe0000
	s_ashr_i32 s59, s58, 31
	s_lshl_b64 s[58:59], s[58:59], 2
	s_add_u32 s58, s10, s58
	s_addc_u32 s59, s11, s59
	s_add_u32 s62, s6, 0x5ba2000
	v_or_b32_e32 v102, s68, v138
	v_add_u32_e32 v70, s66, v139
	s_addc_u32 s63, s65, 0
	v_lshlrev_b32_e32 v188, 10, v70
	v_ashrrev_i32_e32 v103, 31, v102
	s_add_u32 s64, s6, 0x5ba4000
	v_lshlrev_b64 v[72:73], 2, v[102:103]
	v_or_b32_e32 v186, 0x400, v188
	v_or_b32_e32 v185, 0x4400, v188
	v_or_b32_e32 v189, 0x4c00, v188
	v_or_b32_e32 v193, 0x6c00, v188
	s_addc_u32 s65, s65, 0
	v_lshl_add_u64 v[74:75], s[62:63], 0, v[72:73]
	v_add_u32_e32 v132, v188, v102
	v_add_u32_e32 v134, v186, v102
	v_or_b32_e32 v184, 0x800, v188
	v_or_b32_e32 v183, 0xc00, v188
	v_or_b32_e32 v181, 0x2000, v188
	v_or_b32_e32 v179, 0x2400, v188
	v_or_b32_e32 v71, 0x2800, v188
	v_or_b32_e32 v180, 0x2c00, v188
	v_or_b32_e32 v182, 0x4000, v188
	v_add_u32_e32 v112, v185, v102
	v_or_b32_e32 v187, 0x4800, v188
	v_add_u32_e32 v118, v189, v102
	v_or_b32_e32 v190, 0x6000, v188
	v_or_b32_e32 v191, 0x6400, v188
	v_or_b32_e32 v192, 0x6800, v188
	v_add_u32_e32 v128, v193, v102
	global_load_dword v194, v[74:75], off
	v_lshl_add_u64 v[74:75], s[60:61], 0, v[72:73]
	v_lshl_add_u64 v[72:73], s[64:65], 0, v[72:73]
	v_ashrrev_i32_e32 v135, 31, v134
	v_add_u32_e32 v136, v184, v102
	v_add_u32_e32 v130, v183, v102
	v_add_u32_e32 v122, v181, v102
	v_add_u32_e32 v114, v179, v102
	v_add_u32_e32 v106, v71, v102
	v_add_u32_e32 v108, v180, v102
	v_add_u32_e32 v110, v182, v102
	v_ashrrev_i32_e32 v113, 31, v112
	v_add_u32_e32 v116, v187, v102
	v_ashrrev_i32_e32 v119, 31, v118
	v_add_u32_e32 v120, v190, v102
	v_add_u32_e32 v124, v191, v102
	v_add_u32_e32 v126, v192, v102
	v_ashrrev_i32_e32 v129, 31, v128
	v_ashrrev_i32_e32 v133, 31, v132
	global_load_dword v196, v[72:73], off
	v_lshl_add_u64 v[88:89], v[134:135], 2, s[12:13]
	v_ashrrev_i32_e32 v137, 31, v136
	v_ashrrev_i32_e32 v131, 31, v130
	v_ashrrev_i32_e32 v123, 31, v122
	v_ashrrev_i32_e32 v115, 31, v114
	v_ashrrev_i32_e32 v107, 31, v106
	v_ashrrev_i32_e32 v109, 31, v108
	v_ashrrev_i32_e32 v111, 31, v110
	v_lshl_add_u64 v[86:87], v[112:113], 2, s[12:13]
	v_ashrrev_i32_e32 v117, 31, v116
	v_lshl_add_u64 v[92:93], v[118:119], 2, s[12:13]
	v_ashrrev_i32_e32 v121, 31, v120
	v_ashrrev_i32_e32 v125, 31, v124
	v_ashrrev_i32_e32 v127, 31, v126
	v_lshl_add_u64 v[100:101], v[128:129], 2, s[12:13]
	v_lshl_add_u64 v[104:105], v[132:133], 2, s[12:13]
	global_load_dword v195, v[74:75], off
	v_lshl_add_u64 v[84:85], v[136:137], 2, s[12:13]
	v_lshl_add_u64 v[82:83], v[130:131], 2, s[12:13]
	v_lshl_add_u64 v[78:79], v[122:123], 2, s[12:13]
	v_lshl_add_u64 v[72:73], v[114:115], 2, s[12:13]
	v_lshl_add_u64 v[74:75], v[106:107], 2, s[12:13]
	v_lshl_add_u64 v[76:77], v[108:109], 2, s[12:13]
	v_lshl_add_u64 v[80:81], v[110:111], 2, s[12:13]
	global_load_dword v178, v[88:89], off
	global_load_dword v177, v[84:85], off
	global_load_dword v176, v[82:83], off
	global_load_dword v175, v[78:79], off
	global_load_dword v174, v[72:73], off
	global_load_dword v173, v[74:75], off
	global_load_dword v172, v[76:77], off
	global_load_dword v171, v[80:81], off
	v_lshl_add_u64 v[90:91], v[116:117], 2, s[12:13]
	global_load_dword v170, v[86:87], off
	global_load_dword v168, v[90:91], off
	v_lshl_add_u64 v[94:95], v[120:121], 2, s[12:13]
	v_lshl_add_u64 v[96:97], v[124:125], 2, s[12:13]
	v_lshl_add_u64 v[98:99], v[126:127], 2, s[12:13]
	global_load_dword v169, v[92:93], off
	global_load_dword v167, v[94:95], off
	global_load_dword v166, v[96:97], off
	global_load_dword v165, v[98:99], off
	global_load_dword v103, v[100:101], off
	global_load_dword v197, v[104:105], off
	v_lshl_add_u64 v[106:107], v[106:107], 1, s[8:9]
	s_waitcnt vmcnt(0)
	v_add_f32_e32 v196, 1.0, v196
	v_mul_f32_e32 v195, v195, v196
	v_fmac_f32_e32 v178, v49, v194
	v_fmac_f32_e32 v177, v50, v194
	v_fmac_f32_e32 v176, v51, v194
	v_fmac_f32_e32 v175, v52, v194
	v_fmac_f32_e32 v174, v53, v194
	v_fmac_f32_e32 v173, v54, v194
	v_fmac_f32_e32 v172, v55, v194
	v_fmac_f32_e32 v171, v56, v194
	v_fmac_f32_e32 v170, v57, v194
	v_fmac_f32_e32 v168, v58, v194
	v_fmac_f32_e32 v169, v59, v194
	v_fmac_f32_e32 v167, v60, v194
	v_fmac_f32_e32 v166, v61, v194
	v_fmac_f32_e32 v165, v62, v194
	v_fmac_f32_e32 v103, v63, v194
	v_fmac_f32_e32 v197, v48, v194
	v_mul_f32_e32 v48, v195, v197
	v_cvt_pk_bf16_f32 v58, v48, s0
	v_or_b32_e32 v48, 32, v102
	v_ashrrev_i32_e32 v49, 31, v48
	v_lshlrev_b64 v[52:53], 2, v[48:49]
	global_store_dword v[88:89], v178, off sc1
	global_store_dword v[84:85], v177, off sc1
	global_store_dword v[82:83], v176, off sc1
	global_store_dword v[78:79], v175, off sc1
	global_store_dword v[72:73], v174, off sc1
	global_store_dword v[74:75], v173, off sc1
	global_store_dword v[76:77], v172, off sc1
	global_store_dword v[80:81], v171, off sc1
	global_store_dword v[86:87], v170, off sc1
	global_store_dword v[90:91], v168, off sc1
	global_store_dword v[92:93], v169, off sc1
	global_store_dword v[94:95], v167, off sc1
	global_store_dword v[96:97], v166, off sc1
	global_store_dword v[98:99], v165, off sc1
	global_store_dword v[100:101], v103, off sc1
	global_store_dword v[104:105], v197, off sc1
	v_lshl_add_u64 v[50:51], v[132:133], 1, s[8:9]
	v_lshl_add_u64 v[56:57], s[64:65], 0, v[52:53]
	global_load_dword v196, v[104:105], off offset:128
	v_lshl_add_u64 v[54:55], s[60:61], 0, v[52:53]
	global_load_dword v132, v[56:57], off
	global_load_dword v133, v[54:55], off
	v_mul_f32_e32 v49, v195, v178
	global_store_short v[50:51], v58, off sc1
	v_lshl_add_u64 v[50:51], s[62:63], 0, v[52:53]
	global_load_dword v194, v[50:51], off
	v_cvt_pk_bf16_f32 v49, v49, s0
	v_lshl_add_u64 v[50:51], v[134:135], 1, s[8:9]
	global_store_short v[50:51], v49, off sc1
	v_mul_f32_e32 v49, v195, v177
	v_cvt_pk_bf16_f32 v49, v49, s0
	v_lshl_add_u64 v[50:51], v[136:137], 1, s[8:9]
	global_store_short v[50:51], v49, off sc1
	v_mul_f32_e32 v49, v195, v176
	v_cvt_pk_bf16_f32 v49, v49, s0
	v_lshl_add_u64 v[50:51], v[130:131], 1, s[8:9]
	global_store_short v[50:51], v49, off sc1
	v_mul_f32_e32 v49, v195, v175
	v_cvt_pk_bf16_f32 v49, v49, s0
	v_lshl_add_u64 v[50:51], v[122:123], 1, s[8:9]
	global_store_short v[50:51], v49, off sc1
	v_mul_f32_e32 v49, v195, v174
	v_cvt_pk_bf16_f32 v49, v49, s0
	v_lshl_add_u64 v[50:51], v[114:115], 1, s[8:9]
	global_store_short v[50:51], v49, off sc1
	v_mul_f32_e32 v49, v195, v173
	global_load_dword v62, v[84:85], off offset:128
	global_load_dword v60, v[78:79], off offset:128
	global_load_dword v59, v[72:73], off offset:128
	global_load_dword v58, v[74:75], off offset:128
	global_load_dword v56, v[80:81], off offset:128
	global_load_dword v57, v[76:77], off offset:128
	global_load_dword v55, v[86:87], off offset:128
	global_load_dword v61, v[82:83], off offset:128
	global_load_dword v54, v[90:91], off offset:128
	global_load_dword v53, v[92:93], off offset:128
	global_load_dword v52, v[94:95], off offset:128
	global_load_dword v51, v[96:97], off offset:128
	global_load_dword v50, v[98:99], off offset:128
	v_cvt_pk_bf16_f32 v63, v49, s0
	global_load_dword v49, v[100:101], off offset:128
	s_waitcnt vmcnt(19)
	v_fmac_f32_e32 v196, v32, v194
	global_store_short v[106:107], v63, off sc1
	global_load_dword v63, v[88:89], off offset:128
	v_mul_f32_e32 v106, v195, v172
	v_cvt_pk_bf16_f32 v114, v106, s0
	v_lshl_add_u64 v[106:107], v[108:109], 1, s[8:9]
	global_store_short v[106:107], v114, off sc1
	v_mul_f32_e32 v106, v195, v171
	v_cvt_pk_bf16_f32 v108, v106, s0
	v_lshl_add_u64 v[106:107], v[110:111], 1, s[8:9]
	global_store_short v[106:107], v108, off sc1
	v_mul_f32_e32 v106, v195, v170
	v_cvt_pk_bf16_f32 v108, v106, s0
	v_lshl_add_u64 v[106:107], v[112:113], 1, s[8:9]
	global_store_short v[106:107], v108, off sc1
	v_mul_f32_e32 v106, v195, v168
	v_cvt_pk_bf16_f32 v108, v106, s0
	v_lshl_add_u64 v[106:107], v[116:117], 1, s[8:9]
	global_store_short v[106:107], v108, off sc1
	v_mul_f32_e32 v106, v195, v169
	v_cvt_pk_bf16_f32 v108, v106, s0
	v_lshl_add_u64 v[106:107], v[118:119], 1, s[8:9]
	global_store_short v[106:107], v108, off sc1
	v_mul_f32_e32 v106, v195, v167
	v_cvt_pk_bf16_f32 v108, v106, s0
	v_lshl_add_u64 v[106:107], v[120:121], 1, s[8:9]
	global_store_short v[106:107], v108, off sc1
	v_mul_f32_e32 v106, v195, v166
	v_cvt_pk_bf16_f32 v108, v106, s0
	v_lshl_add_u64 v[106:107], v[124:125], 1, s[8:9]
	global_store_short v[106:107], v108, off sc1
	v_mul_f32_e32 v106, v195, v165
	v_cvt_pk_bf16_f32 v108, v106, s0
	v_lshl_add_u64 v[106:107], v[126:127], 1, s[8:9]
	global_store_short v[106:107], v108, off sc1
	v_mul_f32_e32 v106, v195, v103
	v_cvt_pk_bf16_f32 v108, v106, s0
	v_lshl_add_u64 v[106:107], v[128:129], 1, s[8:9]
	global_store_short v[106:107], v108, off sc1
	v_add_f32_e32 v106, 1.0, v132
	v_mul_f32_e32 v110, v133, v106
	v_add_u32_e32 v106, v188, v48
	s_waitcnt vmcnt(24)
	v_fmac_f32_e32 v62, v34, v194
	s_waitcnt vmcnt(17)
	v_fmac_f32_e32 v61, v35, v194
	v_fmac_f32_e32 v60, v36, v194
	v_fmac_f32_e32 v59, v37, v194
	v_fmac_f32_e32 v58, v38, v194
	v_fmac_f32_e32 v57, v39, v194
	v_fmac_f32_e32 v56, v40, v194
	v_fmac_f32_e32 v55, v41, v194
	s_waitcnt vmcnt(16)
	v_fmac_f32_e32 v54, v42, v194
	s_waitcnt vmcnt(15)
	v_fmac_f32_e32 v53, v43, v194
	s_waitcnt vmcnt(14)
	v_fmac_f32_e32 v52, v44, v194
	s_waitcnt vmcnt(13)
	v_fmac_f32_e32 v51, v45, v194
	s_waitcnt vmcnt(12)
	v_fmac_f32_e32 v50, v46, v194
	s_waitcnt vmcnt(11)
	v_fmac_f32_e32 v49, v47, v194
	v_ashrrev_i32_e32 v107, 31, v106
	global_store_dword v[104:105], v196, off offset:128 sc1
	v_mul_f32_e32 v32, v110, v196
	global_store_dword v[84:85], v62, off offset:128 sc1
	global_store_dword v[82:83], v61, off offset:128 sc1
	global_store_dword v[78:79], v60, off offset:128 sc1
	global_store_dword v[72:73], v59, off offset:128 sc1
	global_store_dword v[74:75], v58, off offset:128 sc1
	global_store_dword v[76:77], v57, off offset:128 sc1
	global_store_dword v[80:81], v56, off offset:128 sc1
	global_store_dword v[86:87], v55, off offset:128 sc1
	global_store_dword v[90:91], v54, off offset:128 sc1
	global_store_dword v[92:93], v53, off offset:128 sc1
	global_store_dword v[94:95], v52, off offset:128 sc1
	global_store_dword v[96:97], v51, off offset:128 sc1
	global_store_dword v[98:99], v50, off offset:128 sc1
	global_store_dword v[100:101], v49, off offset:128 sc1
	v_cvt_pk_bf16_f32 v32, v32, s0
	v_lshl_add_u64 v[106:107], v[106:107], 1, s[8:9]
	v_add_u32_e32 v108, v186, v48
	global_load_dword v45, v[88:89], off offset:256
	v_ashrrev_i32_e32 v109, 31, v108
	global_store_short v[106:107], v32, off sc1
	v_mul_f32_e32 v113, v110, v56
	v_cvt_pk_bf16_f32 v113, v113, s0
	v_mul_f32_e32 v106, v196, v196
	s_waitcnt vmcnt(26)
	v_fmac_f32_e32 v63, v33, v194
	v_mul_f32_e32 v32, v110, v63
	v_cvt_pk_bf16_f32 v34, v32, s0
	v_lshl_add_u64 v[32:33], v[108:109], 1, s[8:9]
	global_store_short v[32:33], v34, off sc1
	v_add_u32_e32 v32, v184, v48
	v_ashrrev_i32_e32 v33, 31, v32
	v_mul_f32_e32 v34, v110, v62
	v_cvt_pk_bf16_f32 v34, v34, s0
	v_lshl_add_u64 v[32:33], v[32:33], 1, s[8:9]
	global_store_short v[32:33], v34, off sc1
	v_add_u32_e32 v32, v183, v48
	v_ashrrev_i32_e32 v33, 31, v32
	v_mul_f32_e32 v34, v110, v61
	v_cvt_pk_bf16_f32 v34, v34, s0
	v_lshl_add_u64 v[32:33], v[32:33], 1, s[8:9]
	global_store_short v[32:33], v34, off sc1
	v_add_u32_e32 v32, v181, v48
	v_ashrrev_i32_e32 v33, 31, v32
	v_mul_f32_e32 v34, v110, v60
	v_cvt_pk_bf16_f32 v34, v34, s0
	v_lshl_add_u64 v[32:33], v[32:33], 1, s[8:9]
	global_store_short v[32:33], v34, off sc1
	v_add_u32_e32 v32, v179, v48
	v_ashrrev_i32_e32 v33, 31, v32
	v_mul_f32_e32 v34, v110, v59
	v_cvt_pk_bf16_f32 v42, v34, s0
	v_lshl_add_u64 v[34:35], v[32:33], 1, s[8:9]
	v_or_b32_e32 v32, 64, v102
	v_ashrrev_i32_e32 v33, 31, v32
	v_lshlrev_b64 v[36:37], 2, v[32:33]
	global_store_dword v[88:89], v63, off offset:128 sc1
	v_lshl_add_u64 v[40:41], s[64:65], 0, v[36:37]
	v_lshl_add_u64 v[38:39], s[60:61], 0, v[36:37]
	global_load_dword v107, v[40:41], off
	global_load_dword v111, v[38:39], off
	v_mul_f32_e32 v33, v110, v58
	global_store_short v[34:35], v42, off sc1
	v_lshl_add_u64 v[34:35], s[62:63], 0, v[36:37]
	global_load_dword v112, v[34:35], off
	v_add_u32_e32 v34, v71, v48
	v_ashrrev_i32_e32 v35, 31, v34
	v_cvt_pk_bf16_f32 v33, v33, s0
	v_lshl_add_u64 v[34:35], v[34:35], 1, s[8:9]
	global_store_short v[34:35], v33, off sc1
	v_add_u32_e32 v34, v180, v48
	v_ashrrev_i32_e32 v35, 31, v34
	v_mul_f32_e32 v33, v110, v57
	v_cvt_pk_bf16_f32 v33, v33, s0
	v_lshl_add_u64 v[34:35], v[34:35], 1, s[8:9]
	global_load_dword v38, v[90:91], off offset:256
	global_load_dword v37, v[92:93], off offset:256
	global_load_dword v36, v[94:95], off offset:256
	global_load_dword v114, v[104:105], off offset:256
	global_load_dword v47, v[84:85], off offset:256
	global_load_dword v39, v[86:87], off offset:256
	global_load_dword v46, v[82:83], off offset:256
	global_load_dword v44, v[78:79], off offset:256
	global_load_dword v43, v[72:73], off offset:256
	global_load_dword v42, v[74:75], off offset:256
	global_load_dword v40, v[80:81], off offset:256
	global_load_dword v41, v[76:77], off offset:256
	v_add_u32_e32 v108, v182, v48
	global_store_short v[34:35], v33, off sc1
	global_load_dword v35, v[96:97], off offset:256
	v_ashrrev_i32_e32 v109, 31, v108
	global_load_dword v34, v[98:99], off offset:256
	global_load_dword v33, v[100:101], off offset:256
	v_lshl_add_u64 v[108:109], v[108:109], 1, s[8:9]
	global_store_short v[108:109], v113, off sc1
	v_add_u32_e32 v108, v185, v48
	v_ashrrev_i32_e32 v109, 31, v108
	v_mul_f32_e32 v113, v110, v55
	v_cvt_pk_bf16_f32 v113, v113, s0
	v_lshl_add_u64 v[108:109], v[108:109], 1, s[8:9]
	global_store_short v[108:109], v113, off sc1
	v_add_u32_e32 v108, v187, v48
	v_ashrrev_i32_e32 v109, 31, v108
	v_mul_f32_e32 v113, v110, v54
	v_cvt_pk_bf16_f32 v113, v113, s0
	v_lshl_add_u64 v[108:109], v[108:109], 1, s[8:9]
	global_store_short v[108:109], v113, off sc1
	v_add_u32_e32 v108, v189, v48
	v_ashrrev_i32_e32 v109, 31, v108
	v_mul_f32_e32 v113, v110, v53
	v_cvt_pk_bf16_f32 v113, v113, s0
	v_lshl_add_u64 v[108:109], v[108:109], 1, s[8:9]
	global_store_short v[108:109], v113, off sc1
	v_add_u32_e32 v108, v190, v48
	v_ashrrev_i32_e32 v109, 31, v108
	v_mul_f32_e32 v113, v110, v52
	v_cvt_pk_bf16_f32 v113, v113, s0
	v_lshl_add_u64 v[108:109], v[108:109], 1, s[8:9]
	global_store_short v[108:109], v113, off sc1
	v_add_u32_e32 v108, v191, v48
	v_ashrrev_i32_e32 v109, 31, v108
	v_mul_f32_e32 v113, v110, v51
	v_cvt_pk_bf16_f32 v113, v113, s0
	v_lshl_add_u64 v[108:109], v[108:109], 1, s[8:9]
	global_store_short v[108:109], v113, off sc1
	v_add_u32_e32 v108, v192, v48
	v_ashrrev_i32_e32 v109, 31, v108
	v_mul_f32_e32 v113, v110, v50
	v_cvt_pk_bf16_f32 v113, v113, s0
	v_lshl_add_u64 v[108:109], v[108:109], 1, s[8:9]
	global_store_short v[108:109], v113, off sc1
	v_add_u32_e32 v108, v193, v48
	v_ashrrev_i32_e32 v109, 31, v108
	v_mul_f32_e32 v48, v110, v49
	v_cvt_pk_bf16_f32 v48, v48, s0
	v_lshl_add_u64 v[108:109], v[108:109], 1, s[8:9]
	global_store_short v[108:109], v48, off sc1
	v_add_u32_e32 v108, v188, v32
	v_ashrrev_i32_e32 v109, 31, v108
	s_waitcnt vmcnt(28)
	v_add_f32_e32 v48, 1.0, v107
	s_waitcnt vmcnt(27)
	v_mul_f32_e32 v48, v111, v48
	v_fmac_f32_e32 v106, v197, v197
	s_waitcnt vmcnt(25)
	v_fmac_f32_e32 v45, v17, v112
	global_store_dword v[88:89], v45, off offset:256 sc1
	s_waitcnt vmcnt(24)
	v_fmac_f32_e32 v38, v26, v112
	s_waitcnt vmcnt(23)
	v_fmac_f32_e32 v37, v27, v112
	s_waitcnt vmcnt(22)
	v_fmac_f32_e32 v36, v28, v112
	s_waitcnt vmcnt(21)
	v_fmac_f32_e32 v114, v16, v112
	v_mul_f32_e32 v16, v48, v114
	s_waitcnt vmcnt(20)
	v_fmac_f32_e32 v47, v18, v112
	v_cvt_pk_bf16_f32 v18, v16, s0
	v_lshl_add_u64 v[16:17], v[108:109], 1, s[8:9]
	global_store_short v[16:17], v18, off sc1
	v_add_u32_e32 v16, v186, v32
	v_ashrrev_i32_e32 v17, 31, v16
	v_mul_f32_e32 v18, v48, v45
	v_cvt_pk_bf16_f32 v18, v18, s0
	v_lshl_add_u64 v[16:17], v[16:17], 1, s[8:9]
	global_store_short v[16:17], v18, off sc1
	v_add_u32_e32 v16, v184, v32
	v_ashrrev_i32_e32 v17, 31, v16
	v_mul_f32_e32 v18, v48, v47
	v_cvt_pk_bf16_f32 v18, v18, s0
	v_lshl_add_u64 v[16:17], v[16:17], 1, s[8:9]
	s_waitcnt vmcnt(20)
	v_fmac_f32_e32 v46, v19, v112
	global_store_short v[16:17], v18, off sc1
	v_add_u32_e32 v16, v183, v32
	v_ashrrev_i32_e32 v17, 31, v16
	v_mul_f32_e32 v18, v48, v46
	s_waitcnt vmcnt(20)
	v_fmac_f32_e32 v44, v20, v112
	v_cvt_pk_bf16_f32 v18, v18, s0
	v_lshl_add_u64 v[16:17], v[16:17], 1, s[8:9]
	global_store_short v[16:17], v18, off sc1
	v_mul_f32_e32 v16, v48, v44
	v_cvt_pk_bf16_f32 v26, v16, s0
	v_or_b32_e32 v16, 0x60, v102
	v_add_u32_e32 v18, v181, v32
	v_ashrrev_i32_e32 v17, 31, v16
	s_waitcnt vmcnt(20)
	v_fmac_f32_e32 v43, v21, v112
	s_waitcnt vmcnt(19)
	v_fmac_f32_e32 v42, v22, v112
	s_waitcnt vmcnt(17)
	v_fmac_f32_e32 v41, v23, v112
	v_fmac_f32_e32 v40, v24, v112
	v_fmac_f32_e32 v39, v25, v112
	s_waitcnt vmcnt(15)
	v_fmac_f32_e32 v35, v29, v112
	s_waitcnt vmcnt(14)
	v_fmac_f32_e32 v34, v30, v112
	s_waitcnt vmcnt(13)
	v_fmac_f32_e32 v33, v31, v112
	v_ashrrev_i32_e32 v19, 31, v18
	v_lshlrev_b64 v[20:21], 2, v[16:17]
	global_store_dword v[84:85], v47, off offset:256 sc1
	global_store_dword v[82:83], v46, off offset:256 sc1
	global_store_dword v[78:79], v44, off offset:256 sc1
	global_store_dword v[72:73], v43, off offset:256 sc1
	global_store_dword v[74:75], v42, off offset:256 sc1
	global_store_dword v[76:77], v41, off offset:256 sc1
	global_store_dword v[80:81], v40, off offset:256 sc1
	global_store_dword v[86:87], v39, off offset:256 sc1
	global_store_dword v[90:91], v38, off offset:256 sc1
	global_store_dword v[92:93], v37, off offset:256 sc1
	global_store_dword v[94:95], v36, off offset:256 sc1
	global_store_dword v[96:97], v35, off offset:256 sc1
	global_store_dword v[98:99], v34, off offset:256 sc1
	global_store_dword v[100:101], v33, off offset:256 sc1
	global_store_dword v[104:105], v114, off offset:256 sc1
	v_lshl_add_u64 v[24:25], s[64:65], 0, v[20:21]
	v_lshl_add_u64 v[18:19], v[18:19], 1, s[8:9]
	global_load_dword v29, v[104:105], off offset:384
	v_lshl_add_u64 v[22:23], s[60:61], 0, v[20:21]
	global_load_dword v17, v[24:25], off
	global_load_dword v30, v[22:23], off
	global_load_dword v28, v[88:89], off offset:384
	global_load_dword v27, v[84:85], off offset:384
	v_fmac_f32_e32 v106, v114, v114
	global_store_short v[18:19], v26, off sc1
	v_lshl_add_u64 v[18:19], s[62:63], 0, v[20:21]
	global_load_dword v102, v[18:19], off
	v_add_u32_e32 v18, v179, v32
	v_ashrrev_i32_e32 v19, 31, v18
	v_mul_f32_e32 v20, v48, v43
	v_cvt_pk_bf16_f32 v20, v20, s0
	v_lshl_add_u64 v[18:19], v[18:19], 1, s[8:9]
	global_store_short v[18:19], v20, off sc1
	v_add_u32_e32 v18, v71, v32
	v_ashrrev_i32_e32 v19, 31, v18
	v_mul_f32_e32 v20, v48, v42
	v_cvt_pk_bf16_f32 v20, v20, s0
	v_lshl_add_u64 v[18:19], v[18:19], 1, s[8:9]
	global_store_short v[18:19], v20, off sc1
	v_add_u32_e32 v18, v180, v32
	v_ashrrev_i32_e32 v19, 31, v18
	v_mul_f32_e32 v20, v48, v41
	v_cvt_pk_bf16_f32 v20, v20, s0
	v_lshl_add_u64 v[18:19], v[18:19], 1, s[8:9]
	global_store_short v[18:19], v20, off sc1
	v_add_u32_e32 v18, v182, v32
	v_ashrrev_i32_e32 v19, 31, v18
	v_mul_f32_e32 v20, v48, v40
	v_cvt_pk_bf16_f32 v20, v20, s0
	v_lshl_add_u64 v[18:19], v[18:19], 1, s[8:9]
	global_store_short v[18:19], v20, off sc1
	v_add_u32_e32 v18, v185, v32
	v_ashrrev_i32_e32 v19, 31, v18
	v_mul_f32_e32 v20, v48, v39
	v_cvt_pk_bf16_f32 v20, v20, s0
	v_lshl_add_u64 v[18:19], v[18:19], 1, s[8:9]
	global_store_short v[18:19], v20, off sc1
	v_add_u32_e32 v18, v187, v32
	v_ashrrev_i32_e32 v19, 31, v18
	v_mul_f32_e32 v20, v48, v38
	v_cvt_pk_bf16_f32 v20, v20, s0
	v_lshl_add_u64 v[18:19], v[18:19], 1, s[8:9]
	global_store_short v[18:19], v20, off sc1
	v_add_u32_e32 v18, v189, v32
	v_ashrrev_i32_e32 v19, 31, v18
	v_mul_f32_e32 v20, v48, v37
	v_cvt_pk_bf16_f32 v20, v20, s0
	v_lshl_add_u64 v[18:19], v[18:19], 1, s[8:9]
	global_store_short v[18:19], v20, off sc1
	v_add_u32_e32 v18, v190, v32
	v_ashrrev_i32_e32 v19, 31, v18
	v_mul_f32_e32 v20, v48, v36
	v_cvt_pk_bf16_f32 v20, v20, s0
	v_lshl_add_u64 v[18:19], v[18:19], 1, s[8:9]
	global_store_short v[18:19], v20, off sc1
	v_add_u32_e32 v18, v191, v32
	v_ashrrev_i32_e32 v19, 31, v18
	v_mul_f32_e32 v20, v48, v35
	v_cvt_pk_bf16_f32 v20, v20, s0
	v_lshl_add_u64 v[18:19], v[18:19], 1, s[8:9]
	global_store_short v[18:19], v20, off sc1
	v_add_u32_e32 v18, v192, v32
	v_ashrrev_i32_e32 v19, 31, v18
	v_mul_f32_e32 v20, v48, v34
	v_cvt_pk_bf16_f32 v20, v20, s0
	v_lshl_add_u64 v[18:19], v[18:19], 1, s[8:9]
	global_store_short v[18:19], v20, off sc1
	v_add_u32_e32 v18, v193, v32
	v_ashrrev_i32_e32 v19, 31, v18
	v_mul_f32_e32 v20, v48, v33
	v_cvt_pk_bf16_f32 v20, v20, s0
	v_lshl_add_u64 v[18:19], v[18:19], 1, s[8:9]
	global_store_short v[18:19], v20, off sc1
	global_load_dword v20, v[86:87], off offset:384
	v_add_u32_e32 v18, v188, v16
	global_load_dword v26, v[82:83], off offset:384
	global_load_dword v25, v[78:79], off offset:384
	global_load_dword v24, v[72:73], off offset:384
	global_load_dword v23, v[74:75], off offset:384
	global_load_dword v21, v[80:81], off offset:384
	global_load_dword v22, v[76:77], off offset:384
	s_waitcnt vmcnt(23)
	v_add_f32_e32 v17, 1.0, v17
	s_waitcnt vmcnt(22)
	v_mul_f32_e32 v32, v30, v17
	v_ashrrev_i32_e32 v19, 31, v18
	v_lshl_add_u64 v[18:19], v[18:19], 1, s[8:9]
	v_add_u32_e32 v30, v186, v16
	s_waitcnt vmcnt(18)
	v_fmac_f32_e32 v29, v0, v102
	v_mul_f32_e32 v0, v32, v29
	v_cvt_pk_bf16_f32 v0, v0, s0
	global_store_short v[18:19], v0, off sc1
	global_load_dword v19, v[90:91], off offset:384
	v_ashrrev_i32_e32 v31, 31, v30
	global_load_dword v18, v[92:93], off offset:384
	v_fmac_f32_e32 v28, v1, v102
	v_mul_f32_e32 v0, v32, v28
	v_cvt_pk_bf16_f32 v17, v0, s0
	v_lshl_add_u64 v[0:1], v[30:31], 1, s[8:9]
	global_store_short v[0:1], v17, off sc1
	v_add_u32_e32 v0, v184, v16
	v_fmac_f32_e32 v27, v2, v102
	global_load_dword v17, v[94:95], off offset:384
	v_ashrrev_i32_e32 v1, 31, v0
	v_mul_f32_e32 v2, v32, v27
	v_cvt_pk_bf16_f32 v2, v2, s0
	v_lshl_add_u64 v[0:1], v[0:1], 1, s[8:9]
	global_store_short v[0:1], v2, off sc1
	v_add_u32_e32 v0, v183, v16
	global_load_dword v2, v[96:97], off offset:384
	v_ashrrev_i32_e32 v1, 31, v0
	v_lshl_add_u64 v[0:1], v[0:1], 1, s[8:9]
	v_add_u32_e32 v30, v181, v16
	v_ashrrev_i32_e32 v31, 31, v30
	v_lshl_add_u64 v[30:31], v[30:31], 1, s[8:9]
	v_fmac_f32_e32 v106, v29, v29
	global_store_dword v[104:105], v29, off offset:384 sc1
	global_store_dword v[88:89], v28, off offset:384 sc1
	global_store_dword v[84:85], v27, off offset:384 sc1
	s_waitcnt vmcnt(16)
	v_fmac_f32_e32 v20, v9, v102
	global_store_dword v[86:87], v20, off offset:384 sc1
	s_waitcnt vmcnt(16)
	v_fmac_f32_e32 v26, v3, v102
	v_mul_f32_e32 v3, v32, v26
	v_cvt_pk_bf16_f32 v3, v3, s0
	global_store_short v[0:1], v3, off sc1
	global_load_dword v1, v[98:99], off offset:384
	s_waitcnt vmcnt(17)
	v_fmac_f32_e32 v25, v4, v102
	v_mul_f32_e32 v0, v32, v25
	v_cvt_pk_bf16_f32 v0, v0, s0
	global_store_short v[30:31], v0, off sc1
	global_load_dword v0, v[100:101], off offset:384
	v_add_u32_e32 v30, v179, v16
	s_waitcnt vmcnt(18)
	v_fmac_f32_e32 v24, v5, v102
	v_ashrrev_i32_e32 v31, 31, v30
	v_mul_f32_e32 v3, v32, v24
	v_cvt_pk_bf16_f32 v3, v3, s0
	v_lshl_add_u64 v[4:5], v[30:31], 1, s[8:9]
	global_store_short v[4:5], v3, off sc1
	v_add_u32_e32 v4, v71, v16
	s_waitcnt vmcnt(18)
	v_fmac_f32_e32 v23, v6, v102
	v_ashrrev_i32_e32 v5, 31, v4
	v_mul_f32_e32 v3, v32, v23
	v_cvt_pk_bf16_f32 v3, v3, s0
	v_lshl_add_u64 v[4:5], v[4:5], 1, s[8:9]
	global_store_short v[4:5], v3, off sc1
	v_add_u32_e32 v4, v180, v16
	s_waitcnt vmcnt(17)
	v_fmac_f32_e32 v22, v7, v102
	v_ashrrev_i32_e32 v5, 31, v4
	v_mul_f32_e32 v3, v32, v22
	v_cvt_pk_bf16_f32 v3, v3, s0
	v_lshl_add_u64 v[4:5], v[4:5], 1, s[8:9]
	global_store_short v[4:5], v3, off sc1
	v_add_u32_e32 v4, v182, v16
	v_fmac_f32_e32 v21, v8, v102
	v_ashrrev_i32_e32 v5, 31, v4
	v_mul_f32_e32 v3, v32, v21
	v_cvt_pk_bf16_f32 v3, v3, s0
	v_lshl_add_u64 v[4:5], v[4:5], 1, s[8:9]
	global_store_short v[4:5], v3, off sc1
	v_add_u32_e32 v4, v185, v16
	v_ashrrev_i32_e32 v5, 31, v4
	v_mul_f32_e32 v3, v32, v20
	v_cvt_pk_bf16_f32 v3, v3, s0
	v_lshl_add_u64 v[4:5], v[4:5], 1, s[8:9]
	global_store_short v[4:5], v3, off sc1
	v_add_u32_e32 v4, v187, v16
	s_waitcnt vmcnt(18)
	v_fmac_f32_e32 v19, v10, v102
	v_ashrrev_i32_e32 v5, 31, v4
	v_mul_f32_e32 v3, v32, v19
	v_cvt_pk_bf16_f32 v3, v3, s0
	v_lshl_add_u64 v[4:5], v[4:5], 1, s[8:9]
	global_store_short v[4:5], v3, off sc1
	v_add_u32_e32 v4, v189, v16
	s_waitcnt vmcnt(18)
	v_fmac_f32_e32 v18, v11, v102
	v_ashrrev_i32_e32 v5, 31, v4
	v_mul_f32_e32 v3, v32, v18
	v_cvt_pk_bf16_f32 v3, v3, s0
	v_lshl_add_u64 v[4:5], v[4:5], 1, s[8:9]
	global_store_short v[4:5], v3, off sc1
	v_add_u32_e32 v4, v190, v16
	s_waitcnt vmcnt(17)
	v_fmac_f32_e32 v17, v12, v102
	v_ashrrev_i32_e32 v5, 31, v4
	v_mul_f32_e32 v3, v32, v17
	v_cvt_pk_bf16_f32 v3, v3, s0
	v_lshl_add_u64 v[4:5], v[4:5], 1, s[8:9]
	global_store_short v[4:5], v3, off sc1
	v_add_u32_e32 v4, v191, v16
	s_waitcnt vmcnt(16)
	v_fmac_f32_e32 v2, v13, v102
	v_ashrrev_i32_e32 v5, 31, v4
	v_mul_f32_e32 v3, v32, v2
	v_cvt_pk_bf16_f32 v3, v3, s0
	v_lshl_add_u64 v[4:5], v[4:5], 1, s[8:9]
	global_store_short v[4:5], v3, off sc1
	v_add_u32_e32 v4, v192, v16
	v_ashrrev_i32_e32 v5, 31, v4
	v_lshl_add_u64 v[4:5], v[4:5], 1, s[8:9]
	v_xor_b32_e32 v13, 16, v164
	v_add_u32_e32 v10, v193, v16
	v_ashrrev_i32_e32 v11, 31, v10
	v_lshl_add_u64 v[10:11], v[10:11], 1, s[8:9]
	v_ashrrev_i32_e32 v71, 31, v70
	global_store_dword v[82:83], v26, off offset:384 sc1
	global_store_dword v[78:79], v25, off offset:384 sc1
	global_store_dword v[72:73], v24, off offset:384 sc1
	global_store_dword v[74:75], v23, off offset:384 sc1
	s_waitcnt vmcnt(15)
	v_fmac_f32_e32 v1, v14, v102
	v_mul_f32_e32 v3, v32, v1
	v_cvt_pk_bf16_f32 v3, v3, s0
	global_store_short v[4:5], v3, off sc1
	v_and_b32_e32 v4, 64, v164
	v_xor_b32_e32 v3, 1, v164
	v_add_u32_e32 v7, 64, v4
	v_cmp_lt_i32_e32 vcc, v3, v7
	v_xor_b32_e32 v4, 2, v164
	s_waitcnt vmcnt(14)
	v_fmac_f32_e32 v0, v15, v102
	v_cndmask_b32_e32 v3, v164, v3, vcc
	v_lshlrev_b32_e32 v3, 2, v3
	v_cmp_lt_i32_e32 vcc, v4, v7
	v_mul_f32_e32 v12, v32, v0
	v_cvt_pk_bf16_f32 v12, v12, s0
	v_cndmask_b32_e32 v4, v164, v4, vcc
	v_lshlrev_b32_e32 v4, 2, v4
	v_add_f32_dpp v6, v106, v106 quad_perm:[1,0,3,2] row_mask:0xf bank_mask:0xf
	v_xor_b32_e32 v5, 4, v164
	v_cmp_lt_i32_e32 vcc, v5, v7
	global_store_dword v[76:77], v22, off offset:384 sc1
	global_store_dword v[80:81], v21, off offset:384 sc1
	v_cndmask_b32_e32 v5, v164, v5, vcc
	v_lshlrev_b32_e32 v5, 2, v5
	v_add_f32_dpp v8, v6, v6 quad_perm:[2,3,0,1] row_mask:0xf bank_mask:0xf
	v_xor_b32_e32 v6, 8, v164
	v_cmp_lt_i32_e32 vcc, v6, v7
	global_store_dword v[90:91], v19, off offset:384 sc1
	global_store_dword v[92:93], v18, off offset:384 sc1
	v_cndmask_b32_e32 v6, v164, v6, vcc
	v_lshlrev_b32_e32 v6, 2, v6
	v_add_f32_dpp v8, v8, v8 row_half_mirror row_mask:0xf bank_mask:0xf
	v_cmp_lt_i32_e32 vcc, v13, v7
	global_store_dword v[94:95], v17, off offset:384 sc1
	global_store_dword v[96:97], v2, off offset:384 sc1
	v_cndmask_b32_e32 v7, v164, v13, vcc
	v_lshlrev_b32_e32 v7, 2, v7
	v_add_f32_dpp v8, v8, v8 row_mirror row_mask:0xf bank_mask:0xf
	ds_bpermute_b32 v9, v7, v8
	global_store_dword v[98:99], v1, off offset:384 sc1
	global_store_dword v[100:101], v0, off offset:384 sc1
	global_store_short v[10:11], v12, off sc1
	s_and_saveexec_b64 s[60:61], s[0:1]
	s_cbranch_execz .LBB0_1571
	s_waitcnt lgkmcnt(0)
	v_add_f32_e32 v10, v8, v9
	v_lshl_add_u64 v[8:9], v[70:71], 2, s[58:59]
	global_store_dword v[8:9], v10, off sc1
